# cand27 + the same DPP/permlane butterfly steps in the norm, rotate/quantise, gating-tail and first-row reductions
# speedup vs baseline: 1.0084x; 1.0002x over previous
.LBB0_288:
	s_mul_i32 s59, s59, s55
	s_sub_i32 s2, s71, s59
	s_lshl_b32 s2, s2, 6
	s_waitcnt vmcnt(0)
	v_mul_f32_e32 v144, v130, v139
	v_mul_f32_e32 v145, v131, v139
	v_cvt_pk_bf16_f32 v144, v144, v145
	v_mul_f32_e32 v145, v132, v139
	s_cmp_eq_u64 s[52:53], 0
	v_mul_f32_e32 v139, v133, v139
	v_cvt_pk_bf16_f32 v145, v145, v139
	ds_write_b64 v194, v[144:145] offset:8640
	s_cbranch_scc1 .LBB0_179
	v_lshlrev_b32_e32 v139, 16, v142
	v_and_b32_e32 v142, 0xffff0000, v142
	v_lshlrev_b32_e32 v200, 16, v146
	v_and_b32_e32 v146, 0xffff0000, v146
	v_lshlrev_b32_e32 v194, 16, v143
	v_and_b32_e32 v143, 0xffff0000, v143
	v_max3_f32 v142, |v142|, 0, |v146|
	v_lshlrev_b32_e32 v146, 16, v147
	v_and_b32_e32 v147, 0xffff0000, v147
	v_max3_f32 v139, |v139|, 0, |v200|
	v_max3_f32 v143, |v143|, 0, |v147|
	v_lshlrev_b32_e32 v147, 16, v148
	v_lshlrev_b32_e32 v200, 16, v150
	v_and_b32_e32 v148, 0xffff0000, v148
	v_max3_f32 v139, v139, |v147|, |v200|
	v_and_b32_e32 v147, 0xffff0000, v150
	v_max3_f32 v146, |v194|, 0, |v146|
	v_lshlrev_b32_e32 v194, 16, v149
	v_max3_f32 v142, v142, |v148|, |v147|
	v_lshlrev_b32_e32 v147, 16, v151
	v_and_b32_e32 v149, 0xffff0000, v149
	v_max3_f32 v146, v146, |v194|, |v147|
	v_and_b32_e32 v147, 0xffff0000, v151
	v_max3_f32 v143, v143, |v149|, |v147|
	v_lshlrev_b32_e32 v147, 16, v152
	v_lshlrev_b32_e32 v151, 16, v154
	v_and_b32_e32 v148, 0xffff0000, v152
	v_max3_f32 v139, v139, |v147|, |v151|
	v_and_b32_e32 v147, 0xffff0000, v154
	v_lshlrev_b32_e32 v149, 16, v153
	v_max3_f32 v142, v142, |v148|, |v147|
	v_lshlrev_b32_e32 v147, 16, v155
	v_and_b32_e32 v150, 0xffff0000, v153
	v_max3_f32 v146, v146, |v149|, |v147|
	v_and_b32_e32 v147, 0xffff0000, v155
	v_max3_f32 v143, v143, |v150|, |v147|
	v_lshlrev_b32_e32 v147, 16, v156
	v_lshlrev_b32_e32 v151, 16, v158
	v_and_b32_e32 v148, 0xffff0000, v156
	v_max3_f32 v139, v139, |v147|, |v151|
	v_and_b32_e32 v147, 0xffff0000, v158
	v_lshlrev_b32_e32 v149, 16, v157
	v_max3_f32 v142, v142, |v148|, |v147|
	v_lshlrev_b32_e32 v147, 16, v159
	v_and_b32_e32 v150, 0xffff0000, v157
	v_max3_f32 v146, v146, |v149|, |v147|
	v_and_b32_e32 v147, 0xffff0000, v159
	v_max3_f32 v143, v143, |v150|, |v147|
	v_lshlrev_b32_e32 v147, 16, v160
	v_lshlrev_b32_e32 v151, 16, v162
	v_and_b32_e32 v148, 0xffff0000, v160
	v_max3_f32 v139, v139, |v147|, |v151|
	v_and_b32_e32 v147, 0xffff0000, v162
	v_lshlrev_b32_e32 v149, 16, v161
	v_max3_f32 v142, v142, |v148|, |v147|
	v_lshlrev_b32_e32 v147, 16, v163
	v_and_b32_e32 v150, 0xffff0000, v161
	v_max3_f32 v146, v146, |v149|, |v147|
	v_and_b32_e32 v147, 0xffff0000, v163
	v_max3_f32 v143, v143, |v150|, |v147|
	v_lshlrev_b32_e32 v147, 16, v164
	v_lshlrev_b32_e32 v151, 16, v166
	v_and_b32_e32 v148, 0xffff0000, v164
	v_max3_f32 v139, v139, |v147|, |v151|
	v_and_b32_e32 v147, 0xffff0000, v166
	v_lshlrev_b32_e32 v149, 16, v165
	v_max3_f32 v142, v142, |v148|, |v147|
	v_lshlrev_b32_e32 v147, 16, v167
	v_and_b32_e32 v150, 0xffff0000, v165
	v_max3_f32 v146, v146, |v149|, |v147|
	v_and_b32_e32 v147, 0xffff0000, v167
	v_max3_f32 v143, v143, |v150|, |v147|
	v_lshlrev_b32_e32 v147, 16, v168
	v_lshlrev_b32_e32 v151, 16, v170
	v_and_b32_e32 v148, 0xffff0000, v168
	v_max3_f32 v139, v139, |v147|, |v151|
	v_and_b32_e32 v147, 0xffff0000, v170
	v_lshlrev_b32_e32 v149, 16, v169
	v_max3_f32 v142, v142, |v148|, |v147|
	v_lshlrev_b32_e32 v147, 16, v171
	v_and_b32_e32 v150, 0xffff0000, v169
	v_max3_f32 v146, v146, |v149|, |v147|
	v_and_b32_e32 v147, 0xffff0000, v171
	v_max3_f32 v143, v143, |v150|, |v147|
	v_and_b32_e32 v150, 0xffff0000, v173
	v_and_b32_e32 v151, 0xffff0000, v145
	v_lshlrev_b32_e32 v147, 16, v172
	v_max3_f32 v150, v143, |v150|, |v151|
	v_lshlrev_b32_e32 v143, 16, v144
	v_max3_f32 v139, v139, |v147|, |v143|
	v_and_b32_e32 v147, 64, v193
	v_xor_b32_e32 v143, 16, v193
	v_add_u32_e32 v147, 64, v147
	v_cmp_lt_i32_e32 vcc, v143, v147
	v_and_b32_e32 v148, 0xffff0000, v172
	v_and_b32_e32 v144, 0xffff0000, v144
	v_cndmask_b32_e32 v143, v193, v143, vcc
	v_lshlrev_b32_e32 v151, 2, v143
	ds_bpermute_b32 v143, v151, v139
	v_lshlrev_b32_e32 v149, 16, v173
	v_lshlrev_b32_e32 v145, 16, v145
	v_max3_f32 v144, v142, |v148|, |v144|
	v_max3_f32 v145, v146, |v149|, |v145|
	s_waitcnt lgkmcnt(0)
	v_max_f32_e32 v142, v143, v143
	v_max_f32_e32 v139, v139, v142
	v_xor_b32_e32 v142, 32, v193
	ds_bpermute_b32 v143, v151, v144
	v_cmp_lt_i32_e32 vcc, v142, v147
	ds_bpermute_b32 v147, v151, v150
	v_cndmask_b32_e32 v142, v193, v142, vcc
	s_waitcnt lgkmcnt(0)
	v_max_f32_e32 v143, v143, v143
	v_lshlrev_b32_e32 v148, 2, v142
	s_waitcnt lgkmcnt(0)
	s_waitcnt lgkmcnt(0)
	v_max_f32_e32 v147, v147, v147
	v_max_f32_e32 v143, v144, v143
	v_mov_b32_e32 v146, v145
	s_nop 1
	v_permlane16_swap_b32_e32 v146, v145
	v_max_f32_e32 v145, v145, v146
	v_max_f32_e32 v147, v150, v147
	ds_bpermute_b32 v142, v148, v139
	ds_bpermute_b32 v144, v148, v143
	ds_bpermute_b32 v146, v148, v145
	ds_bpermute_b32 v148, v148, v147
	s_and_saveexec_b64 s[60:61], s[0:1]
	s_cbranch_execz .LBB0_178
	s_ashr_i32 s3, s2, 31
	s_lshl_b64 s[62:63], s[2:3], 2
	s_waitcnt lgkmcnt(0)
	v_max_f32_e32 v142, v142, v142
	v_max_f32_e32 v139, v139, v139
	s_add_u32 s62, s52, s62
	s_waitcnt lgkmcnt(0)
	v_max_f32_e32 v148, v148, v148
	v_max_f32_e32 v147, v147, v147
	v_max_f32_e32 v146, v146, v146
	v_max_f32_e32 v145, v145, v145
	v_max_f32_e32 v144, v144, v144
	v_max_f32_e32 v143, v143, v143
	v_max_f32_e32 v139, v139, v142
	s_addc_u32 s63, s53, s63
	v_lshlrev_b32_e32 v142, 2, v174
	v_max_f32_e32 v147, v147, v148
	v_max_f32_e32 v145, v145, v146
	v_max_f32_e32 v143, v143, v144
	global_atomic_umax v142, v139, s[62:63]
	global_atomic_umax v142, v143, s[62:63] offset:4
	global_atomic_umax v142, v145, s[62:63] offset:8
	global_atomic_umax v142, v147, s[62:63] offset:12
	s_branch .LBB0_178

.LBB0_296:
	s_cmpk_gt_i32 s14, 0x1fff
	s_mov_b64 s[2:3], -1
	s_cbranch_scc0 .LBB0_298
	s_add_i32 s10, s14, 0xffffe000
	s_lshl_b64 s[2:3], s[10:11], 14
	s_add_u32 s2, s6, s2
	s_addc_u32 s3, s7, s3
	global_load_dwordx4 v[30:33], v1, s[2:3]
	global_load_dwordx4 v[22:25], v1, s[2:3] offset:16
	global_load_dwordx4 v[38:41], v1, s[2:3] offset:2048
	global_load_dwordx4 v[26:29], v1, s[2:3] offset:2064
	global_load_dwordx4 v[46:49], v66, s[2:3]
	global_load_dwordx4 v[34:37], v66, s[2:3] offset:16
	global_load_dwordx4 v[54:57], v69, s[2:3]
	global_load_dwordx4 v[42:45], v69, s[2:3] offset:16
	global_load_dwordx4 v[58:61], v74, s[2:3]
	global_load_dwordx4 v[50:53], v74, s[2:3] offset:16
	global_load_dwordx4 v[62:65], v75, s[2:3]
	global_load_dwordx4 v[2:5], v75, s[2:3] offset:16
	global_load_dwordx4 v[14:17], v76, s[2:3]
	global_load_dwordx4 v[6:9], v76, s[2:3] offset:16
	global_load_dwordx4 v[18:21], v83, s[2:3]
	global_load_dwordx4 v[10:13], v83, s[2:3] offset:16
	v_cmp_lt_i32_e32 vcc, v86, v85
	s_lshl_b64 s[30:31], s[10:11], 13
	s_add_u32 s30, s34, s30
	v_cndmask_b32_e32 v92, v84, v86, vcc
	v_lshlrev_b32_e32 v92, 2, v92
	v_cmp_lt_i32_e32 vcc, v87, v85
	s_addc_u32 s31, s35, s31
	s_waitcnt vmcnt(15) lgkmcnt(0)
	v_mul_f32_e32 v93, v31, v31
	v_fmac_f32_e32 v93, v30, v30
	v_fmac_f32_e32 v93, v32, v32
	v_fmac_f32_e32 v93, v33, v33
	s_waitcnt vmcnt(14)
	v_fmac_f32_e32 v93, v22, v22
	v_fmac_f32_e32 v93, v23, v23
	v_fmac_f32_e32 v93, v24, v24
	v_fmac_f32_e32 v93, v25, v25
	s_waitcnt vmcnt(13)
	v_fmac_f32_e32 v93, v38, v38
	v_fmac_f32_e32 v93, v39, v39
	v_fmac_f32_e32 v93, v40, v40
	v_fmac_f32_e32 v93, v41, v41
	s_waitcnt vmcnt(12)
	v_fmac_f32_e32 v93, v26, v26
	v_fmac_f32_e32 v93, v27, v27
	v_fmac_f32_e32 v93, v28, v28
	v_fmac_f32_e32 v93, v29, v29
	s_waitcnt vmcnt(11)
	v_fmac_f32_e32 v93, v46, v46
	v_fmac_f32_e32 v93, v47, v47
	v_fmac_f32_e32 v93, v48, v48
	v_fmac_f32_e32 v93, v49, v49
	s_waitcnt vmcnt(10)
	v_fmac_f32_e32 v93, v34, v34
	v_fmac_f32_e32 v93, v35, v35
	v_fmac_f32_e32 v93, v36, v36
	v_fmac_f32_e32 v93, v37, v37
	s_waitcnt vmcnt(9)
	v_fmac_f32_e32 v93, v54, v54
	v_fmac_f32_e32 v93, v55, v55
	v_fmac_f32_e32 v93, v56, v56
	v_fmac_f32_e32 v93, v57, v57
	s_waitcnt vmcnt(8)
	v_fmac_f32_e32 v93, v42, v42
	v_fmac_f32_e32 v93, v43, v43
	v_fmac_f32_e32 v93, v44, v44
	v_fmac_f32_e32 v93, v45, v45
	s_waitcnt vmcnt(7)
	v_fmac_f32_e32 v93, v58, v58
	v_fmac_f32_e32 v93, v59, v59
	v_fmac_f32_e32 v93, v60, v60
	v_fmac_f32_e32 v93, v61, v61
	s_waitcnt vmcnt(6)
	v_fmac_f32_e32 v93, v50, v50
	v_fmac_f32_e32 v93, v51, v51
	v_fmac_f32_e32 v93, v52, v52
	v_fmac_f32_e32 v93, v53, v53
	s_waitcnt vmcnt(5)
	v_fmac_f32_e32 v93, v62, v62
	v_fmac_f32_e32 v93, v63, v63
	v_fmac_f32_e32 v93, v64, v64
	v_fmac_f32_e32 v93, v65, v65
	s_waitcnt vmcnt(4)
	v_fmac_f32_e32 v93, v2, v2
	v_fmac_f32_e32 v93, v3, v3
	v_fmac_f32_e32 v93, v4, v4
	v_fmac_f32_e32 v93, v5, v5
	s_waitcnt vmcnt(3)
	v_fmac_f32_e32 v93, v14, v14
	v_fmac_f32_e32 v93, v15, v15
	v_fmac_f32_e32 v93, v16, v16
	v_fmac_f32_e32 v93, v17, v17
	s_waitcnt vmcnt(2)
	v_fmac_f32_e32 v93, v6, v6
	v_fmac_f32_e32 v93, v7, v7
	v_fmac_f32_e32 v93, v8, v8
	v_fmac_f32_e32 v93, v9, v9
	s_waitcnt vmcnt(1)
	v_fmac_f32_e32 v93, v18, v18
	v_fmac_f32_e32 v93, v19, v19
	v_fmac_f32_e32 v93, v20, v20
	v_fmac_f32_e32 v93, v21, v21
	s_waitcnt vmcnt(0)
	v_fmac_f32_e32 v93, v10, v10
	v_fmac_f32_e32 v93, v11, v11
	v_fmac_f32_e32 v93, v12, v12
	v_fmac_f32_e32 v93, v13, v13
	ds_bpermute_b32 v92, v92, v93
	v_cndmask_b32_e32 v94, v84, v87, vcc
	v_lshlrev_b32_e32 v94, 2, v94
	v_cmp_lt_i32_e32 vcc, v88, v85
	s_waitcnt lgkmcnt(0)
	v_add_f32_e32 v92, v93, v92
	v_cndmask_b32_e32 v94, v84, v88, vcc
	v_lshlrev_b32_e32 v94, 2, v94
	v_cmp_lt_i32_e32 vcc, v89, v85
	s_waitcnt lgkmcnt(0)
	s_nop 1
	v_add_f32_dpp v92, v92, v92 quad_perm:[2,3,0,1] row_mask:0xf bank_mask:0xf
	ds_bpermute_b32 v93, v94, v92
	v_cndmask_b32_e32 v94, v84, v89, vcc
	v_lshlrev_b32_e32 v94, 2, v94
	v_cmp_lt_i32_e32 vcc, v90, v85
	s_waitcnt lgkmcnt(0)
	v_add_f32_e32 v92, v92, v93
	ds_bpermute_b32 v93, v94, v92
	v_cndmask_b32_e32 v94, v84, v90, vcc
	v_lshlrev_b32_e32 v94, 2, v94
	v_cmp_lt_i32_e32 vcc, v91, v85
	s_waitcnt lgkmcnt(0)
	v_add_f32_e32 v92, v92, v93
	v_cndmask_b32_e32 v94, v84, v91, vcc
	v_lshlrev_b32_e32 v94, 2, v94
	s_waitcnt lgkmcnt(0)
	v_mov_b32_e32 v93, v92
	s_nop 1
	v_permlane16_swap_b32_e32 v93, v92
	v_add_f32_e32 v92, v92, v93
	s_waitcnt lgkmcnt(0)
	v_mov_b32_e32 v93, v92
	s_nop 1
	v_permlane32_swap_b32_e32 v93, v92
	v_add_f32_e32 v92, v92, v93
	v_fmamk_f32 v92, v92, 0x39800000, v77
	v_mul_f32_e32 v93, 0x4f800000, v92
	v_cmp_gt_f32_e32 vcc, s39, v92
	s_nop 1
	v_cndmask_b32_e32 v92, v92, v93, vcc
	v_sqrt_f32_e32 v93, v92
	s_nop 0
	v_add_u32_e32 v94, -1, v93
	v_add_u32_e32 v95, 1, v93
	v_fma_f32 v96, -v94, v93, v92
	v_fma_f32 v97, -v95, v93, v92
	v_cmp_ge_f32_e64 s[2:3], 0, v96
	s_nop 1
	v_cndmask_b32_e64 v93, v93, v94, s[2:3]
	v_cmp_lt_f32_e64 s[2:3], 0, v97
	s_nop 1
	v_cndmask_b32_e64 v93, v93, v95, s[2:3]
	v_mul_f32_e32 v94, 0x37800000, v93
	v_cndmask_b32_e32 v93, v93, v94, vcc
	v_cmp_class_f32_e32 vcc, v92, v78
	s_nop 1
	v_cndmask_b32_e32 v92, v93, v92, vcc
	v_div_scale_f32 v93, s[2:3], v92, v92, 1.0
	v_rcp_f32_e32 v94, v93
	v_div_scale_f32 v95, vcc, 1.0, v92, 1.0
	s_mov_b64 s[2:3], 0
	v_fma_f32 v96, -v93, v94, 1.0
	v_fmac_f32_e32 v94, v96, v94
	v_mul_f32_e32 v96, v95, v94
	v_fma_f32 v97, -v93, v96, v95
	v_fmac_f32_e32 v96, v97, v94
	v_fma_f32 v93, -v93, v96, v95
	v_div_fmas_f32 v93, v93, v94, v96
	v_div_fixup_f32 v92, v93, v92, 1.0
	v_mul_f32_e32 v30, v30, v92
	v_mul_f32_e32 v31, v31, v92
	v_mul_f32_e32 v32, v32, v92
	v_mul_f32_e32 v33, v33, v92
	v_mul_f32_e32 v93, v22, v92
	v_mul_f32_e32 v94, v23, v92
	v_mul_f32_e32 v25, v25, v92
	v_cvt_pk_bf16_f32 v22, v30, v31
	v_cvt_pk_bf16_f32 v23, v32, v33
	v_mul_f32_e32 v95, v24, v92
	v_mul_f32_e32 v38, v38, v92
	v_mul_f32_e32 v39, v39, v92
	v_mul_f32_e32 v40, v40, v92
	v_mul_f32_e32 v41, v41, v92
	v_cvt_pk_bf16_f32 v24, v93, v94
	v_cvt_pk_bf16_f32 v25, v95, v25
	global_store_dwordx4 v79, v[22:25], s[30:31]
	v_mul_f32_e32 v26, v26, v92
	v_mul_f32_e32 v27, v27, v92
	v_cvt_pk_bf16_f32 v22, v38, v39
	v_cvt_pk_bf16_f32 v23, v40, v41
	v_mul_f32_e32 v28, v28, v92
	v_mul_f32_e32 v29, v29, v92
	v_mul_f32_e32 v46, v46, v92
	v_mul_f32_e32 v47, v47, v92
	v_mul_f32_e32 v48, v48, v92
	v_mul_f32_e32 v49, v49, v92
	v_cvt_pk_bf16_f32 v24, v26, v27
	v_cvt_pk_bf16_f32 v25, v28, v29
	global_store_dwordx4 v79, v[22:25], s[30:31] offset:1024
	v_mul_f32_e32 v34, v34, v92
	v_mul_f32_e32 v35, v35, v92
	v_cvt_pk_bf16_f32 v22, v46, v47
	v_cvt_pk_bf16_f32 v23, v48, v49
	v_mul_f32_e32 v36, v36, v92
	v_mul_f32_e32 v37, v37, v92
	v_mul_f32_e32 v54, v54, v92
	v_mul_f32_e32 v55, v55, v92
	v_mul_f32_e32 v56, v56, v92
	v_mul_f32_e32 v57, v57, v92
	v_cvt_pk_bf16_f32 v24, v34, v35
	v_cvt_pk_bf16_f32 v25, v36, v37
	global_store_dwordx4 v79, v[22:25], s[30:31] offset:2048
	v_mul_f32_e32 v42, v42, v92
	v_mul_f32_e32 v43, v43, v92
	v_cvt_pk_bf16_f32 v22, v54, v55
	v_cvt_pk_bf16_f32 v23, v56, v57
	v_mul_f32_e32 v44, v44, v92
	v_mul_f32_e32 v45, v45, v92
	v_mul_f32_e32 v58, v58, v92
	v_mul_f32_e32 v59, v59, v92
	v_mul_f32_e32 v60, v60, v92
	v_mul_f32_e32 v61, v61, v92
	v_cvt_pk_bf16_f32 v24, v42, v43
	v_cvt_pk_bf16_f32 v25, v44, v45
	global_store_dwordx4 v79, v[22:25], s[30:31] offset:3072
	v_mul_f32_e32 v5, v5, v92
	v_mul_f32_e32 v50, v50, v92
	v_cvt_pk_bf16_f32 v22, v58, v59
	v_cvt_pk_bf16_f32 v23, v60, v61
	v_mul_f32_e32 v51, v51, v92
	v_mul_f32_e32 v52, v52, v92
	v_mul_f32_e32 v53, v53, v92
	v_mul_f32_e32 v62, v62, v92
	v_mul_f32_e32 v63, v63, v92
	v_mul_f32_e32 v64, v64, v92
	v_mul_f32_e32 v65, v65, v92
	v_mul_f32_e32 v96, v2, v92
	v_cvt_pk_bf16_f32 v24, v50, v51
	v_cvt_pk_bf16_f32 v25, v52, v53
	global_store_dwordx4 v80, v[22:25], s[30:31]
	v_cvt_pk_bf16_f32 v2, v62, v63
	v_mul_f32_e32 v6, v6, v92
	v_mul_f32_e32 v7, v7, v92
	v_mul_f32_e32 v22, v3, v92
	v_mul_f32_e32 v23, v4, v92
	v_cvt_pk_bf16_f32 v3, v64, v65
	v_cvt_pk_bf16_f32 v4, v96, v22
	v_cvt_pk_bf16_f32 v5, v23, v5
	global_store_dwordx4 v81, v[2:5], s[30:31]
	v_mul_f32_e32 v8, v8, v92
	v_mul_f32_e32 v9, v9, v92
	v_mul_f32_e32 v2, v14, v92
	v_mul_f32_e32 v3, v15, v92
	v_mul_f32_e32 v4, v16, v92
	v_mul_f32_e32 v5, v17, v92
	v_cvt_pk_bf16_f32 v2, v2, v3
	v_cvt_pk_bf16_f32 v3, v4, v5
	v_cvt_pk_bf16_f32 v4, v6, v7
	v_cvt_pk_bf16_f32 v5, v8, v9
	global_store_dwordx4 v82, v[2:5], s[30:31]
	v_mul_f32_e32 v6, v10, v92
	v_mul_f32_e32 v7, v11, v92
	v_mul_f32_e32 v2, v18, v92
	v_mul_f32_e32 v3, v19, v92
	v_mul_f32_e32 v4, v20, v92
	v_mul_f32_e32 v5, v21, v92
	v_mul_f32_e32 v8, v12, v92
	v_mul_f32_e32 v9, v13, v92
	v_cvt_pk_bf16_f32 v2, v2, v3
	v_cvt_pk_bf16_f32 v3, v4, v5
	v_cvt_pk_bf16_f32 v4, v6, v7
	v_cvt_pk_bf16_f32 v5, v8, v9
.LBB0_298:
	s_andn2_b64 vcc, exec, s[2:3]
	s_cbranch_vccnz .LBB0_295
	global_load_dwordx4 v[18:21], v[72:73], off
	global_load_dwordx4 v[10:13], v[72:73], off offset:16
	global_load_dwordx4 v[6:9], v[72:73], off offset:2048
	global_load_dwordx4 v[2:5], v[72:73], off offset:2064
	v_add_co_u32_e32 v38, vcc, s43, v72
	v_lshl_add_u64 v[14:15], v[72:73], 0, s[18:19]
	s_nop 0
	v_addc_co_u32_e32 v39, vcc, 0, v73, vcc
	global_load_dwordx4 v[22:25], v[38:39], off offset:-4096
	v_add_co_u32_e32 v26, vcc, s41, v72
	global_load_dwordx4 v[14:17], v[14:15], off offset:16
	s_nop 0
	v_addc_co_u32_e32 v27, vcc, 0, v73, vcc
	global_load_dwordx4 v[34:37], v[26:27], off offset:2048
	v_lshl_add_u64 v[26:27], v[72:73], 0, s[20:21]
	global_load_dwordx4 v[26:29], v[26:27], off offset:16
	s_nop 0
	global_load_dwordx4 v[42:45], v[38:39], off
	v_lshl_add_u64 v[30:31], v[72:73], 0, s[22:23]
	global_load_dwordx4 v[30:33], v[30:31], off offset:16
	s_nop 0
	global_load_dwordx4 v[46:49], v[38:39], off offset:2048
	v_lshl_add_u64 v[38:39], v[72:73], 0, s[24:25]
	global_load_dwordx4 v[38:41], v[38:39], off offset:16
	v_add_co_u32_e32 v54, vcc, s44, v72
	v_lshl_add_u64 v[50:51], v[72:73], 0, s[26:27]
	s_nop 0
	v_addc_co_u32_e32 v55, vcc, 0, v73, vcc
	global_load_dwordx4 v[58:61], v[54:55], off
	s_nop 0
	global_load_dwordx4 v[50:53], v[50:51], off offset:16
	s_nop 0
	global_load_dwordx4 v[62:65], v[54:55], off offset:2048
	v_lshl_add_u64 v[54:55], v[72:73], 0, s[28:29]
	global_load_dwordx4 v[54:57], v[54:55], off offset:16
	v_cmp_lt_i32_e32 vcc, v86, v85
	s_waitcnt vmcnt(15) lgkmcnt(0)
	v_mul_f32_e32 v93, v19, v19
	v_fmac_f32_e32 v93, v18, v18
	v_fmac_f32_e32 v93, v20, v20
	v_fmac_f32_e32 v93, v21, v21
	s_waitcnt vmcnt(14)
	v_fmac_f32_e32 v93, v10, v10
	v_fmac_f32_e32 v93, v11, v11
	v_fmac_f32_e32 v93, v12, v12
	v_fmac_f32_e32 v93, v13, v13
	s_waitcnt vmcnt(13)
	v_fmac_f32_e32 v93, v6, v6
	v_fmac_f32_e32 v93, v7, v7
	v_fmac_f32_e32 v93, v8, v8
	v_fmac_f32_e32 v93, v9, v9
	s_waitcnt vmcnt(12)
	v_fmac_f32_e32 v93, v2, v2
	v_fmac_f32_e32 v93, v3, v3
	v_fmac_f32_e32 v93, v4, v4
	v_fmac_f32_e32 v93, v5, v5
	s_waitcnt vmcnt(11)
	v_fmac_f32_e32 v93, v22, v22
	v_fmac_f32_e32 v93, v23, v23
	v_fmac_f32_e32 v93, v24, v24
	v_fmac_f32_e32 v93, v25, v25
	s_waitcnt vmcnt(10)
	v_fmac_f32_e32 v93, v14, v14
	v_fmac_f32_e32 v93, v15, v15
	v_fmac_f32_e32 v93, v16, v16
	v_fmac_f32_e32 v93, v17, v17
	s_waitcnt vmcnt(9)
	v_fmac_f32_e32 v93, v34, v34
	v_fmac_f32_e32 v93, v35, v35
	v_fmac_f32_e32 v93, v36, v36
	v_fmac_f32_e32 v93, v37, v37
	s_waitcnt vmcnt(8)
	v_fmac_f32_e32 v93, v26, v26
	v_fmac_f32_e32 v93, v27, v27
	v_fmac_f32_e32 v93, v28, v28
	v_fmac_f32_e32 v93, v29, v29
	s_waitcnt vmcnt(7)
	v_fmac_f32_e32 v93, v42, v42
	v_fmac_f32_e32 v93, v43, v43
	v_fmac_f32_e32 v93, v44, v44
	v_fmac_f32_e32 v93, v45, v45
	s_waitcnt vmcnt(6)
	v_fmac_f32_e32 v93, v30, v30
	v_fmac_f32_e32 v93, v31, v31
	v_fmac_f32_e32 v93, v32, v32
	v_fmac_f32_e32 v93, v33, v33
	s_waitcnt vmcnt(5)
	v_fmac_f32_e32 v93, v46, v46
	v_fmac_f32_e32 v93, v47, v47
	v_fmac_f32_e32 v93, v48, v48
	v_fmac_f32_e32 v93, v49, v49
	s_waitcnt vmcnt(4)
	v_fmac_f32_e32 v93, v38, v38
	v_fmac_f32_e32 v93, v39, v39
	v_fmac_f32_e32 v93, v40, v40
	v_fmac_f32_e32 v93, v41, v41
	s_waitcnt vmcnt(3)
	v_fmac_f32_e32 v93, v58, v58
	v_fmac_f32_e32 v93, v59, v59
	v_fmac_f32_e32 v93, v60, v60
	v_fmac_f32_e32 v93, v61, v61
	s_waitcnt vmcnt(2)
	v_fmac_f32_e32 v93, v50, v50
	v_fmac_f32_e32 v93, v51, v51
	v_fmac_f32_e32 v93, v52, v52
	v_fmac_f32_e32 v93, v53, v53
	s_waitcnt vmcnt(1)
	v_fmac_f32_e32 v93, v62, v62
	v_fmac_f32_e32 v93, v63, v63
	v_fmac_f32_e32 v93, v64, v64
	v_fmac_f32_e32 v93, v65, v65
	s_waitcnt vmcnt(0)
	v_fmac_f32_e32 v93, v54, v54
	v_fmac_f32_e32 v93, v55, v55
	v_cndmask_b32_e32 v92, v84, v86, vcc
	v_fmac_f32_e32 v93, v56, v56
	v_lshlrev_b32_e32 v92, 2, v92
	v_fmac_f32_e32 v93, v57, v57
	ds_bpermute_b32 v92, v92, v93
	v_cmp_lt_i32_e32 vcc, v87, v85
	s_waitcnt lgkmcnt(0)
	v_add_f32_e32 v92, v93, v92
	v_cndmask_b32_e32 v94, v84, v87, vcc
	v_lshlrev_b32_e32 v94, 2, v94
	v_cmp_lt_i32_e32 vcc, v88, v85
	s_waitcnt lgkmcnt(0)
	s_nop 1
	v_add_f32_dpp v92, v92, v92 quad_perm:[2,3,0,1] row_mask:0xf bank_mask:0xf
	v_cndmask_b32_e32 v94, v84, v88, vcc
	v_lshlrev_b32_e32 v94, 2, v94
	ds_bpermute_b32 v93, v94, v92
	v_cmp_lt_i32_e32 vcc, v89, v85
	s_waitcnt lgkmcnt(0)
	v_add_f32_e32 v92, v92, v93
	v_cndmask_b32_e32 v94, v84, v89, vcc
	v_lshlrev_b32_e32 v94, 2, v94
	ds_bpermute_b32 v93, v94, v92
	v_cmp_lt_i32_e32 vcc, v90, v85
	s_waitcnt lgkmcnt(0)
	v_add_f32_e32 v92, v92, v93
	v_cndmask_b32_e32 v94, v84, v90, vcc
	v_lshlrev_b32_e32 v94, 2, v94
	v_cmp_lt_i32_e32 vcc, v91, v85
	s_waitcnt lgkmcnt(0)
	v_mov_b32_e32 v93, v92
	s_nop 1
	v_permlane16_swap_b32_e32 v93, v92
	v_add_f32_e32 v92, v92, v93
	v_cndmask_b32_e32 v94, v84, v91, vcc
	v_lshlrev_b32_e32 v93, 2, v94
	ds_bpermute_b32 v93, v93, v92
	s_and_saveexec_b64 s[30:31], s[0:1]
	s_cbranch_execz .LBB0_294
	s_waitcnt lgkmcnt(0)
	v_add_f32_e32 v92, v92, v93
	v_fmamk_f32 v92, v92, 0x39800000, v77
	v_mul_f32_e32 v93, 0x4f800000, v92
	v_cmp_gt_f32_e32 vcc, s39, v92
	s_nop 1
	v_cndmask_b32_e32 v92, v92, v93, vcc
	v_sqrt_f32_e32 v93, v92
	s_nop 0
	v_add_u32_e32 v94, -1, v93
	v_fma_f32 v96, -v94, v93, v92
	v_add_u32_e32 v95, 1, v93
	v_cmp_ge_f32_e64 s[2:3], 0, v96
	s_nop 1
	v_cndmask_b32_e64 v94, v93, v94, s[2:3]
	v_fma_f32 v93, -v95, v93, v92
	v_cmp_lt_f32_e64 s[2:3], 0, v93
	s_nop 1
	v_cndmask_b32_e64 v93, v94, v95, s[2:3]
	v_mul_f32_e32 v94, 0x37800000, v93
	v_cndmask_b32_e32 v93, v93, v94, vcc
	v_cmp_class_f32_e32 vcc, v92, v78
	s_nop 1
	v_cndmask_b32_e32 v92, v93, v92, vcc
	v_div_scale_f32 v93, s[2:3], v92, v92, 1.0
	v_rcp_f32_e32 v94, v93
	s_add_u32 s2, s8, s36
	s_addc_u32 s3, s9, s37
	v_fma_f32 v95, -v93, v94, 1.0
	v_fmac_f32_e32 v94, v95, v94
	v_div_scale_f32 v95, vcc, 1.0, v92, 1.0
	v_mul_f32_e32 v96, v95, v94
	v_fma_f32 v97, -v93, v96, v95
	v_fmac_f32_e32 v96, v97, v94
	v_fma_f32 v93, -v93, v96, v95
	v_div_fmas_f32 v93, v93, v94, v96
	v_div_fixup_f32 v92, v93, v92, 1.0
	global_store_dword v67, v92, s[2:3]
	s_branch .LBB0_294
.LBB0_301:
	s_load_dwordx2 s[0:1], s[94:95], 0xc8
	s_mov_b32 s41, s92
	s_waitcnt vmcnt(0)
	s_waitcnt lgkmcnt(0)
	s_add_u32 s77, s0, 0x4000
	s_addc_u32 s80, s1, 0
	s_barrier
	s_mov_b64 s[0:1], exec
	v_readlane_b32 s2, v252, 5
	v_readlane_b32 s3, v252, 6
	s_and_b64 s[2:3], s[0:1], s[2:3]
	s_xor_b64 s[0:1], s[2:3], s[0:1]
	s_mov_b64 exec, s[2:3]
	s_cbranch_execz .LBB0_354
	s_add_i32 s2, 0, 0x20160
	v_mov_b32_e32 v1, s2
	s_waitcnt vmcnt(0) expcnt(0) lgkmcnt(0)
	ds_read_b32 v3, v1
	s_add_i32 s2, 0, 0x20164
	v_mov_b32_e32 v1, s2
	ds_read_b32 v1, v1
	s_waitcnt lgkmcnt(0)
	v_cmp_ne_u32_e32 vcc, 0, v3
	s_cbranch_vccnz .LBB0_317
	v_readlane_b32 s2, v252, 0
	v_readlane_b32 s3, v252, 1
	s_load_dwordx2 s[6:7], s[2:3], 0x4
	s_load_dwordx2 s[36:37], s[94:95], 0xc8
	s_mov_b32 s48, 1
	v_mov_b32_e32 v17, 0
	s_waitcnt lgkmcnt(0)
	s_mul_i32 s43, s6, s64
	s_add_u32 s2, s36, 0x4200
	s_addc_u32 s3, s37, 0
	s_add_u32 s4, s36, 0x4400
	s_addc_u32 s5, s37, 0
	s_add_u32 s6, s36, 0x4500
	s_mul_i32 s43, s43, s7
	s_addc_u32 s7, s37, 0
	s_add_u32 s8, s36, 0x4600
	s_addc_u32 s9, s37, 0
	s_add_u32 s10, s36, 0x4700
	s_addc_u32 s11, s37, 0
	s_add_u32 s12, s36, 0x4800
	s_addc_u32 s13, s37, 0
	s_add_u32 s14, s36, 0x4900
	s_addc_u32 s15, s37, 0
	s_add_u32 s16, s36, 0x4a00
	s_addc_u32 s17, s37, 0
	s_add_u32 s18, s36, 0x4b00
	s_addc_u32 s19, s37, 0
	s_add_u32 s20, s36, 0x4c00
	s_addc_u32 s21, s37, 0
	s_add_u32 s22, s36, 0x4d00
	s_addc_u32 s23, s37, 0
	s_add_u32 s24, s36, 0x4e00
	s_addc_u32 s25, s37, 0
	s_add_u32 s26, s36, 0x4f00
	s_addc_u32 s27, s37, 0
	s_add_u32 s28, s36, 0x5000
	s_addc_u32 s29, s37, 0
	s_add_u32 s30, s36, 0x5100
	s_addc_u32 s31, s37, 0
	s_add_u32 s34, s36, 0x5200
	s_addc_u32 s35, s37, 0
	s_add_u32 s36, s36, 0x5300
	s_addc_u32 s37, s37, 0
	s_branch .LBB0_305

.LBB0_601:
	s_ashr_i32 s0, s25, 6
	s_add_i32 s2, s0, s81
	s_cmp_gt_i32 s2, 31
	s_cbranch_scc1 .LBB0_603
	s_ashr_i32 s3, s2, 31
	s_lshl_b64 s[0:1], s[2:3], 15
	v_and_b32_e32 v1, 63, v1
	s_waitcnt lgkmcnt(0)
	s_add_u32 s0, s14, s0
	s_waitcnt vmcnt(3)
	v_mov_b32_e32 v67, 0
	s_addc_u32 s1, s15, s1
	v_lshlrev_b32_e32 v66, 4, v1
	v_lshl_add_u64 v[68:69], s[0:1], 0, v[66:67]
	s_mov_b64 s[0:1], 0x69984000
	v_lshl_add_u64 v[2:3], v[68:69], 0, s[0:1]
	s_mov_b32 s1, 0x69986000
	v_add_co_u32_e32 v4, vcc, s1, v68
	s_mov_b32 s0, 0x69985000
	s_nop 0
	v_addc_co_u32_e32 v5, vcc, 0, v69, vcc
	v_add_co_u32_e32 v6, vcc, s0, v68
	global_load_dwordx4 v[58:61], v[2:3], off offset:1024
	global_load_dwordx4 v[50:53], v[2:3], off offset:2048
	v_addc_co_u32_e32 v7, vcc, 0, v69, vcc
	global_load_dwordx4 v[46:49], v[4:5], off offset:-4096
	global_load_dwordx4 v[42:45], v[6:7], off offset:1024
	global_load_dwordx4 v[38:41], v[6:7], off offset:2048
	global_load_dwordx4 v[34:37], v[6:7], off offset:3072
	v_add_co_u32_e32 v6, vcc, 0x69984000, v68
	global_load_dwordx4 v[30:33], v[4:5], off
	global_load_dwordx4 v[26:29], v[4:5], off offset:1024
	v_addc_co_u32_e32 v7, vcc, 0, v69, vcc
	global_load_dwordx4 v[62:65], v[6:7], off
	global_load_dwordx4 v[54:57], v[2:3], off offset:3072
	global_load_dwordx4 v[22:25], v[4:5], off offset:2048
	s_mov_b32 s0, 0x69987000
	global_load_dwordx4 v[18:21], v[4:5], off offset:3072
	v_add_co_u32_e32 v70, vcc, s0, v68
	s_mov_b32 s0, 0xf800000
	s_nop 0
	v_addc_co_u32_e32 v71, vcc, 0, v69, vcc
	global_load_dwordx4 v[14:17], v[70:71], off
	global_load_dwordx4 v[10:13], v[70:71], off offset:1024
	global_load_dwordx4 v[6:9], v[70:71], off offset:2048
	global_load_dwordx4 v[2:5], v[70:71], off offset:3072
	s_waitcnt vmcnt(15)
	v_mov_b32_e32 v70, v59
	v_mov_b32_e32 v71, v60
	v_mov_b32_e32 v72, v58
	v_mov_b32_e32 v73, v61
	s_waitcnt vmcnt(13)
	v_mov_b32_e32 v78, v47
	v_mov_b32_e32 v79, v48
	v_mov_b32_e32 v80, v46
	v_mov_b32_e32 v81, v49
	s_waitcnt vmcnt(12)
	v_add_f32_e32 v82, v42, v43
	v_add_f32_e32 v84, v44, v45
	s_waitcnt vmcnt(11)
	v_mov_b32_e32 v83, v40
	v_mov_b32_e32 v85, v41
	s_waitcnt vmcnt(10)
	v_mov_b32_e32 v86, v35
	v_mov_b32_e32 v87, v36
	v_mov_b32_e32 v88, v34
	v_mov_b32_e32 v89, v37
	s_waitcnt vmcnt(7)
	v_mov_b32_e32 v94, v63
	v_mov_b32_e32 v95, v64
	v_mov_b32_e32 v96, v62
	v_mov_b32_e32 v97, v65
	v_pk_add_f32 v[70:71], v[70:71], v[72:73]
	v_pk_add_f32 v[78:79], v[78:79], v[80:81]
	v_pk_add_f32 v[80:81], v[82:83], v[84:85]
	v_pk_add_f32 v[82:83], v[86:87], v[88:89]
	v_pk_add_f32 v[86:87], v[94:95], v[96:97]
	v_pk_add_f32 v[70:71], v[70:71], v[70:71] op_sel:[0,1] op_sel_hi:[1,0]
	v_add_f32_e32 v72, v86, v87
	v_add_f32_e32 v74, v50, v51
	v_add_f32_e32 v76, v52, v53
	s_waitcnt vmcnt(6)
	v_mov_b32_e32 v73, v54
	v_mov_b32_e32 v75, v56
	v_mov_b32_e32 v77, v57
	v_mov_b32_e32 v71, v55
	v_add_f32_e32 v72, 0, v72
	v_pk_add_f32 v[74:75], v[74:75], v[76:77]
	v_pk_add_f32 v[70:71], v[72:73], v[70:71]
	v_pk_add_f32 v[76:77], v[78:79], v[78:79] op_sel:[0,1] op_sel_hi:[1,0]
	v_pk_add_f32 v[70:71], v[70:71], v[74:75]
	v_mov_b32_e32 v77, v39
	v_pk_add_f32 v[70:71], v[70:71], v[70:71] op_sel:[0,1] op_sel_hi:[1,0]
	v_pk_add_f32 v[78:79], v[82:83], v[82:83] op_sel:[0,1] op_sel_hi:[1,0]
	v_mov_b32_e32 v71, v38
	v_pk_add_f32 v[70:71], v[70:71], v[76:77]
	v_add_f32_e32 v90, v30, v31
	v_pk_add_f32 v[70:71], v[70:71], v[80:81]
	v_add_f32_e32 v92, v32, v33
	v_pk_add_f32 v[70:71], v[70:71], v[70:71] op_sel:[0,1] op_sel_hi:[1,0]
	v_mov_b32_e32 v91, v28
	v_mov_b32_e32 v93, v29
	v_mov_b32_e32 v79, v27
	v_mov_b32_e32 v71, v26
	v_pk_add_f32 v[84:85], v[90:91], v[92:93]
	v_pk_add_f32 v[70:71], v[70:71], v[78:79]
	s_waitcnt vmcnt(5)
	v_mov_b32_e32 v72, v23
	v_mov_b32_e32 v73, v24
	v_mov_b32_e32 v74, v22
	v_mov_b32_e32 v75, v25
	v_pk_add_f32 v[70:71], v[70:71], v[84:85]
	v_pk_add_f32 v[72:73], v[72:73], v[74:75]
	v_pk_add_f32 v[70:71], v[70:71], v[70:71] op_sel:[0,1] op_sel_hi:[1,0]
	v_pk_add_f32 v[72:73], v[72:73], v[72:73] op_sel:[0,1] op_sel_hi:[1,0]
	s_waitcnt vmcnt(4)
	v_add_f32_e32 v74, v18, v19
	v_add_f32_e32 v76, v20, v21
	s_waitcnt vmcnt(3)
	v_mov_b32_e32 v71, v14
	v_mov_b32_e32 v73, v15
	v_mov_b32_e32 v75, v16
	v_mov_b32_e32 v77, v17
	v_pk_add_f32 v[70:71], v[70:71], v[72:73]
	v_pk_add_f32 v[72:73], v[74:75], v[76:77]
	s_waitcnt vmcnt(2)
	v_mov_b32_e32 v74, v10
	v_pk_add_f32 v[70:71], v[70:71], v[72:73]
	v_mov_b32_e32 v72, v11
	v_mov_b32_e32 v73, v12
	v_mov_b32_e32 v75, v13
	v_pk_add_f32 v[72:73], v[72:73], v[74:75]
	v_pk_add_f32 v[70:71], v[70:71], v[70:71] op_sel:[0,1] op_sel_hi:[1,0]
	v_pk_add_f32 v[72:73], v[72:73], v[72:73] op_sel:[0,1] op_sel_hi:[1,0]
	s_waitcnt vmcnt(1)
	v_add_f32_e32 v74, v6, v7
	v_add_f32_e32 v76, v8, v9
	s_waitcnt vmcnt(0)
	v_mov_b32_e32 v71, v2
	v_mov_b32_e32 v73, v3
	v_mov_b32_e32 v75, v4
	v_mov_b32_e32 v77, v5
	v_pk_add_f32 v[70:71], v[70:71], v[72:73]
	v_pk_add_f32 v[72:73], v[74:75], v[76:77]
	s_nop 0
	v_pk_add_f32 v[70:71], v[70:71], v[72:73]
	s_nop 0
	v_add_f32_e32 v70, v70, v71
	v_mbcnt_hi_u32_b32 v71, -1, v234
	v_and_b32_e32 v72, 64, v71
	v_add_u32_e32 v72, 64, v72
	v_xor_b32_e32 v73, 1, v71
	v_cmp_lt_i32_e32 vcc, v73, v72
	s_nop 1
	v_cndmask_b32_e32 v73, v71, v73, vcc
	v_lshlrev_b32_e32 v78, 2, v73
	s_waitcnt lgkmcnt(0)
	s_nop 1
	v_add_f32_dpp v70, v70, v70 quad_perm:[1,0,3,2] row_mask:0xf bank_mask:0xf
	v_xor_b32_e32 v73, 2, v71
	v_cmp_lt_i32_e32 vcc, v73, v72
	s_nop 1
	v_cndmask_b32_e32 v73, v71, v73, vcc
	v_lshlrev_b32_e32 v84, 2, v73
	s_waitcnt lgkmcnt(0)
	s_nop 1
	v_add_f32_dpp v70, v70, v70 quad_perm:[2,3,0,1] row_mask:0xf bank_mask:0xf
	v_xor_b32_e32 v73, 4, v71
	v_cmp_lt_i32_e32 vcc, v73, v72
	s_nop 1
	v_cndmask_b32_e32 v73, v71, v73, vcc
	v_lshlrev_b32_e32 v85, 2, v73
	s_waitcnt lgkmcnt(0)
	s_nop 1
	v_add_f32_dpp v70, v70, v70 row_half_mirror row_mask:0xf bank_mask:0xf
	v_xor_b32_e32 v73, 8, v71
	v_cmp_lt_i32_e32 vcc, v73, v72
	s_nop 1
	v_cndmask_b32_e32 v73, v71, v73, vcc
	v_lshlrev_b32_e32 v86, 2, v73
	s_waitcnt lgkmcnt(0)
	s_nop 1
	v_add_f32_dpp v70, v70, v70 row_mirror row_mask:0xf bank_mask:0xf
	v_xor_b32_e32 v73, 16, v71
	v_cmp_lt_i32_e32 vcc, v73, v72
	s_nop 1
	v_cndmask_b32_e32 v73, v71, v73, vcc
	v_lshlrev_b32_e32 v87, 2, v73
	s_waitcnt lgkmcnt(0)
	v_mov_b32_e32 v73, v70
	s_nop 1
	v_permlane16_swap_b32_e32 v73, v70
	v_add_f32_e32 v70, v70, v73
	v_xor_b32_e32 v73, 32, v71
	v_cmp_lt_i32_e32 vcc, v73, v72
	s_nop 1
	v_cndmask_b32_e32 v71, v71, v73, vcc
	v_lshlrev_b32_e32 v88, 2, v71
	s_waitcnt lgkmcnt(0)
	v_mov_b32_e32 v79, v70
	v_mov_b32_e32 v71, v70
	s_nop 1
	v_permlane32_swap_b32_e32 v71, v79
	v_add_f32_e32 v79, v79, v71
	v_fmamk_f32 v75, v79, 0xb9800000, v63
	v_fmamk_f32 v74, v79, 0xb9800000, v62
	v_fmamk_f32 v65, v79, 0xb9800000, v65
	v_fmac_f32_e32 v64, 0xb9800000, v79
	v_pk_mul_f32 v[62:63], v[64:65], v[64:65]
	v_pk_mul_f32 v[70:71], v[74:75], v[74:75]
	v_fmamk_f32 v61, v79, 0xb9800000, v61
	v_pk_mov_b32 v[72:73], v[70:71], v[62:63] op_sel:[1,0]
	v_mov_b32_e32 v71, v63
	v_pk_add_f32 v[62:63], v[72:73], v[70:71]
	v_fmamk_f32 v73, v79, 0xb9800000, v59
	v_fmamk_f32 v72, v79, 0xb9800000, v58
	v_fmac_f32_e32 v60, 0xb9800000, v79
	v_pk_mul_f32 v[58:59], v[60:61], v[60:61]
	v_pk_mul_f32 v[70:71], v[72:73], v[72:73]
	v_fmac_f32_e32 v54, 0xb9800000, v79
	v_pk_mov_b32 v[76:77], v[70:71], v[58:59] op_sel:[1,0]
	v_mov_b32_e32 v71, v59
	v_pk_add_f32 v[76:77], v[76:77], v[70:71]
	v_fmamk_f32 v71, v79, 0xb9800000, v51
	v_fmamk_f32 v70, v79, 0xb9800000, v50
	v_fmamk_f32 v58, v79, 0xb9800000, v56
	v_fmamk_f32 v55, v79, 0xb9800000, v55
	v_mul_f32_e32 v56, v54, v54
	v_pk_add_f32 v[50:51], v[62:63], v[62:63] op_sel:[0,1] op_sel_hi:[1,0]
	v_fmamk_f32 v59, v79, 0xb9800000, v57
	v_mul_f32_e32 v80, v55, v55
	v_mov_b32_e32 v51, v56
	v_pk_add_f32 v[56:57], v[76:77], v[76:77] op_sel:[0,1] op_sel_hi:[1,0]
	v_fmamk_f32 v53, v79, 0xb9800000, v53
	v_mov_b32_e32 v57, v80
	v_fmac_f32_e32 v52, 0xb9800000, v79
	v_pk_add_f32 v[50:51], v[50:51], v[56:57]
	v_mul_f32_e32 v56, v71, v71
	v_mul_f32_e32 v62, v53, v53
	v_mul_f32_e32 v81, v58, v58
	v_mul_f32_e32 v82, v59, v59
	v_pk_fma_f32 v[56:57], v[70:71], v[70:71], v[56:57] op_sel_hi:[1,1,0]
	v_pk_fma_f32 v[62:63], v[52:53], v[52:53], v[62:63] op_sel_hi:[1,1,0]
	v_mov_b32_e32 v57, v81
	v_mov_b32_e32 v63, v82
	v_pk_add_f32 v[56:57], v[56:57], v[62:63]
	v_fmamk_f32 v49, v79, 0xb9800000, v49
	v_pk_add_f32 v[62:63], v[50:51], v[56:57]
	v_fmamk_f32 v57, v79, 0xb9800000, v47
	v_fmamk_f32 v56, v79, 0xb9800000, v46
	v_fmac_f32_e32 v48, 0xb9800000, v79
	v_pk_mul_f32 v[46:47], v[48:49], v[48:49]
	v_pk_mul_f32 v[50:51], v[56:57], v[56:57]
	v_fmac_f32_e32 v38, 0xb9800000, v79
	v_pk_mov_b32 v[76:77], v[50:51], v[46:47] op_sel:[1,0]
	v_mov_b32_e32 v51, v47
	v_pk_add_f32 v[76:77], v[76:77], v[50:51]
	v_fmamk_f32 v50, v79, 0xb9800000, v42
	v_fmamk_f32 v47, v79, 0xb9800000, v41
	v_fmamk_f32 v46, v79, 0xb9800000, v40
	v_fmamk_f32 v39, v79, 0xb9800000, v39
	v_mul_f32_e32 v42, v38, v38
	v_pk_add_f32 v[40:41], v[62:63], v[62:63] op_sel:[0,1] op_sel_hi:[1,0]
	v_fmamk_f32 v51, v79, 0xb9800000, v43
	v_mul_f32_e32 v80, v39, v39
	v_mov_b32_e32 v41, v42
	v_pk_add_f32 v[42:43], v[76:77], v[76:77] op_sel:[0,1] op_sel_hi:[1,0]
	v_fmamk_f32 v45, v79, 0xb9800000, v45
	v_mov_b32_e32 v43, v80
	v_fmac_f32_e32 v44, 0xb9800000, v79
	v_pk_add_f32 v[40:41], v[40:41], v[42:43]
	v_mul_f32_e32 v42, v51, v51
	v_mul_f32_e32 v62, v45, v45
	v_mul_f32_e32 v81, v46, v46
	v_mul_f32_e32 v82, v47, v47
	v_pk_fma_f32 v[42:43], v[50:51], v[50:51], v[42:43] op_sel_hi:[1,1,0]
	v_pk_fma_f32 v[62:63], v[44:45], v[44:45], v[62:63] op_sel_hi:[1,1,0]
	v_mov_b32_e32 v43, v81
	v_mov_b32_e32 v63, v82
	v_pk_add_f32 v[42:43], v[42:43], v[62:63]
	v_fmamk_f32 v37, v79, 0xb9800000, v37
	v_pk_add_f32 v[62:63], v[40:41], v[42:43]
	v_fmamk_f32 v43, v79, 0xb9800000, v35
	v_fmamk_f32 v42, v79, 0xb9800000, v34
	v_fmac_f32_e32 v36, 0xb9800000, v79
	v_pk_mul_f32 v[34:35], v[36:37], v[36:37]
	v_pk_mul_f32 v[40:41], v[42:43], v[42:43]
	v_fmac_f32_e32 v26, 0xb9800000, v79
	v_pk_mov_b32 v[76:77], v[40:41], v[34:35] op_sel:[1,0]
	v_mov_b32_e32 v41, v35
	v_pk_add_f32 v[76:77], v[76:77], v[40:41]
	v_fmamk_f32 v40, v79, 0xb9800000, v30
	v_fmamk_f32 v35, v79, 0xb9800000, v29
	v_fmamk_f32 v34, v79, 0xb9800000, v28
	v_fmamk_f32 v27, v79, 0xb9800000, v27
	v_mul_f32_e32 v30, v26, v26
	v_pk_add_f32 v[28:29], v[62:63], v[62:63] op_sel:[0,1] op_sel_hi:[1,0]
	v_fmamk_f32 v41, v79, 0xb9800000, v31
	v_mul_f32_e32 v80, v27, v27
	v_mov_b32_e32 v29, v30
	v_pk_add_f32 v[30:31], v[76:77], v[76:77] op_sel:[0,1] op_sel_hi:[1,0]
	v_fmamk_f32 v33, v79, 0xb9800000, v33
	v_mov_b32_e32 v31, v80
	v_fmac_f32_e32 v32, 0xb9800000, v79
	v_pk_add_f32 v[28:29], v[28:29], v[30:31]
	v_mul_f32_e32 v30, v41, v41
	v_mul_f32_e32 v62, v33, v33
	v_mul_f32_e32 v81, v34, v34
	v_mul_f32_e32 v82, v35, v35
	v_pk_fma_f32 v[30:31], v[40:41], v[40:41], v[30:31] op_sel_hi:[1,1,0]
	v_pk_fma_f32 v[62:63], v[32:33], v[32:33], v[62:63] op_sel_hi:[1,1,0]
	v_mov_b32_e32 v31, v81
	v_mov_b32_e32 v63, v82
	v_pk_add_f32 v[30:31], v[30:31], v[62:63]
	v_fmamk_f32 v25, v79, 0xb9800000, v25
	v_pk_add_f32 v[28:29], v[28:29], v[30:31]
	v_fmamk_f32 v31, v79, 0xb9800000, v23
	v_fmamk_f32 v30, v79, 0xb9800000, v22
	v_fmac_f32_e32 v24, 0xb9800000, v79
	v_pk_mul_f32 v[22:23], v[24:25], v[24:25]
	v_pk_mul_f32 v[62:63], v[30:31], v[30:31]
	v_fmamk_f32 v15, v79, 0xb9800000, v15
	v_pk_mov_b32 v[76:77], v[62:63], v[22:23] op_sel:[1,0]
	v_mov_b32_e32 v63, v23
	v_pk_add_f32 v[62:63], v[76:77], v[62:63]
	v_fmac_f32_e32 v14, 0xb9800000, v79
	v_fmamk_f32 v23, v79, 0xb9800000, v19
	v_fmamk_f32 v22, v79, 0xb9800000, v18
	v_mul_f32_e32 v76, v14, v14
	v_mul_f32_e32 v77, v15, v15
	v_pk_add_f32 v[18:19], v[28:29], v[28:29] op_sel:[0,1] op_sel_hi:[1,0]
	v_pk_add_f32 v[28:29], v[62:63], v[62:63] op_sel:[0,1] op_sel_hi:[1,0]
	v_fmamk_f32 v21, v79, 0xb9800000, v21
	v_mov_b32_e32 v19, v76
	v_mov_b32_e32 v29, v77
	v_fmac_f32_e32 v20, 0xb9800000, v79
	v_fmamk_f32 v17, v79, 0xb9800000, v17
	v_fmamk_f32 v16, v79, 0xb9800000, v16
	v_pk_add_f32 v[18:19], v[18:19], v[28:29]
	v_mul_f32_e32 v28, v23, v23
	v_mul_f32_e32 v62, v21, v21
	v_mul_f32_e32 v80, v16, v16
	v_mul_f32_e32 v81, v17, v17
	v_pk_fma_f32 v[28:29], v[22:23], v[22:23], v[28:29] op_sel_hi:[1,1,0]
	v_pk_fma_f32 v[62:63], v[20:21], v[20:21], v[62:63] op_sel_hi:[1,1,0]
	v_mov_b32_e32 v29, v80
	v_mov_b32_e32 v63, v81
	v_pk_add_f32 v[28:29], v[28:29], v[62:63]
	v_fmamk_f32 v11, v79, 0xb9800000, v11
	v_fmamk_f32 v10, v79, 0xb9800000, v10
	v_fmamk_f32 v13, v79, 0xb9800000, v13
	v_fmac_f32_e32 v12, 0xb9800000, v79
	v_pk_add_f32 v[18:19], v[18:19], v[28:29]
	v_pk_mul_f32 v[28:29], v[12:13], v[12:13]
	v_pk_mul_f32 v[62:63], v[10:11], v[10:11]
	v_fmamk_f32 v3, v79, 0xb9800000, v3
	v_pk_mov_b32 v[76:77], v[62:63], v[28:29] op_sel:[1,0]
	v_mov_b32_e32 v63, v29
	v_pk_add_f32 v[28:29], v[76:77], v[62:63]
	v_fmac_f32_e32 v2, 0xb9800000, v79
	v_mul_f32_e32 v62, v2, v2
	v_mul_f32_e32 v63, v3, v3
	v_pk_add_f32 v[18:19], v[18:19], v[18:19] op_sel:[0,1] op_sel_hi:[1,0]
	v_pk_add_f32 v[28:29], v[28:29], v[28:29] op_sel:[0,1] op_sel_hi:[1,0]
	v_fmamk_f32 v7, v79, 0xb9800000, v7
	v_fmamk_f32 v9, v79, 0xb9800000, v9
	v_mov_b32_e32 v19, v62
	v_mov_b32_e32 v29, v63
	v_fmamk_f32 v6, v79, 0xb9800000, v6
	v_fmac_f32_e32 v8, 0xb9800000, v79
	v_fmamk_f32 v5, v79, 0xb9800000, v5
	v_fmamk_f32 v4, v79, 0xb9800000, v4
	v_pk_add_f32 v[18:19], v[18:19], v[28:29]
	v_mul_f32_e32 v28, v7, v7
	v_mul_f32_e32 v62, v9, v9
	v_mul_f32_e32 v76, v4, v4
	v_mul_f32_e32 v77, v5, v5
	v_pk_fma_f32 v[28:29], v[6:7], v[6:7], v[28:29] op_sel_hi:[1,1,0]
	v_pk_fma_f32 v[62:63], v[8:9], v[8:9], v[62:63] op_sel_hi:[1,1,0]
	v_mov_b32_e32 v29, v76
	v_mov_b32_e32 v63, v77
	v_pk_add_f32 v[28:29], v[28:29], v[62:63]
	s_nop 0
	v_pk_add_f32 v[18:19], v[18:19], v[28:29]
	s_nop 0
	v_add_f32_e32 v18, v18, v19
	global_load_dwordx4 v[76:79], v66, s[4:5]
	global_load_dwordx4 v[80:83], v66, s[6:7]
	s_waitcnt lgkmcnt(0)
	s_nop 1
	v_add_f32_dpp v18, v18, v18 quad_perm:[1,0,3,2] row_mask:0xf bank_mask:0xf
	s_waitcnt lgkmcnt(0)
	s_nop 1
	v_add_f32_dpp v18, v18, v18 quad_perm:[2,3,0,1] row_mask:0xf bank_mask:0xf
	s_waitcnt lgkmcnt(0)
	s_nop 1
	v_add_f32_dpp v18, v18, v18 row_half_mirror row_mask:0xf bank_mask:0xf
	v_lshlrev_b32_e32 v86, 3, v1
	v_mov_b32_e32 v1, 0x10000
	s_waitcnt lgkmcnt(0)
	s_nop 1
	v_add_f32_dpp v18, v18, v18 row_mirror row_mask:0xf bank_mask:0xf
	v_mov_b32_e32 v87, v67
	s_waitcnt lgkmcnt(0)
	v_mov_b32_e32 v19, v18
	s_nop 1
	v_permlane16_swap_b32_e32 v19, v18
	v_add_f32_e32 v18, v18, v19
	s_waitcnt lgkmcnt(0)
	v_mov_b32_e32 v19, v18
	s_nop 1
	v_permlane32_swap_b32_e32 v19, v18
	v_add_f32_e32 v18, v18, v19
	v_mov_b32_e32 v19, 0x358637bd
	v_fmac_f32_e32 v19, 0x39800000, v18
	v_mul_f32_e32 v18, 0x4f800000, v19
	v_cmp_gt_f32_e32 vcc, s0, v19
	s_nop 1
	v_cndmask_b32_e32 v18, v19, v18, vcc
	v_sqrt_f32_e32 v19, v18
	s_nop 0
	v_add_u32_e32 v28, -1, v19
	v_fma_f32 v29, -v28, v19, v18
	v_cmp_ge_f32_e64 s[0:1], 0, v29
	v_add_u32_e32 v29, 1, v19
	s_nop 0
	v_cndmask_b32_e64 v28, v19, v28, s[0:1]
	v_fma_f32 v19, -v29, v19, v18
	v_cmp_lt_f32_e64 s[0:1], 0, v19
	s_nop 1
	v_cndmask_b32_e64 v19, v28, v29, s[0:1]
	v_mul_f32_e32 v28, 0x37800000, v19
	v_cndmask_b32_e32 v19, v19, v28, vcc
	v_mov_b32_e32 v28, 0x260
	v_cmp_class_f32_e32 vcc, v18, v28
	s_nop 1
	v_cndmask_b32_e32 v18, v19, v18, vcc
	v_div_scale_f32 v19, s[0:1], v18, v18, 1.0
	v_rcp_f32_e32 v28, v19
	s_lshl_b64 s[0:1], s[2:3], 14
	s_add_u32 s0, s12, s0
	s_addc_u32 s1, s13, s1
	v_fma_f32 v29, -v19, v28, 1.0
	v_fmac_f32_e32 v28, v29, v28
	v_div_scale_f32 v29, vcc, 1.0, v18, 1.0
	v_mul_f32_e32 v62, v29, v28
	v_fma_f32 v63, -v19, v62, v29
	v_fmac_f32_e32 v62, v63, v28
	v_fma_f32 v19, -v19, v62, v29
	v_div_fmas_f32 v19, v19, v28, v62
	v_div_fixup_f32 v18, v19, v18, 1.0
	v_lshl_add_u64 v[62:63], s[0:1], 0, v[66:67]
	v_pk_mul_f32 v[64:65], v[18:19], v[64:65] op_sel_hi:[0,1]
	s_mov_b32 s0, 0x8881000
	v_pk_mul_f32 v[28:29], v[18:19], v[74:75] op_sel_hi:[0,1]
	s_waitcnt vmcnt(0)
	v_pk_fma_f32 v[78:79], v[78:79], v[64:65], v[82:83]
	v_add_co_u32_e32 v64, vcc, s0, v62
	v_pk_fma_f32 v[76:77], v[76:77], v[28:29], v[80:81]
	s_nop 0
	v_addc_co_u32_e32 v65, vcc, 0, v63, vcc
	s_mov_b32 s0, 0x69981000
	global_store_dwordx4 v[64:65], v[76:79], off offset:-4096
	v_add_co_u32_e32 v74, vcc, s0, v68
	global_load_dword v28, v67, s[8:9]
	global_load_dword v84, v67, s[10:11]
	v_addc_co_u32_e32 v75, vcc, 0, v69, vcc
	global_load_dwordx4 v[80:83], v[74:75], off offset:-4096
	s_lshl_b64 s[0:1], s[2:3], 13
	s_add_u32 s0, s14, s0
	s_addc_u32 s1, s15, s1
	v_lshl_add_u64 v[86:87], s[0:1], 0, v[86:87]
	s_mov_b32 s0, 0x69a81000
	s_mov_b64 s[2:3], 0x8880000
	v_pk_mul_f32 v[60:61], v[18:19], v[60:61] op_sel_hi:[0,1]
	v_pk_mul_f32 v[72:73], v[18:19], v[72:73] op_sel_hi:[0,1]
	v_pk_mul_f32 v[52:53], v[18:19], v[52:53] op_sel_hi:[0,1]
	v_pk_mul_f32 v[70:71], v[18:19], v[70:71] op_sel_hi:[0,1]
	v_pk_mul_f32 v[58:59], v[18:19], v[58:59] op_sel_hi:[0,1]
	v_pk_mul_f32 v[48:49], v[18:19], v[48:49] op_sel_hi:[0,1]
	v_pk_mul_f32 v[56:57], v[18:19], v[56:57] op_sel_hi:[0,1]
	v_pk_mul_f32 v[44:45], v[18:19], v[44:45] op_sel_hi:[0,1]
	v_pk_mul_f32 v[46:47], v[18:19], v[46:47] op_sel_hi:[0,1]
	v_pk_mul_f32 v[38:39], v[18:19], v[38:39] op_sel_hi:[0,1]
	s_waitcnt vmcnt(1)
	v_pk_fma_f32 v[76:77], v[76:77], v[28:29], v[84:85] op_sel_hi:[1,0,0]
	v_pk_fma_f32 v[28:29], v[78:79], v[28:29], v[84:85] op_sel_hi:[1,0,0]
	v_lshl_add_u64 v[84:85], v[62:63], 0, s[2:3]
	s_waitcnt vmcnt(0)
	v_pk_mul_f32 v[28:29], v[82:83], v[28:29]
	v_pk_mul_f32 v[76:77], v[80:81], v[76:77]
	s_nop 0
	v_cvt_pk_bf16_f32 v76, v76, v77
	v_cvt_pk_bf16_f32 v77, v28, v29
	v_add_co_u32_e32 v28, vcc, s0, v86
	s_mov_b64 s[0:1], 0x69980000
	s_nop 0
	v_addc_co_u32_e32 v29, vcc, 0, v87, vcc
	global_store_dwordx2 v[28:29], v[76:77], off offset:-4096
	global_load_dwordx4 v[76:79], v66, s[4:5] offset:1024
	s_nop 0
	global_load_dwordx4 v[80:83], v66, s[6:7] offset:1024
	v_lshl_add_u64 v[90:91], v[68:69], 0, s[0:1]
	s_mov_b64 s[0:1], 0x69a80000
	s_waitcnt vmcnt(0)
	v_pk_fma_f32 v[76:77], v[76:77], v[72:73], v[80:81]
	v_pk_fma_f32 v[78:79], v[78:79], v[60:61], v[82:83]
	global_store_dwordx4 v[84:85], v[76:79], off offset:1024
	global_load_dword v72, v1, s[8:9]
	global_load_dword v88, v67, s[10:11] offset:512
	global_load_dwordx4 v[80:83], v[90:91], off offset:1024
	v_lshl_add_u64 v[60:61], v[86:87], 0, s[0:1]
	v_mov_b32_e32 v1, 0x20000
	s_mov_b32 s0, 0x8883000
	s_mov_b32 s1, 0x69983000
	s_waitcnt vmcnt(1)
	v_pk_fma_f32 v[76:77], v[76:77], v[72:73], v[88:89] op_sel_hi:[1,0,0]
	v_pk_fma_f32 v[72:73], v[78:79], v[72:73], v[88:89] op_sel_hi:[1,0,0]
	s_waitcnt vmcnt(0)
	v_pk_mul_f32 v[76:77], v[80:81], v[76:77]
	v_pk_mul_f32 v[72:73], v[82:83], v[72:73]
	v_cvt_pk_bf16_f32 v76, v76, v77
	s_nop 0
	v_cvt_pk_bf16_f32 v77, v72, v73
	global_store_dwordx2 v[60:61], v[76:77], off offset:512
	global_load_dwordx4 v[76:79], v66, s[4:5] offset:2048
	s_nop 0
	global_load_dwordx4 v[80:83], v66, s[6:7] offset:2048
	s_waitcnt vmcnt(0)
	v_pk_fma_f32 v[70:71], v[76:77], v[70:71], v[80:81]
	v_pk_fma_f32 v[72:73], v[78:79], v[52:53], v[82:83]
	global_store_dwordx4 v[84:85], v[70:73], off offset:2048
	global_load_dword v52, v1, s[8:9]
	global_load_dword v80, v67, s[10:11] offset:1024
	global_load_dwordx4 v[76:79], v[90:91], off offset:2048
	v_mov_b32_e32 v1, 0x30000
	s_waitcnt vmcnt(1)
	v_pk_fma_f32 v[70:71], v[70:71], v[52:53], v[80:81] op_sel_hi:[1,0,0]
	v_pk_fma_f32 v[52:53], v[72:73], v[52:53], v[80:81] op_sel_hi:[1,0,0]
	s_waitcnt vmcnt(0)
	v_pk_mul_f32 v[70:71], v[76:77], v[70:71]
	v_pk_mul_f32 v[52:53], v[78:79], v[52:53]
	v_cvt_pk_bf16_f32 v70, v70, v71
	s_nop 0
	v_cvt_pk_bf16_f32 v71, v52, v53
	global_store_dwordx2 v[60:61], v[70:71], off offset:1024
	global_load_dwordx4 v[70:73], v66, s[4:5] offset:3072
	s_nop 0
	global_load_dwordx4 v[76:79], v66, s[6:7] offset:3072
	v_pk_mul_f32 v[52:53], v[18:19], v[54:55] op_sel_hi:[0,1]
	s_waitcnt vmcnt(0)
	v_pk_fma_f32 v[52:53], v[70:71], v[52:53], v[76:77]
	v_pk_fma_f32 v[54:55], v[72:73], v[58:59], v[78:79]
	global_store_dwordx4 v[84:85], v[52:55], off offset:3072
	global_load_dword v58, v1, s[8:9]
	global_load_dword v76, v67, s[10:11] offset:1536
	global_load_dwordx4 v[70:73], v[90:91], off offset:3072
	v_or_b32_e32 v1, 0x1000, v66
	s_waitcnt vmcnt(1)
	v_pk_fma_f32 v[52:53], v[52:53], v[58:59], v[76:77] op_sel_hi:[1,0,0]
	v_pk_fma_f32 v[54:55], v[54:55], v[58:59], v[76:77] op_sel_hi:[1,0,0]
	s_waitcnt vmcnt(0)
	v_pk_mul_f32 v[52:53], v[70:71], v[52:53]
	v_pk_mul_f32 v[54:55], v[72:73], v[54:55]
	v_cvt_pk_bf16_f32 v52, v52, v53
	s_nop 0
	v_cvt_pk_bf16_f32 v53, v54, v55
	global_store_dwordx2 v[60:61], v[52:53], off offset:1536
	global_load_dwordx4 v[52:55], v1, s[4:5]
	s_nop 0
	global_load_dwordx4 v[70:73], v1, s[6:7]
	v_mov_b32_e32 v1, 0x40000
	s_waitcnt vmcnt(0)
	v_pk_fma_f32 v[52:53], v[52:53], v[56:57], v[70:71]
	v_pk_fma_f32 v[54:55], v[54:55], v[48:49], v[72:73]
	global_store_dwordx4 v[64:65], v[52:55], off
	global_load_dword v48, v1, s[8:9]
	global_load_dword v70, v67, s[10:11] offset:2048
	global_load_dwordx4 v[56:59], v[74:75], off
	v_or_b32_e32 v1, 0x1400, v66
	s_waitcnt vmcnt(1)
	v_pk_fma_f32 v[52:53], v[52:53], v[48:49], v[70:71] op_sel_hi:[1,0,0]
	v_pk_fma_f32 v[48:49], v[54:55], v[48:49], v[70:71] op_sel_hi:[1,0,0]
	s_waitcnt vmcnt(0)
	v_pk_mul_f32 v[52:53], v[56:57], v[52:53]
	v_pk_mul_f32 v[48:49], v[58:59], v[48:49]
	v_cvt_pk_bf16_f32 v52, v52, v53
	s_nop 0
	v_cvt_pk_bf16_f32 v53, v48, v49
	global_store_dwordx2 v[60:61], v[52:53], off offset:2048
	global_load_dwordx4 v[52:55], v1, s[4:5]
	s_nop 0
	global_load_dwordx4 v[56:59], v1, s[6:7]
	v_pk_mul_f32 v[48:49], v[18:19], v[50:51] op_sel_hi:[0,1]
	v_mov_b32_e32 v1, 0x50000
	s_waitcnt vmcnt(0)
	v_pk_fma_f32 v[48:49], v[52:53], v[48:49], v[56:57]
	v_pk_fma_f32 v[50:51], v[54:55], v[44:45], v[58:59]
	global_store_dwordx4 v[64:65], v[48:51], off offset:1024
	global_load_dword v44, v1, s[8:9]
	global_load_dword v56, v67, s[10:11] offset:2560
	global_load_dwordx4 v[52:55], v[74:75], off offset:1024
	v_or_b32_e32 v1, 0x1800, v66
	s_waitcnt vmcnt(1)
	v_pk_fma_f32 v[48:49], v[48:49], v[44:45], v[56:57] op_sel_hi:[1,0,0]
	v_pk_fma_f32 v[44:45], v[50:51], v[44:45], v[56:57] op_sel_hi:[1,0,0]
	s_waitcnt vmcnt(0)
	v_pk_mul_f32 v[48:49], v[52:53], v[48:49]
	v_pk_mul_f32 v[44:45], v[54:55], v[44:45]
	v_cvt_pk_bf16_f32 v48, v48, v49
	s_nop 0
	v_cvt_pk_bf16_f32 v49, v44, v45
	global_store_dwordx2 v[60:61], v[48:49], off offset:2560
	global_load_dwordx4 v[48:51], v1, s[4:5]
	s_nop 0
	global_load_dwordx4 v[52:55], v1, s[6:7]
	v_mov_b32_e32 v1, 0x60000
	s_waitcnt vmcnt(0)
	v_pk_fma_f32 v[44:45], v[48:49], v[38:39], v[52:53]
	v_pk_fma_f32 v[46:47], v[50:51], v[46:47], v[54:55]
	global_store_dwordx4 v[64:65], v[44:47], off offset:2048
	global_load_dword v38, v1, s[8:9]
	global_load_dword v52, v67, s[10:11] offset:3072
	global_load_dwordx4 v[48:51], v[74:75], off offset:2048
	v_or_b32_e32 v1, 0x1c00, v66
	s_waitcnt vmcnt(1)
	v_pk_fma_f32 v[44:45], v[44:45], v[38:39], v[52:53] op_sel_hi:[1,0,0]
	v_pk_fma_f32 v[38:39], v[46:47], v[38:39], v[52:53] op_sel_hi:[1,0,0]
	s_waitcnt vmcnt(0)
	v_pk_mul_f32 v[44:45], v[48:49], v[44:45]
	v_pk_mul_f32 v[38:39], v[50:51], v[38:39]
	v_cvt_pk_bf16_f32 v44, v44, v45
	s_nop 0
	v_cvt_pk_bf16_f32 v45, v38, v39
	global_store_dwordx2 v[60:61], v[44:45], off offset:3072
	global_load_dwordx4 v[44:47], v1, s[4:5]
	s_nop 0
	global_load_dwordx4 v[48:51], v1, s[6:7]
	v_pk_mul_f32 v[38:39], v[18:19], v[36:37] op_sel_hi:[0,1]
	v_pk_mul_f32 v[36:37], v[18:19], v[42:43] op_sel_hi:[0,1]
	v_mov_b32_e32 v1, 0x70000
	v_mov_b32_e32 v19, 0x1000
	v_pk_mul_f32 v[32:33], v[18:19], v[32:33] op_sel_hi:[0,1]
	v_pk_mul_f32 v[34:35], v[18:19], v[34:35] op_sel_hi:[0,1]
	v_pk_mul_f32 v[26:27], v[18:19], v[26:27] op_sel_hi:[0,1]
	v_pk_mul_f32 v[16:17], v[18:19], v[16:17] op_sel_hi:[0,1]
	v_pk_mul_f32 v[14:15], v[18:19], v[14:15] op_sel_hi:[0,1]
	v_pk_mul_f32 v[12:13], v[18:19], v[12:13] op_sel_hi:[0,1]
	v_pk_mul_f32 v[10:11], v[18:19], v[10:11] op_sel_hi:[0,1]
	v_pk_mul_f32 v[8:9], v[18:19], v[8:9] op_sel_hi:[0,1]
	v_pk_mul_f32 v[6:7], v[18:19], v[6:7] op_sel_hi:[0,1]
	v_pk_mul_f32 v[4:5], v[18:19], v[4:5] op_sel_hi:[0,1]
	v_pk_mul_f32 v[2:3], v[18:19], v[2:3] op_sel_hi:[0,1]
	s_waitcnt vmcnt(0)
	v_pk_fma_f32 v[36:37], v[44:45], v[36:37], v[48:49]
	v_pk_fma_f32 v[38:39], v[46:47], v[38:39], v[50:51]
	global_store_dwordx4 v[64:65], v[36:39], off offset:3072
	global_load_dword v46, v1, s[8:9]
	global_load_dword v48, v67, s[10:11] offset:3584
	global_load_dwordx4 v[42:45], v[74:75], off offset:3072
	v_or_b32_e32 v1, 0x2000, v66
	s_waitcnt vmcnt(1)
	v_pk_fma_f32 v[36:37], v[36:37], v[46:47], v[48:49] op_sel_hi:[1,0,0]
	v_pk_fma_f32 v[38:39], v[38:39], v[46:47], v[48:49] op_sel_hi:[1,0,0]
	s_waitcnt vmcnt(0)
	v_pk_mul_f32 v[36:37], v[42:43], v[36:37]
	v_pk_mul_f32 v[38:39], v[44:45], v[38:39]
	v_cvt_pk_bf16_f32 v36, v36, v37
	s_nop 0
	v_cvt_pk_bf16_f32 v37, v38, v39
	global_store_dwordx2 v[60:61], v[36:37], off offset:3584
	global_load_dwordx4 v[42:45], v1, s[4:5]
	global_load_dwordx4 v[46:49], v1, s[6:7]
	v_add_co_u32_e32 v36, vcc, s0, v62
	v_pk_mul_f32 v[38:39], v[18:19], v[40:41] op_sel_hi:[0,1]
	s_nop 0
	v_addc_co_u32_e32 v37, vcc, 0, v63, vcc
	v_mov_b32_e32 v1, 0x80000
	s_mov_b32 s0, 0x8882000
	s_waitcnt vmcnt(0)
	v_pk_fma_f32 v[38:39], v[42:43], v[38:39], v[46:47]
	v_pk_fma_f32 v[40:41], v[44:45], v[32:33], v[48:49]
	global_store_dwordx4 v[36:37], v[38:41], off offset:-4096
	v_add_co_u32_e32 v32, vcc, s1, v68
	global_load_dword v46, v1, s[8:9]
	global_load_dword v48, v19, s[10:11]
	v_addc_co_u32_e32 v33, vcc, 0, v69, vcc
	global_load_dwordx4 v[42:45], v[32:33], off offset:-4096
	v_or_b32_e32 v1, 0x2400, v66
	s_mov_b32 s1, 0x69982000
	s_waitcnt vmcnt(1)
	v_pk_fma_f32 v[38:39], v[38:39], v[46:47], v[48:49] op_sel_hi:[1,0,0]
	v_pk_fma_f32 v[40:41], v[40:41], v[46:47], v[48:49] op_sel_hi:[1,0,0]
	v_add_co_u32_e32 v46, vcc, s0, v62
	s_waitcnt vmcnt(0)
	v_pk_mul_f32 v[38:39], v[42:43], v[38:39]
	v_pk_mul_f32 v[40:41], v[44:45], v[40:41]
	v_cvt_pk_bf16_f32 v38, v38, v39
	v_addc_co_u32_e32 v47, vcc, 0, v63, vcc
	v_cvt_pk_bf16_f32 v39, v40, v41
	global_store_dwordx2 v[28:29], v[38:39], off
	global_load_dwordx4 v[38:41], v1, s[4:5]
	s_nop 0
	global_load_dwordx4 v[42:45], v1, s[6:7]
	v_mov_b32_e32 v1, 0x90000
	v_add_co_u32_e32 v48, vcc, s1, v68
	s_waitcnt vmcnt(0)
	v_pk_fma_f32 v[38:39], v[38:39], v[26:27], v[42:43]
	v_pk_fma_f32 v[40:41], v[40:41], v[34:35], v[44:45]
	global_store_dwordx4 v[46:47], v[38:41], off offset:1024
	global_load_dword v26, v1, s[8:9]
	global_load_dword v34, v19, s[10:11] offset:512
	v_addc_co_u32_e32 v49, vcc, 0, v69, vcc
	global_load_dwordx4 v[42:45], v[48:49], off offset:1024
	v_or_b32_e32 v1, 0x2800, v66
	s_waitcnt vmcnt(1)
	v_pk_fma_f32 v[38:39], v[38:39], v[26:27], v[34:35] op_sel_hi:[1,0,0]
	v_pk_fma_f32 v[26:27], v[40:41], v[26:27], v[34:35] op_sel_hi:[1,0,0]
	s_waitcnt vmcnt(0)
	v_pk_mul_f32 v[34:35], v[42:43], v[38:39]
	v_pk_mul_f32 v[26:27], v[44:45], v[26:27]
	v_cvt_pk_bf16_f32 v34, v34, v35
	s_nop 0
	v_cvt_pk_bf16_f32 v35, v26, v27
	global_store_dwordx2 v[28:29], v[34:35], off offset:512
	global_load_dwordx4 v[38:41], v1, s[4:5]
	global_load_dwordx4 v[42:45], v1, s[6:7]
	v_pk_mul_f32 v[26:27], v[18:19], v[24:25] op_sel_hi:[0,1]
	v_pk_mul_f32 v[24:25], v[18:19], v[30:31] op_sel_hi:[0,1]
	v_mov_b32_e32 v1, 0xa0000
	s_waitcnt vmcnt(0)
	v_pk_fma_f32 v[24:25], v[38:39], v[24:25], v[42:43]
	v_pk_fma_f32 v[26:27], v[40:41], v[26:27], v[44:45]
	global_store_dwordx4 v[46:47], v[24:27], off offset:2048
	global_load_dword v30, v1, s[8:9]
	global_load_dword v34, v19, s[10:11] offset:1024
	global_load_dwordx4 v[38:41], v[48:49], off offset:2048
	v_or_b32_e32 v1, 0x2c00, v66
	s_waitcnt vmcnt(1)
	v_pk_fma_f32 v[24:25], v[24:25], v[30:31], v[34:35] op_sel_hi:[1,0,0]
	v_pk_fma_f32 v[26:27], v[26:27], v[30:31], v[34:35] op_sel_hi:[1,0,0]
	s_waitcnt vmcnt(0)
	v_pk_mul_f32 v[24:25], v[38:39], v[24:25]
	v_pk_mul_f32 v[26:27], v[40:41], v[26:27]
	v_cvt_pk_bf16_f32 v24, v24, v25
	v_pk_mul_f32 v[30:31], v[18:19], v[20:21] op_sel_hi:[0,1]
	v_cvt_pk_bf16_f32 v25, v26, v27
	global_store_dwordx2 v[28:29], v[24:25], off offset:1024
	global_load_dwordx4 v[24:27], v1, s[4:5]
	s_nop 0
	global_load_dwordx4 v[38:41], v1, s[6:7]
	v_pk_mul_f32 v[20:21], v[18:19], v[22:23] op_sel_hi:[0,1]
	v_mov_b32_e32 v1, 0xb0000
	s_waitcnt vmcnt(0)
	v_pk_fma_f32 v[20:21], v[24:25], v[20:21], v[38:39]
	v_pk_fma_f32 v[22:23], v[26:27], v[30:31], v[40:41]
	global_store_dwordx4 v[46:47], v[20:23], off offset:3072
	global_load_dword v30, v1, s[8:9]
	global_load_dword v34, v19, s[10:11] offset:1536
	global_load_dwordx4 v[24:27], v[48:49], off offset:3072
	v_or_b32_e32 v1, 0x3000, v66
	s_waitcnt vmcnt(1)
	v_pk_fma_f32 v[20:21], v[20:21], v[30:31], v[34:35] op_sel_hi:[1,0,0]
	v_pk_fma_f32 v[22:23], v[22:23], v[30:31], v[34:35] op_sel_hi:[1,0,0]
	s_waitcnt vmcnt(0)
	v_pk_mul_f32 v[20:21], v[24:25], v[20:21]
	v_pk_mul_f32 v[22:23], v[26:27], v[22:23]
	v_cvt_pk_bf16_f32 v20, v20, v21
	s_nop 0
	v_cvt_pk_bf16_f32 v21, v22, v23
	global_store_dwordx2 v[28:29], v[20:21], off offset:1536
	global_load_dwordx4 v[20:23], v1, s[4:5]
	s_nop 0
	global_load_dwordx4 v[24:27], v1, s[6:7]
	v_mov_b32_e32 v1, 0xc0000
	s_waitcnt vmcnt(0)
	v_pk_fma_f32 v[14:15], v[20:21], v[14:15], v[24:25]
	v_pk_fma_f32 v[16:17], v[22:23], v[16:17], v[26:27]
	global_store_dwordx4 v[36:37], v[14:17], off
	global_load_dword v24, v1, s[8:9]
	global_load_dword v26, v19, s[10:11] offset:2048
	global_load_dwordx4 v[20:23], v[32:33], off
	v_or_b32_e32 v1, 0x3400, v66
	s_waitcnt vmcnt(1)
	v_pk_fma_f32 v[14:15], v[14:15], v[24:25], v[26:27] op_sel_hi:[1,0,0]
	v_pk_fma_f32 v[16:17], v[16:17], v[24:25], v[26:27] op_sel_hi:[1,0,0]
	s_waitcnt vmcnt(0)
	v_pk_mul_f32 v[14:15], v[20:21], v[14:15]
	v_pk_mul_f32 v[16:17], v[22:23], v[16:17]
	v_cvt_pk_bf16_f32 v14, v14, v15
	s_nop 0
	v_cvt_pk_bf16_f32 v15, v16, v17
	global_store_dwordx2 v[28:29], v[14:15], off offset:2048
	global_load_dwordx4 v[14:17], v1, s[4:5]
	s_nop 0
	global_load_dwordx4 v[20:23], v1, s[6:7]
	v_mov_b32_e32 v1, 0xd0000
	s_waitcnt vmcnt(0)
	v_pk_fma_f32 v[10:11], v[14:15], v[10:11], v[20:21]
	v_pk_fma_f32 v[12:13], v[16:17], v[12:13], v[22:23]
	global_store_dwordx4 v[36:37], v[10:13], off offset:1024
	global_load_dword v20, v1, s[8:9]
	global_load_dword v22, v19, s[10:11] offset:2560
	global_load_dwordx4 v[14:17], v[32:33], off offset:1024
	v_or_b32_e32 v1, 0x3800, v66
	s_waitcnt vmcnt(1)
	v_pk_fma_f32 v[10:11], v[10:11], v[20:21], v[22:23] op_sel_hi:[1,0,0]
	v_pk_fma_f32 v[12:13], v[12:13], v[20:21], v[22:23] op_sel_hi:[1,0,0]
	s_waitcnt vmcnt(0)
	v_pk_mul_f32 v[10:11], v[14:15], v[10:11]
	v_pk_mul_f32 v[12:13], v[16:17], v[12:13]
	v_cvt_pk_bf16_f32 v10, v10, v11
	s_nop 0
	v_cvt_pk_bf16_f32 v11, v12, v13
	global_store_dwordx2 v[28:29], v[10:11], off offset:2560
	global_load_dwordx4 v[10:13], v1, s[4:5]
	s_nop 0
	global_load_dwordx4 v[14:17], v1, s[6:7]
	v_mov_b32_e32 v1, 0xe0000
	s_waitcnt vmcnt(0)
	v_pk_fma_f32 v[6:7], v[10:11], v[6:7], v[14:15]
	v_pk_fma_f32 v[8:9], v[12:13], v[8:9], v[16:17]
	global_store_dwordx4 v[36:37], v[6:9], off offset:2048
	global_load_dword v14, v1, s[8:9]
	global_load_dword v16, v19, s[10:11] offset:3072
	global_load_dwordx4 v[10:13], v[32:33], off offset:2048
	v_or_b32_e32 v1, 0x3c00, v66
	s_waitcnt vmcnt(1)
	v_pk_fma_f32 v[6:7], v[6:7], v[14:15], v[16:17] op_sel_hi:[1,0,0]
	v_pk_fma_f32 v[8:9], v[8:9], v[14:15], v[16:17] op_sel_hi:[1,0,0]
	s_waitcnt vmcnt(0)
	v_pk_mul_f32 v[6:7], v[10:11], v[6:7]
	v_pk_mul_f32 v[8:9], v[12:13], v[8:9]
	v_cvt_pk_bf16_f32 v6, v6, v7
	s_nop 0
	v_cvt_pk_bf16_f32 v7, v8, v9
	global_store_dwordx2 v[28:29], v[6:7], off offset:3072
	global_load_dwordx4 v[6:9], v1, s[4:5]
	s_nop 0
	global_load_dwordx4 v[10:13], v1, s[6:7]
	v_mov_b32_e32 v1, 0xf0000
	s_waitcnt vmcnt(0)
	v_pk_fma_f32 v[2:3], v[6:7], v[2:3], v[10:11]
	v_pk_fma_f32 v[4:5], v[8:9], v[4:5], v[12:13]
	global_store_dwordx4 v[36:37], v[2:5], off offset:3072
	global_load_dword v10, v1, s[8:9]
	global_load_dword v12, v19, s[10:11] offset:3584
	global_load_dwordx4 v[6:9], v[32:33], off offset:3072
	s_waitcnt vmcnt(1)
	v_pk_fma_f32 v[2:3], v[2:3], v[10:11], v[12:13] op_sel_hi:[1,0,0]
	v_pk_fma_f32 v[4:5], v[4:5], v[10:11], v[12:13] op_sel_hi:[1,0,0]
	s_waitcnt vmcnt(0)
	v_pk_mul_f32 v[2:3], v[6:7], v[2:3]
	v_pk_mul_f32 v[4:5], v[8:9], v[4:5]
	v_cvt_pk_bf16_f32 v2, v2, v3
	s_nop 0
	v_cvt_pk_bf16_f32 v3, v4, v5
	global_store_dwordx2 v[28:29], v[2:3], off offset:3584

.LBB0_756:
	v_lshl_add_u64 v[152:153], s[8:9], 0, v[148:149]
	s_mov_b32 s2, 0x3b100000
	s_lshl_b64 s[4:5], s[36:37], 13
	v_add_co_u32_e32 v2, vcc, s2, v152
	s_add_u32 s44, s56, s4
	s_mov_b64 s[2:3], vcc
	v_add_co_u32_e32 v4, vcc, s41, v152
	s_addc_u32 s45, s57, s5
	s_nop 0
	v_addc_co_u32_e32 v5, vcc, 0, v153, vcc
	global_load_dwordx4 v[102:105], v168, s[44:45]
	global_load_dwordx4 v[98:101], v168, s[44:45] offset:16
	global_load_dwordx4 v[110:113], v[4:5], off offset:-4096
	s_mov_b64 s[46:47], 0x3b100000
	v_lshl_add_u64 v[6:7], v[152:153], 0, s[46:47]
	global_load_dwordx4 v[94:97], v[6:7], off offset:16
	v_add_co_u32_e32 v12, vcc, s68, v152
	s_mov_b64 s[48:49], 0x3b100800
	s_nop 0
	v_addc_co_u32_e32 v13, vcc, 0, v153, vcc
	v_add_co_u32_e32 v18, vcc, s69, v152
	v_lshl_add_u64 v[6:7], v[152:153], 0, s[48:49]
	v_lshl_add_u64 v[8:9], v[152:153], 0, s[24:25]
	v_lshl_add_u64 v[10:11], v[152:153], 0, s[26:27]
	v_addc_co_u32_e32 v19, vcc, 0, v153, vcc
	v_lshl_add_u64 v[14:15], v[152:153], 0, s[28:29]
	v_addc_co_u32_e64 v3, vcc, 0, v153, s[2:3]
	global_load_dwordx4 v[70:73], v[6:7], off offset:16
	global_load_dwordx4 v[34:37], v[8:9], off offset:16
	global_load_dwordx4 v[86:89], v[12:13], off offset:2048
	global_load_dwordx4 v[66:69], v[14:15], off offset:16
	global_load_dwordx4 v[46:49], v[18:19], off
	s_nop 0
	global_load_dwordx4 v[14:17], v[18:19], off offset:2048
	global_load_dwordx4 v[90:93], v[2:3], off offset:2048
	global_load_dwordx4 v[54:57], v168, s[44:45] offset:2064
	global_load_dwordx4 v[78:81], v168, s[44:45] offset:2048
	global_load_dwordx4 v[26:29], v160, s[44:45] offset:16
	global_load_dwordx4 v[38:41], v160, s[44:45]
	global_load_dwordx4 v[6:9], v[10:11], off offset:16
	s_nop 0
	global_load_dwordx4 v[10:13], v161, s[44:45]
	global_load_dwordx4 v[50:53], v[4:5], off
	global_load_dwordx4 v[22:25], v[4:5], off offset:2048
	global_load_dwordx4 v[122:125], v[18:19], off offset:-4096
	s_add_u32 s2, s7, s4
	s_addc_u32 s3, s55, s5
	global_load_dwordx4 v[106:109], v168, s[2:3] offset:16
	global_load_dwordx4 v[118:121], v168, s[2:3]
	global_load_dwordx4 v[62:65], v168, s[2:3] offset:2064
	global_load_dwordx4 v[82:85], v168, s[2:3] offset:2048
	global_load_dwordx4 v[30:33], v160, s[2:3] offset:16
	global_load_dwordx4 v[42:45], v160, s[2:3]
	global_load_dwordx4 v[2:5], v161, s[44:45] offset:16
	global_load_dwordx4 v[18:21], v161, s[2:3]
	s_mov_b64 s[46:47], 0x2ad00000
	v_lshl_add_u64 v[58:59], v[152:153], 0, s[46:47]
	v_lshl_add_u64 v[60:61], v[152:153], 0, s[30:31]
	v_lshl_add_u64 v[74:75], v[152:153], 0, s[34:35]
	s_add_u32 s4, s58, s4
	s_addc_u32 s5, s59, s5
	s_waitcnt vmcnt(27)
	v_and_b32_e32 v77, 0xffff0000, v102
	v_mul_f32_e32 v175, v77, v77
	s_waitcnt vmcnt(25)
	v_and_b32_e32 v129, 0xffff0000, v110
	v_lshlrev_b32_e32 v128, 16, v110
	v_mul_f32_e32 v77, v129, v129
	v_lshlrev_b32_e32 v169, 16, v111
	v_fmac_f32_e32 v77, v128, v128
	v_and_b32_e32 v170, 0xffff0000, v111
	v_fmac_f32_e32 v77, v169, v169
	v_lshlrev_b32_e32 v171, 16, v112
	v_fmac_f32_e32 v77, v170, v170
	v_and_b32_e32 v172, 0xffff0000, v112
	v_fmac_f32_e32 v77, v171, v171
	v_lshlrev_b32_e32 v173, 16, v113
	v_fmac_f32_e32 v77, v172, v172
	v_lshlrev_b32_e32 v76, 16, v102
	v_and_b32_e32 v174, 0xffff0000, v113
	v_fmac_f32_e32 v77, v173, v173
	v_lshlrev_b32_e32 v114, 16, v103
	v_fmac_f32_e32 v175, v76, v76
	v_fmac_f32_e32 v77, v174, v174
	s_waitcnt vmcnt(24)
	v_lshlrev_b32_e32 v76, 16, v94
	v_and_b32_e32 v115, 0xffff0000, v103
	v_fmac_f32_e32 v175, v114, v114
	v_and_b32_e32 v114, 0xffff0000, v94
	v_fmac_f32_e32 v77, v76, v76
	v_lshlrev_b32_e32 v116, 16, v104
	v_fmac_f32_e32 v175, v115, v115
	v_lshlrev_b32_e32 v115, 16, v95
	v_fmac_f32_e32 v77, v114, v114
	v_and_b32_e32 v117, 0xffff0000, v104
	v_fmac_f32_e32 v175, v116, v116
	v_and_b32_e32 v116, 0xffff0000, v95
	v_fmac_f32_e32 v77, v115, v115
	v_lshlrev_b32_e32 v126, 16, v105
	v_fmac_f32_e32 v175, v117, v117
	v_lshlrev_b32_e32 v117, 16, v96
	v_fmac_f32_e32 v77, v116, v116
	v_and_b32_e32 v127, 0xffff0000, v105
	v_fmac_f32_e32 v175, v126, v126
	v_and_b32_e32 v126, 0xffff0000, v96
	v_fmac_f32_e32 v77, v117, v117
	v_fmac_f32_e32 v175, v127, v127
	v_lshlrev_b32_e32 v127, 16, v97
	v_fmac_f32_e32 v77, v126, v126
	v_and_b32_e32 v128, 0xffff0000, v97
	v_fmac_f32_e32 v77, v127, v127
	v_fmac_f32_e32 v77, v128, v128
	s_waitcnt vmcnt(17)
	v_lshlrev_b32_e32 v76, 16, v90
	v_and_b32_e32 v114, 0xffff0000, v90
	v_fmac_f32_e32 v77, v76, v76
	v_lshlrev_b32_e32 v115, 16, v91
	v_fmac_f32_e32 v77, v114, v114
	v_and_b32_e32 v116, 0xffff0000, v91
	v_fmac_f32_e32 v77, v115, v115
	v_lshlrev_b32_e32 v117, 16, v92
	v_fmac_f32_e32 v77, v116, v116
	v_and_b32_e32 v126, 0xffff0000, v92
	v_fmac_f32_e32 v77, v117, v117
	v_lshlrev_b32_e32 v127, 16, v93
	v_fmac_f32_e32 v77, v126, v126
	v_and_b32_e32 v128, 0xffff0000, v93
	v_fmac_f32_e32 v77, v127, v127
	v_fmac_f32_e32 v77, v128, v128
	v_lshlrev_b32_e32 v76, 16, v70
	v_and_b32_e32 v114, 0xffff0000, v70
	v_fmac_f32_e32 v77, v76, v76
	v_lshlrev_b32_e32 v115, 16, v71
	v_fmac_f32_e32 v77, v114, v114
	v_and_b32_e32 v116, 0xffff0000, v71
	v_fmac_f32_e32 v77, v115, v115
	v_lshlrev_b32_e32 v117, 16, v72
	v_fmac_f32_e32 v77, v116, v116
	v_and_b32_e32 v126, 0xffff0000, v72
	v_fmac_f32_e32 v77, v117, v117
	v_lshlrev_b32_e32 v127, 16, v73
	v_fmac_f32_e32 v77, v126, v126
	v_and_b32_e32 v128, 0xffff0000, v73
	v_fmac_f32_e32 v77, v127, v127
	v_lshlrev_b32_e32 v129, 16, v98
	v_fmac_f32_e32 v77, v128, v128
	s_waitcnt vmcnt(10)
	v_lshlrev_b32_e32 v76, 16, v50
	v_and_b32_e32 v169, 0xffff0000, v98
	v_fmac_f32_e32 v175, v129, v129
	v_and_b32_e32 v114, 0xffff0000, v50
	v_fmac_f32_e32 v77, v76, v76
	v_lshlrev_b32_e32 v170, 16, v99
	v_fmac_f32_e32 v175, v169, v169
	v_lshlrev_b32_e32 v115, 16, v51
	v_fmac_f32_e32 v77, v114, v114
	v_and_b32_e32 v171, 0xffff0000, v99
	v_fmac_f32_e32 v175, v170, v170
	v_and_b32_e32 v116, 0xffff0000, v51
	v_fmac_f32_e32 v77, v115, v115
	v_lshlrev_b32_e32 v172, 16, v100
	v_fmac_f32_e32 v175, v171, v171
	v_lshlrev_b32_e32 v117, 16, v52
	v_fmac_f32_e32 v77, v116, v116
	v_and_b32_e32 v173, 0xffff0000, v100
	v_fmac_f32_e32 v175, v172, v172
	v_and_b32_e32 v126, 0xffff0000, v52
	v_fmac_f32_e32 v77, v117, v117
	v_lshlrev_b32_e32 v174, 16, v101
	v_fmac_f32_e32 v175, v173, v173
	v_lshlrev_b32_e32 v127, 16, v53
	v_fmac_f32_e32 v77, v126, v126
	v_and_b32_e32 v176, 0xffff0000, v101
	v_fmac_f32_e32 v175, v174, v174
	v_and_b32_e32 v128, 0xffff0000, v53
	v_fmac_f32_e32 v77, v127, v127
	v_fmac_f32_e32 v175, v176, v176
	v_lshlrev_b32_e32 v129, 16, v78
	v_fmac_f32_e32 v77, v128, v128
	v_lshlrev_b32_e32 v76, 16, v34
	v_and_b32_e32 v169, 0xffff0000, v78
	v_fmac_f32_e32 v175, v129, v129
	v_and_b32_e32 v114, 0xffff0000, v34
	v_fmac_f32_e32 v77, v76, v76
	v_lshlrev_b32_e32 v170, 16, v79
	v_fmac_f32_e32 v175, v169, v169
	v_lshlrev_b32_e32 v115, 16, v35
	v_fmac_f32_e32 v77, v114, v114
	v_and_b32_e32 v171, 0xffff0000, v79
	v_fmac_f32_e32 v175, v170, v170
	v_and_b32_e32 v116, 0xffff0000, v35
	v_fmac_f32_e32 v77, v115, v115
	v_lshlrev_b32_e32 v172, 16, v80
	v_fmac_f32_e32 v175, v171, v171
	v_lshlrev_b32_e32 v117, 16, v36
	v_fmac_f32_e32 v77, v116, v116
	v_and_b32_e32 v173, 0xffff0000, v80
	v_fmac_f32_e32 v175, v172, v172
	v_and_b32_e32 v126, 0xffff0000, v36
	v_fmac_f32_e32 v77, v117, v117
	v_lshlrev_b32_e32 v174, 16, v81
	v_fmac_f32_e32 v175, v173, v173
	v_lshlrev_b32_e32 v127, 16, v37
	v_fmac_f32_e32 v77, v126, v126
	v_and_b32_e32 v176, 0xffff0000, v81
	v_fmac_f32_e32 v175, v174, v174
	v_and_b32_e32 v128, 0xffff0000, v37
	v_fmac_f32_e32 v77, v127, v127
	v_fmac_f32_e32 v175, v176, v176
	v_lshlrev_b32_e32 v129, 16, v54
	v_fmac_f32_e32 v77, v128, v128
	s_waitcnt vmcnt(9)
	v_lshlrev_b32_e32 v76, 16, v22
	v_and_b32_e32 v169, 0xffff0000, v54
	v_fmac_f32_e32 v175, v129, v129
	v_and_b32_e32 v114, 0xffff0000, v22
	v_fmac_f32_e32 v77, v76, v76
	v_lshlrev_b32_e32 v170, 16, v55
	v_fmac_f32_e32 v175, v169, v169
	v_lshlrev_b32_e32 v115, 16, v23
	v_fmac_f32_e32 v77, v114, v114
	v_and_b32_e32 v171, 0xffff0000, v55
	v_fmac_f32_e32 v175, v170, v170
	v_and_b32_e32 v116, 0xffff0000, v23
	v_fmac_f32_e32 v77, v115, v115
	v_lshlrev_b32_e32 v172, 16, v56
	v_fmac_f32_e32 v175, v171, v171
	v_lshlrev_b32_e32 v117, 16, v24
	v_fmac_f32_e32 v77, v116, v116
	v_and_b32_e32 v173, 0xffff0000, v56
	v_fmac_f32_e32 v175, v172, v172
	v_and_b32_e32 v126, 0xffff0000, v24
	v_fmac_f32_e32 v77, v117, v117
	v_lshlrev_b32_e32 v174, 16, v57
	v_fmac_f32_e32 v175, v173, v173
	v_lshlrev_b32_e32 v127, 16, v25
	v_fmac_f32_e32 v77, v126, v126
	v_and_b32_e32 v176, 0xffff0000, v57
	v_fmac_f32_e32 v175, v174, v174
	v_and_b32_e32 v128, 0xffff0000, v25
	v_fmac_f32_e32 v77, v127, v127
	v_fmac_f32_e32 v175, v176, v176
	v_lshlrev_b32_e32 v129, 16, v38
	v_fmac_f32_e32 v77, v128, v128
	v_lshlrev_b32_e32 v76, 16, v6
	v_and_b32_e32 v169, 0xffff0000, v38
	v_fmac_f32_e32 v175, v129, v129
	v_and_b32_e32 v114, 0xffff0000, v6
	v_fmac_f32_e32 v77, v76, v76
	v_lshlrev_b32_e32 v170, 16, v39
	v_fmac_f32_e32 v175, v169, v169
	v_lshlrev_b32_e32 v115, 16, v7
	v_fmac_f32_e32 v77, v114, v114
	v_and_b32_e32 v171, 0xffff0000, v39
	v_fmac_f32_e32 v175, v170, v170
	v_and_b32_e32 v116, 0xffff0000, v7
	v_fmac_f32_e32 v77, v115, v115
	v_lshlrev_b32_e32 v172, 16, v40
	v_fmac_f32_e32 v175, v171, v171
	v_lshlrev_b32_e32 v117, 16, v8
	v_fmac_f32_e32 v77, v116, v116
	v_and_b32_e32 v173, 0xffff0000, v40
	v_fmac_f32_e32 v175, v172, v172
	v_and_b32_e32 v126, 0xffff0000, v8
	v_fmac_f32_e32 v77, v117, v117
	v_lshlrev_b32_e32 v174, 16, v41
	v_fmac_f32_e32 v175, v173, v173
	v_lshlrev_b32_e32 v127, 16, v9
	v_fmac_f32_e32 v77, v126, v126
	v_and_b32_e32 v176, 0xffff0000, v41
	v_fmac_f32_e32 v175, v174, v174
	v_and_b32_e32 v128, 0xffff0000, v9
	v_fmac_f32_e32 v77, v127, v127
	v_fmac_f32_e32 v175, v176, v176
	v_lshlrev_b32_e32 v129, 16, v26
	v_fmac_f32_e32 v77, v128, v128
	v_and_b32_e32 v169, 0xffff0000, v26
	v_fmac_f32_e32 v175, v129, v129
	v_lshlrev_b32_e32 v170, 16, v27
	v_fmac_f32_e32 v175, v169, v169
	v_and_b32_e32 v171, 0xffff0000, v27
	v_fmac_f32_e32 v175, v170, v170
	v_lshlrev_b32_e32 v172, 16, v28
	v_fmac_f32_e32 v175, v171, v171
	v_and_b32_e32 v173, 0xffff0000, v28
	v_fmac_f32_e32 v175, v172, v172
	v_lshlrev_b32_e32 v174, 16, v29
	v_fmac_f32_e32 v175, v173, v173
	s_waitcnt lgkmcnt(0)
	s_nop 1
	v_add_f32_dpp v76, v77, v77 quad_perm:[1,0,3,2] row_mask:0xf bank_mask:0xf
	v_and_b32_e32 v176, 0xffff0000, v29
	v_fmac_f32_e32 v175, v174, v174
	v_fmac_f32_e32 v175, v176, v176
	v_lshlrev_b32_e32 v129, 16, v10
	v_and_b32_e32 v169, 0xffff0000, v10
	v_fmac_f32_e32 v175, v129, v129
	v_lshlrev_b32_e32 v170, 16, v11
	v_fmac_f32_e32 v175, v169, v169
	v_and_b32_e32 v171, 0xffff0000, v11
	v_fmac_f32_e32 v175, v170, v170
	v_lshlrev_b32_e32 v172, 16, v12
	v_fmac_f32_e32 v175, v171, v171
	s_waitcnt lgkmcnt(0)
	s_nop 1
	v_add_f32_dpp v76, v76, v76 quad_perm:[2,3,0,1] row_mask:0xf bank_mask:0xf
	v_and_b32_e32 v173, 0xffff0000, v12
	v_fmac_f32_e32 v175, v172, v172
	v_lshlrev_b32_e32 v174, 16, v13
	v_fmac_f32_e32 v175, v173, v173
	v_and_b32_e32 v176, 0xffff0000, v13
	v_fmac_f32_e32 v175, v174, v174
	v_fmac_f32_e32 v175, v176, v176
	s_waitcnt vmcnt(1)
	v_lshlrev_b32_e32 v114, 16, v2
	v_and_b32_e32 v115, 0xffff0000, v2
	v_fmac_f32_e32 v175, v114, v114
	v_lshlrev_b32_e32 v116, 16, v3
	v_fmac_f32_e32 v175, v115, v115
	s_waitcnt lgkmcnt(0)
	s_nop 1
	v_add_f32_dpp v76, v76, v76 row_half_mirror row_mask:0xf bank_mask:0xf
	v_and_b32_e32 v117, 0xffff0000, v3
	v_fmac_f32_e32 v175, v116, v116
	v_lshlrev_b32_e32 v126, 16, v4
	v_fmac_f32_e32 v175, v117, v117
	v_and_b32_e32 v127, 0xffff0000, v4
	v_fmac_f32_e32 v175, v126, v126
	v_lshlrev_b32_e32 v128, 16, v5
	v_fmac_f32_e32 v175, v127, v127
	v_and_b32_e32 v129, 0xffff0000, v5
	v_fmac_f32_e32 v175, v128, v128
	s_waitcnt lgkmcnt(0)
	s_nop 1
	v_add_f32_dpp v126, v76, v76 row_mirror row_mask:0xf bank_mask:0xf
	v_fmac_f32_e32 v175, v129, v129
	global_load_dwordx4 v[114:117], v[60:61], off offset:16
	s_nop 0
	global_load_dwordx4 v[74:77], v[74:75], off offset:16
	v_and_b32_e32 v181, 0xffff0000, v122
	v_lshlrev_b32_e32 v180, 16, v123
	s_waitcnt lgkmcnt(0)
	v_mov_b32_e32 v169, v126
	v_mov_b32_e32 v127, v126
	s_nop 1
	v_permlane16_swap_b32_e32 v127, v169
	v_add_f32_e32 v169, v169, v127
	s_waitcnt lgkmcnt(0)
	s_nop 1
	v_add_f32_dpp v171, v175, v175 quad_perm:[1,0,3,2] row_mask:0xf bank_mask:0xf
	global_load_dwordx4 v[126:129], v[58:59], off offset:16
	s_nop 0
	global_load_dwordx4 v[58:61], v161, s[2:3] offset:16
	global_load_dwordx4 v[184:187], v[132:133], off offset:16
	global_load_dwordx4 v[188:191], v[132:133], off
	v_and_b32_e32 v178, 0xffff0000, v123
	v_lshlrev_b32_e32 v177, 16, v124
	v_and_b32_e32 v176, 0xffff0000, v124
	s_waitcnt lgkmcnt(0)
	v_mov_b32_e32 v170, v169
	s_nop 1
	v_permlane32_swap_b32_e32 v170, v169
	v_add_f32_e32 v169, v169, v170
	s_waitcnt lgkmcnt(0)
	s_nop 1
	v_add_f32_dpp v170, v171, v171 quad_perm:[2,3,0,1] row_mask:0xf bank_mask:0xf
	v_fmamk_f32 v169, v169, 0x39800000, v162
	v_mul_f32_e32 v172, 0x4f800000, v169
	v_cmp_gt_f32_e32 vcc, s70, v169
	v_lshlrev_b32_e32 v192, 16, v102
	s_waitcnt lgkmcnt(0)
	s_nop 1
	v_add_f32_dpp v170, v170, v170 row_half_mirror row_mask:0xf bank_mask:0xf
	v_cndmask_b32_e32 v169, v169, v172, vcc
	v_sqrt_f32_e32 v172, v169
	v_and_b32_e32 v102, 0xffff0000, v102
	v_lshlrev_b32_e32 v193, 16, v103
	s_waitcnt lgkmcnt(0)
	s_nop 1
	v_add_f32_dpp v170, v170, v170 row_mirror row_mask:0xf bank_mask:0xf
	v_add_u32_e32 v173, -1, v172
	v_fma_f32 v174, -v173, v172, v169
	v_cmp_ge_f32_e64 s[2:3], 0, v174
	v_add_u32_e32 v174, 1, v172
	s_waitcnt lgkmcnt(0)
	v_mov_b32_e32 v171, v170
	s_nop 1
	v_permlane16_swap_b32_e32 v171, v170
	v_add_f32_e32 v170, v170, v171
	v_cndmask_b32_e64 v173, v172, v173, s[2:3]
	v_fma_f32 v172, -v174, v172, v169
	v_cmp_lt_f32_e64 s[2:3], 0, v172
	v_and_b32_e32 v103, 0xffff0000, v103
	s_waitcnt lgkmcnt(0)
	v_mov_b32_e32 v171, v170
	s_nop 1
	v_permlane32_swap_b32_e32 v171, v170
	v_add_f32_e32 v170, v170, v171
	v_fmamk_f32 v170, v170, 0x39800000, v162
	v_cndmask_b32_e64 v172, v173, v174, s[2:3]
	v_mul_f32_e32 v171, 0x4f800000, v170
	v_cmp_gt_f32_e64 s[2:3], s70, v170
	v_mul_f32_e32 v173, 0x37800000, v172
	v_cndmask_b32_e32 v172, v172, v173, vcc
	v_cndmask_b32_e64 v170, v170, v171, s[2:3]
	v_sqrt_f32_e32 v171, v170
	v_cmp_class_f32_e32 vcc, v169, v163
	v_lshlrev_b32_e32 v179, 16, v122
	v_lshlrev_b32_e32 v194, 16, v104
	v_cndmask_b32_e32 v169, v172, v169, vcc
	v_add_u32_e32 v172, -1, v171
	v_fma_f32 v173, -v172, v171, v170
	v_cmp_ge_f32_e32 vcc, 0, v173
	v_add_u32_e32 v173, 1, v171
	v_and_b32_e32 v104, 0xffff0000, v104
	v_cndmask_b32_e32 v172, v171, v172, vcc
	v_fma_f32 v171, -v173, v171, v170
	v_cmp_lt_f32_e32 vcc, 0, v171
	v_lshlrev_b32_e32 v195, 16, v105
	v_and_b32_e32 v105, 0xffff0000, v105
	v_cndmask_b32_e32 v171, v172, v173, vcc
	v_div_scale_f32 v173, s[44:45], v169, v169, 1.0
	v_rcp_f32_e32 v174, v173
	v_mul_f32_e32 v172, 0x37800000, v171
	v_cndmask_b32_e64 v171, v171, v172, s[2:3]
	v_cmp_class_f32_e32 vcc, v170, v163
	v_lshlrev_b32_e32 v198, 16, v95
	v_and_b32_e32 v95, 0xffff0000, v95
	v_cndmask_b32_e32 v170, v171, v170, vcc
	v_fma_f32 v171, -v173, v174, 1.0
	v_fmac_f32_e32 v174, v171, v174
	v_div_scale_f32 v171, vcc, 1.0, v169, 1.0
	v_mul_f32_e32 v172, v171, v174
	v_fma_f32 v175, -v173, v172, v171
	v_fmac_f32_e32 v172, v175, v174
	v_fma_f32 v171, -v173, v172, v171
	v_div_scale_f32 v173, s[2:3], v170, v170, 1.0
	v_rcp_f32_e32 v175, v173
	v_div_fmas_f32 v171, v171, v174, v172
	v_div_fixup_f32 v183, v171, v169, 1.0
	v_and_b32_e32 v174, 0xffff0000, v125
	v_fma_f32 v169, -v173, v175, 1.0
	v_fmac_f32_e32 v175, v169, v175
	v_div_scale_f32 v169, vcc, 1.0, v170, 1.0
	v_mul_f32_e32 v171, v169, v175
	v_fma_f32 v172, -v173, v171, v169
	v_fmac_f32_e32 v171, v172, v175
	v_fma_f32 v169, -v173, v171, v169
	v_div_fmas_f32 v169, v169, v175, v171
	v_div_fixup_f32 v182, v169, v170, 1.0
	v_lshlrev_b32_e32 v169, 16, v110
	v_and_b32_e32 v110, 0xffff0000, v110
	v_lshlrev_b32_e32 v170, 16, v111
	v_mul_f32_e32 v110, v183, v110
	v_and_b32_e32 v111, 0xffff0000, v111
	s_waitcnt vmcnt(0)
	v_fmac_f32_e32 v181, v189, v110
	v_mul_f32_e32 v110, v183, v170
	v_lshlrev_b32_e32 v171, 16, v112
	v_fmac_f32_e32 v180, v190, v110
	v_mul_f32_e32 v110, v183, v111
	v_and_b32_e32 v112, 0xffff0000, v112
	v_fmac_f32_e32 v178, v191, v110
	v_mul_f32_e32 v110, v183, v171
	v_lshlrev_b32_e32 v172, 16, v113
	v_fmac_f32_e32 v177, v184, v110
	v_mul_f32_e32 v110, v183, v112
	v_and_b32_e32 v113, 0xffff0000, v113
	v_lshlrev_b32_e32 v175, 16, v125
	v_fmac_f32_e32 v176, v185, v110
	v_mul_f32_e32 v110, v183, v172
	v_and_b32_e32 v173, 0xffff0000, v118
	v_mul_f32_e32 v102, v182, v102
	v_fmac_f32_e32 v175, v186, v110
	v_mul_f32_e32 v110, v183, v113
	v_lshlrev_b32_e32 v172, 16, v119
	v_fmac_f32_e32 v173, v189, v102
	v_mul_f32_e32 v102, v182, v193
	v_mul_f32_e32 v122, v183, v169
	v_fmac_f32_e32 v174, v187, v110
	v_add_co_u32_e32 v110, vcc, s72, v152
	v_and_b32_e32 v170, 0xffff0000, v119
	v_fmac_f32_e32 v172, v190, v102
	v_mul_f32_e32 v102, v182, v103
	v_fmac_f32_e32 v179, v188, v122
	v_cvt_pk_bf16_f32 v122, v179, v181
	v_cvt_pk_bf16_f32 v123, v180, v178
	v_cvt_pk_bf16_f32 v124, v177, v176
	v_cvt_pk_bf16_f32 v125, v175, v174
	v_addc_co_u32_e32 v111, vcc, 0, v153, vcc
	v_lshlrev_b32_e32 v169, 16, v120
	v_fmac_f32_e32 v170, v191, v102
	v_mul_f32_e32 v102, v182, v194
	global_store_dwordx4 v[110:111], v[122:125], off offset:-4096
	v_fmac_f32_e32 v169, v184, v102
	v_mul_f32_e32 v102, v182, v104
	v_and_b32_e32 v125, 0xffff0000, v120
	v_lshlrev_b32_e32 v124, 16, v121
	v_fmac_f32_e32 v125, v185, v102
	v_mul_f32_e32 v102, v182, v195
	v_lshlrev_b32_e32 v171, 16, v118
	v_and_b32_e32 v120, 0xffff0000, v121
	v_mul_f32_e32 v118, v182, v192
	v_fmac_f32_e32 v124, v186, v102
	v_mul_f32_e32 v102, v182, v105
	v_cvt_pk_bf16_f32 v112, v179, v181
	v_cvt_pk_bf16_f32 v113, v180, v178
	v_cvt_pk_bf16_f32 v122, v177, v176
	v_cvt_pk_bf16_f32 v123, v175, v174
	v_fmac_f32_e32 v171, v188, v118
	v_fmac_f32_e32 v120, v187, v102
	v_cvt_pk_bf16_f32 v102, v171, v173
	v_cvt_pk_bf16_f32 v103, v172, v170
	v_cvt_pk_bf16_f32 v104, v169, v125
	v_cvt_pk_bf16_f32 v105, v124, v120
	global_store_dwordx4 v168, v[102:105], s[4:5]
	v_lshlrev_b32_e32 v121, 16, v94
	v_and_b32_e32 v94, 0xffff0000, v94
	v_cvt_pk_bf16_f32 v104, v171, v173
	v_cvt_pk_bf16_f32 v105, v172, v170
	v_cvt_pk_bf16_f32 v118, v169, v125
	v_cvt_pk_bf16_f32 v119, v124, v120
	global_load_dwordx4 v[190:193], v[132:133], off offset:32
	global_load_dwordx4 v[194:197], v[132:133], off offset:48
	v_and_b32_e32 v188, 0xffff0000, v126
	v_mul_f32_e32 v94, v183, v94
	v_lshlrev_b32_e32 v187, 16, v127
	v_lshlrev_b32_e32 v199, 16, v96
	v_and_b32_e32 v186, 0xffff0000, v127
	v_and_b32_e32 v96, 0xffff0000, v96
	v_lshlrev_b32_e32 v185, 16, v128
	v_and_b32_e32 v184, 0xffff0000, v128
	v_and_b32_e32 v128, 0xffff0000, v106
	v_lshlrev_b32_e32 v200, 16, v97
	v_lshlrev_b32_e32 v127, 16, v107
	v_lshlrev_b32_e32 v189, 16, v126
	v_mul_f32_e32 v121, v183, v121
	v_and_b32_e32 v126, 0xffff0000, v107
	v_add_co_u32_e32 v102, vcc, s71, v152
	v_and_b32_e32 v97, 0xffff0000, v97
	s_nop 0
	v_addc_co_u32_e32 v103, vcc, 0, v153, vcc
	v_lshlrev_b32_e32 v153, 16, v129
	v_lshlrev_b32_e32 v201, 16, v101
	v_and_b32_e32 v152, 0xffff0000, v129
	v_and_b32_e32 v101, 0xffff0000, v101
	v_lshlrev_b32_e32 v107, 16, v109
	v_lshlrev_b32_e32 v129, 16, v106
	v_and_b32_e32 v106, 0xffff0000, v109
	v_lshlrev_b32_e32 v206, 16, v91
	v_and_b32_e32 v91, 0xffff0000, v91
	v_lshlrev_b32_e32 v207, 16, v92
	v_and_b32_e32 v92, 0xffff0000, v92
	v_lshlrev_b32_e32 v208, 16, v93
	v_and_b32_e32 v93, 0xffff0000, v93
	v_lshlrev_b32_e32 v209, 16, v81
	v_and_b32_e32 v81, 0xffff0000, v81
	v_lshlrev_b32_e32 v214, 16, v71
	v_and_b32_e32 v71, 0xffff0000, v71
	v_lshlrev_b32_e32 v215, 16, v72
	v_and_b32_e32 v72, 0xffff0000, v72
	v_lshlrev_b32_e32 v216, 16, v73
	v_and_b32_e32 v73, 0xffff0000, v73
	v_lshlrev_b32_e32 v220, 16, v51
	v_and_b32_e32 v51, 0xffff0000, v51
	v_lshlrev_b32_e32 v221, 16, v52
	v_and_b32_e32 v52, 0xffff0000, v52
	v_lshlrev_b32_e32 v222, 16, v53
	v_and_b32_e32 v53, 0xffff0000, v53
	v_lshlrev_b32_e32 v223, 16, v41
	v_and_b32_e32 v41, 0xffff0000, v41
	v_and_b32_e32 v224, 0xffff0000, v114
	v_lshlrev_b32_e32 v225, 16, v115
	v_and_b32_e32 v226, 0xffff0000, v115
	v_lshlrev_b32_e32 v227, 16, v116
	v_and_b32_e32 v228, 0xffff0000, v116
	v_lshlrev_b32_e32 v115, 16, v31
	v_and_b32_e32 v116, 0xffff0000, v31
	v_lshlrev_b32_e32 v229, 16, v117
	v_lshlrev_b32_e32 v230, 16, v29
	v_and_b32_e32 v31, 0xffff0000, v32
	v_and_b32_e32 v117, 0xffff0000, v117
	v_and_b32_e32 v29, 0xffff0000, v29
	v_lshlrev_b32_e32 v231, 16, v14
	v_and_b32_e32 v232, 0xffff0000, v14
	v_lshlrev_b32_e32 v233, 16, v15
	v_and_b32_e32 v235, 0xffff0000, v15
	v_lshlrev_b32_e32 v236, 16, v16
	v_and_b32_e32 v237, 0xffff0000, v16
	v_lshlrev_b32_e32 v238, 16, v17
	v_lshlrev_b32_e32 v240, 16, v20
	v_and_b32_e32 v241, 0xffff0000, v20
	v_and_b32_e32 v239, 0xffff0000, v17
	v_lshlrev_b32_e32 v242, 16, v21
	v_and_b32_e32 v243, 0xffff0000, v21
	v_lshlrev_b32_e32 v244, 16, v61
	v_and_b32_e32 v61, 0xffff0000, v61
	s_add_u32 s44, s8, s16
	s_addc_u32 s45, s9, s17
	s_waitcnt vmcnt(1)
	v_fmac_f32_e32 v188, v191, v94
	v_mul_f32_e32 v94, v183, v198
	v_fmac_f32_e32 v187, v192, v94
	v_mul_f32_e32 v94, v183, v95
	v_lshlrev_b32_e32 v198, 16, v98
	v_and_b32_e32 v98, 0xffff0000, v98
	v_fmac_f32_e32 v186, v193, v94
	v_mul_f32_e32 v94, v183, v199
	v_lshlrev_b32_e32 v199, 16, v99
	v_mul_f32_e32 v98, v182, v98
	s_waitcnt vmcnt(0)
	v_fmac_f32_e32 v185, v194, v94
	v_mul_f32_e32 v94, v183, v96
	v_and_b32_e32 v99, 0xffff0000, v99
	v_fmac_f32_e32 v128, v191, v98
	v_mul_f32_e32 v98, v182, v199
	v_fmac_f32_e32 v184, v195, v94
	v_mul_f32_e32 v94, v183, v200
	v_lshlrev_b32_e32 v200, 16, v100
	v_fmac_f32_e32 v127, v192, v98
	v_mul_f32_e32 v98, v182, v99
	v_fmac_f32_e32 v189, v190, v121
	v_and_b32_e32 v100, 0xffff0000, v100
	v_lshlrev_b32_e32 v121, 16, v108
	v_fmac_f32_e32 v126, v193, v98
	v_mul_f32_e32 v98, v182, v200
	v_and_b32_e32 v108, 0xffff0000, v108
	v_fmac_f32_e32 v121, v194, v98
	v_mul_f32_e32 v98, v182, v100
	v_fmac_f32_e32 v153, v196, v94
	v_mul_f32_e32 v94, v183, v97
	v_fmac_f32_e32 v108, v195, v98
	v_mul_f32_e32 v98, v182, v201
	v_fmac_f32_e32 v152, v197, v94
	v_cvt_pk_bf16_f32 v94, v189, v188
	v_cvt_pk_bf16_f32 v95, v187, v186
	v_cvt_pk_bf16_f32 v96, v185, v184
	v_cvt_pk_bf16_f32 v97, v153, v152
	v_mul_f32_e32 v109, v182, v198
	v_fmac_f32_e32 v107, v196, v98
	v_mul_f32_e32 v98, v182, v101
	global_store_dwordx4 v[102:103], v[94:97], off offset:16
	v_fmac_f32_e32 v129, v190, v109
	v_fmac_f32_e32 v106, v197, v98
	v_cvt_pk_bf16_f32 v94, v189, v188
	v_cvt_pk_bf16_f32 v95, v187, v186
	v_cvt_pk_bf16_f32 v96, v185, v184
	v_cvt_pk_bf16_f32 v97, v153, v152
	v_cvt_pk_bf16_f32 v98, v129, v128
	v_cvt_pk_bf16_f32 v99, v127, v126
	v_cvt_pk_bf16_f32 v100, v121, v108
	v_cvt_pk_bf16_f32 v101, v107, v106
	global_store_dwordx4 v168, v[98:101], s[4:5] offset:16
	v_lshlrev_b32_e32 v109, 16, v90
	v_and_b32_e32 v90, 0xffff0000, v90
	v_cvt_pk_bf16_f32 v98, v129, v128
	v_cvt_pk_bf16_f32 v99, v127, v126
	v_cvt_pk_bf16_f32 v100, v121, v108
	v_cvt_pk_bf16_f32 v101, v107, v106
	global_load_dwordx4 v[198:201], v[134:135], off
	global_load_dwordx4 v[202:205], v[134:135], off offset:16
	v_lshlrev_b32_e32 v197, 16, v86
	v_and_b32_e32 v196, 0xffff0000, v86
	v_mul_f32_e32 v86, v183, v109
	v_lshlrev_b32_e32 v195, 16, v87
	v_and_b32_e32 v194, 0xffff0000, v87
	v_lshlrev_b32_e32 v193, 16, v88
	v_and_b32_e32 v192, 0xffff0000, v88
	v_lshlrev_b32_e32 v191, 16, v89
	v_and_b32_e32 v190, 0xffff0000, v89
	v_lshlrev_b32_e32 v109, 16, v82
	s_waitcnt vmcnt(1)
	v_fmac_f32_e32 v197, v86, v198
	v_mul_f32_e32 v86, v183, v90
	v_fmac_f32_e32 v196, v86, v199
	v_mul_f32_e32 v86, v183, v206
	v_fmac_f32_e32 v195, v86, v200
	v_mul_f32_e32 v86, v183, v91
	v_fmac_f32_e32 v194, v86, v201
	v_mul_f32_e32 v86, v183, v207
	s_waitcnt vmcnt(0)
	v_fmac_f32_e32 v193, v86, v202
	v_mul_f32_e32 v86, v183, v92
	v_fmac_f32_e32 v192, v86, v203
	v_mul_f32_e32 v86, v183, v208
	v_lshlrev_b32_e32 v206, 16, v78
	v_and_b32_e32 v78, 0xffff0000, v78
	v_fmac_f32_e32 v191, v86, v204
	v_mul_f32_e32 v86, v183, v93
	v_lshlrev_b32_e32 v207, 16, v79
	v_and_b32_e32 v93, 0xffff0000, v82
	v_mul_f32_e32 v78, v182, v78
	v_and_b32_e32 v79, 0xffff0000, v79
	v_lshlrev_b32_e32 v92, 16, v83
	v_fmac_f32_e32 v93, v78, v199
	v_mul_f32_e32 v78, v182, v207
	v_lshlrev_b32_e32 v208, 16, v80
	v_and_b32_e32 v91, 0xffff0000, v83
	v_fmac_f32_e32 v92, v78, v200
	v_mul_f32_e32 v78, v182, v79
	v_and_b32_e32 v80, 0xffff0000, v80
	v_lshlrev_b32_e32 v90, 16, v84
	v_fmac_f32_e32 v91, v78, v201
	v_mul_f32_e32 v78, v182, v208
	v_and_b32_e32 v84, 0xffff0000, v84
	v_fmac_f32_e32 v90, v78, v202
	v_mul_f32_e32 v78, v182, v80
	v_lshlrev_b32_e32 v83, 16, v85
	v_fmac_f32_e32 v84, v78, v203
	v_mul_f32_e32 v78, v182, v209
	v_fmac_f32_e32 v190, v86, v205
	v_cvt_pk_bf16_f32 v86, v197, v196
	v_cvt_pk_bf16_f32 v87, v195, v194
	v_cvt_pk_bf16_f32 v88, v193, v192
	v_cvt_pk_bf16_f32 v89, v191, v190
	v_and_b32_e32 v82, 0xffff0000, v85
	v_mul_f32_e32 v85, v182, v206
	v_fmac_f32_e32 v83, v78, v204
	v_mul_f32_e32 v78, v182, v81
	global_store_dwordx4 v[102:103], v[86:89], off offset:2048
	v_fmac_f32_e32 v109, v85, v198
	v_fmac_f32_e32 v82, v78, v205
	v_cvt_pk_bf16_f32 v86, v197, v196
	v_cvt_pk_bf16_f32 v87, v195, v194
	v_cvt_pk_bf16_f32 v88, v193, v192
	v_cvt_pk_bf16_f32 v89, v191, v190
	v_cvt_pk_bf16_f32 v78, v109, v93
	v_cvt_pk_bf16_f32 v79, v92, v91
	v_cvt_pk_bf16_f32 v80, v90, v84
	v_cvt_pk_bf16_f32 v81, v83, v82
	global_store_dwordx4 v168, v[78:81], s[4:5] offset:2048
	v_lshlrev_b32_e32 v85, 16, v70
	v_and_b32_e32 v70, 0xffff0000, v70
	v_cvt_pk_bf16_f32 v78, v109, v93
	v_cvt_pk_bf16_f32 v79, v92, v91
	v_cvt_pk_bf16_f32 v80, v90, v84
	v_cvt_pk_bf16_f32 v81, v83, v82
	global_load_dwordx4 v[206:209], v[136:137], off
	global_load_dwordx4 v[210:213], v[136:137], off offset:16
	v_lshlrev_b32_e32 v205, 16, v66
	v_and_b32_e32 v204, 0xffff0000, v66
	v_mul_f32_e32 v66, v183, v85
	v_lshlrev_b32_e32 v203, 16, v67
	v_and_b32_e32 v202, 0xffff0000, v67
	v_lshlrev_b32_e32 v201, 16, v68
	v_and_b32_e32 v200, 0xffff0000, v68
	v_lshlrev_b32_e32 v199, 16, v69
	v_and_b32_e32 v198, 0xffff0000, v69
	v_lshlrev_b32_e32 v85, 16, v62
	s_waitcnt vmcnt(1)
	v_fmac_f32_e32 v205, v66, v206
	v_mul_f32_e32 v66, v183, v70
	v_fmac_f32_e32 v204, v66, v207
	v_mul_f32_e32 v66, v183, v214
	v_fmac_f32_e32 v203, v66, v208
	v_mul_f32_e32 v66, v183, v71
	v_fmac_f32_e32 v202, v66, v209
	v_mul_f32_e32 v66, v183, v215
	s_waitcnt vmcnt(0)
	v_fmac_f32_e32 v201, v66, v210
	v_mul_f32_e32 v66, v183, v72
	v_fmac_f32_e32 v200, v66, v211
	v_mul_f32_e32 v66, v183, v216
	v_fmac_f32_e32 v199, v66, v212
	v_mul_f32_e32 v66, v183, v73
	v_fmac_f32_e32 v198, v66, v213
	v_cvt_pk_bf16_f32 v66, v205, v204
	v_cvt_pk_bf16_f32 v67, v203, v202
	v_cvt_pk_bf16_f32 v68, v201, v200
	v_cvt_pk_bf16_f32 v69, v199, v198
	global_store_dwordx4 v[102:103], v[66:69], off offset:2064
	v_lshlrev_b32_e32 v102, 16, v54
	v_and_b32_e32 v54, 0xffff0000, v54
	v_lshlrev_b32_e32 v103, 16, v55
	v_and_b32_e32 v73, 0xffff0000, v62
	v_mul_f32_e32 v54, v182, v54
	v_and_b32_e32 v55, 0xffff0000, v55
	v_lshlrev_b32_e32 v72, 16, v63
	v_fmac_f32_e32 v73, v54, v207
	v_mul_f32_e32 v54, v182, v103
	v_lshlrev_b32_e32 v214, 16, v56
	v_and_b32_e32 v71, 0xffff0000, v63
	v_fmac_f32_e32 v72, v54, v208
	v_mul_f32_e32 v54, v182, v55
	v_and_b32_e32 v56, 0xffff0000, v56
	v_lshlrev_b32_e32 v70, 16, v64
	v_fmac_f32_e32 v71, v54, v209
	v_mul_f32_e32 v54, v182, v214
	v_lshlrev_b32_e32 v215, 16, v57
	v_and_b32_e32 v64, 0xffff0000, v64
	v_fmac_f32_e32 v70, v54, v210
	v_mul_f32_e32 v54, v182, v56
	v_and_b32_e32 v57, 0xffff0000, v57
	v_lshlrev_b32_e32 v63, 16, v65
	v_fmac_f32_e32 v64, v54, v211
	v_mul_f32_e32 v54, v182, v215
	v_and_b32_e32 v62, 0xffff0000, v65
	v_mul_f32_e32 v65, v182, v102
	v_fmac_f32_e32 v63, v54, v212
	v_mul_f32_e32 v54, v182, v57
	v_cvt_pk_bf16_f32 v66, v205, v204
	v_cvt_pk_bf16_f32 v67, v203, v202
	v_cvt_pk_bf16_f32 v68, v201, v200
	v_cvt_pk_bf16_f32 v69, v199, v198
	v_fmac_f32_e32 v85, v65, v206
	v_fmac_f32_e32 v62, v54, v213
	v_cvt_pk_bf16_f32 v54, v85, v73
	v_cvt_pk_bf16_f32 v55, v72, v71
	v_cvt_pk_bf16_f32 v56, v70, v64
	v_cvt_pk_bf16_f32 v57, v63, v62
	global_store_dwordx4 v168, v[54:57], s[4:5] offset:2064
	v_lshlrev_b32_e32 v65, 16, v50
	v_and_b32_e32 v50, 0xffff0000, v50
	v_cvt_pk_bf16_f32 v54, v85, v73
	v_cvt_pk_bf16_f32 v55, v72, v71
	v_cvt_pk_bf16_f32 v56, v70, v64
	v_cvt_pk_bf16_f32 v57, v63, v62
	global_load_dwordx4 v[212:215], v[138:139], off
	global_load_dwordx4 v[216:219], v[138:139], off offset:16
	v_lshlrev_b32_e32 v211, 16, v46
	v_and_b32_e32 v210, 0xffff0000, v46
	v_mul_f32_e32 v46, v183, v65
	v_lshlrev_b32_e32 v209, 16, v47
	v_and_b32_e32 v208, 0xffff0000, v47
	v_lshlrev_b32_e32 v207, 16, v48
	v_and_b32_e32 v206, 0xffff0000, v48
	v_lshlrev_b32_e32 v103, 16, v49
	v_and_b32_e32 v102, 0xffff0000, v49
	v_lshlrev_b32_e32 v65, 16, v42
	s_waitcnt vmcnt(1)
	v_fmac_f32_e32 v211, v46, v212
	v_mul_f32_e32 v46, v183, v50
	v_fmac_f32_e32 v210, v46, v213
	v_mul_f32_e32 v46, v183, v220
	v_fmac_f32_e32 v209, v46, v214
	v_mul_f32_e32 v46, v183, v51
	v_fmac_f32_e32 v208, v46, v215
	v_mul_f32_e32 v46, v183, v221
	s_waitcnt vmcnt(0)
	v_fmac_f32_e32 v207, v46, v216
	v_mul_f32_e32 v46, v183, v52
	v_fmac_f32_e32 v206, v46, v217
	v_mul_f32_e32 v46, v183, v222
	v_lshlrev_b32_e32 v220, 16, v38
	v_and_b32_e32 v38, 0xffff0000, v38
	v_fmac_f32_e32 v103, v46, v218
	v_mul_f32_e32 v46, v183, v53
	v_lshlrev_b32_e32 v221, 16, v39
	v_and_b32_e32 v53, 0xffff0000, v42
	v_mul_f32_e32 v38, v182, v38
	v_and_b32_e32 v39, 0xffff0000, v39
	v_lshlrev_b32_e32 v52, 16, v43
	v_fmac_f32_e32 v53, v38, v213
	v_mul_f32_e32 v38, v182, v221
	v_lshlrev_b32_e32 v222, 16, v40
	v_and_b32_e32 v51, 0xffff0000, v43
	v_fmac_f32_e32 v52, v38, v214
	v_mul_f32_e32 v38, v182, v39
	v_and_b32_e32 v40, 0xffff0000, v40
	v_lshlrev_b32_e32 v50, 16, v44
	v_fmac_f32_e32 v51, v38, v215
	v_mul_f32_e32 v38, v182, v222
	v_and_b32_e32 v44, 0xffff0000, v44
	v_fmac_f32_e32 v50, v38, v216
	v_mul_f32_e32 v38, v182, v40
	v_lshlrev_b32_e32 v43, 16, v45
	v_fmac_f32_e32 v44, v38, v217
	v_mul_f32_e32 v38, v182, v223
	v_fmac_f32_e32 v102, v46, v219
	v_cvt_pk_bf16_f32 v46, v211, v210
	v_cvt_pk_bf16_f32 v47, v209, v208
	v_cvt_pk_bf16_f32 v48, v207, v206
	v_cvt_pk_bf16_f32 v49, v103, v102
	v_and_b32_e32 v42, 0xffff0000, v45
	v_mul_f32_e32 v45, v182, v220
	v_fmac_f32_e32 v43, v38, v218
	v_mul_f32_e32 v38, v182, v41
	global_store_dwordx4 v[110:111], v[46:49], off
	v_fmac_f32_e32 v65, v45, v212
	v_fmac_f32_e32 v42, v38, v219
	v_cvt_pk_bf16_f32 v46, v211, v210
	v_cvt_pk_bf16_f32 v47, v209, v208
	v_cvt_pk_bf16_f32 v48, v207, v206
	v_cvt_pk_bf16_f32 v49, v103, v102
	v_cvt_pk_bf16_f32 v38, v65, v53
	v_cvt_pk_bf16_f32 v39, v52, v51
	v_cvt_pk_bf16_f32 v40, v50, v44
	v_cvt_pk_bf16_f32 v41, v43, v42
	global_store_dwordx4 v160, v[38:41], s[4:5]
	v_lshlrev_b32_e32 v45, 16, v34
	v_and_b32_e32 v34, 0xffff0000, v34
	v_cvt_pk_bf16_f32 v38, v65, v53
	v_cvt_pk_bf16_f32 v39, v52, v51
	v_cvt_pk_bf16_f32 v40, v50, v44
	v_cvt_pk_bf16_f32 v41, v43, v42
	global_load_dwordx4 v[212:215], v[140:141], off
	global_load_dwordx4 v[216:219], v[140:141], off offset:16
	v_lshlrev_b32_e32 v220, 16, v35
	v_mul_f32_e32 v34, v183, v34
	v_and_b32_e32 v35, 0xffff0000, v35
	v_lshlrev_b32_e32 v221, 16, v36
	v_and_b32_e32 v36, 0xffff0000, v36
	v_lshlrev_b32_e32 v223, 16, v114
	v_and_b32_e32 v114, 0xffff0000, v30
	v_lshlrev_b32_e32 v222, 16, v37
	v_mul_f32_e32 v45, v183, v45
	v_and_b32_e32 v37, 0xffff0000, v37
	s_waitcnt vmcnt(1)
	v_fmac_f32_e32 v224, v34, v213
	v_mul_f32_e32 v34, v183, v220
	v_fmac_f32_e32 v225, v34, v214
	v_mul_f32_e32 v34, v183, v35
	v_lshlrev_b32_e32 v220, 16, v26
	v_and_b32_e32 v26, 0xffff0000, v26
	v_fmac_f32_e32 v226, v34, v215
	v_mul_f32_e32 v34, v183, v221
	v_lshlrev_b32_e32 v221, 16, v27
	v_mul_f32_e32 v26, v182, v26
	s_waitcnt vmcnt(0)
	v_fmac_f32_e32 v227, v34, v216
	v_mul_f32_e32 v34, v183, v36
	v_and_b32_e32 v27, 0xffff0000, v27
	v_fmac_f32_e32 v114, v26, v213
	v_mul_f32_e32 v26, v182, v221
	v_fmac_f32_e32 v228, v34, v217
	v_mul_f32_e32 v34, v183, v222
	v_lshlrev_b32_e32 v222, 16, v28
	v_fmac_f32_e32 v115, v26, v214
	v_mul_f32_e32 v26, v182, v27
	v_fmac_f32_e32 v223, v45, v212
	v_and_b32_e32 v28, 0xffff0000, v28
	v_lshlrev_b32_e32 v45, 16, v30
	v_lshlrev_b32_e32 v30, 16, v32
	v_fmac_f32_e32 v116, v26, v215
	v_mul_f32_e32 v26, v182, v222
	v_fmac_f32_e32 v30, v26, v216
	v_mul_f32_e32 v26, v182, v28
	v_fmac_f32_e32 v229, v34, v218
	v_mul_f32_e32 v34, v183, v37
	v_lshlrev_b32_e32 v32, 16, v33
	v_fmac_f32_e32 v31, v26, v217
	v_mul_f32_e32 v26, v182, v230
	v_fmac_f32_e32 v117, v34, v219
	v_cvt_pk_bf16_f32 v34, v223, v224
	v_cvt_pk_bf16_f32 v35, v225, v226
	v_cvt_pk_bf16_f32 v36, v227, v228
	v_cvt_pk_bf16_f32 v37, v229, v117
	v_and_b32_e32 v33, 0xffff0000, v33
	v_mul_f32_e32 v220, v182, v220
	v_fmac_f32_e32 v32, v26, v218
	v_mul_f32_e32 v26, v182, v29
	global_store_dwordx4 v[110:111], v[34:37], off offset:16
	v_fmac_f32_e32 v45, v220, v212
	v_fmac_f32_e32 v33, v26, v219
	v_cvt_pk_bf16_f32 v34, v223, v224
	v_cvt_pk_bf16_f32 v35, v225, v226
	v_cvt_pk_bf16_f32 v36, v227, v228
	v_cvt_pk_bf16_f32 v37, v229, v117
	v_cvt_pk_bf16_f32 v26, v45, v114
	v_cvt_pk_bf16_f32 v27, v115, v116
	v_cvt_pk_bf16_f32 v28, v30, v31
	v_cvt_pk_bf16_f32 v29, v32, v33
	global_store_dwordx4 v164, v[26:29], s[4:5]
	v_lshlrev_b32_e32 v220, 16, v22
	v_and_b32_e32 v22, 0xffff0000, v22
	v_cvt_pk_bf16_f32 v26, v45, v114
	v_cvt_pk_bf16_f32 v27, v115, v116
	v_cvt_pk_bf16_f32 v28, v30, v31
	v_cvt_pk_bf16_f32 v29, v32, v33
	global_load_dwordx4 v[212:215], v[142:143], off
	global_load_dwordx4 v[216:219], v[142:143], off offset:16
	v_mul_f32_e32 v14, v183, v220
	v_lshlrev_b32_e32 v221, 16, v23
	v_and_b32_e32 v23, 0xffff0000, v23
	v_lshlrev_b32_e32 v222, 16, v24
	v_and_b32_e32 v24, 0xffff0000, v24
	v_lshlrev_b32_e32 v230, 16, v25
	v_and_b32_e32 v25, 0xffff0000, v25
	v_lshlrev_b32_e32 v220, 16, v18
	s_waitcnt vmcnt(1)
	v_fmac_f32_e32 v231, v14, v212
	v_mul_f32_e32 v14, v183, v22
	v_fmac_f32_e32 v232, v14, v213
	v_mul_f32_e32 v14, v183, v221
	v_fmac_f32_e32 v233, v14, v214
	v_mul_f32_e32 v14, v183, v23
	v_lshlrev_b32_e32 v22, 16, v10
	v_and_b32_e32 v10, 0xffff0000, v10
	v_fmac_f32_e32 v235, v14, v215
	v_mul_f32_e32 v14, v183, v222
	v_lshlrev_b32_e32 v23, 16, v11
	v_and_b32_e32 v221, 0xffff0000, v18
	v_mul_f32_e32 v10, v182, v10
	s_waitcnt vmcnt(0)
	v_fmac_f32_e32 v236, v14, v216
	v_mul_f32_e32 v14, v183, v24
	v_and_b32_e32 v11, 0xffff0000, v11
	v_lshlrev_b32_e32 v222, 16, v19
	v_fmac_f32_e32 v221, v10, v213
	v_mul_f32_e32 v10, v182, v23
	v_fmac_f32_e32 v237, v14, v217
	v_mul_f32_e32 v14, v183, v230
	v_lshlrev_b32_e32 v24, 16, v12
	v_and_b32_e32 v230, 0xffff0000, v19
	v_fmac_f32_e32 v222, v10, v214
	v_mul_f32_e32 v10, v182, v11
	v_and_b32_e32 v12, 0xffff0000, v12
	v_fmac_f32_e32 v230, v10, v215
	v_mul_f32_e32 v10, v182, v24
	v_fmac_f32_e32 v238, v14, v218
	v_mul_f32_e32 v14, v183, v25
	v_lshlrev_b32_e32 v25, 16, v13
	v_fmac_f32_e32 v240, v10, v216
	v_mul_f32_e32 v10, v182, v12
	v_and_b32_e32 v13, 0xffff0000, v13
	v_fmac_f32_e32 v241, v10, v217
	v_mul_f32_e32 v10, v182, v25
	v_fmac_f32_e32 v239, v14, v219
	v_cvt_pk_bf16_f32 v14, v231, v232
	v_cvt_pk_bf16_f32 v15, v233, v235
	v_cvt_pk_bf16_f32 v16, v236, v237
	v_cvt_pk_bf16_f32 v17, v238, v239
	v_mul_f32_e32 v18, v182, v22
	v_fmac_f32_e32 v242, v10, v218
	v_mul_f32_e32 v10, v182, v13
	global_store_dwordx4 v[110:111], v[14:17], off offset:2048
	v_fmac_f32_e32 v220, v18, v212
	v_fmac_f32_e32 v243, v10, v219
	v_cvt_pk_bf16_f32 v14, v231, v232
	v_cvt_pk_bf16_f32 v15, v233, v235
	v_cvt_pk_bf16_f32 v16, v236, v237
	v_cvt_pk_bf16_f32 v17, v238, v239
	v_cvt_pk_bf16_f32 v10, v220, v221
	v_cvt_pk_bf16_f32 v11, v222, v230
	v_cvt_pk_bf16_f32 v12, v240, v241
	v_cvt_pk_bf16_f32 v13, v242, v243
	global_store_dwordx4 v161, v[10:13], s[4:5]
	v_lshlrev_b32_e32 v212, 16, v6
	v_and_b32_e32 v6, 0xffff0000, v6
	v_cvt_pk_bf16_f32 v10, v220, v221
	v_cvt_pk_bf16_f32 v11, v222, v230
	v_cvt_pk_bf16_f32 v12, v240, v241
	v_cvt_pk_bf16_f32 v13, v242, v243
	global_load_dwordx4 v[18:21], v[144:145], off
	global_load_dwordx4 v[22:25], v[144:145], off offset:16
	v_lshlrev_b32_e32 v213, 16, v7
	v_lshlrev_b32_e32 v216, 16, v74
	v_and_b32_e32 v74, 0xffff0000, v74
	v_mul_f32_e32 v6, v183, v6
	v_and_b32_e32 v7, 0xffff0000, v7
	v_lshlrev_b32_e32 v217, 16, v75
	v_lshlrev_b32_e32 v214, 16, v8
	v_and_b32_e32 v75, 0xffff0000, v75
	v_and_b32_e32 v8, 0xffff0000, v8
	v_lshlrev_b32_e32 v218, 16, v76
	v_lshlrev_b32_e32 v215, 16, v9
	v_and_b32_e32 v76, 0xffff0000, v76
	v_and_b32_e32 v9, 0xffff0000, v9
	v_lshlrev_b32_e32 v219, 16, v77
	v_and_b32_e32 v77, 0xffff0000, v77
	v_mul_f32_e32 v212, v183, v212
	s_waitcnt vmcnt(1)
	v_fmac_f32_e32 v74, v6, v19
	v_mul_f32_e32 v6, v183, v213
	v_fmac_f32_e32 v217, v6, v20
	v_mul_f32_e32 v6, v183, v7
	v_fmac_f32_e32 v75, v6, v21
	v_mul_f32_e32 v6, v183, v214
	s_waitcnt vmcnt(0)
	v_fmac_f32_e32 v218, v6, v22
	v_mul_f32_e32 v6, v183, v8
	v_fmac_f32_e32 v76, v6, v23
	v_mul_f32_e32 v6, v183, v215
	v_fmac_f32_e32 v219, v6, v24
	v_mul_f32_e32 v6, v183, v9
	v_fmac_f32_e32 v216, v212, v18
	v_fmac_f32_e32 v77, v6, v25
	v_cvt_pk_bf16_f32 v6, v216, v74
	v_cvt_pk_bf16_f32 v7, v217, v75
	v_cvt_pk_bf16_f32 v8, v218, v76
	v_cvt_pk_bf16_f32 v9, v219, v77
	global_store_dwordx4 v[110:111], v[6:9], off offset:2064
	v_lshlrev_b32_e32 v110, 16, v2
	v_lshlrev_b32_e32 v213, 16, v58
	v_mul_f32_e32 v110, v182, v110
	v_fmac_f32_e32 v213, v110, v18
	v_mul_f32_e32 v18, v181, v181
	v_fmac_f32_e32 v18, v179, v179
	v_fmac_f32_e32 v18, v180, v180
	v_fmac_f32_e32 v18, v178, v178
	v_fmac_f32_e32 v18, v177, v177
	v_fmac_f32_e32 v18, v176, v176
	v_fmac_f32_e32 v18, v175, v175
	v_fmac_f32_e32 v18, v174, v174
	v_fmac_f32_e32 v18, v189, v189
	v_fmac_f32_e32 v18, v188, v188
	v_fmac_f32_e32 v18, v187, v187
	v_fmac_f32_e32 v18, v186, v186
	v_fmac_f32_e32 v18, v185, v185
	v_fmac_f32_e32 v18, v184, v184
	v_fmac_f32_e32 v18, v153, v153
	v_fmac_f32_e32 v18, v152, v152
	v_fmac_f32_e32 v18, v197, v197
	v_fmac_f32_e32 v18, v196, v196
	v_fmac_f32_e32 v18, v195, v195
	v_fmac_f32_e32 v18, v194, v194
	v_fmac_f32_e32 v18, v193, v193
	v_fmac_f32_e32 v18, v192, v192
	v_fmac_f32_e32 v18, v191, v191
	v_fmac_f32_e32 v18, v190, v190
	v_fmac_f32_e32 v18, v205, v205
	v_fmac_f32_e32 v18, v204, v204
	v_fmac_f32_e32 v18, v203, v203
	v_fmac_f32_e32 v18, v202, v202
	v_fmac_f32_e32 v18, v201, v201
	v_fmac_f32_e32 v18, v200, v200
	v_fmac_f32_e32 v18, v199, v199
	v_and_b32_e32 v2, 0xffff0000, v2
	v_fmac_f32_e32 v18, v198, v198
	v_and_b32_e32 v58, 0xffff0000, v58
	v_mul_f32_e32 v2, v182, v2
	v_fmac_f32_e32 v18, v211, v211
	v_fmac_f32_e32 v58, v2, v19
	v_fmac_f32_e32 v18, v210, v210
	v_mul_f32_e32 v19, v173, v173
	v_fmac_f32_e32 v18, v209, v209
	v_fmac_f32_e32 v19, v171, v171
	v_fmac_f32_e32 v18, v208, v208
	v_fmac_f32_e32 v19, v172, v172
	v_fmac_f32_e32 v18, v207, v207
	v_fmac_f32_e32 v19, v170, v170
	v_fmac_f32_e32 v18, v206, v206
	v_fmac_f32_e32 v19, v169, v169
	v_fmac_f32_e32 v18, v103, v103
	v_fmac_f32_e32 v19, v125, v125
	v_fmac_f32_e32 v18, v102, v102
	v_fmac_f32_e32 v19, v124, v124
	v_fmac_f32_e32 v18, v223, v223
	v_fmac_f32_e32 v19, v120, v120
	v_fmac_f32_e32 v18, v224, v224
	v_fmac_f32_e32 v19, v129, v129
	v_fmac_f32_e32 v18, v225, v225
	v_fmac_f32_e32 v19, v128, v128
	v_fmac_f32_e32 v18, v226, v226
	v_fmac_f32_e32 v19, v127, v127
	v_fmac_f32_e32 v18, v227, v227
	v_fmac_f32_e32 v19, v126, v126
	v_fmac_f32_e32 v18, v228, v228
	v_fmac_f32_e32 v19, v121, v121
	v_fmac_f32_e32 v18, v229, v229
	v_fmac_f32_e32 v19, v108, v108
	v_fmac_f32_e32 v18, v117, v117
	v_fmac_f32_e32 v19, v107, v107
	v_fmac_f32_e32 v18, v231, v231
	v_fmac_f32_e32 v19, v106, v106
	v_fmac_f32_e32 v18, v232, v232
	v_fmac_f32_e32 v19, v109, v109
	v_fmac_f32_e32 v18, v233, v233
	v_fmac_f32_e32 v19, v93, v93
	v_fmac_f32_e32 v18, v235, v235
	v_fmac_f32_e32 v19, v92, v92
	v_fmac_f32_e32 v18, v236, v236
	v_fmac_f32_e32 v19, v91, v91
	v_fmac_f32_e32 v18, v237, v237
	v_fmac_f32_e32 v19, v90, v90
	v_fmac_f32_e32 v18, v238, v238
	v_fmac_f32_e32 v19, v84, v84
	v_fmac_f32_e32 v18, v239, v239
	v_fmac_f32_e32 v19, v83, v83
	v_fmac_f32_e32 v18, v216, v216
	v_fmac_f32_e32 v19, v82, v82
	v_fmac_f32_e32 v18, v74, v74
	v_fmac_f32_e32 v19, v85, v85
	v_fmac_f32_e32 v18, v217, v217
	v_fmac_f32_e32 v19, v73, v73
	v_fmac_f32_e32 v18, v75, v75
	v_fmac_f32_e32 v19, v72, v72
	v_fmac_f32_e32 v18, v218, v218
	v_fmac_f32_e32 v19, v71, v71
	v_fmac_f32_e32 v18, v76, v76
	v_fmac_f32_e32 v19, v70, v70
	v_lshlrev_b32_e32 v111, 16, v3
	v_fmac_f32_e32 v18, v219, v219
	v_fmac_f32_e32 v19, v64, v64
	v_lshlrev_b32_e32 v214, 16, v59
	v_mul_f32_e32 v2, v182, v111
	v_fmac_f32_e32 v18, v77, v77
	v_fmac_f32_e32 v19, v63, v63
	v_fmac_f32_e32 v214, v2, v20
	v_fmac_f32_e32 v19, v62, v62
	v_fmac_f32_e32 v19, v65, v65
	v_fmac_f32_e32 v19, v53, v53
	v_fmac_f32_e32 v19, v52, v52
	v_fmac_f32_e32 v19, v51, v51
	v_fmac_f32_e32 v19, v50, v50
	s_waitcnt lgkmcnt(0)
	s_nop 1
	v_add_f32_dpp v18, v18, v18 quad_perm:[1,0,3,2] row_mask:0xf bank_mask:0xf
	v_fmac_f32_e32 v19, v44, v44
	v_fmac_f32_e32 v19, v43, v43
	v_fmac_f32_e32 v19, v42, v42
	v_fmac_f32_e32 v19, v45, v45
	v_fmac_f32_e32 v19, v114, v114
	v_fmac_f32_e32 v19, v115, v115
	s_waitcnt lgkmcnt(0)
	s_nop 1
	v_add_f32_dpp v18, v18, v18 quad_perm:[2,3,0,1] row_mask:0xf bank_mask:0xf
	v_fmac_f32_e32 v19, v116, v116
	v_fmac_f32_e32 v19, v30, v30
	v_fmac_f32_e32 v19, v31, v31
	v_fmac_f32_e32 v19, v32, v32
	v_fmac_f32_e32 v19, v33, v33
	v_fmac_f32_e32 v19, v220, v220
	s_waitcnt lgkmcnt(0)
	s_nop 1
	v_add_f32_dpp v18, v18, v18 row_half_mirror row_mask:0xf bank_mask:0xf
	v_fmac_f32_e32 v19, v221, v221
	v_fmac_f32_e32 v19, v222, v222
	v_fmac_f32_e32 v19, v230, v230
	v_fmac_f32_e32 v19, v240, v240
	v_fmac_f32_e32 v19, v241, v241
	v_fmac_f32_e32 v19, v242, v242
	s_waitcnt lgkmcnt(0)
	s_nop 1
	v_add_f32_dpp v18, v18, v18 row_mirror row_mask:0xf bank_mask:0xf
	v_fmac_f32_e32 v19, v243, v243
	v_and_b32_e32 v3, 0xffff0000, v3
	v_fmac_f32_e32 v19, v213, v213
	v_lshlrev_b32_e32 v183, 16, v4
	v_and_b32_e32 v59, 0xffff0000, v59
	v_mul_f32_e32 v2, v182, v3
	v_fmac_f32_e32 v19, v58, v58
	v_and_b32_e32 v4, 0xffff0000, v4
	v_lshlrev_b32_e32 v215, 16, v60
	v_fmac_f32_e32 v59, v2, v21
	v_mul_f32_e32 v2, v182, v183
	v_fmac_f32_e32 v19, v214, v214
	v_lshlrev_b32_e32 v212, 16, v5
	v_and_b32_e32 v60, 0xffff0000, v60
	v_fmac_f32_e32 v215, v2, v22
	v_mul_f32_e32 v2, v182, v4
	v_fmac_f32_e32 v19, v59, v59
	v_and_b32_e32 v5, 0xffff0000, v5
	v_fmac_f32_e32 v60, v2, v23
	v_mul_f32_e32 v2, v182, v212
	s_waitcnt lgkmcnt(0)
	v_mov_b32_e32 v20, v18
	s_nop 1
	v_permlane16_swap_b32_e32 v20, v18
	v_add_f32_e32 v18, v18, v20
	v_fmac_f32_e32 v19, v215, v215
	v_fmac_f32_e32 v244, v2, v24
	v_mul_f32_e32 v2, v182, v5
	v_fmac_f32_e32 v19, v60, v60
	v_fmac_f32_e32 v61, v2, v25
	v_fmac_f32_e32 v19, v244, v244
	v_fmac_f32_e32 v19, v61, v61
	s_waitcnt lgkmcnt(0)
	v_mov_b32_e32 v20, v18
	s_nop 1
	v_permlane32_swap_b32_e32 v20, v18
	v_add_f32_e32 v18, v18, v20
	v_fmamk_f32 v18, v18, 0x39800000, v162
	v_cvt_pk_bf16_f32 v6, v216, v74
	v_cvt_pk_bf16_f32 v7, v217, v75
	v_cvt_pk_bf16_f32 v8, v218, v76
	v_cvt_pk_bf16_f32 v9, v219, v77
	v_cvt_pk_bf16_f32 v2, v213, v58
	v_cvt_pk_bf16_f32 v3, v214, v59
	v_cvt_pk_bf16_f32 v4, v215, v60
	v_mul_f32_e32 v20, 0x4f800000, v18
	v_cmp_gt_f32_e32 vcc, s70, v18
	v_cvt_pk_bf16_f32 v5, v244, v61
	global_store_dwordx4 v165, v[2:5], s[4:5]
	s_nop 0
	v_cndmask_b32_e32 v20, v18, v20, vcc
	s_waitcnt lgkmcnt(0)
	s_nop 1
	v_add_f32_dpp v4, v19, v19 quad_perm:[1,0,3,2] row_mask:0xf bank_mask:0xf
	v_sqrt_f32_e32 v21, v20
	v_cvt_pk_bf16_f32 v18, v213, v58
	v_add_u32_e32 v2, -1, v21
	v_fma_f32 v3, -v2, v21, v20
	s_waitcnt lgkmcnt(0)
	s_nop 1
	v_add_f32_dpp v4, v4, v4 quad_perm:[2,3,0,1] row_mask:0xf bank_mask:0xf
	v_cmp_ge_f32_e64 s[2:3], 0, v3
	v_add_u32_e32 v3, 1, v21
	v_fma_f32 v19, -v3, v21, v20
	v_cndmask_b32_e64 v2, v21, v2, s[2:3]
	v_cmp_lt_f32_e64 s[2:3], 0, v19
	s_nop 1
	v_cndmask_b32_e64 v2, v2, v3, s[2:3]
	v_mul_f32_e32 v3, 0x37800000, v2
	v_cndmask_b32_e32 v2, v2, v3, vcc
	s_waitcnt lgkmcnt(0)
	s_nop 1
	v_add_f32_dpp v3, v4, v4 row_half_mirror row_mask:0xf bank_mask:0xf
	v_cmp_class_f32_e32 vcc, v20, v163
	s_waitcnt lgkmcnt(0)
	s_nop 1
	v_add_f32_dpp v3, v3, v3 row_mirror row_mask:0xf bank_mask:0xf
	v_cndmask_b32_e32 v2, v2, v20, vcc
	v_div_scale_f32 v5, s[2:3], v2, v2, 1.0
	v_rcp_f32_e32 v22, v5
	s_waitcnt lgkmcnt(0)
	v_mov_b32_e32 v4, v3
	s_nop 1
	v_permlane16_swap_b32_e32 v4, v3
	v_add_f32_e32 v3, v3, v4
	v_cvt_pk_bf16_f32 v20, v214, v59
	v_fma_f32 v23, -v5, v22, 1.0
	v_fmac_f32_e32 v22, v23, v22
	v_div_scale_f32 v23, vcc, 1.0, v2, 1.0
	s_waitcnt lgkmcnt(0)
	v_mov_b32_e32 v4, v3
	s_nop 1
	v_permlane32_swap_b32_e32 v4, v3
	v_add_f32_e32 v3, v3, v4
	v_fmamk_f32 v3, v3, 0x39800000, v162
	v_mul_f32_e32 v4, 0x4f800000, v3
	v_cmp_gt_f32_e64 s[2:3], s70, v3
	v_mul_f32_e32 v24, v23, v22
	v_fma_f32 v25, -v5, v24, v23
	v_cndmask_b32_e64 v3, v3, v4, s[2:3]
	v_sqrt_f32_e32 v4, v3
	v_fmac_f32_e32 v24, v25, v22
	v_fma_f32 v5, -v5, v24, v23
	v_div_fmas_f32 v5, v5, v22, v24
	v_add_u32_e32 v23, -1, v4
	v_fma_f32 v25, -v23, v4, v3
	v_cmp_ge_f32_e64 s[4:5], 0, v25
	v_add_u32_e32 v25, 1, v4
	v_div_fixup_f32 v179, v5, v2, 1.0
	v_cndmask_b32_e64 v23, v4, v23, s[4:5]
	v_fma_f32 v4, -v25, v4, v3
	v_cmp_lt_f32_e64 s[4:5], 0, v4
	v_cvt_pk_bf16_f32 v19, v215, v60
	v_cvt_pk_bf16_f32 v21, v244, v61
	s_nop 1
	v_cndmask_b32_e64 v4, v23, v25, s[4:5]
	v_mul_f32_e32 v23, 0x37800000, v4
	v_cndmask_b32_e64 v4, v4, v23, s[2:3]
	v_cmp_class_f32_e64 s[2:3], v3, v163
	s_nop 1
	v_cndmask_b32_e64 v3, v4, v3, s[2:3]
	v_div_scale_f32 v4, s[2:3], v3, v3, 1.0
	v_rcp_f32_e32 v23, v4
	s_nop 0
	v_fma_f32 v2, -v4, v23, 1.0
	v_fmac_f32_e32 v23, v2, v23
	v_div_scale_f32 v2, vcc, 1.0, v3, 1.0
	v_mul_f32_e32 v5, v2, v23
	v_fma_f32 v22, -v4, v5, v2
	v_fmac_f32_e32 v5, v22, v23
	v_fma_f32 v2, -v4, v5, v2
	v_div_fmas_f32 v2, v2, v23, v5
	v_div_fixup_f32 v180, v2, v3, 1.0
	s_and_saveexec_b64 s[2:3], s[0:1]
	s_cbranch_execz .LBB0_758
	s_lshl_b64 s[4:5], s[36:37], 2
	s_add_u32 s4, s60, s4
	s_addc_u32 s5, s61, s5
	global_store_dword v166, v179, s[44:45]
	global_store_dword v131, v180, s[4:5]
.LBB0_758:
	s_or_b64 exec, exec, s[2:3]
	v_lshlrev_b32_e32 v128, 16, v104
	v_and_b32_e32 v129, 0xffff0000, v104
	v_lshlrev_b32_e32 v152, 16, v105
	v_and_b32_e32 v153, 0xffff0000, v105
	v_max3_f32 v22, |v128|, 0, |v129|
	v_lshlrev_b32_e32 v4, 16, v118
	v_and_b32_e32 v5, 0xffff0000, v118
	v_max3_f32 v22, v22, |v152|, |v153|
	v_lshlrev_b32_e32 v2, 16, v112
	v_and_b32_e32 v176, 0xffff0000, v112
	v_lshlrev_b32_e32 v3, 16, v122
	v_and_b32_e32 v173, 0xffff0000, v122
	v_lshlrev_b32_e32 v174, 16, v123
	v_and_b32_e32 v175, 0xffff0000, v123
	v_lshlrev_b32_e32 v122, 16, v119
	v_and_b32_e32 v123, 0xffff0000, v119
	v_max3_f32 v22, v22, |v4|, |v5|
	v_lshlrev_b32_e32 v177, 16, v113
	v_and_b32_e32 v178, 0xffff0000, v113
	v_max3_f32 v22, v22, |v122|, |v123|
	v_max3_f32 v23, |v2|, 0, |v176|
	v_lshlrev_b32_e32 v118, 16, v98
	v_and_b32_e32 v119, 0xffff0000, v98
	v_max3_f32 v23, v23, |v177|, |v178|
	v_lshlrev_b32_e32 v120, 16, v99
	v_and_b32_e32 v121, 0xffff0000, v99
	v_max3_f32 v22, v22, |v118|, |v119|
	v_max3_f32 v23, v23, |v3|, |v173|
	v_lshlrev_b32_e32 v114, 16, v100
	v_and_b32_e32 v115, 0xffff0000, v100
	v_max3_f32 v22, v22, |v120|, |v121|
	v_max3_f32 v23, v23, |v174|, |v175|
	v_lshlrev_b32_e32 v169, 16, v94
	v_and_b32_e32 v170, 0xffff0000, v94
	v_lshlrev_b32_e32 v116, 16, v101
	v_and_b32_e32 v117, 0xffff0000, v101
	v_max3_f32 v22, v22, |v114|, |v115|
	v_lshlrev_b32_e32 v171, 16, v95
	v_and_b32_e32 v172, 0xffff0000, v95
	v_max3_f32 v22, v22, |v116|, |v117|
	v_max3_f32 v23, v23, |v169|, |v170|
	v_lshlrev_b32_e32 v98, 16, v78
	v_and_b32_e32 v99, 0xffff0000, v78
	v_lshlrev_b32_e32 v124, 16, v96
	v_and_b32_e32 v125, 0xffff0000, v96
	v_max3_f32 v23, v23, |v171|, |v172|
	v_lshlrev_b32_e32 v100, 16, v79
	v_and_b32_e32 v101, 0xffff0000, v79
	v_max3_f32 v22, v22, |v98|, |v99|
	v_lshlrev_b32_e32 v126, 16, v97
	v_and_b32_e32 v127, 0xffff0000, v97
	v_max3_f32 v23, v23, |v124|, |v125|
	v_lshlrev_b32_e32 v90, 16, v80
	v_and_b32_e32 v91, 0xffff0000, v80
	v_max3_f32 v22, v22, |v100|, |v101|
	v_max3_f32 v23, v23, |v126|, |v127|
	v_lshlrev_b32_e32 v110, 16, v86
	v_and_b32_e32 v111, 0xffff0000, v86
	v_lshlrev_b32_e32 v92, 16, v81
	v_and_b32_e32 v93, 0xffff0000, v81
	v_max3_f32 v22, v22, |v90|, |v91|
	v_lshlrev_b32_e32 v112, 16, v87
	v_and_b32_e32 v113, 0xffff0000, v87
	v_max3_f32 v22, v22, |v92|, |v93|
	v_max3_f32 v23, v23, |v110|, |v111|
	v_lshlrev_b32_e32 v86, 16, v54
	v_and_b32_e32 v87, 0xffff0000, v54
	v_lshlrev_b32_e32 v106, 16, v88
	v_and_b32_e32 v107, 0xffff0000, v88
	v_lshlrev_b32_e32 v108, 16, v89
	v_and_b32_e32 v109, 0xffff0000, v89
	v_max3_f32 v23, v23, |v112|, |v113|
	v_lshlrev_b32_e32 v88, 16, v55
	v_and_b32_e32 v89, 0xffff0000, v55
	v_max3_f32 v22, v22, |v86|, |v87|
	v_max3_f32 v23, v23, |v106|, |v107|
	v_lshlrev_b32_e32 v82, 16, v56
	v_and_b32_e32 v83, 0xffff0000, v56
	v_max3_f32 v22, v22, |v88|, |v89|
	v_max3_f32 v23, v23, |v108|, |v109|
	v_lshlrev_b32_e32 v102, 16, v66
	v_and_b32_e32 v103, 0xffff0000, v66
	v_lshlrev_b32_e32 v84, 16, v57
	v_and_b32_e32 v85, 0xffff0000, v57
	v_max3_f32 v22, v22, |v82|, |v83|
	v_lshlrev_b32_e32 v104, 16, v67
	v_and_b32_e32 v105, 0xffff0000, v67
	v_max3_f32 v22, v22, |v84|, |v85|
	v_max3_f32 v23, v23, |v102|, |v103|
	v_lshlrev_b32_e32 v66, 16, v38
	v_and_b32_e32 v67, 0xffff0000, v38
	v_lshlrev_b32_e32 v94, 16, v68
	v_and_b32_e32 v95, 0xffff0000, v68
	v_lshlrev_b32_e32 v96, 16, v69
	v_and_b32_e32 v97, 0xffff0000, v69
	v_max3_f32 v23, v23, |v104|, |v105|
	v_lshlrev_b32_e32 v68, 16, v39
	v_and_b32_e32 v69, 0xffff0000, v39
	v_max3_f32 v22, v22, |v66|, |v67|
	v_max3_f32 v23, v23, |v94|, |v95|
	v_lshlrev_b32_e32 v58, 16, v40
	v_and_b32_e32 v59, 0xffff0000, v40
	v_max3_f32 v22, v22, |v68|, |v69|
	v_max3_f32 v23, v23, |v96|, |v97|
	v_lshlrev_b32_e32 v78, 16, v46
	v_and_b32_e32 v79, 0xffff0000, v46
	v_lshlrev_b32_e32 v60, 16, v41
	v_and_b32_e32 v61, 0xffff0000, v41
	v_max3_f32 v22, v22, |v58|, |v59|
	v_lshlrev_b32_e32 v80, 16, v47
	v_and_b32_e32 v81, 0xffff0000, v47
	v_max3_f32 v22, v22, |v60|, |v61|
	v_max3_f32 v23, v23, |v78|, |v79|
	v_lshlrev_b32_e32 v54, 16, v26
	v_and_b32_e32 v55, 0xffff0000, v26
	v_lshlrev_b32_e32 v74, 16, v48
	v_and_b32_e32 v75, 0xffff0000, v48
	v_max3_f32 v23, v23, |v80|, |v81|
	v_lshlrev_b32_e32 v56, 16, v27
	v_and_b32_e32 v57, 0xffff0000, v27
	v_max3_f32 v22, v22, |v54|, |v55|
	v_lshlrev_b32_e32 v76, 16, v49
	v_and_b32_e32 v77, 0xffff0000, v49
	v_max3_f32 v23, v23, |v74|, |v75|
	v_lshlrev_b32_e32 v50, 16, v28
	v_and_b32_e32 v51, 0xffff0000, v28
	v_max3_f32 v22, v22, |v56|, |v57|
	v_max3_f32 v23, v23, |v76|, |v77|
	v_lshlrev_b32_e32 v70, 16, v34
	v_and_b32_e32 v71, 0xffff0000, v34
	v_lshlrev_b32_e32 v52, 16, v29
	v_and_b32_e32 v53, 0xffff0000, v29
	v_max3_f32 v22, v22, |v50|, |v51|
	v_lshlrev_b32_e32 v72, 16, v35
	v_and_b32_e32 v73, 0xffff0000, v35
	v_max3_f32 v22, v22, |v52|, |v53|
	v_max3_f32 v23, v23, |v70|, |v71|
	v_lshlrev_b32_e32 v34, 16, v10
	v_and_b32_e32 v35, 0xffff0000, v10
	v_lshlrev_b32_e32 v62, 16, v36
	v_and_b32_e32 v63, 0xffff0000, v36
	v_lshlrev_b32_e32 v64, 16, v37
	v_and_b32_e32 v65, 0xffff0000, v37
	v_max3_f32 v23, v23, |v72|, |v73|
	v_lshlrev_b32_e32 v36, 16, v11
	v_and_b32_e32 v37, 0xffff0000, v11
	v_max3_f32 v10, v22, |v34|, |v35|
	v_max3_f32 v23, v23, |v62|, |v63|
	v_lshlrev_b32_e32 v26, 16, v12
	v_and_b32_e32 v27, 0xffff0000, v12
	v_max3_f32 v10, v10, |v36|, |v37|
	v_max3_f32 v23, v23, |v64|, |v65|
	v_lshlrev_b32_e32 v46, 16, v14
	v_and_b32_e32 v47, 0xffff0000, v14
	v_lshlrev_b32_e32 v28, 16, v13
	v_and_b32_e32 v29, 0xffff0000, v13
	v_max3_f32 v10, v10, |v26|, |v27|
	v_lshlrev_b32_e32 v48, 16, v15
	v_and_b32_e32 v49, 0xffff0000, v15
	v_max3_f32 v10, v10, |v28|, |v29|
	v_max3_f32 v11, v23, |v46|, |v47|
	v_lshlrev_b32_e32 v22, 16, v18
	v_and_b32_e32 v23, 0xffff0000, v18
	v_lshlrev_b32_e32 v42, 16, v16
	v_and_b32_e32 v43, 0xffff0000, v16
	v_max3_f32 v11, v11, |v48|, |v49|
	v_lshlrev_b32_e32 v38, 16, v6
	v_and_b32_e32 v39, 0xffff0000, v6
	v_lshlrev_b32_e32 v24, 16, v20
	v_and_b32_e32 v25, 0xffff0000, v20
	v_max3_f32 v6, v10, |v22|, |v23|
	v_lshlrev_b32_e32 v44, 16, v17
	v_and_b32_e32 v45, 0xffff0000, v17
	v_max3_f32 v11, v11, |v42|, |v43|
	v_lshlrev_b32_e32 v18, 16, v19
	v_and_b32_e32 v19, 0xffff0000, v19
	v_max3_f32 v6, v6, |v24|, |v25|
	v_max3_f32 v11, v11, |v44|, |v45|
	v_lshlrev_b32_e32 v20, 16, v21
	v_and_b32_e32 v21, 0xffff0000, v21
	v_max3_f32 v6, v6, |v18|, |v19|
	v_lshlrev_b32_e32 v40, 16, v7
	v_and_b32_e32 v41, 0xffff0000, v7
	v_max3_f32 v7, v6, |v20|, |v21|
	v_max3_f32 v6, v11, |v38|, |v39|
	v_lshlrev_b32_e32 v30, 16, v8
	v_and_b32_e32 v31, 0xffff0000, v8
	v_max3_f32 v6, v6, |v40|, |v41|
	v_lshlrev_b32_e32 v32, 16, v9
	v_and_b32_e32 v33, 0xffff0000, v9
	v_max3_f32 v6, v6, |v30|, |v31|
	v_max3_f32 v6, v6, |v32|, |v33|
	s_cmp_gt_i32 s14, -1
	s_cselect_b64 s[48:49], -1, 0
	s_lshl_b64 s[2:3], s[14:15], 12
	s_add_u32 s4, s43, s2
	s_waitcnt lgkmcnt(0)
	s_nop 1
	v_max_f32_dpp v6, v6, v6 quad_perm:[1,0,3,2] row_mask:0xf bank_mask:0xf
	s_addc_u32 s5, s52, s3
	s_and_b64 s[2:3], s[48:49], exec
	s_cselect_b32 s3, s5, 0
	s_cselect_b32 s2, s4, 0
	s_waitcnt lgkmcnt(0)
	s_nop 1
	v_max_f32_dpp v6, v6, v6 quad_perm:[2,3,0,1] row_mask:0xf bank_mask:0xf
	s_cmp_gt_i32 s38, -1
	s_mov_b32 s39, s15
	s_cselect_b64 s[46:47], -1, 0
	s_lshl_b64 s[4:5], s[38:39], 12
	s_waitcnt lgkmcnt(0)
	s_nop 1
	v_max_f32_dpp v6, v6, v6 row_half_mirror row_mask:0xf bank_mask:0xf
	s_add_u32 s39, s43, s4
	s_addc_u32 s50, s52, s5
	s_and_b64 s[4:5], s[46:47], exec
	s_cselect_b32 s5, s50, 0
	s_waitcnt lgkmcnt(0)
	s_nop 1
	v_max_f32_dpp v6, v6, v6 row_mirror row_mask:0xf bank_mask:0xf
	s_cselect_b32 s4, s39, 0
	s_waitcnt lgkmcnt(0)
	v_mov_b32_e32 v8, v6
	s_nop 1
	v_permlane16_swap_b32_e32 v8, v6
	v_max_f32_e32 v6, v6, v8
	s_waitcnt lgkmcnt(0)
	v_mov_b32_e32 v8, v6
	s_nop 1
	v_permlane32_swap_b32_e32 v8, v6
	v_max_f32_e32 v6, v6, v8
	s_waitcnt lgkmcnt(0)
	s_nop 1
	v_max_f32_dpp v7, v7, v7 quad_perm:[1,0,3,2] row_mask:0xf bank_mask:0xf
	s_waitcnt lgkmcnt(0)
	s_nop 1
	v_max_f32_dpp v7, v7, v7 quad_perm:[2,3,0,1] row_mask:0xf bank_mask:0xf
	s_waitcnt lgkmcnt(0)
	s_nop 1
	v_max_f32_dpp v7, v7, v7 row_half_mirror row_mask:0xf bank_mask:0xf
	s_waitcnt lgkmcnt(0)
	s_nop 1
	v_max_f32_dpp v7, v7, v7 row_mirror row_mask:0xf bank_mask:0xf
	s_waitcnt lgkmcnt(0)
	v_mov_b32_e32 v8, v7
	s_nop 1
	v_permlane16_swap_b32_e32 v8, v7
	v_max_f32_e32 v7, v7, v8
	s_waitcnt lgkmcnt(0)
	v_mov_b32_e32 v8, v7
	s_nop 1
	v_permlane32_swap_b32_e32 v8, v7
	v_max_f32_e32 v7, v7, v8
	s_and_saveexec_b64 s[50:51], s[0:1]
	s_cbranch_execz .LBB0_763
	s_lshl_b64 s[78:79], s[36:37], 2
	s_add_u32 s78, s62, s78
	v_mul_f32_e32 v8, v179, v6
	s_addc_u32 s79, s63, s79
	v_mul_f32_e32 v9, 0x3c010204, v8
	v_mul_f32_e32 v8, v180, v7
	v_mul_f32_e32 v8, 0x3c010204, v8
	s_cmp_eq_u64 s[2:3], 0
	global_store_dword v167, v9, s[44:45]
	global_store_dword v131, v8, s[78:79]
	s_cbranch_scc1 .LBB0_761
	s_ashr_i32 s45, s14, 31
	s_mov_b32 s44, s14
	s_lshl_b64 s[44:45], s[44:45], 2
	s_add_u32 s14, s53, s44
	s_addc_u32 s39, s54, s45
	s_and_b64 s[44:45], s[48:49], exec
	s_cselect_b32 s45, s39, 0
	s_cselect_b32 s44, s14, 0
	global_store_dword v131, v9, s[44:45]

.LBB0_779:
	s_cmp_lt_i32 s6, 32
	s_cbranch_scc0 .LBB0_783
	s_ashr_i32 s7, s6, 31
	s_lshl_b64 s[2:3], s[6:7], 12
	s_lshl_b64 s[0:1], s[6:7], 14
	s_add_u32 s16, s8, s0
	s_addc_u32 s15, s9, s1
	s_add_u32 s4, s16, 0x69ac0000
	s_addc_u32 s5, s15, 0
	v_lshlrev_b32_e32 v102, 5, v1
	global_load_dwordx4 v[2:5], v102, s[4:5]
	v_lshlrev_b32_e32 v66, 3, v1
	v_or_b32_e32 v69, 0xe00, v66
	v_lshlrev_b32_e32 v79, 2, v69
	global_load_dwordx4 v[34:37], v79, s[4:5] offset:16
	global_load_dwordx4 v[6:9], v102, s[4:5] offset:16
	global_load_dwordx4 v[14:17], v102, s[4:5] offset:2048
	global_load_dwordx4 v[10:13], v102, s[4:5] offset:2064
	v_or_b32_e32 v103, 0x1000, v102
	global_load_dwordx4 v[22:25], v103, s[4:5]
	global_load_dwordx4 v[18:21], v103, s[4:5] offset:16
	v_or_b32_e32 v104, 0x1800, v102
	global_load_dwordx4 v[30:33], v104, s[4:5]
	global_load_dwordx4 v[26:29], v104, s[4:5] offset:16
	v_or_b32_e32 v72, 0x800, v66
	v_lshlrev_b32_e32 v105, 2, v72
	global_load_dwordx4 v[42:45], v105, s[4:5]
	global_load_dwordx4 v[38:41], v105, s[4:5] offset:16
	v_or_b32_e32 v71, 0xa00, v66
	v_lshlrev_b32_e32 v106, 2, v71
	global_load_dwordx4 v[54:57], v106, s[4:5]
	global_load_dwordx4 v[50:53], v106, s[4:5] offset:16
	v_or_b32_e32 v70, 0xc00, v66
	v_lshlrev_b32_e32 v67, 2, v70
	global_load_dwordx4 v[62:65], v67, s[4:5]
	global_load_dwordx4 v[58:61], v67, s[4:5] offset:16
	global_load_dwordx4 v[46:49], v79, s[4:5]
	s_add_u32 s12, s12, s0
	s_addc_u32 s13, s13, s1
	global_load_dwordx4 v[82:85], v102, s[10:11] offset:16
	global_load_dwordx4 v[86:89], v102, s[10:11]
	global_load_dwordx4 v[90:93], v102, s[12:13] offset:16
	global_load_dwordx4 v[94:97], v102, s[12:13]
	v_mbcnt_hi_u32_b32 v68, -1, v234
	v_and_b32_e32 v73, 64, v68
	v_xor_b32_e32 v74, 1, v68
	v_add_u32_e32 v80, 64, v73
	v_cmp_lt_i32_e32 vcc, v74, v80
	s_mov_b32 s14, 0xf800000
	s_add_u32 s4, s16, 0x69b40000
	v_cndmask_b32_e32 v73, v68, v74, vcc
	v_lshlrev_b32_e32 v73, 2, v73
	s_addc_u32 s5, s15, 0
	v_lshlrev_b32_e32 v72, 1, v72
	v_lshlrev_b32_e32 v71, 1, v71
	v_lshlrev_b32_e32 v70, 1, v70
	s_waitcnt vmcnt(19)
	v_mul_f32_e32 v76, v3, v3
	v_fmac_f32_e32 v76, v2, v2
	v_fmac_f32_e32 v76, v4, v4
	v_fmac_f32_e32 v76, v5, v5
	s_waitcnt vmcnt(17)
	v_fmac_f32_e32 v76, v6, v6
	v_fmac_f32_e32 v76, v7, v7
	v_fmac_f32_e32 v76, v8, v8
	v_fmac_f32_e32 v76, v9, v9
	s_waitcnt vmcnt(16)
	v_fmac_f32_e32 v76, v14, v14
	v_fmac_f32_e32 v76, v15, v15
	v_fmac_f32_e32 v76, v16, v16
	v_fmac_f32_e32 v76, v17, v17
	s_waitcnt vmcnt(15)
	v_fmac_f32_e32 v76, v10, v10
	v_fmac_f32_e32 v76, v11, v11
	v_fmac_f32_e32 v76, v12, v12
	v_fmac_f32_e32 v76, v13, v13
	s_waitcnt vmcnt(14)
	v_fmac_f32_e32 v76, v22, v22
	v_fmac_f32_e32 v76, v23, v23
	v_fmac_f32_e32 v76, v24, v24
	v_fmac_f32_e32 v76, v25, v25
	s_waitcnt vmcnt(13)
	v_fmac_f32_e32 v76, v18, v18
	v_fmac_f32_e32 v76, v19, v19
	v_fmac_f32_e32 v76, v20, v20
	v_fmac_f32_e32 v76, v21, v21
	s_waitcnt vmcnt(12)
	v_fmac_f32_e32 v76, v30, v30
	v_fmac_f32_e32 v76, v31, v31
	v_fmac_f32_e32 v76, v32, v32
	v_fmac_f32_e32 v76, v33, v33
	s_waitcnt vmcnt(11)
	v_fmac_f32_e32 v76, v26, v26
	v_fmac_f32_e32 v76, v27, v27
	v_fmac_f32_e32 v76, v28, v28
	v_fmac_f32_e32 v76, v29, v29
	s_waitcnt vmcnt(10)
	v_fmac_f32_e32 v76, v42, v42
	v_fmac_f32_e32 v76, v43, v43
	v_fmac_f32_e32 v76, v44, v44
	v_fmac_f32_e32 v76, v45, v45
	s_waitcnt vmcnt(9)
	v_fmac_f32_e32 v76, v38, v38
	v_fmac_f32_e32 v76, v39, v39
	v_fmac_f32_e32 v76, v40, v40
	v_fmac_f32_e32 v76, v41, v41
	s_waitcnt vmcnt(8)
	v_fmac_f32_e32 v76, v54, v54
	v_fmac_f32_e32 v76, v55, v55
	v_fmac_f32_e32 v76, v56, v56
	v_fmac_f32_e32 v76, v57, v57
	s_waitcnt vmcnt(7)
	v_fmac_f32_e32 v76, v50, v50
	v_fmac_f32_e32 v76, v51, v51
	v_fmac_f32_e32 v76, v52, v52
	v_fmac_f32_e32 v76, v53, v53
	s_waitcnt vmcnt(6)
	v_fmac_f32_e32 v76, v62, v62
	v_fmac_f32_e32 v76, v63, v63
	v_fmac_f32_e32 v76, v64, v64
	v_fmac_f32_e32 v76, v65, v65
	s_waitcnt vmcnt(5)
	v_fmac_f32_e32 v76, v58, v58
	v_fmac_f32_e32 v76, v59, v59
	v_fmac_f32_e32 v76, v60, v60
	v_fmac_f32_e32 v76, v61, v61
	s_waitcnt vmcnt(4)
	v_fmac_f32_e32 v76, v46, v46
	v_fmac_f32_e32 v76, v47, v47
	v_fmac_f32_e32 v76, v48, v48
	v_fmac_f32_e32 v76, v49, v49
	v_fmac_f32_e32 v76, v34, v34
	v_pk_mul_f32 v[74:75], v[36:37], v[36:37]
	v_fmac_f32_e32 v76, v35, v35
	v_add_f32_e32 v74, v74, v76
	v_add_f32_e32 v74, v75, v74
	v_xor_b32_e32 v76, 2, v68
	v_cmp_lt_i32_e32 vcc, v76, v80
	s_waitcnt lgkmcnt(0)
	s_nop 1
	v_add_f32_dpp v74, v74, v74 quad_perm:[1,0,3,2] row_mask:0xf bank_mask:0xf
	v_cndmask_b32_e32 v76, v68, v76, vcc
	v_lshlrev_b32_e32 v78, 2, v76
	v_xor_b32_e32 v76, 4, v68
	v_cmp_lt_i32_e32 vcc, v76, v80
	s_waitcnt lgkmcnt(0)
	s_nop 1
	v_add_f32_dpp v74, v74, v74 quad_perm:[2,3,0,1] row_mask:0xf bank_mask:0xf
	v_cndmask_b32_e32 v76, v68, v76, vcc
	v_lshlrev_b32_e32 v77, 2, v76
	v_xor_b32_e32 v76, 8, v68
	v_cmp_lt_i32_e32 vcc, v76, v80
	s_waitcnt lgkmcnt(0)
	s_nop 1
	v_add_f32_dpp v74, v74, v74 row_half_mirror row_mask:0xf bank_mask:0xf
	v_cndmask_b32_e32 v76, v68, v76, vcc
	v_lshlrev_b32_e32 v76, 2, v76
	v_xor_b32_e32 v75, 16, v68
	v_cmp_lt_i32_e32 vcc, v75, v80
	s_waitcnt lgkmcnt(0)
	s_nop 1
	v_add_f32_dpp v81, v74, v74 row_mirror row_mask:0xf bank_mask:0xf
	v_cndmask_b32_e32 v75, v68, v75, vcc
	v_lshlrev_b32_e32 v75, 2, v75
	v_xor_b32_e32 v74, 32, v68
	v_cmp_lt_i32_e32 vcc, v74, v80
	s_nop 1
	v_cndmask_b32_e32 v68, v68, v74, vcc
	v_lshlrev_b32_e32 v74, 2, v68
	s_waitcnt lgkmcnt(0)
	v_mov_b32_e32 v68, v81
	v_mov_b32_e32 v98, v81
	s_nop 1
	v_permlane16_swap_b32_e32 v98, v68
	v_add_f32_e32 v68, v68, v98
	v_mov_b32_e32 v81, 0x358637bd
	s_waitcnt lgkmcnt(0)
	v_mov_b32_e32 v80, v68
	s_nop 1
	v_permlane32_swap_b32_e32 v80, v68
	v_add_f32_e32 v68, v68, v80
	v_fmamk_f32 v68, v68, 0x39800000, v81
	v_mul_f32_e32 v80, 0x4f800000, v68
	v_cmp_gt_f32_e32 vcc, s14, v68
	s_nop 1
	v_cndmask_b32_e32 v68, v68, v80, vcc
	v_sqrt_f32_e32 v98, v68
	v_mov_b32_e32 v80, 0x260
	v_add_u32_e32 v99, -1, v98
	v_add_u32_e32 v100, 1, v98
	v_fma_f32 v101, -v99, v98, v68
	v_fma_f32 v107, -v100, v98, v68
	v_cmp_ge_f32_e64 s[0:1], 0, v101
	s_nop 1
	v_cndmask_b32_e64 v98, v98, v99, s[0:1]
	v_cmp_lt_f32_e64 s[0:1], 0, v107
	s_nop 1
	v_cndmask_b32_e64 v98, v98, v100, s[0:1]
	v_mul_f32_e32 v99, 0x37800000, v98
	v_cndmask_b32_e32 v98, v98, v99, vcc
	v_cmp_class_f32_e32 vcc, v68, v80
	s_nop 1
	v_cndmask_b32_e32 v68, v98, v68, vcc
	v_div_scale_f32 v98, s[0:1], v68, v68, 1.0
	v_rcp_f32_e32 v99, v98
	v_div_scale_f32 v100, vcc, 1.0, v68, 1.0
	s_lshl_b64 s[0:1], s[6:7], 13
	v_fma_f32 v101, -v98, v99, 1.0
	v_fmac_f32_e32 v99, v101, v99
	v_mul_f32_e32 v101, v100, v99
	v_fma_f32 v107, -v98, v101, v100
	v_fmac_f32_e32 v101, v107, v99
	v_fma_f32 v98, -v98, v101, v100
	v_div_fmas_f32 v98, v98, v99, v101
	v_div_fixup_f32 v68, v98, v68, 1.0
	v_pk_mul_f32 v[2:3], v[2:3], v[68:69] op_sel_hi:[1,0]
	v_pk_mul_f32 v[4:5], v[4:5], v[68:69] op_sel_hi:[1,0]
	v_pk_mul_f32 v[98:99], v[6:7], v[68:69] op_sel_hi:[1,0]
	v_pk_mul_f32 v[100:101], v[8:9], v[68:69] op_sel_hi:[1,0]
	s_waitcnt vmcnt(0)
	v_pk_fma_f32 v[6:7], v[86:87], v[2:3], v[94:95]
	v_pk_fma_f32 v[8:9], v[88:89], v[4:5], v[96:97]
	v_pk_fma_f32 v[2:3], v[82:83], v[98:99], v[90:91]
	v_pk_fma_f32 v[4:5], v[84:85], v[100:101], v[92:93]
	global_store_dwordx4 v102, v[6:9], s[4:5]
	global_store_dwordx4 v102, v[2:5], s[4:5] offset:16
	global_load_dwordx4 v[82:85], v102, s[10:11] offset:2048
	global_load_dwordx4 v[86:89], v102, s[12:13] offset:2048
	global_load_dwordx4 v[90:93], v102, s[12:13] offset:2064
	global_load_dwordx4 v[94:97], v102, s[10:11] offset:2064
	v_pk_mul_f32 v[14:15], v[14:15], v[68:69] op_sel_hi:[1,0]
	v_pk_mul_f32 v[16:17], v[16:17], v[68:69] op_sel_hi:[1,0]
	v_pk_mul_f32 v[10:11], v[10:11], v[68:69] op_sel_hi:[1,0]
	v_pk_mul_f32 v[12:13], v[12:13], v[68:69] op_sel_hi:[1,0]
	v_pk_mul_f32 v[22:23], v[22:23], v[68:69] op_sel_hi:[1,0]
	v_pk_mul_f32 v[24:25], v[24:25], v[68:69] op_sel_hi:[1,0]
	v_pk_mul_f32 v[18:19], v[18:19], v[68:69] op_sel_hi:[1,0]
	v_pk_mul_f32 v[20:21], v[20:21], v[68:69] op_sel_hi:[1,0]
	v_pk_mul_f32 v[30:31], v[30:31], v[68:69] op_sel_hi:[1,0]
	v_pk_mul_f32 v[32:33], v[32:33], v[68:69] op_sel_hi:[1,0]
	v_pk_mul_f32 v[26:27], v[26:27], v[68:69] op_sel_hi:[1,0]
	v_pk_mul_f32 v[28:29], v[28:29], v[68:69] op_sel_hi:[1,0]
	v_pk_mul_f32 v[42:43], v[42:43], v[68:69] op_sel_hi:[1,0]
	v_pk_mul_f32 v[44:45], v[44:45], v[68:69] op_sel_hi:[1,0]
	v_pk_mul_f32 v[38:39], v[38:39], v[68:69] op_sel_hi:[1,0]
	v_pk_mul_f32 v[40:41], v[40:41], v[68:69] op_sel_hi:[1,0]
	v_pk_mul_f32 v[54:55], v[54:55], v[68:69] op_sel_hi:[1,0]
	v_pk_mul_f32 v[56:57], v[56:57], v[68:69] op_sel_hi:[1,0]
	v_pk_mul_f32 v[50:51], v[50:51], v[68:69] op_sel_hi:[1,0]
	v_pk_mul_f32 v[52:53], v[52:53], v[68:69] op_sel_hi:[1,0]
	v_pk_mul_f32 v[62:63], v[62:63], v[68:69] op_sel_hi:[1,0]
	v_pk_mul_f32 v[64:65], v[64:65], v[68:69] op_sel_hi:[1,0]
	v_pk_mul_f32 v[58:59], v[58:59], v[68:69] op_sel_hi:[1,0]
	v_pk_mul_f32 v[60:61], v[60:61], v[68:69] op_sel_hi:[1,0]
	v_pk_mul_f32 v[98:99], v[46:47], v[68:69] op_sel_hi:[1,0]
	v_pk_mul_f32 v[100:101], v[48:49], v[68:69] op_sel_hi:[1,0]
	v_pk_mul_f32 v[108:109], v[8:9], v[8:9]
	v_pk_mul_f32 v[110:111], v[2:3], v[2:3]
	v_pk_mul_f32 v[112:113], v[4:5], v[4:5]
	s_add_u32 s0, s8, s0
	s_addc_u32 s1, s9, s1
	s_add_u32 s8, s0, 0x69900000
	s_addc_u32 s9, s1, 0
	s_waitcnt vmcnt(2)
	v_pk_fma_f32 v[14:15], v[82:83], v[14:15], v[86:87]
	v_pk_fma_f32 v[16:17], v[84:85], v[16:17], v[88:89]
	s_waitcnt vmcnt(0)
	v_pk_fma_f32 v[10:11], v[94:95], v[10:11], v[90:91]
	v_pk_fma_f32 v[12:13], v[96:97], v[12:13], v[92:93]
	global_store_dwordx4 v102, v[14:17], s[4:5] offset:2048
	global_store_dwordx4 v102, v[10:13], s[4:5] offset:2064
	global_load_dwordx4 v[82:85], v103, s[10:11]
	global_load_dwordx4 v[86:89], v103, s[12:13]
	global_load_dwordx4 v[90:93], v103, s[12:13] offset:16
	global_load_dwordx4 v[94:97], v103, s[10:11] offset:16
	s_waitcnt vmcnt(2)
	v_pk_fma_f32 v[22:23], v[82:83], v[22:23], v[86:87]
	v_pk_fma_f32 v[24:25], v[84:85], v[24:25], v[88:89]
	s_waitcnt vmcnt(0)
	v_pk_fma_f32 v[18:19], v[94:95], v[18:19], v[90:91]
	v_pk_fma_f32 v[20:21], v[96:97], v[20:21], v[92:93]
	global_store_dwordx4 v103, v[22:25], s[4:5]
	global_store_dwordx4 v103, v[18:21], s[4:5] offset:16
	global_load_dwordx4 v[82:85], v104, s[10:11]
	global_load_dwordx4 v[86:89], v104, s[12:13]
	global_load_dwordx4 v[90:93], v104, s[12:13] offset:16
	global_load_dwordx4 v[94:97], v104, s[10:11] offset:16
	v_pk_mul_f32 v[102:103], v[34:35], v[68:69] op_sel_hi:[1,0]
	s_waitcnt vmcnt(2)
	v_pk_fma_f32 v[30:31], v[82:83], v[30:31], v[86:87]
	v_pk_fma_f32 v[32:33], v[84:85], v[32:33], v[88:89]
	s_waitcnt vmcnt(0)
	v_pk_fma_f32 v[26:27], v[94:95], v[26:27], v[90:91]
	v_pk_fma_f32 v[28:29], v[96:97], v[28:29], v[92:93]
	global_store_dwordx4 v104, v[30:33], s[4:5]
	global_store_dwordx4 v104, v[26:29], s[4:5] offset:16
	global_load_dwordx4 v[82:85], v105, s[10:11]
	global_load_dwordx4 v[86:89], v105, s[12:13]
	global_load_dwordx4 v[90:93], v105, s[12:13] offset:16
	global_load_dwordx4 v[94:97], v105, s[10:11] offset:16
	s_waitcnt vmcnt(2)
	v_pk_fma_f32 v[42:43], v[82:83], v[42:43], v[86:87]
	v_pk_fma_f32 v[44:45], v[84:85], v[44:45], v[88:89]
	s_waitcnt vmcnt(0)
	v_pk_fma_f32 v[38:39], v[94:95], v[38:39], v[90:91]
	v_pk_fma_f32 v[40:41], v[96:97], v[40:41], v[92:93]
	global_store_dwordx4 v105, v[42:45], s[4:5]
	global_store_dwordx4 v105, v[38:41], s[4:5] offset:16
	global_load_dwordx4 v[82:85], v106, s[10:11]
	global_load_dwordx4 v[86:89], v106, s[12:13]
	global_load_dwordx4 v[90:93], v106, s[12:13] offset:16
	global_load_dwordx4 v[94:97], v106, s[10:11] offset:16
	v_pk_mul_f32 v[104:105], v[36:37], v[68:69] op_sel_hi:[1,0]
	s_waitcnt vmcnt(2)
	v_pk_fma_f32 v[54:55], v[82:83], v[54:55], v[86:87]
	v_pk_fma_f32 v[56:57], v[84:85], v[56:57], v[88:89]
	s_waitcnt vmcnt(0)
	v_pk_fma_f32 v[50:51], v[94:95], v[50:51], v[90:91]
	v_pk_fma_f32 v[52:53], v[96:97], v[52:53], v[92:93]
	global_store_dwordx4 v106, v[54:57], s[4:5]
	global_store_dwordx4 v106, v[50:53], s[4:5] offset:16
	global_load_dwordx4 v[82:85], v67, s[10:11]
	global_load_dwordx4 v[86:89], v67, s[12:13]
	global_load_dwordx4 v[90:93], v67, s[12:13] offset:16
	global_load_dwordx4 v[94:97], v67, s[10:11] offset:16
	v_pk_mul_f32 v[106:107], v[6:7], v[6:7]
	s_waitcnt vmcnt(2)
	v_pk_fma_f32 v[46:47], v[82:83], v[62:63], v[86:87]
	v_pk_fma_f32 v[48:49], v[84:85], v[64:65], v[88:89]
	s_waitcnt vmcnt(0)
	v_pk_fma_f32 v[34:35], v[94:95], v[58:59], v[90:91]
	v_pk_fma_f32 v[36:37], v[96:97], v[60:61], v[92:93]
	global_store_dwordx4 v67, v[46:49], s[4:5]
	global_store_dwordx4 v67, v[34:37], s[4:5] offset:16
	global_load_dwordx4 v[58:61], v79, s[12:13] offset:16
	global_load_dwordx4 v[62:65], v79, s[12:13]
	global_load_dwordx4 v[82:85], v79, s[10:11] offset:16
	global_load_dwordx4 v[86:89], v79, s[10:11]
	v_add_f32_e32 v67, v106, v107
	v_add_f32_e32 v67, v108, v67
	v_add_f32_e32 v67, v109, v67
	v_add_f32_e32 v67, v110, v67
	v_add_f32_e32 v67, v111, v67
	v_add_f32_e32 v67, v112, v67
	v_add_f32_e32 v67, v113, v67
	v_pk_mul_f32 v[90:91], v[14:15], v[14:15]
	v_pk_mul_f32 v[92:93], v[16:17], v[16:17]
	v_add_f32_e32 v67, v90, v67
	v_add_f32_e32 v67, v91, v67
	v_add_f32_e32 v67, v92, v67
	v_pk_mul_f32 v[94:95], v[10:11], v[10:11]
	v_add_f32_e32 v67, v93, v67
	v_add_f32_e32 v67, v94, v67
	v_pk_mul_f32 v[96:97], v[12:13], v[12:13]
	v_add_f32_e32 v67, v95, v67
	v_add_f32_e32 v67, v96, v67
	v_add_f32_e32 v67, v97, v67
	v_pk_mul_f32 v[90:91], v[22:23], v[22:23]
	v_pk_mul_f32 v[92:93], v[24:25], v[24:25]
	v_add_f32_e32 v67, v90, v67
	v_add_f32_e32 v67, v91, v67
	v_add_f32_e32 v67, v92, v67
	v_pk_mul_f32 v[94:95], v[18:19], v[18:19]
	v_add_f32_e32 v67, v93, v67
	v_add_f32_e32 v67, v94, v67
	v_pk_mul_f32 v[96:97], v[20:21], v[20:21]
	v_add_f32_e32 v67, v95, v67
	v_add_f32_e32 v67, v96, v67
	v_add_f32_e32 v67, v97, v67
	v_pk_mul_f32 v[90:91], v[30:31], v[30:31]
	v_pk_mul_f32 v[92:93], v[32:33], v[32:33]
	v_add_f32_e32 v67, v90, v67
	v_add_f32_e32 v67, v91, v67
	v_add_f32_e32 v67, v92, v67
	v_pk_mul_f32 v[94:95], v[26:27], v[26:27]
	v_add_f32_e32 v67, v93, v67
	v_add_f32_e32 v67, v94, v67
	v_pk_mul_f32 v[96:97], v[28:29], v[28:29]
	v_add_f32_e32 v67, v95, v67
	v_add_f32_e32 v67, v96, v67
	v_add_f32_e32 v67, v97, v67
	v_pk_mul_f32 v[90:91], v[42:43], v[42:43]
	v_pk_mul_f32 v[92:93], v[44:45], v[44:45]
	v_add_f32_e32 v67, v90, v67
	v_add_f32_e32 v67, v91, v67
	v_add_f32_e32 v67, v92, v67
	v_pk_mul_f32 v[94:95], v[38:39], v[38:39]
	v_add_f32_e32 v67, v93, v67
	v_add_f32_e32 v67, v94, v67
	v_pk_mul_f32 v[96:97], v[40:41], v[40:41]
	v_add_f32_e32 v67, v95, v67
	v_add_f32_e32 v67, v96, v67
	v_add_f32_e32 v67, v97, v67
	v_pk_mul_f32 v[90:91], v[54:55], v[54:55]
	v_pk_mul_f32 v[92:93], v[56:57], v[56:57]
	v_add_f32_e32 v67, v90, v67
	v_add_f32_e32 v67, v91, v67
	v_add_f32_e32 v67, v92, v67
	v_pk_mul_f32 v[94:95], v[50:51], v[50:51]
	v_add_f32_e32 v67, v93, v67
	v_add_f32_e32 v67, v94, v67
	v_pk_mul_f32 v[96:97], v[52:53], v[52:53]
	v_add_f32_e32 v67, v95, v67
	v_add_f32_e32 v67, v96, v67
	v_add_f32_e32 v67, v97, v67
	v_pk_mul_f32 v[90:91], v[46:47], v[46:47]
	v_pk_mul_f32 v[92:93], v[48:49], v[48:49]
	v_add_f32_e32 v67, v90, v67
	v_add_f32_e32 v67, v91, v67
	v_add_f32_e32 v67, v92, v67
	v_pk_mul_f32 v[94:95], v[34:35], v[34:35]
	v_add_f32_e32 v67, v93, v67
	v_add_f32_e32 v67, v94, v67
	v_pk_mul_f32 v[96:97], v[36:37], v[36:37]
	v_add_f32_e32 v67, v95, v67
	v_add_f32_e32 v67, v96, v67
	v_add_f32_e32 v67, v97, v67
	s_waitcnt vmcnt(0)
	v_pk_fma_f32 v[62:63], v[86:87], v[98:99], v[62:63]
	v_pk_fma_f32 v[58:59], v[82:83], v[102:103], v[58:59]
	v_pk_mul_f32 v[82:83], v[62:63], v[62:63]
	v_pk_fma_f32 v[64:65], v[88:89], v[100:101], v[64:65]
	v_add_f32_e32 v67, v82, v67
	v_pk_fma_f32 v[60:61], v[84:85], v[104:105], v[60:61]
	v_pk_mul_f32 v[84:85], v[64:65], v[64:65]
	v_add_f32_e32 v67, v83, v67
	v_add_f32_e32 v67, v84, v67
	v_pk_mul_f32 v[86:87], v[58:59], v[58:59]
	v_add_f32_e32 v67, v85, v67
	v_add_f32_e32 v67, v86, v67
	v_pk_mul_f32 v[88:89], v[60:61], v[60:61]
	v_add_f32_e32 v67, v87, v67
	v_add_f32_e32 v67, v88, v67
	v_add_f32_e32 v67, v89, v67
	global_store_dwordx4 v79, v[62:65], s[4:5]
	global_store_dwordx4 v79, v[58:61], s[4:5] offset:16
	s_movk_i32 s10, 0x7fff
	s_waitcnt lgkmcnt(0)
	s_nop 1
	v_add_f32_dpp v67, v67, v67 quad_perm:[1,0,3,2] row_mask:0xf bank_mask:0xf
	s_waitcnt lgkmcnt(0)
	s_nop 1
	v_add_f32_dpp v67, v67, v67 quad_perm:[2,3,0,1] row_mask:0xf bank_mask:0xf
	s_waitcnt lgkmcnt(0)
	s_nop 1
	v_add_f32_dpp v67, v67, v67 row_half_mirror row_mask:0xf bank_mask:0xf
	s_waitcnt lgkmcnt(0)
	s_nop 1
	v_add_f32_dpp v68, v67, v67 row_mirror row_mask:0xf bank_mask:0xf
	v_mov_b32_e32 v67, 0
	s_waitcnt lgkmcnt(0)
	v_mov_b32_e32 v82, v68
	s_nop 1
	v_permlane16_swap_b32_e32 v82, v68
	v_add_f32_e32 v68, v68, v82
	s_waitcnt lgkmcnt(0)
	v_mov_b32_e32 v82, v68
	s_nop 1
	v_permlane32_swap_b32_e32 v82, v68
	v_add_f32_e32 v68, v68, v82
	v_fmac_f32_e32 v81, 0x39800000, v68
	v_mul_f32_e32 v68, 0x4f800000, v81
	v_cmp_gt_f32_e32 vcc, s14, v81
	s_nop 1
	v_cndmask_b32_e32 v68, v81, v68, vcc
	v_sqrt_f32_e32 v81, v68
	s_nop 0
	v_add_u32_e32 v82, -1, v81
	v_add_u32_e32 v83, 1, v81
	v_fma_f32 v84, -v82, v81, v68
	v_fma_f32 v85, -v83, v81, v68
	v_cmp_ge_f32_e64 s[0:1], 0, v84
	s_nop 1
	v_cndmask_b32_e64 v81, v81, v82, s[0:1]
	v_cmp_lt_f32_e64 s[0:1], 0, v85
	s_nop 1
	v_cndmask_b32_e64 v81, v81, v83, s[0:1]
	v_mul_f32_e32 v82, 0x37800000, v81
	v_cndmask_b32_e32 v81, v81, v82, vcc
	v_cmp_class_f32_e32 vcc, v68, v80
	s_nop 1
	v_cndmask_b32_e32 v68, v81, v68, vcc
	v_div_scale_f32 v80, s[0:1], v68, v68, 1.0
	v_rcp_f32_e32 v81, v80
	v_div_scale_f32 v79, vcc, 1.0, v68, 1.0
	v_fma_f32 v82, -v80, v81, 1.0
	v_fmac_f32_e32 v81, v82, v81
	v_mul_f32_e32 v82, v79, v81
	v_fma_f32 v83, -v80, v82, v79
	v_fmac_f32_e32 v82, v83, v81
	v_fma_f32 v79, -v80, v82, v79
	v_div_fmas_f32 v79, v79, v81, v82
	v_div_fixup_f32 v68, v79, v68, 1.0
	v_mul_f32_e32 v6, v6, v68
	v_mul_f32_e32 v7, v7, v68
	v_mul_f32_e32 v8, v8, v68
	v_mul_f32_e32 v9, v9, v68
	v_mul_f32_e32 v17, v17, v68
	v_mul_f32_e32 v21, v21, v68
	v_mul_f32_e32 v88, v26, v68
	v_mul_f32_e32 v89, v27, v68
	v_mul_f32_e32 v96, v38, v68
	v_mul_f32_e32 v97, v39, v68
	v_bfe_u32 v26, v6, 16, 1
	v_bfe_u32 v27, v7, 16, 1
	v_mul_f32_e32 v79, v2, v68
	v_mul_f32_e32 v80, v3, v68
	v_mul_f32_e32 v82, v5, v68
	v_mul_f32_e32 v25, v25, v68
	v_mul_f32_e32 v90, v28, v68
	v_mul_f32_e32 v91, v29, v68
	v_mul_f32_e32 v98, v40, v68
	v_mul_f32_e32 v99, v41, v68
	v_mul_f32_e32 v111, v49, v68
	v_mul_f32_e32 v115, v37, v68
	v_mul_f32_e32 v116, v62, v68
	v_mul_f32_e32 v117, v63, v68
	v_cvt_pk_bf16_f32 v2, v6, v7
	v_cvt_pk_bf16_f32 v3, v8, v9
	v_bfe_u32 v28, v8, 16, 1
	v_bfe_u32 v29, v9, 16, 1
	v_bfe_u32 v37, v17, 16, 1
	v_bfe_u32 v49, v21, 16, 1
	v_bfe_u32 v62, v96, 16, 1
	v_bfe_u32 v63, v97, 16, 1
	v_add3_u32 v6, v6, v26, s10
	v_add3_u32 v7, v7, v27, s10
	v_mul_f32_e32 v81, v4, v68
	v_mul_f32_e32 v14, v14, v68
	v_mul_f32_e32 v15, v15, v68
	v_mul_f32_e32 v16, v16, v68
	v_mul_f32_e32 v84, v30, v68
	v_mul_f32_e32 v85, v31, v68
	v_mul_f32_e32 v87, v33, v68
	v_mul_f32_e32 v92, v42, v68
	v_mul_f32_e32 v93, v43, v68
	v_mul_f32_e32 v95, v45, v68
	v_mul_f32_e32 v118, v64, v68
	v_mul_f32_e32 v119, v65, v68
	v_cvt_pk_bf16_f32 v4, v79, v80
	v_cvt_pk_bf16_f32 v5, v81, v82
	v_bfe_u32 v30, v79, 16, 1
	v_bfe_u32 v31, v80, 16, 1
	v_bfe_u32 v33, v82, 16, 1
	v_bfe_u32 v45, v25, 16, 1
	v_bfe_u32 v64, v98, 16, 1
	v_bfe_u32 v65, v99, 16, 1
	global_store_dwordx4 v130, v[2:5], s[8:9]
	v_add3_u32 v8, v8, v28, s10
	v_add3_u32 v9, v9, v29, s10
	v_cvt_pk_bf16_f32 v2, v14, v15
	v_cvt_pk_bf16_f32 v3, v16, v17
	v_add3_u32 v17, v17, v37, s10
	v_add3_u32 v37, v21, v49, s10
	v_add3_u32 v154, v96, v62, s10
	v_add3_u32 v155, v97, v63, s10
	v_and_b32_e32 v62, 0xffff0000, v6
	v_and_b32_e32 v63, 0xffff0000, v7
	v_mul_f32_e32 v86, v32, v68
	v_mul_f32_e32 v94, v44, v68
	v_mul_f32_e32 v120, v58, v68
	v_mul_f32_e32 v121, v59, v68
	v_bfe_u32 v32, v81, 16, 1
	v_bfe_u32 v58, v92, 16, 1
	v_bfe_u32 v59, v93, 16, 1
	v_add3_u32 v26, v79, v30, s10
	v_add3_u32 v27, v80, v31, s10
	v_add3_u32 v29, v82, v33, s10
	v_add3_u32 v33, v25, v45, s10
	v_add3_u32 v156, v98, v64, s10
	v_add3_u32 v157, v99, v65, s10
	v_and_b32_e32 v64, 0xffff0000, v8
	v_and_b32_e32 v65, 0xffff0000, v9
	v_and_b32_e32 v45, 0xffff0000, v37
	v_max3_f32 v37, |v62|, 0, |v63|
	v_mul_f32_e32 v10, v10, v68
	v_mul_f32_e32 v11, v11, v68
	v_mul_f32_e32 v12, v12, v68
	v_mul_f32_e32 v13, v13, v68
	v_mul_f32_e32 v22, v22, v68
	v_mul_f32_e32 v23, v23, v68
	v_mul_f32_e32 v24, v24, v68
	v_mul_f32_e32 v18, v18, v68
	v_mul_f32_e32 v19, v19, v68
	v_mul_f32_e32 v20, v20, v68
	v_mul_f32_e32 v100, v54, v68
	v_mul_f32_e32 v101, v55, v68
	v_mul_f32_e32 v102, v56, v68
	v_mul_f32_e32 v103, v57, v68
	v_mul_f32_e32 v104, v50, v68
	v_mul_f32_e32 v105, v51, v68
	v_mul_f32_e32 v106, v52, v68
	v_mul_f32_e32 v107, v53, v68
	v_mul_f32_e32 v108, v46, v68
	v_mul_f32_e32 v109, v47, v68
	v_mul_f32_e32 v110, v48, v68
	v_mul_f32_e32 v112, v34, v68
	v_mul_f32_e32 v113, v35, v68
	v_mul_f32_e32 v114, v36, v68
	v_mul_f32_e32 v122, v60, v68
	v_mul_f32_e32 v68, v61, v68
	v_bfe_u32 v34, v14, 16, 1
	v_bfe_u32 v35, v15, 16, 1
	v_bfe_u32 v60, v94, 16, 1
	v_bfe_u32 v61, v95, 16, 1
	v_add3_u32 v28, v81, v32, s10
	v_add3_u32 v150, v92, v58, s10
	v_add3_u32 v151, v93, v59, s10
	v_and_b32_e32 v58, 0xffff0000, v26
	v_and_b32_e32 v59, 0xffff0000, v27
	v_max3_f32 v37, v37, |v64|, |v65|
	v_bfe_u32 v36, v16, 16, 1
	v_bfe_u32 v54, v88, 16, 1
	v_bfe_u32 v55, v89, 16, 1
	v_add3_u32 v14, v14, v34, s10
	v_add3_u32 v15, v15, v35, s10
	v_add3_u32 v152, v94, v60, s10
	v_add3_u32 v153, v95, v61, s10
	v_and_b32_e32 v60, 0xffff0000, v28
	v_and_b32_e32 v61, 0xffff0000, v29
	v_max3_f32 v37, v37, |v58|, |v59|
	v_bfe_u32 v38, v10, 16, 1
	v_bfe_u32 v39, v11, 16, 1
	v_bfe_u32 v56, v90, 16, 1
	v_bfe_u32 v57, v91, 16, 1
	v_add3_u32 v16, v16, v36, s10
	v_add3_u32 v79, v88, v54, s10
	v_add3_u32 v147, v89, v55, s10
	v_and_b32_e32 v54, 0xffff0000, v14
	v_and_b32_e32 v55, 0xffff0000, v15
	v_max3_f32 v37, v37, |v60|, |v61|
	v_bfe_u32 v40, v12, 16, 1
	v_bfe_u32 v41, v13, 16, 1
	v_bfe_u32 v50, v84, 16, 1
	v_bfe_u32 v51, v85, 16, 1
	v_cvt_pk_bf16_f32 v4, v10, v11
	v_add3_u32 v10, v10, v38, s10
	v_add3_u32 v11, v11, v39, s10
	v_add3_u32 v148, v90, v56, s10
	v_add3_u32 v149, v91, v57, s10
	v_and_b32_e32 v56, 0xffff0000, v16
	v_and_b32_e32 v57, 0xffff0000, v17
	v_max3_f32 v37, v37, |v54|, |v55|
	v_bfe_u32 v42, v22, 16, 1
	v_bfe_u32 v43, v23, 16, 1
	v_bfe_u32 v52, v86, 16, 1
	v_bfe_u32 v53, v87, 16, 1
	v_cvt_pk_bf16_f32 v5, v12, v13
	v_add3_u32 v12, v12, v40, s10
	v_add3_u32 v13, v13, v41, s10
	v_add3_u32 v38, v84, v50, s10
	v_add3_u32 v39, v85, v51, s10
	v_and_b32_e32 v50, 0xffff0000, v10
	v_and_b32_e32 v51, 0xffff0000, v11
	v_max3_f32 v37, v37, |v56|, |v57|
	v_bfe_u32 v44, v24, 16, 1
	v_bfe_u32 v46, v18, 16, 1
	v_bfe_u32 v47, v19, 16, 1
	v_add3_u32 v30, v22, v42, s10
	v_add3_u32 v31, v23, v43, s10
	v_add3_u32 v40, v86, v52, s10
	v_add3_u32 v41, v87, v53, s10
	v_and_b32_e32 v52, 0xffff0000, v12
	v_and_b32_e32 v53, 0xffff0000, v13
	v_max3_f32 v37, v37, |v50|, |v51|
	v_bfe_u32 v48, v20, 16, 1
	v_add3_u32 v32, v24, v44, s10
	v_add3_u32 v34, v18, v46, s10
	v_add3_u32 v35, v19, v47, s10
	v_and_b32_e32 v46, 0xffff0000, v30
	v_and_b32_e32 v47, 0xffff0000, v31
	v_max3_f32 v37, v37, |v52|, |v53|
	v_add3_u32 v36, v20, v48, s10
	v_and_b32_e32 v48, 0xffff0000, v32
	v_and_b32_e32 v49, 0xffff0000, v33
	v_max3_f32 v37, v37, |v46|, |v47|
	v_and_b32_e32 v42, 0xffff0000, v34
	v_and_b32_e32 v43, 0xffff0000, v35
	v_max3_f32 v37, v37, |v48|, |v49|
	v_and_b32_e32 v44, 0xffff0000, v36
	v_max3_f32 v37, v37, |v42|, |v43|
	v_and_b32_e32 v38, 0xffff0000, v38
	v_and_b32_e32 v39, 0xffff0000, v39
	v_max3_f32 v37, v37, |v44|, |v45|
	v_and_b32_e32 v40, 0xffff0000, v40
	v_and_b32_e32 v41, 0xffff0000, v41
	v_max3_f32 v37, v37, |v38|, |v39|
	v_and_b32_e32 v33, 0xffff0000, v79
	v_and_b32_e32 v34, 0xffff0000, v147
	v_max3_f32 v37, v37, |v40|, |v41|
	v_and_b32_e32 v35, 0xffff0000, v148
	v_and_b32_e32 v36, 0xffff0000, v149
	v_max3_f32 v37, v37, |v33|, |v34|
	v_and_b32_e32 v29, 0xffff0000, v150
	v_and_b32_e32 v30, 0xffff0000, v151
	v_max3_f32 v37, v37, |v35|, |v36|
	v_and_b32_e32 v31, 0xffff0000, v152
	v_and_b32_e32 v32, 0xffff0000, v153
	v_max3_f32 v37, v37, |v29|, |v30|
	v_bfe_u32 v83, v100, 16, 1
	v_bfe_u32 v123, v101, 16, 1
	global_store_dwordx4 v130, v[2:5], s[8:9] offset:1024
	v_cvt_pk_bf16_f32 v80, v22, v23
	v_cvt_pk_bf16_f32 v81, v24, v25
	v_and_b32_e32 v25, 0xffff0000, v154
	v_and_b32_e32 v26, 0xffff0000, v155
	v_max3_f32 v37, v37, |v31|, |v32|
	v_bfe_u32 v124, v102, 16, 1
	v_bfe_u32 v125, v103, 16, 1
	v_add3_u32 v158, v100, v83, s10
	v_add3_u32 v123, v101, v123, s10
	v_and_b32_e32 v27, 0xffff0000, v156
	v_and_b32_e32 v28, 0xffff0000, v157
	v_max3_f32 v37, v37, |v25|, |v26|
	v_bfe_u32 v126, v104, 16, 1
	v_bfe_u32 v127, v105, 16, 1
	v_add3_u32 v124, v102, v124, s10
	v_add3_u32 v125, v103, v125, s10
	v_cvt_pk_bf16_f32 v82, v18, v19
	v_cvt_pk_bf16_f32 v83, v20, v21
	v_and_b32_e32 v21, 0xffff0000, v158
	v_and_b32_e32 v22, 0xffff0000, v123
	v_max3_f32 v37, v37, |v27|, |v28|
	v_bfe_u32 v128, v106, 16, 1
	v_bfe_u32 v129, v107, 16, 1
	v_add3_u32 v126, v104, v126, s10
	v_add3_u32 v127, v105, v127, s10
	v_and_b32_e32 v23, 0xffff0000, v124
	v_and_b32_e32 v24, 0xffff0000, v125
	v_max3_f32 v37, v37, |v21|, |v22|
	v_bfe_u32 v131, v108, 16, 1
	v_bfe_u32 v132, v109, 16, 1
	v_add3_u32 v128, v106, v128, s10
	v_add3_u32 v129, v107, v129, s10
	v_and_b32_e32 v17, 0xffff0000, v126
	v_and_b32_e32 v18, 0xffff0000, v127
	v_max3_f32 v37, v37, |v23|, |v24|
	v_bfe_u32 v133, v110, 16, 1
	v_bfe_u32 v134, v111, 16, 1
	v_add3_u32 v131, v108, v131, s10
	v_add3_u32 v132, v109, v132, s10
	v_and_b32_e32 v19, 0xffff0000, v128
	v_and_b32_e32 v20, 0xffff0000, v129
	v_max3_f32 v37, v37, |v17|, |v18|
	v_bfe_u32 v135, v112, 16, 1
	v_bfe_u32 v136, v113, 16, 1
	v_add3_u32 v133, v110, v133, s10
	v_add3_u32 v134, v111, v134, s10
	v_and_b32_e32 v13, 0xffff0000, v131
	v_and_b32_e32 v14, 0xffff0000, v132
	v_max3_f32 v37, v37, |v19|, |v20|
	v_bfe_u32 v137, v114, 16, 1
	v_bfe_u32 v138, v115, 16, 1
	v_add3_u32 v135, v112, v135, s10
	v_add3_u32 v136, v113, v136, s10
	v_and_b32_e32 v15, 0xffff0000, v133
	v_and_b32_e32 v16, 0xffff0000, v134
	v_max3_f32 v37, v37, |v13|, |v14|
	v_bfe_u32 v139, v116, 16, 1
	v_bfe_u32 v140, v117, 16, 1
	v_add3_u32 v137, v114, v137, s10
	v_add3_u32 v138, v115, v138, s10
	v_and_b32_e32 v9, 0xffff0000, v135
	v_and_b32_e32 v10, 0xffff0000, v136
	v_max3_f32 v37, v37, |v15|, |v16|
	v_bfe_u32 v141, v118, 16, 1
	v_bfe_u32 v142, v119, 16, 1
	v_add3_u32 v139, v116, v139, s10
	v_add3_u32 v140, v117, v140, s10
	v_and_b32_e32 v11, 0xffff0000, v137
	v_and_b32_e32 v12, 0xffff0000, v138
	v_max3_f32 v37, v37, |v9|, |v10|
	v_bfe_u32 v143, v120, 16, 1
	v_bfe_u32 v144, v121, 16, 1
	v_add3_u32 v141, v118, v141, s10
	v_add3_u32 v142, v119, v142, s10
	v_and_b32_e32 v5, 0xffff0000, v139
	v_and_b32_e32 v6, 0xffff0000, v140
	v_max3_f32 v37, v37, |v11|, |v12|
	v_bfe_u32 v145, v122, 16, 1
	v_bfe_u32 v146, v68, 16, 1
	v_add3_u32 v143, v120, v143, s10
	v_add3_u32 v144, v121, v144, s10
	v_and_b32_e32 v7, 0xffff0000, v141
	v_and_b32_e32 v8, 0xffff0000, v142
	v_max3_f32 v37, v37, |v5|, |v6|
	v_add3_u32 v145, v122, v145, s10
	v_add3_u32 v146, v68, v146, s10
	v_and_b32_e32 v2, 0xffff0000, v143
	v_and_b32_e32 v3, 0xffff0000, v144
	v_max3_f32 v37, v37, |v7|, |v8|
	v_and_b32_e32 v4, 0xffff0000, v145
	v_max3_f32 v79, v37, |v2|, |v3|
	v_and_b32_e32 v37, 0xffff0000, v146
	v_max3_f32 v79, v79, |v4|, |v37|
	ds_bpermute_b32 v73, v73, v79
	global_store_dwordx4 v130, v[80:83], s[8:9] offset:2048
	v_cmp_eq_u32_e32 vcc, 0, v1
	s_waitcnt lgkmcnt(0)
	v_max_f32_e32 v73, v73, v73
	v_max_f32_e32 v73, v79, v73
	v_cvt_pk_bf16_f32 v80, v84, v85
	ds_bpermute_b32 v84, v78, v73
	v_cvt_pk_bf16_f32 v81, v86, v87
	v_cvt_pk_bf16_f32 v82, v88, v89
	v_cvt_pk_bf16_f32 v83, v90, v91
	global_store_dwordx4 v130, v[80:83], s[8:9] offset:3072
	s_nop 1
	v_cvt_pk_bf16_f32 v80, v92, v93
	v_cvt_pk_bf16_f32 v81, v94, v95
	v_cvt_pk_bf16_f32 v82, v96, v97
	v_cvt_pk_bf16_f32 v83, v98, v99
	global_store_dwordx4 v72, v[80:83], s[8:9]
	s_waitcnt lgkmcnt(0)
	v_max_f32_e32 v72, v84, v84
	v_max_f32_e32 v72, v73, v72
	ds_bpermute_b32 v73, v77, v72
	v_cvt_pk_bf16_f32 v78, v100, v101
	v_cvt_pk_bf16_f32 v79, v102, v103
	v_cvt_pk_bf16_f32 v80, v104, v105
	v_cvt_pk_bf16_f32 v81, v106, v107
	global_store_dwordx4 v71, v[78:81], s[8:9]
	s_waitcnt lgkmcnt(0)
	v_max_f32_e32 v71, v73, v73
	v_max_f32_e32 v71, v72, v71
	ds_bpermute_b32 v72, v76, v71
	v_cvt_pk_bf16_f32 v78, v108, v109
	v_cvt_pk_bf16_f32 v79, v110, v111
	v_cvt_pk_bf16_f32 v80, v112, v113
	v_cvt_pk_bf16_f32 v81, v114, v115
	s_waitcnt lgkmcnt(0)
	v_max_f32_e32 v72, v72, v72
	v_max_f32_e32 v73, v71, v72
	ds_bpermute_b32 v75, v75, v73
	global_store_dwordx4 v70, v[78:81], s[8:9]
	v_cvt_pk_bf16_f32 v70, v116, v117
	v_cvt_pk_bf16_f32 v71, v118, v119
	v_cvt_pk_bf16_f32 v72, v120, v121
	s_waitcnt lgkmcnt(0)
	v_max_f32_e32 v75, v75, v75
	v_max_f32_e32 v75, v73, v75
	ds_bpermute_b32 v74, v74, v75
	v_cvt_pk_bf16_f32 v73, v122, v68
	v_lshlrev_b32_e32 v68, 1, v69
	global_store_dwordx4 v68, v[70:73], s[8:9]
	s_waitcnt lgkmcnt(0)
	v_max_f32_e32 v1, v74, v74
	v_max_f32_e32 v1, v75, v1
	s_and_saveexec_b64 s[0:1], vcc
	s_cbranch_execz .LBB0_782
	s_lshl_b64 s[4:5], s[6:7], 2
	s_add_u32 s4, s53, s4
	v_mul_f32_e32 v68, 0x3c010204, v1
	s_addc_u32 s5, s54, s5
	global_store_dword v67, v68, s[4:5]

.LBB0_1008:
	s_waitcnt vmcnt(19)
	v_lshlrev_b32_e32 v187, 16, v2
	s_waitcnt vmcnt(1)
	v_lshlrev_b32_e32 v186, 16, v42
	v_and_b32_e32 v195, 0xffff0000, v2
	v_and_b32_e32 v194, 0xffff0000, v42
	v_lshlrev_b32_e32 v197, 16, v3
	v_lshlrev_b32_e32 v196, 16, v43
	v_and_b32_e32 v3, 0xffff0000, v3
	v_and_b32_e32 v2, 0xffff0000, v43
	v_lshlrev_b32_e32 v43, 16, v4
	v_lshlrev_b32_e32 v42, 16, v44
	v_and_b32_e32 v199, 0xffff0000, v4
	v_and_b32_e32 v198, 0xffff0000, v44
	v_lshlrev_b32_e32 v201, 16, v5
	v_lshlrev_b32_e32 v200, 16, v45
	v_and_b32_e32 v5, 0xffff0000, v5
	v_and_b32_e32 v4, 0xffff0000, v45
	v_pk_add_f32 v[44:45], v[186:187], v[194:195]
	v_pk_add_f32 v[202:203], v[196:197], v[2:3]
	v_pk_add_f32 v[204:205], v[42:43], v[198:199]
	v_pk_add_f32 v[206:207], v[200:201], v[4:5]
	v_pk_add_f32 v[186:187], v[186:187], v[194:195] neg_lo:[0,1] neg_hi:[0,1]
	v_pk_add_f32 v[2:3], v[196:197], v[2:3] neg_lo:[0,1] neg_hi:[0,1]
	v_pk_add_f32 v[42:43], v[42:43], v[198:199] neg_lo:[0,1] neg_hi:[0,1]
	v_pk_add_f32 v[4:5], v[200:201], v[4:5] neg_lo:[0,1] neg_hi:[0,1]
	v_pk_add_f32 v[208:209], v[44:45], v[202:203] neg_lo:[0,1] neg_hi:[0,1]
	v_pk_add_f32 v[44:45], v[44:45], v[202:203]
	v_pk_add_f32 v[202:203], v[204:205], v[206:207]
	v_pk_add_f32 v[194:195], v[186:187], v[2:3] neg_lo:[0,1] neg_hi:[0,1]
	v_pk_add_f32 v[196:197], v[42:43], v[4:5] neg_lo:[0,1] neg_hi:[0,1]
	v_pk_add_f32 v[2:3], v[186:187], v[2:3]
	v_pk_add_f32 v[4:5], v[42:43], v[4:5]
	v_pk_add_f32 v[210:211], v[204:205], v[206:207] neg_lo:[0,1] neg_hi:[0,1]
	v_pk_add_f32 v[204:205], v[44:45], v[202:203]
	v_pk_add_f32 v[42:43], v[2:3], v[4:5]
	v_pk_add_f32 v[2:3], v[2:3], v[4:5] neg_lo:[0,1] neg_hi:[0,1]
	v_pk_add_f32 v[44:45], v[44:45], v[202:203] neg_lo:[0,1] neg_hi:[0,1]
	v_pk_add_f32 v[202:203], v[208:209], v[210:211]
	v_pk_add_f32 v[206:207], v[208:209], v[210:211] neg_lo:[0,1] neg_hi:[0,1]
	v_pk_add_f32 v[4:5], v[194:195], v[196:197]
	v_pk_add_f32 v[186:187], v[194:195], v[196:197] neg_lo:[0,1] neg_hi:[0,1]
	v_pk_add_f32 v[194:195], v[204:205], v[204:205] op_sel:[0,1] op_sel_hi:[1,0]
	v_pk_add_f32 v[210:211], v[2:3], v[2:3] op_sel:[0,1] op_sel_hi:[1,0]
	v_pk_add_f32 v[2:3], v[2:3], v[2:3] op_sel:[0,1] op_sel_hi:[1,0] neg_lo:[0,1] neg_hi:[0,1]
	v_pk_add_f32 v[196:197], v[204:205], v[204:205] op_sel:[0,1] op_sel_hi:[1,0] neg_lo:[0,1] neg_hi:[0,1]
	v_pk_add_f32 v[198:199], v[42:43], v[42:43] op_sel:[0,1] op_sel_hi:[1,0]
	v_pk_add_f32 v[204:205], v[4:5], v[4:5] op_sel:[0,1] op_sel_hi:[1,0]
	v_pk_add_f32 v[4:5], v[4:5], v[4:5] op_sel:[0,1] op_sel_hi:[1,0] neg_lo:[0,1] neg_hi:[0,1]
	v_pk_add_f32 v[214:215], v[186:187], v[186:187] op_sel:[0,1] op_sel_hi:[1,0]
	v_pk_add_f32 v[186:187], v[186:187], v[186:187] op_sel:[0,1] op_sel_hi:[1,0] neg_lo:[0,1] neg_hi:[0,1]
	v_xor_b32_e32 v3, v181, v194
	v_pk_add_f32 v[42:43], v[42:43], v[42:43] op_sel:[0,1] op_sel_hi:[1,0] neg_lo:[0,1] neg_hi:[0,1]
	v_pk_add_f32 v[200:201], v[202:203], v[202:203] op_sel:[0,1] op_sel_hi:[1,0]
	v_add_f32_dpp v3, v194, v3 quad_perm:[1,0,3,2] row_mask:0xf bank_mask:0xf bound_ctrl:1
	v_xor_b32_e32 v5, v181, v198
	v_xor_b32_e32 v199, v181, v186
	v_pk_add_f32 v[208:209], v[44:45], v[44:45] op_sel:[0,1] op_sel_hi:[1,0]
	v_pk_add_f32 v[44:45], v[44:45], v[44:45] op_sel:[0,1] op_sel_hi:[1,0] neg_lo:[0,1] neg_hi:[0,1]
	v_add_f32_dpp v5, v198, v5 quad_perm:[1,0,3,2] row_mask:0xf bank_mask:0xf bound_ctrl:1
	v_xor_b32_e32 v43, v181, v200
	v_add_f32_dpp v186, v186, v199 quad_perm:[1,0,3,2] row_mask:0xf bank_mask:0xf bound_ctrl:1
	v_xor_b32_e32 v199, v189, v3
	v_add_f32_dpp v43, v200, v43 quad_perm:[1,0,3,2] row_mask:0xf bank_mask:0xf bound_ctrl:1
	v_xor_b32_e32 v45, v181, v204
	v_add_f32_dpp v3, v3, v199 quad_perm:[2,3,0,1] row_mask:0xf bank_mask:0xf bound_ctrl:1
	v_xor_b32_e32 v199, v189, v5
	v_add_f32_dpp v45, v204, v45 quad_perm:[1,0,3,2] row_mask:0xf bank_mask:0xf bound_ctrl:1
	v_xor_b32_e32 v187, v181, v208
	v_add_f32_dpp v5, v5, v199 quad_perm:[2,3,0,1] row_mask:0xf bank_mask:0xf bound_ctrl:1
	v_xor_b32_e32 v199, v189, v43
	v_pk_add_f32 v[212:213], v[206:207], v[206:207] op_sel:[0,1] op_sel_hi:[1,0]
	v_add_f32_dpp v187, v208, v187 quad_perm:[1,0,3,2] row_mask:0xf bank_mask:0xf bound_ctrl:1
	v_xor_b32_e32 v193, v181, v210
	v_add_f32_dpp v43, v43, v199 quad_perm:[2,3,0,1] row_mask:0xf bank_mask:0xf bound_ctrl:1
	v_xor_b32_e32 v199, v189, v45
	v_add_f32_dpp v193, v210, v193 quad_perm:[1,0,3,2] row_mask:0xf bank_mask:0xf bound_ctrl:1
	v_xor_b32_e32 v194, v181, v212
	v_add_f32_dpp v45, v45, v199 quad_perm:[2,3,0,1] row_mask:0xf bank_mask:0xf bound_ctrl:1
	v_xor_b32_e32 v199, v189, v187
	v_add_f32_dpp v194, v212, v194 quad_perm:[1,0,3,2] row_mask:0xf bank_mask:0xf bound_ctrl:1
	v_xor_b32_e32 v195, v181, v214
	v_add_f32_dpp v187, v187, v199 quad_perm:[2,3,0,1] row_mask:0xf bank_mask:0xf bound_ctrl:1
	v_xor_b32_e32 v199, v189, v193
	v_add_f32_dpp v195, v214, v195 quad_perm:[1,0,3,2] row_mask:0xf bank_mask:0xf bound_ctrl:1
	v_xor_b32_e32 v197, v181, v196
	v_add_f32_dpp v193, v193, v199 quad_perm:[2,3,0,1] row_mask:0xf bank_mask:0xf bound_ctrl:1
	v_xor_b32_e32 v199, v189, v194
	v_pk_add_f32 v[202:203], v[202:203], v[202:203] op_sel:[0,1] op_sel_hi:[1,0] neg_lo:[0,1] neg_hi:[0,1]
	v_add_f32_dpp v196, v196, v197 quad_perm:[1,0,3,2] row_mask:0xf bank_mask:0xf bound_ctrl:1
	v_xor_b32_e32 v197, v181, v42
	v_add_f32_dpp v194, v194, v199 quad_perm:[2,3,0,1] row_mask:0xf bank_mask:0xf bound_ctrl:1
	v_xor_b32_e32 v199, v189, v195
	v_add_f32_dpp v42, v42, v197 quad_perm:[1,0,3,2] row_mask:0xf bank_mask:0xf bound_ctrl:1
	v_xor_b32_e32 v197, v181, v202
	v_add_f32_dpp v195, v195, v199 quad_perm:[2,3,0,1] row_mask:0xf bank_mask:0xf bound_ctrl:1
	v_xor_b32_e32 v199, v189, v196
	v_add_f32_dpp v197, v202, v197 quad_perm:[1,0,3,2] row_mask:0xf bank_mask:0xf bound_ctrl:1
	v_xor_b32_e32 v198, v181, v4
	v_add_f32_dpp v196, v196, v199 quad_perm:[2,3,0,1] row_mask:0xf bank_mask:0xf bound_ctrl:1
	v_xor_b32_e32 v199, v189, v42
	v_add_f32_dpp v4, v4, v198 quad_perm:[1,0,3,2] row_mask:0xf bank_mask:0xf bound_ctrl:1
	v_xor_b32_e32 v198, v181, v44
	v_add_f32_dpp v199, v42, v199 quad_perm:[2,3,0,1] row_mask:0xf bank_mask:0xf bound_ctrl:1
	v_xor_b32_e32 v42, v189, v197
	v_pk_add_f32 v[206:207], v[206:207], v[206:207] op_sel:[0,1] op_sel_hi:[1,0] neg_lo:[0,1] neg_hi:[0,1]
	v_add_f32_dpp v44, v44, v198 quad_perm:[1,0,3,2] row_mask:0xf bank_mask:0xf bound_ctrl:1
	v_xor_b32_e32 v198, v181, v2
	v_add_f32_dpp v197, v197, v42 quad_perm:[2,3,0,1] row_mask:0xf bank_mask:0xf bound_ctrl:1
	v_xor_b32_e32 v42, v189, v4
	v_add_f32_dpp v2, v2, v198 quad_perm:[1,0,3,2] row_mask:0xf bank_mask:0xf bound_ctrl:1
	v_xor_b32_e32 v198, v181, v206
	v_add_f32_dpp v4, v4, v42 quad_perm:[2,3,0,1] row_mask:0xf bank_mask:0xf bound_ctrl:1
	v_xor_b32_e32 v42, v189, v44
	v_add_f32_dpp v198, v206, v198 quad_perm:[1,0,3,2] row_mask:0xf bank_mask:0xf bound_ctrl:1
	s_ashr_i32 s31, s30, 31
	v_add_f32_dpp v200, v44, v42 quad_perm:[2,3,0,1] row_mask:0xf bank_mask:0xf bound_ctrl:1
	v_xor_b32_e32 v42, v189, v2
	v_max_f32_e64 v44, |v194|, |v195|
	s_nop 0
	v_add_f32_dpp v201, v2, v42 quad_perm:[2,3,0,1] row_mask:0xf bank_mask:0xf bound_ctrl:1
	v_xor_b32_e32 v2, v189, v198
	v_max_f32_e64 v42, |v43|, |v45|
	s_nop 0
	v_add_f32_dpp v198, v198, v2 quad_perm:[2,3,0,1] row_mask:0xf bank_mask:0xf bound_ctrl:1
	v_xor_b32_e32 v2, v189, v186
	s_nop 1
	v_add_f32_dpp v186, v186, v2 quad_perm:[2,3,0,1] row_mask:0xf bank_mask:0xf bound_ctrl:1
	v_max_f32_e64 v2, |v3|, |v5|
	v_max3_f32 v2, v2, 0, v42
	v_max_f32_e64 v42, |v187|, |v193|
	v_max3_f32 v2, v2, v42, v44
	v_max_f32_e64 v42, |v196|, |v199|
	v_max_f32_e64 v44, |v197|, |v4|
	v_max3_f32 v2, v2, v42, v44
	v_max_f32_e64 v42, |v200|, |v201|
	v_max_f32_e64 v44, |v198|, |v186|
	v_max3_f32 v216, v2, v42, v44
	v_cvt_pk_bf16_f32 v42, v3, v5
	v_cvt_pk_bf16_f32 v43, v43, v45
	v_cvt_pk_bf16_f32 v44, v187, v193
	v_cvt_pk_bf16_f32 v45, v194, v195
	v_cvt_pk_bf16_f32 v2, v196, v199
	v_cvt_pk_bf16_f32 v3, v197, v4
	v_cvt_pk_bf16_f32 v4, v200, v201
	v_cvt_pk_bf16_f32 v5, v198, v186
	v_and_b32_e32 v187, 0xffff0000, v13
	v_and_b32_e32 v186, 0xffff0000, v9
	v_lshlrev_b32_e32 v195, 16, v10
	v_lshlrev_b32_e32 v194, 16, v6
	v_and_b32_e32 v197, 0xffff0000, v10
	v_and_b32_e32 v196, 0xffff0000, v6
	v_lshlrev_b32_e32 v199, 16, v11
	v_lshlrev_b32_e32 v198, 16, v7
	v_and_b32_e32 v11, 0xffff0000, v11
	v_and_b32_e32 v10, 0xffff0000, v7
	v_lshlrev_b32_e32 v7, 16, v12
	v_lshlrev_b32_e32 v6, 16, v8
	v_and_b32_e32 v201, 0xffff0000, v12
	v_and_b32_e32 v200, 0xffff0000, v8
	v_lshlrev_b32_e32 v13, 16, v13
	v_lshlrev_b32_e32 v12, 16, v9
	v_pk_add_f32 v[8:9], v[194:195], v[196:197]
	v_pk_add_f32 v[202:203], v[198:199], v[10:11]
	v_pk_add_f32 v[204:205], v[6:7], v[200:201]
	v_pk_add_f32 v[206:207], v[12:13], v[186:187]
	v_pk_add_f32 v[194:195], v[194:195], v[196:197] neg_lo:[0,1] neg_hi:[0,1]
	v_pk_add_f32 v[10:11], v[198:199], v[10:11] neg_lo:[0,1] neg_hi:[0,1]
	v_pk_add_f32 v[6:7], v[6:7], v[200:201] neg_lo:[0,1] neg_hi:[0,1]
	v_pk_add_f32 v[12:13], v[12:13], v[186:187] neg_lo:[0,1] neg_hi:[0,1]
	v_pk_add_f32 v[208:209], v[8:9], v[202:203] neg_lo:[0,1] neg_hi:[0,1]
	v_pk_add_f32 v[8:9], v[8:9], v[202:203]
	v_pk_add_f32 v[202:203], v[204:205], v[206:207]
	v_pk_add_f32 v[186:187], v[194:195], v[10:11] neg_lo:[0,1] neg_hi:[0,1]
	v_pk_add_f32 v[196:197], v[6:7], v[12:13] neg_lo:[0,1] neg_hi:[0,1]
	v_pk_add_f32 v[10:11], v[194:195], v[10:11]
	v_pk_add_f32 v[6:7], v[6:7], v[12:13]
	v_pk_add_f32 v[210:211], v[204:205], v[206:207] neg_lo:[0,1] neg_hi:[0,1]
	v_pk_add_f32 v[204:205], v[8:9], v[202:203]
	v_pk_add_f32 v[12:13], v[10:11], v[6:7]
	v_pk_add_f32 v[6:7], v[10:11], v[6:7] neg_lo:[0,1] neg_hi:[0,1]
	v_pk_add_f32 v[8:9], v[8:9], v[202:203] neg_lo:[0,1] neg_hi:[0,1]
	v_pk_add_f32 v[202:203], v[208:209], v[210:211]
	v_pk_add_f32 v[206:207], v[208:209], v[210:211] neg_lo:[0,1] neg_hi:[0,1]
	v_pk_add_f32 v[10:11], v[186:187], v[196:197]
	v_pk_add_f32 v[186:187], v[186:187], v[196:197] neg_lo:[0,1] neg_hi:[0,1]
	v_pk_add_f32 v[194:195], v[204:205], v[204:205] op_sel:[0,1] op_sel_hi:[1,0]
	v_pk_add_f32 v[210:211], v[6:7], v[6:7] op_sel:[0,1] op_sel_hi:[1,0]
	v_pk_add_f32 v[6:7], v[6:7], v[6:7] op_sel:[0,1] op_sel_hi:[1,0] neg_lo:[0,1] neg_hi:[0,1]
	v_pk_add_f32 v[198:199], v[12:13], v[12:13] op_sel:[0,1] op_sel_hi:[1,0]
	v_pk_add_f32 v[208:209], v[8:9], v[8:9] op_sel:[0,1] op_sel_hi:[1,0]
	v_pk_add_f32 v[8:9], v[8:9], v[8:9] op_sel:[0,1] op_sel_hi:[1,0] neg_lo:[0,1] neg_hi:[0,1]
	v_pk_add_f32 v[214:215], v[186:187], v[186:187] op_sel:[0,1] op_sel_hi:[1,0]
	v_pk_add_f32 v[186:187], v[186:187], v[186:187] op_sel:[0,1] op_sel_hi:[1,0] neg_lo:[0,1] neg_hi:[0,1]
	v_xor_b32_e32 v7, v181, v194
	v_pk_add_f32 v[196:197], v[204:205], v[204:205] op_sel:[0,1] op_sel_hi:[1,0] neg_lo:[0,1] neg_hi:[0,1]
	v_pk_add_f32 v[200:201], v[202:203], v[202:203] op_sel:[0,1] op_sel_hi:[1,0]
	v_pk_add_f32 v[204:205], v[10:11], v[10:11] op_sel:[0,1] op_sel_hi:[1,0]
	v_pk_add_f32 v[10:11], v[10:11], v[10:11] op_sel:[0,1] op_sel_hi:[1,0] neg_lo:[0,1] neg_hi:[0,1]
	v_add_f32_dpp v7, v194, v7 quad_perm:[1,0,3,2] row_mask:0xf bank_mask:0xf bound_ctrl:1
	v_xor_b32_e32 v9, v181, v198
	v_xor_b32_e32 v199, v181, v186
	v_pk_add_f32 v[12:13], v[12:13], v[12:13] op_sel:[0,1] op_sel_hi:[1,0] neg_lo:[0,1] neg_hi:[0,1]
	v_add_f32_dpp v9, v198, v9 quad_perm:[1,0,3,2] row_mask:0xf bank_mask:0xf bound_ctrl:1
	v_xor_b32_e32 v11, v181, v200
	v_add_f32_dpp v186, v186, v199 quad_perm:[1,0,3,2] row_mask:0xf bank_mask:0xf bound_ctrl:1
	v_xor_b32_e32 v199, v189, v7
	v_add_f32_dpp v11, v200, v11 quad_perm:[1,0,3,2] row_mask:0xf bank_mask:0xf bound_ctrl:1
	v_xor_b32_e32 v13, v181, v204
	v_add_f32_dpp v7, v7, v199 quad_perm:[2,3,0,1] row_mask:0xf bank_mask:0xf bound_ctrl:1
	v_xor_b32_e32 v199, v189, v9
	v_add_f32_dpp v13, v204, v13 quad_perm:[1,0,3,2] row_mask:0xf bank_mask:0xf bound_ctrl:1
	v_xor_b32_e32 v187, v181, v208
	v_add_f32_dpp v9, v9, v199 quad_perm:[2,3,0,1] row_mask:0xf bank_mask:0xf bound_ctrl:1
	v_xor_b32_e32 v199, v189, v11
	v_pk_add_f32 v[212:213], v[206:207], v[206:207] op_sel:[0,1] op_sel_hi:[1,0]
	v_add_f32_dpp v187, v208, v187 quad_perm:[1,0,3,2] row_mask:0xf bank_mask:0xf bound_ctrl:1
	v_xor_b32_e32 v193, v181, v210
	v_add_f32_dpp v11, v11, v199 quad_perm:[2,3,0,1] row_mask:0xf bank_mask:0xf bound_ctrl:1
	v_xor_b32_e32 v199, v189, v13
	v_add_f32_dpp v193, v210, v193 quad_perm:[1,0,3,2] row_mask:0xf bank_mask:0xf bound_ctrl:1
	v_xor_b32_e32 v194, v181, v212
	v_add_f32_dpp v13, v13, v199 quad_perm:[2,3,0,1] row_mask:0xf bank_mask:0xf bound_ctrl:1
	v_xor_b32_e32 v199, v189, v187
	v_add_f32_dpp v194, v212, v194 quad_perm:[1,0,3,2] row_mask:0xf bank_mask:0xf bound_ctrl:1
	v_xor_b32_e32 v195, v181, v214
	v_add_f32_dpp v187, v187, v199 quad_perm:[2,3,0,1] row_mask:0xf bank_mask:0xf bound_ctrl:1
	v_xor_b32_e32 v199, v189, v193
	v_add_f32_dpp v195, v214, v195 quad_perm:[1,0,3,2] row_mask:0xf bank_mask:0xf bound_ctrl:1
	v_xor_b32_e32 v197, v181, v196
	v_add_f32_dpp v193, v193, v199 quad_perm:[2,3,0,1] row_mask:0xf bank_mask:0xf bound_ctrl:1
	v_xor_b32_e32 v199, v189, v194
	v_pk_add_f32 v[202:203], v[202:203], v[202:203] op_sel:[0,1] op_sel_hi:[1,0] neg_lo:[0,1] neg_hi:[0,1]
	v_add_f32_dpp v196, v196, v197 quad_perm:[1,0,3,2] row_mask:0xf bank_mask:0xf bound_ctrl:1
	v_xor_b32_e32 v197, v181, v12
	v_add_f32_dpp v194, v194, v199 quad_perm:[2,3,0,1] row_mask:0xf bank_mask:0xf bound_ctrl:1
	v_xor_b32_e32 v199, v189, v195
	v_add_f32_dpp v12, v12, v197 quad_perm:[1,0,3,2] row_mask:0xf bank_mask:0xf bound_ctrl:1
	v_xor_b32_e32 v197, v181, v202
	v_add_f32_dpp v195, v195, v199 quad_perm:[2,3,0,1] row_mask:0xf bank_mask:0xf bound_ctrl:1
	v_xor_b32_e32 v199, v189, v196
	v_add_f32_dpp v197, v202, v197 quad_perm:[1,0,3,2] row_mask:0xf bank_mask:0xf bound_ctrl:1
	v_xor_b32_e32 v198, v181, v10
	v_add_f32_dpp v196, v196, v199 quad_perm:[2,3,0,1] row_mask:0xf bank_mask:0xf bound_ctrl:1
	v_xor_b32_e32 v199, v189, v12
	v_add_f32_dpp v10, v10, v198 quad_perm:[1,0,3,2] row_mask:0xf bank_mask:0xf bound_ctrl:1
	v_xor_b32_e32 v198, v181, v8
	v_add_f32_dpp v12, v12, v199 quad_perm:[2,3,0,1] row_mask:0xf bank_mask:0xf bound_ctrl:1
	v_xor_b32_e32 v199, v189, v197
	v_pk_add_f32 v[206:207], v[206:207], v[206:207] op_sel:[0,1] op_sel_hi:[1,0] neg_lo:[0,1] neg_hi:[0,1]
	v_add_f32_dpp v8, v8, v198 quad_perm:[1,0,3,2] row_mask:0xf bank_mask:0xf bound_ctrl:1
	v_xor_b32_e32 v198, v181, v6
	v_add_f32_dpp v197, v197, v199 quad_perm:[2,3,0,1] row_mask:0xf bank_mask:0xf bound_ctrl:1
	v_xor_b32_e32 v199, v189, v10
	v_add_f32_dpp v6, v6, v198 quad_perm:[1,0,3,2] row_mask:0xf bank_mask:0xf bound_ctrl:1
	v_xor_b32_e32 v198, v181, v206
	v_add_f32_dpp v199, v10, v199 quad_perm:[2,3,0,1] row_mask:0xf bank_mask:0xf bound_ctrl:1
	v_xor_b32_e32 v10, v189, v8
	v_add_f32_dpp v198, v206, v198 quad_perm:[1,0,3,2] row_mask:0xf bank_mask:0xf bound_ctrl:1
	s_nop 0
	v_add_f32_dpp v200, v8, v10 quad_perm:[2,3,0,1] row_mask:0xf bank_mask:0xf bound_ctrl:1
	v_xor_b32_e32 v8, v189, v6
	v_max_f32_e64 v10, |v194|, |v195|
	s_nop 0
	v_add_f32_dpp v201, v6, v8 quad_perm:[2,3,0,1] row_mask:0xf bank_mask:0xf bound_ctrl:1
	v_xor_b32_e32 v6, v189, v198
	v_max_f32_e64 v8, |v11|, |v13|
	s_nop 0
	v_add_f32_dpp v198, v198, v6 quad_perm:[2,3,0,1] row_mask:0xf bank_mask:0xf bound_ctrl:1
	v_xor_b32_e32 v6, v189, v186
	s_nop 1
	v_add_f32_dpp v186, v186, v6 quad_perm:[2,3,0,1] row_mask:0xf bank_mask:0xf bound_ctrl:1
	v_max_f32_e64 v6, |v7|, |v9|
	v_max3_f32 v6, v216, v6, v8
	v_max_f32_e64 v8, |v187|, |v193|
	v_max3_f32 v6, v6, v8, v10
	v_max_f32_e64 v8, |v196|, |v12|
	v_max_f32_e64 v10, |v197|, |v199|
	v_max3_f32 v6, v6, v8, v10
	v_max_f32_e64 v8, |v200|, |v201|
	v_max_f32_e64 v10, |v198|, |v186|
	v_max3_f32 v216, v6, v8, v10
	v_cvt_pk_bf16_f32 v6, v7, v9
	v_cvt_pk_bf16_f32 v7, v11, v13
	v_cvt_pk_bf16_f32 v8, v187, v193
	v_cvt_pk_bf16_f32 v9, v194, v195
	v_cvt_pk_bf16_f32 v10, v196, v12
	v_cvt_pk_bf16_f32 v11, v197, v199
	v_cvt_pk_bf16_f32 v12, v200, v201
	v_cvt_pk_bf16_f32 v13, v198, v186
	v_and_b32_e32 v187, 0xffff0000, v25
	v_and_b32_e32 v186, 0xffff0000, v17
	v_lshlrev_b32_e32 v195, 16, v22
	v_lshlrev_b32_e32 v194, 16, v14
	v_and_b32_e32 v197, 0xffff0000, v22
	v_and_b32_e32 v196, 0xffff0000, v14
	v_lshlrev_b32_e32 v199, 16, v23
	v_lshlrev_b32_e32 v198, 16, v15
	v_and_b32_e32 v23, 0xffff0000, v23
	v_and_b32_e32 v22, 0xffff0000, v15
	v_lshlrev_b32_e32 v15, 16, v24
	v_lshlrev_b32_e32 v14, 16, v16
	v_and_b32_e32 v201, 0xffff0000, v24
	v_and_b32_e32 v200, 0xffff0000, v16
	v_lshlrev_b32_e32 v25, 16, v25
	v_lshlrev_b32_e32 v24, 16, v17
	v_pk_add_f32 v[16:17], v[194:195], v[196:197]
	v_pk_add_f32 v[202:203], v[198:199], v[22:23]
	v_pk_add_f32 v[204:205], v[14:15], v[200:201]
	v_pk_add_f32 v[206:207], v[24:25], v[186:187]
	v_pk_add_f32 v[194:195], v[194:195], v[196:197] neg_lo:[0,1] neg_hi:[0,1]
	v_pk_add_f32 v[22:23], v[198:199], v[22:23] neg_lo:[0,1] neg_hi:[0,1]
	v_pk_add_f32 v[14:15], v[14:15], v[200:201] neg_lo:[0,1] neg_hi:[0,1]
	v_pk_add_f32 v[24:25], v[24:25], v[186:187] neg_lo:[0,1] neg_hi:[0,1]
	v_pk_add_f32 v[208:209], v[16:17], v[202:203] neg_lo:[0,1] neg_hi:[0,1]
	v_pk_add_f32 v[16:17], v[16:17], v[202:203]
	v_pk_add_f32 v[202:203], v[204:205], v[206:207]
	v_pk_add_f32 v[186:187], v[194:195], v[22:23] neg_lo:[0,1] neg_hi:[0,1]
	v_pk_add_f32 v[196:197], v[14:15], v[24:25] neg_lo:[0,1] neg_hi:[0,1]
	v_pk_add_f32 v[22:23], v[194:195], v[22:23]
	v_pk_add_f32 v[14:15], v[14:15], v[24:25]
	v_pk_add_f32 v[210:211], v[204:205], v[206:207] neg_lo:[0,1] neg_hi:[0,1]
	v_pk_add_f32 v[204:205], v[16:17], v[202:203]
	v_pk_add_f32 v[24:25], v[22:23], v[14:15]
	v_pk_add_f32 v[14:15], v[22:23], v[14:15] neg_lo:[0,1] neg_hi:[0,1]
	v_pk_add_f32 v[16:17], v[16:17], v[202:203] neg_lo:[0,1] neg_hi:[0,1]
	v_pk_add_f32 v[202:203], v[208:209], v[210:211]
	v_pk_add_f32 v[206:207], v[208:209], v[210:211] neg_lo:[0,1] neg_hi:[0,1]
	v_pk_add_f32 v[22:23], v[186:187], v[196:197]
	v_pk_add_f32 v[186:187], v[186:187], v[196:197] neg_lo:[0,1] neg_hi:[0,1]
	v_pk_add_f32 v[194:195], v[204:205], v[204:205] op_sel:[0,1] op_sel_hi:[1,0]
	v_pk_add_f32 v[210:211], v[14:15], v[14:15] op_sel:[0,1] op_sel_hi:[1,0]
	v_pk_add_f32 v[14:15], v[14:15], v[14:15] op_sel:[0,1] op_sel_hi:[1,0] neg_lo:[0,1] neg_hi:[0,1]
	v_pk_add_f32 v[198:199], v[24:25], v[24:25] op_sel:[0,1] op_sel_hi:[1,0]
	v_pk_add_f32 v[208:209], v[16:17], v[16:17] op_sel:[0,1] op_sel_hi:[1,0]
	v_pk_add_f32 v[16:17], v[16:17], v[16:17] op_sel:[0,1] op_sel_hi:[1,0] neg_lo:[0,1] neg_hi:[0,1]
	v_pk_add_f32 v[214:215], v[186:187], v[186:187] op_sel:[0,1] op_sel_hi:[1,0]
	v_pk_add_f32 v[186:187], v[186:187], v[186:187] op_sel:[0,1] op_sel_hi:[1,0] neg_lo:[0,1] neg_hi:[0,1]
	v_xor_b32_e32 v15, v181, v194
	v_pk_add_f32 v[196:197], v[204:205], v[204:205] op_sel:[0,1] op_sel_hi:[1,0] neg_lo:[0,1] neg_hi:[0,1]
	v_pk_add_f32 v[200:201], v[202:203], v[202:203] op_sel:[0,1] op_sel_hi:[1,0]
	v_pk_add_f32 v[204:205], v[22:23], v[22:23] op_sel:[0,1] op_sel_hi:[1,0]
	v_pk_add_f32 v[22:23], v[22:23], v[22:23] op_sel:[0,1] op_sel_hi:[1,0] neg_lo:[0,1] neg_hi:[0,1]
	v_add_f32_dpp v15, v194, v15 quad_perm:[1,0,3,2] row_mask:0xf bank_mask:0xf bound_ctrl:1
	v_xor_b32_e32 v17, v181, v198
	v_xor_b32_e32 v199, v181, v186
	v_pk_add_f32 v[24:25], v[24:25], v[24:25] op_sel:[0,1] op_sel_hi:[1,0] neg_lo:[0,1] neg_hi:[0,1]
	v_add_f32_dpp v17, v198, v17 quad_perm:[1,0,3,2] row_mask:0xf bank_mask:0xf bound_ctrl:1
	v_xor_b32_e32 v23, v181, v200
	v_add_f32_dpp v186, v186, v199 quad_perm:[1,0,3,2] row_mask:0xf bank_mask:0xf bound_ctrl:1
	v_xor_b32_e32 v199, v189, v15
	v_add_f32_dpp v23, v200, v23 quad_perm:[1,0,3,2] row_mask:0xf bank_mask:0xf bound_ctrl:1
	v_xor_b32_e32 v25, v181, v204
	v_add_f32_dpp v15, v15, v199 quad_perm:[2,3,0,1] row_mask:0xf bank_mask:0xf bound_ctrl:1
	v_xor_b32_e32 v199, v189, v17
	v_add_f32_dpp v25, v204, v25 quad_perm:[1,0,3,2] row_mask:0xf bank_mask:0xf bound_ctrl:1
	v_xor_b32_e32 v187, v181, v208
	v_add_f32_dpp v17, v17, v199 quad_perm:[2,3,0,1] row_mask:0xf bank_mask:0xf bound_ctrl:1
	v_xor_b32_e32 v199, v189, v23
	v_pk_add_f32 v[212:213], v[206:207], v[206:207] op_sel:[0,1] op_sel_hi:[1,0]
	v_add_f32_dpp v187, v208, v187 quad_perm:[1,0,3,2] row_mask:0xf bank_mask:0xf bound_ctrl:1
	v_xor_b32_e32 v193, v181, v210
	v_add_f32_dpp v23, v23, v199 quad_perm:[2,3,0,1] row_mask:0xf bank_mask:0xf bound_ctrl:1
	v_xor_b32_e32 v199, v189, v25
	v_add_f32_dpp v193, v210, v193 quad_perm:[1,0,3,2] row_mask:0xf bank_mask:0xf bound_ctrl:1
	v_xor_b32_e32 v194, v181, v212
	v_add_f32_dpp v25, v25, v199 quad_perm:[2,3,0,1] row_mask:0xf bank_mask:0xf bound_ctrl:1
	v_xor_b32_e32 v199, v189, v187
	v_add_f32_dpp v194, v212, v194 quad_perm:[1,0,3,2] row_mask:0xf bank_mask:0xf bound_ctrl:1
	v_xor_b32_e32 v195, v181, v214
	v_add_f32_dpp v187, v187, v199 quad_perm:[2,3,0,1] row_mask:0xf bank_mask:0xf bound_ctrl:1
	v_xor_b32_e32 v199, v189, v193
	v_add_f32_dpp v195, v214, v195 quad_perm:[1,0,3,2] row_mask:0xf bank_mask:0xf bound_ctrl:1
	v_xor_b32_e32 v197, v181, v196
	v_add_f32_dpp v193, v193, v199 quad_perm:[2,3,0,1] row_mask:0xf bank_mask:0xf bound_ctrl:1
	v_xor_b32_e32 v199, v189, v194
	v_pk_add_f32 v[202:203], v[202:203], v[202:203] op_sel:[0,1] op_sel_hi:[1,0] neg_lo:[0,1] neg_hi:[0,1]
	v_add_f32_dpp v196, v196, v197 quad_perm:[1,0,3,2] row_mask:0xf bank_mask:0xf bound_ctrl:1
	v_xor_b32_e32 v197, v181, v24
	v_add_f32_dpp v194, v194, v199 quad_perm:[2,3,0,1] row_mask:0xf bank_mask:0xf bound_ctrl:1
	v_xor_b32_e32 v199, v189, v195
	v_add_f32_dpp v24, v24, v197 quad_perm:[1,0,3,2] row_mask:0xf bank_mask:0xf bound_ctrl:1
	v_xor_b32_e32 v197, v181, v202
	v_add_f32_dpp v195, v195, v199 quad_perm:[2,3,0,1] row_mask:0xf bank_mask:0xf bound_ctrl:1
	v_xor_b32_e32 v199, v189, v196
	v_add_f32_dpp v197, v202, v197 quad_perm:[1,0,3,2] row_mask:0xf bank_mask:0xf bound_ctrl:1
	v_xor_b32_e32 v198, v181, v22
	v_add_f32_dpp v196, v196, v199 quad_perm:[2,3,0,1] row_mask:0xf bank_mask:0xf bound_ctrl:1
	v_xor_b32_e32 v199, v189, v24
	v_add_f32_dpp v22, v22, v198 quad_perm:[1,0,3,2] row_mask:0xf bank_mask:0xf bound_ctrl:1
	v_xor_b32_e32 v198, v181, v16
	v_add_f32_dpp v24, v24, v199 quad_perm:[2,3,0,1] row_mask:0xf bank_mask:0xf bound_ctrl:1
	v_xor_b32_e32 v199, v189, v197
	v_pk_add_f32 v[206:207], v[206:207], v[206:207] op_sel:[0,1] op_sel_hi:[1,0] neg_lo:[0,1] neg_hi:[0,1]
	v_add_f32_dpp v16, v16, v198 quad_perm:[1,0,3,2] row_mask:0xf bank_mask:0xf bound_ctrl:1
	v_xor_b32_e32 v198, v181, v14
	v_add_f32_dpp v197, v197, v199 quad_perm:[2,3,0,1] row_mask:0xf bank_mask:0xf bound_ctrl:1
	v_xor_b32_e32 v199, v189, v22
	v_add_f32_dpp v14, v14, v198 quad_perm:[1,0,3,2] row_mask:0xf bank_mask:0xf bound_ctrl:1
	v_xor_b32_e32 v198, v181, v206
	v_add_f32_dpp v199, v22, v199 quad_perm:[2,3,0,1] row_mask:0xf bank_mask:0xf bound_ctrl:1
	v_xor_b32_e32 v22, v189, v16
	v_add_f32_dpp v198, v206, v198 quad_perm:[1,0,3,2] row_mask:0xf bank_mask:0xf bound_ctrl:1
	s_nop 0
	v_add_f32_dpp v200, v16, v22 quad_perm:[2,3,0,1] row_mask:0xf bank_mask:0xf bound_ctrl:1
	v_xor_b32_e32 v16, v189, v14
	v_max_f32_e64 v22, |v194|, |v195|
	s_nop 0
	v_add_f32_dpp v201, v14, v16 quad_perm:[2,3,0,1] row_mask:0xf bank_mask:0xf bound_ctrl:1
	v_xor_b32_e32 v14, v189, v198
	v_max_f32_e64 v16, |v23|, |v25|
	s_nop 0
	v_add_f32_dpp v198, v198, v14 quad_perm:[2,3,0,1] row_mask:0xf bank_mask:0xf bound_ctrl:1
	v_xor_b32_e32 v14, v189, v186
	s_nop 1
	v_add_f32_dpp v186, v186, v14 quad_perm:[2,3,0,1] row_mask:0xf bank_mask:0xf bound_ctrl:1
	v_max_f32_e64 v14, |v15|, |v17|
	v_max3_f32 v14, v216, v14, v16
	v_max_f32_e64 v16, |v187|, |v193|
	v_max3_f32 v14, v14, v16, v22
	v_max_f32_e64 v16, |v196|, |v24|
	v_max_f32_e64 v22, |v197|, |v199|
	v_max3_f32 v14, v14, v16, v22
	v_max_f32_e64 v16, |v200|, |v201|
	v_max_f32_e64 v22, |v198|, |v186|
	v_max3_f32 v216, v14, v16, v22
	v_cvt_pk_bf16_f32 v14, v15, v17
	v_cvt_pk_bf16_f32 v15, v23, v25
	v_cvt_pk_bf16_f32 v16, v187, v193
	v_cvt_pk_bf16_f32 v17, v194, v195
	v_cvt_pk_bf16_f32 v22, v196, v24
	v_cvt_pk_bf16_f32 v23, v197, v199
	v_cvt_pk_bf16_f32 v24, v200, v201
	v_cvt_pk_bf16_f32 v25, v198, v186
	v_and_b32_e32 v187, 0xffff0000, v29
	v_and_b32_e32 v186, 0xffff0000, v21
	v_lshlrev_b32_e32 v195, 16, v26
	v_lshlrev_b32_e32 v194, 16, v18
	v_and_b32_e32 v197, 0xffff0000, v26
	v_and_b32_e32 v196, 0xffff0000, v18
	v_lshlrev_b32_e32 v199, 16, v27
	v_lshlrev_b32_e32 v198, 16, v19
	v_and_b32_e32 v27, 0xffff0000, v27
	v_and_b32_e32 v26, 0xffff0000, v19
	v_lshlrev_b32_e32 v19, 16, v28
	v_lshlrev_b32_e32 v18, 16, v20
	v_and_b32_e32 v201, 0xffff0000, v28
	v_and_b32_e32 v200, 0xffff0000, v20
	v_lshlrev_b32_e32 v29, 16, v29
	v_lshlrev_b32_e32 v28, 16, v21
	v_pk_add_f32 v[20:21], v[194:195], v[196:197]
	v_pk_add_f32 v[202:203], v[198:199], v[26:27]
	v_pk_add_f32 v[204:205], v[18:19], v[200:201]
	v_pk_add_f32 v[206:207], v[28:29], v[186:187]
	v_pk_add_f32 v[194:195], v[194:195], v[196:197] neg_lo:[0,1] neg_hi:[0,1]
	v_pk_add_f32 v[26:27], v[198:199], v[26:27] neg_lo:[0,1] neg_hi:[0,1]
	v_pk_add_f32 v[18:19], v[18:19], v[200:201] neg_lo:[0,1] neg_hi:[0,1]
	v_pk_add_f32 v[28:29], v[28:29], v[186:187] neg_lo:[0,1] neg_hi:[0,1]
	v_pk_add_f32 v[208:209], v[20:21], v[202:203] neg_lo:[0,1] neg_hi:[0,1]
	v_pk_add_f32 v[20:21], v[20:21], v[202:203]
	v_pk_add_f32 v[202:203], v[204:205], v[206:207]
	v_pk_add_f32 v[186:187], v[194:195], v[26:27] neg_lo:[0,1] neg_hi:[0,1]
	v_pk_add_f32 v[196:197], v[18:19], v[28:29] neg_lo:[0,1] neg_hi:[0,1]
	v_pk_add_f32 v[26:27], v[194:195], v[26:27]
	v_pk_add_f32 v[18:19], v[18:19], v[28:29]
	v_pk_add_f32 v[210:211], v[204:205], v[206:207] neg_lo:[0,1] neg_hi:[0,1]
	v_pk_add_f32 v[204:205], v[20:21], v[202:203]
	v_pk_add_f32 v[28:29], v[26:27], v[18:19]
	v_pk_add_f32 v[18:19], v[26:27], v[18:19] neg_lo:[0,1] neg_hi:[0,1]
	v_pk_add_f32 v[20:21], v[20:21], v[202:203] neg_lo:[0,1] neg_hi:[0,1]
	v_pk_add_f32 v[202:203], v[208:209], v[210:211]
	v_pk_add_f32 v[206:207], v[208:209], v[210:211] neg_lo:[0,1] neg_hi:[0,1]
	v_pk_add_f32 v[26:27], v[186:187], v[196:197]
	v_pk_add_f32 v[186:187], v[186:187], v[196:197] neg_lo:[0,1] neg_hi:[0,1]
	v_pk_add_f32 v[194:195], v[204:205], v[204:205] op_sel:[0,1] op_sel_hi:[1,0]
	v_pk_add_f32 v[210:211], v[18:19], v[18:19] op_sel:[0,1] op_sel_hi:[1,0]
	v_pk_add_f32 v[18:19], v[18:19], v[18:19] op_sel:[0,1] op_sel_hi:[1,0] neg_lo:[0,1] neg_hi:[0,1]
	v_pk_add_f32 v[198:199], v[28:29], v[28:29] op_sel:[0,1] op_sel_hi:[1,0]
	v_pk_add_f32 v[208:209], v[20:21], v[20:21] op_sel:[0,1] op_sel_hi:[1,0]
	v_pk_add_f32 v[20:21], v[20:21], v[20:21] op_sel:[0,1] op_sel_hi:[1,0] neg_lo:[0,1] neg_hi:[0,1]
	v_pk_add_f32 v[214:215], v[186:187], v[186:187] op_sel:[0,1] op_sel_hi:[1,0]
	v_pk_add_f32 v[186:187], v[186:187], v[186:187] op_sel:[0,1] op_sel_hi:[1,0] neg_lo:[0,1] neg_hi:[0,1]
	v_xor_b32_e32 v19, v181, v194
	v_pk_add_f32 v[196:197], v[204:205], v[204:205] op_sel:[0,1] op_sel_hi:[1,0] neg_lo:[0,1] neg_hi:[0,1]
	v_pk_add_f32 v[200:201], v[202:203], v[202:203] op_sel:[0,1] op_sel_hi:[1,0]
	v_pk_add_f32 v[204:205], v[26:27], v[26:27] op_sel:[0,1] op_sel_hi:[1,0]
	v_pk_add_f32 v[26:27], v[26:27], v[26:27] op_sel:[0,1] op_sel_hi:[1,0] neg_lo:[0,1] neg_hi:[0,1]
	v_add_f32_dpp v19, v194, v19 quad_perm:[1,0,3,2] row_mask:0xf bank_mask:0xf bound_ctrl:1
	v_xor_b32_e32 v21, v181, v198
	v_xor_b32_e32 v199, v181, v186
	v_pk_add_f32 v[28:29], v[28:29], v[28:29] op_sel:[0,1] op_sel_hi:[1,0] neg_lo:[0,1] neg_hi:[0,1]
	v_add_f32_dpp v21, v198, v21 quad_perm:[1,0,3,2] row_mask:0xf bank_mask:0xf bound_ctrl:1
	v_xor_b32_e32 v27, v181, v200
	v_add_f32_dpp v186, v186, v199 quad_perm:[1,0,3,2] row_mask:0xf bank_mask:0xf bound_ctrl:1
	v_xor_b32_e32 v199, v189, v19
	v_add_f32_dpp v27, v200, v27 quad_perm:[1,0,3,2] row_mask:0xf bank_mask:0xf bound_ctrl:1
	v_xor_b32_e32 v29, v181, v204
	v_add_f32_dpp v19, v19, v199 quad_perm:[2,3,0,1] row_mask:0xf bank_mask:0xf bound_ctrl:1
	v_xor_b32_e32 v199, v189, v21
	v_add_f32_dpp v29, v204, v29 quad_perm:[1,0,3,2] row_mask:0xf bank_mask:0xf bound_ctrl:1
	v_xor_b32_e32 v187, v181, v208
	v_add_f32_dpp v21, v21, v199 quad_perm:[2,3,0,1] row_mask:0xf bank_mask:0xf bound_ctrl:1
	v_xor_b32_e32 v199, v189, v27
	v_pk_add_f32 v[212:213], v[206:207], v[206:207] op_sel:[0,1] op_sel_hi:[1,0]
	v_add_f32_dpp v187, v208, v187 quad_perm:[1,0,3,2] row_mask:0xf bank_mask:0xf bound_ctrl:1
	v_xor_b32_e32 v193, v181, v210
	v_add_f32_dpp v27, v27, v199 quad_perm:[2,3,0,1] row_mask:0xf bank_mask:0xf bound_ctrl:1
	v_xor_b32_e32 v199, v189, v29
	v_add_f32_dpp v193, v210, v193 quad_perm:[1,0,3,2] row_mask:0xf bank_mask:0xf bound_ctrl:1
	v_xor_b32_e32 v194, v181, v212
	v_add_f32_dpp v29, v29, v199 quad_perm:[2,3,0,1] row_mask:0xf bank_mask:0xf bound_ctrl:1
	v_xor_b32_e32 v199, v189, v187
	v_add_f32_dpp v194, v212, v194 quad_perm:[1,0,3,2] row_mask:0xf bank_mask:0xf bound_ctrl:1
	v_xor_b32_e32 v195, v181, v214
	v_add_f32_dpp v187, v187, v199 quad_perm:[2,3,0,1] row_mask:0xf bank_mask:0xf bound_ctrl:1
	v_xor_b32_e32 v199, v189, v193
	v_add_f32_dpp v195, v214, v195 quad_perm:[1,0,3,2] row_mask:0xf bank_mask:0xf bound_ctrl:1
	v_xor_b32_e32 v197, v181, v196
	v_add_f32_dpp v193, v193, v199 quad_perm:[2,3,0,1] row_mask:0xf bank_mask:0xf bound_ctrl:1
	v_xor_b32_e32 v199, v189, v194
	v_pk_add_f32 v[202:203], v[202:203], v[202:203] op_sel:[0,1] op_sel_hi:[1,0] neg_lo:[0,1] neg_hi:[0,1]
	v_add_f32_dpp v196, v196, v197 quad_perm:[1,0,3,2] row_mask:0xf bank_mask:0xf bound_ctrl:1
	v_xor_b32_e32 v197, v181, v28
	v_add_f32_dpp v194, v194, v199 quad_perm:[2,3,0,1] row_mask:0xf bank_mask:0xf bound_ctrl:1
	v_xor_b32_e32 v199, v189, v195
	v_add_f32_dpp v28, v28, v197 quad_perm:[1,0,3,2] row_mask:0xf bank_mask:0xf bound_ctrl:1
	v_xor_b32_e32 v197, v181, v202
	v_add_f32_dpp v195, v195, v199 quad_perm:[2,3,0,1] row_mask:0xf bank_mask:0xf bound_ctrl:1
	v_xor_b32_e32 v199, v189, v196
	v_add_f32_dpp v197, v202, v197 quad_perm:[1,0,3,2] row_mask:0xf bank_mask:0xf bound_ctrl:1
	v_xor_b32_e32 v198, v181, v26
	v_add_f32_dpp v196, v196, v199 quad_perm:[2,3,0,1] row_mask:0xf bank_mask:0xf bound_ctrl:1
	v_xor_b32_e32 v199, v189, v28
	v_add_f32_dpp v26, v26, v198 quad_perm:[1,0,3,2] row_mask:0xf bank_mask:0xf bound_ctrl:1
	v_xor_b32_e32 v198, v181, v20
	v_add_f32_dpp v28, v28, v199 quad_perm:[2,3,0,1] row_mask:0xf bank_mask:0xf bound_ctrl:1
	v_xor_b32_e32 v199, v189, v197
	v_pk_add_f32 v[206:207], v[206:207], v[206:207] op_sel:[0,1] op_sel_hi:[1,0] neg_lo:[0,1] neg_hi:[0,1]
	v_add_f32_dpp v20, v20, v198 quad_perm:[1,0,3,2] row_mask:0xf bank_mask:0xf bound_ctrl:1
	v_xor_b32_e32 v198, v181, v18
	v_add_f32_dpp v197, v197, v199 quad_perm:[2,3,0,1] row_mask:0xf bank_mask:0xf bound_ctrl:1
	v_xor_b32_e32 v199, v189, v26
	v_add_f32_dpp v18, v18, v198 quad_perm:[1,0,3,2] row_mask:0xf bank_mask:0xf bound_ctrl:1
	v_xor_b32_e32 v198, v181, v206
	v_add_f32_dpp v199, v26, v199 quad_perm:[2,3,0,1] row_mask:0xf bank_mask:0xf bound_ctrl:1
	v_xor_b32_e32 v26, v189, v20
	v_add_f32_dpp v198, v206, v198 quad_perm:[1,0,3,2] row_mask:0xf bank_mask:0xf bound_ctrl:1
	s_nop 0
	v_add_f32_dpp v200, v20, v26 quad_perm:[2,3,0,1] row_mask:0xf bank_mask:0xf bound_ctrl:1
	v_xor_b32_e32 v20, v189, v18
	v_max_f32_e64 v26, |v194|, |v195|
	s_nop 0
	v_add_f32_dpp v201, v18, v20 quad_perm:[2,3,0,1] row_mask:0xf bank_mask:0xf bound_ctrl:1
	v_xor_b32_e32 v18, v189, v198
	v_max_f32_e64 v20, |v27|, |v29|
	s_nop 0
	v_add_f32_dpp v198, v198, v18 quad_perm:[2,3,0,1] row_mask:0xf bank_mask:0xf bound_ctrl:1
	v_xor_b32_e32 v18, v189, v186
	s_nop 1
	v_add_f32_dpp v186, v186, v18 quad_perm:[2,3,0,1] row_mask:0xf bank_mask:0xf bound_ctrl:1
	v_max_f32_e64 v18, |v19|, |v21|
	v_max3_f32 v18, v216, v18, v20
	v_max_f32_e64 v20, |v187|, |v193|
	v_max3_f32 v18, v18, v20, v26
	v_max_f32_e64 v20, |v196|, |v28|
	v_max_f32_e64 v26, |v197|, |v199|
	v_max3_f32 v18, v18, v20, v26
	v_max_f32_e64 v20, |v200|, |v201|
	v_max_f32_e64 v26, |v198|, |v186|
	v_max3_f32 v216, v18, v20, v26
	v_cvt_pk_bf16_f32 v18, v19, v21
	v_cvt_pk_bf16_f32 v19, v27, v29
	v_cvt_pk_bf16_f32 v20, v187, v193
	v_cvt_pk_bf16_f32 v21, v194, v195
	v_cvt_pk_bf16_f32 v26, v196, v28
	v_cvt_pk_bf16_f32 v27, v197, v199
	v_cvt_pk_bf16_f32 v28, v200, v201
	v_cvt_pk_bf16_f32 v29, v198, v186
	v_and_b32_e32 v187, 0xffff0000, v37
	v_and_b32_e32 v186, 0xffff0000, v33
	v_lshlrev_b32_e32 v195, 16, v34
	v_lshlrev_b32_e32 v194, 16, v30
	v_and_b32_e32 v197, 0xffff0000, v34
	v_and_b32_e32 v196, 0xffff0000, v30
	v_lshlrev_b32_e32 v199, 16, v35
	v_lshlrev_b32_e32 v198, 16, v31
	v_and_b32_e32 v35, 0xffff0000, v35
	v_and_b32_e32 v34, 0xffff0000, v31
	v_lshlrev_b32_e32 v31, 16, v36
	v_lshlrev_b32_e32 v30, 16, v32
	v_and_b32_e32 v201, 0xffff0000, v36
	v_and_b32_e32 v200, 0xffff0000, v32
	v_lshlrev_b32_e32 v37, 16, v37
	v_lshlrev_b32_e32 v36, 16, v33
	v_pk_add_f32 v[32:33], v[194:195], v[196:197]
	v_pk_add_f32 v[202:203], v[198:199], v[34:35]
	v_pk_add_f32 v[204:205], v[30:31], v[200:201]
	v_pk_add_f32 v[206:207], v[36:37], v[186:187]
	v_pk_add_f32 v[194:195], v[194:195], v[196:197] neg_lo:[0,1] neg_hi:[0,1]
	v_pk_add_f32 v[34:35], v[198:199], v[34:35] neg_lo:[0,1] neg_hi:[0,1]
	v_pk_add_f32 v[30:31], v[30:31], v[200:201] neg_lo:[0,1] neg_hi:[0,1]
	v_pk_add_f32 v[36:37], v[36:37], v[186:187] neg_lo:[0,1] neg_hi:[0,1]
	v_pk_add_f32 v[208:209], v[32:33], v[202:203] neg_lo:[0,1] neg_hi:[0,1]
	v_pk_add_f32 v[32:33], v[32:33], v[202:203]
	v_pk_add_f32 v[202:203], v[204:205], v[206:207]
	v_pk_add_f32 v[186:187], v[194:195], v[34:35] neg_lo:[0,1] neg_hi:[0,1]
	v_pk_add_f32 v[196:197], v[30:31], v[36:37] neg_lo:[0,1] neg_hi:[0,1]
	v_pk_add_f32 v[34:35], v[194:195], v[34:35]
	v_pk_add_f32 v[30:31], v[30:31], v[36:37]
	v_pk_add_f32 v[210:211], v[204:205], v[206:207] neg_lo:[0,1] neg_hi:[0,1]
	v_pk_add_f32 v[204:205], v[32:33], v[202:203]
	v_pk_add_f32 v[36:37], v[34:35], v[30:31]
	v_pk_add_f32 v[30:31], v[34:35], v[30:31] neg_lo:[0,1] neg_hi:[0,1]
	v_pk_add_f32 v[32:33], v[32:33], v[202:203] neg_lo:[0,1] neg_hi:[0,1]
	v_pk_add_f32 v[202:203], v[208:209], v[210:211]
	v_pk_add_f32 v[206:207], v[208:209], v[210:211] neg_lo:[0,1] neg_hi:[0,1]
	v_pk_add_f32 v[34:35], v[186:187], v[196:197]
	v_pk_add_f32 v[186:187], v[186:187], v[196:197] neg_lo:[0,1] neg_hi:[0,1]
	v_pk_add_f32 v[194:195], v[204:205], v[204:205] op_sel:[0,1] op_sel_hi:[1,0]
	v_pk_add_f32 v[210:211], v[30:31], v[30:31] op_sel:[0,1] op_sel_hi:[1,0]
	v_pk_add_f32 v[30:31], v[30:31], v[30:31] op_sel:[0,1] op_sel_hi:[1,0] neg_lo:[0,1] neg_hi:[0,1]
	v_pk_add_f32 v[198:199], v[36:37], v[36:37] op_sel:[0,1] op_sel_hi:[1,0]
	v_pk_add_f32 v[208:209], v[32:33], v[32:33] op_sel:[0,1] op_sel_hi:[1,0]
	v_pk_add_f32 v[32:33], v[32:33], v[32:33] op_sel:[0,1] op_sel_hi:[1,0] neg_lo:[0,1] neg_hi:[0,1]
	v_pk_add_f32 v[214:215], v[186:187], v[186:187] op_sel:[0,1] op_sel_hi:[1,0]
	v_pk_add_f32 v[186:187], v[186:187], v[186:187] op_sel:[0,1] op_sel_hi:[1,0] neg_lo:[0,1] neg_hi:[0,1]
	v_xor_b32_e32 v31, v181, v194
	v_pk_add_f32 v[196:197], v[204:205], v[204:205] op_sel:[0,1] op_sel_hi:[1,0] neg_lo:[0,1] neg_hi:[0,1]
	v_pk_add_f32 v[200:201], v[202:203], v[202:203] op_sel:[0,1] op_sel_hi:[1,0]
	v_pk_add_f32 v[204:205], v[34:35], v[34:35] op_sel:[0,1] op_sel_hi:[1,0]
	v_pk_add_f32 v[34:35], v[34:35], v[34:35] op_sel:[0,1] op_sel_hi:[1,0] neg_lo:[0,1] neg_hi:[0,1]
	v_add_f32_dpp v31, v194, v31 quad_perm:[1,0,3,2] row_mask:0xf bank_mask:0xf bound_ctrl:1
	v_xor_b32_e32 v33, v181, v198
	v_xor_b32_e32 v199, v181, v186
	v_pk_add_f32 v[36:37], v[36:37], v[36:37] op_sel:[0,1] op_sel_hi:[1,0] neg_lo:[0,1] neg_hi:[0,1]
	v_add_f32_dpp v33, v198, v33 quad_perm:[1,0,3,2] row_mask:0xf bank_mask:0xf bound_ctrl:1
	v_xor_b32_e32 v35, v181, v200
	v_add_f32_dpp v186, v186, v199 quad_perm:[1,0,3,2] row_mask:0xf bank_mask:0xf bound_ctrl:1
	v_xor_b32_e32 v199, v189, v31
	v_add_f32_dpp v35, v200, v35 quad_perm:[1,0,3,2] row_mask:0xf bank_mask:0xf bound_ctrl:1
	v_xor_b32_e32 v37, v181, v204
	v_add_f32_dpp v31, v31, v199 quad_perm:[2,3,0,1] row_mask:0xf bank_mask:0xf bound_ctrl:1
	v_xor_b32_e32 v199, v189, v33
	v_add_f32_dpp v37, v204, v37 quad_perm:[1,0,3,2] row_mask:0xf bank_mask:0xf bound_ctrl:1
	v_xor_b32_e32 v187, v181, v208
	v_add_f32_dpp v33, v33, v199 quad_perm:[2,3,0,1] row_mask:0xf bank_mask:0xf bound_ctrl:1
	v_xor_b32_e32 v199, v189, v35
	v_pk_add_f32 v[212:213], v[206:207], v[206:207] op_sel:[0,1] op_sel_hi:[1,0]
	v_add_f32_dpp v187, v208, v187 quad_perm:[1,0,3,2] row_mask:0xf bank_mask:0xf bound_ctrl:1
	v_xor_b32_e32 v193, v181, v210
	v_add_f32_dpp v35, v35, v199 quad_perm:[2,3,0,1] row_mask:0xf bank_mask:0xf bound_ctrl:1
	v_xor_b32_e32 v199, v189, v37
	v_add_f32_dpp v193, v210, v193 quad_perm:[1,0,3,2] row_mask:0xf bank_mask:0xf bound_ctrl:1
	v_xor_b32_e32 v194, v181, v212
	v_add_f32_dpp v37, v37, v199 quad_perm:[2,3,0,1] row_mask:0xf bank_mask:0xf bound_ctrl:1
	v_xor_b32_e32 v199, v189, v187
	v_add_f32_dpp v194, v212, v194 quad_perm:[1,0,3,2] row_mask:0xf bank_mask:0xf bound_ctrl:1
	v_xor_b32_e32 v195, v181, v214
	v_add_f32_dpp v187, v187, v199 quad_perm:[2,3,0,1] row_mask:0xf bank_mask:0xf bound_ctrl:1
	v_xor_b32_e32 v199, v189, v193
	v_add_f32_dpp v195, v214, v195 quad_perm:[1,0,3,2] row_mask:0xf bank_mask:0xf bound_ctrl:1
	v_xor_b32_e32 v197, v181, v196
	v_add_f32_dpp v193, v193, v199 quad_perm:[2,3,0,1] row_mask:0xf bank_mask:0xf bound_ctrl:1
	v_xor_b32_e32 v199, v189, v194
	v_pk_add_f32 v[202:203], v[202:203], v[202:203] op_sel:[0,1] op_sel_hi:[1,0] neg_lo:[0,1] neg_hi:[0,1]
	v_add_f32_dpp v196, v196, v197 quad_perm:[1,0,3,2] row_mask:0xf bank_mask:0xf bound_ctrl:1
	v_xor_b32_e32 v197, v181, v36
	v_add_f32_dpp v194, v194, v199 quad_perm:[2,3,0,1] row_mask:0xf bank_mask:0xf bound_ctrl:1
	v_xor_b32_e32 v199, v189, v195
	v_add_f32_dpp v36, v36, v197 quad_perm:[1,0,3,2] row_mask:0xf bank_mask:0xf bound_ctrl:1
	v_xor_b32_e32 v197, v181, v202
	v_add_f32_dpp v195, v195, v199 quad_perm:[2,3,0,1] row_mask:0xf bank_mask:0xf bound_ctrl:1
	v_xor_b32_e32 v199, v189, v196
	v_add_f32_dpp v197, v202, v197 quad_perm:[1,0,3,2] row_mask:0xf bank_mask:0xf bound_ctrl:1
	v_xor_b32_e32 v198, v181, v34
	v_add_f32_dpp v196, v196, v199 quad_perm:[2,3,0,1] row_mask:0xf bank_mask:0xf bound_ctrl:1
	v_xor_b32_e32 v199, v189, v36
	v_add_f32_dpp v34, v34, v198 quad_perm:[1,0,3,2] row_mask:0xf bank_mask:0xf bound_ctrl:1
	v_xor_b32_e32 v198, v181, v32
	v_add_f32_dpp v36, v36, v199 quad_perm:[2,3,0,1] row_mask:0xf bank_mask:0xf bound_ctrl:1
	v_xor_b32_e32 v199, v189, v197
	v_pk_add_f32 v[206:207], v[206:207], v[206:207] op_sel:[0,1] op_sel_hi:[1,0] neg_lo:[0,1] neg_hi:[0,1]
	v_add_f32_dpp v32, v32, v198 quad_perm:[1,0,3,2] row_mask:0xf bank_mask:0xf bound_ctrl:1
	v_xor_b32_e32 v198, v181, v30
	v_add_f32_dpp v197, v197, v199 quad_perm:[2,3,0,1] row_mask:0xf bank_mask:0xf bound_ctrl:1
	v_xor_b32_e32 v199, v189, v34
	v_add_f32_dpp v30, v30, v198 quad_perm:[1,0,3,2] row_mask:0xf bank_mask:0xf bound_ctrl:1
	v_xor_b32_e32 v198, v181, v206
	v_add_f32_dpp v199, v34, v199 quad_perm:[2,3,0,1] row_mask:0xf bank_mask:0xf bound_ctrl:1
	v_xor_b32_e32 v34, v189, v32
	v_add_f32_dpp v198, v206, v198 quad_perm:[1,0,3,2] row_mask:0xf bank_mask:0xf bound_ctrl:1
	s_nop 0
	v_add_f32_dpp v200, v32, v34 quad_perm:[2,3,0,1] row_mask:0xf bank_mask:0xf bound_ctrl:1
	v_xor_b32_e32 v32, v189, v30
	v_max_f32_e64 v34, |v194|, |v195|
	s_nop 0
	v_add_f32_dpp v201, v30, v32 quad_perm:[2,3,0,1] row_mask:0xf bank_mask:0xf bound_ctrl:1
	v_xor_b32_e32 v30, v189, v198
	v_max_f32_e64 v32, |v35|, |v37|
	s_nop 0
	v_add_f32_dpp v198, v198, v30 quad_perm:[2,3,0,1] row_mask:0xf bank_mask:0xf bound_ctrl:1
	v_xor_b32_e32 v30, v189, v186
	s_nop 1
	v_add_f32_dpp v186, v186, v30 quad_perm:[2,3,0,1] row_mask:0xf bank_mask:0xf bound_ctrl:1
	v_max_f32_e64 v30, |v31|, |v33|
	v_max3_f32 v30, v216, v30, v32
	v_max_f32_e64 v32, |v187|, |v193|
	v_max3_f32 v30, v30, v32, v34
	v_max_f32_e64 v32, |v196|, |v36|
	v_max_f32_e64 v34, |v197|, |v199|
	v_max3_f32 v30, v30, v32, v34
	v_max_f32_e64 v32, |v200|, |v201|
	v_max_f32_e64 v34, |v198|, |v186|
	v_max3_f32 v216, v30, v32, v34
	v_cvt_pk_bf16_f32 v30, v31, v33
	v_cvt_pk_bf16_f32 v31, v35, v37
	v_cvt_pk_bf16_f32 v32, v187, v193
	v_cvt_pk_bf16_f32 v33, v194, v195
	v_cvt_pk_bf16_f32 v34, v196, v36
	v_cvt_pk_bf16_f32 v35, v197, v199
	v_cvt_pk_bf16_f32 v36, v200, v201
	v_cvt_pk_bf16_f32 v37, v198, v186
	v_and_b32_e32 v187, 0xffff0000, v49
	v_and_b32_e32 v186, 0xffff0000, v41
	v_lshlrev_b32_e32 v195, 16, v46
	v_lshlrev_b32_e32 v194, 16, v38
	v_and_b32_e32 v197, 0xffff0000, v46
	v_and_b32_e32 v196, 0xffff0000, v38
	v_lshlrev_b32_e32 v199, 16, v47
	v_lshlrev_b32_e32 v198, 16, v39
	v_and_b32_e32 v47, 0xffff0000, v47
	v_and_b32_e32 v46, 0xffff0000, v39
	v_lshlrev_b32_e32 v39, 16, v48
	v_lshlrev_b32_e32 v38, 16, v40
	v_and_b32_e32 v201, 0xffff0000, v48
	v_and_b32_e32 v200, 0xffff0000, v40
	v_lshlrev_b32_e32 v49, 16, v49
	v_lshlrev_b32_e32 v48, 16, v41
	v_pk_add_f32 v[40:41], v[194:195], v[196:197]
	v_pk_add_f32 v[202:203], v[198:199], v[46:47]
	v_pk_add_f32 v[204:205], v[38:39], v[200:201]
	v_pk_add_f32 v[206:207], v[48:49], v[186:187]
	v_pk_add_f32 v[194:195], v[194:195], v[196:197] neg_lo:[0,1] neg_hi:[0,1]
	v_pk_add_f32 v[46:47], v[198:199], v[46:47] neg_lo:[0,1] neg_hi:[0,1]
	v_pk_add_f32 v[38:39], v[38:39], v[200:201] neg_lo:[0,1] neg_hi:[0,1]
	v_pk_add_f32 v[48:49], v[48:49], v[186:187] neg_lo:[0,1] neg_hi:[0,1]
	v_pk_add_f32 v[208:209], v[40:41], v[202:203] neg_lo:[0,1] neg_hi:[0,1]
	v_pk_add_f32 v[40:41], v[40:41], v[202:203]
	v_pk_add_f32 v[202:203], v[204:205], v[206:207]
	v_pk_add_f32 v[186:187], v[194:195], v[46:47] neg_lo:[0,1] neg_hi:[0,1]
	v_pk_add_f32 v[196:197], v[38:39], v[48:49] neg_lo:[0,1] neg_hi:[0,1]
	v_pk_add_f32 v[46:47], v[194:195], v[46:47]
	v_pk_add_f32 v[38:39], v[38:39], v[48:49]
	v_pk_add_f32 v[210:211], v[204:205], v[206:207] neg_lo:[0,1] neg_hi:[0,1]
	v_pk_add_f32 v[204:205], v[40:41], v[202:203]
	v_pk_add_f32 v[48:49], v[46:47], v[38:39]
	v_pk_add_f32 v[38:39], v[46:47], v[38:39] neg_lo:[0,1] neg_hi:[0,1]
	v_pk_add_f32 v[40:41], v[40:41], v[202:203] neg_lo:[0,1] neg_hi:[0,1]
	v_pk_add_f32 v[202:203], v[208:209], v[210:211]
	v_pk_add_f32 v[206:207], v[208:209], v[210:211] neg_lo:[0,1] neg_hi:[0,1]
	v_pk_add_f32 v[46:47], v[186:187], v[196:197]
	v_pk_add_f32 v[186:187], v[186:187], v[196:197] neg_lo:[0,1] neg_hi:[0,1]
	v_pk_add_f32 v[194:195], v[204:205], v[204:205] op_sel:[0,1] op_sel_hi:[1,0]
	v_pk_add_f32 v[210:211], v[38:39], v[38:39] op_sel:[0,1] op_sel_hi:[1,0]
	v_pk_add_f32 v[38:39], v[38:39], v[38:39] op_sel:[0,1] op_sel_hi:[1,0] neg_lo:[0,1] neg_hi:[0,1]
	v_pk_add_f32 v[198:199], v[48:49], v[48:49] op_sel:[0,1] op_sel_hi:[1,0]
	v_pk_add_f32 v[208:209], v[40:41], v[40:41] op_sel:[0,1] op_sel_hi:[1,0]
	v_pk_add_f32 v[40:41], v[40:41], v[40:41] op_sel:[0,1] op_sel_hi:[1,0] neg_lo:[0,1] neg_hi:[0,1]
	v_pk_add_f32 v[214:215], v[186:187], v[186:187] op_sel:[0,1] op_sel_hi:[1,0]
	v_pk_add_f32 v[186:187], v[186:187], v[186:187] op_sel:[0,1] op_sel_hi:[1,0] neg_lo:[0,1] neg_hi:[0,1]
	v_xor_b32_e32 v39, v181, v194
	v_pk_add_f32 v[196:197], v[204:205], v[204:205] op_sel:[0,1] op_sel_hi:[1,0] neg_lo:[0,1] neg_hi:[0,1]
	v_pk_add_f32 v[200:201], v[202:203], v[202:203] op_sel:[0,1] op_sel_hi:[1,0]
	v_pk_add_f32 v[204:205], v[46:47], v[46:47] op_sel:[0,1] op_sel_hi:[1,0]
	v_pk_add_f32 v[46:47], v[46:47], v[46:47] op_sel:[0,1] op_sel_hi:[1,0] neg_lo:[0,1] neg_hi:[0,1]
	v_add_f32_dpp v39, v194, v39 quad_perm:[1,0,3,2] row_mask:0xf bank_mask:0xf bound_ctrl:1
	v_xor_b32_e32 v41, v181, v198
	v_xor_b32_e32 v199, v181, v186
	v_pk_add_f32 v[48:49], v[48:49], v[48:49] op_sel:[0,1] op_sel_hi:[1,0] neg_lo:[0,1] neg_hi:[0,1]
	v_add_f32_dpp v41, v198, v41 quad_perm:[1,0,3,2] row_mask:0xf bank_mask:0xf bound_ctrl:1
	v_xor_b32_e32 v47, v181, v200
	v_add_f32_dpp v186, v186, v199 quad_perm:[1,0,3,2] row_mask:0xf bank_mask:0xf bound_ctrl:1
	v_xor_b32_e32 v199, v189, v39
	v_add_f32_dpp v47, v200, v47 quad_perm:[1,0,3,2] row_mask:0xf bank_mask:0xf bound_ctrl:1
	v_xor_b32_e32 v49, v181, v204
	v_add_f32_dpp v39, v39, v199 quad_perm:[2,3,0,1] row_mask:0xf bank_mask:0xf bound_ctrl:1
	v_xor_b32_e32 v199, v189, v41
	v_add_f32_dpp v49, v204, v49 quad_perm:[1,0,3,2] row_mask:0xf bank_mask:0xf bound_ctrl:1
	v_xor_b32_e32 v187, v181, v208
	v_add_f32_dpp v41, v41, v199 quad_perm:[2,3,0,1] row_mask:0xf bank_mask:0xf bound_ctrl:1
	v_xor_b32_e32 v199, v189, v47
	v_pk_add_f32 v[212:213], v[206:207], v[206:207] op_sel:[0,1] op_sel_hi:[1,0]
	v_add_f32_dpp v187, v208, v187 quad_perm:[1,0,3,2] row_mask:0xf bank_mask:0xf bound_ctrl:1
	v_xor_b32_e32 v193, v181, v210
	v_add_f32_dpp v47, v47, v199 quad_perm:[2,3,0,1] row_mask:0xf bank_mask:0xf bound_ctrl:1
	v_xor_b32_e32 v199, v189, v49
	v_add_f32_dpp v193, v210, v193 quad_perm:[1,0,3,2] row_mask:0xf bank_mask:0xf bound_ctrl:1
	v_xor_b32_e32 v194, v181, v212
	v_add_f32_dpp v49, v49, v199 quad_perm:[2,3,0,1] row_mask:0xf bank_mask:0xf bound_ctrl:1
	v_xor_b32_e32 v199, v189, v187
	v_add_f32_dpp v194, v212, v194 quad_perm:[1,0,3,2] row_mask:0xf bank_mask:0xf bound_ctrl:1
	v_xor_b32_e32 v195, v181, v214
	v_add_f32_dpp v187, v187, v199 quad_perm:[2,3,0,1] row_mask:0xf bank_mask:0xf bound_ctrl:1
	v_xor_b32_e32 v199, v189, v193
	v_add_f32_dpp v195, v214, v195 quad_perm:[1,0,3,2] row_mask:0xf bank_mask:0xf bound_ctrl:1
	v_xor_b32_e32 v197, v181, v196
	v_add_f32_dpp v193, v193, v199 quad_perm:[2,3,0,1] row_mask:0xf bank_mask:0xf bound_ctrl:1
	v_xor_b32_e32 v199, v189, v194
	v_pk_add_f32 v[202:203], v[202:203], v[202:203] op_sel:[0,1] op_sel_hi:[1,0] neg_lo:[0,1] neg_hi:[0,1]
	v_add_f32_dpp v196, v196, v197 quad_perm:[1,0,3,2] row_mask:0xf bank_mask:0xf bound_ctrl:1
	v_xor_b32_e32 v197, v181, v48
	v_add_f32_dpp v194, v194, v199 quad_perm:[2,3,0,1] row_mask:0xf bank_mask:0xf bound_ctrl:1
	v_xor_b32_e32 v199, v189, v195
	v_add_f32_dpp v48, v48, v197 quad_perm:[1,0,3,2] row_mask:0xf bank_mask:0xf bound_ctrl:1
	v_xor_b32_e32 v197, v181, v202
	v_add_f32_dpp v195, v195, v199 quad_perm:[2,3,0,1] row_mask:0xf bank_mask:0xf bound_ctrl:1
	v_xor_b32_e32 v199, v189, v196
	v_add_f32_dpp v197, v202, v197 quad_perm:[1,0,3,2] row_mask:0xf bank_mask:0xf bound_ctrl:1
	v_xor_b32_e32 v198, v181, v46
	v_add_f32_dpp v196, v196, v199 quad_perm:[2,3,0,1] row_mask:0xf bank_mask:0xf bound_ctrl:1
	v_xor_b32_e32 v199, v189, v48
	v_add_f32_dpp v46, v46, v198 quad_perm:[1,0,3,2] row_mask:0xf bank_mask:0xf bound_ctrl:1
	v_xor_b32_e32 v198, v181, v40
	v_add_f32_dpp v48, v48, v199 quad_perm:[2,3,0,1] row_mask:0xf bank_mask:0xf bound_ctrl:1
	v_xor_b32_e32 v199, v189, v197
	v_pk_add_f32 v[206:207], v[206:207], v[206:207] op_sel:[0,1] op_sel_hi:[1,0] neg_lo:[0,1] neg_hi:[0,1]
	v_add_f32_dpp v40, v40, v198 quad_perm:[1,0,3,2] row_mask:0xf bank_mask:0xf bound_ctrl:1
	v_xor_b32_e32 v198, v181, v38
	v_add_f32_dpp v197, v197, v199 quad_perm:[2,3,0,1] row_mask:0xf bank_mask:0xf bound_ctrl:1
	v_xor_b32_e32 v199, v189, v46
	v_add_f32_dpp v38, v38, v198 quad_perm:[1,0,3,2] row_mask:0xf bank_mask:0xf bound_ctrl:1
	v_xor_b32_e32 v198, v181, v206
	v_add_f32_dpp v199, v46, v199 quad_perm:[2,3,0,1] row_mask:0xf bank_mask:0xf bound_ctrl:1
	v_xor_b32_e32 v46, v189, v40
	v_add_f32_dpp v198, v206, v198 quad_perm:[1,0,3,2] row_mask:0xf bank_mask:0xf bound_ctrl:1
	s_nop 0
	v_add_f32_dpp v200, v40, v46 quad_perm:[2,3,0,1] row_mask:0xf bank_mask:0xf bound_ctrl:1
	v_xor_b32_e32 v40, v189, v38
	v_max_f32_e64 v46, |v194|, |v195|
	s_nop 0
	v_add_f32_dpp v201, v38, v40 quad_perm:[2,3,0,1] row_mask:0xf bank_mask:0xf bound_ctrl:1
	v_xor_b32_e32 v38, v189, v198
	v_max_f32_e64 v40, |v47|, |v49|
	s_nop 0
	v_add_f32_dpp v198, v198, v38 quad_perm:[2,3,0,1] row_mask:0xf bank_mask:0xf bound_ctrl:1
	v_xor_b32_e32 v38, v189, v186
	s_nop 1
	v_add_f32_dpp v186, v186, v38 quad_perm:[2,3,0,1] row_mask:0xf bank_mask:0xf bound_ctrl:1
	v_max_f32_e64 v38, |v39|, |v41|
	v_max3_f32 v38, v216, v38, v40
	v_max_f32_e64 v40, |v187|, |v193|
	v_max3_f32 v38, v38, v40, v46
	v_max_f32_e64 v40, |v196|, |v48|
	v_max_f32_e64 v46, |v197|, |v199|
	v_max3_f32 v38, v38, v40, v46
	v_max_f32_e64 v40, |v200|, |v201|
	v_max_f32_e64 v46, |v198|, |v186|
	v_max3_f32 v216, v38, v40, v46
	v_cvt_pk_bf16_f32 v38, v39, v41
	v_cvt_pk_bf16_f32 v39, v47, v49
	v_cvt_pk_bf16_f32 v40, v187, v193
	v_cvt_pk_bf16_f32 v41, v194, v195
	v_cvt_pk_bf16_f32 v46, v196, v48
	v_cvt_pk_bf16_f32 v47, v197, v199
	v_cvt_pk_bf16_f32 v48, v200, v201
	v_cvt_pk_bf16_f32 v49, v198, v186
	v_and_b32_e32 v187, 0xffff0000, v57
	v_and_b32_e32 v186, 0xffff0000, v53
	v_lshlrev_b32_e32 v195, 16, v54
	v_lshlrev_b32_e32 v194, 16, v50
	v_and_b32_e32 v197, 0xffff0000, v54
	v_and_b32_e32 v196, 0xffff0000, v50
	v_lshlrev_b32_e32 v199, 16, v55
	v_lshlrev_b32_e32 v198, 16, v51
	v_and_b32_e32 v55, 0xffff0000, v55
	v_and_b32_e32 v54, 0xffff0000, v51
	v_lshlrev_b32_e32 v51, 16, v56
	v_lshlrev_b32_e32 v50, 16, v52
	v_and_b32_e32 v201, 0xffff0000, v56
	v_and_b32_e32 v200, 0xffff0000, v52
	v_lshlrev_b32_e32 v57, 16, v57
	v_lshlrev_b32_e32 v56, 16, v53
	v_pk_add_f32 v[52:53], v[194:195], v[196:197]
	v_pk_add_f32 v[202:203], v[198:199], v[54:55]
	v_pk_add_f32 v[204:205], v[50:51], v[200:201]
	v_pk_add_f32 v[206:207], v[56:57], v[186:187]
	v_pk_add_f32 v[194:195], v[194:195], v[196:197] neg_lo:[0,1] neg_hi:[0,1]
	v_pk_add_f32 v[54:55], v[198:199], v[54:55] neg_lo:[0,1] neg_hi:[0,1]
	v_pk_add_f32 v[50:51], v[50:51], v[200:201] neg_lo:[0,1] neg_hi:[0,1]
	v_pk_add_f32 v[56:57], v[56:57], v[186:187] neg_lo:[0,1] neg_hi:[0,1]
	v_pk_add_f32 v[208:209], v[52:53], v[202:203] neg_lo:[0,1] neg_hi:[0,1]
	v_pk_add_f32 v[52:53], v[52:53], v[202:203]
	v_pk_add_f32 v[202:203], v[204:205], v[206:207]
	v_pk_add_f32 v[186:187], v[194:195], v[54:55] neg_lo:[0,1] neg_hi:[0,1]
	v_pk_add_f32 v[196:197], v[50:51], v[56:57] neg_lo:[0,1] neg_hi:[0,1]
	v_pk_add_f32 v[54:55], v[194:195], v[54:55]
	v_pk_add_f32 v[50:51], v[50:51], v[56:57]
	v_pk_add_f32 v[210:211], v[204:205], v[206:207] neg_lo:[0,1] neg_hi:[0,1]
	v_pk_add_f32 v[204:205], v[52:53], v[202:203]
	v_pk_add_f32 v[56:57], v[54:55], v[50:51]
	v_pk_add_f32 v[50:51], v[54:55], v[50:51] neg_lo:[0,1] neg_hi:[0,1]
	v_pk_add_f32 v[52:53], v[52:53], v[202:203] neg_lo:[0,1] neg_hi:[0,1]
	v_pk_add_f32 v[202:203], v[208:209], v[210:211]
	v_pk_add_f32 v[206:207], v[208:209], v[210:211] neg_lo:[0,1] neg_hi:[0,1]
	v_pk_add_f32 v[54:55], v[186:187], v[196:197]
	v_pk_add_f32 v[186:187], v[186:187], v[196:197] neg_lo:[0,1] neg_hi:[0,1]
	v_pk_add_f32 v[194:195], v[204:205], v[204:205] op_sel:[0,1] op_sel_hi:[1,0]
	v_pk_add_f32 v[210:211], v[50:51], v[50:51] op_sel:[0,1] op_sel_hi:[1,0]
	v_pk_add_f32 v[50:51], v[50:51], v[50:51] op_sel:[0,1] op_sel_hi:[1,0] neg_lo:[0,1] neg_hi:[0,1]
	v_pk_add_f32 v[198:199], v[56:57], v[56:57] op_sel:[0,1] op_sel_hi:[1,0]
	v_pk_add_f32 v[208:209], v[52:53], v[52:53] op_sel:[0,1] op_sel_hi:[1,0]
	v_pk_add_f32 v[52:53], v[52:53], v[52:53] op_sel:[0,1] op_sel_hi:[1,0] neg_lo:[0,1] neg_hi:[0,1]
	v_pk_add_f32 v[214:215], v[186:187], v[186:187] op_sel:[0,1] op_sel_hi:[1,0]
	v_pk_add_f32 v[186:187], v[186:187], v[186:187] op_sel:[0,1] op_sel_hi:[1,0] neg_lo:[0,1] neg_hi:[0,1]
	v_xor_b32_e32 v51, v181, v194
	v_pk_add_f32 v[196:197], v[204:205], v[204:205] op_sel:[0,1] op_sel_hi:[1,0] neg_lo:[0,1] neg_hi:[0,1]
	v_pk_add_f32 v[200:201], v[202:203], v[202:203] op_sel:[0,1] op_sel_hi:[1,0]
	v_pk_add_f32 v[204:205], v[54:55], v[54:55] op_sel:[0,1] op_sel_hi:[1,0]
	v_pk_add_f32 v[54:55], v[54:55], v[54:55] op_sel:[0,1] op_sel_hi:[1,0] neg_lo:[0,1] neg_hi:[0,1]
	v_add_f32_dpp v51, v194, v51 quad_perm:[1,0,3,2] row_mask:0xf bank_mask:0xf bound_ctrl:1
	v_xor_b32_e32 v53, v181, v198
	v_xor_b32_e32 v199, v181, v186
	v_pk_add_f32 v[56:57], v[56:57], v[56:57] op_sel:[0,1] op_sel_hi:[1,0] neg_lo:[0,1] neg_hi:[0,1]
	v_add_f32_dpp v53, v198, v53 quad_perm:[1,0,3,2] row_mask:0xf bank_mask:0xf bound_ctrl:1
	v_xor_b32_e32 v55, v181, v200
	v_add_f32_dpp v186, v186, v199 quad_perm:[1,0,3,2] row_mask:0xf bank_mask:0xf bound_ctrl:1
	v_xor_b32_e32 v199, v189, v51
	v_add_f32_dpp v55, v200, v55 quad_perm:[1,0,3,2] row_mask:0xf bank_mask:0xf bound_ctrl:1
	v_xor_b32_e32 v57, v181, v204
	v_add_f32_dpp v51, v51, v199 quad_perm:[2,3,0,1] row_mask:0xf bank_mask:0xf bound_ctrl:1
	v_xor_b32_e32 v199, v189, v53
	v_add_f32_dpp v57, v204, v57 quad_perm:[1,0,3,2] row_mask:0xf bank_mask:0xf bound_ctrl:1
	v_xor_b32_e32 v187, v181, v208
	v_add_f32_dpp v53, v53, v199 quad_perm:[2,3,0,1] row_mask:0xf bank_mask:0xf bound_ctrl:1
	v_xor_b32_e32 v199, v189, v55
	v_pk_add_f32 v[212:213], v[206:207], v[206:207] op_sel:[0,1] op_sel_hi:[1,0]
	v_add_f32_dpp v187, v208, v187 quad_perm:[1,0,3,2] row_mask:0xf bank_mask:0xf bound_ctrl:1
	v_xor_b32_e32 v193, v181, v210
	v_add_f32_dpp v55, v55, v199 quad_perm:[2,3,0,1] row_mask:0xf bank_mask:0xf bound_ctrl:1
	v_xor_b32_e32 v199, v189, v57
	v_add_f32_dpp v193, v210, v193 quad_perm:[1,0,3,2] row_mask:0xf bank_mask:0xf bound_ctrl:1
	v_xor_b32_e32 v194, v181, v212
	v_add_f32_dpp v57, v57, v199 quad_perm:[2,3,0,1] row_mask:0xf bank_mask:0xf bound_ctrl:1
	v_xor_b32_e32 v199, v189, v187
	v_add_f32_dpp v194, v212, v194 quad_perm:[1,0,3,2] row_mask:0xf bank_mask:0xf bound_ctrl:1
	v_xor_b32_e32 v195, v181, v214
	v_add_f32_dpp v187, v187, v199 quad_perm:[2,3,0,1] row_mask:0xf bank_mask:0xf bound_ctrl:1
	v_xor_b32_e32 v199, v189, v193
	v_add_f32_dpp v195, v214, v195 quad_perm:[1,0,3,2] row_mask:0xf bank_mask:0xf bound_ctrl:1
	v_xor_b32_e32 v197, v181, v196
	v_add_f32_dpp v193, v193, v199 quad_perm:[2,3,0,1] row_mask:0xf bank_mask:0xf bound_ctrl:1
	v_xor_b32_e32 v199, v189, v194
	v_pk_add_f32 v[202:203], v[202:203], v[202:203] op_sel:[0,1] op_sel_hi:[1,0] neg_lo:[0,1] neg_hi:[0,1]
	v_add_f32_dpp v196, v196, v197 quad_perm:[1,0,3,2] row_mask:0xf bank_mask:0xf bound_ctrl:1
	v_xor_b32_e32 v197, v181, v56
	v_add_f32_dpp v194, v194, v199 quad_perm:[2,3,0,1] row_mask:0xf bank_mask:0xf bound_ctrl:1
	v_xor_b32_e32 v199, v189, v195
	v_add_f32_dpp v56, v56, v197 quad_perm:[1,0,3,2] row_mask:0xf bank_mask:0xf bound_ctrl:1
	v_xor_b32_e32 v197, v181, v202
	v_add_f32_dpp v195, v195, v199 quad_perm:[2,3,0,1] row_mask:0xf bank_mask:0xf bound_ctrl:1
	v_xor_b32_e32 v199, v189, v196
	v_add_f32_dpp v197, v202, v197 quad_perm:[1,0,3,2] row_mask:0xf bank_mask:0xf bound_ctrl:1
	v_xor_b32_e32 v198, v181, v54
	v_add_f32_dpp v196, v196, v199 quad_perm:[2,3,0,1] row_mask:0xf bank_mask:0xf bound_ctrl:1
	v_xor_b32_e32 v199, v189, v56
	v_add_f32_dpp v54, v54, v198 quad_perm:[1,0,3,2] row_mask:0xf bank_mask:0xf bound_ctrl:1
	v_xor_b32_e32 v198, v181, v52
	v_add_f32_dpp v56, v56, v199 quad_perm:[2,3,0,1] row_mask:0xf bank_mask:0xf bound_ctrl:1
	v_xor_b32_e32 v199, v189, v197
	v_pk_add_f32 v[206:207], v[206:207], v[206:207] op_sel:[0,1] op_sel_hi:[1,0] neg_lo:[0,1] neg_hi:[0,1]
	v_add_f32_dpp v52, v52, v198 quad_perm:[1,0,3,2] row_mask:0xf bank_mask:0xf bound_ctrl:1
	v_xor_b32_e32 v198, v181, v50
	v_add_f32_dpp v197, v197, v199 quad_perm:[2,3,0,1] row_mask:0xf bank_mask:0xf bound_ctrl:1
	v_xor_b32_e32 v199, v189, v54
	v_add_f32_dpp v50, v50, v198 quad_perm:[1,0,3,2] row_mask:0xf bank_mask:0xf bound_ctrl:1
	v_xor_b32_e32 v198, v181, v206
	v_add_f32_dpp v199, v54, v199 quad_perm:[2,3,0,1] row_mask:0xf bank_mask:0xf bound_ctrl:1
	v_xor_b32_e32 v54, v189, v52
	v_add_f32_dpp v198, v206, v198 quad_perm:[1,0,3,2] row_mask:0xf bank_mask:0xf bound_ctrl:1
	s_nop 0
	v_add_f32_dpp v200, v52, v54 quad_perm:[2,3,0,1] row_mask:0xf bank_mask:0xf bound_ctrl:1
	v_xor_b32_e32 v52, v189, v50
	v_max_f32_e64 v54, |v194|, |v195|
	s_nop 0
	v_add_f32_dpp v201, v50, v52 quad_perm:[2,3,0,1] row_mask:0xf bank_mask:0xf bound_ctrl:1
	v_xor_b32_e32 v50, v189, v198
	v_max_f32_e64 v52, |v55|, |v57|
	s_nop 0
	v_add_f32_dpp v198, v198, v50 quad_perm:[2,3,0,1] row_mask:0xf bank_mask:0xf bound_ctrl:1
	v_xor_b32_e32 v50, v189, v186
	s_nop 1
	v_add_f32_dpp v186, v186, v50 quad_perm:[2,3,0,1] row_mask:0xf bank_mask:0xf bound_ctrl:1
	v_max_f32_e64 v50, |v51|, |v53|
	v_max3_f32 v50, v216, v50, v52
	v_max_f32_e64 v52, |v187|, |v193|
	v_max3_f32 v50, v50, v52, v54
	v_max_f32_e64 v52, |v196|, |v56|
	v_max_f32_e64 v54, |v197|, |v199|
	v_max3_f32 v50, v50, v52, v54
	v_max_f32_e64 v52, |v200|, |v201|
	v_max_f32_e64 v54, |v198|, |v186|
	v_max3_f32 v216, v50, v52, v54
	v_cvt_pk_bf16_f32 v50, v51, v53
	v_cvt_pk_bf16_f32 v51, v55, v57
	v_cvt_pk_bf16_f32 v52, v187, v193
	v_cvt_pk_bf16_f32 v53, v194, v195
	v_cvt_pk_bf16_f32 v54, v196, v56
	v_cvt_pk_bf16_f32 v55, v197, v199
	v_cvt_pk_bf16_f32 v56, v200, v201
	v_cvt_pk_bf16_f32 v57, v198, v186
	v_and_b32_e32 v187, 0xffff0000, v65
	v_and_b32_e32 v186, 0xffff0000, v61
	v_lshlrev_b32_e32 v195, 16, v62
	v_lshlrev_b32_e32 v194, 16, v58
	v_and_b32_e32 v197, 0xffff0000, v62
	v_and_b32_e32 v196, 0xffff0000, v58
	v_lshlrev_b32_e32 v199, 16, v63
	v_lshlrev_b32_e32 v198, 16, v59
	v_and_b32_e32 v63, 0xffff0000, v63
	v_and_b32_e32 v62, 0xffff0000, v59
	v_lshlrev_b32_e32 v59, 16, v64
	v_lshlrev_b32_e32 v58, 16, v60
	v_and_b32_e32 v201, 0xffff0000, v64
	v_and_b32_e32 v200, 0xffff0000, v60
	v_lshlrev_b32_e32 v65, 16, v65
	v_lshlrev_b32_e32 v64, 16, v61
	v_pk_add_f32 v[60:61], v[194:195], v[196:197]
	v_pk_add_f32 v[202:203], v[198:199], v[62:63]
	v_pk_add_f32 v[204:205], v[58:59], v[200:201]
	v_pk_add_f32 v[206:207], v[64:65], v[186:187]
	v_pk_add_f32 v[194:195], v[194:195], v[196:197] neg_lo:[0,1] neg_hi:[0,1]
	v_pk_add_f32 v[62:63], v[198:199], v[62:63] neg_lo:[0,1] neg_hi:[0,1]
	v_pk_add_f32 v[58:59], v[58:59], v[200:201] neg_lo:[0,1] neg_hi:[0,1]
	v_pk_add_f32 v[64:65], v[64:65], v[186:187] neg_lo:[0,1] neg_hi:[0,1]
	v_pk_add_f32 v[208:209], v[60:61], v[202:203] neg_lo:[0,1] neg_hi:[0,1]
	v_pk_add_f32 v[60:61], v[60:61], v[202:203]
	v_pk_add_f32 v[202:203], v[204:205], v[206:207]
	v_pk_add_f32 v[186:187], v[194:195], v[62:63] neg_lo:[0,1] neg_hi:[0,1]
	v_pk_add_f32 v[196:197], v[58:59], v[64:65] neg_lo:[0,1] neg_hi:[0,1]
	v_pk_add_f32 v[62:63], v[194:195], v[62:63]
	v_pk_add_f32 v[58:59], v[58:59], v[64:65]
	v_pk_add_f32 v[210:211], v[204:205], v[206:207] neg_lo:[0,1] neg_hi:[0,1]
	v_pk_add_f32 v[204:205], v[60:61], v[202:203]
	v_pk_add_f32 v[64:65], v[62:63], v[58:59]
	v_pk_add_f32 v[58:59], v[62:63], v[58:59] neg_lo:[0,1] neg_hi:[0,1]
	v_pk_add_f32 v[60:61], v[60:61], v[202:203] neg_lo:[0,1] neg_hi:[0,1]
	v_pk_add_f32 v[202:203], v[208:209], v[210:211]
	v_pk_add_f32 v[206:207], v[208:209], v[210:211] neg_lo:[0,1] neg_hi:[0,1]
	v_pk_add_f32 v[62:63], v[186:187], v[196:197]
	v_pk_add_f32 v[186:187], v[186:187], v[196:197] neg_lo:[0,1] neg_hi:[0,1]
	v_pk_add_f32 v[194:195], v[204:205], v[204:205] op_sel:[0,1] op_sel_hi:[1,0]
	v_pk_add_f32 v[210:211], v[58:59], v[58:59] op_sel:[0,1] op_sel_hi:[1,0]
	v_pk_add_f32 v[58:59], v[58:59], v[58:59] op_sel:[0,1] op_sel_hi:[1,0] neg_lo:[0,1] neg_hi:[0,1]
	v_pk_add_f32 v[198:199], v[64:65], v[64:65] op_sel:[0,1] op_sel_hi:[1,0]
	v_pk_add_f32 v[208:209], v[60:61], v[60:61] op_sel:[0,1] op_sel_hi:[1,0]
	v_pk_add_f32 v[60:61], v[60:61], v[60:61] op_sel:[0,1] op_sel_hi:[1,0] neg_lo:[0,1] neg_hi:[0,1]
	v_pk_add_f32 v[214:215], v[186:187], v[186:187] op_sel:[0,1] op_sel_hi:[1,0]
	v_pk_add_f32 v[186:187], v[186:187], v[186:187] op_sel:[0,1] op_sel_hi:[1,0] neg_lo:[0,1] neg_hi:[0,1]
	v_xor_b32_e32 v59, v181, v194
	v_pk_add_f32 v[196:197], v[204:205], v[204:205] op_sel:[0,1] op_sel_hi:[1,0] neg_lo:[0,1] neg_hi:[0,1]
	v_pk_add_f32 v[200:201], v[202:203], v[202:203] op_sel:[0,1] op_sel_hi:[1,0]
	v_pk_add_f32 v[204:205], v[62:63], v[62:63] op_sel:[0,1] op_sel_hi:[1,0]
	v_pk_add_f32 v[62:63], v[62:63], v[62:63] op_sel:[0,1] op_sel_hi:[1,0] neg_lo:[0,1] neg_hi:[0,1]
	v_add_f32_dpp v59, v194, v59 quad_perm:[1,0,3,2] row_mask:0xf bank_mask:0xf bound_ctrl:1
	v_xor_b32_e32 v61, v181, v198
	v_xor_b32_e32 v199, v181, v186
	v_pk_add_f32 v[64:65], v[64:65], v[64:65] op_sel:[0,1] op_sel_hi:[1,0] neg_lo:[0,1] neg_hi:[0,1]
	v_add_f32_dpp v61, v198, v61 quad_perm:[1,0,3,2] row_mask:0xf bank_mask:0xf bound_ctrl:1
	v_xor_b32_e32 v63, v181, v200
	v_add_f32_dpp v186, v186, v199 quad_perm:[1,0,3,2] row_mask:0xf bank_mask:0xf bound_ctrl:1
	v_xor_b32_e32 v199, v189, v59
	v_add_f32_dpp v63, v200, v63 quad_perm:[1,0,3,2] row_mask:0xf bank_mask:0xf bound_ctrl:1
	v_xor_b32_e32 v65, v181, v204
	v_add_f32_dpp v59, v59, v199 quad_perm:[2,3,0,1] row_mask:0xf bank_mask:0xf bound_ctrl:1
	v_xor_b32_e32 v199, v189, v61
	v_add_f32_dpp v65, v204, v65 quad_perm:[1,0,3,2] row_mask:0xf bank_mask:0xf bound_ctrl:1
	v_xor_b32_e32 v187, v181, v208
	v_add_f32_dpp v61, v61, v199 quad_perm:[2,3,0,1] row_mask:0xf bank_mask:0xf bound_ctrl:1
	v_xor_b32_e32 v199, v189, v63
	v_pk_add_f32 v[212:213], v[206:207], v[206:207] op_sel:[0,1] op_sel_hi:[1,0]
	v_add_f32_dpp v187, v208, v187 quad_perm:[1,0,3,2] row_mask:0xf bank_mask:0xf bound_ctrl:1
	v_xor_b32_e32 v193, v181, v210
	v_add_f32_dpp v63, v63, v199 quad_perm:[2,3,0,1] row_mask:0xf bank_mask:0xf bound_ctrl:1
	v_xor_b32_e32 v199, v189, v65
	v_add_f32_dpp v193, v210, v193 quad_perm:[1,0,3,2] row_mask:0xf bank_mask:0xf bound_ctrl:1
	v_xor_b32_e32 v194, v181, v212
	v_add_f32_dpp v65, v65, v199 quad_perm:[2,3,0,1] row_mask:0xf bank_mask:0xf bound_ctrl:1
	v_xor_b32_e32 v199, v189, v187
	v_add_f32_dpp v194, v212, v194 quad_perm:[1,0,3,2] row_mask:0xf bank_mask:0xf bound_ctrl:1
	v_xor_b32_e32 v195, v181, v214
	v_add_f32_dpp v187, v187, v199 quad_perm:[2,3,0,1] row_mask:0xf bank_mask:0xf bound_ctrl:1
	v_xor_b32_e32 v199, v189, v193
	v_add_f32_dpp v195, v214, v195 quad_perm:[1,0,3,2] row_mask:0xf bank_mask:0xf bound_ctrl:1
	v_xor_b32_e32 v197, v181, v196
	v_add_f32_dpp v193, v193, v199 quad_perm:[2,3,0,1] row_mask:0xf bank_mask:0xf bound_ctrl:1
	v_xor_b32_e32 v199, v189, v194
	v_pk_add_f32 v[202:203], v[202:203], v[202:203] op_sel:[0,1] op_sel_hi:[1,0] neg_lo:[0,1] neg_hi:[0,1]
	v_add_f32_dpp v196, v196, v197 quad_perm:[1,0,3,2] row_mask:0xf bank_mask:0xf bound_ctrl:1
	v_xor_b32_e32 v197, v181, v64
	v_add_f32_dpp v194, v194, v199 quad_perm:[2,3,0,1] row_mask:0xf bank_mask:0xf bound_ctrl:1
	v_xor_b32_e32 v199, v189, v195
	v_add_f32_dpp v64, v64, v197 quad_perm:[1,0,3,2] row_mask:0xf bank_mask:0xf bound_ctrl:1
	v_xor_b32_e32 v197, v181, v202
	v_add_f32_dpp v195, v195, v199 quad_perm:[2,3,0,1] row_mask:0xf bank_mask:0xf bound_ctrl:1
	v_xor_b32_e32 v199, v189, v196
	v_add_f32_dpp v197, v202, v197 quad_perm:[1,0,3,2] row_mask:0xf bank_mask:0xf bound_ctrl:1
	v_xor_b32_e32 v198, v181, v62
	v_add_f32_dpp v196, v196, v199 quad_perm:[2,3,0,1] row_mask:0xf bank_mask:0xf bound_ctrl:1
	v_xor_b32_e32 v199, v189, v64
	v_add_f32_dpp v62, v62, v198 quad_perm:[1,0,3,2] row_mask:0xf bank_mask:0xf bound_ctrl:1
	v_xor_b32_e32 v198, v181, v60
	v_add_f32_dpp v64, v64, v199 quad_perm:[2,3,0,1] row_mask:0xf bank_mask:0xf bound_ctrl:1
	v_xor_b32_e32 v199, v189, v197
	v_pk_add_f32 v[206:207], v[206:207], v[206:207] op_sel:[0,1] op_sel_hi:[1,0] neg_lo:[0,1] neg_hi:[0,1]
	v_add_f32_dpp v60, v60, v198 quad_perm:[1,0,3,2] row_mask:0xf bank_mask:0xf bound_ctrl:1
	v_xor_b32_e32 v198, v181, v58
	v_add_f32_dpp v197, v197, v199 quad_perm:[2,3,0,1] row_mask:0xf bank_mask:0xf bound_ctrl:1
	v_xor_b32_e32 v199, v189, v62
	v_add_f32_dpp v58, v58, v198 quad_perm:[1,0,3,2] row_mask:0xf bank_mask:0xf bound_ctrl:1
	v_xor_b32_e32 v198, v181, v206
	v_add_f32_dpp v199, v62, v199 quad_perm:[2,3,0,1] row_mask:0xf bank_mask:0xf bound_ctrl:1
	v_xor_b32_e32 v62, v189, v60
	v_add_f32_dpp v198, v206, v198 quad_perm:[1,0,3,2] row_mask:0xf bank_mask:0xf bound_ctrl:1
	s_nop 0
	v_add_f32_dpp v200, v60, v62 quad_perm:[2,3,0,1] row_mask:0xf bank_mask:0xf bound_ctrl:1
	v_xor_b32_e32 v60, v189, v58
	v_max_f32_e64 v62, |v194|, |v195|
	s_nop 0
	v_add_f32_dpp v201, v58, v60 quad_perm:[2,3,0,1] row_mask:0xf bank_mask:0xf bound_ctrl:1
	v_xor_b32_e32 v58, v189, v198
	v_max_f32_e64 v60, |v63|, |v65|
	s_nop 0
	v_add_f32_dpp v198, v198, v58 quad_perm:[2,3,0,1] row_mask:0xf bank_mask:0xf bound_ctrl:1
	v_xor_b32_e32 v58, v189, v186
	s_nop 1
	v_add_f32_dpp v186, v186, v58 quad_perm:[2,3,0,1] row_mask:0xf bank_mask:0xf bound_ctrl:1
	v_max_f32_e64 v58, |v59|, |v61|
	v_max3_f32 v58, v216, v58, v60
	v_max_f32_e64 v60, |v187|, |v193|
	v_max3_f32 v58, v58, v60, v62
	v_max_f32_e64 v60, |v196|, |v64|
	v_max_f32_e64 v62, |v197|, |v199|
	v_max3_f32 v58, v58, v60, v62
	v_max_f32_e64 v60, |v200|, |v201|
	v_max_f32_e64 v62, |v198|, |v186|
	v_max3_f32 v216, v58, v60, v62
	v_cvt_pk_bf16_f32 v58, v59, v61
	v_cvt_pk_bf16_f32 v59, v63, v65
	v_cvt_pk_bf16_f32 v60, v187, v193
	v_cvt_pk_bf16_f32 v61, v194, v195
	v_cvt_pk_bf16_f32 v62, v196, v64
	v_cvt_pk_bf16_f32 v63, v197, v199
	v_cvt_pk_bf16_f32 v64, v200, v201
	v_cvt_pk_bf16_f32 v65, v198, v186
	v_and_b32_e32 v187, 0xffff0000, v157
	v_and_b32_e32 v186, 0xffff0000, v149
	v_lshlrev_b32_e32 v195, 16, v154
	v_lshlrev_b32_e32 v194, 16, v146
	v_and_b32_e32 v197, 0xffff0000, v154
	v_and_b32_e32 v196, 0xffff0000, v146
	v_lshlrev_b32_e32 v199, 16, v155
	v_lshlrev_b32_e32 v198, 16, v147
	v_and_b32_e32 v155, 0xffff0000, v155
	v_and_b32_e32 v154, 0xffff0000, v147
	v_lshlrev_b32_e32 v147, 16, v156
	v_lshlrev_b32_e32 v146, 16, v148
	v_and_b32_e32 v201, 0xffff0000, v156
	v_and_b32_e32 v200, 0xffff0000, v148
	v_lshlrev_b32_e32 v157, 16, v157
	v_lshlrev_b32_e32 v156, 16, v149
	v_pk_add_f32 v[148:149], v[194:195], v[196:197]
	v_pk_add_f32 v[202:203], v[198:199], v[154:155]
	v_pk_add_f32 v[204:205], v[146:147], v[200:201]
	v_pk_add_f32 v[206:207], v[156:157], v[186:187]
	v_pk_add_f32 v[194:195], v[194:195], v[196:197] neg_lo:[0,1] neg_hi:[0,1]
	v_pk_add_f32 v[154:155], v[198:199], v[154:155] neg_lo:[0,1] neg_hi:[0,1]
	v_pk_add_f32 v[146:147], v[146:147], v[200:201] neg_lo:[0,1] neg_hi:[0,1]
	v_pk_add_f32 v[156:157], v[156:157], v[186:187] neg_lo:[0,1] neg_hi:[0,1]
	v_pk_add_f32 v[208:209], v[148:149], v[202:203] neg_lo:[0,1] neg_hi:[0,1]
	v_pk_add_f32 v[148:149], v[148:149], v[202:203]
	v_pk_add_f32 v[202:203], v[204:205], v[206:207]
	v_pk_add_f32 v[186:187], v[194:195], v[154:155] neg_lo:[0,1] neg_hi:[0,1]
	v_pk_add_f32 v[196:197], v[146:147], v[156:157] neg_lo:[0,1] neg_hi:[0,1]
	v_pk_add_f32 v[154:155], v[194:195], v[154:155]
	v_pk_add_f32 v[146:147], v[146:147], v[156:157]
	v_pk_add_f32 v[210:211], v[204:205], v[206:207] neg_lo:[0,1] neg_hi:[0,1]
	v_pk_add_f32 v[204:205], v[148:149], v[202:203]
	v_pk_add_f32 v[156:157], v[154:155], v[146:147]
	v_pk_add_f32 v[146:147], v[154:155], v[146:147] neg_lo:[0,1] neg_hi:[0,1]
	v_pk_add_f32 v[148:149], v[148:149], v[202:203] neg_lo:[0,1] neg_hi:[0,1]
	v_pk_add_f32 v[202:203], v[208:209], v[210:211]
	v_pk_add_f32 v[206:207], v[208:209], v[210:211] neg_lo:[0,1] neg_hi:[0,1]
	v_pk_add_f32 v[154:155], v[186:187], v[196:197]
	v_pk_add_f32 v[186:187], v[186:187], v[196:197] neg_lo:[0,1] neg_hi:[0,1]
	v_pk_add_f32 v[194:195], v[204:205], v[204:205] op_sel:[0,1] op_sel_hi:[1,0]
	v_pk_add_f32 v[210:211], v[146:147], v[146:147] op_sel:[0,1] op_sel_hi:[1,0]
	v_pk_add_f32 v[146:147], v[146:147], v[146:147] op_sel:[0,1] op_sel_hi:[1,0] neg_lo:[0,1] neg_hi:[0,1]
	v_pk_add_f32 v[198:199], v[156:157], v[156:157] op_sel:[0,1] op_sel_hi:[1,0]
	v_pk_add_f32 v[208:209], v[148:149], v[148:149] op_sel:[0,1] op_sel_hi:[1,0]
	v_pk_add_f32 v[148:149], v[148:149], v[148:149] op_sel:[0,1] op_sel_hi:[1,0] neg_lo:[0,1] neg_hi:[0,1]
	v_pk_add_f32 v[214:215], v[186:187], v[186:187] op_sel:[0,1] op_sel_hi:[1,0]
	v_pk_add_f32 v[186:187], v[186:187], v[186:187] op_sel:[0,1] op_sel_hi:[1,0] neg_lo:[0,1] neg_hi:[0,1]
	v_xor_b32_e32 v147, v181, v194
	v_pk_add_f32 v[196:197], v[204:205], v[204:205] op_sel:[0,1] op_sel_hi:[1,0] neg_lo:[0,1] neg_hi:[0,1]
	v_pk_add_f32 v[200:201], v[202:203], v[202:203] op_sel:[0,1] op_sel_hi:[1,0]
	v_pk_add_f32 v[204:205], v[154:155], v[154:155] op_sel:[0,1] op_sel_hi:[1,0]
	v_pk_add_f32 v[154:155], v[154:155], v[154:155] op_sel:[0,1] op_sel_hi:[1,0] neg_lo:[0,1] neg_hi:[0,1]
	v_add_f32_dpp v147, v194, v147 quad_perm:[1,0,3,2] row_mask:0xf bank_mask:0xf bound_ctrl:1
	v_xor_b32_e32 v149, v181, v198
	v_xor_b32_e32 v199, v181, v186
	v_pk_add_f32 v[156:157], v[156:157], v[156:157] op_sel:[0,1] op_sel_hi:[1,0] neg_lo:[0,1] neg_hi:[0,1]
	v_add_f32_dpp v149, v198, v149 quad_perm:[1,0,3,2] row_mask:0xf bank_mask:0xf bound_ctrl:1
	v_xor_b32_e32 v155, v181, v200
	v_xor_b32_e32 v187, v181, v208
	v_add_f32_dpp v186, v186, v199 quad_perm:[1,0,3,2] row_mask:0xf bank_mask:0xf bound_ctrl:1
	v_xor_b32_e32 v199, v189, v147
	v_add_f32_dpp v155, v200, v155 quad_perm:[1,0,3,2] row_mask:0xf bank_mask:0xf bound_ctrl:1
	v_xor_b32_e32 v157, v181, v204
	v_add_f32_dpp v187, v208, v187 quad_perm:[1,0,3,2] row_mask:0xf bank_mask:0xf bound_ctrl:1
	v_add_f32_dpp v208, v147, v199 quad_perm:[2,3,0,1] row_mask:0xf bank_mask:0xf bound_ctrl:1
	v_xor_b32_e32 v147, v189, v149
	v_add_f32_dpp v157, v204, v157 quad_perm:[1,0,3,2] row_mask:0xf bank_mask:0xf bound_ctrl:1
	v_xor_b32_e32 v193, v181, v210
	v_add_f32_dpp v209, v149, v147 quad_perm:[2,3,0,1] row_mask:0xf bank_mask:0xf bound_ctrl:1
	v_xor_b32_e32 v147, v189, v155
	v_pk_add_f32 v[212:213], v[206:207], v[206:207] op_sel:[0,1] op_sel_hi:[1,0]
	v_add_f32_dpp v193, v210, v193 quad_perm:[1,0,3,2] row_mask:0xf bank_mask:0xf bound_ctrl:1
	v_add_f32_dpp v210, v155, v147 quad_perm:[2,3,0,1] row_mask:0xf bank_mask:0xf bound_ctrl:1
	v_xor_b32_e32 v147, v189, v157
	v_xor_b32_e32 v194, v181, v212
	v_xor_b32_e32 v195, v181, v214
	v_add_f32_dpp v211, v157, v147 quad_perm:[2,3,0,1] row_mask:0xf bank_mask:0xf bound_ctrl:1
	v_xor_b32_e32 v147, v189, v187
	v_add_f32_dpp v194, v212, v194 quad_perm:[1,0,3,2] row_mask:0xf bank_mask:0xf bound_ctrl:1
	v_add_f32_dpp v195, v214, v195 quad_perm:[1,0,3,2] row_mask:0xf bank_mask:0xf bound_ctrl:1
	v_add_f32_dpp v212, v187, v147 quad_perm:[2,3,0,1] row_mask:0xf bank_mask:0xf bound_ctrl:1
	v_xor_b32_e32 v147, v189, v193
	v_xor_b32_e32 v197, v181, v196
	v_pk_add_f32 v[202:203], v[202:203], v[202:203] op_sel:[0,1] op_sel_hi:[1,0] neg_lo:[0,1] neg_hi:[0,1]
	v_add_f32_dpp v213, v193, v147 quad_perm:[2,3,0,1] row_mask:0xf bank_mask:0xf bound_ctrl:1
	v_xor_b32_e32 v147, v189, v194
	v_add_f32_dpp v196, v196, v197 quad_perm:[1,0,3,2] row_mask:0xf bank_mask:0xf bound_ctrl:1
	v_xor_b32_e32 v197, v181, v156
	v_add_f32_dpp v214, v194, v147 quad_perm:[2,3,0,1] row_mask:0xf bank_mask:0xf bound_ctrl:1
	v_xor_b32_e32 v147, v189, v195
	v_add_f32_dpp v156, v156, v197 quad_perm:[1,0,3,2] row_mask:0xf bank_mask:0xf bound_ctrl:1
	v_xor_b32_e32 v197, v181, v202
	v_add_f32_dpp v215, v195, v147 quad_perm:[2,3,0,1] row_mask:0xf bank_mask:0xf bound_ctrl:1
	v_xor_b32_e32 v147, v189, v196
	v_add_f32_dpp v197, v202, v197 quad_perm:[1,0,3,2] row_mask:0xf bank_mask:0xf bound_ctrl:1
	v_xor_b32_e32 v198, v181, v154
	v_add_f32_dpp v217, v196, v147 quad_perm:[2,3,0,1] row_mask:0xf bank_mask:0xf bound_ctrl:1
	v_xor_b32_e32 v147, v189, v156
	v_add_f32_dpp v154, v154, v198 quad_perm:[1,0,3,2] row_mask:0xf bank_mask:0xf bound_ctrl:1
	v_xor_b32_e32 v198, v181, v148
	v_add_f32_dpp v218, v156, v147 quad_perm:[2,3,0,1] row_mask:0xf bank_mask:0xf bound_ctrl:1
	v_xor_b32_e32 v147, v189, v197
	v_pk_add_f32 v[206:207], v[206:207], v[206:207] op_sel:[0,1] op_sel_hi:[1,0] neg_lo:[0,1] neg_hi:[0,1]
	v_add_f32_dpp v148, v148, v198 quad_perm:[1,0,3,2] row_mask:0xf bank_mask:0xf bound_ctrl:1
	v_xor_b32_e32 v198, v181, v146
	v_add_f32_dpp v219, v197, v147 quad_perm:[2,3,0,1] row_mask:0xf bank_mask:0xf bound_ctrl:1
	v_xor_b32_e32 v147, v189, v154
	v_add_f32_dpp v146, v146, v198 quad_perm:[1,0,3,2] row_mask:0xf bank_mask:0xf bound_ctrl:1
	v_xor_b32_e32 v198, v181, v206
	v_add_f32_dpp v220, v154, v147 quad_perm:[2,3,0,1] row_mask:0xf bank_mask:0xf bound_ctrl:1
	v_xor_b32_e32 v147, v189, v148
	v_add_f32_dpp v198, v206, v198 quad_perm:[1,0,3,2] row_mask:0xf bank_mask:0xf bound_ctrl:1
	s_waitcnt vmcnt(0)
	v_lshlrev_b32_e32 v149, 16, v114
	v_add_f32_dpp v221, v148, v147 quad_perm:[2,3,0,1] row_mask:0xf bank_mask:0xf bound_ctrl:1
	v_xor_b32_e32 v147, v189, v146
	v_max_f32_e64 v148, |v214|, |v215|
	v_and_b32_e32 v155, 0xffff0000, v114
	v_add_f32_dpp v222, v146, v147 quad_perm:[2,3,0,1] row_mask:0xf bank_mask:0xf bound_ctrl:1
	v_xor_b32_e32 v146, v189, v198
	v_max_f32_e64 v147, |v210|, |v211|
	v_and_b32_e32 v154, 0xffff0000, v102
	v_add_f32_dpp v223, v198, v146 quad_perm:[2,3,0,1] row_mask:0xf bank_mask:0xf bound_ctrl:1
	v_xor_b32_e32 v146, v189, v186
	v_lshlrev_b32_e32 v157, 16, v115
	v_lshlrev_b32_e32 v156, 16, v103
	v_add_f32_dpp v224, v186, v146 quad_perm:[2,3,0,1] row_mask:0xf bank_mask:0xf bound_ctrl:1
	v_max_f32_e64 v146, |v208|, |v209|
	v_max3_f32 v146, v216, v146, v147
	v_max_f32_e64 v147, |v212|, |v213|
	v_max3_f32 v146, v146, v147, v148
	v_max_f32_e64 v147, |v217|, |v218|
	v_max_f32_e64 v148, |v219|, |v220|
	v_max3_f32 v146, v146, v147, v148
	v_max_f32_e64 v147, |v221|, |v222|
	v_max_f32_e64 v148, |v223|, |v224|
	v_max3_f32 v193, v146, v147, v148
	v_and_b32_e32 v147, 0xffff0000, v117
	v_and_b32_e32 v146, 0xffff0000, v105
	v_lshlrev_b32_e32 v148, 16, v102
	v_and_b32_e32 v115, 0xffff0000, v115
	v_and_b32_e32 v114, 0xffff0000, v103
	v_lshlrev_b32_e32 v103, 16, v116
	v_lshlrev_b32_e32 v102, 16, v104
	v_and_b32_e32 v187, 0xffff0000, v116
	v_and_b32_e32 v186, 0xffff0000, v104
	v_lshlrev_b32_e32 v117, 16, v117
	v_lshlrev_b32_e32 v116, 16, v105
	v_pk_add_f32 v[104:105], v[148:149], v[154:155]
	v_pk_add_f32 v[194:195], v[156:157], v[114:115]
	v_pk_add_f32 v[196:197], v[102:103], v[186:187]
	v_pk_add_f32 v[198:199], v[116:117], v[146:147]
	v_pk_add_f32 v[148:149], v[148:149], v[154:155] neg_lo:[0,1] neg_hi:[0,1]
	v_pk_add_f32 v[114:115], v[156:157], v[114:115] neg_lo:[0,1] neg_hi:[0,1]
	v_pk_add_f32 v[102:103], v[102:103], v[186:187] neg_lo:[0,1] neg_hi:[0,1]
	v_pk_add_f32 v[116:117], v[116:117], v[146:147] neg_lo:[0,1] neg_hi:[0,1]
	v_pk_add_f32 v[200:201], v[104:105], v[194:195] neg_lo:[0,1] neg_hi:[0,1]
	v_pk_add_f32 v[202:203], v[196:197], v[198:199] neg_lo:[0,1] neg_hi:[0,1]
	v_pk_add_f32 v[104:105], v[104:105], v[194:195]
	v_pk_add_f32 v[194:195], v[196:197], v[198:199]
	v_pk_add_f32 v[146:147], v[148:149], v[114:115] neg_lo:[0,1] neg_hi:[0,1]
	v_pk_add_f32 v[154:155], v[102:103], v[116:117] neg_lo:[0,1] neg_hi:[0,1]
	v_pk_add_f32 v[114:115], v[148:149], v[114:115]
	v_pk_add_f32 v[102:103], v[102:103], v[116:117]
	v_pk_add_f32 v[196:197], v[104:105], v[194:195]
	v_pk_add_f32 v[104:105], v[104:105], v[194:195] neg_lo:[0,1] neg_hi:[0,1]
	v_pk_add_f32 v[194:195], v[200:201], v[202:203]
	v_pk_add_f32 v[116:117], v[114:115], v[102:103]
	v_pk_add_f32 v[102:103], v[114:115], v[102:103] neg_lo:[0,1] neg_hi:[0,1]
	v_pk_add_f32 v[114:115], v[146:147], v[154:155]
	v_pk_add_f32 v[198:199], v[200:201], v[202:203] neg_lo:[0,1] neg_hi:[0,1]
	v_pk_add_f32 v[146:147], v[146:147], v[154:155] neg_lo:[0,1] neg_hi:[0,1]
	v_pk_add_f32 v[148:149], v[196:197], v[196:197] op_sel:[0,1] op_sel_hi:[1,0]
	v_pk_add_f32 v[154:155], v[196:197], v[196:197] op_sel:[0,1] op_sel_hi:[1,0] neg_lo:[0,1] neg_hi:[0,1]
	v_pk_add_f32 v[186:187], v[194:195], v[194:195] op_sel:[0,1] op_sel_hi:[1,0]
	v_pk_add_f32 v[196:197], v[114:115], v[114:115] op_sel:[0,1] op_sel_hi:[1,0]
	v_pk_add_f32 v[114:115], v[114:115], v[114:115] op_sel:[0,1] op_sel_hi:[1,0] neg_lo:[0,1] neg_hi:[0,1]
	v_pk_add_f32 v[202:203], v[102:103], v[102:103] op_sel:[0,1] op_sel_hi:[1,0]
	v_pk_add_f32 v[102:103], v[102:103], v[102:103] op_sel:[0,1] op_sel_hi:[1,0] neg_lo:[0,1] neg_hi:[0,1]
	v_pk_add_f32 v[156:157], v[116:117], v[116:117] op_sel:[0,1] op_sel_hi:[1,0]
	v_pk_add_f32 v[200:201], v[104:105], v[104:105] op_sel:[0,1] op_sel_hi:[1,0]
	v_pk_add_f32 v[104:105], v[104:105], v[104:105] op_sel:[0,1] op_sel_hi:[1,0] neg_lo:[0,1] neg_hi:[0,1]
	v_pk_add_f32 v[206:207], v[146:147], v[146:147] op_sel:[0,1] op_sel_hi:[1,0]
	v_pk_add_f32 v[146:147], v[146:147], v[146:147] op_sel:[0,1] op_sel_hi:[1,0] neg_lo:[0,1] neg_hi:[0,1]
	v_xor_b32_e32 v103, v181, v148
	v_xor_b32_e32 v115, v181, v186
	v_xor_b32_e32 v105, v181, v156
	v_add_f32_dpp v103, v148, v103 quad_perm:[1,0,3,2] row_mask:0xf bank_mask:0xf bound_ctrl:1
	v_add_f32_dpp v115, v186, v115 quad_perm:[1,0,3,2] row_mask:0xf bank_mask:0xf bound_ctrl:1
	v_xor_b32_e32 v186, v181, v146
	v_pk_add_f32 v[116:117], v[116:117], v[116:117] op_sel:[0,1] op_sel_hi:[1,0] neg_lo:[0,1] neg_hi:[0,1]
	v_add_f32_dpp v105, v156, v105 quad_perm:[1,0,3,2] row_mask:0xf bank_mask:0xf bound_ctrl:1
	v_xor_b32_e32 v147, v181, v200
	v_add_f32_dpp v146, v146, v186 quad_perm:[1,0,3,2] row_mask:0xf bank_mask:0xf bound_ctrl:1
	v_xor_b32_e32 v186, v189, v103
	v_xor_b32_e32 v117, v181, v196
	v_add_f32_dpp v147, v200, v147 quad_perm:[1,0,3,2] row_mask:0xf bank_mask:0xf bound_ctrl:1
	v_add_f32_dpp v200, v103, v186 quad_perm:[2,3,0,1] row_mask:0xf bank_mask:0xf bound_ctrl:1
	v_xor_b32_e32 v103, v189, v105
	v_add_f32_dpp v117, v196, v117 quad_perm:[1,0,3,2] row_mask:0xf bank_mask:0xf bound_ctrl:1
	v_xor_b32_e32 v148, v181, v202
	v_add_f32_dpp v201, v105, v103 quad_perm:[2,3,0,1] row_mask:0xf bank_mask:0xf bound_ctrl:1
	v_xor_b32_e32 v103, v189, v115
	v_pk_add_f32 v[204:205], v[198:199], v[198:199] op_sel:[0,1] op_sel_hi:[1,0]
	v_add_f32_dpp v148, v202, v148 quad_perm:[1,0,3,2] row_mask:0xf bank_mask:0xf bound_ctrl:1
	v_add_f32_dpp v202, v115, v103 quad_perm:[2,3,0,1] row_mask:0xf bank_mask:0xf bound_ctrl:1
	v_xor_b32_e32 v103, v189, v117
	v_xor_b32_e32 v149, v181, v204
	v_xor_b32_e32 v155, v181, v206
	v_add_f32_dpp v203, v117, v103 quad_perm:[2,3,0,1] row_mask:0xf bank_mask:0xf bound_ctrl:1
	v_xor_b32_e32 v103, v189, v147
	v_add_f32_dpp v149, v204, v149 quad_perm:[1,0,3,2] row_mask:0xf bank_mask:0xf bound_ctrl:1
	v_add_f32_dpp v155, v206, v155 quad_perm:[1,0,3,2] row_mask:0xf bank_mask:0xf bound_ctrl:1
	v_add_f32_dpp v204, v147, v103 quad_perm:[2,3,0,1] row_mask:0xf bank_mask:0xf bound_ctrl:1
	v_xor_b32_e32 v103, v189, v148
	v_xor_b32_e32 v156, v181, v154
	v_pk_add_f32 v[194:195], v[194:195], v[194:195] op_sel:[0,1] op_sel_hi:[1,0] neg_lo:[0,1] neg_hi:[0,1]
	v_add_f32_dpp v205, v148, v103 quad_perm:[2,3,0,1] row_mask:0xf bank_mask:0xf bound_ctrl:1
	v_xor_b32_e32 v103, v189, v149
	v_add_f32_dpp v154, v154, v156 quad_perm:[1,0,3,2] row_mask:0xf bank_mask:0xf bound_ctrl:1
	v_xor_b32_e32 v156, v181, v116
	v_add_f32_dpp v206, v149, v103 quad_perm:[2,3,0,1] row_mask:0xf bank_mask:0xf bound_ctrl:1
	v_xor_b32_e32 v103, v189, v155
	v_add_f32_dpp v116, v116, v156 quad_perm:[1,0,3,2] row_mask:0xf bank_mask:0xf bound_ctrl:1
	v_xor_b32_e32 v156, v181, v194
	v_add_f32_dpp v207, v155, v103 quad_perm:[2,3,0,1] row_mask:0xf bank_mask:0xf bound_ctrl:1
	v_xor_b32_e32 v103, v189, v154
	v_add_f32_dpp v156, v194, v156 quad_perm:[1,0,3,2] row_mask:0xf bank_mask:0xf bound_ctrl:1
	v_xor_b32_e32 v157, v181, v114
	v_add_f32_dpp v216, v154, v103 quad_perm:[2,3,0,1] row_mask:0xf bank_mask:0xf bound_ctrl:1
	v_xor_b32_e32 v103, v189, v116
	v_add_f32_dpp v114, v114, v157 quad_perm:[1,0,3,2] row_mask:0xf bank_mask:0xf bound_ctrl:1
	v_xor_b32_e32 v157, v181, v104
	v_add_f32_dpp v225, v116, v103 quad_perm:[2,3,0,1] row_mask:0xf bank_mask:0xf bound_ctrl:1
	v_xor_b32_e32 v103, v189, v156
	v_pk_add_f32 v[198:199], v[198:199], v[198:199] op_sel:[0,1] op_sel_hi:[1,0] neg_lo:[0,1] neg_hi:[0,1]
	v_add_f32_dpp v104, v104, v157 quad_perm:[1,0,3,2] row_mask:0xf bank_mask:0xf bound_ctrl:1
	v_xor_b32_e32 v157, v181, v102
	v_add_f32_dpp v226, v156, v103 quad_perm:[2,3,0,1] row_mask:0xf bank_mask:0xf bound_ctrl:1
	v_xor_b32_e32 v103, v189, v114
	v_add_f32_dpp v102, v102, v157 quad_perm:[1,0,3,2] row_mask:0xf bank_mask:0xf bound_ctrl:1
	v_xor_b32_e32 v157, v181, v198
	v_add_f32_dpp v227, v114, v103 quad_perm:[2,3,0,1] row_mask:0xf bank_mask:0xf bound_ctrl:1
	v_xor_b32_e32 v103, v189, v104
	v_add_f32_dpp v157, v198, v157 quad_perm:[1,0,3,2] row_mask:0xf bank_mask:0xf bound_ctrl:1
	v_lshlrev_b32_e32 v105, 16, v70
	v_add_f32_dpp v228, v104, v103 quad_perm:[2,3,0,1] row_mask:0xf bank_mask:0xf bound_ctrl:1
	v_xor_b32_e32 v103, v189, v102
	v_max_f32_e64 v104, |v206|, |v207|
	v_and_b32_e32 v115, 0xffff0000, v70
	v_add_f32_dpp v229, v102, v103 quad_perm:[2,3,0,1] row_mask:0xf bank_mask:0xf bound_ctrl:1
	v_xor_b32_e32 v102, v189, v157
	v_max_f32_e64 v103, |v202|, |v203|
	v_and_b32_e32 v114, 0xffff0000, v66
	v_add_f32_dpp v230, v157, v102 quad_perm:[2,3,0,1] row_mask:0xf bank_mask:0xf bound_ctrl:1
	v_xor_b32_e32 v102, v189, v146
	v_lshlrev_b32_e32 v116, 16, v67
	v_lshlrev_b32_e32 v117, 16, v71
	v_add_f32_dpp v231, v146, v102 quad_perm:[2,3,0,1] row_mask:0xf bank_mask:0xf bound_ctrl:1
	v_max_f32_e64 v102, |v200|, |v201|
	v_max3_f32 v102, v193, v102, v103
	v_max_f32_e64 v103, |v204|, |v205|
	v_max3_f32 v102, v102, v103, v104
	v_max_f32_e64 v103, |v216|, |v225|
	v_max_f32_e64 v104, |v226|, |v227|
	v_max3_f32 v102, v102, v103, v104
	v_max_f32_e64 v103, |v228|, |v229|
	v_max_f32_e64 v104, |v230|, |v231|
	v_max3_f32 v193, v102, v103, v104
	v_and_b32_e32 v103, 0xffff0000, v73
	v_and_b32_e32 v102, 0xffff0000, v69
	v_lshlrev_b32_e32 v104, 16, v66
	v_and_b32_e32 v71, 0xffff0000, v71
	v_and_b32_e32 v70, 0xffff0000, v67
	v_lshlrev_b32_e32 v67, 16, v72
	v_lshlrev_b32_e32 v66, 16, v68
	v_and_b32_e32 v147, 0xffff0000, v72
	v_and_b32_e32 v146, 0xffff0000, v68
	v_lshlrev_b32_e32 v68, 16, v69
	v_lshlrev_b32_e32 v69, 16, v73
	v_pk_add_f32 v[72:73], v[104:105], v[114:115]
	v_pk_add_f32 v[148:149], v[116:117], v[70:71]
	v_pk_add_f32 v[154:155], v[66:67], v[146:147]
	v_pk_add_f32 v[156:157], v[68:69], v[102:103]
	v_pk_add_f32 v[104:105], v[104:105], v[114:115] neg_lo:[0,1] neg_hi:[0,1]
	v_pk_add_f32 v[70:71], v[116:117], v[70:71] neg_lo:[0,1] neg_hi:[0,1]
	v_pk_add_f32 v[66:67], v[66:67], v[146:147] neg_lo:[0,1] neg_hi:[0,1]
	v_pk_add_f32 v[68:69], v[68:69], v[102:103] neg_lo:[0,1] neg_hi:[0,1]
	v_pk_add_f32 v[186:187], v[72:73], v[148:149] neg_lo:[0,1] neg_hi:[0,1]
	v_pk_add_f32 v[194:195], v[154:155], v[156:157] neg_lo:[0,1] neg_hi:[0,1]
	v_pk_add_f32 v[72:73], v[72:73], v[148:149]
	v_pk_add_f32 v[148:149], v[154:155], v[156:157]
	v_pk_add_f32 v[102:103], v[104:105], v[70:71] neg_lo:[0,1] neg_hi:[0,1]
	v_pk_add_f32 v[114:115], v[66:67], v[68:69] neg_lo:[0,1] neg_hi:[0,1]
	v_pk_add_f32 v[70:71], v[104:105], v[70:71]
	v_pk_add_f32 v[66:67], v[66:67], v[68:69]
	v_pk_add_f32 v[154:155], v[72:73], v[148:149]
	v_pk_add_f32 v[72:73], v[72:73], v[148:149] neg_lo:[0,1] neg_hi:[0,1]
	v_pk_add_f32 v[148:149], v[186:187], v[194:195]
	v_pk_add_f32 v[68:69], v[70:71], v[66:67]
	v_pk_add_f32 v[66:67], v[70:71], v[66:67] neg_lo:[0,1] neg_hi:[0,1]
	v_pk_add_f32 v[70:71], v[102:103], v[114:115]
	v_pk_add_f32 v[156:157], v[186:187], v[194:195] neg_lo:[0,1] neg_hi:[0,1]
	v_pk_add_f32 v[102:103], v[102:103], v[114:115] neg_lo:[0,1] neg_hi:[0,1]
	v_pk_add_f32 v[104:105], v[154:155], v[154:155] op_sel:[0,1] op_sel_hi:[1,0]
	v_pk_add_f32 v[114:115], v[154:155], v[154:155] op_sel:[0,1] op_sel_hi:[1,0] neg_lo:[0,1] neg_hi:[0,1]
	v_pk_add_f32 v[146:147], v[148:149], v[148:149] op_sel:[0,1] op_sel_hi:[1,0]
	v_pk_add_f32 v[154:155], v[70:71], v[70:71] op_sel:[0,1] op_sel_hi:[1,0]
	v_pk_add_f32 v[70:71], v[70:71], v[70:71] op_sel:[0,1] op_sel_hi:[1,0] neg_lo:[0,1] neg_hi:[0,1]
	v_pk_add_f32 v[194:195], v[66:67], v[66:67] op_sel:[0,1] op_sel_hi:[1,0]
	v_pk_add_f32 v[66:67], v[66:67], v[66:67] op_sel:[0,1] op_sel_hi:[1,0] neg_lo:[0,1] neg_hi:[0,1]
	v_pk_add_f32 v[116:117], v[68:69], v[68:69] op_sel:[0,1] op_sel_hi:[1,0]
	v_pk_add_f32 v[68:69], v[68:69], v[68:69] op_sel:[0,1] op_sel_hi:[1,0] neg_lo:[0,1] neg_hi:[0,1]
	v_pk_add_f32 v[198:199], v[102:103], v[102:103] op_sel:[0,1] op_sel_hi:[1,0]
	v_pk_add_f32 v[102:103], v[102:103], v[102:103] op_sel:[0,1] op_sel_hi:[1,0] neg_lo:[0,1] neg_hi:[0,1]
	v_xor_b32_e32 v67, v181, v104
	v_xor_b32_e32 v71, v181, v146
	v_xor_b32_e32 v69, v181, v116
	v_add_f32_dpp v67, v104, v67 quad_perm:[1,0,3,2] row_mask:0xf bank_mask:0xf bound_ctrl:1
	v_add_f32_dpp v71, v146, v71 quad_perm:[1,0,3,2] row_mask:0xf bank_mask:0xf bound_ctrl:1
	v_xor_b32_e32 v146, v181, v102
	v_pk_add_f32 v[186:187], v[72:73], v[72:73] op_sel:[0,1] op_sel_hi:[1,0]
	v_pk_add_f32 v[72:73], v[72:73], v[72:73] op_sel:[0,1] op_sel_hi:[1,0] neg_lo:[0,1] neg_hi:[0,1]
	v_add_f32_dpp v69, v116, v69 quad_perm:[1,0,3,2] row_mask:0xf bank_mask:0xf bound_ctrl:1
	v_add_f32_dpp v102, v102, v146 quad_perm:[1,0,3,2] row_mask:0xf bank_mask:0xf bound_ctrl:1
	v_xor_b32_e32 v146, v189, v67
	v_xor_b32_e32 v73, v181, v154
	v_xor_b32_e32 v103, v181, v186
	v_add_f32_dpp v67, v67, v146 quad_perm:[2,3,0,1] row_mask:0xf bank_mask:0xf bound_ctrl:1
	v_xor_b32_e32 v146, v189, v69
	v_add_f32_dpp v73, v154, v73 quad_perm:[1,0,3,2] row_mask:0xf bank_mask:0xf bound_ctrl:1
	v_pk_add_f32 v[196:197], v[156:157], v[156:157] op_sel:[0,1] op_sel_hi:[1,0]
	v_add_f32_dpp v69, v69, v146 quad_perm:[2,3,0,1] row_mask:0xf bank_mask:0xf bound_ctrl:1
	v_xor_b32_e32 v146, v189, v71
	v_add_f32_dpp v103, v186, v103 quad_perm:[1,0,3,2] row_mask:0xf bank_mask:0xf bound_ctrl:1
	v_xor_b32_e32 v104, v181, v194
	v_add_f32_dpp v71, v71, v146 quad_perm:[2,3,0,1] row_mask:0xf bank_mask:0xf bound_ctrl:1
	v_xor_b32_e32 v146, v189, v73
	v_add_f32_dpp v104, v194, v104 quad_perm:[1,0,3,2] row_mask:0xf bank_mask:0xf bound_ctrl:1
	v_xor_b32_e32 v105, v181, v196
	v_add_f32_dpp v73, v73, v146 quad_perm:[2,3,0,1] row_mask:0xf bank_mask:0xf bound_ctrl:1
	v_xor_b32_e32 v146, v189, v103
	v_add_f32_dpp v105, v196, v105 quad_perm:[1,0,3,2] row_mask:0xf bank_mask:0xf bound_ctrl:1
	v_xor_b32_e32 v115, v181, v198
	v_add_f32_dpp v186, v103, v146 quad_perm:[2,3,0,1] row_mask:0xf bank_mask:0xf bound_ctrl:1
	v_xor_b32_e32 v103, v189, v104
	v_add_f32_dpp v115, v198, v115 quad_perm:[1,0,3,2] row_mask:0xf bank_mask:0xf bound_ctrl:1
	v_xor_b32_e32 v116, v181, v114
	v_add_f32_dpp v187, v104, v103 quad_perm:[2,3,0,1] row_mask:0xf bank_mask:0xf bound_ctrl:1
	v_xor_b32_e32 v103, v189, v105
	v_pk_add_f32 v[148:149], v[148:149], v[148:149] op_sel:[0,1] op_sel_hi:[1,0] neg_lo:[0,1] neg_hi:[0,1]
	v_add_f32_dpp v114, v114, v116 quad_perm:[1,0,3,2] row_mask:0xf bank_mask:0xf bound_ctrl:1
	v_xor_b32_e32 v116, v181, v68
	v_add_f32_dpp v198, v105, v103 quad_perm:[2,3,0,1] row_mask:0xf bank_mask:0xf bound_ctrl:1
	v_xor_b32_e32 v103, v189, v115
	v_add_f32_dpp v68, v68, v116 quad_perm:[1,0,3,2] row_mask:0xf bank_mask:0xf bound_ctrl:1
	v_xor_b32_e32 v116, v181, v148
	v_add_f32_dpp v199, v115, v103 quad_perm:[2,3,0,1] row_mask:0xf bank_mask:0xf bound_ctrl:1
	v_xor_b32_e32 v103, v189, v114
	v_add_f32_dpp v116, v148, v116 quad_perm:[1,0,3,2] row_mask:0xf bank_mask:0xf bound_ctrl:1
	v_xor_b32_e32 v117, v181, v70
	v_add_f32_dpp v232, v114, v103 quad_perm:[2,3,0,1] row_mask:0xf bank_mask:0xf bound_ctrl:1
	v_xor_b32_e32 v103, v189, v68
	v_add_f32_dpp v70, v70, v117 quad_perm:[1,0,3,2] row_mask:0xf bank_mask:0xf bound_ctrl:1
	v_xor_b32_e32 v117, v181, v72
	v_add_f32_dpp v233, v68, v103 quad_perm:[2,3,0,1] row_mask:0xf bank_mask:0xf bound_ctrl:1
	v_xor_b32_e32 v68, v189, v116
	v_pk_add_f32 v[156:157], v[156:157], v[156:157] op_sel:[0,1] op_sel_hi:[1,0] neg_lo:[0,1] neg_hi:[0,1]
	v_add_f32_dpp v72, v72, v117 quad_perm:[1,0,3,2] row_mask:0xf bank_mask:0xf bound_ctrl:1
	v_xor_b32_e32 v117, v181, v66
	v_add_f32_dpp v235, v116, v68 quad_perm:[2,3,0,1] row_mask:0xf bank_mask:0xf bound_ctrl:1
	v_xor_b32_e32 v68, v189, v70
	v_add_f32_dpp v66, v66, v117 quad_perm:[1,0,3,2] row_mask:0xf bank_mask:0xf bound_ctrl:1
	v_xor_b32_e32 v117, v181, v156
	v_add_f32_dpp v236, v70, v68 quad_perm:[2,3,0,1] row_mask:0xf bank_mask:0xf bound_ctrl:1
	v_xor_b32_e32 v68, v189, v72
	v_add_f32_dpp v117, v156, v117 quad_perm:[1,0,3,2] row_mask:0xf bank_mask:0xf bound_ctrl:1
	v_max_f32_e64 v70, |v198|, |v199|
	v_add_f32_dpp v72, v72, v68 quad_perm:[2,3,0,1] row_mask:0xf bank_mask:0xf bound_ctrl:1
	v_xor_b32_e32 v68, v189, v66
	v_cvt_pk_bf16_f32 v146, v208, v209
	v_cvt_pk_bf16_f32 v147, v210, v211
	v_cvt_pk_bf16_f32 v148, v212, v213
	v_cvt_pk_bf16_f32 v149, v214, v215
	v_cvt_pk_bf16_f32 v154, v217, v218
	s_nop 1
	v_add_f32_dpp v237, v66, v68 quad_perm:[2,3,0,1] row_mask:0xf bank_mask:0xf bound_ctrl:1
	v_xor_b32_e32 v66, v189, v117
	v_max_f32_e64 v68, |v71|, |v73|
	v_cvt_pk_bf16_f32 v155, v219, v220
	v_cvt_pk_bf16_f32 v156, v221, v222
	v_cvt_pk_bf16_f32 v157, v223, v224
	s_nop 0
	v_add_f32_dpp v238, v117, v66 quad_perm:[2,3,0,1] row_mask:0xf bank_mask:0xf bound_ctrl:1
	v_xor_b32_e32 v66, v189, v102
	s_nop 1
	v_add_f32_dpp v239, v102, v66 quad_perm:[2,3,0,1] row_mask:0xf bank_mask:0xf bound_ctrl:1
	v_max_f32_e64 v66, |v67|, |v69|
	v_max3_f32 v66, v193, v66, v68
	v_max_f32_e64 v68, |v186|, |v187|
	v_max3_f32 v66, v66, v68, v70
	v_max_f32_e64 v68, |v232|, |v233|
	v_max_f32_e64 v70, |v235|, |v236|
	v_max3_f32 v66, v66, v68, v70
	v_max_f32_e64 v68, |v72|, |v237|
	v_max_f32_e64 v70, |v238|, |v239|
	v_max3_f32 v66, v66, v68, v70
	v_and_b32_e32 v68, 64, v190
	v_add_u32_e32 v70, 64, v68
	v_xor_b32_e32 v68, 1, v190
	v_cmp_lt_i32_e32 vcc, v68, v70
	v_cvt_pk_bf16_f32 v102, v200, v201
	v_cvt_pk_bf16_f32 v103, v202, v203
	v_cvt_pk_bf16_f32 v104, v204, v205
	v_cvt_pk_bf16_f32 v105, v206, v207
	v_cvt_pk_bf16_f32 v114, v216, v225
	s_nop 1
	v_cndmask_b32_e32 v68, v190, v68, vcc
	v_lshlrev_b32_e32 v193, 2, v68
	v_cvt_pk_bf16_f32 v115, v226, v227
	v_cvt_pk_bf16_f32 v116, v228, v229
	v_cvt_pk_bf16_f32 v117, v230, v231
	s_waitcnt lgkmcnt(0)
	s_nop 1
	v_max_f32_dpp v66, v66, v66 quad_perm:[1,0,3,2] row_mask:0xf bank_mask:0xf
	v_xor_b32_e32 v68, 2, v190
	v_cmp_lt_i32_e32 vcc, v68, v70
	s_nop 1
	v_cndmask_b32_e32 v68, v190, v68, vcc
	v_lshlrev_b32_e32 v194, 2, v68
	s_waitcnt lgkmcnt(0)
	s_nop 1
	v_max_f32_dpp v66, v66, v66 quad_perm:[2,3,0,1] row_mask:0xf bank_mask:0xf
	v_xor_b32_e32 v68, 4, v190
	v_cmp_lt_i32_e32 vcc, v68, v70
	s_nop 1
	v_cndmask_b32_e32 v68, v190, v68, vcc
	v_lshlrev_b32_e32 v195, 2, v68
	s_waitcnt lgkmcnt(0)
	s_nop 1
	v_max_f32_dpp v66, v66, v66 row_half_mirror row_mask:0xf bank_mask:0xf
	v_xor_b32_e32 v68, 8, v190
	v_cmp_lt_i32_e32 vcc, v68, v70
	s_nop 1
	v_cndmask_b32_e32 v68, v190, v68, vcc
	v_lshlrev_b32_e32 v196, 2, v68
	s_waitcnt lgkmcnt(0)
	s_nop 1
	v_max_f32_dpp v200, v66, v66 row_mirror row_mask:0xf bank_mask:0xf
	v_xor_b32_e32 v66, 16, v190
	v_cmp_lt_i32_e32 vcc, v66, v70
	s_nop 1
	v_cndmask_b32_e32 v66, v190, v66, vcc
	v_lshlrev_b32_e32 v197, 2, v66
	ds_bpermute_b32 v201, v197, v200
	v_cvt_pk_bf16_f32 v66, v67, v69
	v_cvt_pk_bf16_f32 v67, v71, v73
	v_cvt_pk_bf16_f32 v68, v186, v187
	v_cvt_pk_bf16_f32 v69, v198, v199
	s_waitcnt lgkmcnt(0)
	v_max_f32_e32 v71, v201, v201
	v_max_f32_e32 v186, v200, v71
	v_xor_b32_e32 v71, 32, v190
	v_cmp_lt_i32_e32 vcc, v71, v70
	s_nop 1
	v_cndmask_b32_e32 v70, v190, v71, vcc
	v_lshlrev_b32_e32 v198, 2, v70
	v_cvt_pk_bf16_f32 v70, v232, v233
	v_cvt_pk_bf16_f32 v71, v235, v236
	v_cvt_pk_bf16_f32 v72, v72, v237
	v_cvt_pk_bf16_f32 v73, v238, v239
	s_waitcnt lgkmcnt(0)
	v_mov_b32_e32 v187, v186
	s_nop 1
	v_permlane32_swap_b32_e32 v187, v186
	v_max_f32_e32 v186, v186, v187
	s_and_saveexec_b64 s[34:35], s[2:3]
	s_cbranch_execz .LBB0_1010
	s_lshl_b64 s[46:47], s[30:31], 2
	s_sub_u32 s46, s37, s46
	s_subb_u32 s47, s38, s47
	v_mul_f32_e32 v187, 0x3a810204, v186
	global_store_dword v179, v187, s[46:47]

.LBB0_1017:
	v_lshlrev_b32_e32 v187, 16, v78
	v_lshlrev_b32_e32 v186, 16, v74
	v_and_b32_e32 v201, 0xffff0000, v78
	v_and_b32_e32 v200, 0xffff0000, v74
	v_lshlrev_b32_e32 v202, 16, v75
	v_lshlrev_b32_e32 v203, 16, v79
	v_and_b32_e32 v79, 0xffff0000, v79
	v_and_b32_e32 v78, 0xffff0000, v75
	v_lshlrev_b32_e32 v75, 16, v80
	v_lshlrev_b32_e32 v74, 16, v76
	v_and_b32_e32 v205, 0xffff0000, v80
	v_and_b32_e32 v204, 0xffff0000, v76
	v_lshlrev_b32_e32 v206, 16, v77
	v_lshlrev_b32_e32 v207, 16, v81
	v_and_b32_e32 v81, 0xffff0000, v81
	v_and_b32_e32 v80, 0xffff0000, v77
	v_pk_add_f32 v[76:77], v[186:187], v[200:201]
	v_pk_add_f32 v[208:209], v[202:203], v[78:79]
	v_pk_add_f32 v[210:211], v[74:75], v[204:205]
	v_pk_add_f32 v[212:213], v[206:207], v[80:81]
	v_pk_add_f32 v[186:187], v[186:187], v[200:201] neg_lo:[0,1] neg_hi:[0,1]
	v_pk_add_f32 v[78:79], v[202:203], v[78:79] neg_lo:[0,1] neg_hi:[0,1]
	v_pk_add_f32 v[74:75], v[74:75], v[204:205] neg_lo:[0,1] neg_hi:[0,1]
	v_pk_add_f32 v[80:81], v[206:207], v[80:81] neg_lo:[0,1] neg_hi:[0,1]
	v_pk_add_f32 v[214:215], v[76:77], v[208:209] neg_lo:[0,1] neg_hi:[0,1]
	v_pk_add_f32 v[76:77], v[76:77], v[208:209]
	v_pk_add_f32 v[208:209], v[210:211], v[212:213]
	v_pk_add_f32 v[200:201], v[186:187], v[78:79] neg_lo:[0,1] neg_hi:[0,1]
	v_pk_add_f32 v[202:203], v[74:75], v[80:81] neg_lo:[0,1] neg_hi:[0,1]
	v_pk_add_f32 v[78:79], v[186:187], v[78:79]
	v_pk_add_f32 v[74:75], v[74:75], v[80:81]
	v_pk_add_f32 v[216:217], v[210:211], v[212:213] neg_lo:[0,1] neg_hi:[0,1]
	v_pk_add_f32 v[210:211], v[76:77], v[208:209]
	v_pk_add_f32 v[80:81], v[78:79], v[74:75]
	v_pk_add_f32 v[74:75], v[78:79], v[74:75] neg_lo:[0,1] neg_hi:[0,1]
	v_pk_add_f32 v[76:77], v[76:77], v[208:209] neg_lo:[0,1] neg_hi:[0,1]
	v_pk_add_f32 v[208:209], v[214:215], v[216:217]
	v_pk_add_f32 v[212:213], v[214:215], v[216:217] neg_lo:[0,1] neg_hi:[0,1]
	v_pk_add_f32 v[78:79], v[200:201], v[202:203]
	v_pk_add_f32 v[186:187], v[200:201], v[202:203] neg_lo:[0,1] neg_hi:[0,1]
	v_pk_add_f32 v[200:201], v[210:211], v[210:211] op_sel:[1,0] op_sel_hi:[0,1]
	v_pk_add_f32 v[216:217], v[74:75], v[74:75] op_sel:[1,0] op_sel_hi:[0,1]
	v_pk_add_f32 v[74:75], v[74:75], v[74:75] op_sel:[0,1] op_sel_hi:[1,0] neg_lo:[0,1] neg_hi:[0,1]
	v_pk_add_f32 v[204:205], v[80:81], v[80:81] op_sel:[1,0] op_sel_hi:[0,1]
	v_pk_add_f32 v[214:215], v[76:77], v[76:77] op_sel:[1,0] op_sel_hi:[0,1]
	v_pk_add_f32 v[76:77], v[76:77], v[76:77] op_sel:[0,1] op_sel_hi:[1,0] neg_lo:[0,1] neg_hi:[0,1]
	v_pk_add_f32 v[220:221], v[186:187], v[186:187] op_sel:[1,0] op_sel_hi:[0,1]
	v_pk_add_f32 v[186:187], v[186:187], v[186:187] op_sel:[0,1] op_sel_hi:[1,0] neg_lo:[0,1] neg_hi:[0,1]
	v_xor_b32_e32 v75, v181, v200
	v_pk_add_f32 v[202:203], v[210:211], v[210:211] op_sel:[0,1] op_sel_hi:[1,0] neg_lo:[0,1] neg_hi:[0,1]
	v_pk_add_f32 v[206:207], v[208:209], v[208:209] op_sel:[1,0] op_sel_hi:[0,1]
	v_pk_add_f32 v[210:211], v[78:79], v[78:79] op_sel:[1,0] op_sel_hi:[0,1]
	v_pk_add_f32 v[78:79], v[78:79], v[78:79] op_sel:[0,1] op_sel_hi:[1,0] neg_lo:[0,1] neg_hi:[0,1]
	v_add_f32_dpp v75, v200, v75 quad_perm:[1,0,3,2] row_mask:0xf bank_mask:0xf bound_ctrl:1
	v_xor_b32_e32 v77, v181, v204
	v_xor_b32_e32 v205, v181, v186
	v_pk_add_f32 v[80:81], v[80:81], v[80:81] op_sel:[0,1] op_sel_hi:[1,0] neg_lo:[0,1] neg_hi:[0,1]
	v_add_f32_dpp v77, v204, v77 quad_perm:[1,0,3,2] row_mask:0xf bank_mask:0xf bound_ctrl:1
	v_xor_b32_e32 v79, v181, v206
	v_add_f32_dpp v186, v186, v205 quad_perm:[1,0,3,2] row_mask:0xf bank_mask:0xf bound_ctrl:1
	v_xor_b32_e32 v205, v189, v75
	v_add_f32_dpp v79, v206, v79 quad_perm:[1,0,3,2] row_mask:0xf bank_mask:0xf bound_ctrl:1
	v_xor_b32_e32 v81, v181, v210
	v_add_f32_dpp v75, v75, v205 quad_perm:[2,3,0,1] row_mask:0xf bank_mask:0xf bound_ctrl:1
	v_xor_b32_e32 v205, v189, v77
	v_add_f32_dpp v81, v210, v81 quad_perm:[1,0,3,2] row_mask:0xf bank_mask:0xf bound_ctrl:1
	v_xor_b32_e32 v187, v181, v214
	v_add_f32_dpp v77, v77, v205 quad_perm:[2,3,0,1] row_mask:0xf bank_mask:0xf bound_ctrl:1
	v_xor_b32_e32 v205, v189, v79
	v_pk_add_f32 v[218:219], v[212:213], v[212:213] op_sel:[1,0] op_sel_hi:[0,1]
	v_add_f32_dpp v187, v214, v187 quad_perm:[1,0,3,2] row_mask:0xf bank_mask:0xf bound_ctrl:1
	v_xor_b32_e32 v199, v181, v216
	v_add_f32_dpp v79, v79, v205 quad_perm:[2,3,0,1] row_mask:0xf bank_mask:0xf bound_ctrl:1
	v_xor_b32_e32 v205, v189, v81
	v_add_f32_dpp v199, v216, v199 quad_perm:[1,0,3,2] row_mask:0xf bank_mask:0xf bound_ctrl:1
	v_xor_b32_e32 v200, v181, v218
	v_add_f32_dpp v81, v81, v205 quad_perm:[2,3,0,1] row_mask:0xf bank_mask:0xf bound_ctrl:1
	v_xor_b32_e32 v205, v189, v187
	v_add_f32_dpp v200, v218, v200 quad_perm:[1,0,3,2] row_mask:0xf bank_mask:0xf bound_ctrl:1
	v_xor_b32_e32 v201, v181, v220
	v_add_f32_dpp v187, v187, v205 quad_perm:[2,3,0,1] row_mask:0xf bank_mask:0xf bound_ctrl:1
	v_xor_b32_e32 v205, v189, v199
	v_add_f32_dpp v201, v220, v201 quad_perm:[1,0,3,2] row_mask:0xf bank_mask:0xf bound_ctrl:1
	v_xor_b32_e32 v203, v181, v202
	v_add_f32_dpp v199, v199, v205 quad_perm:[2,3,0,1] row_mask:0xf bank_mask:0xf bound_ctrl:1
	v_xor_b32_e32 v205, v189, v200
	v_pk_add_f32 v[208:209], v[208:209], v[208:209] op_sel:[0,1] op_sel_hi:[1,0] neg_lo:[0,1] neg_hi:[0,1]
	v_add_f32_dpp v202, v202, v203 quad_perm:[1,0,3,2] row_mask:0xf bank_mask:0xf bound_ctrl:1
	v_xor_b32_e32 v203, v181, v80
	v_add_f32_dpp v200, v200, v205 quad_perm:[2,3,0,1] row_mask:0xf bank_mask:0xf bound_ctrl:1
	v_xor_b32_e32 v205, v189, v201
	v_add_f32_dpp v80, v80, v203 quad_perm:[1,0,3,2] row_mask:0xf bank_mask:0xf bound_ctrl:1
	v_xor_b32_e32 v203, v181, v208
	v_add_f32_dpp v201, v201, v205 quad_perm:[2,3,0,1] row_mask:0xf bank_mask:0xf bound_ctrl:1
	v_xor_b32_e32 v205, v189, v202
	v_add_f32_dpp v203, v208, v203 quad_perm:[1,0,3,2] row_mask:0xf bank_mask:0xf bound_ctrl:1
	v_xor_b32_e32 v204, v181, v78
	v_add_f32_dpp v202, v202, v205 quad_perm:[2,3,0,1] row_mask:0xf bank_mask:0xf bound_ctrl:1
	v_xor_b32_e32 v205, v189, v80
	v_add_f32_dpp v78, v78, v204 quad_perm:[1,0,3,2] row_mask:0xf bank_mask:0xf bound_ctrl:1
	v_xor_b32_e32 v204, v181, v76
	v_add_f32_dpp v80, v80, v205 quad_perm:[2,3,0,1] row_mask:0xf bank_mask:0xf bound_ctrl:1
	v_xor_b32_e32 v205, v189, v203
	v_pk_add_f32 v[212:213], v[212:213], v[212:213] op_sel:[0,1] op_sel_hi:[1,0] neg_lo:[0,1] neg_hi:[0,1]
	v_add_f32_dpp v76, v76, v204 quad_perm:[1,0,3,2] row_mask:0xf bank_mask:0xf bound_ctrl:1
	v_xor_b32_e32 v204, v181, v74
	v_add_f32_dpp v203, v203, v205 quad_perm:[2,3,0,1] row_mask:0xf bank_mask:0xf bound_ctrl:1
	v_xor_b32_e32 v205, v189, v78
	v_add_f32_dpp v74, v74, v204 quad_perm:[1,0,3,2] row_mask:0xf bank_mask:0xf bound_ctrl:1
	v_xor_b32_e32 v204, v181, v212
	v_add_f32_dpp v205, v78, v205 quad_perm:[2,3,0,1] row_mask:0xf bank_mask:0xf bound_ctrl:1
	v_xor_b32_e32 v78, v189, v76
	v_add_f32_dpp v204, v212, v204 quad_perm:[1,0,3,2] row_mask:0xf bank_mask:0xf bound_ctrl:1
	s_ashr_i32 s27, s26, 31
	v_add_f32_dpp v206, v76, v78 quad_perm:[2,3,0,1] row_mask:0xf bank_mask:0xf bound_ctrl:1
	v_xor_b32_e32 v76, v189, v74
	v_max_f32_e64 v78, |v200|, |v201|
	s_nop 0
	v_add_f32_dpp v207, v74, v76 quad_perm:[2,3,0,1] row_mask:0xf bank_mask:0xf bound_ctrl:1
	v_xor_b32_e32 v74, v189, v204
	v_max_f32_e64 v76, |v79|, |v81|
	s_nop 0
	v_add_f32_dpp v204, v204, v74 quad_perm:[2,3,0,1] row_mask:0xf bank_mask:0xf bound_ctrl:1
	v_xor_b32_e32 v74, v189, v186
	s_nop 1
	v_add_f32_dpp v186, v186, v74 quad_perm:[2,3,0,1] row_mask:0xf bank_mask:0xf bound_ctrl:1
	v_max_f32_e64 v74, |v75|, |v77|
	v_max3_f32 v74, v74, 0, v76
	v_max_f32_e64 v76, |v187|, |v199|
	v_max3_f32 v74, v74, v76, v78
	v_max_f32_e64 v76, |v202|, |v80|
	v_max_f32_e64 v78, |v203|, |v205|
	v_max3_f32 v74, v74, v76, v78
	v_max_f32_e64 v76, |v206|, |v207|
	v_max_f32_e64 v78, |v204|, |v186|
	v_max3_f32 v222, v74, v76, v78
	v_cvt_pk_bf16_f32 v74, v75, v77
	v_cvt_pk_bf16_f32 v75, v79, v81
	v_cvt_pk_bf16_f32 v76, v187, v199
	v_cvt_pk_bf16_f32 v77, v200, v201
	v_cvt_pk_bf16_f32 v78, v202, v80
	v_cvt_pk_bf16_f32 v79, v203, v205
	v_cvt_pk_bf16_f32 v80, v206, v207
	v_cvt_pk_bf16_f32 v81, v204, v186
	v_and_b32_e32 v187, 0xffff0000, v89
	v_and_b32_e32 v186, 0xffff0000, v85
	v_lshlrev_b32_e32 v201, 16, v86
	v_lshlrev_b32_e32 v200, 16, v82
	v_and_b32_e32 v203, 0xffff0000, v86
	v_and_b32_e32 v202, 0xffff0000, v82
	v_lshlrev_b32_e32 v204, 16, v83
	v_lshlrev_b32_e32 v205, 16, v87
	v_and_b32_e32 v87, 0xffff0000, v87
	v_and_b32_e32 v86, 0xffff0000, v83
	v_lshlrev_b32_e32 v83, 16, v88
	v_lshlrev_b32_e32 v82, 16, v84
	v_and_b32_e32 v207, 0xffff0000, v88
	v_and_b32_e32 v206, 0xffff0000, v84
	v_lshlrev_b32_e32 v84, 16, v85
	v_lshlrev_b32_e32 v85, 16, v89
	v_pk_add_f32 v[88:89], v[200:201], v[202:203]
	v_pk_add_f32 v[208:209], v[204:205], v[86:87]
	v_pk_add_f32 v[210:211], v[82:83], v[206:207]
	v_pk_add_f32 v[212:213], v[84:85], v[186:187]
	v_pk_add_f32 v[200:201], v[200:201], v[202:203] neg_lo:[0,1] neg_hi:[0,1]
	v_pk_add_f32 v[86:87], v[204:205], v[86:87] neg_lo:[0,1] neg_hi:[0,1]
	v_pk_add_f32 v[82:83], v[82:83], v[206:207] neg_lo:[0,1] neg_hi:[0,1]
	v_pk_add_f32 v[84:85], v[84:85], v[186:187] neg_lo:[0,1] neg_hi:[0,1]
	v_pk_add_f32 v[214:215], v[88:89], v[208:209] neg_lo:[0,1] neg_hi:[0,1]
	v_pk_add_f32 v[88:89], v[88:89], v[208:209]
	v_pk_add_f32 v[208:209], v[210:211], v[212:213]
	v_pk_add_f32 v[186:187], v[200:201], v[86:87] neg_lo:[0,1] neg_hi:[0,1]
	v_pk_add_f32 v[202:203], v[82:83], v[84:85] neg_lo:[0,1] neg_hi:[0,1]
	v_pk_add_f32 v[86:87], v[200:201], v[86:87]
	v_pk_add_f32 v[82:83], v[82:83], v[84:85]
	v_pk_add_f32 v[216:217], v[210:211], v[212:213] neg_lo:[0,1] neg_hi:[0,1]
	v_pk_add_f32 v[210:211], v[88:89], v[208:209]
	v_pk_add_f32 v[84:85], v[86:87], v[82:83]
	v_pk_add_f32 v[82:83], v[86:87], v[82:83] neg_lo:[0,1] neg_hi:[0,1]
	v_pk_add_f32 v[88:89], v[88:89], v[208:209] neg_lo:[0,1] neg_hi:[0,1]
	v_pk_add_f32 v[208:209], v[214:215], v[216:217]
	v_pk_add_f32 v[212:213], v[214:215], v[216:217] neg_lo:[0,1] neg_hi:[0,1]
	v_pk_add_f32 v[86:87], v[186:187], v[202:203]
	v_pk_add_f32 v[186:187], v[186:187], v[202:203] neg_lo:[0,1] neg_hi:[0,1]
	v_pk_add_f32 v[200:201], v[210:211], v[210:211] op_sel:[1,0] op_sel_hi:[0,1]
	v_pk_add_f32 v[216:217], v[82:83], v[82:83] op_sel:[1,0] op_sel_hi:[0,1]
	v_pk_add_f32 v[82:83], v[82:83], v[82:83] op_sel:[0,1] op_sel_hi:[1,0] neg_lo:[0,1] neg_hi:[0,1]
	v_pk_add_f32 v[204:205], v[84:85], v[84:85] op_sel:[1,0] op_sel_hi:[0,1]
	v_pk_add_f32 v[84:85], v[84:85], v[84:85] op_sel:[0,1] op_sel_hi:[1,0] neg_lo:[0,1] neg_hi:[0,1]
	v_pk_add_f32 v[220:221], v[186:187], v[186:187] op_sel:[1,0] op_sel_hi:[0,1]
	v_pk_add_f32 v[186:187], v[186:187], v[186:187] op_sel:[0,1] op_sel_hi:[1,0] neg_lo:[0,1] neg_hi:[0,1]
	v_xor_b32_e32 v83, v181, v200
	v_pk_add_f32 v[202:203], v[210:211], v[210:211] op_sel:[0,1] op_sel_hi:[1,0] neg_lo:[0,1] neg_hi:[0,1]
	v_pk_add_f32 v[206:207], v[208:209], v[208:209] op_sel:[1,0] op_sel_hi:[0,1]
	v_pk_add_f32 v[210:211], v[86:87], v[86:87] op_sel:[1,0] op_sel_hi:[0,1]
	v_pk_add_f32 v[86:87], v[86:87], v[86:87] op_sel:[0,1] op_sel_hi:[1,0] neg_lo:[0,1] neg_hi:[0,1]
	v_add_f32_dpp v83, v200, v83 quad_perm:[1,0,3,2] row_mask:0xf bank_mask:0xf bound_ctrl:1
	v_xor_b32_e32 v85, v181, v204
	v_xor_b32_e32 v205, v181, v186
	v_pk_add_f32 v[214:215], v[88:89], v[88:89] op_sel:[1,0] op_sel_hi:[0,1]
	v_pk_add_f32 v[88:89], v[88:89], v[88:89] op_sel:[0,1] op_sel_hi:[1,0] neg_lo:[0,1] neg_hi:[0,1]
	v_add_f32_dpp v85, v204, v85 quad_perm:[1,0,3,2] row_mask:0xf bank_mask:0xf bound_ctrl:1
	v_xor_b32_e32 v87, v181, v206
	v_add_f32_dpp v186, v186, v205 quad_perm:[1,0,3,2] row_mask:0xf bank_mask:0xf bound_ctrl:1
	v_xor_b32_e32 v205, v189, v83
	v_add_f32_dpp v87, v206, v87 quad_perm:[1,0,3,2] row_mask:0xf bank_mask:0xf bound_ctrl:1
	v_xor_b32_e32 v89, v181, v210
	v_add_f32_dpp v83, v83, v205 quad_perm:[2,3,0,1] row_mask:0xf bank_mask:0xf bound_ctrl:1
	v_xor_b32_e32 v205, v189, v85
	v_add_f32_dpp v89, v210, v89 quad_perm:[1,0,3,2] row_mask:0xf bank_mask:0xf bound_ctrl:1
	v_xor_b32_e32 v187, v181, v214
	v_add_f32_dpp v85, v85, v205 quad_perm:[2,3,0,1] row_mask:0xf bank_mask:0xf bound_ctrl:1
	v_xor_b32_e32 v205, v189, v87
	v_pk_add_f32 v[218:219], v[212:213], v[212:213] op_sel:[1,0] op_sel_hi:[0,1]
	v_add_f32_dpp v187, v214, v187 quad_perm:[1,0,3,2] row_mask:0xf bank_mask:0xf bound_ctrl:1
	v_xor_b32_e32 v199, v181, v216
	v_add_f32_dpp v87, v87, v205 quad_perm:[2,3,0,1] row_mask:0xf bank_mask:0xf bound_ctrl:1
	v_xor_b32_e32 v205, v189, v89
	v_add_f32_dpp v199, v216, v199 quad_perm:[1,0,3,2] row_mask:0xf bank_mask:0xf bound_ctrl:1
	v_xor_b32_e32 v200, v181, v218
	v_add_f32_dpp v89, v89, v205 quad_perm:[2,3,0,1] row_mask:0xf bank_mask:0xf bound_ctrl:1
	v_xor_b32_e32 v205, v189, v187
	v_add_f32_dpp v200, v218, v200 quad_perm:[1,0,3,2] row_mask:0xf bank_mask:0xf bound_ctrl:1
	v_xor_b32_e32 v201, v181, v220
	v_add_f32_dpp v187, v187, v205 quad_perm:[2,3,0,1] row_mask:0xf bank_mask:0xf bound_ctrl:1
	v_xor_b32_e32 v205, v189, v199
	v_add_f32_dpp v201, v220, v201 quad_perm:[1,0,3,2] row_mask:0xf bank_mask:0xf bound_ctrl:1
	v_xor_b32_e32 v203, v181, v202
	v_add_f32_dpp v199, v199, v205 quad_perm:[2,3,0,1] row_mask:0xf bank_mask:0xf bound_ctrl:1
	v_xor_b32_e32 v205, v189, v200
	v_pk_add_f32 v[208:209], v[208:209], v[208:209] op_sel:[0,1] op_sel_hi:[1,0] neg_lo:[0,1] neg_hi:[0,1]
	v_add_f32_dpp v202, v202, v203 quad_perm:[1,0,3,2] row_mask:0xf bank_mask:0xf bound_ctrl:1
	v_xor_b32_e32 v203, v181, v84
	v_add_f32_dpp v200, v200, v205 quad_perm:[2,3,0,1] row_mask:0xf bank_mask:0xf bound_ctrl:1
	v_xor_b32_e32 v205, v189, v201
	v_add_f32_dpp v84, v84, v203 quad_perm:[1,0,3,2] row_mask:0xf bank_mask:0xf bound_ctrl:1
	v_xor_b32_e32 v203, v181, v208
	v_add_f32_dpp v201, v201, v205 quad_perm:[2,3,0,1] row_mask:0xf bank_mask:0xf bound_ctrl:1
	v_xor_b32_e32 v205, v189, v202
	v_add_f32_dpp v203, v208, v203 quad_perm:[1,0,3,2] row_mask:0xf bank_mask:0xf bound_ctrl:1
	v_xor_b32_e32 v204, v181, v86
	v_add_f32_dpp v202, v202, v205 quad_perm:[2,3,0,1] row_mask:0xf bank_mask:0xf bound_ctrl:1
	v_xor_b32_e32 v205, v189, v84
	v_add_f32_dpp v86, v86, v204 quad_perm:[1,0,3,2] row_mask:0xf bank_mask:0xf bound_ctrl:1
	v_xor_b32_e32 v204, v181, v88
	v_add_f32_dpp v205, v84, v205 quad_perm:[2,3,0,1] row_mask:0xf bank_mask:0xf bound_ctrl:1
	v_xor_b32_e32 v84, v189, v203
	v_pk_add_f32 v[212:213], v[212:213], v[212:213] op_sel:[0,1] op_sel_hi:[1,0] neg_lo:[0,1] neg_hi:[0,1]
	v_add_f32_dpp v88, v88, v204 quad_perm:[1,0,3,2] row_mask:0xf bank_mask:0xf bound_ctrl:1
	v_xor_b32_e32 v204, v181, v82
	v_add_f32_dpp v203, v203, v84 quad_perm:[2,3,0,1] row_mask:0xf bank_mask:0xf bound_ctrl:1
	v_xor_b32_e32 v84, v189, v86
	v_add_f32_dpp v82, v82, v204 quad_perm:[1,0,3,2] row_mask:0xf bank_mask:0xf bound_ctrl:1
	v_xor_b32_e32 v204, v181, v212
	v_add_f32_dpp v206, v86, v84 quad_perm:[2,3,0,1] row_mask:0xf bank_mask:0xf bound_ctrl:1
	v_xor_b32_e32 v84, v189, v88
	v_add_f32_dpp v204, v212, v204 quad_perm:[1,0,3,2] row_mask:0xf bank_mask:0xf bound_ctrl:1
	v_max_f32_e64 v86, |v200|, |v201|
	v_add_f32_dpp v88, v88, v84 quad_perm:[2,3,0,1] row_mask:0xf bank_mask:0xf bound_ctrl:1
	v_xor_b32_e32 v84, v189, v82
	s_nop 1
	v_add_f32_dpp v207, v82, v84 quad_perm:[2,3,0,1] row_mask:0xf bank_mask:0xf bound_ctrl:1
	v_xor_b32_e32 v82, v189, v204
	v_max_f32_e64 v84, |v87|, |v89|
	s_nop 0
	v_add_f32_dpp v204, v204, v82 quad_perm:[2,3,0,1] row_mask:0xf bank_mask:0xf bound_ctrl:1
	v_xor_b32_e32 v82, v189, v186
	s_nop 1
	v_add_f32_dpp v186, v186, v82 quad_perm:[2,3,0,1] row_mask:0xf bank_mask:0xf bound_ctrl:1
	v_max_f32_e64 v82, |v83|, |v85|
	v_max3_f32 v82, v222, v82, v84
	v_max_f32_e64 v84, |v187|, |v199|
	v_max3_f32 v82, v82, v84, v86
	v_max_f32_e64 v84, |v202|, |v205|
	v_max_f32_e64 v86, |v203|, |v206|
	v_max3_f32 v82, v82, v84, v86
	v_max_f32_e64 v84, |v88|, |v207|
	v_max_f32_e64 v86, |v204|, |v186|
	v_max3_f32 v222, v82, v84, v86
	v_cvt_pk_bf16_f32 v82, v83, v85
	v_cvt_pk_bf16_f32 v83, v87, v89
	v_cvt_pk_bf16_f32 v84, v187, v199
	v_cvt_pk_bf16_f32 v85, v200, v201
	v_cvt_pk_bf16_f32 v86, v202, v205
	v_cvt_pk_bf16_f32 v87, v203, v206
	v_cvt_pk_bf16_f32 v88, v88, v207
	v_cvt_pk_bf16_f32 v89, v204, v186
	v_and_b32_e32 v187, 0xffff0000, v97
	v_and_b32_e32 v186, 0xffff0000, v93
	v_lshlrev_b32_e32 v201, 16, v94
	v_lshlrev_b32_e32 v200, 16, v90
	v_and_b32_e32 v203, 0xffff0000, v94
	v_and_b32_e32 v202, 0xffff0000, v90
	v_lshlrev_b32_e32 v204, 16, v91
	v_lshlrev_b32_e32 v205, 16, v95
	v_and_b32_e32 v95, 0xffff0000, v95
	v_and_b32_e32 v94, 0xffff0000, v91
	v_lshlrev_b32_e32 v91, 16, v96
	v_lshlrev_b32_e32 v90, 16, v92
	v_and_b32_e32 v207, 0xffff0000, v96
	v_and_b32_e32 v206, 0xffff0000, v92
	v_lshlrev_b32_e32 v92, 16, v93
	v_lshlrev_b32_e32 v93, 16, v97
	v_pk_add_f32 v[96:97], v[200:201], v[202:203]
	v_pk_add_f32 v[208:209], v[204:205], v[94:95]
	v_pk_add_f32 v[210:211], v[90:91], v[206:207]
	v_pk_add_f32 v[212:213], v[92:93], v[186:187]
	v_pk_add_f32 v[200:201], v[200:201], v[202:203] neg_lo:[0,1] neg_hi:[0,1]
	v_pk_add_f32 v[94:95], v[204:205], v[94:95] neg_lo:[0,1] neg_hi:[0,1]
	v_pk_add_f32 v[90:91], v[90:91], v[206:207] neg_lo:[0,1] neg_hi:[0,1]
	v_pk_add_f32 v[92:93], v[92:93], v[186:187] neg_lo:[0,1] neg_hi:[0,1]
	v_pk_add_f32 v[214:215], v[96:97], v[208:209] neg_lo:[0,1] neg_hi:[0,1]
	v_pk_add_f32 v[96:97], v[96:97], v[208:209]
	v_pk_add_f32 v[208:209], v[210:211], v[212:213]
	v_pk_add_f32 v[186:187], v[200:201], v[94:95] neg_lo:[0,1] neg_hi:[0,1]
	v_pk_add_f32 v[202:203], v[90:91], v[92:93] neg_lo:[0,1] neg_hi:[0,1]
	v_pk_add_f32 v[94:95], v[200:201], v[94:95]
	v_pk_add_f32 v[90:91], v[90:91], v[92:93]
	v_pk_add_f32 v[216:217], v[210:211], v[212:213] neg_lo:[0,1] neg_hi:[0,1]
	v_pk_add_f32 v[210:211], v[96:97], v[208:209]
	v_pk_add_f32 v[92:93], v[94:95], v[90:91]
	v_pk_add_f32 v[90:91], v[94:95], v[90:91] neg_lo:[0,1] neg_hi:[0,1]
	v_pk_add_f32 v[96:97], v[96:97], v[208:209] neg_lo:[0,1] neg_hi:[0,1]
	v_pk_add_f32 v[208:209], v[214:215], v[216:217]
	v_pk_add_f32 v[212:213], v[214:215], v[216:217] neg_lo:[0,1] neg_hi:[0,1]
	v_pk_add_f32 v[94:95], v[186:187], v[202:203]
	v_pk_add_f32 v[186:187], v[186:187], v[202:203] neg_lo:[0,1] neg_hi:[0,1]
	v_pk_add_f32 v[200:201], v[210:211], v[210:211] op_sel:[1,0] op_sel_hi:[0,1]
	v_pk_add_f32 v[216:217], v[90:91], v[90:91] op_sel:[1,0] op_sel_hi:[0,1]
	v_pk_add_f32 v[90:91], v[90:91], v[90:91] op_sel:[0,1] op_sel_hi:[1,0] neg_lo:[0,1] neg_hi:[0,1]
	v_pk_add_f32 v[204:205], v[92:93], v[92:93] op_sel:[1,0] op_sel_hi:[0,1]
	v_pk_add_f32 v[92:93], v[92:93], v[92:93] op_sel:[0,1] op_sel_hi:[1,0] neg_lo:[0,1] neg_hi:[0,1]
	v_pk_add_f32 v[220:221], v[186:187], v[186:187] op_sel:[1,0] op_sel_hi:[0,1]
	v_pk_add_f32 v[186:187], v[186:187], v[186:187] op_sel:[0,1] op_sel_hi:[1,0] neg_lo:[0,1] neg_hi:[0,1]
	v_xor_b32_e32 v91, v181, v200
	v_pk_add_f32 v[202:203], v[210:211], v[210:211] op_sel:[0,1] op_sel_hi:[1,0] neg_lo:[0,1] neg_hi:[0,1]
	v_pk_add_f32 v[206:207], v[208:209], v[208:209] op_sel:[1,0] op_sel_hi:[0,1]
	v_pk_add_f32 v[210:211], v[94:95], v[94:95] op_sel:[1,0] op_sel_hi:[0,1]
	v_pk_add_f32 v[94:95], v[94:95], v[94:95] op_sel:[0,1] op_sel_hi:[1,0] neg_lo:[0,1] neg_hi:[0,1]
	v_add_f32_dpp v91, v200, v91 quad_perm:[1,0,3,2] row_mask:0xf bank_mask:0xf bound_ctrl:1
	v_xor_b32_e32 v93, v181, v204
	v_xor_b32_e32 v205, v181, v186
	v_pk_add_f32 v[214:215], v[96:97], v[96:97] op_sel:[1,0] op_sel_hi:[0,1]
	v_pk_add_f32 v[96:97], v[96:97], v[96:97] op_sel:[0,1] op_sel_hi:[1,0] neg_lo:[0,1] neg_hi:[0,1]
	v_add_f32_dpp v93, v204, v93 quad_perm:[1,0,3,2] row_mask:0xf bank_mask:0xf bound_ctrl:1
	v_xor_b32_e32 v95, v181, v206
	v_add_f32_dpp v186, v186, v205 quad_perm:[1,0,3,2] row_mask:0xf bank_mask:0xf bound_ctrl:1
	v_xor_b32_e32 v205, v189, v91
	v_add_f32_dpp v95, v206, v95 quad_perm:[1,0,3,2] row_mask:0xf bank_mask:0xf bound_ctrl:1
	v_xor_b32_e32 v97, v181, v210
	v_add_f32_dpp v91, v91, v205 quad_perm:[2,3,0,1] row_mask:0xf bank_mask:0xf bound_ctrl:1
	v_xor_b32_e32 v205, v189, v93
	v_add_f32_dpp v97, v210, v97 quad_perm:[1,0,3,2] row_mask:0xf bank_mask:0xf bound_ctrl:1
	v_xor_b32_e32 v187, v181, v214
	v_add_f32_dpp v93, v93, v205 quad_perm:[2,3,0,1] row_mask:0xf bank_mask:0xf bound_ctrl:1
	v_xor_b32_e32 v205, v189, v95
	v_pk_add_f32 v[218:219], v[212:213], v[212:213] op_sel:[1,0] op_sel_hi:[0,1]
	v_add_f32_dpp v187, v214, v187 quad_perm:[1,0,3,2] row_mask:0xf bank_mask:0xf bound_ctrl:1
	v_xor_b32_e32 v199, v181, v216
	v_add_f32_dpp v95, v95, v205 quad_perm:[2,3,0,1] row_mask:0xf bank_mask:0xf bound_ctrl:1
	v_xor_b32_e32 v205, v189, v97
	v_add_f32_dpp v199, v216, v199 quad_perm:[1,0,3,2] row_mask:0xf bank_mask:0xf bound_ctrl:1
	v_xor_b32_e32 v200, v181, v218
	v_add_f32_dpp v97, v97, v205 quad_perm:[2,3,0,1] row_mask:0xf bank_mask:0xf bound_ctrl:1
	v_xor_b32_e32 v205, v189, v187
	v_add_f32_dpp v200, v218, v200 quad_perm:[1,0,3,2] row_mask:0xf bank_mask:0xf bound_ctrl:1
	v_xor_b32_e32 v201, v181, v220
	v_add_f32_dpp v187, v187, v205 quad_perm:[2,3,0,1] row_mask:0xf bank_mask:0xf bound_ctrl:1
	v_xor_b32_e32 v205, v189, v199
	v_add_f32_dpp v201, v220, v201 quad_perm:[1,0,3,2] row_mask:0xf bank_mask:0xf bound_ctrl:1
	v_xor_b32_e32 v203, v181, v202
	v_add_f32_dpp v199, v199, v205 quad_perm:[2,3,0,1] row_mask:0xf bank_mask:0xf bound_ctrl:1
	v_xor_b32_e32 v205, v189, v200
	v_pk_add_f32 v[208:209], v[208:209], v[208:209] op_sel:[0,1] op_sel_hi:[1,0] neg_lo:[0,1] neg_hi:[0,1]
	v_add_f32_dpp v202, v202, v203 quad_perm:[1,0,3,2] row_mask:0xf bank_mask:0xf bound_ctrl:1
	v_xor_b32_e32 v203, v181, v92
	v_add_f32_dpp v200, v200, v205 quad_perm:[2,3,0,1] row_mask:0xf bank_mask:0xf bound_ctrl:1
	v_xor_b32_e32 v205, v189, v201
	v_add_f32_dpp v92, v92, v203 quad_perm:[1,0,3,2] row_mask:0xf bank_mask:0xf bound_ctrl:1
	v_xor_b32_e32 v203, v181, v208
	v_add_f32_dpp v201, v201, v205 quad_perm:[2,3,0,1] row_mask:0xf bank_mask:0xf bound_ctrl:1
	v_xor_b32_e32 v205, v189, v202
	v_add_f32_dpp v203, v208, v203 quad_perm:[1,0,3,2] row_mask:0xf bank_mask:0xf bound_ctrl:1
	v_xor_b32_e32 v204, v181, v94
	v_add_f32_dpp v202, v202, v205 quad_perm:[2,3,0,1] row_mask:0xf bank_mask:0xf bound_ctrl:1
	v_xor_b32_e32 v205, v189, v92
	v_add_f32_dpp v94, v94, v204 quad_perm:[1,0,3,2] row_mask:0xf bank_mask:0xf bound_ctrl:1
	v_xor_b32_e32 v204, v181, v96
	v_add_f32_dpp v205, v92, v205 quad_perm:[2,3,0,1] row_mask:0xf bank_mask:0xf bound_ctrl:1
	v_xor_b32_e32 v92, v189, v203
	v_pk_add_f32 v[212:213], v[212:213], v[212:213] op_sel:[0,1] op_sel_hi:[1,0] neg_lo:[0,1] neg_hi:[0,1]
	v_add_f32_dpp v96, v96, v204 quad_perm:[1,0,3,2] row_mask:0xf bank_mask:0xf bound_ctrl:1
	v_xor_b32_e32 v204, v181, v90
	v_add_f32_dpp v203, v203, v92 quad_perm:[2,3,0,1] row_mask:0xf bank_mask:0xf bound_ctrl:1
	v_xor_b32_e32 v92, v189, v94
	v_add_f32_dpp v90, v90, v204 quad_perm:[1,0,3,2] row_mask:0xf bank_mask:0xf bound_ctrl:1
	v_xor_b32_e32 v204, v181, v212
	v_add_f32_dpp v206, v94, v92 quad_perm:[2,3,0,1] row_mask:0xf bank_mask:0xf bound_ctrl:1
	v_xor_b32_e32 v92, v189, v96
	v_add_f32_dpp v204, v212, v204 quad_perm:[1,0,3,2] row_mask:0xf bank_mask:0xf bound_ctrl:1
	v_max_f32_e64 v94, |v200|, |v201|
	v_add_f32_dpp v96, v96, v92 quad_perm:[2,3,0,1] row_mask:0xf bank_mask:0xf bound_ctrl:1
	v_xor_b32_e32 v92, v189, v90
	s_nop 1
	v_add_f32_dpp v207, v90, v92 quad_perm:[2,3,0,1] row_mask:0xf bank_mask:0xf bound_ctrl:1
	v_xor_b32_e32 v90, v189, v204
	v_max_f32_e64 v92, |v95|, |v97|
	s_nop 0
	v_add_f32_dpp v204, v204, v90 quad_perm:[2,3,0,1] row_mask:0xf bank_mask:0xf bound_ctrl:1
	v_xor_b32_e32 v90, v189, v186
	s_nop 1
	v_add_f32_dpp v186, v186, v90 quad_perm:[2,3,0,1] row_mask:0xf bank_mask:0xf bound_ctrl:1
	v_max_f32_e64 v90, |v91|, |v93|
	v_max3_f32 v90, v222, v90, v92
	v_max_f32_e64 v92, |v187|, |v199|
	v_max3_f32 v90, v90, v92, v94
	v_max_f32_e64 v92, |v202|, |v205|
	v_max_f32_e64 v94, |v203|, |v206|
	v_max3_f32 v90, v90, v92, v94
	v_max_f32_e64 v92, |v96|, |v207|
	v_max_f32_e64 v94, |v204|, |v186|
	v_max3_f32 v222, v90, v92, v94
	v_cvt_pk_bf16_f32 v90, v91, v93
	v_cvt_pk_bf16_f32 v91, v95, v97
	v_cvt_pk_bf16_f32 v92, v187, v199
	v_cvt_pk_bf16_f32 v93, v200, v201
	v_cvt_pk_bf16_f32 v94, v202, v205
	v_cvt_pk_bf16_f32 v95, v203, v206
	v_cvt_pk_bf16_f32 v96, v96, v207
	v_cvt_pk_bf16_f32 v97, v204, v186
	v_and_b32_e32 v187, 0xffff0000, v109
	v_and_b32_e32 v186, 0xffff0000, v101
	v_lshlrev_b32_e32 v201, 16, v106
	v_lshlrev_b32_e32 v200, 16, v98
	v_and_b32_e32 v203, 0xffff0000, v106
	v_and_b32_e32 v202, 0xffff0000, v98
	v_lshlrev_b32_e32 v204, 16, v99
	v_lshlrev_b32_e32 v205, 16, v107
	v_and_b32_e32 v107, 0xffff0000, v107
	v_and_b32_e32 v106, 0xffff0000, v99
	v_lshlrev_b32_e32 v99, 16, v108
	v_lshlrev_b32_e32 v98, 16, v100
	v_and_b32_e32 v207, 0xffff0000, v108
	v_and_b32_e32 v206, 0xffff0000, v100
	v_lshlrev_b32_e32 v100, 16, v101
	v_lshlrev_b32_e32 v101, 16, v109
	v_pk_add_f32 v[108:109], v[200:201], v[202:203]
	v_pk_add_f32 v[208:209], v[204:205], v[106:107]
	v_pk_add_f32 v[210:211], v[98:99], v[206:207]
	v_pk_add_f32 v[212:213], v[100:101], v[186:187]
	v_pk_add_f32 v[200:201], v[200:201], v[202:203] neg_lo:[0,1] neg_hi:[0,1]
	v_pk_add_f32 v[106:107], v[204:205], v[106:107] neg_lo:[0,1] neg_hi:[0,1]
	v_pk_add_f32 v[98:99], v[98:99], v[206:207] neg_lo:[0,1] neg_hi:[0,1]
	v_pk_add_f32 v[100:101], v[100:101], v[186:187] neg_lo:[0,1] neg_hi:[0,1]
	v_pk_add_f32 v[214:215], v[108:109], v[208:209] neg_lo:[0,1] neg_hi:[0,1]
	v_pk_add_f32 v[108:109], v[108:109], v[208:209]
	v_pk_add_f32 v[208:209], v[210:211], v[212:213]
	v_pk_add_f32 v[186:187], v[200:201], v[106:107] neg_lo:[0,1] neg_hi:[0,1]
	v_pk_add_f32 v[202:203], v[98:99], v[100:101] neg_lo:[0,1] neg_hi:[0,1]
	v_pk_add_f32 v[106:107], v[200:201], v[106:107]
	v_pk_add_f32 v[98:99], v[98:99], v[100:101]
	v_pk_add_f32 v[216:217], v[210:211], v[212:213] neg_lo:[0,1] neg_hi:[0,1]
	v_pk_add_f32 v[210:211], v[108:109], v[208:209]
	v_pk_add_f32 v[100:101], v[106:107], v[98:99]
	v_pk_add_f32 v[98:99], v[106:107], v[98:99] neg_lo:[0,1] neg_hi:[0,1]
	v_pk_add_f32 v[108:109], v[108:109], v[208:209] neg_lo:[0,1] neg_hi:[0,1]
	v_pk_add_f32 v[208:209], v[214:215], v[216:217]
	v_pk_add_f32 v[212:213], v[214:215], v[216:217] neg_lo:[0,1] neg_hi:[0,1]
	v_pk_add_f32 v[106:107], v[186:187], v[202:203]
	v_pk_add_f32 v[186:187], v[186:187], v[202:203] neg_lo:[0,1] neg_hi:[0,1]
	v_pk_add_f32 v[200:201], v[210:211], v[210:211] op_sel:[1,0] op_sel_hi:[0,1]
	v_pk_add_f32 v[216:217], v[98:99], v[98:99] op_sel:[1,0] op_sel_hi:[0,1]
	v_pk_add_f32 v[98:99], v[98:99], v[98:99] op_sel:[0,1] op_sel_hi:[1,0] neg_lo:[0,1] neg_hi:[0,1]
	v_pk_add_f32 v[204:205], v[100:101], v[100:101] op_sel:[1,0] op_sel_hi:[0,1]
	v_pk_add_f32 v[100:101], v[100:101], v[100:101] op_sel:[0,1] op_sel_hi:[1,0] neg_lo:[0,1] neg_hi:[0,1]
	v_pk_add_f32 v[220:221], v[186:187], v[186:187] op_sel:[1,0] op_sel_hi:[0,1]
	v_pk_add_f32 v[186:187], v[186:187], v[186:187] op_sel:[0,1] op_sel_hi:[1,0] neg_lo:[0,1] neg_hi:[0,1]
	v_xor_b32_e32 v99, v181, v200
	v_pk_add_f32 v[202:203], v[210:211], v[210:211] op_sel:[0,1] op_sel_hi:[1,0] neg_lo:[0,1] neg_hi:[0,1]
	v_pk_add_f32 v[206:207], v[208:209], v[208:209] op_sel:[1,0] op_sel_hi:[0,1]
	v_pk_add_f32 v[210:211], v[106:107], v[106:107] op_sel:[1,0] op_sel_hi:[0,1]
	v_pk_add_f32 v[106:107], v[106:107], v[106:107] op_sel:[0,1] op_sel_hi:[1,0] neg_lo:[0,1] neg_hi:[0,1]
	v_add_f32_dpp v99, v200, v99 quad_perm:[1,0,3,2] row_mask:0xf bank_mask:0xf bound_ctrl:1
	v_xor_b32_e32 v101, v181, v204
	v_xor_b32_e32 v205, v181, v186
	v_pk_add_f32 v[214:215], v[108:109], v[108:109] op_sel:[1,0] op_sel_hi:[0,1]
	v_pk_add_f32 v[108:109], v[108:109], v[108:109] op_sel:[0,1] op_sel_hi:[1,0] neg_lo:[0,1] neg_hi:[0,1]
	v_add_f32_dpp v101, v204, v101 quad_perm:[1,0,3,2] row_mask:0xf bank_mask:0xf bound_ctrl:1
	v_xor_b32_e32 v107, v181, v206
	v_add_f32_dpp v186, v186, v205 quad_perm:[1,0,3,2] row_mask:0xf bank_mask:0xf bound_ctrl:1
	v_xor_b32_e32 v205, v189, v99
	v_add_f32_dpp v107, v206, v107 quad_perm:[1,0,3,2] row_mask:0xf bank_mask:0xf bound_ctrl:1
	v_xor_b32_e32 v109, v181, v210
	v_add_f32_dpp v99, v99, v205 quad_perm:[2,3,0,1] row_mask:0xf bank_mask:0xf bound_ctrl:1
	v_xor_b32_e32 v205, v189, v101
	v_add_f32_dpp v109, v210, v109 quad_perm:[1,0,3,2] row_mask:0xf bank_mask:0xf bound_ctrl:1
	v_xor_b32_e32 v187, v181, v214
	v_add_f32_dpp v101, v101, v205 quad_perm:[2,3,0,1] row_mask:0xf bank_mask:0xf bound_ctrl:1
	v_xor_b32_e32 v205, v189, v107
	v_pk_add_f32 v[218:219], v[212:213], v[212:213] op_sel:[1,0] op_sel_hi:[0,1]
	v_add_f32_dpp v187, v214, v187 quad_perm:[1,0,3,2] row_mask:0xf bank_mask:0xf bound_ctrl:1
	v_xor_b32_e32 v199, v181, v216
	v_add_f32_dpp v107, v107, v205 quad_perm:[2,3,0,1] row_mask:0xf bank_mask:0xf bound_ctrl:1
	v_xor_b32_e32 v205, v189, v109
	v_add_f32_dpp v199, v216, v199 quad_perm:[1,0,3,2] row_mask:0xf bank_mask:0xf bound_ctrl:1
	v_xor_b32_e32 v200, v181, v218
	v_add_f32_dpp v109, v109, v205 quad_perm:[2,3,0,1] row_mask:0xf bank_mask:0xf bound_ctrl:1
	v_xor_b32_e32 v205, v189, v187
	v_add_f32_dpp v200, v218, v200 quad_perm:[1,0,3,2] row_mask:0xf bank_mask:0xf bound_ctrl:1
	v_xor_b32_e32 v201, v181, v220
	v_add_f32_dpp v187, v187, v205 quad_perm:[2,3,0,1] row_mask:0xf bank_mask:0xf bound_ctrl:1
	v_xor_b32_e32 v205, v189, v199
	v_add_f32_dpp v201, v220, v201 quad_perm:[1,0,3,2] row_mask:0xf bank_mask:0xf bound_ctrl:1
	v_xor_b32_e32 v203, v181, v202
	v_add_f32_dpp v199, v199, v205 quad_perm:[2,3,0,1] row_mask:0xf bank_mask:0xf bound_ctrl:1
	v_xor_b32_e32 v205, v189, v200
	v_pk_add_f32 v[208:209], v[208:209], v[208:209] op_sel:[0,1] op_sel_hi:[1,0] neg_lo:[0,1] neg_hi:[0,1]
	v_add_f32_dpp v202, v202, v203 quad_perm:[1,0,3,2] row_mask:0xf bank_mask:0xf bound_ctrl:1
	v_xor_b32_e32 v203, v181, v100
	v_add_f32_dpp v200, v200, v205 quad_perm:[2,3,0,1] row_mask:0xf bank_mask:0xf bound_ctrl:1
	v_xor_b32_e32 v205, v189, v201
	v_add_f32_dpp v100, v100, v203 quad_perm:[1,0,3,2] row_mask:0xf bank_mask:0xf bound_ctrl:1
	v_xor_b32_e32 v203, v181, v208
	v_add_f32_dpp v201, v201, v205 quad_perm:[2,3,0,1] row_mask:0xf bank_mask:0xf bound_ctrl:1
	v_xor_b32_e32 v205, v189, v202
	v_add_f32_dpp v203, v208, v203 quad_perm:[1,0,3,2] row_mask:0xf bank_mask:0xf bound_ctrl:1
	v_xor_b32_e32 v204, v181, v106
	v_add_f32_dpp v202, v202, v205 quad_perm:[2,3,0,1] row_mask:0xf bank_mask:0xf bound_ctrl:1
	v_xor_b32_e32 v205, v189, v100
	v_add_f32_dpp v106, v106, v204 quad_perm:[1,0,3,2] row_mask:0xf bank_mask:0xf bound_ctrl:1
	v_xor_b32_e32 v204, v181, v108
	v_add_f32_dpp v205, v100, v205 quad_perm:[2,3,0,1] row_mask:0xf bank_mask:0xf bound_ctrl:1
	v_xor_b32_e32 v100, v189, v203
	v_pk_add_f32 v[212:213], v[212:213], v[212:213] op_sel:[0,1] op_sel_hi:[1,0] neg_lo:[0,1] neg_hi:[0,1]
	v_add_f32_dpp v108, v108, v204 quad_perm:[1,0,3,2] row_mask:0xf bank_mask:0xf bound_ctrl:1
	v_xor_b32_e32 v204, v181, v98
	v_add_f32_dpp v203, v203, v100 quad_perm:[2,3,0,1] row_mask:0xf bank_mask:0xf bound_ctrl:1
	v_xor_b32_e32 v100, v189, v106
	v_add_f32_dpp v98, v98, v204 quad_perm:[1,0,3,2] row_mask:0xf bank_mask:0xf bound_ctrl:1
	v_xor_b32_e32 v204, v181, v212
	v_add_f32_dpp v206, v106, v100 quad_perm:[2,3,0,1] row_mask:0xf bank_mask:0xf bound_ctrl:1
	v_xor_b32_e32 v100, v189, v108
	v_add_f32_dpp v204, v212, v204 quad_perm:[1,0,3,2] row_mask:0xf bank_mask:0xf bound_ctrl:1
	v_max_f32_e64 v106, |v200|, |v201|
	v_add_f32_dpp v108, v108, v100 quad_perm:[2,3,0,1] row_mask:0xf bank_mask:0xf bound_ctrl:1
	v_xor_b32_e32 v100, v189, v98
	s_nop 1
	v_add_f32_dpp v207, v98, v100 quad_perm:[2,3,0,1] row_mask:0xf bank_mask:0xf bound_ctrl:1
	v_xor_b32_e32 v98, v189, v204
	v_max_f32_e64 v100, |v107|, |v109|
	s_nop 0
	v_add_f32_dpp v204, v204, v98 quad_perm:[2,3,0,1] row_mask:0xf bank_mask:0xf bound_ctrl:1
	v_xor_b32_e32 v98, v189, v186
	s_nop 1
	v_add_f32_dpp v186, v186, v98 quad_perm:[2,3,0,1] row_mask:0xf bank_mask:0xf bound_ctrl:1
	v_max_f32_e64 v98, |v99|, |v101|
	v_max3_f32 v98, v222, v98, v100
	v_max_f32_e64 v100, |v187|, |v199|
	v_max3_f32 v98, v98, v100, v106
	v_max_f32_e64 v100, |v202|, |v205|
	v_max_f32_e64 v106, |v203|, |v206|
	v_max3_f32 v98, v98, v100, v106
	v_max_f32_e64 v100, |v108|, |v207|
	v_max_f32_e64 v106, |v204|, |v186|
	v_max3_f32 v222, v98, v100, v106
	v_cvt_pk_bf16_f32 v98, v99, v101
	v_cvt_pk_bf16_f32 v99, v107, v109
	v_cvt_pk_bf16_f32 v100, v187, v199
	v_cvt_pk_bf16_f32 v101, v200, v201
	v_cvt_pk_bf16_f32 v106, v202, v205
	v_cvt_pk_bf16_f32 v107, v203, v206
	v_cvt_pk_bf16_f32 v108, v108, v207
	v_cvt_pk_bf16_f32 v109, v204, v186
	v_and_b32_e32 v187, 0xffff0000, v121
	v_and_b32_e32 v186, 0xffff0000, v113
	v_lshlrev_b32_e32 v201, 16, v118
	v_lshlrev_b32_e32 v200, 16, v110
	v_and_b32_e32 v203, 0xffff0000, v118
	v_and_b32_e32 v202, 0xffff0000, v110
	v_lshlrev_b32_e32 v204, 16, v111
	v_lshlrev_b32_e32 v205, 16, v119
	v_and_b32_e32 v119, 0xffff0000, v119
	v_and_b32_e32 v118, 0xffff0000, v111
	v_lshlrev_b32_e32 v111, 16, v120
	v_lshlrev_b32_e32 v110, 16, v112
	v_and_b32_e32 v207, 0xffff0000, v120
	v_and_b32_e32 v206, 0xffff0000, v112
	v_lshlrev_b32_e32 v112, 16, v113
	v_lshlrev_b32_e32 v113, 16, v121
	v_pk_add_f32 v[120:121], v[200:201], v[202:203]
	v_pk_add_f32 v[208:209], v[204:205], v[118:119]
	v_pk_add_f32 v[210:211], v[110:111], v[206:207]
	v_pk_add_f32 v[212:213], v[112:113], v[186:187]
	v_pk_add_f32 v[200:201], v[200:201], v[202:203] neg_lo:[0,1] neg_hi:[0,1]
	v_pk_add_f32 v[118:119], v[204:205], v[118:119] neg_lo:[0,1] neg_hi:[0,1]
	v_pk_add_f32 v[110:111], v[110:111], v[206:207] neg_lo:[0,1] neg_hi:[0,1]
	v_pk_add_f32 v[112:113], v[112:113], v[186:187] neg_lo:[0,1] neg_hi:[0,1]
	v_pk_add_f32 v[214:215], v[120:121], v[208:209] neg_lo:[0,1] neg_hi:[0,1]
	v_pk_add_f32 v[120:121], v[120:121], v[208:209]
	v_pk_add_f32 v[208:209], v[210:211], v[212:213]
	v_pk_add_f32 v[186:187], v[200:201], v[118:119] neg_lo:[0,1] neg_hi:[0,1]
	v_pk_add_f32 v[202:203], v[110:111], v[112:113] neg_lo:[0,1] neg_hi:[0,1]
	v_pk_add_f32 v[118:119], v[200:201], v[118:119]
	v_pk_add_f32 v[110:111], v[110:111], v[112:113]
	v_pk_add_f32 v[216:217], v[210:211], v[212:213] neg_lo:[0,1] neg_hi:[0,1]
	v_pk_add_f32 v[210:211], v[120:121], v[208:209]
	v_pk_add_f32 v[112:113], v[118:119], v[110:111]
	v_pk_add_f32 v[110:111], v[118:119], v[110:111] neg_lo:[0,1] neg_hi:[0,1]
	v_pk_add_f32 v[120:121], v[120:121], v[208:209] neg_lo:[0,1] neg_hi:[0,1]
	v_pk_add_f32 v[208:209], v[214:215], v[216:217]
	v_pk_add_f32 v[212:213], v[214:215], v[216:217] neg_lo:[0,1] neg_hi:[0,1]
	v_pk_add_f32 v[118:119], v[186:187], v[202:203]
	v_pk_add_f32 v[186:187], v[186:187], v[202:203] neg_lo:[0,1] neg_hi:[0,1]
	v_pk_add_f32 v[200:201], v[210:211], v[210:211] op_sel:[1,0] op_sel_hi:[0,1]
	v_pk_add_f32 v[216:217], v[110:111], v[110:111] op_sel:[1,0] op_sel_hi:[0,1]
	v_pk_add_f32 v[110:111], v[110:111], v[110:111] op_sel:[0,1] op_sel_hi:[1,0] neg_lo:[0,1] neg_hi:[0,1]
	v_pk_add_f32 v[204:205], v[112:113], v[112:113] op_sel:[1,0] op_sel_hi:[0,1]
	v_pk_add_f32 v[112:113], v[112:113], v[112:113] op_sel:[0,1] op_sel_hi:[1,0] neg_lo:[0,1] neg_hi:[0,1]
	v_pk_add_f32 v[220:221], v[186:187], v[186:187] op_sel:[1,0] op_sel_hi:[0,1]
	v_pk_add_f32 v[186:187], v[186:187], v[186:187] op_sel:[0,1] op_sel_hi:[1,0] neg_lo:[0,1] neg_hi:[0,1]
	v_xor_b32_e32 v111, v181, v200
	v_pk_add_f32 v[202:203], v[210:211], v[210:211] op_sel:[0,1] op_sel_hi:[1,0] neg_lo:[0,1] neg_hi:[0,1]
	v_pk_add_f32 v[206:207], v[208:209], v[208:209] op_sel:[1,0] op_sel_hi:[0,1]
	v_pk_add_f32 v[210:211], v[118:119], v[118:119] op_sel:[1,0] op_sel_hi:[0,1]
	v_pk_add_f32 v[118:119], v[118:119], v[118:119] op_sel:[0,1] op_sel_hi:[1,0] neg_lo:[0,1] neg_hi:[0,1]
	v_add_f32_dpp v111, v200, v111 quad_perm:[1,0,3,2] row_mask:0xf bank_mask:0xf bound_ctrl:1
	v_xor_b32_e32 v113, v181, v204
	v_xor_b32_e32 v205, v181, v186
	v_pk_add_f32 v[214:215], v[120:121], v[120:121] op_sel:[1,0] op_sel_hi:[0,1]
	v_pk_add_f32 v[120:121], v[120:121], v[120:121] op_sel:[0,1] op_sel_hi:[1,0] neg_lo:[0,1] neg_hi:[0,1]
	v_add_f32_dpp v113, v204, v113 quad_perm:[1,0,3,2] row_mask:0xf bank_mask:0xf bound_ctrl:1
	v_xor_b32_e32 v119, v181, v206
	v_add_f32_dpp v186, v186, v205 quad_perm:[1,0,3,2] row_mask:0xf bank_mask:0xf bound_ctrl:1
	v_xor_b32_e32 v205, v189, v111
	v_add_f32_dpp v119, v206, v119 quad_perm:[1,0,3,2] row_mask:0xf bank_mask:0xf bound_ctrl:1
	v_xor_b32_e32 v121, v181, v210
	v_add_f32_dpp v111, v111, v205 quad_perm:[2,3,0,1] row_mask:0xf bank_mask:0xf bound_ctrl:1
	v_xor_b32_e32 v205, v189, v113
	v_add_f32_dpp v121, v210, v121 quad_perm:[1,0,3,2] row_mask:0xf bank_mask:0xf bound_ctrl:1
	v_xor_b32_e32 v187, v181, v214
	v_add_f32_dpp v113, v113, v205 quad_perm:[2,3,0,1] row_mask:0xf bank_mask:0xf bound_ctrl:1
	v_xor_b32_e32 v205, v189, v119
	v_pk_add_f32 v[218:219], v[212:213], v[212:213] op_sel:[1,0] op_sel_hi:[0,1]
	v_add_f32_dpp v187, v214, v187 quad_perm:[1,0,3,2] row_mask:0xf bank_mask:0xf bound_ctrl:1
	v_xor_b32_e32 v199, v181, v216
	v_add_f32_dpp v119, v119, v205 quad_perm:[2,3,0,1] row_mask:0xf bank_mask:0xf bound_ctrl:1
	v_xor_b32_e32 v205, v189, v121
	v_add_f32_dpp v199, v216, v199 quad_perm:[1,0,3,2] row_mask:0xf bank_mask:0xf bound_ctrl:1
	v_xor_b32_e32 v200, v181, v218
	v_add_f32_dpp v121, v121, v205 quad_perm:[2,3,0,1] row_mask:0xf bank_mask:0xf bound_ctrl:1
	v_xor_b32_e32 v205, v189, v187
	v_add_f32_dpp v200, v218, v200 quad_perm:[1,0,3,2] row_mask:0xf bank_mask:0xf bound_ctrl:1
	v_xor_b32_e32 v201, v181, v220
	v_add_f32_dpp v187, v187, v205 quad_perm:[2,3,0,1] row_mask:0xf bank_mask:0xf bound_ctrl:1
	v_xor_b32_e32 v205, v189, v199
	v_add_f32_dpp v201, v220, v201 quad_perm:[1,0,3,2] row_mask:0xf bank_mask:0xf bound_ctrl:1
	v_xor_b32_e32 v203, v181, v202
	v_add_f32_dpp v199, v199, v205 quad_perm:[2,3,0,1] row_mask:0xf bank_mask:0xf bound_ctrl:1
	v_xor_b32_e32 v205, v189, v200
	v_pk_add_f32 v[208:209], v[208:209], v[208:209] op_sel:[0,1] op_sel_hi:[1,0] neg_lo:[0,1] neg_hi:[0,1]
	v_add_f32_dpp v202, v202, v203 quad_perm:[1,0,3,2] row_mask:0xf bank_mask:0xf bound_ctrl:1
	v_xor_b32_e32 v203, v181, v112
	v_add_f32_dpp v200, v200, v205 quad_perm:[2,3,0,1] row_mask:0xf bank_mask:0xf bound_ctrl:1
	v_xor_b32_e32 v205, v189, v201
	v_add_f32_dpp v112, v112, v203 quad_perm:[1,0,3,2] row_mask:0xf bank_mask:0xf bound_ctrl:1
	v_xor_b32_e32 v203, v181, v208
	v_add_f32_dpp v201, v201, v205 quad_perm:[2,3,0,1] row_mask:0xf bank_mask:0xf bound_ctrl:1
	v_xor_b32_e32 v205, v189, v202
	v_add_f32_dpp v203, v208, v203 quad_perm:[1,0,3,2] row_mask:0xf bank_mask:0xf bound_ctrl:1
	v_xor_b32_e32 v204, v181, v118
	v_add_f32_dpp v202, v202, v205 quad_perm:[2,3,0,1] row_mask:0xf bank_mask:0xf bound_ctrl:1
	v_xor_b32_e32 v205, v189, v112
	v_add_f32_dpp v118, v118, v204 quad_perm:[1,0,3,2] row_mask:0xf bank_mask:0xf bound_ctrl:1
	v_xor_b32_e32 v204, v181, v120
	v_add_f32_dpp v205, v112, v205 quad_perm:[2,3,0,1] row_mask:0xf bank_mask:0xf bound_ctrl:1
	v_xor_b32_e32 v112, v189, v203
	v_pk_add_f32 v[212:213], v[212:213], v[212:213] op_sel:[0,1] op_sel_hi:[1,0] neg_lo:[0,1] neg_hi:[0,1]
	v_add_f32_dpp v120, v120, v204 quad_perm:[1,0,3,2] row_mask:0xf bank_mask:0xf bound_ctrl:1
	v_xor_b32_e32 v204, v181, v110
	v_add_f32_dpp v203, v203, v112 quad_perm:[2,3,0,1] row_mask:0xf bank_mask:0xf bound_ctrl:1
	v_xor_b32_e32 v112, v189, v118
	v_add_f32_dpp v110, v110, v204 quad_perm:[1,0,3,2] row_mask:0xf bank_mask:0xf bound_ctrl:1
	v_xor_b32_e32 v204, v181, v212
	v_add_f32_dpp v206, v118, v112 quad_perm:[2,3,0,1] row_mask:0xf bank_mask:0xf bound_ctrl:1
	v_xor_b32_e32 v112, v189, v120
	v_add_f32_dpp v204, v212, v204 quad_perm:[1,0,3,2] row_mask:0xf bank_mask:0xf bound_ctrl:1
	v_max_f32_e64 v118, |v200|, |v201|
	v_add_f32_dpp v120, v120, v112 quad_perm:[2,3,0,1] row_mask:0xf bank_mask:0xf bound_ctrl:1
	v_xor_b32_e32 v112, v189, v110
	s_nop 1
	v_add_f32_dpp v207, v110, v112 quad_perm:[2,3,0,1] row_mask:0xf bank_mask:0xf bound_ctrl:1
	v_xor_b32_e32 v110, v189, v204
	v_max_f32_e64 v112, |v119|, |v121|
	s_nop 0
	v_add_f32_dpp v204, v204, v110 quad_perm:[2,3,0,1] row_mask:0xf bank_mask:0xf bound_ctrl:1
	v_xor_b32_e32 v110, v189, v186
	s_nop 1
	v_add_f32_dpp v186, v186, v110 quad_perm:[2,3,0,1] row_mask:0xf bank_mask:0xf bound_ctrl:1
	v_max_f32_e64 v110, |v111|, |v113|
	v_max3_f32 v110, v222, v110, v112
	v_max_f32_e64 v112, |v187|, |v199|
	v_max3_f32 v110, v110, v112, v118
	v_max_f32_e64 v112, |v202|, |v205|
	v_max_f32_e64 v118, |v203|, |v206|
	v_max3_f32 v110, v110, v112, v118
	v_max_f32_e64 v112, |v120|, |v207|
	v_max_f32_e64 v118, |v204|, |v186|
	v_max3_f32 v222, v110, v112, v118
	v_cvt_pk_bf16_f32 v110, v111, v113
	v_cvt_pk_bf16_f32 v111, v119, v121
	v_cvt_pk_bf16_f32 v112, v187, v199
	v_cvt_pk_bf16_f32 v113, v200, v201
	v_cvt_pk_bf16_f32 v118, v202, v205
	v_cvt_pk_bf16_f32 v119, v203, v206
	v_cvt_pk_bf16_f32 v120, v120, v207
	v_cvt_pk_bf16_f32 v121, v204, v186
	v_and_b32_e32 v187, 0xffff0000, v129
	v_and_b32_e32 v186, 0xffff0000, v125
	v_lshlrev_b32_e32 v201, 16, v126
	v_lshlrev_b32_e32 v200, 16, v122
	v_and_b32_e32 v203, 0xffff0000, v126
	v_and_b32_e32 v202, 0xffff0000, v122
	v_lshlrev_b32_e32 v204, 16, v123
	v_lshlrev_b32_e32 v205, 16, v127
	v_and_b32_e32 v127, 0xffff0000, v127
	v_and_b32_e32 v126, 0xffff0000, v123
	v_lshlrev_b32_e32 v123, 16, v128
	v_lshlrev_b32_e32 v122, 16, v124
	v_and_b32_e32 v207, 0xffff0000, v128
	v_and_b32_e32 v206, 0xffff0000, v124
	v_lshlrev_b32_e32 v124, 16, v125
	v_lshlrev_b32_e32 v125, 16, v129
	v_pk_add_f32 v[128:129], v[200:201], v[202:203]
	v_pk_add_f32 v[208:209], v[204:205], v[126:127]
	v_pk_add_f32 v[210:211], v[122:123], v[206:207]
	v_pk_add_f32 v[212:213], v[124:125], v[186:187]
	v_pk_add_f32 v[200:201], v[200:201], v[202:203] neg_lo:[0,1] neg_hi:[0,1]
	v_pk_add_f32 v[126:127], v[204:205], v[126:127] neg_lo:[0,1] neg_hi:[0,1]
	v_pk_add_f32 v[122:123], v[122:123], v[206:207] neg_lo:[0,1] neg_hi:[0,1]
	v_pk_add_f32 v[124:125], v[124:125], v[186:187] neg_lo:[0,1] neg_hi:[0,1]
	v_pk_add_f32 v[214:215], v[128:129], v[208:209] neg_lo:[0,1] neg_hi:[0,1]
	v_pk_add_f32 v[128:129], v[128:129], v[208:209]
	v_pk_add_f32 v[208:209], v[210:211], v[212:213]
	v_pk_add_f32 v[186:187], v[200:201], v[126:127] neg_lo:[0,1] neg_hi:[0,1]
	v_pk_add_f32 v[202:203], v[122:123], v[124:125] neg_lo:[0,1] neg_hi:[0,1]
	v_pk_add_f32 v[126:127], v[200:201], v[126:127]
	v_pk_add_f32 v[122:123], v[122:123], v[124:125]
	v_pk_add_f32 v[216:217], v[210:211], v[212:213] neg_lo:[0,1] neg_hi:[0,1]
	v_pk_add_f32 v[210:211], v[128:129], v[208:209]
	v_pk_add_f32 v[124:125], v[126:127], v[122:123]
	v_pk_add_f32 v[122:123], v[126:127], v[122:123] neg_lo:[0,1] neg_hi:[0,1]
	v_pk_add_f32 v[128:129], v[128:129], v[208:209] neg_lo:[0,1] neg_hi:[0,1]
	v_pk_add_f32 v[208:209], v[214:215], v[216:217]
	v_pk_add_f32 v[212:213], v[214:215], v[216:217] neg_lo:[0,1] neg_hi:[0,1]
	v_pk_add_f32 v[126:127], v[186:187], v[202:203]
	v_pk_add_f32 v[186:187], v[186:187], v[202:203] neg_lo:[0,1] neg_hi:[0,1]
	v_pk_add_f32 v[200:201], v[210:211], v[210:211] op_sel:[1,0] op_sel_hi:[0,1]
	v_pk_add_f32 v[216:217], v[122:123], v[122:123] op_sel:[1,0] op_sel_hi:[0,1]
	v_pk_add_f32 v[122:123], v[122:123], v[122:123] op_sel:[0,1] op_sel_hi:[1,0] neg_lo:[0,1] neg_hi:[0,1]
	v_pk_add_f32 v[204:205], v[124:125], v[124:125] op_sel:[1,0] op_sel_hi:[0,1]
	v_pk_add_f32 v[124:125], v[124:125], v[124:125] op_sel:[0,1] op_sel_hi:[1,0] neg_lo:[0,1] neg_hi:[0,1]
	v_pk_add_f32 v[220:221], v[186:187], v[186:187] op_sel:[1,0] op_sel_hi:[0,1]
	v_pk_add_f32 v[186:187], v[186:187], v[186:187] op_sel:[0,1] op_sel_hi:[1,0] neg_lo:[0,1] neg_hi:[0,1]
	v_xor_b32_e32 v123, v181, v200
	v_pk_add_f32 v[202:203], v[210:211], v[210:211] op_sel:[0,1] op_sel_hi:[1,0] neg_lo:[0,1] neg_hi:[0,1]
	v_pk_add_f32 v[206:207], v[208:209], v[208:209] op_sel:[1,0] op_sel_hi:[0,1]
	v_pk_add_f32 v[210:211], v[126:127], v[126:127] op_sel:[1,0] op_sel_hi:[0,1]
	v_pk_add_f32 v[126:127], v[126:127], v[126:127] op_sel:[0,1] op_sel_hi:[1,0] neg_lo:[0,1] neg_hi:[0,1]
	v_add_f32_dpp v123, v200, v123 quad_perm:[1,0,3,2] row_mask:0xf bank_mask:0xf bound_ctrl:1
	v_xor_b32_e32 v125, v181, v204
	v_xor_b32_e32 v205, v181, v186
	v_pk_add_f32 v[214:215], v[128:129], v[128:129] op_sel:[1,0] op_sel_hi:[0,1]
	v_pk_add_f32 v[128:129], v[128:129], v[128:129] op_sel:[0,1] op_sel_hi:[1,0] neg_lo:[0,1] neg_hi:[0,1]
	v_add_f32_dpp v125, v204, v125 quad_perm:[1,0,3,2] row_mask:0xf bank_mask:0xf bound_ctrl:1
	v_xor_b32_e32 v127, v181, v206
	v_add_f32_dpp v186, v186, v205 quad_perm:[1,0,3,2] row_mask:0xf bank_mask:0xf bound_ctrl:1
	v_xor_b32_e32 v205, v189, v123
	v_add_f32_dpp v127, v206, v127 quad_perm:[1,0,3,2] row_mask:0xf bank_mask:0xf bound_ctrl:1
	v_xor_b32_e32 v129, v181, v210
	v_add_f32_dpp v123, v123, v205 quad_perm:[2,3,0,1] row_mask:0xf bank_mask:0xf bound_ctrl:1
	v_xor_b32_e32 v205, v189, v125
	v_add_f32_dpp v129, v210, v129 quad_perm:[1,0,3,2] row_mask:0xf bank_mask:0xf bound_ctrl:1
	v_xor_b32_e32 v187, v181, v214
	v_add_f32_dpp v125, v125, v205 quad_perm:[2,3,0,1] row_mask:0xf bank_mask:0xf bound_ctrl:1
	v_xor_b32_e32 v205, v189, v127
	v_pk_add_f32 v[218:219], v[212:213], v[212:213] op_sel:[1,0] op_sel_hi:[0,1]
	v_add_f32_dpp v187, v214, v187 quad_perm:[1,0,3,2] row_mask:0xf bank_mask:0xf bound_ctrl:1
	v_xor_b32_e32 v199, v181, v216
	v_add_f32_dpp v127, v127, v205 quad_perm:[2,3,0,1] row_mask:0xf bank_mask:0xf bound_ctrl:1
	v_xor_b32_e32 v205, v189, v129
	v_add_f32_dpp v199, v216, v199 quad_perm:[1,0,3,2] row_mask:0xf bank_mask:0xf bound_ctrl:1
	v_xor_b32_e32 v200, v181, v218
	v_add_f32_dpp v129, v129, v205 quad_perm:[2,3,0,1] row_mask:0xf bank_mask:0xf bound_ctrl:1
	v_xor_b32_e32 v205, v189, v187
	v_add_f32_dpp v200, v218, v200 quad_perm:[1,0,3,2] row_mask:0xf bank_mask:0xf bound_ctrl:1
	v_xor_b32_e32 v201, v181, v220
	v_add_f32_dpp v187, v187, v205 quad_perm:[2,3,0,1] row_mask:0xf bank_mask:0xf bound_ctrl:1
	v_xor_b32_e32 v205, v189, v199
	v_add_f32_dpp v201, v220, v201 quad_perm:[1,0,3,2] row_mask:0xf bank_mask:0xf bound_ctrl:1
	v_xor_b32_e32 v203, v181, v202
	v_add_f32_dpp v199, v199, v205 quad_perm:[2,3,0,1] row_mask:0xf bank_mask:0xf bound_ctrl:1
	v_xor_b32_e32 v205, v189, v200
	v_pk_add_f32 v[208:209], v[208:209], v[208:209] op_sel:[0,1] op_sel_hi:[1,0] neg_lo:[0,1] neg_hi:[0,1]
	v_add_f32_dpp v202, v202, v203 quad_perm:[1,0,3,2] row_mask:0xf bank_mask:0xf bound_ctrl:1
	v_xor_b32_e32 v203, v181, v124
	v_add_f32_dpp v200, v200, v205 quad_perm:[2,3,0,1] row_mask:0xf bank_mask:0xf bound_ctrl:1
	v_xor_b32_e32 v205, v189, v201
	v_add_f32_dpp v124, v124, v203 quad_perm:[1,0,3,2] row_mask:0xf bank_mask:0xf bound_ctrl:1
	v_xor_b32_e32 v203, v181, v208
	v_add_f32_dpp v201, v201, v205 quad_perm:[2,3,0,1] row_mask:0xf bank_mask:0xf bound_ctrl:1
	v_xor_b32_e32 v205, v189, v202
	v_add_f32_dpp v203, v208, v203 quad_perm:[1,0,3,2] row_mask:0xf bank_mask:0xf bound_ctrl:1
	v_xor_b32_e32 v204, v181, v126
	v_add_f32_dpp v202, v202, v205 quad_perm:[2,3,0,1] row_mask:0xf bank_mask:0xf bound_ctrl:1
	v_xor_b32_e32 v205, v189, v124
	v_add_f32_dpp v126, v126, v204 quad_perm:[1,0,3,2] row_mask:0xf bank_mask:0xf bound_ctrl:1
	v_xor_b32_e32 v204, v181, v128
	v_add_f32_dpp v205, v124, v205 quad_perm:[2,3,0,1] row_mask:0xf bank_mask:0xf bound_ctrl:1
	v_xor_b32_e32 v124, v189, v203
	v_pk_add_f32 v[212:213], v[212:213], v[212:213] op_sel:[0,1] op_sel_hi:[1,0] neg_lo:[0,1] neg_hi:[0,1]
	v_add_f32_dpp v128, v128, v204 quad_perm:[1,0,3,2] row_mask:0xf bank_mask:0xf bound_ctrl:1
	v_xor_b32_e32 v204, v181, v122
	v_add_f32_dpp v203, v203, v124 quad_perm:[2,3,0,1] row_mask:0xf bank_mask:0xf bound_ctrl:1
	v_xor_b32_e32 v124, v189, v126
	v_add_f32_dpp v122, v122, v204 quad_perm:[1,0,3,2] row_mask:0xf bank_mask:0xf bound_ctrl:1
	v_xor_b32_e32 v204, v181, v212
	v_add_f32_dpp v206, v126, v124 quad_perm:[2,3,0,1] row_mask:0xf bank_mask:0xf bound_ctrl:1
	v_xor_b32_e32 v124, v189, v128
	v_add_f32_dpp v204, v212, v204 quad_perm:[1,0,3,2] row_mask:0xf bank_mask:0xf bound_ctrl:1
	v_max_f32_e64 v126, |v200|, |v201|
	v_add_f32_dpp v128, v128, v124 quad_perm:[2,3,0,1] row_mask:0xf bank_mask:0xf bound_ctrl:1
	v_xor_b32_e32 v124, v189, v122
	s_nop 1
	v_add_f32_dpp v207, v122, v124 quad_perm:[2,3,0,1] row_mask:0xf bank_mask:0xf bound_ctrl:1
	v_xor_b32_e32 v122, v189, v204
	v_max_f32_e64 v124, |v127|, |v129|
	s_nop 0
	v_add_f32_dpp v204, v204, v122 quad_perm:[2,3,0,1] row_mask:0xf bank_mask:0xf bound_ctrl:1
	v_xor_b32_e32 v122, v189, v186
	s_nop 1
	v_add_f32_dpp v186, v186, v122 quad_perm:[2,3,0,1] row_mask:0xf bank_mask:0xf bound_ctrl:1
	v_max_f32_e64 v122, |v123|, |v125|
	v_max3_f32 v122, v222, v122, v124
	v_max_f32_e64 v124, |v187|, |v199|
	v_max3_f32 v122, v122, v124, v126
	v_max_f32_e64 v124, |v202|, |v205|
	v_max_f32_e64 v126, |v203|, |v206|
	v_max3_f32 v122, v122, v124, v126
	v_max_f32_e64 v124, |v128|, |v207|
	v_max_f32_e64 v126, |v204|, |v186|
	v_max3_f32 v222, v122, v124, v126
	v_cvt_pk_bf16_f32 v122, v123, v125
	v_cvt_pk_bf16_f32 v123, v127, v129
	v_cvt_pk_bf16_f32 v124, v187, v199
	v_cvt_pk_bf16_f32 v125, v200, v201
	v_cvt_pk_bf16_f32 v126, v202, v205
	v_cvt_pk_bf16_f32 v127, v203, v206
	v_cvt_pk_bf16_f32 v128, v128, v207
	v_cvt_pk_bf16_f32 v129, v204, v186
	v_and_b32_e32 v187, 0xffff0000, v137
	v_and_b32_e32 v186, 0xffff0000, v133
	v_lshlrev_b32_e32 v201, 16, v134
	v_lshlrev_b32_e32 v200, 16, v130
	v_and_b32_e32 v203, 0xffff0000, v134
	v_and_b32_e32 v202, 0xffff0000, v130
	v_lshlrev_b32_e32 v204, 16, v131
	v_lshlrev_b32_e32 v205, 16, v135
	v_and_b32_e32 v135, 0xffff0000, v135
	v_and_b32_e32 v134, 0xffff0000, v131
	v_lshlrev_b32_e32 v131, 16, v136
	v_lshlrev_b32_e32 v130, 16, v132
	v_and_b32_e32 v207, 0xffff0000, v136
	v_and_b32_e32 v206, 0xffff0000, v132
	v_lshlrev_b32_e32 v132, 16, v133
	v_lshlrev_b32_e32 v133, 16, v137
	v_pk_add_f32 v[136:137], v[200:201], v[202:203]
	v_pk_add_f32 v[208:209], v[204:205], v[134:135]
	v_pk_add_f32 v[210:211], v[130:131], v[206:207]
	v_pk_add_f32 v[212:213], v[132:133], v[186:187]
	v_pk_add_f32 v[200:201], v[200:201], v[202:203] neg_lo:[0,1] neg_hi:[0,1]
	v_pk_add_f32 v[134:135], v[204:205], v[134:135] neg_lo:[0,1] neg_hi:[0,1]
	v_pk_add_f32 v[130:131], v[130:131], v[206:207] neg_lo:[0,1] neg_hi:[0,1]
	v_pk_add_f32 v[132:133], v[132:133], v[186:187] neg_lo:[0,1] neg_hi:[0,1]
	v_pk_add_f32 v[214:215], v[136:137], v[208:209] neg_lo:[0,1] neg_hi:[0,1]
	v_pk_add_f32 v[136:137], v[136:137], v[208:209]
	v_pk_add_f32 v[208:209], v[210:211], v[212:213]
	v_pk_add_f32 v[186:187], v[200:201], v[134:135] neg_lo:[0,1] neg_hi:[0,1]
	v_pk_add_f32 v[202:203], v[130:131], v[132:133] neg_lo:[0,1] neg_hi:[0,1]
	v_pk_add_f32 v[134:135], v[200:201], v[134:135]
	v_pk_add_f32 v[130:131], v[130:131], v[132:133]
	v_pk_add_f32 v[216:217], v[210:211], v[212:213] neg_lo:[0,1] neg_hi:[0,1]
	v_pk_add_f32 v[210:211], v[136:137], v[208:209]
	v_pk_add_f32 v[132:133], v[134:135], v[130:131]
	v_pk_add_f32 v[130:131], v[134:135], v[130:131] neg_lo:[0,1] neg_hi:[0,1]
	v_pk_add_f32 v[136:137], v[136:137], v[208:209] neg_lo:[0,1] neg_hi:[0,1]
	v_pk_add_f32 v[208:209], v[214:215], v[216:217]
	v_pk_add_f32 v[212:213], v[214:215], v[216:217] neg_lo:[0,1] neg_hi:[0,1]
	v_pk_add_f32 v[134:135], v[186:187], v[202:203]
	v_pk_add_f32 v[186:187], v[186:187], v[202:203] neg_lo:[0,1] neg_hi:[0,1]
	v_pk_add_f32 v[200:201], v[210:211], v[210:211] op_sel:[1,0] op_sel_hi:[0,1]
	v_pk_add_f32 v[216:217], v[130:131], v[130:131] op_sel:[1,0] op_sel_hi:[0,1]
	v_pk_add_f32 v[130:131], v[130:131], v[130:131] op_sel:[0,1] op_sel_hi:[1,0] neg_lo:[0,1] neg_hi:[0,1]
	v_pk_add_f32 v[204:205], v[132:133], v[132:133] op_sel:[1,0] op_sel_hi:[0,1]
	v_pk_add_f32 v[132:133], v[132:133], v[132:133] op_sel:[0,1] op_sel_hi:[1,0] neg_lo:[0,1] neg_hi:[0,1]
	v_pk_add_f32 v[220:221], v[186:187], v[186:187] op_sel:[1,0] op_sel_hi:[0,1]
	v_pk_add_f32 v[186:187], v[186:187], v[186:187] op_sel:[0,1] op_sel_hi:[1,0] neg_lo:[0,1] neg_hi:[0,1]
	v_xor_b32_e32 v131, v181, v200
	v_pk_add_f32 v[202:203], v[210:211], v[210:211] op_sel:[0,1] op_sel_hi:[1,0] neg_lo:[0,1] neg_hi:[0,1]
	v_pk_add_f32 v[206:207], v[208:209], v[208:209] op_sel:[1,0] op_sel_hi:[0,1]
	v_pk_add_f32 v[210:211], v[134:135], v[134:135] op_sel:[1,0] op_sel_hi:[0,1]
	v_pk_add_f32 v[134:135], v[134:135], v[134:135] op_sel:[0,1] op_sel_hi:[1,0] neg_lo:[0,1] neg_hi:[0,1]
	v_add_f32_dpp v131, v200, v131 quad_perm:[1,0,3,2] row_mask:0xf bank_mask:0xf bound_ctrl:1
	v_xor_b32_e32 v133, v181, v204
	v_xor_b32_e32 v205, v181, v186
	v_pk_add_f32 v[214:215], v[136:137], v[136:137] op_sel:[1,0] op_sel_hi:[0,1]
	v_pk_add_f32 v[136:137], v[136:137], v[136:137] op_sel:[0,1] op_sel_hi:[1,0] neg_lo:[0,1] neg_hi:[0,1]
	v_add_f32_dpp v133, v204, v133 quad_perm:[1,0,3,2] row_mask:0xf bank_mask:0xf bound_ctrl:1
	v_xor_b32_e32 v135, v181, v206
	v_add_f32_dpp v186, v186, v205 quad_perm:[1,0,3,2] row_mask:0xf bank_mask:0xf bound_ctrl:1
	v_xor_b32_e32 v205, v189, v131
	v_add_f32_dpp v135, v206, v135 quad_perm:[1,0,3,2] row_mask:0xf bank_mask:0xf bound_ctrl:1
	v_xor_b32_e32 v137, v181, v210
	v_add_f32_dpp v131, v131, v205 quad_perm:[2,3,0,1] row_mask:0xf bank_mask:0xf bound_ctrl:1
	v_xor_b32_e32 v205, v189, v133
	v_add_f32_dpp v137, v210, v137 quad_perm:[1,0,3,2] row_mask:0xf bank_mask:0xf bound_ctrl:1
	v_xor_b32_e32 v187, v181, v214
	v_add_f32_dpp v133, v133, v205 quad_perm:[2,3,0,1] row_mask:0xf bank_mask:0xf bound_ctrl:1
	v_xor_b32_e32 v205, v189, v135
	v_pk_add_f32 v[218:219], v[212:213], v[212:213] op_sel:[1,0] op_sel_hi:[0,1]
	v_add_f32_dpp v187, v214, v187 quad_perm:[1,0,3,2] row_mask:0xf bank_mask:0xf bound_ctrl:1
	v_xor_b32_e32 v199, v181, v216
	v_add_f32_dpp v135, v135, v205 quad_perm:[2,3,0,1] row_mask:0xf bank_mask:0xf bound_ctrl:1
	v_xor_b32_e32 v205, v189, v137
	v_add_f32_dpp v199, v216, v199 quad_perm:[1,0,3,2] row_mask:0xf bank_mask:0xf bound_ctrl:1
	v_xor_b32_e32 v200, v181, v218
	v_add_f32_dpp v137, v137, v205 quad_perm:[2,3,0,1] row_mask:0xf bank_mask:0xf bound_ctrl:1
	v_xor_b32_e32 v205, v189, v187
	v_add_f32_dpp v200, v218, v200 quad_perm:[1,0,3,2] row_mask:0xf bank_mask:0xf bound_ctrl:1
	v_xor_b32_e32 v201, v181, v220
	v_add_f32_dpp v187, v187, v205 quad_perm:[2,3,0,1] row_mask:0xf bank_mask:0xf bound_ctrl:1
	v_xor_b32_e32 v205, v189, v199
	v_add_f32_dpp v201, v220, v201 quad_perm:[1,0,3,2] row_mask:0xf bank_mask:0xf bound_ctrl:1
	v_xor_b32_e32 v203, v181, v202
	v_add_f32_dpp v199, v199, v205 quad_perm:[2,3,0,1] row_mask:0xf bank_mask:0xf bound_ctrl:1
	v_xor_b32_e32 v205, v189, v200
	v_pk_add_f32 v[208:209], v[208:209], v[208:209] op_sel:[0,1] op_sel_hi:[1,0] neg_lo:[0,1] neg_hi:[0,1]
	v_add_f32_dpp v202, v202, v203 quad_perm:[1,0,3,2] row_mask:0xf bank_mask:0xf bound_ctrl:1
	v_xor_b32_e32 v203, v181, v132
	v_add_f32_dpp v200, v200, v205 quad_perm:[2,3,0,1] row_mask:0xf bank_mask:0xf bound_ctrl:1
	v_xor_b32_e32 v205, v189, v201
	v_add_f32_dpp v132, v132, v203 quad_perm:[1,0,3,2] row_mask:0xf bank_mask:0xf bound_ctrl:1
	v_xor_b32_e32 v203, v181, v208
	v_add_f32_dpp v201, v201, v205 quad_perm:[2,3,0,1] row_mask:0xf bank_mask:0xf bound_ctrl:1
	v_xor_b32_e32 v205, v189, v202
	v_add_f32_dpp v203, v208, v203 quad_perm:[1,0,3,2] row_mask:0xf bank_mask:0xf bound_ctrl:1
	v_xor_b32_e32 v204, v181, v134
	v_add_f32_dpp v202, v202, v205 quad_perm:[2,3,0,1] row_mask:0xf bank_mask:0xf bound_ctrl:1
	v_xor_b32_e32 v205, v189, v132
	v_add_f32_dpp v134, v134, v204 quad_perm:[1,0,3,2] row_mask:0xf bank_mask:0xf bound_ctrl:1
	v_xor_b32_e32 v204, v181, v136
	v_add_f32_dpp v205, v132, v205 quad_perm:[2,3,0,1] row_mask:0xf bank_mask:0xf bound_ctrl:1
	v_xor_b32_e32 v132, v189, v203
	v_pk_add_f32 v[212:213], v[212:213], v[212:213] op_sel:[0,1] op_sel_hi:[1,0] neg_lo:[0,1] neg_hi:[0,1]
	v_add_f32_dpp v136, v136, v204 quad_perm:[1,0,3,2] row_mask:0xf bank_mask:0xf bound_ctrl:1
	v_xor_b32_e32 v204, v181, v130
	v_add_f32_dpp v203, v203, v132 quad_perm:[2,3,0,1] row_mask:0xf bank_mask:0xf bound_ctrl:1
	v_xor_b32_e32 v132, v189, v134
	v_add_f32_dpp v130, v130, v204 quad_perm:[1,0,3,2] row_mask:0xf bank_mask:0xf bound_ctrl:1
	v_xor_b32_e32 v204, v181, v212
	v_add_f32_dpp v206, v134, v132 quad_perm:[2,3,0,1] row_mask:0xf bank_mask:0xf bound_ctrl:1
	v_xor_b32_e32 v132, v189, v136
	v_add_f32_dpp v204, v212, v204 quad_perm:[1,0,3,2] row_mask:0xf bank_mask:0xf bound_ctrl:1
	v_max_f32_e64 v134, |v200|, |v201|
	v_add_f32_dpp v136, v136, v132 quad_perm:[2,3,0,1] row_mask:0xf bank_mask:0xf bound_ctrl:1
	v_xor_b32_e32 v132, v189, v130
	s_nop 1
	v_add_f32_dpp v207, v130, v132 quad_perm:[2,3,0,1] row_mask:0xf bank_mask:0xf bound_ctrl:1
	v_xor_b32_e32 v130, v189, v204
	v_max_f32_e64 v132, |v135|, |v137|
	s_nop 0
	v_add_f32_dpp v204, v204, v130 quad_perm:[2,3,0,1] row_mask:0xf bank_mask:0xf bound_ctrl:1
	v_xor_b32_e32 v130, v189, v186
	s_nop 1
	v_add_f32_dpp v186, v186, v130 quad_perm:[2,3,0,1] row_mask:0xf bank_mask:0xf bound_ctrl:1
	v_max_f32_e64 v130, |v131|, |v133|
	v_max3_f32 v130, v222, v130, v132
	v_max_f32_e64 v132, |v187|, |v199|
	v_max3_f32 v130, v130, v132, v134
	v_max_f32_e64 v132, |v202|, |v205|
	v_max_f32_e64 v134, |v203|, |v206|
	v_max3_f32 v130, v130, v132, v134
	v_max_f32_e64 v132, |v136|, |v207|
	v_max_f32_e64 v134, |v204|, |v186|
	v_max3_f32 v222, v130, v132, v134
	v_cvt_pk_bf16_f32 v130, v131, v133
	v_cvt_pk_bf16_f32 v131, v135, v137
	v_cvt_pk_bf16_f32 v132, v187, v199
	v_cvt_pk_bf16_f32 v133, v200, v201
	v_cvt_pk_bf16_f32 v134, v202, v205
	v_cvt_pk_bf16_f32 v135, v203, v206
	v_cvt_pk_bf16_f32 v136, v136, v207
	v_cvt_pk_bf16_f32 v137, v204, v186
	v_and_b32_e32 v187, 0xffff0000, v145
	v_and_b32_e32 v186, 0xffff0000, v141
	v_lshlrev_b32_e32 v201, 16, v142
	v_lshlrev_b32_e32 v200, 16, v138
	v_and_b32_e32 v203, 0xffff0000, v142
	v_and_b32_e32 v202, 0xffff0000, v138
	v_lshlrev_b32_e32 v204, 16, v139
	v_lshlrev_b32_e32 v205, 16, v143
	v_and_b32_e32 v143, 0xffff0000, v143
	v_and_b32_e32 v142, 0xffff0000, v139
	v_lshlrev_b32_e32 v139, 16, v144
	v_lshlrev_b32_e32 v138, 16, v140
	v_and_b32_e32 v207, 0xffff0000, v144
	v_and_b32_e32 v206, 0xffff0000, v140
	v_lshlrev_b32_e32 v140, 16, v141
	v_lshlrev_b32_e32 v141, 16, v145
	v_pk_add_f32 v[144:145], v[200:201], v[202:203]
	v_pk_add_f32 v[208:209], v[204:205], v[142:143]
	v_pk_add_f32 v[210:211], v[138:139], v[206:207]
	v_pk_add_f32 v[212:213], v[140:141], v[186:187]
	v_pk_add_f32 v[200:201], v[200:201], v[202:203] neg_lo:[0,1] neg_hi:[0,1]
	v_pk_add_f32 v[142:143], v[204:205], v[142:143] neg_lo:[0,1] neg_hi:[0,1]
	v_pk_add_f32 v[138:139], v[138:139], v[206:207] neg_lo:[0,1] neg_hi:[0,1]
	v_pk_add_f32 v[140:141], v[140:141], v[186:187] neg_lo:[0,1] neg_hi:[0,1]
	v_pk_add_f32 v[214:215], v[144:145], v[208:209] neg_lo:[0,1] neg_hi:[0,1]
	v_pk_add_f32 v[144:145], v[144:145], v[208:209]
	v_pk_add_f32 v[208:209], v[210:211], v[212:213]
	v_pk_add_f32 v[186:187], v[200:201], v[142:143] neg_lo:[0,1] neg_hi:[0,1]
	v_pk_add_f32 v[202:203], v[138:139], v[140:141] neg_lo:[0,1] neg_hi:[0,1]
	v_pk_add_f32 v[142:143], v[200:201], v[142:143]
	v_pk_add_f32 v[138:139], v[138:139], v[140:141]
	v_pk_add_f32 v[216:217], v[210:211], v[212:213] neg_lo:[0,1] neg_hi:[0,1]
	v_pk_add_f32 v[210:211], v[144:145], v[208:209]
	v_pk_add_f32 v[140:141], v[142:143], v[138:139]
	v_pk_add_f32 v[138:139], v[142:143], v[138:139] neg_lo:[0,1] neg_hi:[0,1]
	v_pk_add_f32 v[144:145], v[144:145], v[208:209] neg_lo:[0,1] neg_hi:[0,1]
	v_pk_add_f32 v[208:209], v[214:215], v[216:217]
	v_pk_add_f32 v[212:213], v[214:215], v[216:217] neg_lo:[0,1] neg_hi:[0,1]
	v_pk_add_f32 v[142:143], v[186:187], v[202:203]
	v_pk_add_f32 v[186:187], v[186:187], v[202:203] neg_lo:[0,1] neg_hi:[0,1]
	v_pk_add_f32 v[200:201], v[210:211], v[210:211] op_sel:[1,0] op_sel_hi:[0,1]
	v_pk_add_f32 v[216:217], v[138:139], v[138:139] op_sel:[1,0] op_sel_hi:[0,1]
	v_pk_add_f32 v[138:139], v[138:139], v[138:139] op_sel:[0,1] op_sel_hi:[1,0] neg_lo:[0,1] neg_hi:[0,1]
	v_pk_add_f32 v[204:205], v[140:141], v[140:141] op_sel:[1,0] op_sel_hi:[0,1]
	v_pk_add_f32 v[140:141], v[140:141], v[140:141] op_sel:[0,1] op_sel_hi:[1,0] neg_lo:[0,1] neg_hi:[0,1]
	v_pk_add_f32 v[220:221], v[186:187], v[186:187] op_sel:[1,0] op_sel_hi:[0,1]
	v_pk_add_f32 v[186:187], v[186:187], v[186:187] op_sel:[0,1] op_sel_hi:[1,0] neg_lo:[0,1] neg_hi:[0,1]
	v_xor_b32_e32 v139, v181, v200
	v_pk_add_f32 v[202:203], v[210:211], v[210:211] op_sel:[0,1] op_sel_hi:[1,0] neg_lo:[0,1] neg_hi:[0,1]
	v_pk_add_f32 v[206:207], v[208:209], v[208:209] op_sel:[1,0] op_sel_hi:[0,1]
	v_pk_add_f32 v[210:211], v[142:143], v[142:143] op_sel:[1,0] op_sel_hi:[0,1]
	v_pk_add_f32 v[142:143], v[142:143], v[142:143] op_sel:[0,1] op_sel_hi:[1,0] neg_lo:[0,1] neg_hi:[0,1]
	v_add_f32_dpp v139, v200, v139 quad_perm:[1,0,3,2] row_mask:0xf bank_mask:0xf bound_ctrl:1
	v_xor_b32_e32 v141, v181, v204
	v_xor_b32_e32 v205, v181, v186
	v_pk_add_f32 v[214:215], v[144:145], v[144:145] op_sel:[1,0] op_sel_hi:[0,1]
	v_pk_add_f32 v[144:145], v[144:145], v[144:145] op_sel:[0,1] op_sel_hi:[1,0] neg_lo:[0,1] neg_hi:[0,1]
	v_add_f32_dpp v141, v204, v141 quad_perm:[1,0,3,2] row_mask:0xf bank_mask:0xf bound_ctrl:1
	v_xor_b32_e32 v143, v181, v206
	v_add_f32_dpp v186, v186, v205 quad_perm:[1,0,3,2] row_mask:0xf bank_mask:0xf bound_ctrl:1
	v_xor_b32_e32 v205, v189, v139
	v_add_f32_dpp v143, v206, v143 quad_perm:[1,0,3,2] row_mask:0xf bank_mask:0xf bound_ctrl:1
	v_xor_b32_e32 v145, v181, v210
	v_add_f32_dpp v139, v139, v205 quad_perm:[2,3,0,1] row_mask:0xf bank_mask:0xf bound_ctrl:1
	v_xor_b32_e32 v205, v189, v141
	v_add_f32_dpp v145, v210, v145 quad_perm:[1,0,3,2] row_mask:0xf bank_mask:0xf bound_ctrl:1
	v_xor_b32_e32 v187, v181, v214
	v_add_f32_dpp v141, v141, v205 quad_perm:[2,3,0,1] row_mask:0xf bank_mask:0xf bound_ctrl:1
	v_xor_b32_e32 v205, v189, v143
	v_pk_add_f32 v[218:219], v[212:213], v[212:213] op_sel:[1,0] op_sel_hi:[0,1]
	v_add_f32_dpp v187, v214, v187 quad_perm:[1,0,3,2] row_mask:0xf bank_mask:0xf bound_ctrl:1
	v_xor_b32_e32 v199, v181, v216
	v_add_f32_dpp v143, v143, v205 quad_perm:[2,3,0,1] row_mask:0xf bank_mask:0xf bound_ctrl:1
	v_xor_b32_e32 v205, v189, v145
	v_add_f32_dpp v199, v216, v199 quad_perm:[1,0,3,2] row_mask:0xf bank_mask:0xf bound_ctrl:1
	v_xor_b32_e32 v200, v181, v218
	v_add_f32_dpp v145, v145, v205 quad_perm:[2,3,0,1] row_mask:0xf bank_mask:0xf bound_ctrl:1
	v_xor_b32_e32 v205, v189, v187
	v_add_f32_dpp v200, v218, v200 quad_perm:[1,0,3,2] row_mask:0xf bank_mask:0xf bound_ctrl:1
	v_xor_b32_e32 v201, v181, v220
	v_add_f32_dpp v187, v187, v205 quad_perm:[2,3,0,1] row_mask:0xf bank_mask:0xf bound_ctrl:1
	v_xor_b32_e32 v205, v189, v199
	v_add_f32_dpp v201, v220, v201 quad_perm:[1,0,3,2] row_mask:0xf bank_mask:0xf bound_ctrl:1
	v_xor_b32_e32 v203, v181, v202
	v_add_f32_dpp v199, v199, v205 quad_perm:[2,3,0,1] row_mask:0xf bank_mask:0xf bound_ctrl:1
	v_xor_b32_e32 v205, v189, v200
	v_pk_add_f32 v[208:209], v[208:209], v[208:209] op_sel:[0,1] op_sel_hi:[1,0] neg_lo:[0,1] neg_hi:[0,1]
	v_add_f32_dpp v202, v202, v203 quad_perm:[1,0,3,2] row_mask:0xf bank_mask:0xf bound_ctrl:1
	v_xor_b32_e32 v203, v181, v140
	v_add_f32_dpp v200, v200, v205 quad_perm:[2,3,0,1] row_mask:0xf bank_mask:0xf bound_ctrl:1
	v_xor_b32_e32 v205, v189, v201
	v_add_f32_dpp v140, v140, v203 quad_perm:[1,0,3,2] row_mask:0xf bank_mask:0xf bound_ctrl:1
	v_xor_b32_e32 v203, v181, v208
	v_add_f32_dpp v201, v201, v205 quad_perm:[2,3,0,1] row_mask:0xf bank_mask:0xf bound_ctrl:1
	v_xor_b32_e32 v205, v189, v202
	v_add_f32_dpp v203, v208, v203 quad_perm:[1,0,3,2] row_mask:0xf bank_mask:0xf bound_ctrl:1
	v_xor_b32_e32 v204, v181, v142
	v_add_f32_dpp v202, v202, v205 quad_perm:[2,3,0,1] row_mask:0xf bank_mask:0xf bound_ctrl:1
	v_xor_b32_e32 v205, v189, v140
	v_add_f32_dpp v142, v142, v204 quad_perm:[1,0,3,2] row_mask:0xf bank_mask:0xf bound_ctrl:1
	v_xor_b32_e32 v204, v181, v144
	v_add_f32_dpp v205, v140, v205 quad_perm:[2,3,0,1] row_mask:0xf bank_mask:0xf bound_ctrl:1
	v_xor_b32_e32 v140, v189, v203
	v_pk_add_f32 v[212:213], v[212:213], v[212:213] op_sel:[0,1] op_sel_hi:[1,0] neg_lo:[0,1] neg_hi:[0,1]
	v_add_f32_dpp v144, v144, v204 quad_perm:[1,0,3,2] row_mask:0xf bank_mask:0xf bound_ctrl:1
	v_xor_b32_e32 v204, v181, v138
	v_add_f32_dpp v203, v203, v140 quad_perm:[2,3,0,1] row_mask:0xf bank_mask:0xf bound_ctrl:1
	v_xor_b32_e32 v140, v189, v142
	v_add_f32_dpp v138, v138, v204 quad_perm:[1,0,3,2] row_mask:0xf bank_mask:0xf bound_ctrl:1
	v_xor_b32_e32 v204, v181, v212
	v_add_f32_dpp v206, v142, v140 quad_perm:[2,3,0,1] row_mask:0xf bank_mask:0xf bound_ctrl:1
	v_xor_b32_e32 v140, v189, v144
	v_add_f32_dpp v204, v212, v204 quad_perm:[1,0,3,2] row_mask:0xf bank_mask:0xf bound_ctrl:1
	v_max_f32_e64 v142, |v200|, |v201|
	v_add_f32_dpp v144, v144, v140 quad_perm:[2,3,0,1] row_mask:0xf bank_mask:0xf bound_ctrl:1
	v_xor_b32_e32 v140, v189, v138
	s_nop 1
	v_add_f32_dpp v207, v138, v140 quad_perm:[2,3,0,1] row_mask:0xf bank_mask:0xf bound_ctrl:1
	v_xor_b32_e32 v138, v189, v204
	v_max_f32_e64 v140, |v143|, |v145|
	s_nop 0
	v_add_f32_dpp v204, v204, v138 quad_perm:[2,3,0,1] row_mask:0xf bank_mask:0xf bound_ctrl:1
	v_xor_b32_e32 v138, v189, v186
	s_nop 1
	v_add_f32_dpp v186, v186, v138 quad_perm:[2,3,0,1] row_mask:0xf bank_mask:0xf bound_ctrl:1
	v_max_f32_e64 v138, |v139|, |v141|
	v_max3_f32 v138, v222, v138, v140
	v_max_f32_e64 v140, |v187|, |v199|
	v_max3_f32 v138, v138, v140, v142
	v_max_f32_e64 v140, |v202|, |v205|
	v_max_f32_e64 v142, |v203|, |v206|
	v_max3_f32 v138, v138, v140, v142
	v_max_f32_e64 v140, |v144|, |v207|
	v_max_f32_e64 v142, |v204|, |v186|
	v_max3_f32 v222, v138, v140, v142
	v_cvt_pk_bf16_f32 v138, v139, v141
	v_cvt_pk_bf16_f32 v139, v143, v145
	v_cvt_pk_bf16_f32 v140, v187, v199
	v_cvt_pk_bf16_f32 v141, v200, v201
	v_cvt_pk_bf16_f32 v142, v202, v205
	v_cvt_pk_bf16_f32 v143, v203, v206
	v_cvt_pk_bf16_f32 v144, v144, v207
	v_cvt_pk_bf16_f32 v145, v204, v186
	v_and_b32_e32 v187, 0xffff0000, v177
	v_and_b32_e32 v186, 0xffff0000, v173
	v_lshlrev_b32_e32 v201, 16, v174
	v_lshlrev_b32_e32 v200, 16, v170
	v_and_b32_e32 v203, 0xffff0000, v174
	v_and_b32_e32 v202, 0xffff0000, v170
	v_lshlrev_b32_e32 v204, 16, v171
	v_lshlrev_b32_e32 v205, 16, v175
	v_and_b32_e32 v175, 0xffff0000, v175
	v_and_b32_e32 v174, 0xffff0000, v171
	v_lshlrev_b32_e32 v171, 16, v176
	v_lshlrev_b32_e32 v170, 16, v172
	v_and_b32_e32 v207, 0xffff0000, v176
	v_and_b32_e32 v206, 0xffff0000, v172
	v_lshlrev_b32_e32 v172, 16, v173
	v_lshlrev_b32_e32 v173, 16, v177
	v_pk_add_f32 v[176:177], v[200:201], v[202:203]
	v_pk_add_f32 v[208:209], v[204:205], v[174:175]
	v_pk_add_f32 v[210:211], v[170:171], v[206:207]
	v_pk_add_f32 v[212:213], v[172:173], v[186:187]
	v_pk_add_f32 v[200:201], v[200:201], v[202:203] neg_lo:[0,1] neg_hi:[0,1]
	v_pk_add_f32 v[174:175], v[204:205], v[174:175] neg_lo:[0,1] neg_hi:[0,1]
	v_pk_add_f32 v[170:171], v[170:171], v[206:207] neg_lo:[0,1] neg_hi:[0,1]
	v_pk_add_f32 v[172:173], v[172:173], v[186:187] neg_lo:[0,1] neg_hi:[0,1]
	v_pk_add_f32 v[214:215], v[176:177], v[208:209] neg_lo:[0,1] neg_hi:[0,1]
	v_pk_add_f32 v[176:177], v[176:177], v[208:209]
	v_pk_add_f32 v[208:209], v[210:211], v[212:213]
	v_pk_add_f32 v[186:187], v[200:201], v[174:175] neg_lo:[0,1] neg_hi:[0,1]
	v_pk_add_f32 v[202:203], v[170:171], v[172:173] neg_lo:[0,1] neg_hi:[0,1]
	v_pk_add_f32 v[174:175], v[200:201], v[174:175]
	v_pk_add_f32 v[170:171], v[170:171], v[172:173]
	v_pk_add_f32 v[216:217], v[210:211], v[212:213] neg_lo:[0,1] neg_hi:[0,1]
	v_pk_add_f32 v[210:211], v[176:177], v[208:209]
	v_pk_add_f32 v[172:173], v[174:175], v[170:171]
	v_pk_add_f32 v[170:171], v[174:175], v[170:171] neg_lo:[0,1] neg_hi:[0,1]
	v_pk_add_f32 v[176:177], v[176:177], v[208:209] neg_lo:[0,1] neg_hi:[0,1]
	v_pk_add_f32 v[208:209], v[214:215], v[216:217]
	v_pk_add_f32 v[212:213], v[214:215], v[216:217] neg_lo:[0,1] neg_hi:[0,1]
	v_pk_add_f32 v[174:175], v[186:187], v[202:203]
	v_pk_add_f32 v[186:187], v[186:187], v[202:203] neg_lo:[0,1] neg_hi:[0,1]
	v_pk_add_f32 v[200:201], v[210:211], v[210:211] op_sel:[1,0] op_sel_hi:[0,1]
	v_pk_add_f32 v[216:217], v[170:171], v[170:171] op_sel:[1,0] op_sel_hi:[0,1]
	v_pk_add_f32 v[170:171], v[170:171], v[170:171] op_sel:[0,1] op_sel_hi:[1,0] neg_lo:[0,1] neg_hi:[0,1]
	v_pk_add_f32 v[204:205], v[172:173], v[172:173] op_sel:[1,0] op_sel_hi:[0,1]
	v_pk_add_f32 v[172:173], v[172:173], v[172:173] op_sel:[0,1] op_sel_hi:[1,0] neg_lo:[0,1] neg_hi:[0,1]
	v_pk_add_f32 v[220:221], v[186:187], v[186:187] op_sel:[1,0] op_sel_hi:[0,1]
	v_pk_add_f32 v[186:187], v[186:187], v[186:187] op_sel:[0,1] op_sel_hi:[1,0] neg_lo:[0,1] neg_hi:[0,1]
	v_xor_b32_e32 v171, v181, v200
	v_pk_add_f32 v[202:203], v[210:211], v[210:211] op_sel:[0,1] op_sel_hi:[1,0] neg_lo:[0,1] neg_hi:[0,1]
	v_pk_add_f32 v[206:207], v[208:209], v[208:209] op_sel:[1,0] op_sel_hi:[0,1]
	v_pk_add_f32 v[210:211], v[174:175], v[174:175] op_sel:[1,0] op_sel_hi:[0,1]
	v_pk_add_f32 v[174:175], v[174:175], v[174:175] op_sel:[0,1] op_sel_hi:[1,0] neg_lo:[0,1] neg_hi:[0,1]
	v_pk_add_f32 v[214:215], v[176:177], v[176:177] op_sel:[1,0] op_sel_hi:[0,1]
	v_add_f32_dpp v171, v200, v171 quad_perm:[1,0,3,2] row_mask:0xf bank_mask:0xf bound_ctrl:1
	v_xor_b32_e32 v173, v181, v204
	v_xor_b32_e32 v205, v181, v186
	v_pk_add_f32 v[176:177], v[176:177], v[176:177] op_sel:[0,1] op_sel_hi:[1,0] neg_lo:[0,1] neg_hi:[0,1]
	v_add_f32_dpp v173, v204, v173 quad_perm:[1,0,3,2] row_mask:0xf bank_mask:0xf bound_ctrl:1
	v_xor_b32_e32 v175, v181, v206
	v_xor_b32_e32 v187, v181, v214
	v_add_f32_dpp v186, v186, v205 quad_perm:[1,0,3,2] row_mask:0xf bank_mask:0xf bound_ctrl:1
	v_xor_b32_e32 v205, v189, v171
	v_add_f32_dpp v175, v206, v175 quad_perm:[1,0,3,2] row_mask:0xf bank_mask:0xf bound_ctrl:1
	v_xor_b32_e32 v177, v181, v210
	v_add_f32_dpp v187, v214, v187 quad_perm:[1,0,3,2] row_mask:0xf bank_mask:0xf bound_ctrl:1
	v_add_f32_dpp v214, v171, v205 quad_perm:[2,3,0,1] row_mask:0xf bank_mask:0xf bound_ctrl:1
	v_xor_b32_e32 v171, v189, v173
	v_add_f32_dpp v177, v210, v177 quad_perm:[1,0,3,2] row_mask:0xf bank_mask:0xf bound_ctrl:1
	v_xor_b32_e32 v199, v181, v216
	v_add_f32_dpp v215, v173, v171 quad_perm:[2,3,0,1] row_mask:0xf bank_mask:0xf bound_ctrl:1
	v_xor_b32_e32 v171, v189, v175
	v_pk_add_f32 v[218:219], v[212:213], v[212:213] op_sel:[1,0] op_sel_hi:[0,1]
	v_add_f32_dpp v199, v216, v199 quad_perm:[1,0,3,2] row_mask:0xf bank_mask:0xf bound_ctrl:1
	v_add_f32_dpp v216, v175, v171 quad_perm:[2,3,0,1] row_mask:0xf bank_mask:0xf bound_ctrl:1
	v_xor_b32_e32 v171, v189, v177
	v_xor_b32_e32 v200, v181, v218
	v_xor_b32_e32 v201, v181, v220
	v_add_f32_dpp v217, v177, v171 quad_perm:[2,3,0,1] row_mask:0xf bank_mask:0xf bound_ctrl:1
	v_xor_b32_e32 v171, v189, v187
	v_add_f32_dpp v200, v218, v200 quad_perm:[1,0,3,2] row_mask:0xf bank_mask:0xf bound_ctrl:1
	v_add_f32_dpp v201, v220, v201 quad_perm:[1,0,3,2] row_mask:0xf bank_mask:0xf bound_ctrl:1
	v_add_f32_dpp v218, v187, v171 quad_perm:[2,3,0,1] row_mask:0xf bank_mask:0xf bound_ctrl:1
	v_xor_b32_e32 v171, v189, v199
	v_xor_b32_e32 v203, v181, v202
	v_pk_add_f32 v[208:209], v[208:209], v[208:209] op_sel:[0,1] op_sel_hi:[1,0] neg_lo:[0,1] neg_hi:[0,1]
	v_add_f32_dpp v199, v199, v171 quad_perm:[2,3,0,1] row_mask:0xf bank_mask:0xf bound_ctrl:1
	v_xor_b32_e32 v171, v189, v200
	v_add_f32_dpp v202, v202, v203 quad_perm:[1,0,3,2] row_mask:0xf bank_mask:0xf bound_ctrl:1
	v_xor_b32_e32 v203, v181, v172
	v_add_f32_dpp v219, v200, v171 quad_perm:[2,3,0,1] row_mask:0xf bank_mask:0xf bound_ctrl:1
	v_xor_b32_e32 v171, v189, v201
	v_add_f32_dpp v172, v172, v203 quad_perm:[1,0,3,2] row_mask:0xf bank_mask:0xf bound_ctrl:1
	v_xor_b32_e32 v203, v181, v208
	v_add_f32_dpp v220, v201, v171 quad_perm:[2,3,0,1] row_mask:0xf bank_mask:0xf bound_ctrl:1
	v_xor_b32_e32 v171, v189, v202
	v_add_f32_dpp v203, v208, v203 quad_perm:[1,0,3,2] row_mask:0xf bank_mask:0xf bound_ctrl:1
	v_xor_b32_e32 v204, v181, v174
	v_add_f32_dpp v221, v202, v171 quad_perm:[2,3,0,1] row_mask:0xf bank_mask:0xf bound_ctrl:1
	v_xor_b32_e32 v171, v189, v172
	v_add_f32_dpp v174, v174, v204 quad_perm:[1,0,3,2] row_mask:0xf bank_mask:0xf bound_ctrl:1
	v_xor_b32_e32 v204, v181, v176
	v_add_f32_dpp v223, v172, v171 quad_perm:[2,3,0,1] row_mask:0xf bank_mask:0xf bound_ctrl:1
	v_xor_b32_e32 v171, v189, v203
	v_pk_add_f32 v[212:213], v[212:213], v[212:213] op_sel:[0,1] op_sel_hi:[1,0] neg_lo:[0,1] neg_hi:[0,1]
	v_add_f32_dpp v176, v176, v204 quad_perm:[1,0,3,2] row_mask:0xf bank_mask:0xf bound_ctrl:1
	v_xor_b32_e32 v204, v181, v170
	v_add_f32_dpp v224, v203, v171 quad_perm:[2,3,0,1] row_mask:0xf bank_mask:0xf bound_ctrl:1
	v_xor_b32_e32 v171, v189, v174
	v_add_f32_dpp v170, v170, v204 quad_perm:[1,0,3,2] row_mask:0xf bank_mask:0xf bound_ctrl:1
	v_xor_b32_e32 v204, v181, v212
	v_add_f32_dpp v225, v174, v171 quad_perm:[2,3,0,1] row_mask:0xf bank_mask:0xf bound_ctrl:1
	v_xor_b32_e32 v171, v189, v176
	v_add_f32_dpp v204, v212, v204 quad_perm:[1,0,3,2] row_mask:0xf bank_mask:0xf bound_ctrl:1
	v_max_f32_e64 v172, |v219|, |v220|
	v_add_f32_dpp v226, v176, v171 quad_perm:[2,3,0,1] row_mask:0xf bank_mask:0xf bound_ctrl:1
	v_xor_b32_e32 v171, v189, v170
	v_lshlrev_b32_e32 v173, 16, v166
	v_and_b32_e32 v175, 0xffff0000, v166
	v_add_f32_dpp v227, v170, v171 quad_perm:[2,3,0,1] row_mask:0xf bank_mask:0xf bound_ctrl:1
	v_xor_b32_e32 v170, v189, v204
	v_max_f32_e64 v171, |v216|, |v217|
	v_and_b32_e32 v174, 0xffff0000, v162
	v_add_f32_dpp v228, v204, v170 quad_perm:[2,3,0,1] row_mask:0xf bank_mask:0xf bound_ctrl:1
	v_xor_b32_e32 v170, v189, v186
	v_lshlrev_b32_e32 v176, 16, v163
	v_lshlrev_b32_e32 v177, 16, v167
	v_add_f32_dpp v229, v186, v170 quad_perm:[2,3,0,1] row_mask:0xf bank_mask:0xf bound_ctrl:1
	v_max_f32_e64 v170, |v214|, |v215|
	v_max3_f32 v170, v222, v170, v171
	v_max_f32_e64 v171, |v218|, |v199|
	v_max3_f32 v170, v170, v171, v172
	v_max_f32_e64 v171, |v221|, |v223|
	v_max_f32_e64 v172, |v224|, |v225|
	v_max3_f32 v170, v170, v171, v172
	v_max_f32_e64 v171, |v226|, |v227|
	v_max_f32_e64 v172, |v228|, |v229|
	v_max3_f32 v222, v170, v171, v172
	v_and_b32_e32 v171, 0xffff0000, v169
	v_and_b32_e32 v170, 0xffff0000, v165
	v_lshlrev_b32_e32 v172, 16, v162
	v_and_b32_e32 v167, 0xffff0000, v167
	v_and_b32_e32 v166, 0xffff0000, v163
	v_lshlrev_b32_e32 v163, 16, v168
	v_lshlrev_b32_e32 v162, 16, v164
	v_and_b32_e32 v187, 0xffff0000, v168
	v_and_b32_e32 v186, 0xffff0000, v164
	v_lshlrev_b32_e32 v164, 16, v165
	v_lshlrev_b32_e32 v165, 16, v169
	v_pk_add_f32 v[168:169], v[172:173], v[174:175]
	v_pk_add_f32 v[200:201], v[176:177], v[166:167]
	v_pk_add_f32 v[202:203], v[162:163], v[186:187]
	v_pk_add_f32 v[204:205], v[164:165], v[170:171]
	v_pk_add_f32 v[172:173], v[172:173], v[174:175] neg_lo:[0,1] neg_hi:[0,1]
	v_pk_add_f32 v[166:167], v[176:177], v[166:167] neg_lo:[0,1] neg_hi:[0,1]
	v_pk_add_f32 v[162:163], v[162:163], v[186:187] neg_lo:[0,1] neg_hi:[0,1]
	v_pk_add_f32 v[164:165], v[164:165], v[170:171] neg_lo:[0,1] neg_hi:[0,1]
	v_pk_add_f32 v[206:207], v[168:169], v[200:201] neg_lo:[0,1] neg_hi:[0,1]
	v_pk_add_f32 v[208:209], v[202:203], v[204:205] neg_lo:[0,1] neg_hi:[0,1]
	v_pk_add_f32 v[168:169], v[168:169], v[200:201]
	v_pk_add_f32 v[200:201], v[202:203], v[204:205]
	v_pk_add_f32 v[170:171], v[172:173], v[166:167] neg_lo:[0,1] neg_hi:[0,1]
	v_pk_add_f32 v[174:175], v[162:163], v[164:165] neg_lo:[0,1] neg_hi:[0,1]
	v_pk_add_f32 v[166:167], v[172:173], v[166:167]
	v_pk_add_f32 v[162:163], v[162:163], v[164:165]
	v_pk_add_f32 v[202:203], v[168:169], v[200:201]
	v_pk_add_f32 v[168:169], v[168:169], v[200:201] neg_lo:[0,1] neg_hi:[0,1]
	v_pk_add_f32 v[200:201], v[206:207], v[208:209]
	v_pk_add_f32 v[164:165], v[166:167], v[162:163]
	v_pk_add_f32 v[162:163], v[166:167], v[162:163] neg_lo:[0,1] neg_hi:[0,1]
	v_pk_add_f32 v[166:167], v[170:171], v[174:175]
	v_pk_add_f32 v[204:205], v[206:207], v[208:209] neg_lo:[0,1] neg_hi:[0,1]
	v_pk_add_f32 v[170:171], v[170:171], v[174:175] neg_lo:[0,1] neg_hi:[0,1]
	v_pk_add_f32 v[172:173], v[202:203], v[202:203] op_sel:[1,0] op_sel_hi:[0,1]
	v_pk_add_f32 v[174:175], v[202:203], v[202:203] op_sel:[0,1] op_sel_hi:[1,0] neg_lo:[0,1] neg_hi:[0,1]
	v_pk_add_f32 v[186:187], v[200:201], v[200:201] op_sel:[1,0] op_sel_hi:[0,1]
	v_pk_add_f32 v[202:203], v[166:167], v[166:167] op_sel:[1,0] op_sel_hi:[0,1]
	v_pk_add_f32 v[166:167], v[166:167], v[166:167] op_sel:[0,1] op_sel_hi:[1,0] neg_lo:[0,1] neg_hi:[0,1]
	v_pk_add_f32 v[208:209], v[162:163], v[162:163] op_sel:[1,0] op_sel_hi:[0,1]
	v_pk_add_f32 v[162:163], v[162:163], v[162:163] op_sel:[0,1] op_sel_hi:[1,0] neg_lo:[0,1] neg_hi:[0,1]
	v_pk_add_f32 v[176:177], v[164:165], v[164:165] op_sel:[1,0] op_sel_hi:[0,1]
	v_pk_add_f32 v[164:165], v[164:165], v[164:165] op_sel:[0,1] op_sel_hi:[1,0] neg_lo:[0,1] neg_hi:[0,1]
	v_pk_add_f32 v[212:213], v[170:171], v[170:171] op_sel:[1,0] op_sel_hi:[0,1]
	v_pk_add_f32 v[170:171], v[170:171], v[170:171] op_sel:[0,1] op_sel_hi:[1,0] neg_lo:[0,1] neg_hi:[0,1]
	v_xor_b32_e32 v163, v181, v172
	v_xor_b32_e32 v167, v181, v186
	v_pk_add_f32 v[206:207], v[168:169], v[168:169] op_sel:[1,0] op_sel_hi:[0,1]
	v_add_f32_dpp v163, v172, v163 quad_perm:[1,0,3,2] row_mask:0xf bank_mask:0xf bound_ctrl:1
	v_xor_b32_e32 v165, v181, v176
	v_add_f32_dpp v167, v186, v167 quad_perm:[1,0,3,2] row_mask:0xf bank_mask:0xf bound_ctrl:1
	v_xor_b32_e32 v186, v181, v170
	v_pk_add_f32 v[168:169], v[168:169], v[168:169] op_sel:[0,1] op_sel_hi:[1,0] neg_lo:[0,1] neg_hi:[0,1]
	v_add_f32_dpp v165, v176, v165 quad_perm:[1,0,3,2] row_mask:0xf bank_mask:0xf bound_ctrl:1
	v_xor_b32_e32 v171, v181, v206
	v_add_f32_dpp v170, v170, v186 quad_perm:[1,0,3,2] row_mask:0xf bank_mask:0xf bound_ctrl:1
	v_xor_b32_e32 v186, v189, v163
	v_xor_b32_e32 v169, v181, v202
	v_add_f32_dpp v171, v206, v171 quad_perm:[1,0,3,2] row_mask:0xf bank_mask:0xf bound_ctrl:1
	v_add_f32_dpp v206, v163, v186 quad_perm:[2,3,0,1] row_mask:0xf bank_mask:0xf bound_ctrl:1
	v_xor_b32_e32 v163, v189, v165
	v_add_f32_dpp v169, v202, v169 quad_perm:[1,0,3,2] row_mask:0xf bank_mask:0xf bound_ctrl:1
	v_xor_b32_e32 v172, v181, v208
	v_add_f32_dpp v207, v165, v163 quad_perm:[2,3,0,1] row_mask:0xf bank_mask:0xf bound_ctrl:1
	v_xor_b32_e32 v163, v189, v167
	v_pk_add_f32 v[210:211], v[204:205], v[204:205] op_sel:[1,0] op_sel_hi:[0,1]
	v_add_f32_dpp v172, v208, v172 quad_perm:[1,0,3,2] row_mask:0xf bank_mask:0xf bound_ctrl:1
	v_add_f32_dpp v208, v167, v163 quad_perm:[2,3,0,1] row_mask:0xf bank_mask:0xf bound_ctrl:1
	v_xor_b32_e32 v163, v189, v169
	v_xor_b32_e32 v173, v181, v210
	v_xor_b32_e32 v175, v181, v212
	v_add_f32_dpp v209, v169, v163 quad_perm:[2,3,0,1] row_mask:0xf bank_mask:0xf bound_ctrl:1
	v_xor_b32_e32 v163, v189, v171
	v_add_f32_dpp v173, v210, v173 quad_perm:[1,0,3,2] row_mask:0xf bank_mask:0xf bound_ctrl:1
	v_add_f32_dpp v175, v212, v175 quad_perm:[1,0,3,2] row_mask:0xf bank_mask:0xf bound_ctrl:1
	v_add_f32_dpp v210, v171, v163 quad_perm:[2,3,0,1] row_mask:0xf bank_mask:0xf bound_ctrl:1
	v_xor_b32_e32 v163, v189, v172
	v_xor_b32_e32 v176, v181, v174
	v_pk_add_f32 v[200:201], v[200:201], v[200:201] op_sel:[0,1] op_sel_hi:[1,0] neg_lo:[0,1] neg_hi:[0,1]
	v_add_f32_dpp v211, v172, v163 quad_perm:[2,3,0,1] row_mask:0xf bank_mask:0xf bound_ctrl:1
	v_xor_b32_e32 v163, v189, v173
	v_add_f32_dpp v174, v174, v176 quad_perm:[1,0,3,2] row_mask:0xf bank_mask:0xf bound_ctrl:1
	v_xor_b32_e32 v176, v181, v164
	v_add_f32_dpp v212, v173, v163 quad_perm:[2,3,0,1] row_mask:0xf bank_mask:0xf bound_ctrl:1
	v_xor_b32_e32 v163, v189, v175
	v_add_f32_dpp v164, v164, v176 quad_perm:[1,0,3,2] row_mask:0xf bank_mask:0xf bound_ctrl:1
	v_xor_b32_e32 v176, v181, v200
	v_add_f32_dpp v213, v175, v163 quad_perm:[2,3,0,1] row_mask:0xf bank_mask:0xf bound_ctrl:1
	v_xor_b32_e32 v163, v189, v174
	v_add_f32_dpp v176, v200, v176 quad_perm:[1,0,3,2] row_mask:0xf bank_mask:0xf bound_ctrl:1
	v_xor_b32_e32 v177, v181, v166
	v_add_f32_dpp v230, v174, v163 quad_perm:[2,3,0,1] row_mask:0xf bank_mask:0xf bound_ctrl:1
	v_xor_b32_e32 v163, v189, v164
	v_add_f32_dpp v166, v166, v177 quad_perm:[1,0,3,2] row_mask:0xf bank_mask:0xf bound_ctrl:1
	v_xor_b32_e32 v177, v181, v168
	v_add_f32_dpp v231, v164, v163 quad_perm:[2,3,0,1] row_mask:0xf bank_mask:0xf bound_ctrl:1
	v_xor_b32_e32 v163, v189, v176
	v_pk_add_f32 v[204:205], v[204:205], v[204:205] op_sel:[0,1] op_sel_hi:[1,0] neg_lo:[0,1] neg_hi:[0,1]
	v_add_f32_dpp v168, v168, v177 quad_perm:[1,0,3,2] row_mask:0xf bank_mask:0xf bound_ctrl:1
	v_xor_b32_e32 v177, v181, v162
	v_add_f32_dpp v232, v176, v163 quad_perm:[2,3,0,1] row_mask:0xf bank_mask:0xf bound_ctrl:1
	v_xor_b32_e32 v163, v189, v166
	v_add_f32_dpp v162, v162, v177 quad_perm:[1,0,3,2] row_mask:0xf bank_mask:0xf bound_ctrl:1
	v_xor_b32_e32 v177, v181, v204
	v_add_f32_dpp v233, v166, v163 quad_perm:[2,3,0,1] row_mask:0xf bank_mask:0xf bound_ctrl:1
	v_xor_b32_e32 v163, v189, v168
	v_add_f32_dpp v177, v204, v177 quad_perm:[1,0,3,2] row_mask:0xf bank_mask:0xf bound_ctrl:1
	v_max_f32_e64 v164, |v212|, |v213|
	v_add_f32_dpp v235, v168, v163 quad_perm:[2,3,0,1] row_mask:0xf bank_mask:0xf bound_ctrl:1
	v_xor_b32_e32 v163, v189, v162
	v_lshlrev_b32_e32 v165, 16, v158
	v_and_b32_e32 v167, 0xffff0000, v158
	v_add_f32_dpp v236, v162, v163 quad_perm:[2,3,0,1] row_mask:0xf bank_mask:0xf bound_ctrl:1
	v_xor_b32_e32 v162, v189, v177
	v_max_f32_e64 v163, |v208|, |v209|
	v_and_b32_e32 v166, 0xffff0000, v150
	v_add_f32_dpp v237, v177, v162 quad_perm:[2,3,0,1] row_mask:0xf bank_mask:0xf bound_ctrl:1
	v_xor_b32_e32 v162, v189, v170
	v_lshlrev_b32_e32 v168, 16, v151
	v_lshlrev_b32_e32 v169, 16, v159
	v_add_f32_dpp v238, v170, v162 quad_perm:[2,3,0,1] row_mask:0xf bank_mask:0xf bound_ctrl:1
	v_max_f32_e64 v162, |v206|, |v207|
	v_max3_f32 v162, v222, v162, v163
	v_max_f32_e64 v163, |v210|, |v211|
	v_max3_f32 v162, v162, v163, v164
	v_max_f32_e64 v163, |v230|, |v231|
	v_max_f32_e64 v164, |v232|, |v233|
	v_max3_f32 v162, v162, v163, v164
	v_max_f32_e64 v163, |v235|, |v236|
	v_max_f32_e64 v164, |v237|, |v238|
	v_max3_f32 v222, v162, v163, v164
	v_and_b32_e32 v163, 0xffff0000, v161
	v_and_b32_e32 v162, 0xffff0000, v153
	v_lshlrev_b32_e32 v164, 16, v150
	v_and_b32_e32 v159, 0xffff0000, v159
	v_and_b32_e32 v158, 0xffff0000, v151
	v_lshlrev_b32_e32 v151, 16, v160
	v_lshlrev_b32_e32 v150, 16, v152
	v_and_b32_e32 v171, 0xffff0000, v160
	v_and_b32_e32 v170, 0xffff0000, v152
	v_lshlrev_b32_e32 v152, 16, v153
	v_lshlrev_b32_e32 v153, 16, v161
	v_pk_add_f32 v[160:161], v[164:165], v[166:167]
	v_pk_add_f32 v[172:173], v[168:169], v[158:159]
	v_pk_add_f32 v[174:175], v[150:151], v[170:171]
	v_pk_add_f32 v[176:177], v[152:153], v[162:163]
	v_pk_add_f32 v[164:165], v[164:165], v[166:167] neg_lo:[0,1] neg_hi:[0,1]
	v_pk_add_f32 v[158:159], v[168:169], v[158:159] neg_lo:[0,1] neg_hi:[0,1]
	v_pk_add_f32 v[150:151], v[150:151], v[170:171] neg_lo:[0,1] neg_hi:[0,1]
	v_pk_add_f32 v[152:153], v[152:153], v[162:163] neg_lo:[0,1] neg_hi:[0,1]
	v_pk_add_f32 v[186:187], v[160:161], v[172:173] neg_lo:[0,1] neg_hi:[0,1]
	v_pk_add_f32 v[200:201], v[174:175], v[176:177] neg_lo:[0,1] neg_hi:[0,1]
	v_pk_add_f32 v[160:161], v[160:161], v[172:173]
	v_pk_add_f32 v[172:173], v[174:175], v[176:177]
	v_pk_add_f32 v[162:163], v[164:165], v[158:159] neg_lo:[0,1] neg_hi:[0,1]
	v_pk_add_f32 v[166:167], v[150:151], v[152:153] neg_lo:[0,1] neg_hi:[0,1]
	v_pk_add_f32 v[158:159], v[164:165], v[158:159]
	v_pk_add_f32 v[150:151], v[150:151], v[152:153]
	v_pk_add_f32 v[174:175], v[160:161], v[172:173]
	v_pk_add_f32 v[160:161], v[160:161], v[172:173] neg_lo:[0,1] neg_hi:[0,1]
	v_pk_add_f32 v[172:173], v[186:187], v[200:201]
	v_pk_add_f32 v[152:153], v[158:159], v[150:151]
	v_pk_add_f32 v[150:151], v[158:159], v[150:151] neg_lo:[0,1] neg_hi:[0,1]
	v_pk_add_f32 v[158:159], v[162:163], v[166:167]
	v_pk_add_f32 v[176:177], v[186:187], v[200:201] neg_lo:[0,1] neg_hi:[0,1]
	v_pk_add_f32 v[162:163], v[162:163], v[166:167] neg_lo:[0,1] neg_hi:[0,1]
	v_pk_add_f32 v[164:165], v[174:175], v[174:175] op_sel:[1,0] op_sel_hi:[0,1]
	v_pk_add_f32 v[166:167], v[174:175], v[174:175] op_sel:[0,1] op_sel_hi:[1,0] neg_lo:[0,1] neg_hi:[0,1]
	v_pk_add_f32 v[170:171], v[172:173], v[172:173] op_sel:[1,0] op_sel_hi:[0,1]
	v_pk_add_f32 v[174:175], v[158:159], v[158:159] op_sel:[1,0] op_sel_hi:[0,1]
	v_pk_add_f32 v[158:159], v[158:159], v[158:159] op_sel:[0,1] op_sel_hi:[1,0] neg_lo:[0,1] neg_hi:[0,1]
	v_pk_add_f32 v[200:201], v[150:151], v[150:151] op_sel:[1,0] op_sel_hi:[0,1]
	v_pk_add_f32 v[150:151], v[150:151], v[150:151] op_sel:[0,1] op_sel_hi:[1,0] neg_lo:[0,1] neg_hi:[0,1]
	v_pk_add_f32 v[168:169], v[152:153], v[152:153] op_sel:[1,0] op_sel_hi:[0,1]
	v_pk_add_f32 v[152:153], v[152:153], v[152:153] op_sel:[0,1] op_sel_hi:[1,0] neg_lo:[0,1] neg_hi:[0,1]
	v_pk_add_f32 v[204:205], v[162:163], v[162:163] op_sel:[1,0] op_sel_hi:[0,1]
	v_pk_add_f32 v[162:163], v[162:163], v[162:163] op_sel:[0,1] op_sel_hi:[1,0] neg_lo:[0,1] neg_hi:[0,1]
	v_xor_b32_e32 v151, v181, v164
	v_xor_b32_e32 v159, v181, v170
	v_xor_b32_e32 v153, v181, v168
	v_add_f32_dpp v151, v164, v151 quad_perm:[1,0,3,2] row_mask:0xf bank_mask:0xf bound_ctrl:1
	v_add_f32_dpp v159, v170, v159 quad_perm:[1,0,3,2] row_mask:0xf bank_mask:0xf bound_ctrl:1
	v_xor_b32_e32 v170, v181, v162
	v_pk_add_f32 v[186:187], v[160:161], v[160:161] op_sel:[1,0] op_sel_hi:[0,1]
	v_pk_add_f32 v[160:161], v[160:161], v[160:161] op_sel:[0,1] op_sel_hi:[1,0] neg_lo:[0,1] neg_hi:[0,1]
	v_add_f32_dpp v153, v168, v153 quad_perm:[1,0,3,2] row_mask:0xf bank_mask:0xf bound_ctrl:1
	v_add_f32_dpp v162, v162, v170 quad_perm:[1,0,3,2] row_mask:0xf bank_mask:0xf bound_ctrl:1
	v_xor_b32_e32 v170, v189, v151
	v_xor_b32_e32 v161, v181, v174
	v_xor_b32_e32 v163, v181, v186
	v_add_f32_dpp v151, v151, v170 quad_perm:[2,3,0,1] row_mask:0xf bank_mask:0xf bound_ctrl:1
	v_xor_b32_e32 v170, v189, v153
	v_add_f32_dpp v161, v174, v161 quad_perm:[1,0,3,2] row_mask:0xf bank_mask:0xf bound_ctrl:1
	v_pk_add_f32 v[202:203], v[176:177], v[176:177] op_sel:[1,0] op_sel_hi:[0,1]
	v_add_f32_dpp v153, v153, v170 quad_perm:[2,3,0,1] row_mask:0xf bank_mask:0xf bound_ctrl:1
	v_xor_b32_e32 v170, v189, v159
	v_add_f32_dpp v163, v186, v163 quad_perm:[1,0,3,2] row_mask:0xf bank_mask:0xf bound_ctrl:1
	v_xor_b32_e32 v164, v181, v200
	v_add_f32_dpp v159, v159, v170 quad_perm:[2,3,0,1] row_mask:0xf bank_mask:0xf bound_ctrl:1
	v_xor_b32_e32 v170, v189, v161
	v_add_f32_dpp v164, v200, v164 quad_perm:[1,0,3,2] row_mask:0xf bank_mask:0xf bound_ctrl:1
	v_xor_b32_e32 v165, v181, v202
	v_add_f32_dpp v161, v161, v170 quad_perm:[2,3,0,1] row_mask:0xf bank_mask:0xf bound_ctrl:1
	v_xor_b32_e32 v170, v189, v163
	v_add_f32_dpp v165, v202, v165 quad_perm:[1,0,3,2] row_mask:0xf bank_mask:0xf bound_ctrl:1
	v_xor_b32_e32 v167, v181, v204
	v_add_f32_dpp v186, v163, v170 quad_perm:[2,3,0,1] row_mask:0xf bank_mask:0xf bound_ctrl:1
	v_xor_b32_e32 v163, v189, v164
	v_add_f32_dpp v167, v204, v167 quad_perm:[1,0,3,2] row_mask:0xf bank_mask:0xf bound_ctrl:1
	v_xor_b32_e32 v168, v181, v166
	v_add_f32_dpp v187, v164, v163 quad_perm:[2,3,0,1] row_mask:0xf bank_mask:0xf bound_ctrl:1
	v_xor_b32_e32 v163, v189, v165
	v_pk_add_f32 v[172:173], v[172:173], v[172:173] op_sel:[0,1] op_sel_hi:[1,0] neg_lo:[0,1] neg_hi:[0,1]
	v_add_f32_dpp v166, v166, v168 quad_perm:[1,0,3,2] row_mask:0xf bank_mask:0xf bound_ctrl:1
	v_xor_b32_e32 v168, v181, v152
	v_add_f32_dpp v200, v165, v163 quad_perm:[2,3,0,1] row_mask:0xf bank_mask:0xf bound_ctrl:1
	v_xor_b32_e32 v163, v189, v167
	v_add_f32_dpp v152, v152, v168 quad_perm:[1,0,3,2] row_mask:0xf bank_mask:0xf bound_ctrl:1
	v_xor_b32_e32 v168, v181, v172
	v_add_f32_dpp v201, v167, v163 quad_perm:[2,3,0,1] row_mask:0xf bank_mask:0xf bound_ctrl:1
	v_xor_b32_e32 v163, v189, v166
	v_add_f32_dpp v168, v172, v168 quad_perm:[1,0,3,2] row_mask:0xf bank_mask:0xf bound_ctrl:1
	v_xor_b32_e32 v169, v181, v158
	v_add_f32_dpp v202, v166, v163 quad_perm:[2,3,0,1] row_mask:0xf bank_mask:0xf bound_ctrl:1
	v_xor_b32_e32 v163, v189, v152
	v_add_f32_dpp v158, v158, v169 quad_perm:[1,0,3,2] row_mask:0xf bank_mask:0xf bound_ctrl:1
	v_xor_b32_e32 v169, v181, v160
	v_add_f32_dpp v203, v152, v163 quad_perm:[2,3,0,1] row_mask:0xf bank_mask:0xf bound_ctrl:1
	v_xor_b32_e32 v152, v189, v168
	v_pk_add_f32 v[176:177], v[176:177], v[176:177] op_sel:[0,1] op_sel_hi:[1,0] neg_lo:[0,1] neg_hi:[0,1]
	v_add_f32_dpp v160, v160, v169 quad_perm:[1,0,3,2] row_mask:0xf bank_mask:0xf bound_ctrl:1
	v_xor_b32_e32 v169, v181, v150
	v_add_f32_dpp v204, v168, v152 quad_perm:[2,3,0,1] row_mask:0xf bank_mask:0xf bound_ctrl:1
	v_xor_b32_e32 v152, v189, v158
	v_add_f32_dpp v150, v150, v169 quad_perm:[1,0,3,2] row_mask:0xf bank_mask:0xf bound_ctrl:1
	v_xor_b32_e32 v169, v181, v176
	v_add_f32_dpp v205, v158, v152 quad_perm:[2,3,0,1] row_mask:0xf bank_mask:0xf bound_ctrl:1
	v_xor_b32_e32 v152, v189, v160
	v_add_f32_dpp v169, v176, v169 quad_perm:[1,0,3,2] row_mask:0xf bank_mask:0xf bound_ctrl:1
	v_max_f32_e64 v158, |v200|, |v201|
	v_add_f32_dpp v160, v160, v152 quad_perm:[2,3,0,1] row_mask:0xf bank_mask:0xf bound_ctrl:1
	v_xor_b32_e32 v152, v189, v150
	v_cvt_pk_bf16_f32 v170, v214, v215
	v_cvt_pk_bf16_f32 v171, v216, v217
	v_cvt_pk_bf16_f32 v172, v218, v199
	v_cvt_pk_bf16_f32 v173, v219, v220
	v_cvt_pk_bf16_f32 v174, v221, v223
	s_nop 1
	v_add_f32_dpp v239, v150, v152 quad_perm:[2,3,0,1] row_mask:0xf bank_mask:0xf bound_ctrl:1
	v_xor_b32_e32 v150, v189, v169
	v_max_f32_e64 v152, |v159|, |v161|
	v_cvt_pk_bf16_f32 v175, v224, v225
	v_cvt_pk_bf16_f32 v176, v226, v227
	v_cvt_pk_bf16_f32 v177, v228, v229
	s_nop 0
	v_add_f32_dpp v240, v169, v150 quad_perm:[2,3,0,1] row_mask:0xf bank_mask:0xf bound_ctrl:1
	v_xor_b32_e32 v150, v189, v162
	s_nop 1
	v_add_f32_dpp v241, v162, v150 quad_perm:[2,3,0,1] row_mask:0xf bank_mask:0xf bound_ctrl:1
	v_max_f32_e64 v150, |v151|, |v153|
	v_max3_f32 v150, v222, v150, v152
	v_max_f32_e64 v152, |v186|, |v187|
	v_max3_f32 v150, v150, v152, v158
	v_max_f32_e64 v152, |v202|, |v203|
	v_max_f32_e64 v158, |v204|, |v205|
	v_max3_f32 v150, v150, v152, v158
	v_max_f32_e64 v152, |v160|, |v239|
	v_max_f32_e64 v158, |v240|, |v241|
	v_max3_f32 v150, v150, v152, v158
	v_cvt_pk_bf16_f32 v162, v206, v207
	v_cvt_pk_bf16_f32 v163, v208, v209
	v_cvt_pk_bf16_f32 v164, v210, v211
	v_cvt_pk_bf16_f32 v165, v212, v213
	s_waitcnt lgkmcnt(0)
	s_nop 1
	v_max_f32_dpp v150, v150, v150 quad_perm:[1,0,3,2] row_mask:0xf bank_mask:0xf
	v_cvt_pk_bf16_f32 v166, v230, v231
	v_cvt_pk_bf16_f32 v167, v232, v233
	v_cvt_pk_bf16_f32 v168, v235, v236
	v_cvt_pk_bf16_f32 v169, v237, v238
	s_waitcnt lgkmcnt(0)
	s_nop 1
	v_max_f32_dpp v150, v150, v150 quad_perm:[2,3,0,1] row_mask:0xf bank_mask:0xf
	s_waitcnt lgkmcnt(0)
	s_nop 1
	v_max_f32_dpp v150, v150, v150 row_half_mirror row_mask:0xf bank_mask:0xf
	s_waitcnt lgkmcnt(0)
	s_nop 1
	v_max_f32_dpp v158, v150, v150 row_mirror row_mask:0xf bank_mask:0xf
	ds_bpermute_b32 v193, v197, v158
	v_cvt_pk_bf16_f32 v150, v151, v153
	v_cvt_pk_bf16_f32 v151, v159, v161
	v_cvt_pk_bf16_f32 v152, v186, v187
	v_cvt_pk_bf16_f32 v153, v200, v201
	s_waitcnt lgkmcnt(0)
	v_max_f32_e32 v159, v193, v193
	v_max_f32_e32 v186, v158, v159
	v_cvt_pk_bf16_f32 v158, v202, v203
	v_cvt_pk_bf16_f32 v159, v204, v205
	v_cvt_pk_bf16_f32 v160, v160, v239
	v_cvt_pk_bf16_f32 v161, v240, v241
	s_waitcnt lgkmcnt(0)
	v_mov_b32_e32 v187, v186
	s_nop 1
	v_permlane32_swap_b32_e32 v187, v186
	v_max_f32_e32 v186, v186, v187
	s_and_saveexec_b64 s[28:29], s[2:3]
	s_cbranch_execz .LBB0_1019
	s_lshl_b64 s[30:31], s[26:27], 2
	s_sub_u32 s30, s37, s30
	s_subb_u32 s31, s38, s31
	v_mul_f32_e32 v187, 0x3a810204, v186
	global_store_dword v179, v187, s[30:31]

.LBB0_1174:
	s_add_i32 s14, s42, s23
	s_mov_b64 s[2:3], -1
	s_cmpk_gt_i32 s14, 0x1fff
	v_lshl_add_u64 v[10:11], s[4:5], 0, v[146:147]
	s_cbranch_scc0 .LBB0_1178
	v_add_co_u32_e32 v16, vcc, s19, v10
	s_nop 1
	v_addc_co_u32_e32 v17, vcc, 0, v11, vcc
	s_waitcnt lgkmcnt(0)
	global_load_dwordx4 v[2:5], v[16:17], off
	global_load_dwordx4 v[6:9], v[16:17], off offset:1024
	global_load_dwordx4 v[12:15], v[16:17], off offset:2048
	global_load_dwordx4 v[40:43], v[16:17], off offset:3072
	v_add_co_u32_e32 v16, vcc, 0x3b100000, v10
	s_waitcnt vmcnt(3)
	v_lshlrev_b32_e32 v39, 16, v2
	v_addc_co_u32_e32 v17, vcc, 0, v11, vcc
	global_load_dwordx4 v[44:47], v[16:17], off
	global_load_dwordx4 v[48:51], v[16:17], off offset:1024
	global_load_dwordx4 v[52:55], v[16:17], off offset:2048
	global_load_dwordx4 v[56:59], v[16:17], off offset:3072
	v_and_b32_e32 v60, 0xffff0000, v2
	v_lshlrev_b32_e32 v61, 16, v3
	v_and_b32_e32 v62, 0xffff0000, v3
	v_lshlrev_b32_e32 v63, 16, v4
	v_and_b32_e32 v38, 0xffff0000, v4
	v_lshlrev_b32_e32 v37, 16, v5
	v_and_b32_e32 v36, 0xffff0000, v5
	s_waitcnt vmcnt(6)
	v_lshlrev_b32_e32 v35, 16, v6
	v_and_b32_e32 v34, 0xffff0000, v6
	v_lshlrev_b32_e32 v33, 16, v7
	v_and_b32_e32 v32, 0xffff0000, v7
	v_lshlrev_b32_e32 v31, 16, v8
	v_and_b32_e32 v30, 0xffff0000, v8
	v_lshlrev_b32_e32 v29, 16, v9
	v_and_b32_e32 v28, 0xffff0000, v9
	s_waitcnt vmcnt(5)
	v_lshlrev_b32_e32 v27, 16, v12
	v_and_b32_e32 v26, 0xffff0000, v12
	v_lshlrev_b32_e32 v25, 16, v13
	v_and_b32_e32 v24, 0xffff0000, v13
	v_lshlrev_b32_e32 v23, 16, v14
	v_and_b32_e32 v22, 0xffff0000, v14
	v_lshlrev_b32_e32 v21, 16, v15
	v_and_b32_e32 v20, 0xffff0000, v15
	s_waitcnt vmcnt(4)
	v_lshlrev_b32_e32 v16, 16, v40
	v_and_b32_e32 v15, 0xffff0000, v40
	v_lshlrev_b32_e32 v13, 16, v41
	v_and_b32_e32 v12, 0xffff0000, v41
	v_lshlrev_b32_e32 v9, 16, v42
	v_and_b32_e32 v8, 0xffff0000, v42
	v_cmp_lt_i32_e32 vcc, v162, v161
	v_lshlrev_b32_e32 v7, 16, v43
	v_and_b32_e32 v6, 0xffff0000, v43
	v_cndmask_b32_e32 v17, v160, v162, vcc
	v_lshlrev_b32_e32 v4, 2, v17
	v_cmp_lt_i32_e32 vcc, v163, v161
	s_waitcnt vmcnt(3)
	v_and_b32_e32 v65, 0xffff0000, v44
	v_lshlrev_b32_e32 v64, 16, v44
	v_mul_f32_e32 v2, v65, v65
	v_lshlrev_b32_e32 v66, 16, v45
	v_fmac_f32_e32 v2, v64, v64
	v_and_b32_e32 v67, 0xffff0000, v45
	v_fmac_f32_e32 v2, v66, v66
	v_lshlrev_b32_e32 v68, 16, v46
	v_fmac_f32_e32 v2, v67, v67
	v_and_b32_e32 v69, 0xffff0000, v46
	v_fmac_f32_e32 v2, v68, v68
	v_lshlrev_b32_e32 v70, 16, v47
	v_fmac_f32_e32 v2, v69, v69
	v_and_b32_e32 v71, 0xffff0000, v47
	v_fmac_f32_e32 v2, v70, v70
	s_waitcnt vmcnt(2)
	v_lshlrev_b32_e32 v72, 16, v48
	v_fmac_f32_e32 v2, v71, v71
	v_and_b32_e32 v73, 0xffff0000, v48
	v_fmac_f32_e32 v2, v72, v72
	v_lshlrev_b32_e32 v74, 16, v49
	v_fmac_f32_e32 v2, v73, v73
	v_and_b32_e32 v75, 0xffff0000, v49
	v_fmac_f32_e32 v2, v74, v74
	v_lshlrev_b32_e32 v76, 16, v50
	v_fmac_f32_e32 v2, v75, v75
	v_and_b32_e32 v77, 0xffff0000, v50
	v_fmac_f32_e32 v2, v76, v76
	v_lshlrev_b32_e32 v78, 16, v51
	v_fmac_f32_e32 v2, v77, v77
	v_and_b32_e32 v79, 0xffff0000, v51
	v_fmac_f32_e32 v2, v78, v78
	s_waitcnt vmcnt(1)
	v_lshlrev_b32_e32 v80, 16, v52
	v_fmac_f32_e32 v2, v79, v79
	v_and_b32_e32 v81, 0xffff0000, v52
	v_fmac_f32_e32 v2, v80, v80
	v_lshlrev_b32_e32 v82, 16, v53
	v_fmac_f32_e32 v2, v81, v81
	v_and_b32_e32 v83, 0xffff0000, v53
	v_fmac_f32_e32 v2, v82, v82
	v_lshlrev_b32_e32 v84, 16, v54
	v_fmac_f32_e32 v2, v83, v83
	v_and_b32_e32 v54, 0xffff0000, v54
	v_fmac_f32_e32 v2, v84, v84
	v_lshlrev_b32_e32 v85, 16, v55
	v_fmac_f32_e32 v2, v54, v54
	v_and_b32_e32 v55, 0xffff0000, v55
	v_fmac_f32_e32 v2, v85, v85
	s_waitcnt vmcnt(0)
	v_lshlrev_b32_e32 v86, 16, v56
	v_fmac_f32_e32 v2, v55, v55
	v_and_b32_e32 v56, 0xffff0000, v56
	v_fmac_f32_e32 v2, v86, v86
	v_lshlrev_b32_e32 v87, 16, v57
	v_fmac_f32_e32 v2, v56, v56
	v_and_b32_e32 v57, 0xffff0000, v57
	v_fmac_f32_e32 v2, v87, v87
	v_lshlrev_b32_e32 v88, 16, v58
	v_fmac_f32_e32 v2, v57, v57
	v_and_b32_e32 v58, 0xffff0000, v58
	v_fmac_f32_e32 v2, v88, v88
	v_lshlrev_b32_e32 v89, 16, v59
	v_fmac_f32_e32 v2, v58, v58
	v_and_b32_e32 v59, 0xffff0000, v59
	v_fmac_f32_e32 v2, v89, v89
	v_fmac_f32_e32 v2, v59, v59
	v_fmac_f32_e32 v2, v39, v39
	v_fmac_f32_e32 v2, v60, v60
	v_fmac_f32_e32 v2, v61, v61
	v_fmac_f32_e32 v2, v62, v62
	v_fmac_f32_e32 v2, v63, v63
	v_fmac_f32_e32 v2, v38, v38
	v_fmac_f32_e32 v2, v37, v37
	v_fmac_f32_e32 v2, v36, v36
	v_fmac_f32_e32 v2, v35, v35
	v_fmac_f32_e32 v2, v34, v34
	v_fmac_f32_e32 v2, v33, v33
	v_fmac_f32_e32 v2, v32, v32
	v_fmac_f32_e32 v2, v31, v31
	v_fmac_f32_e32 v2, v30, v30
	v_fmac_f32_e32 v2, v29, v29
	v_fmac_f32_e32 v2, v28, v28
	v_fmac_f32_e32 v2, v27, v27
	v_fmac_f32_e32 v2, v26, v26
	v_fmac_f32_e32 v2, v25, v25
	v_fmac_f32_e32 v2, v24, v24
	v_fmac_f32_e32 v2, v23, v23
	v_fmac_f32_e32 v2, v22, v22
	v_fmac_f32_e32 v2, v21, v21
	v_fmac_f32_e32 v2, v20, v20
	v_fmac_f32_e32 v2, v16, v16
	v_fmac_f32_e32 v2, v15, v15
	v_fmac_f32_e32 v2, v13, v13
	v_fmac_f32_e32 v2, v12, v12
	v_fmac_f32_e32 v2, v9, v9
	v_fmac_f32_e32 v2, v8, v8
	v_fmac_f32_e32 v2, v7, v7
	v_fmac_f32_e32 v2, v6, v6
	v_cndmask_b32_e32 v5, v160, v163, vcc
	global_load_dwordx4 v[44:47], v[132:133], off
	global_load_dwordx4 v[48:51], v[132:133], off offset:16
	v_lshlrev_b32_e32 v5, 2, v5
	s_waitcnt lgkmcnt(0)
	s_nop 1
	v_add_f32_dpp v14, v2, v2 quad_perm:[1,0,3,2] row_mask:0xf bank_mask:0xf
	v_add_co_u32_e32 v2, vcc, s22, v10
	s_nop 0
	v_addc_co_u32_e32 v3, vcc, 0, v11, vcc
	global_load_dwordx4 v[40:43], v[2:3], off offset:-4096
	v_cmp_lt_i32_e32 vcc, v164, v161
	s_waitcnt lgkmcnt(0)
	s_nop 1
	v_add_f32_dpp v17, v14, v14 quad_perm:[2,3,0,1] row_mask:0xf bank_mask:0xf
	s_waitcnt vmcnt(0)
	v_and_b32_e32 v94, 0xffff0000, v41
	v_cndmask_b32_e32 v14, v160, v164, vcc
	v_lshlrev_b32_e32 v14, 2, v14
	v_cmp_lt_i32_e32 vcc, v165, v161
	v_lshlrev_b32_e32 v95, 16, v42
	v_and_b32_e32 v96, 0xffff0000, v42
	v_lshlrev_b32_e32 v97, 16, v43
	s_waitcnt lgkmcnt(0)
	s_nop 1
	v_add_f32_dpp v18, v17, v17 row_half_mirror row_mask:0xf bank_mask:0xf
	v_cndmask_b32_e32 v17, v160, v165, vcc
	v_lshlrev_b32_e32 v17, 2, v17
	v_cmp_lt_i32_e32 vcc, v166, v161
	v_and_b32_e32 v98, 0xffff0000, v43
	s_waitcnt lgkmcnt(0)
	s_nop 1
	v_add_f32_dpp v19, v18, v18 row_mirror row_mask:0xf bank_mask:0xf
	v_cndmask_b32_e32 v18, v160, v166, vcc
	v_lshlrev_b32_e32 v18, 2, v18
	ds_bpermute_b32 v52, v18, v19
	v_cmp_lt_i32_e32 vcc, v167, v161
	s_waitcnt lgkmcnt(0)
	v_add_f32_e32 v52, v19, v52
	v_cndmask_b32_e32 v19, v160, v167, vcc
	v_lshlrev_b32_e32 v19, 2, v19
	s_waitcnt lgkmcnt(0)
	v_mov_b32_e32 v53, v52
	s_nop 1
	v_permlane32_swap_b32_e32 v53, v52
	v_add_f32_e32 v52, v52, v53
	v_fmamk_f32 v52, v52, 0x39800000, v158
	v_mul_f32_e32 v53, 0x4f800000, v52
	v_cmp_gt_f32_e32 vcc, s20, v52
	s_nop 1
	v_cndmask_b32_e32 v52, v52, v53, vcc
	v_sqrt_f32_e32 v53, v52
	s_nop 0
	v_add_u32_e32 v90, -1, v53
	v_add_u32_e32 v91, 1, v53
	v_fma_f32 v92, -v90, v53, v52
	v_fma_f32 v93, -v91, v53, v52
	v_cmp_ge_f32_e64 s[2:3], 0, v92
	s_nop 1
	v_cndmask_b32_e64 v53, v53, v90, s[2:3]
	v_cmp_lt_f32_e64 s[2:3], 0, v93
	s_nop 1
	v_cndmask_b32_e64 v53, v53, v91, s[2:3]
	v_mul_f32_e32 v90, 0x37800000, v53
	v_cndmask_b32_e32 v53, v53, v90, vcc
	v_cmp_class_f32_e32 vcc, v52, v159
	s_nop 1
	v_cndmask_b32_e32 v52, v53, v52, vcc
	v_div_scale_f32 v53, s[2:3], v52, v52, 1.0
	v_rcp_f32_e32 v90, v53
	s_nop 0
	v_fma_f32 v91, -v53, v90, 1.0
	v_fmac_f32_e32 v90, v91, v90
	v_div_scale_f32 v91, vcc, 1.0, v52, 1.0
	v_mul_f32_e32 v92, v91, v90
	v_fma_f32 v93, -v53, v92, v91
	v_fmac_f32_e32 v92, v93, v90
	v_fma_f32 v53, -v53, v92, v91
	v_div_fmas_f32 v53, v53, v90, v92
	v_div_fixup_f32 v90, v53, v52, 1.0
	v_lshlrev_b32_e32 v91, 16, v40
	v_and_b32_e32 v92, 0xffff0000, v40
	v_mul_f32_e32 v40, v90, v64
	v_fmac_f32_e32 v91, v44, v40
	v_mul_f32_e32 v40, v90, v65
	v_lshlrev_b32_e32 v93, 16, v41
	v_fmac_f32_e32 v92, v45, v40
	v_mul_f32_e32 v40, v90, v66
	v_fmac_f32_e32 v93, v46, v40
	v_mul_f32_e32 v40, v90, v67
	v_fmac_f32_e32 v94, v47, v40
	v_mul_f32_e32 v40, v90, v68
	v_fmac_f32_e32 v95, v48, v40
	v_mul_f32_e32 v40, v90, v69
	v_add_co_u32_e32 v52, vcc, s21, v10
	v_fmac_f32_e32 v96, v49, v40
	v_mul_f32_e32 v40, v90, v70
	v_addc_co_u32_e32 v53, vcc, 0, v11, vcc
	v_fmac_f32_e32 v97, v50, v40
	v_mul_f32_e32 v40, v90, v71
	v_fmac_f32_e32 v98, v51, v40
	v_cvt_pk_bf16_f32 v40, v91, v92
	v_cvt_pk_bf16_f32 v41, v93, v94
	v_cvt_pk_bf16_f32 v42, v95, v96
	v_cvt_pk_bf16_f32 v43, v97, v98
	global_load_dwordx4 v[44:47], v[52:53], off offset:1024
	v_mul_f32_e32 v64, v90, v72
	global_store_dwordx4 v[2:3], v[40:43], off offset:-4096
	global_load_dwordx4 v[40:43], v[132:133], off offset:2048
	s_nop 0
	global_load_dwordx4 v[48:51], v[132:133], off offset:2064
	v_mul_f32_e32 v65, v90, v73
	v_mul_f32_e32 v66, v90, v74
	v_mul_f32_e32 v67, v90, v75
	v_mul_f32_e32 v68, v90, v76
	v_mul_f32_e32 v69, v90, v77
	v_mul_f32_e32 v70, v90, v78
	v_mul_f32_e32 v71, v90, v79
	v_mul_f32_e32 v54, v90, v54
	v_mul_f32_e32 v55, v90, v55
	v_mul_f32_e32 v57, v90, v57
	v_mul_f32_e32 v58, v90, v58
	v_mul_f32_e32 v59, v90, v59
	v_mul_f32_e32 v39, v90, v39
	v_mul_f32_e32 v38, v90, v38
	v_mul_f32_e32 v37, v90, v37
	v_mul_f32_e32 v36, v90, v36
	v_mul_f32_e32 v35, v90, v35
	v_mul_f32_e32 v34, v90, v34
	v_mul_f32_e32 v33, v90, v33
	v_mul_f32_e32 v32, v90, v32
	v_mul_f32_e32 v31, v90, v31
	v_mul_f32_e32 v30, v90, v30
	v_mul_f32_e32 v29, v90, v29
	v_mul_f32_e32 v28, v90, v28
	v_mul_f32_e32 v27, v90, v27
	v_mul_f32_e32 v26, v90, v26
	v_mul_f32_e32 v25, v90, v25
	v_mul_f32_e32 v24, v90, v24
	v_mul_f32_e32 v23, v90, v23
	v_mul_f32_e32 v22, v90, v22
	v_mul_f32_e32 v21, v90, v21
	v_mul_f32_e32 v20, v90, v20
	v_mul_f32_e32 v16, v90, v16
	v_mul_f32_e32 v15, v90, v15
	v_mul_f32_e32 v13, v90, v13
	v_mul_f32_e32 v12, v90, v12
	v_mul_f32_e32 v9, v90, v9
	v_mul_f32_e32 v8, v90, v8
	v_mul_f32_e32 v7, v90, v7
	v_mul_f32_e32 v6, v90, v6
	s_waitcnt vmcnt(3)
	v_lshlrev_b32_e32 v72, 16, v44
	v_and_b32_e32 v73, 0xffff0000, v44
	v_lshlrev_b32_e32 v74, 16, v45
	v_and_b32_e32 v75, 0xffff0000, v45
	v_lshlrev_b32_e32 v76, 16, v46
	v_and_b32_e32 v77, 0xffff0000, v46
	v_lshlrev_b32_e32 v78, 16, v47
	v_and_b32_e32 v79, 0xffff0000, v47
	s_waitcnt vmcnt(1)
	v_fmac_f32_e32 v72, v40, v64
	v_fmac_f32_e32 v73, v41, v65
	v_fmac_f32_e32 v74, v42, v66
	v_fmac_f32_e32 v75, v43, v67
	s_waitcnt vmcnt(0)
	v_fmac_f32_e32 v76, v48, v68
	v_fmac_f32_e32 v77, v49, v69
	v_fmac_f32_e32 v78, v50, v70
	v_fmac_f32_e32 v79, v51, v71
	v_cvt_pk_bf16_f32 v40, v72, v73
	v_cvt_pk_bf16_f32 v41, v74, v75
	v_cvt_pk_bf16_f32 v42, v76, v77
	v_cvt_pk_bf16_f32 v43, v78, v79
	global_load_dwordx4 v[44:47], v[52:53], off offset:2048
	v_mul_f32_e32 v64, v90, v80
	global_store_dwordx4 v[52:53], v[40:43], off offset:1024
	global_load_dwordx4 v[40:43], v[134:135], off
	s_nop 0
	global_load_dwordx4 v[48:51], v[134:135], off offset:16
	v_mul_f32_e32 v65, v90, v81
	v_mul_f32_e32 v66, v90, v82
	v_mul_f32_e32 v67, v90, v83
	v_mul_f32_e32 v68, v90, v84
	v_mul_f32_e32 v69, v90, v85
	s_waitcnt vmcnt(3)
	v_lshlrev_b32_e32 v70, 16, v44
	v_and_b32_e32 v71, 0xffff0000, v44
	v_lshlrev_b32_e32 v80, 16, v45
	v_and_b32_e32 v81, 0xffff0000, v45
	v_lshlrev_b32_e32 v82, 16, v46
	v_and_b32_e32 v83, 0xffff0000, v46
	v_lshlrev_b32_e32 v84, 16, v47
	v_and_b32_e32 v85, 0xffff0000, v47
	s_waitcnt vmcnt(1)
	v_fmac_f32_e32 v70, v40, v64
	v_fmac_f32_e32 v71, v41, v65
	v_fmac_f32_e32 v80, v42, v66
	v_fmac_f32_e32 v81, v43, v67
	s_waitcnt vmcnt(0)
	v_fmac_f32_e32 v82, v48, v68
	v_fmac_f32_e32 v83, v49, v54
	v_fmac_f32_e32 v84, v50, v69
	v_fmac_f32_e32 v85, v51, v55
	v_cvt_pk_bf16_f32 v40, v70, v71
	v_cvt_pk_bf16_f32 v41, v80, v81
	v_cvt_pk_bf16_f32 v42, v82, v83
	v_cvt_pk_bf16_f32 v43, v84, v85
	global_load_dwordx4 v[44:47], v[52:53], off offset:3072
	v_mul_f32_e32 v54, v90, v86
	global_store_dwordx4 v[52:53], v[40:43], off offset:2048
	global_load_dwordx4 v[40:43], v[136:137], off
	s_nop 0
	global_load_dwordx4 v[48:51], v[136:137], off offset:16
	v_mul_f32_e32 v55, v90, v56
	v_mul_f32_e32 v56, v90, v87
	v_mul_f32_e32 v64, v90, v88
	v_mul_f32_e32 v65, v90, v89
	s_waitcnt vmcnt(3)
	v_lshlrev_b32_e32 v66, 16, v44
	v_and_b32_e32 v67, 0xffff0000, v44
	v_lshlrev_b32_e32 v68, 16, v45
	v_and_b32_e32 v69, 0xffff0000, v45
	v_lshlrev_b32_e32 v86, 16, v46
	v_and_b32_e32 v87, 0xffff0000, v46
	v_lshlrev_b32_e32 v88, 16, v47
	v_and_b32_e32 v89, 0xffff0000, v47
	s_waitcnt vmcnt(1)
	v_fmac_f32_e32 v66, v40, v54
	v_fmac_f32_e32 v67, v41, v55
	v_fmac_f32_e32 v68, v42, v56
	v_fmac_f32_e32 v69, v43, v57
	s_waitcnt vmcnt(0)
	v_fmac_f32_e32 v86, v48, v64
	v_fmac_f32_e32 v87, v49, v58
	v_fmac_f32_e32 v88, v50, v65
	v_fmac_f32_e32 v89, v51, v59
	v_cvt_pk_bf16_f32 v40, v66, v67
	v_cvt_pk_bf16_f32 v41, v68, v69
	v_cvt_pk_bf16_f32 v42, v86, v87
	v_cvt_pk_bf16_f32 v43, v88, v89
	global_load_dwordx4 v[44:47], v[2:3], off
	v_mul_f32_e32 v54, v90, v62
	global_store_dwordx4 v[52:53], v[40:43], off offset:3072
	global_load_dwordx4 v[40:43], v[138:139], off
	s_nop 0
	global_load_dwordx4 v[48:51], v[138:139], off offset:16
	v_mul_f32_e32 v52, v90, v60
	v_mul_f32_e32 v53, v90, v61
	v_mul_f32_e32 v55, v90, v63
	s_waitcnt vmcnt(3)
	v_lshlrev_b32_e32 v56, 16, v44
	v_and_b32_e32 v57, 0xffff0000, v44
	v_lshlrev_b32_e32 v58, 16, v45
	v_and_b32_e32 v59, 0xffff0000, v45
	v_lshlrev_b32_e32 v60, 16, v46
	v_and_b32_e32 v61, 0xffff0000, v46
	v_lshlrev_b32_e32 v62, 16, v47
	v_and_b32_e32 v63, 0xffff0000, v47
	s_waitcnt vmcnt(1)
	v_fmac_f32_e32 v56, v40, v39
	v_fmac_f32_e32 v57, v41, v52
	v_fmac_f32_e32 v58, v42, v53
	v_fmac_f32_e32 v59, v43, v54
	s_waitcnt vmcnt(0)
	v_fmac_f32_e32 v60, v48, v55
	v_fmac_f32_e32 v61, v49, v38
	v_fmac_f32_e32 v62, v50, v37
	v_fmac_f32_e32 v63, v51, v36
	v_cvt_pk_bf16_f32 v36, v56, v57
	v_cvt_pk_bf16_f32 v37, v58, v59
	v_cvt_pk_bf16_f32 v38, v60, v61
	v_cvt_pk_bf16_f32 v39, v62, v63
	global_load_dwordx4 v[40:43], v[2:3], off offset:1024
	s_waitcnt vmcnt(0)
	v_lshlrev_b32_e32 v48, 16, v40
	global_store_dwordx4 v[2:3], v[36:39], off
	global_load_dwordx4 v[36:39], v[140:141], off
	s_nop 0
	global_load_dwordx4 v[44:47], v[140:141], off offset:16
	v_and_b32_e32 v40, 0xffff0000, v40
	v_lshlrev_b32_e32 v49, 16, v41
	v_and_b32_e32 v41, 0xffff0000, v41
	v_lshlrev_b32_e32 v50, 16, v42
	v_and_b32_e32 v42, 0xffff0000, v42
	v_lshlrev_b32_e32 v51, 16, v43
	v_and_b32_e32 v43, 0xffff0000, v43
	s_waitcnt vmcnt(1)
	v_fmac_f32_e32 v48, v36, v35
	v_fmac_f32_e32 v40, v37, v34
	v_fmac_f32_e32 v49, v38, v33
	v_fmac_f32_e32 v41, v39, v32
	s_waitcnt vmcnt(0)
	v_fmac_f32_e32 v50, v44, v31
	v_fmac_f32_e32 v42, v45, v30
	v_fmac_f32_e32 v51, v46, v29
	v_fmac_f32_e32 v43, v47, v28
	v_cvt_pk_bf16_f32 v28, v48, v40
	v_cvt_pk_bf16_f32 v29, v49, v41
	v_cvt_pk_bf16_f32 v30, v50, v42
	v_cvt_pk_bf16_f32 v31, v51, v43
	global_load_dwordx4 v[32:35], v[2:3], off offset:2048
	s_waitcnt vmcnt(0)
	v_lshlrev_b32_e32 v44, 16, v32
	global_store_dwordx4 v[2:3], v[28:31], off offset:1024
	global_load_dwordx4 v[28:31], v[142:143], off
	s_nop 0
	global_load_dwordx4 v[36:39], v[142:143], off offset:16
	v_and_b32_e32 v32, 0xffff0000, v32
	v_lshlrev_b32_e32 v45, 16, v33
	v_and_b32_e32 v33, 0xffff0000, v33
	v_lshlrev_b32_e32 v46, 16, v34
	v_and_b32_e32 v34, 0xffff0000, v34
	v_lshlrev_b32_e32 v47, 16, v35
	v_and_b32_e32 v35, 0xffff0000, v35
	s_waitcnt vmcnt(1)
	v_fmac_f32_e32 v44, v28, v27
	v_fmac_f32_e32 v32, v29, v26
	v_fmac_f32_e32 v45, v30, v25
	v_fmac_f32_e32 v33, v31, v24
	s_waitcnt vmcnt(0)
	v_fmac_f32_e32 v46, v36, v23
	v_fmac_f32_e32 v34, v37, v22
	v_fmac_f32_e32 v47, v38, v21
	v_fmac_f32_e32 v35, v39, v20
	v_cvt_pk_bf16_f32 v20, v44, v32
	v_cvt_pk_bf16_f32 v21, v45, v33
	v_cvt_pk_bf16_f32 v22, v46, v34
	v_cvt_pk_bf16_f32 v23, v47, v35
	global_load_dwordx4 v[24:27], v[2:3], off offset:3072
	v_mul_f32_e32 v36, v92, v92
	global_store_dwordx4 v[2:3], v[20:23], off offset:2048
	global_load_dwordx4 v[20:23], v[144:145], off
	s_nop 0
	global_load_dwordx4 v[28:31], v[144:145], off offset:16
	v_fmac_f32_e32 v36, v91, v91
	v_fmac_f32_e32 v36, v93, v93
	v_fmac_f32_e32 v36, v94, v94
	v_fmac_f32_e32 v36, v95, v95
	v_fmac_f32_e32 v36, v96, v96
	v_fmac_f32_e32 v36, v97, v97
	v_fmac_f32_e32 v36, v98, v98
	v_fmac_f32_e32 v36, v72, v72
	v_fmac_f32_e32 v36, v73, v73
	v_fmac_f32_e32 v36, v74, v74
	v_fmac_f32_e32 v36, v75, v75
	v_fmac_f32_e32 v36, v76, v76
	v_fmac_f32_e32 v36, v77, v77
	v_fmac_f32_e32 v36, v78, v78
	v_fmac_f32_e32 v36, v79, v79
	v_fmac_f32_e32 v36, v70, v70
	v_fmac_f32_e32 v36, v71, v71
	v_fmac_f32_e32 v36, v80, v80
	v_fmac_f32_e32 v36, v81, v81
	v_fmac_f32_e32 v36, v82, v82
	v_fmac_f32_e32 v36, v83, v83
	v_fmac_f32_e32 v36, v84, v84
	v_fmac_f32_e32 v36, v85, v85
	v_fmac_f32_e32 v36, v66, v66
	v_fmac_f32_e32 v36, v67, v67
	v_fmac_f32_e32 v36, v68, v68
	v_fmac_f32_e32 v36, v69, v69
	v_fmac_f32_e32 v36, v86, v86
	v_fmac_f32_e32 v36, v87, v87
	v_fmac_f32_e32 v36, v88, v88
	v_fmac_f32_e32 v36, v89, v89
	v_fmac_f32_e32 v36, v56, v56
	v_fmac_f32_e32 v36, v57, v57
	v_fmac_f32_e32 v36, v58, v58
	v_fmac_f32_e32 v36, v59, v59
	v_fmac_f32_e32 v36, v60, v60
	v_fmac_f32_e32 v36, v61, v61
	v_fmac_f32_e32 v36, v62, v62
	v_fmac_f32_e32 v36, v63, v63
	v_fmac_f32_e32 v36, v48, v48
	v_fmac_f32_e32 v36, v40, v40
	v_fmac_f32_e32 v36, v49, v49
	v_fmac_f32_e32 v36, v41, v41
	v_fmac_f32_e32 v36, v50, v50
	v_fmac_f32_e32 v36, v42, v42
	v_fmac_f32_e32 v36, v51, v51
	v_fmac_f32_e32 v36, v43, v43
	v_fmac_f32_e32 v36, v44, v44
	v_fmac_f32_e32 v36, v32, v32
	v_fmac_f32_e32 v36, v45, v45
	v_fmac_f32_e32 v36, v33, v33
	v_fmac_f32_e32 v36, v46, v46
	v_fmac_f32_e32 v36, v34, v34
	v_fmac_f32_e32 v36, v47, v47
	v_fmac_f32_e32 v36, v35, v35
	s_waitcnt vmcnt(3)
	v_lshlrev_b32_e32 v32, 16, v24
	v_and_b32_e32 v24, 0xffff0000, v24
	s_waitcnt vmcnt(1)
	v_fmac_f32_e32 v32, v20, v16
	v_lshlrev_b32_e32 v33, 16, v25
	v_fmac_f32_e32 v24, v21, v15
	v_fmac_f32_e32 v36, v32, v32
	v_and_b32_e32 v25, 0xffff0000, v25
	v_fmac_f32_e32 v33, v22, v13
	v_fmac_f32_e32 v36, v24, v24
	v_lshlrev_b32_e32 v34, 16, v26
	v_fmac_f32_e32 v25, v23, v12
	v_fmac_f32_e32 v36, v33, v33
	v_and_b32_e32 v26, 0xffff0000, v26
	s_waitcnt vmcnt(0)
	v_fmac_f32_e32 v34, v28, v9
	v_fmac_f32_e32 v36, v25, v25
	v_lshlrev_b32_e32 v37, 16, v27
	v_fmac_f32_e32 v26, v29, v8
	v_fmac_f32_e32 v36, v34, v34
	v_and_b32_e32 v27, 0xffff0000, v27
	v_fmac_f32_e32 v37, v30, v7
	v_fmac_f32_e32 v36, v26, v26
	v_fmac_f32_e32 v27, v31, v6
	v_fmac_f32_e32 v36, v37, v37
	v_fmac_f32_e32 v36, v27, v27
	ds_bpermute_b32 v4, v4, v36
	v_cvt_pk_bf16_f32 v6, v32, v24
	v_cvt_pk_bf16_f32 v7, v33, v25
	v_cvt_pk_bf16_f32 v8, v34, v26
	v_cvt_pk_bf16_f32 v9, v37, v27
	s_waitcnt lgkmcnt(0)
	v_add_f32_e32 v4, v36, v4
	ds_bpermute_b32 v5, v5, v4
	global_store_dwordx4 v[2:3], v[6:9], off offset:3072
	s_waitcnt lgkmcnt(0)
	v_add_f32_e32 v4, v4, v5
	ds_bpermute_b32 v5, v14, v4
	s_waitcnt lgkmcnt(0)
	v_add_f32_e32 v4, v4, v5
	ds_bpermute_b32 v5, v17, v4
	s_waitcnt lgkmcnt(0)
	v_add_f32_e32 v4, v4, v5
	s_waitcnt lgkmcnt(0)
	v_mov_b32_e32 v5, v4
	s_nop 1
	v_permlane16_swap_b32_e32 v5, v4
	v_add_f32_e32 v4, v4, v5
	ds_bpermute_b32 v5, v19, v4
	s_and_saveexec_b64 s[14:15], s[0:1]
	s_cbranch_execz .LBB0_1177
	s_waitcnt lgkmcnt(0)
	v_add_f32_e32 v2, v4, v5
	v_fmamk_f32 v2, v2, 0x39800000, v158
	v_mul_f32_e32 v3, 0x4f800000, v2
	v_cmp_gt_f32_e32 vcc, s20, v2
	s_nop 1
	v_cndmask_b32_e32 v2, v2, v3, vcc
	v_sqrt_f32_e32 v3, v2
	s_nop 0
	v_add_u32_e32 v4, -1, v3
	v_fma_f32 v6, -v4, v3, v2
	v_add_u32_e32 v5, 1, v3
	v_cmp_ge_f32_e64 s[2:3], 0, v6
	s_nop 1
	v_cndmask_b32_e64 v4, v3, v4, s[2:3]
	v_fma_f32 v3, -v5, v3, v2
	v_cmp_lt_f32_e64 s[2:3], 0, v3
	s_nop 1
	v_cndmask_b32_e64 v3, v4, v5, s[2:3]
	v_mul_f32_e32 v4, 0x37800000, v3
	v_cndmask_b32_e32 v3, v3, v4, vcc
	v_cmp_class_f32_e32 vcc, v2, v159
	s_nop 1
	v_cndmask_b32_e32 v2, v3, v2, vcc
	v_div_scale_f32 v3, s[2:3], v2, v2, 1.0
	v_rcp_f32_e32 v4, v3
	s_add_u32 s2, s4, s7
	s_addc_u32 s3, s5, s16
	v_fma_f32 v5, -v3, v4, 1.0
	v_fmac_f32_e32 v4, v5, v4
	v_div_scale_f32 v5, vcc, 1.0, v2, 1.0
	v_mul_f32_e32 v6, v5, v4
	v_fma_f32 v7, -v3, v6, v5
	v_fmac_f32_e32 v6, v7, v4
	v_fma_f32 v3, -v3, v6, v5
	v_div_fmas_f32 v3, v3, v4, v6
	v_div_fixup_f32 v2, v3, v2, 1.0
	global_store_dword v131, v2, s[2:3]

.LBB0_1178:
	s_andn2_b64 vcc, exec, s[2:3]
	s_cbranch_vccnz .LBB0_1173
	v_add_co_u32_e32 v2, vcc, 0x3b100000, v10
	v_lshl_add_u64 v[12:13], s[4:5], 0, v[148:149]
	s_waitcnt lgkmcnt(0)
	v_addc_co_u32_e32 v3, vcc, 0, v11, vcc
	global_load_dwordx4 v[118:121], v[2:3], off
	v_add_co_u32_e32 v4, vcc, 0x3b100000, v12
	s_waitcnt vmcnt(0)
	v_and_b32_e32 v79, 0xffff0000, v118
	s_waitcnt lgkmcnt(0)
	v_addc_co_u32_e32 v5, vcc, 0, v13, vcc
	global_load_dwordx4 v[114:117], v[4:5], off
	global_load_dwordx4 v[106:109], v[2:3], off offset:1024
	global_load_dwordx4 v[86:89], v[2:3], off offset:2048
	global_load_dwordx4 v[66:69], v[2:3], off offset:3072
	global_load_dwordx4 v[94:97], v[4:5], off offset:1024
	global_load_dwordx4 v[74:77], v[4:5], off offset:2048
	global_load_dwordx4 v[58:61], v[4:5], off offset:3072
	v_add_co_u32_e32 v2, vcc, 0x3b101000, v10
	v_lshlrev_b32_e32 v78, 16, v118
	s_nop 0
	v_addc_co_u32_e32 v3, vcc, 0, v11, vcc
	global_load_dwordx4 v[46:49], v[2:3], off
	global_load_dwordx4 v[34:37], v[2:3], off offset:1024
	global_load_dwordx4 v[18:21], v[2:3], off offset:2048
	global_load_dwordx4 v[6:9], v[2:3], off offset:3072
	v_add_co_u32_e32 v4, vcc, 0x3b101000, v12
	v_mul_f32_e32 v79, v79, v79
	s_nop 0
	v_addc_co_u32_e32 v5, vcc, 0, v13, vcc
	global_load_dwordx4 v[42:45], v[4:5], off
	global_load_dwordx4 v[26:29], v[4:5], off offset:1024
	global_load_dwordx4 v[14:17], v[4:5], off offset:2048
	s_nop 0
	global_load_dwordx4 v[2:5], v[4:5], off offset:3072
	v_lshlrev_b32_e32 v80, 16, v119
	v_fmac_f32_e32 v79, v78, v78
	v_and_b32_e32 v81, 0xffff0000, v119
	v_fmac_f32_e32 v79, v80, v80
	v_lshlrev_b32_e32 v98, 16, v120
	v_fmac_f32_e32 v79, v81, v81
	v_and_b32_e32 v99, 0xffff0000, v120
	v_fmac_f32_e32 v79, v98, v98
	v_lshlrev_b32_e32 v100, 16, v121
	v_fmac_f32_e32 v79, v99, v99
	v_and_b32_e32 v101, 0xffff0000, v121
	v_fmac_f32_e32 v79, v100, v100
	v_fmac_f32_e32 v79, v101, v101
	v_add_co_u32_e32 v156, vcc, 0x43100000, v10
	s_waitcnt vmcnt(14)
	v_and_b32_e32 v169, 0xffff0000, v114
	s_waitcnt vmcnt(13)
	v_lshlrev_b32_e32 v78, 16, v106
	v_and_b32_e32 v80, 0xffff0000, v106
	v_fmac_f32_e32 v79, v78, v78
	v_lshlrev_b32_e32 v81, 16, v107
	v_fmac_f32_e32 v79, v80, v80
	v_and_b32_e32 v98, 0xffff0000, v107
	v_fmac_f32_e32 v79, v81, v81
	v_lshlrev_b32_e32 v99, 16, v108
	v_fmac_f32_e32 v79, v98, v98
	v_and_b32_e32 v100, 0xffff0000, v108
	v_fmac_f32_e32 v79, v99, v99
	v_lshlrev_b32_e32 v168, 16, v114
	v_mul_f32_e32 v176, v169, v169
	v_lshlrev_b32_e32 v101, 16, v109
	v_fmac_f32_e32 v79, v100, v100
	v_fmac_f32_e32 v176, v168, v168
	v_and_b32_e32 v168, 0xffff0000, v109
	v_fmac_f32_e32 v79, v101, v101
	v_fmac_f32_e32 v79, v168, v168
	s_waitcnt vmcnt(12)
	v_lshlrev_b32_e32 v78, 16, v86
	v_and_b32_e32 v80, 0xffff0000, v86
	v_fmac_f32_e32 v79, v78, v78
	v_lshlrev_b32_e32 v81, 16, v87
	v_fmac_f32_e32 v79, v80, v80
	v_and_b32_e32 v98, 0xffff0000, v87
	v_fmac_f32_e32 v79, v81, v81
	v_lshlrev_b32_e32 v99, 16, v88
	v_fmac_f32_e32 v79, v98, v98
	v_and_b32_e32 v100, 0xffff0000, v88
	v_fmac_f32_e32 v79, v99, v99
	v_lshlrev_b32_e32 v101, 16, v89
	v_fmac_f32_e32 v79, v100, v100
	v_and_b32_e32 v168, 0xffff0000, v89
	v_fmac_f32_e32 v79, v101, v101
	v_lshlrev_b32_e32 v170, 16, v115
	v_fmac_f32_e32 v79, v168, v168
	s_waitcnt vmcnt(11)
	v_lshlrev_b32_e32 v78, 16, v66
	v_and_b32_e32 v171, 0xffff0000, v115
	v_fmac_f32_e32 v176, v170, v170
	v_and_b32_e32 v80, 0xffff0000, v66
	v_fmac_f32_e32 v79, v78, v78
	v_lshlrev_b32_e32 v172, 16, v116
	v_fmac_f32_e32 v176, v171, v171
	v_lshlrev_b32_e32 v81, 16, v67
	v_fmac_f32_e32 v79, v80, v80
	v_and_b32_e32 v173, 0xffff0000, v116
	v_fmac_f32_e32 v176, v172, v172
	v_and_b32_e32 v98, 0xffff0000, v67
	v_fmac_f32_e32 v79, v81, v81
	v_lshlrev_b32_e32 v174, 16, v117
	v_fmac_f32_e32 v176, v173, v173
	v_lshlrev_b32_e32 v99, 16, v68
	v_fmac_f32_e32 v79, v98, v98
	v_and_b32_e32 v175, 0xffff0000, v117
	v_fmac_f32_e32 v176, v174, v174
	v_and_b32_e32 v100, 0xffff0000, v68
	v_fmac_f32_e32 v79, v99, v99
	v_fmac_f32_e32 v176, v175, v175
	s_waitcnt vmcnt(10)
	v_lshlrev_b32_e32 v169, 16, v94
	v_lshlrev_b32_e32 v101, 16, v69
	v_fmac_f32_e32 v79, v100, v100
	v_and_b32_e32 v170, 0xffff0000, v94
	v_fmac_f32_e32 v176, v169, v169
	v_and_b32_e32 v168, 0xffff0000, v69
	v_fmac_f32_e32 v79, v101, v101
	v_lshlrev_b32_e32 v171, 16, v95
	v_fmac_f32_e32 v176, v170, v170
	v_fmac_f32_e32 v79, v168, v168
	s_waitcnt vmcnt(7)
	v_lshlrev_b32_e32 v78, 16, v46
	v_and_b32_e32 v172, 0xffff0000, v95
	v_fmac_f32_e32 v176, v171, v171
	v_and_b32_e32 v80, 0xffff0000, v46
	v_fmac_f32_e32 v79, v78, v78
	v_lshlrev_b32_e32 v173, 16, v96
	v_fmac_f32_e32 v176, v172, v172
	v_lshlrev_b32_e32 v81, 16, v47
	v_fmac_f32_e32 v79, v80, v80
	v_and_b32_e32 v174, 0xffff0000, v96
	v_fmac_f32_e32 v176, v173, v173
	v_and_b32_e32 v98, 0xffff0000, v47
	v_fmac_f32_e32 v79, v81, v81
	v_lshlrev_b32_e32 v175, 16, v97
	v_fmac_f32_e32 v176, v174, v174
	v_lshlrev_b32_e32 v99, 16, v48
	v_fmac_f32_e32 v79, v98, v98
	v_and_b32_e32 v177, 0xffff0000, v97
	v_fmac_f32_e32 v176, v175, v175
	v_and_b32_e32 v100, 0xffff0000, v48
	v_fmac_f32_e32 v79, v99, v99
	v_fmac_f32_e32 v176, v177, v177
	v_lshlrev_b32_e32 v169, 16, v74
	v_lshlrev_b32_e32 v101, 16, v49
	v_fmac_f32_e32 v79, v100, v100
	v_and_b32_e32 v170, 0xffff0000, v74
	v_fmac_f32_e32 v176, v169, v169
	v_and_b32_e32 v168, 0xffff0000, v49
	v_fmac_f32_e32 v79, v101, v101
	v_lshlrev_b32_e32 v171, 16, v75
	v_fmac_f32_e32 v176, v170, v170
	v_fmac_f32_e32 v79, v168, v168
	s_waitcnt vmcnt(6)
	v_lshlrev_b32_e32 v78, 16, v34
	v_and_b32_e32 v172, 0xffff0000, v75
	v_fmac_f32_e32 v176, v171, v171
	v_and_b32_e32 v80, 0xffff0000, v34
	v_fmac_f32_e32 v79, v78, v78
	v_lshlrev_b32_e32 v173, 16, v76
	v_fmac_f32_e32 v176, v172, v172
	v_lshlrev_b32_e32 v81, 16, v35
	v_fmac_f32_e32 v79, v80, v80
	v_and_b32_e32 v174, 0xffff0000, v76
	v_fmac_f32_e32 v176, v173, v173
	v_and_b32_e32 v98, 0xffff0000, v35
	v_fmac_f32_e32 v79, v81, v81
	v_lshlrev_b32_e32 v175, 16, v77
	v_fmac_f32_e32 v176, v174, v174
	v_lshlrev_b32_e32 v99, 16, v36
	v_fmac_f32_e32 v79, v98, v98
	v_and_b32_e32 v177, 0xffff0000, v77
	v_fmac_f32_e32 v176, v175, v175
	v_and_b32_e32 v100, 0xffff0000, v36
	v_fmac_f32_e32 v79, v99, v99
	v_fmac_f32_e32 v176, v177, v177
	v_lshlrev_b32_e32 v169, 16, v58
	v_lshlrev_b32_e32 v101, 16, v37
	v_fmac_f32_e32 v79, v100, v100
	v_and_b32_e32 v170, 0xffff0000, v58
	v_fmac_f32_e32 v176, v169, v169
	v_and_b32_e32 v168, 0xffff0000, v37
	v_fmac_f32_e32 v79, v101, v101
	v_lshlrev_b32_e32 v171, 16, v59
	v_fmac_f32_e32 v176, v170, v170
	v_fmac_f32_e32 v79, v168, v168
	s_waitcnt vmcnt(5)
	v_lshlrev_b32_e32 v78, 16, v18
	v_and_b32_e32 v172, 0xffff0000, v59
	v_fmac_f32_e32 v176, v171, v171
	v_and_b32_e32 v80, 0xffff0000, v18
	v_fmac_f32_e32 v79, v78, v78
	v_lshlrev_b32_e32 v173, 16, v60
	v_fmac_f32_e32 v176, v172, v172
	v_lshlrev_b32_e32 v81, 16, v19
	v_fmac_f32_e32 v79, v80, v80
	v_and_b32_e32 v174, 0xffff0000, v60
	v_fmac_f32_e32 v176, v173, v173
	v_and_b32_e32 v98, 0xffff0000, v19
	v_fmac_f32_e32 v79, v81, v81
	v_lshlrev_b32_e32 v175, 16, v61
	v_fmac_f32_e32 v176, v174, v174
	v_lshlrev_b32_e32 v99, 16, v20
	v_fmac_f32_e32 v79, v98, v98
	v_and_b32_e32 v177, 0xffff0000, v61
	v_fmac_f32_e32 v176, v175, v175
	v_and_b32_e32 v100, 0xffff0000, v20
	v_fmac_f32_e32 v79, v99, v99
	v_fmac_f32_e32 v176, v177, v177
	s_waitcnt vmcnt(3)
	v_lshlrev_b32_e32 v169, 16, v42
	v_lshlrev_b32_e32 v101, 16, v21
	v_fmac_f32_e32 v79, v100, v100
	v_addc_co_u32_e32 v157, vcc, 0, v11, vcc
	v_and_b32_e32 v170, 0xffff0000, v42
	v_fmac_f32_e32 v176, v169, v169
	v_and_b32_e32 v168, 0xffff0000, v21
	v_fmac_f32_e32 v79, v101, v101
	v_add_co_u32_e32 v154, vcc, 0x43100000, v12
	v_lshlrev_b32_e32 v171, 16, v43
	v_fmac_f32_e32 v176, v170, v170
	v_fmac_f32_e32 v79, v168, v168
	v_lshlrev_b32_e32 v78, 16, v6
	v_addc_co_u32_e32 v155, vcc, 0, v13, vcc
	v_and_b32_e32 v172, 0xffff0000, v43
	v_fmac_f32_e32 v176, v171, v171
	v_and_b32_e32 v80, 0xffff0000, v6
	v_fmac_f32_e32 v79, v78, v78
	v_add_co_u32_e32 v150, vcc, 0x43101000, v10
	v_lshlrev_b32_e32 v173, 16, v44
	v_fmac_f32_e32 v176, v172, v172
	v_lshlrev_b32_e32 v81, 16, v7
	v_fmac_f32_e32 v79, v80, v80
	v_addc_co_u32_e32 v151, vcc, 0, v11, vcc
	v_and_b32_e32 v174, 0xffff0000, v44
	v_fmac_f32_e32 v176, v173, v173
	v_and_b32_e32 v98, 0xffff0000, v7
	v_fmac_f32_e32 v79, v81, v81
	v_add_co_u32_e32 v152, vcc, 0x43101000, v12
	v_lshlrev_b32_e32 v175, 16, v45
	v_fmac_f32_e32 v176, v174, v174
	v_lshlrev_b32_e32 v99, 16, v8
	v_fmac_f32_e32 v79, v98, v98
	v_addc_co_u32_e32 v153, vcc, 0, v13, vcc
	v_and_b32_e32 v177, 0xffff0000, v45
	v_fmac_f32_e32 v176, v175, v175
	v_and_b32_e32 v100, 0xffff0000, v8
	v_fmac_f32_e32 v79, v99, v99
	v_fmac_f32_e32 v176, v177, v177
	s_waitcnt vmcnt(2)
	v_lshlrev_b32_e32 v169, 16, v26
	v_lshlrev_b32_e32 v101, 16, v9
	v_fmac_f32_e32 v79, v100, v100
	v_cmp_lt_i32_e32 vcc, v162, v161
	v_and_b32_e32 v170, 0xffff0000, v26
	v_fmac_f32_e32 v176, v169, v169
	v_and_b32_e32 v168, 0xffff0000, v9
	v_fmac_f32_e32 v79, v101, v101
	v_cndmask_b32_e32 v78, v160, v162, vcc
	v_lshlrev_b32_e32 v171, 16, v27
	v_fmac_f32_e32 v176, v170, v170
	v_fmac_f32_e32 v79, v168, v168
	v_lshlrev_b32_e32 v168, 2, v78
	v_and_b32_e32 v172, 0xffff0000, v27
	v_fmac_f32_e32 v176, v171, v171
	v_lshlrev_b32_e32 v173, 16, v28
	v_fmac_f32_e32 v176, v172, v172
	v_and_b32_e32 v174, 0xffff0000, v28
	v_fmac_f32_e32 v176, v173, v173
	v_lshlrev_b32_e32 v175, 16, v29
	v_fmac_f32_e32 v176, v174, v174
	v_and_b32_e32 v177, 0xffff0000, v29
	v_fmac_f32_e32 v176, v175, v175
	v_cmp_lt_i32_e32 vcc, v163, v161
	v_fmac_f32_e32 v176, v177, v177
	s_waitcnt vmcnt(1)
	v_lshlrev_b32_e32 v169, 16, v14
	s_waitcnt lgkmcnt(0)
	s_nop 1
	v_add_f32_dpp v78, v79, v79 quad_perm:[1,0,3,2] row_mask:0xf bank_mask:0xf
	v_cndmask_b32_e32 v79, v160, v163, vcc
	v_fmac_f32_e32 v176, v169, v169
	v_lshlrev_b32_e32 v169, 2, v79
	v_cmp_lt_i32_e32 vcc, v164, v161
	v_and_b32_e32 v170, 0xffff0000, v14
	v_fmac_f32_e32 v176, v170, v170
	v_lshlrev_b32_e32 v171, 16, v15
	s_waitcnt lgkmcnt(0)
	s_nop 1
	v_add_f32_dpp v78, v78, v78 quad_perm:[2,3,0,1] row_mask:0xf bank_mask:0xf
	v_cndmask_b32_e32 v79, v160, v164, vcc
	v_lshlrev_b32_e32 v170, 2, v79
	v_cmp_lt_i32_e32 vcc, v165, v161
	v_and_b32_e32 v172, 0xffff0000, v15
	v_fmac_f32_e32 v176, v171, v171
	v_lshlrev_b32_e32 v173, 16, v16
	s_waitcnt lgkmcnt(0)
	s_nop 1
	v_add_f32_dpp v78, v78, v78 row_half_mirror row_mask:0xf bank_mask:0xf
	v_cndmask_b32_e32 v79, v160, v165, vcc
	v_fmac_f32_e32 v176, v172, v172
	v_lshlrev_b32_e32 v171, 2, v79
	v_and_b32_e32 v174, 0xffff0000, v16
	v_fmac_f32_e32 v176, v173, v173
	v_lshlrev_b32_e32 v175, 16, v17
	v_fmac_f32_e32 v176, v174, v174
	v_and_b32_e32 v177, 0xffff0000, v17
	v_fmac_f32_e32 v176, v175, v175
	v_fmac_f32_e32 v176, v177, v177
	s_waitcnt vmcnt(0)
	v_lshlrev_b32_e32 v80, 16, v2
	v_and_b32_e32 v81, 0xffff0000, v2
	v_fmac_f32_e32 v176, v80, v80
	v_cmp_lt_i32_e32 vcc, v166, v161
	v_lshlrev_b32_e32 v98, 16, v3
	v_fmac_f32_e32 v176, v81, v81
	s_waitcnt lgkmcnt(0)
	s_nop 1
	v_add_f32_dpp v78, v78, v78 row_mirror row_mask:0xf bank_mask:0xf
	v_cndmask_b32_e32 v79, v160, v166, vcc
	v_and_b32_e32 v99, 0xffff0000, v3
	v_fmac_f32_e32 v176, v98, v98
	v_lshlrev_b32_e32 v172, 2, v79
	v_lshlrev_b32_e32 v100, 16, v4
	v_fmac_f32_e32 v176, v99, v99
	v_and_b32_e32 v101, 0xffff0000, v4
	v_fmac_f32_e32 v176, v100, v100
	v_lshlrev_b32_e32 v173, 16, v5
	v_fmac_f32_e32 v176, v101, v101
	v_and_b32_e32 v174, 0xffff0000, v5
	v_fmac_f32_e32 v176, v173, v173
	v_fmac_f32_e32 v176, v174, v174
	s_waitcnt lgkmcnt(0)
	v_mov_b32_e32 v174, v78
	v_mov_b32_e32 v79, v78
	s_nop 1
	v_permlane16_swap_b32_e32 v79, v174
	v_add_f32_e32 v174, v174, v79
	v_cmp_lt_i32_e32 vcc, v167, v161
	global_load_dwordx4 v[126:129], v[156:157], off
	global_load_dwordx4 v[110:113], v[156:157], off offset:1024
	global_load_dwordx4 v[90:93], v[156:157], off offset:2048
	global_load_dwordx4 v[70:73], v[156:157], off offset:3072
	v_cndmask_b32_e32 v79, v160, v167, vcc
	global_load_dwordx4 v[122:125], v[154:155], off
	global_load_dwordx4 v[102:105], v[154:155], off offset:1024
	global_load_dwordx4 v[82:85], v[154:155], off offset:2048
	global_load_dwordx4 v[62:65], v[154:155], off offset:3072
	global_load_dwordx4 v[54:57], v[150:151], off
	global_load_dwordx4 v[38:41], v[150:151], off offset:1024
	global_load_dwordx4 v[22:25], v[150:151], off offset:2048
	global_load_dwordx4 v[10:13], v[150:151], off offset:3072
	global_load_dwordx4 v[50:53], v[152:153], off
	global_load_dwordx4 v[30:33], v[152:153], off offset:1024
	v_lshlrev_b32_e32 v173, 2, v79
	s_waitcnt lgkmcnt(0)
	s_nop 1
	v_add_f32_dpp v176, v176, v176 quad_perm:[1,0,3,2] row_mask:0xf bank_mask:0xf
	global_load_dwordx4 v[98:101], v[152:153], off offset:2048
	global_load_dwordx4 v[78:81], v[152:153], off offset:3072
	global_load_dwordx4 v[182:185], v[132:133], off offset:16
	global_load_dwordx4 v[186:189], v[132:133], off
	v_lshlrev_b32_e32 v190, 16, v119
	v_and_b32_e32 v119, 0xffff0000, v119
	v_lshlrev_b32_e32 v191, 16, v120
	s_waitcnt lgkmcnt(0)
	v_mov_b32_e32 v175, v174
	s_nop 1
	v_permlane32_swap_b32_e32 v175, v174
	v_add_f32_e32 v174, v174, v175
	s_waitcnt lgkmcnt(0)
	s_nop 1
	v_add_f32_dpp v175, v176, v176 quad_perm:[2,3,0,1] row_mask:0xf bank_mask:0xf
	v_fmamk_f32 v174, v174, 0x39800000, v158
	v_mul_f32_e32 v177, 0x4f800000, v174
	v_cmp_gt_f32_e32 vcc, s20, v174
	v_and_b32_e32 v120, 0xffff0000, v120
	s_waitcnt lgkmcnt(0)
	s_nop 1
	v_add_f32_dpp v175, v175, v175 row_half_mirror row_mask:0xf bank_mask:0xf
	v_cndmask_b32_e32 v174, v174, v177, vcc
	v_sqrt_f32_e32 v177, v174
	v_lshlrev_b32_e32 v192, 16, v121
	v_and_b32_e32 v121, 0xffff0000, v121
	s_waitcnt lgkmcnt(0)
	s_nop 1
	v_add_f32_dpp v175, v175, v175 row_mirror row_mask:0xf bank_mask:0xf
	v_add_u32_e32 v178, -1, v177
	v_fma_f32 v179, -v178, v177, v174
	v_cmp_ge_f32_e64 s[2:3], 0, v179
	v_add_u32_e32 v179, 1, v177
	s_waitcnt lgkmcnt(0)
	v_mov_b32_e32 v176, v175
	s_nop 1
	v_permlane16_swap_b32_e32 v176, v175
	v_add_f32_e32 v175, v175, v176
	v_cndmask_b32_e64 v178, v177, v178, s[2:3]
	v_fma_f32 v177, -v179, v177, v174
	v_cmp_lt_f32_e64 s[2:3], 0, v177
	v_and_b32_e32 v193, 0xffff0000, v116
	s_waitcnt lgkmcnt(0)
	v_mov_b32_e32 v176, v175
	s_nop 1
	v_permlane32_swap_b32_e32 v176, v175
	v_add_f32_e32 v175, v175, v176
	v_fmamk_f32 v175, v175, 0x39800000, v158
	v_cndmask_b32_e64 v177, v178, v179, s[2:3]
	v_mul_f32_e32 v176, 0x4f800000, v175
	v_cmp_gt_f32_e64 s[2:3], s20, v175
	v_mul_f32_e32 v178, 0x37800000, v177
	v_cndmask_b32_e32 v177, v177, v178, vcc
	v_cndmask_b32_e64 v175, v175, v176, s[2:3]
	v_sqrt_f32_e32 v176, v175
	v_cmp_class_f32_e32 vcc, v174, v159
	v_lshlrev_b32_e32 v194, 16, v117
	v_and_b32_e32 v195, 0xffff0000, v117
	v_cndmask_b32_e32 v174, v177, v174, vcc
	v_add_u32_e32 v177, -1, v176
	v_fma_f32 v178, -v177, v176, v175
	v_cmp_ge_f32_e32 vcc, 0, v178
	v_add_u32_e32 v178, 1, v176
	s_waitcnt vmcnt(13)
	v_lshlrev_b32_e32 v117, 16, v124
	v_cndmask_b32_e32 v177, v176, v177, vcc
	v_fma_f32 v176, -v178, v176, v175
	v_cmp_lt_f32_e32 vcc, 0, v176
	s_nop 1
	v_cndmask_b32_e32 v176, v177, v178, vcc
	v_div_scale_f32 v178, s[14:15], v174, v174, 1.0
	v_rcp_f32_e32 v179, v178
	v_mul_f32_e32 v177, 0x37800000, v176
	v_cndmask_b32_e64 v176, v176, v177, s[2:3]
	v_cmp_class_f32_e32 vcc, v175, v159
	s_nop 1
	v_cndmask_b32_e32 v175, v176, v175, vcc
	v_fma_f32 v176, -v178, v179, 1.0
	v_fmac_f32_e32 v179, v176, v179
	v_div_scale_f32 v176, vcc, 1.0, v174, 1.0
	v_mul_f32_e32 v177, v176, v179
	v_fma_f32 v180, -v178, v177, v176
	v_fmac_f32_e32 v177, v180, v179
	v_fma_f32 v176, -v178, v177, v176
	v_div_scale_f32 v178, s[2:3], v175, v175, 1.0
	v_rcp_f32_e32 v181, v178
	v_div_fmas_f32 v176, v176, v179, v177
	v_div_fixup_f32 v180, v176, v174, 1.0
	v_fma_f32 v174, -v178, v181, 1.0
	v_fmac_f32_e32 v181, v174, v181
	v_div_scale_f32 v174, vcc, 1.0, v175, 1.0
	v_mul_f32_e32 v176, v174, v181
	v_fma_f32 v177, -v178, v176, v174
	v_fmac_f32_e32 v176, v177, v181
	v_fma_f32 v174, -v178, v176, v174
	v_div_fmas_f32 v174, v174, v181, v176
	v_lshlrev_b32_e32 v181, 16, v118
	v_and_b32_e32 v118, 0xffff0000, v118
	v_and_b32_e32 v178, 0xffff0000, v126
	v_mul_f32_e32 v118, v180, v118
	v_lshlrev_b32_e32 v177, 16, v127
	s_waitcnt vmcnt(0)
	v_fmac_f32_e32 v178, v187, v118
	v_mul_f32_e32 v118, v180, v190
	v_div_fixup_f32 v179, v174, v175, 1.0
	v_and_b32_e32 v175, 0xffff0000, v127
	v_fmac_f32_e32 v177, v188, v118
	v_mul_f32_e32 v118, v180, v119
	v_lshlrev_b32_e32 v174, 16, v128
	v_fmac_f32_e32 v175, v189, v118
	v_mul_f32_e32 v118, v180, v191
	v_and_b32_e32 v128, 0xffff0000, v128
	v_fmac_f32_e32 v174, v182, v118
	v_mul_f32_e32 v118, v180, v120
	v_lshlrev_b32_e32 v127, 16, v129
	v_fmac_f32_e32 v128, v183, v118
	v_mul_f32_e32 v118, v180, v192
	v_lshlrev_b32_e32 v176, 16, v126
	v_and_b32_e32 v126, 0xffff0000, v129
	v_mul_f32_e32 v129, v180, v181
	v_fmac_f32_e32 v127, v184, v118
	v_mul_f32_e32 v118, v180, v121
	v_fmac_f32_e32 v176, v186, v129
	v_fmac_f32_e32 v126, v185, v118
	v_cvt_pk_bf16_f32 v118, v176, v178
	v_cvt_pk_bf16_f32 v119, v177, v175
	v_cvt_pk_bf16_f32 v120, v174, v128
	v_cvt_pk_bf16_f32 v121, v127, v126
	v_lshlrev_b32_e32 v129, 16, v114
	global_store_dwordx4 v[156:157], v[118:121], off
	v_and_b32_e32 v181, 0xffff0000, v114
	v_lshlrev_b32_e32 v190, 16, v115
	v_lshlrev_b32_e32 v119, 16, v122
	v_and_b32_e32 v121, 0xffff0000, v122
	v_mul_f32_e32 v122, v179, v129
	v_fmac_f32_e32 v119, v186, v122
	v_mul_f32_e32 v122, v179, v181
	v_and_b32_e32 v191, 0xffff0000, v115
	v_lshlrev_b32_e32 v120, 16, v123
	v_fmac_f32_e32 v121, v187, v122
	v_mul_f32_e32 v122, v179, v190
	v_lshlrev_b32_e32 v192, 16, v116
	v_and_b32_e32 v118, 0xffff0000, v123
	v_fmac_f32_e32 v120, v188, v122
	v_mul_f32_e32 v122, v179, v191
	v_fmac_f32_e32 v118, v189, v122
	v_mul_f32_e32 v122, v179, v192
	v_and_b32_e32 v116, 0xffff0000, v124
	v_fmac_f32_e32 v117, v182, v122
	v_mul_f32_e32 v122, v179, v193
	v_lshlrev_b32_e32 v115, 16, v125
	v_fmac_f32_e32 v116, v183, v122
	v_mul_f32_e32 v122, v179, v194
	v_and_b32_e32 v114, 0xffff0000, v125
	v_fmac_f32_e32 v115, v184, v122
	v_mul_f32_e32 v122, v179, v195
	v_fmac_f32_e32 v114, v185, v122
	v_cvt_pk_bf16_f32 v122, v119, v121
	v_cvt_pk_bf16_f32 v123, v120, v118
	v_cvt_pk_bf16_f32 v124, v117, v116
	v_cvt_pk_bf16_f32 v125, v115, v114
	global_store_dwordx4 v[154:155], v[122:125], off
	global_load_dwordx4 v[182:185], v[132:133], off offset:2048
	global_load_dwordx4 v[186:189], v[132:133], off offset:2064
	v_lshlrev_b32_e32 v181, 16, v106
	v_and_b32_e32 v106, 0xffff0000, v106
	v_lshlrev_b32_e32 v190, 16, v107
	v_and_b32_e32 v125, 0xffff0000, v110
	v_mul_f32_e32 v106, v180, v106
	v_and_b32_e32 v107, 0xffff0000, v107
	v_lshlrev_b32_e32 v124, 16, v111
	v_lshlrev_b32_e32 v191, 16, v108
	v_and_b32_e32 v123, 0xffff0000, v111
	v_and_b32_e32 v108, 0xffff0000, v108
	v_lshlrev_b32_e32 v122, 16, v112
	v_lshlrev_b32_e32 v192, 16, v109
	v_and_b32_e32 v111, 0xffff0000, v112
	v_and_b32_e32 v193, 0xffff0000, v109
	v_lshlrev_b32_e32 v129, 16, v110
	v_lshlrev_b32_e32 v110, 16, v113
	v_mul_f32_e32 v112, v180, v181
	v_and_b32_e32 v109, 0xffff0000, v113
	v_and_b32_e32 v113, 0xffff0000, v94
	v_lshlrev_b32_e32 v181, 16, v95
	v_and_b32_e32 v194, 0xffff0000, v97
	s_waitcnt vmcnt(1)
	v_fmac_f32_e32 v125, v183, v106
	v_mul_f32_e32 v106, v180, v190
	v_fmac_f32_e32 v124, v184, v106
	v_mul_f32_e32 v106, v180, v107
	v_fmac_f32_e32 v123, v185, v106
	v_mul_f32_e32 v106, v180, v191
	s_waitcnt vmcnt(0)
	v_fmac_f32_e32 v122, v186, v106
	v_mul_f32_e32 v106, v180, v108
	v_fmac_f32_e32 v111, v187, v106
	v_mul_f32_e32 v106, v180, v192
	v_fmac_f32_e32 v129, v182, v112
	v_fmac_f32_e32 v110, v188, v106
	v_mul_f32_e32 v106, v180, v193
	v_lshlrev_b32_e32 v112, 16, v94
	v_fmac_f32_e32 v109, v189, v106
	v_lshlrev_b32_e32 v108, 16, v102
	v_and_b32_e32 v107, 0xffff0000, v102
	v_lshlrev_b32_e32 v106, 16, v103
	v_and_b32_e32 v102, 0xffff0000, v103
	v_mul_f32_e32 v103, v179, v112
	v_cvt_pk_bf16_f32 v190, v129, v125
	v_fmac_f32_e32 v108, v182, v103
	v_mul_f32_e32 v103, v179, v113
	v_cvt_pk_bf16_f32 v191, v124, v123
	v_cvt_pk_bf16_f32 v192, v122, v111
	v_cvt_pk_bf16_f32 v193, v110, v109
	global_store_dwordx4 v[156:157], v[190:193], off offset:1024
	v_fmac_f32_e32 v107, v183, v103
	v_mul_f32_e32 v103, v179, v181
	v_and_b32_e32 v190, 0xffff0000, v95
	v_lshlrev_b32_e32 v191, 16, v96
	v_fmac_f32_e32 v106, v184, v103
	v_mul_f32_e32 v103, v179, v190
	v_and_b32_e32 v192, 0xffff0000, v96
	v_lshlrev_b32_e32 v193, 16, v97
	v_lshlrev_b32_e32 v97, 16, v104
	v_fmac_f32_e32 v102, v185, v103
	v_mul_f32_e32 v103, v179, v191
	v_and_b32_e32 v96, 0xffff0000, v104
	v_fmac_f32_e32 v97, v186, v103
	v_mul_f32_e32 v103, v179, v192
	v_lshlrev_b32_e32 v95, 16, v105
	v_fmac_f32_e32 v96, v187, v103
	v_mul_f32_e32 v103, v179, v193
	v_and_b32_e32 v94, 0xffff0000, v105
	v_fmac_f32_e32 v95, v188, v103
	v_mul_f32_e32 v103, v179, v194
	v_fmac_f32_e32 v94, v189, v103
	v_cvt_pk_bf16_f32 v182, v108, v107
	v_cvt_pk_bf16_f32 v183, v106, v102
	v_cvt_pk_bf16_f32 v184, v97, v96
	v_cvt_pk_bf16_f32 v185, v95, v94
	global_store_dwordx4 v[154:155], v[182:185], off offset:1024
	global_load_dwordx4 v[182:185], v[134:135], off
	s_nop 0
	global_load_dwordx4 v[186:189], v[134:135], off offset:16
	v_lshlrev_b32_e32 v181, 16, v86
	v_and_b32_e32 v86, 0xffff0000, v86
	v_lshlrev_b32_e32 v190, 16, v87
	v_and_b32_e32 v112, 0xffff0000, v90
	v_mul_f32_e32 v86, v180, v86
	v_and_b32_e32 v87, 0xffff0000, v87
	v_lshlrev_b32_e32 v105, 16, v91
	v_lshlrev_b32_e32 v191, 16, v88
	v_and_b32_e32 v104, 0xffff0000, v91
	v_and_b32_e32 v88, 0xffff0000, v88
	v_lshlrev_b32_e32 v103, 16, v92
	v_lshlrev_b32_e32 v192, 16, v89
	v_and_b32_e32 v91, 0xffff0000, v92
	v_and_b32_e32 v193, 0xffff0000, v89
	v_lshlrev_b32_e32 v113, 16, v90
	v_lshlrev_b32_e32 v90, 16, v93
	v_mul_f32_e32 v92, v180, v181
	v_and_b32_e32 v89, 0xffff0000, v93
	v_and_b32_e32 v93, 0xffff0000, v74
	v_lshlrev_b32_e32 v181, 16, v75
	v_and_b32_e32 v194, 0xffff0000, v77
	s_waitcnt vmcnt(1)
	v_fmac_f32_e32 v112, v86, v183
	v_mul_f32_e32 v86, v180, v190
	v_fmac_f32_e32 v105, v86, v184
	v_mul_f32_e32 v86, v180, v87
	v_fmac_f32_e32 v104, v86, v185
	v_mul_f32_e32 v86, v180, v191
	s_waitcnt vmcnt(0)
	v_fmac_f32_e32 v103, v86, v186
	v_mul_f32_e32 v86, v180, v88
	v_fmac_f32_e32 v91, v86, v187
	v_mul_f32_e32 v86, v180, v192
	v_fmac_f32_e32 v113, v92, v182
	v_fmac_f32_e32 v90, v86, v188
	v_mul_f32_e32 v86, v180, v193
	v_lshlrev_b32_e32 v92, 16, v74
	v_fmac_f32_e32 v89, v86, v189
	v_lshlrev_b32_e32 v88, 16, v82
	v_and_b32_e32 v87, 0xffff0000, v82
	v_lshlrev_b32_e32 v86, 16, v83
	v_and_b32_e32 v82, 0xffff0000, v83
	v_mul_f32_e32 v83, v179, v92
	v_cvt_pk_bf16_f32 v190, v113, v112
	v_fmac_f32_e32 v88, v83, v182
	v_mul_f32_e32 v83, v179, v93
	v_cvt_pk_bf16_f32 v191, v105, v104
	v_cvt_pk_bf16_f32 v192, v103, v91
	v_cvt_pk_bf16_f32 v193, v90, v89
	global_store_dwordx4 v[156:157], v[190:193], off offset:2048
	v_fmac_f32_e32 v87, v83, v183
	v_mul_f32_e32 v83, v179, v181
	v_and_b32_e32 v190, 0xffff0000, v75
	v_lshlrev_b32_e32 v191, 16, v76
	v_fmac_f32_e32 v86, v83, v184
	v_mul_f32_e32 v83, v179, v190
	v_and_b32_e32 v192, 0xffff0000, v76
	v_lshlrev_b32_e32 v193, 16, v77
	v_lshlrev_b32_e32 v77, 16, v84
	v_fmac_f32_e32 v82, v83, v185
	v_mul_f32_e32 v83, v179, v191
	v_and_b32_e32 v76, 0xffff0000, v84
	v_fmac_f32_e32 v77, v83, v186
	v_mul_f32_e32 v83, v179, v192
	v_lshlrev_b32_e32 v75, 16, v85
	v_fmac_f32_e32 v76, v83, v187
	v_mul_f32_e32 v83, v179, v193
	v_and_b32_e32 v74, 0xffff0000, v85
	v_fmac_f32_e32 v75, v83, v188
	v_mul_f32_e32 v83, v179, v194
	v_fmac_f32_e32 v74, v83, v189
	v_cvt_pk_bf16_f32 v182, v88, v87
	v_cvt_pk_bf16_f32 v183, v86, v82
	v_cvt_pk_bf16_f32 v184, v77, v76
	v_cvt_pk_bf16_f32 v185, v75, v74
	global_store_dwordx4 v[154:155], v[182:185], off offset:2048
	global_load_dwordx4 v[182:185], v[136:137], off
	s_nop 0
	global_load_dwordx4 v[186:189], v[136:137], off offset:16
	v_lshlrev_b32_e32 v181, 16, v66
	v_and_b32_e32 v66, 0xffff0000, v66
	v_lshlrev_b32_e32 v190, 16, v67
	v_and_b32_e32 v92, 0xffff0000, v70
	v_mul_f32_e32 v66, v180, v66
	v_and_b32_e32 v67, 0xffff0000, v67
	v_lshlrev_b32_e32 v85, 16, v71
	v_lshlrev_b32_e32 v191, 16, v68
	v_and_b32_e32 v84, 0xffff0000, v71
	v_and_b32_e32 v68, 0xffff0000, v68
	v_lshlrev_b32_e32 v83, 16, v72
	v_lshlrev_b32_e32 v192, 16, v69
	v_and_b32_e32 v71, 0xffff0000, v72
	v_and_b32_e32 v193, 0xffff0000, v69
	v_lshlrev_b32_e32 v93, 16, v70
	v_lshlrev_b32_e32 v70, 16, v73
	v_mul_f32_e32 v72, v180, v181
	v_and_b32_e32 v69, 0xffff0000, v73
	v_and_b32_e32 v73, 0xffff0000, v58
	v_lshlrev_b32_e32 v181, 16, v60
	s_waitcnt vmcnt(1)
	v_fmac_f32_e32 v92, v66, v183
	v_mul_f32_e32 v66, v180, v190
	v_fmac_f32_e32 v85, v66, v184
	v_mul_f32_e32 v66, v180, v67
	v_fmac_f32_e32 v84, v66, v185
	v_mul_f32_e32 v66, v180, v191
	s_waitcnt vmcnt(0)
	v_fmac_f32_e32 v83, v66, v186
	v_mul_f32_e32 v66, v180, v68
	v_fmac_f32_e32 v71, v66, v187
	v_mul_f32_e32 v66, v180, v192
	v_fmac_f32_e32 v93, v72, v182
	v_fmac_f32_e32 v70, v66, v188
	v_mul_f32_e32 v66, v180, v193
	v_lshlrev_b32_e32 v72, 16, v58
	v_fmac_f32_e32 v69, v66, v189
	v_lshlrev_b32_e32 v68, 16, v62
	v_and_b32_e32 v67, 0xffff0000, v62
	v_lshlrev_b32_e32 v66, 16, v63
	v_and_b32_e32 v62, 0xffff0000, v63
	v_mul_f32_e32 v63, v179, v72
	v_cvt_pk_bf16_f32 v190, v93, v92
	v_cvt_pk_bf16_f32 v191, v85, v84
	v_cvt_pk_bf16_f32 v192, v83, v71
	v_cvt_pk_bf16_f32 v193, v70, v69
	global_store_dwordx4 v[156:157], v[190:193], off offset:3072
	v_lshlrev_b32_e32 v156, 16, v59
	v_fmac_f32_e32 v68, v63, v182
	v_mul_f32_e32 v63, v179, v73
	v_and_b32_e32 v157, 0xffff0000, v59
	v_fmac_f32_e32 v67, v63, v183
	v_mul_f32_e32 v63, v179, v156
	v_fmac_f32_e32 v66, v63, v184
	v_mul_f32_e32 v63, v179, v157
	v_and_b32_e32 v190, 0xffff0000, v60
	v_lshlrev_b32_e32 v191, 16, v61
	v_and_b32_e32 v192, 0xffff0000, v61
	v_lshlrev_b32_e32 v61, 16, v64
	v_fmac_f32_e32 v62, v63, v185
	v_mul_f32_e32 v63, v179, v181
	v_and_b32_e32 v60, 0xffff0000, v64
	v_fmac_f32_e32 v61, v63, v186
	v_mul_f32_e32 v63, v179, v190
	v_lshlrev_b32_e32 v59, 16, v65
	v_fmac_f32_e32 v60, v63, v187
	v_mul_f32_e32 v63, v179, v191
	v_and_b32_e32 v58, 0xffff0000, v65
	v_fmac_f32_e32 v59, v63, v188
	v_mul_f32_e32 v63, v179, v192
	v_fmac_f32_e32 v58, v63, v189
	v_cvt_pk_bf16_f32 v182, v68, v67
	v_cvt_pk_bf16_f32 v183, v66, v62
	v_cvt_pk_bf16_f32 v184, v61, v60
	v_cvt_pk_bf16_f32 v185, v59, v58
	global_store_dwordx4 v[154:155], v[182:185], off offset:3072
	global_load_dwordx4 v[154:157], v[138:139], off
	s_nop 0
	global_load_dwordx4 v[182:185], v[138:139], off offset:16
	v_lshlrev_b32_e32 v63, 16, v46
	v_and_b32_e32 v46, 0xffff0000, v46
	v_lshlrev_b32_e32 v64, 16, v47
	v_and_b32_e32 v181, 0xffff0000, v54
	v_mul_f32_e32 v46, v180, v46
	v_and_b32_e32 v47, 0xffff0000, v47
	v_lshlrev_b32_e32 v186, 16, v55
	v_lshlrev_b32_e32 v65, 16, v48
	v_and_b32_e32 v187, 0xffff0000, v55
	v_and_b32_e32 v48, 0xffff0000, v48
	v_lshlrev_b32_e32 v188, 16, v56
	v_lshlrev_b32_e32 v72, 16, v49
	v_and_b32_e32 v189, 0xffff0000, v56
	v_and_b32_e32 v49, 0xffff0000, v49
	v_lshlrev_b32_e32 v190, 16, v57
	v_lshlrev_b32_e32 v73, 16, v54
	v_and_b32_e32 v191, 0xffff0000, v57
	v_mul_f32_e32 v54, v180, v63
	v_and_b32_e32 v55, 0xffff0000, v42
	v_lshlrev_b32_e32 v56, 16, v43
	v_and_b32_e32 v57, 0xffff0000, v43
	v_lshlrev_b32_e32 v63, 16, v44
	v_lshlrev_b32_e32 v43, 16, v53
	s_waitcnt vmcnt(1)
	v_fmac_f32_e32 v181, v46, v155
	v_mul_f32_e32 v46, v180, v64
	v_fmac_f32_e32 v186, v46, v156
	v_mul_f32_e32 v46, v180, v47
	v_fmac_f32_e32 v187, v46, v157
	v_mul_f32_e32 v46, v180, v65
	s_waitcnt vmcnt(0)
	v_fmac_f32_e32 v188, v46, v182
	v_mul_f32_e32 v46, v180, v48
	v_fmac_f32_e32 v189, v46, v183
	v_mul_f32_e32 v46, v180, v72
	v_fmac_f32_e32 v190, v46, v184
	v_mul_f32_e32 v46, v180, v49
	v_fmac_f32_e32 v73, v54, v154
	v_fmac_f32_e32 v191, v46, v185
	v_cvt_pk_bf16_f32 v46, v73, v181
	v_cvt_pk_bf16_f32 v47, v186, v187
	v_cvt_pk_bf16_f32 v48, v188, v189
	v_cvt_pk_bf16_f32 v49, v190, v191
	v_lshlrev_b32_e32 v54, 16, v42
	global_store_dwordx4 v[150:151], v[46:49], off
	v_and_b32_e32 v64, 0xffff0000, v44
	v_lshlrev_b32_e32 v65, 16, v45
	v_lshlrev_b32_e32 v49, 16, v50
	v_and_b32_e32 v48, 0xffff0000, v50
	v_mul_f32_e32 v50, v179, v54
	v_fmac_f32_e32 v49, v50, v154
	v_mul_f32_e32 v50, v179, v55
	v_lshlrev_b32_e32 v47, 16, v51
	v_fmac_f32_e32 v48, v50, v155
	v_mul_f32_e32 v50, v179, v56
	v_and_b32_e32 v46, 0xffff0000, v51
	v_fmac_f32_e32 v47, v50, v156
	v_mul_f32_e32 v50, v179, v57
	v_and_b32_e32 v72, 0xffff0000, v45
	v_lshlrev_b32_e32 v45, 16, v52
	v_fmac_f32_e32 v46, v50, v157
	v_mul_f32_e32 v50, v179, v63
	v_and_b32_e32 v44, 0xffff0000, v52
	v_fmac_f32_e32 v45, v50, v182
	v_mul_f32_e32 v50, v179, v64
	v_fmac_f32_e32 v44, v50, v183
	v_mul_f32_e32 v50, v179, v65
	v_and_b32_e32 v42, 0xffff0000, v53
	v_fmac_f32_e32 v43, v50, v184
	v_mul_f32_e32 v50, v179, v72
	v_fmac_f32_e32 v42, v50, v185
	v_cvt_pk_bf16_f32 v50, v49, v48
	v_cvt_pk_bf16_f32 v51, v47, v46
	v_cvt_pk_bf16_f32 v52, v45, v44
	v_cvt_pk_bf16_f32 v53, v43, v42
	global_store_dwordx4 v[152:153], v[50:53], off
	global_load_dwordx4 v[50:53], v[140:141], off
	s_nop 0
	global_load_dwordx4 v[54:57], v[140:141], off offset:16
	v_lshlrev_b32_e32 v63, 16, v34
	v_and_b32_e32 v34, 0xffff0000, v34
	v_lshlrev_b32_e32 v64, 16, v35
	v_lshlrev_b32_e32 v154, 16, v38
	v_and_b32_e32 v38, 0xffff0000, v38
	v_mul_f32_e32 v34, v180, v34
	v_and_b32_e32 v35, 0xffff0000, v35
	v_lshlrev_b32_e32 v155, 16, v39
	v_lshlrev_b32_e32 v65, 16, v36
	v_and_b32_e32 v39, 0xffff0000, v39
	v_and_b32_e32 v36, 0xffff0000, v36
	v_lshlrev_b32_e32 v156, 16, v40
	v_lshlrev_b32_e32 v72, 16, v37
	v_and_b32_e32 v40, 0xffff0000, v40
	v_and_b32_e32 v37, 0xffff0000, v37
	v_lshlrev_b32_e32 v157, 16, v41
	v_and_b32_e32 v41, 0xffff0000, v41
	v_mul_f32_e32 v63, v180, v63
	v_lshlrev_b32_e32 v182, 16, v32
	v_and_b32_e32 v183, 0xffff0000, v32
	v_lshlrev_b32_e32 v184, 16, v33
	v_and_b32_e32 v185, 0xffff0000, v33
	s_waitcnt vmcnt(1)
	v_fmac_f32_e32 v38, v34, v51
	v_mul_f32_e32 v34, v180, v64
	v_fmac_f32_e32 v155, v34, v52
	v_mul_f32_e32 v34, v180, v35
	v_fmac_f32_e32 v39, v34, v53
	v_mul_f32_e32 v34, v180, v65
	s_waitcnt vmcnt(0)
	v_fmac_f32_e32 v156, v34, v54
	v_mul_f32_e32 v34, v180, v36
	v_fmac_f32_e32 v40, v34, v55
	v_mul_f32_e32 v34, v180, v72
	v_fmac_f32_e32 v157, v34, v56
	v_mul_f32_e32 v34, v180, v37
	v_fmac_f32_e32 v154, v63, v50
	v_fmac_f32_e32 v41, v34, v57
	v_cvt_pk_bf16_f32 v34, v154, v38
	v_cvt_pk_bf16_f32 v35, v155, v39
	v_cvt_pk_bf16_f32 v36, v156, v40
	v_cvt_pk_bf16_f32 v37, v157, v41
	global_store_dwordx4 v[150:151], v[34:37], off offset:1024
	v_and_b32_e32 v64, 0xffff0000, v30
	v_lshlrev_b32_e32 v65, 16, v31
	v_lshlrev_b32_e32 v34, 16, v26
	v_and_b32_e32 v26, 0xffff0000, v26
	v_lshlrev_b32_e32 v35, 16, v27
	v_mul_f32_e32 v26, v179, v26
	v_and_b32_e32 v27, 0xffff0000, v27
	v_fmac_f32_e32 v64, v26, v51
	v_mul_f32_e32 v26, v179, v35
	v_lshlrev_b32_e32 v36, 16, v28
	v_and_b32_e32 v72, 0xffff0000, v31
	v_fmac_f32_e32 v65, v26, v52
	v_mul_f32_e32 v26, v179, v27
	v_and_b32_e32 v28, 0xffff0000, v28
	v_fmac_f32_e32 v72, v26, v53
	v_mul_f32_e32 v26, v179, v36
	v_lshlrev_b32_e32 v37, 16, v29
	v_fmac_f32_e32 v182, v26, v54
	v_mul_f32_e32 v26, v179, v28
	v_and_b32_e32 v29, 0xffff0000, v29
	v_fmac_f32_e32 v183, v26, v55
	v_mul_f32_e32 v26, v179, v37
	v_lshlrev_b32_e32 v63, 16, v30
	v_mul_f32_e32 v30, v179, v34
	v_fmac_f32_e32 v184, v26, v56
	v_mul_f32_e32 v26, v179, v29
	v_fmac_f32_e32 v63, v30, v50
	v_fmac_f32_e32 v185, v26, v57
	v_cvt_pk_bf16_f32 v26, v63, v64
	v_cvt_pk_bf16_f32 v27, v65, v72
	v_cvt_pk_bf16_f32 v28, v182, v183
	v_cvt_pk_bf16_f32 v29, v184, v185
	global_store_dwordx4 v[152:153], v[26:29], off offset:1024
	global_load_dwordx4 v[26:29], v[142:143], off
	s_nop 0
	global_load_dwordx4 v[30:33], v[142:143], off offset:16
	v_lshlrev_b32_e32 v34, 16, v18
	v_and_b32_e32 v18, 0xffff0000, v18
	v_lshlrev_b32_e32 v35, 16, v19
	v_lshlrev_b32_e32 v50, 16, v22
	v_and_b32_e32 v22, 0xffff0000, v22
	v_mul_f32_e32 v18, v180, v18
	v_and_b32_e32 v19, 0xffff0000, v19
	v_lshlrev_b32_e32 v51, 16, v23
	v_lshlrev_b32_e32 v36, 16, v20
	v_and_b32_e32 v23, 0xffff0000, v23
	v_and_b32_e32 v20, 0xffff0000, v20
	v_lshlrev_b32_e32 v52, 16, v24
	v_lshlrev_b32_e32 v37, 16, v21
	v_and_b32_e32 v24, 0xffff0000, v24
	v_and_b32_e32 v21, 0xffff0000, v21
	v_lshlrev_b32_e32 v53, 16, v25
	v_and_b32_e32 v25, 0xffff0000, v25
	v_mul_f32_e32 v34, v180, v34
	v_lshlrev_b32_e32 v54, 16, v100
	v_and_b32_e32 v55, 0xffff0000, v100
	v_lshlrev_b32_e32 v56, 16, v101
	v_and_b32_e32 v57, 0xffff0000, v101
	s_waitcnt vmcnt(1)
	v_fmac_f32_e32 v22, v18, v27
	v_mul_f32_e32 v18, v180, v35
	v_fmac_f32_e32 v51, v18, v28
	v_mul_f32_e32 v18, v180, v19
	v_fmac_f32_e32 v23, v18, v29
	v_mul_f32_e32 v18, v180, v36
	s_waitcnt vmcnt(0)
	v_fmac_f32_e32 v52, v18, v30
	v_mul_f32_e32 v18, v180, v20
	v_fmac_f32_e32 v24, v18, v31
	v_mul_f32_e32 v18, v180, v37
	v_fmac_f32_e32 v53, v18, v32
	v_mul_f32_e32 v18, v180, v21
	v_fmac_f32_e32 v50, v34, v26
	v_fmac_f32_e32 v25, v18, v33
	v_cvt_pk_bf16_f32 v18, v50, v22
	v_cvt_pk_bf16_f32 v19, v51, v23
	v_cvt_pk_bf16_f32 v20, v52, v24
	v_cvt_pk_bf16_f32 v21, v53, v25
	global_store_dwordx4 v[150:151], v[18:21], off offset:2048
	v_and_b32_e32 v35, 0xffff0000, v98
	v_lshlrev_b32_e32 v36, 16, v99
	v_lshlrev_b32_e32 v18, 16, v14
	v_and_b32_e32 v14, 0xffff0000, v14
	v_lshlrev_b32_e32 v19, 16, v15
	v_mul_f32_e32 v14, v179, v14
	v_and_b32_e32 v15, 0xffff0000, v15
	v_fmac_f32_e32 v35, v14, v27
	v_mul_f32_e32 v14, v179, v19
	v_lshlrev_b32_e32 v20, 16, v16
	v_and_b32_e32 v37, 0xffff0000, v99
	v_fmac_f32_e32 v36, v14, v28
	v_mul_f32_e32 v14, v179, v15
	v_and_b32_e32 v16, 0xffff0000, v16
	v_fmac_f32_e32 v37, v14, v29
	v_mul_f32_e32 v14, v179, v20
	v_lshlrev_b32_e32 v21, 16, v17
	v_fmac_f32_e32 v54, v14, v30
	v_mul_f32_e32 v14, v179, v16
	v_and_b32_e32 v17, 0xffff0000, v17
	v_fmac_f32_e32 v55, v14, v31
	v_mul_f32_e32 v14, v179, v21
	v_lshlrev_b32_e32 v34, 16, v98
	v_mul_f32_e32 v18, v179, v18
	v_fmac_f32_e32 v56, v14, v32
	v_mul_f32_e32 v14, v179, v17
	v_fmac_f32_e32 v34, v18, v26
	v_fmac_f32_e32 v57, v14, v33
	v_cvt_pk_bf16_f32 v14, v34, v35
	v_cvt_pk_bf16_f32 v15, v36, v37
	v_cvt_pk_bf16_f32 v16, v54, v55
	v_cvt_pk_bf16_f32 v17, v56, v57
	global_store_dwordx4 v[152:153], v[14:17], off offset:2048
	global_load_dwordx4 v[14:17], v[144:145], off
	s_nop 0
	global_load_dwordx4 v[18:21], v[144:145], off offset:16
	v_lshlrev_b32_e32 v26, 16, v6
	v_and_b32_e32 v6, 0xffff0000, v6
	v_lshlrev_b32_e32 v27, 16, v7
	v_lshlrev_b32_e32 v30, 16, v10
	v_and_b32_e32 v10, 0xffff0000, v10
	v_mul_f32_e32 v6, v180, v6
	v_and_b32_e32 v7, 0xffff0000, v7
	v_lshlrev_b32_e32 v31, 16, v11
	v_lshlrev_b32_e32 v28, 16, v8
	v_and_b32_e32 v11, 0xffff0000, v11
	v_and_b32_e32 v8, 0xffff0000, v8
	v_lshlrev_b32_e32 v32, 16, v12
	v_lshlrev_b32_e32 v29, 16, v9
	v_and_b32_e32 v12, 0xffff0000, v12
	v_and_b32_e32 v9, 0xffff0000, v9
	v_lshlrev_b32_e32 v33, 16, v13
	v_and_b32_e32 v13, 0xffff0000, v13
	v_mul_f32_e32 v26, v180, v26
	s_waitcnt vmcnt(1)
	v_fmac_f32_e32 v10, v6, v15
	v_mul_f32_e32 v6, v180, v27
	v_fmac_f32_e32 v31, v6, v16
	v_mul_f32_e32 v6, v180, v7
	v_fmac_f32_e32 v11, v6, v17
	v_mul_f32_e32 v6, v180, v28
	s_waitcnt vmcnt(0)
	v_fmac_f32_e32 v32, v6, v18
	v_mul_f32_e32 v6, v180, v8
	v_fmac_f32_e32 v12, v6, v19
	v_mul_f32_e32 v6, v180, v29
	v_fmac_f32_e32 v33, v6, v20
	v_mul_f32_e32 v6, v180, v9
	v_fmac_f32_e32 v13, v6, v21
	v_lshlrev_b32_e32 v6, 16, v2
	v_and_b32_e32 v2, 0xffff0000, v2
	v_lshlrev_b32_e32 v7, 16, v3
	v_and_b32_e32 v27, 0xffff0000, v78
	v_mul_f32_e32 v2, v179, v2
	v_and_b32_e32 v3, 0xffff0000, v3
	v_lshlrev_b32_e32 v28, 16, v79
	v_fmac_f32_e32 v27, v2, v15
	v_mul_f32_e32 v2, v179, v7
	v_lshlrev_b32_e32 v8, 16, v4
	v_and_b32_e32 v29, 0xffff0000, v79
	v_fmac_f32_e32 v28, v2, v16
	v_mul_f32_e32 v2, v179, v3
	v_fmac_f32_e32 v30, v26, v14
	v_and_b32_e32 v4, 0xffff0000, v4
	v_lshlrev_b32_e32 v26, 16, v78
	v_lshlrev_b32_e32 v78, 16, v80
	v_fmac_f32_e32 v29, v2, v17
	v_mul_f32_e32 v2, v179, v8
	v_lshlrev_b32_e32 v9, 16, v5
	v_and_b32_e32 v79, 0xffff0000, v80
	v_fmac_f32_e32 v78, v2, v18
	v_mul_f32_e32 v2, v179, v4
	v_and_b32_e32 v5, 0xffff0000, v5
	v_lshlrev_b32_e32 v80, 16, v81
	v_fmac_f32_e32 v79, v2, v19
	v_mul_f32_e32 v2, v179, v9
	v_and_b32_e32 v81, 0xffff0000, v81
	v_fmac_f32_e32 v80, v2, v20
	v_mul_f32_e32 v2, v179, v5
	v_fmac_f32_e32 v81, v2, v21
	v_mul_f32_e32 v2, v178, v178
	v_mul_f32_e32 v3, v121, v121
	v_fmac_f32_e32 v2, v176, v176
	v_fmac_f32_e32 v3, v119, v119
	v_fmac_f32_e32 v2, v177, v177
	v_fmac_f32_e32 v3, v120, v120
	v_fmac_f32_e32 v2, v175, v175
	v_fmac_f32_e32 v3, v118, v118
	v_fmac_f32_e32 v2, v174, v174
	v_fmac_f32_e32 v3, v117, v117
	v_fmac_f32_e32 v2, v128, v128
	v_fmac_f32_e32 v3, v116, v116
	v_fmac_f32_e32 v2, v127, v127
	v_fmac_f32_e32 v3, v115, v115
	v_fmac_f32_e32 v2, v126, v126
	v_fmac_f32_e32 v3, v114, v114
	v_fmac_f32_e32 v2, v129, v129
	v_fmac_f32_e32 v3, v108, v108
	v_fmac_f32_e32 v2, v125, v125
	v_fmac_f32_e32 v3, v107, v107
	v_fmac_f32_e32 v2, v124, v124
	v_fmac_f32_e32 v3, v106, v106
	v_fmac_f32_e32 v2, v123, v123
	v_fmac_f32_e32 v3, v102, v102
	v_fmac_f32_e32 v2, v122, v122
	v_fmac_f32_e32 v3, v97, v97
	v_fmac_f32_e32 v2, v111, v111
	v_fmac_f32_e32 v3, v96, v96
	v_fmac_f32_e32 v2, v110, v110
	v_fmac_f32_e32 v3, v95, v95
	v_fmac_f32_e32 v2, v109, v109
	v_fmac_f32_e32 v3, v94, v94
	v_fmac_f32_e32 v2, v113, v113
	v_fmac_f32_e32 v3, v88, v88
	v_fmac_f32_e32 v2, v112, v112
	v_fmac_f32_e32 v3, v87, v87
	v_fmac_f32_e32 v2, v105, v105
	v_fmac_f32_e32 v3, v86, v86
	v_fmac_f32_e32 v2, v104, v104
	v_fmac_f32_e32 v3, v82, v82
	v_fmac_f32_e32 v2, v103, v103
	v_fmac_f32_e32 v3, v77, v77
	v_fmac_f32_e32 v2, v91, v91
	v_fmac_f32_e32 v3, v76, v76
	v_fmac_f32_e32 v2, v90, v90
	v_fmac_f32_e32 v3, v75, v75
	v_fmac_f32_e32 v2, v89, v89
	v_fmac_f32_e32 v3, v74, v74
	v_fmac_f32_e32 v2, v93, v93
	v_fmac_f32_e32 v3, v68, v68
	v_fmac_f32_e32 v2, v92, v92
	v_fmac_f32_e32 v3, v67, v67
	v_fmac_f32_e32 v2, v85, v85
	v_fmac_f32_e32 v3, v66, v66
	v_fmac_f32_e32 v2, v84, v84
	v_fmac_f32_e32 v3, v62, v62
	v_fmac_f32_e32 v2, v83, v83
	v_fmac_f32_e32 v3, v61, v61
	v_fmac_f32_e32 v2, v71, v71
	v_fmac_f32_e32 v3, v60, v60
	v_fmac_f32_e32 v2, v70, v70
	v_fmac_f32_e32 v3, v59, v59
	v_fmac_f32_e32 v2, v69, v69
	v_fmac_f32_e32 v3, v58, v58
	v_fmac_f32_e32 v2, v73, v73
	v_fmac_f32_e32 v3, v49, v49
	v_fmac_f32_e32 v2, v181, v181
	v_fmac_f32_e32 v3, v48, v48
	v_fmac_f32_e32 v2, v186, v186
	v_fmac_f32_e32 v3, v47, v47
	v_fmac_f32_e32 v2, v187, v187
	v_fmac_f32_e32 v3, v46, v46
	v_fmac_f32_e32 v2, v188, v188
	v_fmac_f32_e32 v3, v45, v45
	v_fmac_f32_e32 v2, v189, v189
	v_fmac_f32_e32 v3, v44, v44
	v_fmac_f32_e32 v2, v190, v190
	v_fmac_f32_e32 v3, v43, v43
	v_fmac_f32_e32 v2, v191, v191
	v_fmac_f32_e32 v3, v42, v42
	v_fmac_f32_e32 v2, v154, v154
	v_fmac_f32_e32 v3, v63, v63
	v_fmac_f32_e32 v2, v38, v38
	v_fmac_f32_e32 v3, v64, v64
	v_fmac_f32_e32 v2, v155, v155
	v_fmac_f32_e32 v3, v65, v65
	v_fmac_f32_e32 v2, v39, v39
	v_fmac_f32_e32 v3, v72, v72
	v_fmac_f32_e32 v2, v156, v156
	v_fmac_f32_e32 v3, v182, v182
	v_fmac_f32_e32 v2, v40, v40
	v_fmac_f32_e32 v3, v183, v183
	v_fmac_f32_e32 v2, v157, v157
	v_fmac_f32_e32 v3, v184, v184
	v_fmac_f32_e32 v2, v41, v41
	v_fmac_f32_e32 v3, v185, v185
	v_fmac_f32_e32 v2, v50, v50
	v_fmac_f32_e32 v3, v34, v34
	v_fmac_f32_e32 v2, v22, v22
	v_fmac_f32_e32 v3, v35, v35
	v_fmac_f32_e32 v2, v51, v51
	v_fmac_f32_e32 v3, v36, v36
	v_fmac_f32_e32 v2, v23, v23
	v_fmac_f32_e32 v3, v37, v37
	v_fmac_f32_e32 v2, v52, v52
	v_fmac_f32_e32 v3, v54, v54
	v_fmac_f32_e32 v2, v24, v24
	v_fmac_f32_e32 v3, v55, v55
	v_mul_f32_e32 v6, v179, v6
	v_fmac_f32_e32 v2, v53, v53
	v_fmac_f32_e32 v3, v56, v56
	v_fmac_f32_e32 v26, v6, v14
	v_fmac_f32_e32 v2, v25, v25
	v_fmac_f32_e32 v3, v57, v57
	v_fmac_f32_e32 v2, v30, v30
	v_fmac_f32_e32 v3, v26, v26
	v_fmac_f32_e32 v2, v10, v10
	v_fmac_f32_e32 v3, v27, v27
	v_fmac_f32_e32 v2, v31, v31
	v_fmac_f32_e32 v3, v28, v28
	v_fmac_f32_e32 v2, v11, v11
	v_fmac_f32_e32 v3, v29, v29
	v_fmac_f32_e32 v2, v32, v32
	v_fmac_f32_e32 v3, v78, v78
	v_fmac_f32_e32 v2, v12, v12
	v_fmac_f32_e32 v3, v79, v79
	v_fmac_f32_e32 v2, v33, v33
	v_fmac_f32_e32 v3, v80, v80
	v_fmac_f32_e32 v2, v13, v13
	v_fmac_f32_e32 v3, v81, v81
	s_waitcnt lgkmcnt(0)
	s_nop 1
	v_add_f32_dpp v2, v2, v2 quad_perm:[1,0,3,2] row_mask:0xf bank_mask:0xf
	s_waitcnt lgkmcnt(0)
	s_nop 1
	v_add_f32_dpp v3, v3, v3 quad_perm:[1,0,3,2] row_mask:0xf bank_mask:0xf
	s_waitcnt lgkmcnt(0)
	s_nop 1
	v_add_f32_dpp v4, v2, v2 quad_perm:[2,3,0,1] row_mask:0xf bank_mask:0xf
	s_waitcnt lgkmcnt(0)
	s_nop 1
	v_add_f32_dpp v5, v3, v3 quad_perm:[2,3,0,1] row_mask:0xf bank_mask:0xf
	v_cvt_pk_bf16_f32 v2, v30, v10
	v_cvt_pk_bf16_f32 v3, v31, v11
	s_waitcnt lgkmcnt(0)
	s_nop 1
	v_add_f32_dpp v6, v4, v4 row_half_mirror row_mask:0xf bank_mask:0xf
	s_waitcnt lgkmcnt(0)
	s_nop 1
	v_add_f32_dpp v7, v5, v5 row_half_mirror row_mask:0xf bank_mask:0xf
	v_cvt_pk_bf16_f32 v4, v32, v12
	v_cvt_pk_bf16_f32 v5, v33, v13
	global_store_dwordx4 v[150:151], v[2:5], off offset:3072
	s_waitcnt lgkmcnt(0)
	s_nop 1
	v_add_f32_dpp v8, v6, v6 row_mirror row_mask:0xf bank_mask:0xf
	s_waitcnt lgkmcnt(0)
	s_nop 1
	v_add_f32_dpp v7, v7, v7 row_mirror row_mask:0xf bank_mask:0xf
	v_cvt_pk_bf16_f32 v6, v26, v27
	s_waitcnt lgkmcnt(0)
	v_mov_b32_e32 v2, v8
	v_mov_b32_e32 v10, v8
	s_nop 1
	v_permlane16_swap_b32_e32 v10, v2
	v_add_f32_e32 v2, v2, v10
	s_waitcnt lgkmcnt(0)
	v_mov_b32_e32 v4, v7
	v_mov_b32_e32 v9, v7
	s_nop 1
	v_permlane16_swap_b32_e32 v9, v4
	v_add_f32_e32 v4, v4, v9
	ds_bpermute_b32 v3, v173, v2
	ds_bpermute_b32 v5, v173, v4
	v_cvt_pk_bf16_f32 v7, v28, v29
	v_cvt_pk_bf16_f32 v8, v78, v79
	v_cvt_pk_bf16_f32 v9, v80, v81
	global_store_dwordx4 v[152:153], v[6:9], off offset:3072
	s_and_saveexec_b64 s[14:15], s[0:1]
	s_cbranch_execz .LBB0_1172
	s_waitcnt lgkmcnt(0)
	v_add_f32_e32 v4, v4, v5
	v_fmamk_f32 v4, v4, 0x39800000, v158
	v_mul_f32_e32 v5, 0x4f800000, v4
	v_cmp_gt_f32_e32 vcc, s20, v4
	v_add_f32_e32 v2, v2, v3
	v_fmamk_f32 v2, v2, 0x39800000, v158
	v_cndmask_b32_e32 v4, v4, v5, vcc
	v_sqrt_f32_e32 v5, v4
	v_mul_f32_e32 v3, 0x4f800000, v2
	s_add_u32 s24, s4, s17
	s_addc_u32 s25, s5, s18
	v_add_u32_e32 v6, -1, v5
	v_fma_f32 v7, -v6, v5, v4
	v_cmp_ge_f32_e64 s[2:3], 0, v7
	v_add_u32_e32 v7, 1, v5
	s_add_u32 s26, s4, s7
	v_cndmask_b32_e64 v6, v5, v6, s[2:3]
	v_fma_f32 v5, -v7, v5, v4
	v_cmp_lt_f32_e64 s[2:3], 0, v5
	s_addc_u32 s27, s5, s16
	s_nop 0
	v_cndmask_b32_e64 v5, v6, v7, s[2:3]
	v_cmp_gt_f32_e64 s[2:3], s20, v2
	v_mul_f32_e32 v6, 0x37800000, v5
	v_cndmask_b32_e32 v5, v5, v6, vcc
	v_cndmask_b32_e64 v2, v2, v3, s[2:3]
	v_sqrt_f32_e32 v3, v2
	v_cmp_class_f32_e32 vcc, v4, v159
	s_nop 1
	v_cndmask_b32_e32 v4, v5, v4, vcc
	v_add_u32_e32 v5, -1, v3
	v_fma_f32 v6, -v5, v3, v2
	v_cmp_ge_f32_e32 vcc, 0, v6
	v_add_u32_e32 v6, 1, v3
	s_nop 0
	v_cndmask_b32_e32 v5, v3, v5, vcc
	v_fma_f32 v3, -v6, v3, v2
	v_cmp_lt_f32_e32 vcc, 0, v3
	s_nop 1
	v_cndmask_b32_e32 v3, v5, v6, vcc
	v_div_scale_f32 v6, s[28:29], v4, v4, 1.0
	v_rcp_f32_e32 v7, v6
	v_mul_f32_e32 v5, 0x37800000, v3
	v_cndmask_b32_e64 v3, v3, v5, s[2:3]
	v_cmp_class_f32_e32 vcc, v2, v159
	s_nop 1
	v_cndmask_b32_e32 v2, v3, v2, vcc
	v_fma_f32 v3, -v6, v7, 1.0
	v_fmac_f32_e32 v7, v3, v7
	v_div_scale_f32 v3, vcc, 1.0, v4, 1.0
	v_mul_f32_e32 v5, v3, v7
	v_fma_f32 v8, -v6, v5, v3
	v_fmac_f32_e32 v5, v8, v7
	v_fma_f32 v3, -v6, v5, v3
	v_div_scale_f32 v6, s[2:3], v2, v2, 1.0
	v_rcp_f32_e32 v8, v6
	v_div_fmas_f32 v3, v3, v7, v5
	v_div_fixup_f32 v3, v3, v4, 1.0
	v_fma_f32 v4, -v6, v8, 1.0
	v_fmac_f32_e32 v8, v4, v8
	v_div_scale_f32 v4, vcc, 1.0, v2, 1.0
	v_mul_f32_e32 v5, v4, v8
	v_fma_f32 v7, -v6, v5, v4
	v_fmac_f32_e32 v5, v7, v8
	v_fma_f32 v4, -v6, v5, v4
	v_div_fmas_f32 v4, v4, v8, v5
	v_div_fixup_f32 v2, v4, v2, 1.0
	global_store_dword v131, v2, s[26:27]
	global_store_dword v131, v3, s[24:25]
	s_branch .LBB0_1172

.Lattq_entry_A:
	v_mov_b64_e32 v[6:7], v[180:181]
	v_mov_b64_e32 v[8:9], v[182:183]
	v_mov_b64_e32 v[30:31], v[184:185]
	v_mov_b64_e32 v[32:33], v[186:187]
	global_load_dwordx4 v[180:183], v[84:85], off offset:-64
	global_load_dwordx4 v[184:187], v[84:85], off
	v_add_u32_e32 v2, s28, v90
	ds_read_b128 v[10:13], v2
	ds_read_b128 v[14:17], v2 offset:64
	ds_read_b128 v[18:21], v2 offset:2304
	ds_read_b128 v[22:25], v2 offset:2368
	ds_read_b128 v[26:29], v2 offset:4608
	ds_read_b128 v[104:107], v2 offset:4672
	v_mov_b32_e32 v5, v4
	v_lshl_add_u64 v[84:85], v[84:85], 0, s[34:35]
	s_waitcnt lgkmcnt(1)
	v_mfma_f32_16x16x32_bf16 v[108:111], v[26:29], v[6:9], 0
	ds_read_b128 v[26:29], v2 offset:6912
	ds_read_b128 v[112:115], v2 offset:6976
	s_waitcnt lgkmcnt(1)
	v_mfma_f32_16x16x32_bf16 v[116:119], v[26:29], v[6:9], 0
	ds_read_b128 v[26:29], v2 offset:9216
	ds_read_b128 v[120:123], v2 offset:9280
	s_waitcnt lgkmcnt(1)
	v_mfma_f32_16x16x32_bf16 v[124:127], v[26:29], v[6:9], 0
	ds_read_b128 v[26:29], v2 offset:11520
	ds_read_b128 v[128:131], v2 offset:11584
	s_waitcnt lgkmcnt(1)
	v_mfma_f32_16x16x32_bf16 v[132:135], v[26:29], v[6:9], 0
	ds_read_b128 v[26:29], v2 offset:13824
	ds_read_b128 v[136:139], v2 offset:13888
	s_waitcnt lgkmcnt(1)
	v_mfma_f32_16x16x32_bf16 v[140:143], v[26:29], v[6:9], 0
	ds_read_b128 v[26:29], v2 offset:16128
	ds_read_b128 v[46:49], v2 offset:16192
	v_mfma_f32_16x16x32_bf16 v[10:13], v[10:13], v[6:9], 0
	v_mfma_f32_16x16x32_bf16 v[18:21], v[18:21], v[6:9], 0
	s_waitcnt lgkmcnt(1)
	v_mfma_f32_16x16x32_bf16 v[50:53], v[26:29], v[6:9], 0
	ds_read_b128 v[26:29], v2 offset:18432
	ds_read_b128 v[38:41], v2 offset:18496
	v_mfma_f32_16x16x32_bf16 v[34:37], v[14:17], v[30:33], v[10:13]
	s_waitcnt lgkmcnt(1)
	v_mfma_f32_16x16x32_bf16 v[42:45], v[26:29], v[6:9], 0
	v_mfma_f32_16x16x32_bf16 v[26:29], v[22:25], v[30:33], v[18:21]
	s_nop 4
	v_mul_f32_e32 v2, 0x3e38aa3b, v34
	v_mul_f32_e32 v3, 0x3e38aa3b, v35
	v_mul_f32_e32 v34, 0x3e38aa3b, v36
	v_mfma_f32_16x16x32_bf16 v[22:25], v[104:107], v[30:33], v[108:111]
	v_mul_f32_e32 v35, 0x3e38aa3b, v37
	v_cndmask_b32_e64 v2, v97, v2, s[2:3]
	v_cndmask_b32_e64 v3, v97, v3, s[4:5]
	v_mfma_f32_16x16x32_bf16 v[18:21], v[112:115], v[30:33], v[116:119]
	v_cndmask_b32_e64 v34, v97, v34, s[6:7]
	v_cndmask_b32_e64 v35, v97, v35, s[8:9]
	v_mul_f32_e32 v36, 0x3e38aa3b, v26
	v_max3_f32 v118, v99, v2, v3
	v_mul_f32_e32 v37, 0x3e38aa3b, v27
	v_max3_f32 v118, v118, v34, v35
	v_mfma_f32_16x16x32_bf16 v[14:17], v[120:123], v[30:33], v[124:127]
	v_max3_f32 v36, v118, v36, v37
	v_add_u32_e32 v120, s28, v89
	s_addk_i32 s28, 0x900
	v_mfma_f32_16x16x32_bf16 v[10:13], v[128:131], v[30:33], v[132:135]
	s_cmpk_lg_i32 s28, 0x4800
	s_nop 2
	v_mul_f32_e32 v104, 0x3e38aa3b, v16
	v_mul_f32_e32 v105, 0x3e38aa3b, v17
	v_mfma_f32_16x16x32_bf16 v[6:9], v[136:139], v[30:33], v[140:143]
	v_mfma_f32_16x16x32_bf16 v[46:49], v[46:49], v[30:33], v[50:53]
	v_mul_f32_e32 v106, 0x3e38aa3b, v10
	v_mul_f32_e32 v107, 0x3e38aa3b, v11
	v_mul_f32_e32 v108, 0x3e38aa3b, v12
	s_waitcnt lgkmcnt(0)
	v_mfma_f32_16x16x32_bf16 v[30:33], v[38:41], v[30:33], v[42:45]
	v_mul_f32_e32 v38, 0x3e38aa3b, v28
	v_mul_f32_e32 v39, 0x3e38aa3b, v29
	v_mul_f32_e32 v40, 0x3e38aa3b, v22
	v_mul_f32_e32 v41, 0x3e38aa3b, v23
	v_max3_f32 v36, v36, v38, v39
	v_mul_f32_e32 v42, 0x3e38aa3b, v24
	v_mul_f32_e32 v43, 0x3e38aa3b, v25
	v_max3_f32 v36, v36, v40, v41
	v_mul_f32_e32 v44, 0x3e38aa3b, v18
	v_mul_f32_e32 v45, 0x3e38aa3b, v19
	v_max3_f32 v36, v36, v42, v43
	v_mul_f32_e32 v50, 0x3e38aa3b, v20
	v_mul_f32_e32 v51, 0x3e38aa3b, v21
	v_max3_f32 v36, v36, v44, v45
	v_mul_f32_e32 v52, 0x3e38aa3b, v14
	v_mul_f32_e32 v53, 0x3e38aa3b, v15
	v_max3_f32 v36, v36, v50, v51
	v_max3_f32 v36, v36, v52, v53
	v_max3_f32 v36, v36, v104, v105
	v_mul_f32_e32 v109, 0x3e38aa3b, v13
	v_max3_f32 v36, v36, v106, v107
	v_mul_f32_e32 v110, 0x3e38aa3b, v6
	v_mul_f32_e32 v111, 0x3e38aa3b, v7
	v_max3_f32 v36, v36, v108, v109
	v_mul_f32_e32 v112, 0x3e38aa3b, v8
	v_mul_f32_e32 v113, 0x3e38aa3b, v9
	v_max3_f32 v36, v36, v110, v111
	v_mul_f32_e32 v114, 0x3e38aa3b, v46
	v_mul_f32_e32 v115, 0x3e38aa3b, v47
	v_max3_f32 v36, v36, v112, v113
	v_mul_f32_e32 v116, 0x3e38aa3b, v48
	v_mul_f32_e32 v117, 0x3e38aa3b, v49
	v_mul_f32_e32 v30, 0x3e38aa3b, v30
	v_mul_f32_e32 v31, 0x3e38aa3b, v31
	v_max3_f32 v36, v36, v114, v115
	v_mul_f32_e32 v32, 0x3e38aa3b, v32
	v_mul_f32_e32 v33, 0x3e38aa3b, v33
	v_cndmask_b32_e64 v30, v97, v30, s[10:11]
	v_cndmask_b32_e64 v31, v97, v31, s[12:13]
	v_max3_f32 v36, v36, v116, v117
	v_cndmask_b32_e64 v32, v97, v32, s[14:15]
	v_cndmask_b32_e64 v33, v97, v33, s[16:17]
	v_max3_f32 v36, v36, v30, v31
	v_max3_f32 v36, v36, v32, v33
	s_waitcnt lgkmcnt(0)
	v_mov_b32_e32 v37, v36
	s_nop 1
	v_permlane16_swap_b32_e32 v37, v36
	v_max_f32_e32 v36, v36, v37
	s_waitcnt lgkmcnt(0)
	v_mov_b32_e32 v37, v36
	s_nop 1
	v_permlane32_swap_b32_e32 v37, v36
	v_max_f32_e32 v36, v36, v37
	v_sub_f32_e32 v2, v2, v36
	v_sub_f32_e32 v3, v3, v36
	v_sub_f32_e32 v34, v34, v36
	v_sub_f32_e32 v35, v35, v36
	v_fma_f32 v26, v26, s55, -v36
	v_fma_f32 v27, v27, s55, -v36
	v_fma_f32 v28, v28, s55, -v36
	v_fma_f32 v29, v29, s55, -v36
	v_fma_f32 v22, v22, s55, -v36
	v_fma_f32 v23, v23, s55, -v36
	v_fma_f32 v24, v24, s55, -v36
	v_fma_f32 v25, v25, s55, -v36
	v_fma_f32 v18, v18, s55, -v36
	v_fma_f32 v19, v19, s55, -v36
	v_fma_f32 v20, v20, s55, -v36
	v_fma_f32 v21, v21, s55, -v36
	v_fma_f32 v14, v14, s55, -v36
	v_fma_f32 v15, v15, s55, -v36
	v_fma_f32 v16, v16, s55, -v36
	v_fma_f32 v17, v17, s55, -v36
	v_fma_f32 v10, v10, s55, -v36
	v_fma_f32 v11, v11, s55, -v36
	v_fma_f32 v12, v12, s55, -v36
	v_fma_f32 v13, v13, s55, -v36
	v_fma_f32 v6, v6, s55, -v36
	v_fma_f32 v7, v7, s55, -v36
	v_fma_f32 v8, v8, s55, -v36
	v_fma_f32 v9, v9, s55, -v36
	v_exp_f32_e32 v2, v2
	v_exp_f32_e32 v121, v3
	v_exp_f32_e32 v122, v34
	v_exp_f32_e32 v123, v35
	v_exp_f32_e32 v124, v26
	v_exp_f32_e32 v125, v27
	v_exp_f32_e32 v126, v28
	v_exp_f32_e32 v127, v29
	v_exp_f32_e32 v128, v22
	v_exp_f32_e32 v129, v23
	v_exp_f32_e32 v130, v24
	v_exp_f32_e32 v131, v25
	v_exp_f32_e32 v132, v18
	v_exp_f32_e32 v133, v19
	v_exp_f32_e32 v134, v20
	v_exp_f32_e32 v135, v21
	v_exp_f32_e32 v136, v14
	v_exp_f32_e32 v137, v15
	v_exp_f32_e32 v138, v16
	v_exp_f32_e32 v139, v17
	v_exp_f32_e32 v140, v10
	v_exp_f32_e32 v141, v11
	v_exp_f32_e32 v142, v12
	v_exp_f32_e32 v143, v13
	v_exp_f32_e32 v144, v6
	v_exp_f32_e32 v145, v7
	v_exp_f32_e32 v146, v8
	v_exp_f32_e32 v147, v9
	v_cvt_pk_bf16_f32 v6, v2, v121
	v_cvt_pk_bf16_f32 v7, v122, v123
	v_cvt_pk_bf16_f32 v8, v124, v125
	v_cvt_pk_bf16_f32 v9, v126, v127
	ds_read_b64_tr_b16 v[10:11], v120 offset:36864
	ds_read_b64_tr_b16 v[14:15], v120 offset:36896
	ds_read_b64_tr_b16 v[18:19], v120 offset:36928
	ds_read_b64_tr_b16 v[22:23], v120 offset:36960
	ds_read_b64_tr_b16 v[12:13], v120 offset:39168
	ds_read_b64_tr_b16 v[16:17], v120 offset:39200
	ds_read_b64_tr_b16 v[20:21], v120 offset:39232
	ds_read_b64_tr_b16 v[24:25], v120 offset:39264
	v_fma_f32 v37, v46, s55, -v36
	v_fma_f32 v38, v47, s55, -v36
	v_fma_f32 v39, v48, s55, -v36
	v_fma_f32 v40, v49, s55, -v36
	v_sub_f32_e32 v30, v30, v36
	v_sub_f32_e32 v31, v31, v36
	v_sub_f32_e32 v32, v32, v36
	v_sub_f32_e32 v33, v33, v36
	v_sub_f32_e32 v36, v99, v36
	v_exp_f32_e32 v148, v37
	v_exp_f32_e32 v149, v38
	v_exp_f32_e32 v150, v39
	v_exp_f32_e32 v151, v40
	v_exp_f32_e32 v152, v30
	v_exp_f32_e32 v153, v31
	v_exp_f32_e32 v154, v32
	v_exp_f32_e32 v155, v33
	v_exp_f32_e32 v156, v36
	v_cvt_pk_bf16_f32 v26, v128, v129
	v_cvt_pk_bf16_f32 v27, v130, v131
	v_cvt_pk_bf16_f32 v28, v132, v133
	v_cvt_pk_bf16_f32 v29, v134, v135
	ds_read_b64_tr_b16 v[30:31], v120 offset:41472
	ds_read_b64_tr_b16 v[34:35], v120 offset:41504
	ds_read_b64_tr_b16 v[38:39], v120 offset:41536
	ds_read_b64_tr_b16 v[42:43], v120 offset:41568
	ds_read_b64_tr_b16 v[32:33], v120 offset:43776
	ds_read_b64_tr_b16 v[36:37], v120 offset:43808
	ds_read_b64_tr_b16 v[40:41], v120 offset:43840
	ds_read_b64_tr_b16 v[44:45], v120 offset:43872
	v_cvt_pk_bf16_f32 v46, v136, v137
	v_cvt_pk_bf16_f32 v47, v138, v139
	s_waitcnt lgkmcnt(11)
	v_mfma_f32_16x16x32_bf16 v[10:13], v[10:13], v[6:9], 0
	v_cvt_pk_bf16_f32 v48, v140, v141
	v_cvt_pk_bf16_f32 v49, v142, v143
	ds_read_b64_tr_b16 v[50:51], v120 offset:46080
	ds_read_b64_tr_b16 v[52:53], v120 offset:48384
	ds_read_b64_tr_b16 v[106:107], v120 offset:48416
	ds_read_b64_tr_b16 v[110:111], v120 offset:48448
	s_waitcnt lgkmcnt(13)
	v_mfma_f32_16x16x32_bf16 v[18:21], v[18:21], v[6:9], 0
	ds_read_b64_tr_b16 v[104:105], v120 offset:46112
	ds_read_b64_tr_b16 v[108:109], v120 offset:46144
	ds_read_b64_tr_b16 v[112:113], v120 offset:46176
	ds_read_b64_tr_b16 v[114:115], v120 offset:48480
	v_add_f32_e32 v157, 0, v2
	v_mfma_f32_16x16x32_bf16 v[14:17], v[14:17], v[6:9], 0
	s_waitcnt lgkmcnt(14)
	v_mfma_f32_16x16x32_bf16 v[6:9], v[22:25], v[6:9], 0
	v_cvt_pk_bf16_f32 v22, v144, v145
	v_cvt_pk_bf16_f32 v23, v146, v147
	v_cvt_pk_bf16_f32 v24, v148, v149
	s_waitcnt lgkmcnt(11)
	v_mfma_f32_16x16x32_bf16 v[10:13], v[30:33], v[26:29], v[10:13]
	v_cvt_pk_bf16_f32 v25, v150, v151
	ds_read_b64_tr_b16 v[30:31], v120 offset:50688
	s_waitcnt lgkmcnt(10)
	v_mfma_f32_16x16x32_bf16 v[18:21], v[38:41], v[26:29], v[18:21]
	v_mfma_f32_16x16x32_bf16 v[14:17], v[34:37], v[26:29], v[14:17]
	ds_read_b64_tr_b16 v[32:33], v120 offset:52992
	ds_read_b64_tr_b16 v[36:37], v120 offset:53024
	ds_read_b64_tr_b16 v[118:119], v120 offset:53056
	ds_read_b64_tr_b16 v[34:35], v120 offset:50720
	ds_read_b64_tr_b16 v[116:117], v120 offset:50752
	ds_read_b64_tr_b16 v[38:39], v120 offset:50784
	ds_read_b64_tr_b16 v[40:41], v120 offset:53088
	s_waitcnt lgkmcnt(14)
	v_mfma_f32_16x16x32_bf16 v[6:9], v[42:45], v[26:29], v[6:9]
	v_cvt_pk_bf16_f32 v2, v152, v153
	v_cvt_pk_bf16_f32 v3, v154, v155
	ds_read_b64_tr_b16 v[26:27], v120 offset:55296
	ds_read_b64_tr_b16 v[28:29], v120 offset:57600
	ds_read_b64_tr_b16 v[44:45], v120 offset:57632
	v_mfma_f32_16x16x32_bf16 v[10:13], v[50:53], v[46:49], v[10:13]
	s_waitcnt lgkmcnt(13)
	v_mfma_f32_16x16x32_bf16 v[18:21], v[108:111], v[46:49], v[18:21]
	v_add_f32_e32 v108, v121, v157
	v_mfma_f32_16x16x32_bf16 v[14:17], v[104:107], v[46:49], v[14:17]
	ds_read_b64_tr_b16 v[42:43], v120 offset:55328
	ds_read_b64_tr_b16 v[50:51], v120 offset:55360
	ds_read_b64_tr_b16 v[104:105], v120 offset:55392
	ds_read_b64_tr_b16 v[52:53], v120 offset:57664
	ds_read_b64_tr_b16 v[106:107], v120 offset:57696
	s_waitcnt lgkmcnt(14)
	v_mfma_f32_16x16x32_bf16 v[6:9], v[112:115], v[46:49], v[6:9]
	v_add_f32_e32 v46, v122, v108
	v_add_f32_e32 v46, v123, v46
	v_add_f32_e32 v46, v124, v46
	v_mfma_f32_16x16x32_bf16 v[10:13], v[30:33], v[22:25], v[10:13]
	v_add_f32_e32 v30, v125, v46
	v_add_f32_e32 v30, v126, v30
	v_add_f32_e32 v30, v127, v30
	v_add_f32_e32 v30, v128, v30
	v_add_f32_e32 v30, v129, v30
	v_add_f32_e32 v30, v130, v30
	v_add_f32_e32 v30, v131, v30
	v_add_f32_e32 v30, v132, v30
	v_add_f32_e32 v30, v133, v30
	s_waitcnt lgkmcnt(11)
	v_mfma_f32_16x16x32_bf16 v[14:17], v[34:37], v[22:25], v[14:17]
	s_waitcnt lgkmcnt(10)
	v_mfma_f32_16x16x32_bf16 v[18:21], v[116:119], v[22:25], v[18:21]
	s_waitcnt lgkmcnt(8)
	v_mfma_f32_16x16x32_bf16 v[6:9], v[38:41], v[22:25], v[6:9]
	v_add_f32_e32 v22, v134, v30
	v_add_f32_e32 v22, v135, v22
	v_add_f32_e32 v22, v136, v22
	v_add_f32_e32 v22, v137, v22
	v_add_f32_e32 v22, v138, v22
	v_add_f32_e32 v22, v139, v22
	v_add_f32_e32 v22, v140, v22
	v_add_f32_e32 v22, v141, v22
	v_add_f32_e32 v22, v142, v22
	v_add_f32_e32 v22, v143, v22
	v_add_f32_e32 v22, v144, v22
	v_add_f32_e32 v22, v145, v22
	s_waitcnt lgkmcnt(6)
	v_mfma_f32_16x16x32_bf16 v[10:13], v[26:29], v[2:5], v[10:13]
	s_waitcnt lgkmcnt(4)
	v_mfma_f32_16x16x32_bf16 v[14:17], v[42:45], v[2:5], v[14:17]
	s_waitcnt lgkmcnt(1)
	v_mfma_f32_16x16x32_bf16 v[18:21], v[50:53], v[2:5], v[18:21]
	s_waitcnt lgkmcnt(0)
	v_mfma_f32_16x16x32_bf16 v[6:9], v[104:107], v[2:5], v[6:9]
	v_add_f32_e32 v2, v146, v22
	v_add_f32_e32 v2, v147, v2
	v_add_f32_e32 v2, v148, v2
	v_add_f32_e32 v2, v149, v2
	v_add_f32_e32 v2, v150, v2
	v_add_f32_e32 v2, v151, v2
	v_add_f32_e32 v2, v152, v2
	v_add_f32_e32 v2, v153, v2
	v_add_f32_e32 v2, v154, v2
	v_add_f32_e32 v2, v155, v2
	s_waitcnt lgkmcnt(0)
	v_mov_b32_e32 v3, v2
	s_nop 1
	v_permlane16_swap_b32_e32 v3, v2
	v_add_f32_e32 v2, v2, v3
	s_waitcnt lgkmcnt(0)
	v_mov_b32_e32 v3, v2
	s_nop 1
	v_permlane32_swap_b32_e32 v3, v2
	v_add_f32_e32 v2, v2, v3
	v_add_f32_e32 v2, v156, v2
	v_div_scale_f32 v3, s[50:51], v2, v2, 1.0
	v_rcp_f32_e32 v22, v3
	v_div_scale_f32 v5, vcc, 1.0, v2, 1.0
	v_fma_f32 v23, -v3, v22, 1.0
	v_fmac_f32_e32 v22, v23, v22
	v_mul_f32_e32 v23, v5, v22
	v_fma_f32 v24, -v3, v23, v5
	v_fmac_f32_e32 v23, v24, v22
	v_fma_f32 v3, -v3, v23, v5
	v_div_fmas_f32 v3, v3, v22, v23
	v_div_fixup_f32 v2, v3, v2, 1.0
	v_mul_f32_e32 v3, v2, v10
	v_mul_f32_e32 v5, v2, v11
	v_mul_f32_e32 v10, v2, v12
	v_mul_f32_e32 v11, v2, v13
	v_mul_f32_e32 v12, v2, v14
	v_mul_f32_e32 v13, v2, v15
	v_mul_f32_e32 v14, v2, v16
	v_mul_f32_e32 v15, v2, v17
	v_mul_f32_e32 v16, v2, v18
	v_mul_f32_e32 v17, v2, v19
	v_mul_f32_e32 v18, v2, v20
	v_mul_f32_e32 v19, v2, v21
	v_mul_f32_e32 v6, v2, v6
	v_mul_f32_e32 v7, v2, v7
	v_mul_f32_e32 v8, v2, v8
	v_mul_f32_e32 v9, v2, v9
	v_cvt_pk_bf16_f32 v2, v3, v5
	v_cvt_pk_bf16_f32 v3, v10, v11
	global_store_dwordx2 v[86:87], v[2:3], off offset:-64
	v_cvt_pk_bf16_f32 v2, v12, v13
	v_cvt_pk_bf16_f32 v3, v14, v15
	global_store_dwordx2 v[86:87], v[2:3], off offset:-32
	v_cvt_pk_bf16_f32 v2, v16, v17
	v_cvt_pk_bf16_f32 v3, v18, v19
	global_store_dwordx2 v[86:87], v[2:3], off
	v_cvt_pk_bf16_f32 v2, v6, v7
	v_cvt_pk_bf16_f32 v3, v8, v9
	global_store_dwordx2 v[86:87], v[2:3], off offset:32
	v_lshl_add_u64 v[86:87], v[86:87], 0, s[36:37]
	s_cbranch_scc1 .LBB0_1406
	s_barrier
	s_branch .LBB0_1401

.Lattq_entry_B:
	v_mov_b64_e32 v[10:11], v[180:181]
	v_mov_b64_e32 v[12:13], v[182:183]
	v_mov_b64_e32 v[6:7], v[184:185]
	v_mov_b64_e32 v[8:9], v[186:187]
	global_load_dwordx4 v[180:183], v[50:51], off offset:-64
	global_load_dwordx4 v[184:187], v[50:51], off
	v_add_u32_e32 v2, s28, v91
	ds_read_b128 v[14:17], v2
	ds_read_b128 v[18:21], v2 offset:64
	ds_read_b128 v[22:25], v2 offset:2304
	ds_read_b128 v[26:29], v2 offset:2368
	ds_read_b128 v[30:33], v2 offset:4608
	ds_read_b128 v[104:107], v2 offset:4672
	s_add_i32 s39, s38, 1
	s_cmp_gt_u32 s38, 6
	s_mov_b32 s38, s39
	s_cselect_b64 vcc, -1, 0
	s_sub_i32 s39, s48, 32
	s_cmp_lt_u32 s39, 0xffffff80
	v_add_u32_e32 v87, s28, v89
	v_mov_b32_e32 v5, v4
	v_lshl_add_u64 v[50:51], v[50:51], 0, s[34:35]
	s_waitcnt lgkmcnt(1)
	v_mfma_f32_16x16x32_bf16 v[108:111], v[30:33], v[10:13], 0
	ds_read_b128 v[30:33], v2 offset:6912
	ds_read_b128 v[112:115], v2 offset:6976
	s_waitcnt lgkmcnt(1)
	v_mfma_f32_16x16x32_bf16 v[116:119], v[30:33], v[10:13], 0
	ds_read_b128 v[30:33], v2 offset:9216
	ds_read_b128 v[120:123], v2 offset:9280
	s_waitcnt lgkmcnt(1)
	v_mfma_f32_16x16x32_bf16 v[124:127], v[30:33], v[10:13], 0
	ds_read_b128 v[30:33], v2 offset:11520
	ds_read_b128 v[128:131], v2 offset:11584
	s_waitcnt lgkmcnt(1)
	v_mfma_f32_16x16x32_bf16 v[132:135], v[30:33], v[10:13], 0
	ds_read_b128 v[30:33], v2 offset:13824
	ds_read_b128 v[42:45], v2 offset:13888
	v_mfma_f32_16x16x32_bf16 v[14:17], v[14:17], v[10:13], 0
	s_waitcnt lgkmcnt(1)
	v_mfma_f32_16x16x32_bf16 v[46:49], v[30:33], v[10:13], 0
	ds_read_b128 v[30:33], v2 offset:16128
	ds_read_b128 v[34:37], v2 offset:16192
	v_mfma_f32_16x16x32_bf16 v[22:25], v[22:25], v[10:13], 0
	s_waitcnt lgkmcnt(1)
	v_mfma_f32_16x16x32_bf16 v[38:41], v[30:33], v[10:13], 0
	v_mfma_f32_16x16x32_bf16 v[30:33], v[18:21], v[6:9], v[14:17]
	v_mfma_f32_16x16x32_bf16 v[26:29], v[26:29], v[6:9], v[22:25]
	v_mfma_f32_16x16x32_bf16 v[22:25], v[104:107], v[6:9], v[108:111]
	s_nop 5
	v_mul_f32_e32 v2, 0x3e38aa3b, v30
	v_mul_f32_e32 v3, 0x3e38aa3b, v31
	v_mul_f32_e32 v30, 0x3e38aa3b, v32
	v_mul_f32_e32 v31, 0x3e38aa3b, v33
	v_cndmask_b32_e32 v2, v97, v2, vcc
	v_cndmask_b32_e32 v3, v97, v3, vcc
	v_cndmask_b32_e32 v30, v97, v30, vcc
	v_cndmask_b32_e32 v31, v97, v31, vcc
	s_cselect_b64 vcc, -1, 0
	s_sub_i32 s39, s48, 31
	v_mul_f32_e32 v26, 0x3e38aa3b, v26
	s_cmp_lt_u32 s39, 0xffffff80
	v_cndmask_b32_e32 v26, v97, v26, vcc
	s_cselect_b64 vcc, -1, 0
	s_sub_i32 s39, s48, 30
	v_mul_f32_e32 v27, 0x3e38aa3b, v27
	s_cmp_lt_u32 s39, 0xffffff80
	v_cndmask_b32_e32 v27, v97, v27, vcc
	s_cselect_b64 vcc, -1, 0
	s_sub_i32 s39, s48, 29
	v_mul_f32_e32 v28, 0x3e38aa3b, v28
	s_cmp_lt_u32 s39, 0xffffff80
	v_cndmask_b32_e32 v28, v97, v28, vcc
	s_cselect_b64 vcc, -1, 0
	s_add_i32 s39, s48, -16
	v_mul_f32_e32 v29, 0x3e38aa3b, v29
	s_cmp_lt_u32 s39, 0xffffff80
	v_cndmask_b32_e32 v29, v97, v29, vcc
	s_cselect_b64 vcc, -1, 0
	s_add_i32 s39, s48, -15
	v_mul_f32_e32 v22, 0x3e38aa3b, v22
	s_cmp_lt_u32 s39, 0xffffff80
	v_cndmask_b32_e32 v22, v97, v22, vcc
	s_cselect_b64 vcc, -1, 0
	s_add_i32 s39, s48, -14
	v_mul_f32_e32 v23, 0x3e38aa3b, v23
	s_cmp_lt_u32 s39, 0xffffff80
	v_mfma_f32_16x16x32_bf16 v[18:21], v[112:115], v[6:9], v[116:119]
	v_cndmask_b32_e32 v23, v97, v23, vcc
	s_cselect_b64 vcc, -1, 0
	s_add_i32 s39, s48, -13
	v_mul_f32_e32 v24, 0x3e38aa3b, v24
	s_cmp_lt_u32 s39, 0xffffff80
	v_mul_f32_e32 v25, 0x3e38aa3b, v25
	v_cndmask_b32_e32 v24, v97, v24, vcc
	s_cselect_b64 vcc, -1, 0
	s_cmp_lt_u32 s48, 0xffffff80
	v_cndmask_b32_e32 v25, v97, v25, vcc
	s_cselect_b64 vcc, -1, 0
	s_add_i32 s39, s48, 1
	v_mul_f32_e32 v18, 0x3e38aa3b, v18
	s_cmp_lt_u32 s39, 0xffffff80
	v_cndmask_b32_e32 v18, v97, v18, vcc
	s_cselect_b64 vcc, -1, 0
	s_add_i32 s39, s48, 2
	v_mul_f32_e32 v19, 0x3e38aa3b, v19
	s_cmp_lt_u32 s39, 0xffffff80
	v_cndmask_b32_e32 v19, v97, v19, vcc
	s_cselect_b64 vcc, -1, 0
	s_add_i32 s39, s48, 3
	v_mfma_f32_16x16x32_bf16 v[14:17], v[120:123], v[6:9], v[124:127]
	v_mul_f32_e32 v20, 0x3e38aa3b, v20
	s_cmp_lt_u32 s39, 0xffffff80
	v_cndmask_b32_e32 v20, v97, v20, vcc
	s_cselect_b64 vcc, -1, 0
	s_add_i32 s39, s48, 16
	v_mul_f32_e32 v21, 0x3e38aa3b, v21
	s_cmp_lt_u32 s39, 0xffffff80
	v_cndmask_b32_e32 v21, v97, v21, vcc
	s_cselect_b64 vcc, -1, 0
	s_add_i32 s46, s48, 17
	v_mul_f32_e32 v14, 0x3e38aa3b, v14
	s_cmp_lt_u32 s46, 0xffffff80
	v_cndmask_b32_e32 v14, v97, v14, vcc
	s_cselect_b64 vcc, -1, 0
	s_add_i32 s46, s48, 18
	v_mul_f32_e32 v15, 0x3e38aa3b, v15
	s_cmp_lt_u32 s46, 0xffffff80
	v_cndmask_b32_e32 v15, v97, v15, vcc
	s_cselect_b64 vcc, -1, 0
	s_add_i32 s46, s48, 19
	v_mfma_f32_16x16x32_bf16 v[10:13], v[128:131], v[6:9], v[132:135]
	v_mul_f32_e32 v16, 0x3e38aa3b, v16
	s_cmp_lt_u32 s46, 0xffffff80
	v_cndmask_b32_e32 v16, v97, v16, vcc
	s_cselect_b64 vcc, -1, 0
	s_add_i32 s46, s48, 32
	v_mul_f32_e32 v17, 0x3e38aa3b, v17
	s_cmp_lt_u32 s46, 0xffffff80
	v_cndmask_b32_e32 v17, v97, v17, vcc
	s_cselect_b64 vcc, -1, 0
	s_add_i32 s46, s48, 33
	v_mul_f32_e32 v10, 0x3e38aa3b, v10
	s_cmp_lt_u32 s46, 0xffffff80
	v_cndmask_b32_e32 v10, v97, v10, vcc
	s_cselect_b64 vcc, -1, 0
	s_add_i32 s46, s48, 34
	v_mfma_f32_16x16x32_bf16 v[42:45], v[42:45], v[6:9], v[46:49]
	v_mul_f32_e32 v11, 0x3e38aa3b, v11
	s_cmp_lt_u32 s46, 0xffffff80
	v_cndmask_b32_e32 v11, v97, v11, vcc
	s_waitcnt lgkmcnt(0)
	v_mfma_f32_16x16x32_bf16 v[6:9], v[34:37], v[6:9], v[38:41]
	v_max3_f32 v36, v86, v2, v3
	v_max3_f32 v36, v36, v30, v31
	s_cselect_b64 vcc, -1, 0
	s_add_i32 s46, s48, 35
	v_mul_f32_e32 v12, 0x3e38aa3b, v12
	v_max3_f32 v36, v36, v26, v27
	s_cmp_lt_u32 s46, 0xffffff80
	v_max3_f32 v36, v36, v28, v29
	v_cndmask_b32_e32 v12, v97, v12, vcc
	s_cselect_b64 vcc, -1, 0
	s_add_i32 s46, s48, 48
	v_mul_f32_e32 v13, 0x3e38aa3b, v13
	v_max3_f32 v36, v36, v22, v23
	s_cmp_lt_u32 s46, 0xffffff80
	v_max3_f32 v36, v36, v24, v25
	v_cndmask_b32_e32 v13, v97, v13, vcc
	s_cselect_b64 vcc, -1, 0
	s_add_i32 s46, s48, 49
	v_mul_f32_e32 v32, 0x3e38aa3b, v42
	v_max3_f32 v36, v36, v18, v19
	s_cmp_lt_u32 s46, 0xffffff80
	v_max3_f32 v36, v36, v20, v21
	v_cndmask_b32_e32 v32, v97, v32, vcc
	s_cselect_b64 vcc, -1, 0
	s_add_i32 s46, s48, 50
	v_mul_f32_e32 v33, 0x3e38aa3b, v43
	v_max3_f32 v36, v36, v14, v15
	s_cmp_lt_u32 s46, 0xffffff80
	v_max3_f32 v36, v36, v16, v17
	v_cndmask_b32_e32 v33, v97, v33, vcc
	s_cselect_b64 vcc, -1, 0
	s_add_i32 s46, s48, 51
	v_mul_f32_e32 v34, 0x3e38aa3b, v44
	v_max3_f32 v36, v36, v10, v11
	s_cmp_lt_u32 s46, 0xffffff80
	v_mul_f32_e32 v35, 0x3e38aa3b, v45
	v_max3_f32 v36, v36, v12, v13
	v_cndmask_b32_e32 v34, v97, v34, vcc
	s_cselect_b64 vcc, -1, 0
	v_mul_f32_e32 v6, 0x3e38aa3b, v6
	v_mul_f32_e32 v7, 0x3e38aa3b, v7
	v_max3_f32 v36, v36, v32, v33
	v_cndmask_b32_e32 v35, v97, v35, vcc
	v_mul_f32_e32 v8, 0x3e38aa3b, v8
	v_mul_f32_e32 v9, 0x3e38aa3b, v9
	v_cndmask_b32_e64 v6, v97, v6, s[10:11]
	v_cndmask_b32_e64 v7, v97, v7, s[12:13]
	v_max3_f32 v36, v36, v34, v35
	v_cndmask_b32_e64 v8, v97, v8, s[14:15]
	v_cndmask_b32_e64 v9, v97, v9, s[16:17]
	v_max3_f32 v36, v36, v6, v7
	v_max3_f32 v36, v36, v8, v9
	s_addk_i32 s28, 0x900
	s_mov_b32 s48, s39
	s_cmpk_lg_i32 s28, 0x4800
	s_waitcnt lgkmcnt(0)
	v_mov_b32_e32 v37, v36
	s_nop 1
	v_permlane16_swap_b32_e32 v37, v36
	v_max_f32_e32 v36, v36, v37
	s_waitcnt lgkmcnt(0)
	v_mov_b32_e32 v37, v36
	s_nop 1
	v_permlane32_swap_b32_e32 v37, v36
	v_max_f32_e32 v36, v36, v37
	v_sub_f32_e32 v37, 0xff800000, v36
	v_sub_f32_e32 v2, v2, v36
	v_sub_f32_e32 v3, v3, v36
	v_sub_f32_e32 v30, v30, v36
	v_sub_f32_e32 v31, v31, v36
	v_sub_f32_e32 v22, v22, v36
	v_sub_f32_e32 v23, v23, v36
	v_sub_f32_e32 v24, v24, v36
	v_sub_f32_e32 v25, v25, v36
	v_sub_f32_e32 v18, v18, v36
	v_sub_f32_e32 v19, v19, v36
	v_sub_f32_e32 v20, v20, v36
	v_sub_f32_e32 v21, v21, v36
	v_sub_f32_e32 v14, v14, v36
	v_sub_f32_e32 v15, v15, v36
	v_sub_f32_e32 v16, v16, v36
	v_sub_f32_e32 v17, v17, v36
	v_sub_f32_e32 v10, v10, v36
	v_sub_f32_e32 v11, v11, v36
	v_sub_f32_e32 v12, v12, v36
	v_sub_f32_e32 v13, v13, v36
	v_sub_f32_e32 v6, v6, v36
	v_sub_f32_e32 v7, v7, v36
	v_sub_f32_e32 v8, v8, v36
	v_sub_f32_e32 v9, v9, v36
	v_exp_f32_e32 v98, v37
	v_exp_f32_e32 v99, v2
	v_exp_f32_e32 v124, v3
	v_exp_f32_e32 v125, v30
	v_exp_f32_e32 v126, v31
	v_exp_f32_e32 v131, v22
	v_exp_f32_e32 v132, v23
	v_exp_f32_e32 v133, v24
	v_exp_f32_e32 v134, v25
	v_exp_f32_e32 v135, v18
	v_exp_f32_e32 v136, v19
	v_exp_f32_e32 v137, v20
	v_exp_f32_e32 v138, v21
	v_exp_f32_e32 v139, v14
	v_exp_f32_e32 v140, v15
	v_exp_f32_e32 v141, v16
	v_exp_f32_e32 v142, v17
	v_exp_f32_e32 v143, v10
	v_exp_f32_e32 v144, v11
	v_exp_f32_e32 v145, v12
	v_exp_f32_e32 v146, v13
	v_exp_f32_e32 v151, v6
	v_exp_f32_e32 v152, v7
	v_exp_f32_e32 v153, v8
	v_exp_f32_e32 v154, v9
	v_cvt_pk_bf16_f32 v6, v98, v98
	v_cvt_pk_bf16_f32 v7, v98, v98
	v_cvt_pk_bf16_f32 v8, v99, v124
	v_cvt_pk_bf16_f32 v9, v125, v126
	ds_read_b64_tr_b16 v[10:11], v87 offset:36864
	ds_read_b64_tr_b16 v[14:15], v87 offset:36896
	ds_read_b64_tr_b16 v[18:19], v87 offset:36928
	ds_read_b64_tr_b16 v[22:23], v87 offset:36960
	ds_read_b64_tr_b16 v[12:13], v87 offset:39168
	ds_read_b64_tr_b16 v[16:17], v87 offset:39200
	ds_read_b64_tr_b16 v[20:21], v87 offset:39232
	ds_read_b64_tr_b16 v[24:25], v87 offset:39264
	v_sub_f32_e32 v26, v26, v36
	v_sub_f32_e32 v27, v27, v36
	v_sub_f32_e32 v28, v28, v36
	v_sub_f32_e32 v29, v29, v36
	v_sub_f32_e32 v32, v32, v36
	v_sub_f32_e32 v33, v33, v36
	v_sub_f32_e32 v34, v34, v36
	v_sub_f32_e32 v35, v35, v36
	v_sub_f32_e32 v36, v85, v36
	v_exp_f32_e32 v127, v26
	v_exp_f32_e32 v128, v27
	v_exp_f32_e32 v129, v28
	v_exp_f32_e32 v130, v29
	v_exp_f32_e32 v147, v32
	v_exp_f32_e32 v148, v33
	v_exp_f32_e32 v149, v34
	v_exp_f32_e32 v150, v35
	v_exp_f32_e32 v155, v36
	v_cvt_pk_bf16_f32 v26, v127, v128
	v_cvt_pk_bf16_f32 v27, v129, v130
	v_cvt_pk_bf16_f32 v28, v131, v132
	v_cvt_pk_bf16_f32 v29, v133, v134
	ds_read_b64_tr_b16 v[30:31], v87 offset:41472
	ds_read_b64_tr_b16 v[34:35], v87 offset:41504
	ds_read_b64_tr_b16 v[38:39], v87 offset:41536
	ds_read_b64_tr_b16 v[42:43], v87 offset:41568
	ds_read_b64_tr_b16 v[32:33], v87 offset:43776
	ds_read_b64_tr_b16 v[36:37], v87 offset:43808
	ds_read_b64_tr_b16 v[40:41], v87 offset:43840
	ds_read_b64_tr_b16 v[44:45], v87 offset:43872
	v_cvt_pk_bf16_f32 v46, v135, v136
	v_cvt_pk_bf16_f32 v47, v137, v138
	s_waitcnt lgkmcnt(0)
	v_mfma_f32_16x16x32_bf16 v[10:13], v[10:13], v[6:9], 0
	v_cvt_pk_bf16_f32 v48, v139, v140
	v_cvt_pk_bf16_f32 v49, v141, v142
	ds_read_b64_tr_b16 v[104:105], v87 offset:46080
	s_waitcnt lgkmcnt(11)
	v_mfma_f32_16x16x32_bf16 v[14:17], v[14:17], v[6:9], 0
	ds_read_b64_tr_b16 v[106:107], v87 offset:48384
	ds_read_b64_tr_b16 v[110:111], v87 offset:48416
	ds_read_b64_tr_b16 v[114:115], v87 offset:48448
	ds_read_b64_tr_b16 v[108:109], v87 offset:46112
	ds_read_b64_tr_b16 v[112:113], v87 offset:46144
	ds_read_b64_tr_b16 v[116:117], v87 offset:46176
	ds_read_b64_tr_b16 v[118:119], v87 offset:48480
	s_waitcnt lgkmcnt(14)
	v_mfma_f32_16x16x32_bf16 v[18:21], v[18:21], v[6:9], 0
	v_add_f32_e32 v156, 0, v98
	v_mfma_f32_16x16x32_bf16 v[6:9], v[22:25], v[6:9], 0
	v_cvt_pk_bf16_f32 v22, v143, v144
	v_cvt_pk_bf16_f32 v23, v145, v146
	v_cvt_pk_bf16_f32 v24, v147, v148
	s_waitcnt lgkmcnt(11)
	v_mfma_f32_16x16x32_bf16 v[10:13], v[30:33], v[26:29], v[10:13]
	v_cvt_pk_bf16_f32 v25, v149, v150
	ds_read_b64_tr_b16 v[30:31], v87 offset:50688
	s_waitcnt lgkmcnt(11)
	v_mfma_f32_16x16x32_bf16 v[14:17], v[34:37], v[26:29], v[14:17]
	ds_read_b64_tr_b16 v[32:33], v87 offset:52992
	ds_read_b64_tr_b16 v[36:37], v87 offset:53024
	ds_read_b64_tr_b16 v[122:123], v87 offset:53056
	s_waitcnt lgkmcnt(13)
	v_mfma_f32_16x16x32_bf16 v[18:21], v[38:41], v[26:29], v[18:21]
	ds_read_b64_tr_b16 v[34:35], v87 offset:50720
	ds_read_b64_tr_b16 v[120:121], v87 offset:50752
	ds_read_b64_tr_b16 v[38:39], v87 offset:50784
	ds_read_b64_tr_b16 v[40:41], v87 offset:53088
	v_cvt_pk_bf16_f32 v2, v151, v152
	s_waitcnt lgkmcnt(14)
	v_mfma_f32_16x16x32_bf16 v[6:9], v[42:45], v[26:29], v[6:9]
	v_cvt_pk_bf16_f32 v3, v153, v154
	ds_read_b64_tr_b16 v[26:27], v87 offset:55296
	ds_read_b64_tr_b16 v[28:29], v87 offset:57600
	ds_read_b64_tr_b16 v[44:45], v87 offset:57632
	v_mfma_f32_16x16x32_bf16 v[10:13], v[104:107], v[46:49], v[10:13]
	s_waitcnt lgkmcnt(14)
	v_mfma_f32_16x16x32_bf16 v[14:17], v[108:111], v[46:49], v[14:17]
	ds_read_b64_tr_b16 v[42:43], v87 offset:55328
	ds_read_b64_tr_b16 v[104:105], v87 offset:55360
	ds_read_b64_tr_b16 v[108:109], v87 offset:55392
	ds_read_b64_tr_b16 v[106:107], v87 offset:57664
	ds_read_b64_tr_b16 v[110:111], v87 offset:57696
	v_add_f32_e32 v87, v98, v156
	s_waitcnt lgkmcnt(14)
	v_mfma_f32_16x16x32_bf16 v[18:21], v[112:115], v[46:49], v[18:21]
	v_mfma_f32_16x16x32_bf16 v[6:9], v[116:119], v[46:49], v[6:9]
	v_add_f32_e32 v46, v98, v87
	v_add_f32_e32 v46, v98, v46
	v_add_f32_e32 v46, v99, v46
	v_mfma_f32_16x16x32_bf16 v[10:13], v[30:33], v[22:25], v[10:13]
	v_add_f32_e32 v30, v124, v46
	v_add_f32_e32 v30, v125, v30
	v_add_f32_e32 v30, v126, v30
	v_add_f32_e32 v30, v127, v30
	v_add_f32_e32 v30, v128, v30
	v_add_f32_e32 v30, v129, v30
	v_add_f32_e32 v30, v130, v30
	v_add_f32_e32 v30, v131, v30
	v_add_f32_e32 v30, v132, v30
	s_waitcnt lgkmcnt(11)
	v_mfma_f32_16x16x32_bf16 v[14:17], v[34:37], v[22:25], v[14:17]
	s_waitcnt lgkmcnt(10)
	v_mfma_f32_16x16x32_bf16 v[18:21], v[120:123], v[22:25], v[18:21]
	s_waitcnt lgkmcnt(8)
	v_mfma_f32_16x16x32_bf16 v[6:9], v[38:41], v[22:25], v[6:9]
	v_add_f32_e32 v22, v133, v30
	v_add_f32_e32 v22, v134, v22
	v_add_f32_e32 v22, v135, v22
	v_add_f32_e32 v22, v136, v22
	v_add_f32_e32 v22, v137, v22
	v_add_f32_e32 v22, v138, v22
	v_add_f32_e32 v22, v139, v22
	v_add_f32_e32 v22, v140, v22
	v_add_f32_e32 v22, v141, v22
	v_add_f32_e32 v22, v142, v22
	v_add_f32_e32 v22, v143, v22
	v_add_f32_e32 v22, v144, v22
	s_waitcnt lgkmcnt(6)
	v_mfma_f32_16x16x32_bf16 v[10:13], v[26:29], v[2:5], v[10:13]
	s_waitcnt lgkmcnt(4)
	v_mfma_f32_16x16x32_bf16 v[14:17], v[42:45], v[2:5], v[14:17]
	s_waitcnt lgkmcnt(1)
	v_mfma_f32_16x16x32_bf16 v[18:21], v[104:107], v[2:5], v[18:21]
	s_waitcnt lgkmcnt(0)
	v_mfma_f32_16x16x32_bf16 v[6:9], v[108:111], v[2:5], v[6:9]
	v_add_f32_e32 v2, v145, v22
	v_add_f32_e32 v2, v146, v2
	v_add_f32_e32 v2, v147, v2
	v_add_f32_e32 v2, v148, v2
	v_add_f32_e32 v2, v149, v2
	v_add_f32_e32 v2, v150, v2
	v_add_f32_e32 v2, v151, v2
	v_add_f32_e32 v2, v152, v2
	v_add_f32_e32 v2, v153, v2
	v_add_f32_e32 v2, v154, v2
	s_waitcnt lgkmcnt(0)
	v_mov_b32_e32 v3, v2
	s_nop 1
	v_permlane16_swap_b32_e32 v3, v2
	v_add_f32_e32 v2, v2, v3
	s_waitcnt lgkmcnt(0)
	v_mov_b32_e32 v3, v2
	s_nop 1
	v_permlane32_swap_b32_e32 v3, v2
	v_add_f32_e32 v2, v2, v3
	v_add_f32_e32 v2, v155, v2
	v_div_scale_f32 v3, s[46:47], v2, v2, 1.0
	v_rcp_f32_e32 v22, v3
	v_div_scale_f32 v5, vcc, 1.0, v2, 1.0
	v_fma_f32 v23, -v3, v22, 1.0
	v_fmac_f32_e32 v22, v23, v22
	v_mul_f32_e32 v23, v5, v22
	v_fma_f32 v24, -v3, v23, v5
	v_fmac_f32_e32 v23, v24, v22
	v_fma_f32 v3, -v3, v23, v5
	v_div_fmas_f32 v3, v3, v22, v23
	v_div_fixup_f32 v2, v3, v2, 1.0
	v_mul_f32_e32 v3, v2, v10
	v_mul_f32_e32 v5, v2, v11
	v_mul_f32_e32 v10, v2, v12
	v_mul_f32_e32 v11, v2, v13
	v_mul_f32_e32 v12, v2, v14
	v_mul_f32_e32 v13, v2, v15
	v_mul_f32_e32 v14, v2, v16
	v_mul_f32_e32 v15, v2, v17
	v_mul_f32_e32 v16, v2, v18
	v_mul_f32_e32 v17, v2, v19
	v_mul_f32_e32 v18, v2, v20
	v_mul_f32_e32 v19, v2, v21
	v_mul_f32_e32 v6, v2, v6
	v_mul_f32_e32 v7, v2, v7
	v_mul_f32_e32 v8, v2, v8
	v_mul_f32_e32 v9, v2, v9
	v_cvt_pk_bf16_f32 v2, v3, v5
	v_cvt_pk_bf16_f32 v3, v10, v11
	global_store_dwordx2 v[52:53], v[2:3], off offset:-64
	v_cvt_pk_bf16_f32 v2, v12, v13
	v_cvt_pk_bf16_f32 v3, v14, v15
	global_store_dwordx2 v[52:53], v[2:3], off offset:-32
	v_cvt_pk_bf16_f32 v2, v16, v17
	v_cvt_pk_bf16_f32 v3, v18, v19
	global_store_dwordx2 v[52:53], v[2:3], off
	v_cvt_pk_bf16_f32 v2, v6, v7
	v_cvt_pk_bf16_f32 v3, v8, v9
	global_store_dwordx2 v[52:53], v[2:3], off offset:32
	v_lshl_add_u64 v[52:53], v[52:53], 0, s[36:37]
	s_cbranch_scc1 .LBB0_1420
	s_barrier
	s_branch .LBB0_1401

.LBB0_1609:
	v_lshl_add_u64 v[2:3], s[8:9], 0, v[150:151]
	s_lshl_b64 s[4:5], s[38:39], 13
	v_add_co_u32_e32 v4, vcc, s41, v2
	s_add_u32 s46, s7, s4
	s_mov_b64 s[2:3], vcc
	v_add_co_u32_e32 v14, vcc, s67, v2
	s_addc_u32 s47, s58, s5
	v_lshlrev_b32_e32 v172, 1, v130
	v_addc_co_u32_e32 v15, vcc, 0, v3, vcc
	global_load_dwordx4 v[106:109], v172, s[46:47]
	global_load_dwordx4 v[98:101], v172, s[46:47] offset:16
	global_load_dwordx4 v[114:117], v[14:15], off offset:-4096
	s_mov_b64 s[48:49], 0x3b100000
	v_lshl_add_u64 v[6:7], v[2:3], 0, s[48:49]
	global_load_dwordx4 v[94:97], v[6:7], off offset:16
	v_add_co_u32_e32 v156, vcc, s68, v2
	v_lshl_add_u64 v[6:7], v[2:3], 0, s[24:25]
	s_nop 0
	v_addc_co_u32_e32 v157, vcc, 0, v3, vcc
	v_add_co_u32_e32 v154, vcc, s69, v2
	v_lshl_add_u64 v[8:9], v[2:3], 0, s[26:27]
	v_lshl_add_u64 v[10:11], v[2:3], 0, s[28:29]
	v_addc_co_u32_e32 v155, vcc, 0, v3, vcc
	v_lshl_add_u64 v[12:13], v[2:3], 0, s[30:31]
	v_addc_co_u32_e64 v5, vcc, 0, v3, s[2:3]
	global_load_dwordx4 v[74:77], v[6:7], off offset:16
	global_load_dwordx4 v[34:37], v[8:9], off offset:16
	global_load_dwordx4 v[86:89], v[156:157], off offset:2048
	global_load_dwordx4 v[70:73], v[12:13], off offset:16
	global_load_dwordx4 v[46:49], v[154:155], off
	global_load_dwordx4 v[18:21], v[154:155], off offset:2048
	global_load_dwordx4 v[90:93], v[4:5], off offset:2048
	global_load_dwordx4 v[58:61], v172, s[46:47] offset:2064
	global_load_dwordx4 v[78:81], v172, s[46:47] offset:2048
	global_load_dwordx4 v[26:29], v164, s[46:47] offset:16
	global_load_dwordx4 v[38:41], v164, s[46:47]
	global_load_dwordx4 v[6:9], v[10:11], off offset:16
	s_nop 0
	global_load_dwordx4 v[10:13], v165, s[46:47]
	s_add_u32 s4, s59, s4
	v_lshl_add_u64 v[54:55], v[2:3], 0, s[12:13]
	v_lshl_add_u64 v[56:57], v[2:3], 0, s[34:35]
	v_lshl_add_u64 v[66:67], v[2:3], 0, s[36:37]
	s_addc_u32 s5, s60, s5
	global_load_dwordx4 v[50:53], v[14:15], off
	global_load_dwordx4 v[22:25], v[14:15], off offset:2048
	global_load_dwordx4 v[122:125], v[154:155], off offset:-4096
	global_load_dwordx4 v[102:105], v172, s[4:5] offset:16
	global_load_dwordx4 v[118:121], v172, s[4:5]
	global_load_dwordx4 v[62:65], v172, s[4:5] offset:2064
	global_load_dwordx4 v[82:85], v172, s[4:5] offset:2048
	global_load_dwordx4 v[30:33], v164, s[4:5] offset:16
	global_load_dwordx4 v[42:45], v164, s[4:5]
	global_load_dwordx4 v[2:5], v165, s[46:47] offset:16
	global_load_dwordx4 v[14:17], v165, s[4:5]
	s_waitcnt vmcnt(27)
	v_and_b32_e32 v69, 0xffff0000, v106
	v_mul_f32_e32 v179, v69, v69
	s_waitcnt vmcnt(25)
	v_and_b32_e32 v129, 0xffff0000, v114
	v_lshlrev_b32_e32 v128, 16, v114
	v_mul_f32_e32 v69, v129, v129
	v_lshlrev_b32_e32 v173, 16, v115
	v_fmac_f32_e32 v69, v128, v128
	v_and_b32_e32 v174, 0xffff0000, v115
	v_fmac_f32_e32 v69, v173, v173
	v_lshlrev_b32_e32 v175, 16, v116
	v_fmac_f32_e32 v69, v174, v174
	v_and_b32_e32 v176, 0xffff0000, v116
	v_fmac_f32_e32 v69, v175, v175
	v_lshlrev_b32_e32 v177, 16, v117
	v_fmac_f32_e32 v69, v176, v176
	v_lshlrev_b32_e32 v68, 16, v106
	v_and_b32_e32 v178, 0xffff0000, v117
	v_fmac_f32_e32 v69, v177, v177
	v_lshlrev_b32_e32 v110, 16, v107
	v_fmac_f32_e32 v179, v68, v68
	v_fmac_f32_e32 v69, v178, v178
	s_waitcnt vmcnt(24)
	v_lshlrev_b32_e32 v68, 16, v94
	v_and_b32_e32 v111, 0xffff0000, v107
	v_fmac_f32_e32 v179, v110, v110
	v_and_b32_e32 v110, 0xffff0000, v94
	v_fmac_f32_e32 v69, v68, v68
	v_lshlrev_b32_e32 v112, 16, v108
	v_fmac_f32_e32 v179, v111, v111
	v_lshlrev_b32_e32 v111, 16, v95
	v_fmac_f32_e32 v69, v110, v110
	v_and_b32_e32 v113, 0xffff0000, v108
	v_fmac_f32_e32 v179, v112, v112
	v_and_b32_e32 v112, 0xffff0000, v95
	v_fmac_f32_e32 v69, v111, v111
	v_lshlrev_b32_e32 v126, 16, v109
	v_fmac_f32_e32 v179, v113, v113
	v_lshlrev_b32_e32 v113, 16, v96
	v_fmac_f32_e32 v69, v112, v112
	v_and_b32_e32 v127, 0xffff0000, v109
	v_fmac_f32_e32 v179, v126, v126
	v_and_b32_e32 v126, 0xffff0000, v96
	v_fmac_f32_e32 v69, v113, v113
	v_fmac_f32_e32 v179, v127, v127
	v_lshlrev_b32_e32 v127, 16, v97
	v_fmac_f32_e32 v69, v126, v126
	v_and_b32_e32 v128, 0xffff0000, v97
	v_fmac_f32_e32 v69, v127, v127
	v_fmac_f32_e32 v69, v128, v128
	s_waitcnt vmcnt(17)
	v_lshlrev_b32_e32 v68, 16, v90
	v_and_b32_e32 v110, 0xffff0000, v90
	v_fmac_f32_e32 v69, v68, v68
	v_lshlrev_b32_e32 v111, 16, v91
	v_fmac_f32_e32 v69, v110, v110
	v_and_b32_e32 v112, 0xffff0000, v91
	v_fmac_f32_e32 v69, v111, v111
	v_lshlrev_b32_e32 v113, 16, v92
	v_fmac_f32_e32 v69, v112, v112
	v_and_b32_e32 v126, 0xffff0000, v92
	v_fmac_f32_e32 v69, v113, v113
	v_lshlrev_b32_e32 v127, 16, v93
	v_fmac_f32_e32 v69, v126, v126
	v_and_b32_e32 v128, 0xffff0000, v93
	v_fmac_f32_e32 v69, v127, v127
	v_fmac_f32_e32 v69, v128, v128
	v_lshlrev_b32_e32 v68, 16, v74
	v_and_b32_e32 v110, 0xffff0000, v74
	v_fmac_f32_e32 v69, v68, v68
	v_lshlrev_b32_e32 v111, 16, v75
	v_fmac_f32_e32 v69, v110, v110
	v_and_b32_e32 v112, 0xffff0000, v75
	v_fmac_f32_e32 v69, v111, v111
	v_lshlrev_b32_e32 v113, 16, v76
	v_fmac_f32_e32 v69, v112, v112
	v_and_b32_e32 v126, 0xffff0000, v76
	v_fmac_f32_e32 v69, v113, v113
	v_lshlrev_b32_e32 v127, 16, v77
	v_fmac_f32_e32 v69, v126, v126
	v_and_b32_e32 v128, 0xffff0000, v77
	v_fmac_f32_e32 v69, v127, v127
	v_lshlrev_b32_e32 v129, 16, v98
	v_fmac_f32_e32 v69, v128, v128
	s_waitcnt vmcnt(10)
	v_lshlrev_b32_e32 v68, 16, v50
	v_and_b32_e32 v173, 0xffff0000, v98
	v_fmac_f32_e32 v179, v129, v129
	v_and_b32_e32 v110, 0xffff0000, v50
	v_fmac_f32_e32 v69, v68, v68
	v_lshlrev_b32_e32 v174, 16, v99
	v_fmac_f32_e32 v179, v173, v173
	v_lshlrev_b32_e32 v111, 16, v51
	v_fmac_f32_e32 v69, v110, v110
	v_and_b32_e32 v175, 0xffff0000, v99
	v_fmac_f32_e32 v179, v174, v174
	v_and_b32_e32 v112, 0xffff0000, v51
	v_fmac_f32_e32 v69, v111, v111
	v_lshlrev_b32_e32 v176, 16, v100
	v_fmac_f32_e32 v179, v175, v175
	v_lshlrev_b32_e32 v113, 16, v52
	v_fmac_f32_e32 v69, v112, v112
	v_and_b32_e32 v177, 0xffff0000, v100
	v_fmac_f32_e32 v179, v176, v176
	v_and_b32_e32 v126, 0xffff0000, v52
	v_fmac_f32_e32 v69, v113, v113
	v_lshlrev_b32_e32 v178, 16, v101
	v_fmac_f32_e32 v179, v177, v177
	v_lshlrev_b32_e32 v127, 16, v53
	v_fmac_f32_e32 v69, v126, v126
	v_and_b32_e32 v180, 0xffff0000, v101
	v_fmac_f32_e32 v179, v178, v178
	v_and_b32_e32 v128, 0xffff0000, v53
	v_fmac_f32_e32 v69, v127, v127
	v_fmac_f32_e32 v179, v180, v180
	v_lshlrev_b32_e32 v129, 16, v78
	v_fmac_f32_e32 v69, v128, v128
	v_lshlrev_b32_e32 v68, 16, v34
	v_and_b32_e32 v173, 0xffff0000, v78
	v_fmac_f32_e32 v179, v129, v129
	v_and_b32_e32 v110, 0xffff0000, v34
	v_fmac_f32_e32 v69, v68, v68
	v_lshlrev_b32_e32 v174, 16, v79
	v_fmac_f32_e32 v179, v173, v173
	v_lshlrev_b32_e32 v111, 16, v35
	v_fmac_f32_e32 v69, v110, v110
	v_and_b32_e32 v175, 0xffff0000, v79
	v_fmac_f32_e32 v179, v174, v174
	v_and_b32_e32 v112, 0xffff0000, v35
	v_fmac_f32_e32 v69, v111, v111
	v_lshlrev_b32_e32 v176, 16, v80
	v_fmac_f32_e32 v179, v175, v175
	v_lshlrev_b32_e32 v113, 16, v36
	v_fmac_f32_e32 v69, v112, v112
	v_and_b32_e32 v177, 0xffff0000, v80
	v_fmac_f32_e32 v179, v176, v176
	v_and_b32_e32 v126, 0xffff0000, v36
	v_fmac_f32_e32 v69, v113, v113
	v_lshlrev_b32_e32 v178, 16, v81
	v_fmac_f32_e32 v179, v177, v177
	v_lshlrev_b32_e32 v127, 16, v37
	v_fmac_f32_e32 v69, v126, v126
	v_and_b32_e32 v180, 0xffff0000, v81
	v_fmac_f32_e32 v179, v178, v178
	v_and_b32_e32 v128, 0xffff0000, v37
	v_fmac_f32_e32 v69, v127, v127
	v_fmac_f32_e32 v179, v180, v180
	v_lshlrev_b32_e32 v129, 16, v58
	v_fmac_f32_e32 v69, v128, v128
	s_waitcnt vmcnt(9)
	v_lshlrev_b32_e32 v68, 16, v22
	v_and_b32_e32 v173, 0xffff0000, v58
	v_fmac_f32_e32 v179, v129, v129
	v_and_b32_e32 v110, 0xffff0000, v22
	v_fmac_f32_e32 v69, v68, v68
	v_lshlrev_b32_e32 v174, 16, v59
	v_fmac_f32_e32 v179, v173, v173
	v_lshlrev_b32_e32 v111, 16, v23
	v_fmac_f32_e32 v69, v110, v110
	v_and_b32_e32 v175, 0xffff0000, v59
	v_fmac_f32_e32 v179, v174, v174
	v_and_b32_e32 v112, 0xffff0000, v23
	v_fmac_f32_e32 v69, v111, v111
	v_lshlrev_b32_e32 v176, 16, v60
	v_fmac_f32_e32 v179, v175, v175
	v_lshlrev_b32_e32 v113, 16, v24
	v_fmac_f32_e32 v69, v112, v112
	v_and_b32_e32 v177, 0xffff0000, v60
	v_fmac_f32_e32 v179, v176, v176
	v_and_b32_e32 v126, 0xffff0000, v24
	v_fmac_f32_e32 v69, v113, v113
	v_lshlrev_b32_e32 v178, 16, v61
	v_fmac_f32_e32 v179, v177, v177
	v_lshlrev_b32_e32 v127, 16, v25
	v_fmac_f32_e32 v69, v126, v126
	v_and_b32_e32 v180, 0xffff0000, v61
	v_fmac_f32_e32 v179, v178, v178
	v_and_b32_e32 v128, 0xffff0000, v25
	v_fmac_f32_e32 v69, v127, v127
	v_fmac_f32_e32 v179, v180, v180
	v_lshlrev_b32_e32 v129, 16, v38
	v_fmac_f32_e32 v69, v128, v128
	v_lshlrev_b32_e32 v68, 16, v6
	v_and_b32_e32 v173, 0xffff0000, v38
	v_fmac_f32_e32 v179, v129, v129
	v_and_b32_e32 v110, 0xffff0000, v6
	v_fmac_f32_e32 v69, v68, v68
	v_lshlrev_b32_e32 v174, 16, v39
	v_fmac_f32_e32 v179, v173, v173
	v_lshlrev_b32_e32 v111, 16, v7
	v_fmac_f32_e32 v69, v110, v110
	v_and_b32_e32 v175, 0xffff0000, v39
	v_fmac_f32_e32 v179, v174, v174
	v_and_b32_e32 v112, 0xffff0000, v7
	v_fmac_f32_e32 v69, v111, v111
	v_lshlrev_b32_e32 v176, 16, v40
	v_fmac_f32_e32 v179, v175, v175
	v_lshlrev_b32_e32 v113, 16, v8
	v_fmac_f32_e32 v69, v112, v112
	v_and_b32_e32 v177, 0xffff0000, v40
	v_fmac_f32_e32 v179, v176, v176
	v_and_b32_e32 v126, 0xffff0000, v8
	v_fmac_f32_e32 v69, v113, v113
	v_lshlrev_b32_e32 v178, 16, v41
	v_fmac_f32_e32 v179, v177, v177
	v_lshlrev_b32_e32 v127, 16, v9
	v_fmac_f32_e32 v69, v126, v126
	v_and_b32_e32 v180, 0xffff0000, v41
	v_fmac_f32_e32 v179, v178, v178
	v_and_b32_e32 v128, 0xffff0000, v9
	v_fmac_f32_e32 v69, v127, v127
	v_fmac_f32_e32 v179, v180, v180
	v_lshlrev_b32_e32 v129, 16, v26
	v_fmac_f32_e32 v69, v128, v128
	v_and_b32_e32 v173, 0xffff0000, v26
	v_fmac_f32_e32 v179, v129, v129
	v_lshlrev_b32_e32 v174, 16, v27
	v_fmac_f32_e32 v179, v173, v173
	v_and_b32_e32 v175, 0xffff0000, v27
	v_fmac_f32_e32 v179, v174, v174
	v_lshlrev_b32_e32 v176, 16, v28
	v_fmac_f32_e32 v179, v175, v175
	v_and_b32_e32 v177, 0xffff0000, v28
	v_fmac_f32_e32 v179, v176, v176
	v_lshlrev_b32_e32 v178, 16, v29
	v_fmac_f32_e32 v179, v177, v177
	s_waitcnt lgkmcnt(0)
	s_nop 1
	v_add_f32_dpp v68, v69, v69 quad_perm:[1,0,3,2] row_mask:0xf bank_mask:0xf
	v_and_b32_e32 v180, 0xffff0000, v29
	v_fmac_f32_e32 v179, v178, v178
	v_fmac_f32_e32 v179, v180, v180
	v_lshlrev_b32_e32 v129, 16, v10
	v_and_b32_e32 v173, 0xffff0000, v10
	v_fmac_f32_e32 v179, v129, v129
	v_lshlrev_b32_e32 v174, 16, v11
	v_fmac_f32_e32 v179, v173, v173
	v_and_b32_e32 v175, 0xffff0000, v11
	v_fmac_f32_e32 v179, v174, v174
	v_lshlrev_b32_e32 v176, 16, v12
	v_fmac_f32_e32 v179, v175, v175
	s_waitcnt lgkmcnt(0)
	s_nop 1
	v_add_f32_dpp v68, v68, v68 quad_perm:[2,3,0,1] row_mask:0xf bank_mask:0xf
	v_and_b32_e32 v177, 0xffff0000, v12
	v_fmac_f32_e32 v179, v176, v176
	v_lshlrev_b32_e32 v178, 16, v13
	v_fmac_f32_e32 v179, v177, v177
	v_and_b32_e32 v180, 0xffff0000, v13
	v_fmac_f32_e32 v179, v178, v178
	v_fmac_f32_e32 v179, v180, v180
	s_waitcnt vmcnt(1)
	v_lshlrev_b32_e32 v110, 16, v2
	v_and_b32_e32 v111, 0xffff0000, v2
	v_fmac_f32_e32 v179, v110, v110
	v_lshlrev_b32_e32 v112, 16, v3
	v_fmac_f32_e32 v179, v111, v111
	s_waitcnt lgkmcnt(0)
	s_nop 1
	v_add_f32_dpp v68, v68, v68 row_half_mirror row_mask:0xf bank_mask:0xf
	v_and_b32_e32 v113, 0xffff0000, v3
	v_fmac_f32_e32 v179, v112, v112
	v_lshlrev_b32_e32 v126, 16, v4
	v_fmac_f32_e32 v179, v113, v113
	v_and_b32_e32 v127, 0xffff0000, v4
	v_fmac_f32_e32 v179, v126, v126
	v_lshlrev_b32_e32 v128, 16, v5
	v_fmac_f32_e32 v179, v127, v127
	v_and_b32_e32 v129, 0xffff0000, v5
	v_fmac_f32_e32 v179, v128, v128
	s_waitcnt lgkmcnt(0)
	s_nop 1
	v_add_f32_dpp v126, v68, v68 row_mirror row_mask:0xf bank_mask:0xf
	v_fmac_f32_e32 v179, v129, v129
	global_load_dwordx4 v[110:113], v[56:57], off offset:16
	s_nop 0
	global_load_dwordx4 v[66:69], v[66:67], off offset:16
	v_and_b32_e32 v181, 0xffff0000, v122
	v_lshlrev_b32_e32 v180, 16, v123
	s_waitcnt lgkmcnt(0)
	v_mov_b32_e32 v173, v126
	v_mov_b32_e32 v127, v126
	s_nop 1
	v_permlane16_swap_b32_e32 v127, v173
	v_add_f32_e32 v173, v173, v127
	s_waitcnt lgkmcnt(0)
	s_nop 1
	v_add_f32_dpp v175, v179, v179 quad_perm:[1,0,3,2] row_mask:0xf bank_mask:0xf
	global_load_dwordx4 v[126:129], v[54:55], off offset:16
	s_nop 0
	global_load_dwordx4 v[54:57], v165, s[4:5] offset:16
	global_load_dwordx4 v[184:187], v[132:133], off offset:16
	global_load_dwordx4 v[188:191], v[132:133], off
	v_lshlrev_b32_e32 v192, 16, v115
	v_and_b32_e32 v115, 0xffff0000, v115
	v_lshlrev_b32_e32 v193, 16, v116
	s_waitcnt lgkmcnt(0)
	v_mov_b32_e32 v174, v173
	s_nop 1
	v_permlane32_swap_b32_e32 v174, v173
	v_add_f32_e32 v173, v173, v174
	s_waitcnt lgkmcnt(0)
	s_nop 1
	v_add_f32_dpp v174, v175, v175 quad_perm:[2,3,0,1] row_mask:0xf bank_mask:0xf
	v_fmamk_f32 v173, v173, 0x39800000, v168
	v_mul_f32_e32 v176, 0x4f800000, v173
	v_cmp_gt_f32_e32 vcc, s70, v173
	v_and_b32_e32 v116, 0xffff0000, v116
	s_waitcnt lgkmcnt(0)
	s_nop 1
	v_add_f32_dpp v174, v174, v174 row_half_mirror row_mask:0xf bank_mask:0xf
	v_cndmask_b32_e32 v173, v173, v176, vcc
	v_sqrt_f32_e32 v176, v173
	v_lshlrev_b32_e32 v194, 16, v117
	v_and_b32_e32 v117, 0xffff0000, v117
	s_waitcnt lgkmcnt(0)
	s_nop 1
	v_add_f32_dpp v174, v174, v174 row_mirror row_mask:0xf bank_mask:0xf
	v_add_u32_e32 v177, -1, v176
	v_fma_f32 v178, -v177, v176, v173
	v_cmp_ge_f32_e64 s[2:3], 0, v178
	v_add_u32_e32 v178, 1, v176
	s_waitcnt lgkmcnt(0)
	v_mov_b32_e32 v175, v174
	s_nop 1
	v_permlane16_swap_b32_e32 v175, v174
	v_add_f32_e32 v174, v174, v175
	v_cndmask_b32_e64 v177, v176, v177, s[2:3]
	v_fma_f32 v176, -v178, v176, v173
	v_cmp_lt_f32_e64 s[2:3], 0, v176
	v_lshlrev_b32_e32 v195, 16, v109
	s_waitcnt lgkmcnt(0)
	v_mov_b32_e32 v175, v174
	s_nop 1
	v_permlane32_swap_b32_e32 v175, v174
	v_add_f32_e32 v174, v174, v175
	v_fmamk_f32 v174, v174, 0x39800000, v168
	v_cndmask_b32_e64 v176, v177, v178, s[2:3]
	v_mul_f32_e32 v175, 0x4f800000, v174
	v_cmp_gt_f32_e64 s[2:3], s70, v174
	v_mul_f32_e32 v177, 0x37800000, v176
	v_cndmask_b32_e32 v176, v176, v177, vcc
	v_cndmask_b32_e64 v174, v174, v175, s[2:3]
	v_sqrt_f32_e32 v175, v174
	v_cmp_class_f32_e32 vcc, v173, v169
	v_and_b32_e32 v109, 0xffff0000, v109
	v_lshlrev_b32_e32 v200, 16, v95
	v_cndmask_b32_e32 v173, v176, v173, vcc
	v_add_u32_e32 v176, -1, v175
	v_fma_f32 v177, -v176, v175, v174
	v_cmp_ge_f32_e32 vcc, 0, v177
	v_add_u32_e32 v177, 1, v175
	v_and_b32_e32 v95, 0xffff0000, v95
	v_cndmask_b32_e32 v176, v175, v176, vcc
	v_fma_f32 v175, -v177, v175, v174
	v_cmp_lt_f32_e32 vcc, 0, v175
	v_lshlrev_b32_e32 v201, 16, v96
	v_and_b32_e32 v96, 0xffff0000, v96
	v_cndmask_b32_e32 v175, v176, v177, vcc
	v_div_scale_f32 v177, s[46:47], v173, v173, 1.0
	v_rcp_f32_e32 v178, v177
	v_mul_f32_e32 v176, 0x37800000, v175
	v_cndmask_b32_e64 v175, v175, v176, s[2:3]
	v_cmp_class_f32_e32 vcc, v174, v169
	v_lshlrev_b32_e32 v202, 16, v97
	v_and_b32_e32 v97, 0xffff0000, v97
	v_cndmask_b32_e32 v174, v175, v174, vcc
	v_fma_f32 v175, -v177, v178, 1.0
	v_fmac_f32_e32 v178, v175, v178
	v_div_scale_f32 v175, vcc, 1.0, v173, 1.0
	v_mul_f32_e32 v176, v175, v178
	v_fma_f32 v179, -v177, v176, v175
	v_fmac_f32_e32 v176, v179, v178
	v_fma_f32 v175, -v177, v176, v175
	v_div_scale_f32 v177, s[2:3], v174, v174, 1.0
	v_rcp_f32_e32 v179, v177
	v_div_fmas_f32 v175, v175, v178, v176
	v_div_fixup_f32 v183, v175, v173, 1.0
	v_and_b32_e32 v178, 0xffff0000, v123
	v_fma_f32 v173, -v177, v179, 1.0
	v_fmac_f32_e32 v179, v173, v179
	v_div_scale_f32 v173, vcc, 1.0, v174, 1.0
	v_mul_f32_e32 v175, v173, v179
	v_fma_f32 v176, -v177, v175, v173
	v_fmac_f32_e32 v175, v176, v179
	v_fma_f32 v173, -v177, v175, v173
	v_div_fmas_f32 v173, v173, v179, v175
	v_div_fixup_f32 v182, v173, v174, 1.0
	v_lshlrev_b32_e32 v173, 16, v114
	v_and_b32_e32 v114, 0xffff0000, v114
	v_mul_f32_e32 v114, v183, v114
	s_waitcnt vmcnt(0)
	v_fmac_f32_e32 v181, v189, v114
	v_mul_f32_e32 v114, v183, v192
	v_fmac_f32_e32 v180, v190, v114
	v_mul_f32_e32 v114, v183, v115
	v_lshlrev_b32_e32 v192, 16, v106
	v_and_b32_e32 v106, 0xffff0000, v106
	v_lshlrev_b32_e32 v179, 16, v122
	v_lshlrev_b32_e32 v177, 16, v124
	v_mul_f32_e32 v122, v183, v173
	v_fmac_f32_e32 v178, v191, v114
	v_mul_f32_e32 v114, v183, v193
	v_lshlrev_b32_e32 v193, 16, v107
	v_and_b32_e32 v173, 0xffff0000, v118
	v_mul_f32_e32 v106, v182, v106
	v_and_b32_e32 v176, 0xffff0000, v124
	v_lshlrev_b32_e32 v175, 16, v125
	v_and_b32_e32 v174, 0xffff0000, v125
	v_fmac_f32_e32 v177, v184, v114
	v_mul_f32_e32 v114, v183, v116
	v_and_b32_e32 v107, 0xffff0000, v107
	v_lshlrev_b32_e32 v125, 16, v119
	v_fmac_f32_e32 v173, v189, v106
	v_mul_f32_e32 v106, v182, v193
	v_fmac_f32_e32 v176, v185, v114
	v_mul_f32_e32 v114, v183, v194
	v_lshlrev_b32_e32 v194, 16, v108
	v_and_b32_e32 v123, 0xffff0000, v119
	v_fmac_f32_e32 v125, v190, v106
	v_mul_f32_e32 v106, v182, v107
	v_fmac_f32_e32 v179, v188, v122
	v_and_b32_e32 v108, 0xffff0000, v108
	v_lshlrev_b32_e32 v122, 16, v120
	v_fmac_f32_e32 v123, v191, v106
	v_mul_f32_e32 v106, v182, v194
	v_and_b32_e32 v120, 0xffff0000, v120
	v_fmac_f32_e32 v122, v184, v106
	v_mul_f32_e32 v106, v182, v108
	v_fmac_f32_e32 v175, v186, v114
	v_mul_f32_e32 v114, v183, v117
	v_lshlrev_b32_e32 v119, 16, v121
	v_fmac_f32_e32 v120, v185, v106
	v_mul_f32_e32 v106, v182, v195
	v_fmac_f32_e32 v174, v187, v114
	v_cvt_pk_bf16_f32 v114, v179, v181
	v_cvt_pk_bf16_f32 v115, v180, v178
	v_cvt_pk_bf16_f32 v116, v177, v176
	v_cvt_pk_bf16_f32 v117, v175, v174
	v_lshlrev_b32_e32 v124, 16, v118
	v_and_b32_e32 v118, 0xffff0000, v121
	v_mul_f32_e32 v121, v182, v192
	v_fmac_f32_e32 v119, v186, v106
	v_mul_f32_e32 v106, v182, v109
	global_store_dwordx4 v[154:155], v[114:117], off offset:-4096
	v_fmac_f32_e32 v124, v188, v121
	v_fmac_f32_e32 v118, v187, v106
	v_cvt_pk_bf16_f32 v114, v179, v181
	v_cvt_pk_bf16_f32 v115, v180, v178
	v_cvt_pk_bf16_f32 v116, v177, v176
	v_cvt_pk_bf16_f32 v117, v175, v174
	v_cvt_pk_bf16_f32 v106, v124, v173
	v_cvt_pk_bf16_f32 v107, v125, v123
	v_cvt_pk_bf16_f32 v108, v122, v120
	v_cvt_pk_bf16_f32 v109, v119, v118
	global_store_dwordx4 v172, v[106:109], s[4:5]
	v_lshlrev_b32_e32 v121, 16, v94
	v_and_b32_e32 v94, 0xffff0000, v94
	v_cvt_pk_bf16_f32 v106, v124, v173
	v_cvt_pk_bf16_f32 v107, v125, v123
	v_cvt_pk_bf16_f32 v108, v122, v120
	v_cvt_pk_bf16_f32 v109, v119, v118
	global_load_dwordx4 v[192:195], v[134:135], off
	global_load_dwordx4 v[196:199], v[134:135], off offset:16
	v_and_b32_e32 v190, 0xffff0000, v126
	v_mul_f32_e32 v94, v183, v94
	v_lshlrev_b32_e32 v189, 16, v127
	v_and_b32_e32 v188, 0xffff0000, v127
	v_lshlrev_b32_e32 v187, 16, v128
	v_and_b32_e32 v186, 0xffff0000, v128
	v_and_b32_e32 v128, 0xffff0000, v102
	v_lshlrev_b32_e32 v127, 16, v103
	v_lshlrev_b32_e32 v191, 16, v126
	v_mul_f32_e32 v121, v183, v121
	v_and_b32_e32 v126, 0xffff0000, v103
	v_lshlrev_b32_e32 v185, 16, v129
	v_lshlrev_b32_e32 v203, 16, v101
	v_and_b32_e32 v184, 0xffff0000, v129
	v_and_b32_e32 v101, 0xffff0000, v101
	v_lshlrev_b32_e32 v103, 16, v105
	v_lshlrev_b32_e32 v129, 16, v102
	v_and_b32_e32 v102, 0xffff0000, v105
	v_lshlrev_b32_e32 v208, 16, v91
	v_and_b32_e32 v91, 0xffff0000, v91
	v_lshlrev_b32_e32 v209, 16, v92
	v_and_b32_e32 v92, 0xffff0000, v92
	v_lshlrev_b32_e32 v210, 16, v93
	v_and_b32_e32 v93, 0xffff0000, v93
	v_lshlrev_b32_e32 v211, 16, v81
	v_and_b32_e32 v81, 0xffff0000, v81
	v_lshlrev_b32_e32 v216, 16, v75
	v_and_b32_e32 v75, 0xffff0000, v75
	v_lshlrev_b32_e32 v217, 16, v76
	v_and_b32_e32 v76, 0xffff0000, v76
	v_lshlrev_b32_e32 v218, 16, v77
	v_and_b32_e32 v77, 0xffff0000, v77
	v_lshlrev_b32_e32 v222, 16, v52
	v_and_b32_e32 v52, 0xffff0000, v52
	v_lshlrev_b32_e32 v223, 16, v53
	v_and_b32_e32 v53, 0xffff0000, v53
	v_lshlrev_b32_e32 v224, 16, v41
	v_and_b32_e32 v41, 0xffff0000, v41
	v_and_b32_e32 v225, 0xffff0000, v110
	v_lshlrev_b32_e32 v226, 16, v111
	v_and_b32_e32 v227, 0xffff0000, v111
	v_lshlrev_b32_e32 v228, 16, v112
	v_and_b32_e32 v229, 0xffff0000, v112
	v_lshlrev_b32_e32 v111, 16, v31
	v_and_b32_e32 v112, 0xffff0000, v31
	v_lshlrev_b32_e32 v230, 16, v113
	v_lshlrev_b32_e32 v231, 16, v29
	v_and_b32_e32 v31, 0xffff0000, v32
	v_and_b32_e32 v113, 0xffff0000, v113
	v_and_b32_e32 v29, 0xffff0000, v29
	v_lshlrev_b32_e32 v232, 16, v18
	v_and_b32_e32 v233, 0xffff0000, v18
	v_lshlrev_b32_e32 v235, 16, v19
	v_and_b32_e32 v236, 0xffff0000, v19
	v_lshlrev_b32_e32 v237, 16, v20
	v_and_b32_e32 v238, 0xffff0000, v20
	v_lshlrev_b32_e32 v239, 16, v21
	v_lshlrev_b32_e32 v241, 16, v16
	v_and_b32_e32 v242, 0xffff0000, v16
	v_and_b32_e32 v240, 0xffff0000, v21
	v_lshlrev_b32_e32 v243, 16, v17
	v_and_b32_e32 v244, 0xffff0000, v17
	v_lshlrev_b32_e32 v245, 16, v57
	v_and_b32_e32 v57, 0xffff0000, v57
	s_add_u32 s46, s8, s16
	s_addc_u32 s47, s9, s17
	s_waitcnt vmcnt(1)
	v_fmac_f32_e32 v190, v193, v94
	v_mul_f32_e32 v94, v183, v200
	v_fmac_f32_e32 v189, v194, v94
	v_mul_f32_e32 v94, v183, v95
	v_lshlrev_b32_e32 v200, 16, v98
	v_and_b32_e32 v98, 0xffff0000, v98
	v_fmac_f32_e32 v188, v195, v94
	v_mul_f32_e32 v94, v183, v201
	v_lshlrev_b32_e32 v201, 16, v99
	v_mul_f32_e32 v98, v182, v98
	s_waitcnt vmcnt(0)
	v_fmac_f32_e32 v187, v196, v94
	v_mul_f32_e32 v94, v183, v96
	v_and_b32_e32 v99, 0xffff0000, v99
	v_fmac_f32_e32 v128, v193, v98
	v_mul_f32_e32 v98, v182, v201
	v_fmac_f32_e32 v186, v197, v94
	v_mul_f32_e32 v94, v183, v202
	v_lshlrev_b32_e32 v202, 16, v100
	v_fmac_f32_e32 v127, v194, v98
	v_mul_f32_e32 v98, v182, v99
	v_fmac_f32_e32 v191, v192, v121
	v_and_b32_e32 v100, 0xffff0000, v100
	v_lshlrev_b32_e32 v121, 16, v104
	v_fmac_f32_e32 v126, v195, v98
	v_mul_f32_e32 v98, v182, v202
	v_and_b32_e32 v104, 0xffff0000, v104
	v_fmac_f32_e32 v121, v196, v98
	v_mul_f32_e32 v98, v182, v100
	v_fmac_f32_e32 v185, v198, v94
	v_mul_f32_e32 v94, v183, v97
	v_fmac_f32_e32 v104, v197, v98
	v_mul_f32_e32 v98, v182, v203
	v_fmac_f32_e32 v184, v199, v94
	v_cvt_pk_bf16_f32 v94, v191, v190
	v_cvt_pk_bf16_f32 v95, v189, v188
	v_cvt_pk_bf16_f32 v96, v187, v186
	v_cvt_pk_bf16_f32 v97, v185, v184
	v_mul_f32_e32 v105, v182, v200
	v_fmac_f32_e32 v103, v198, v98
	v_mul_f32_e32 v98, v182, v101
	global_store_dwordx4 v[156:157], v[94:97], off offset:16
	v_fmac_f32_e32 v129, v192, v105
	v_fmac_f32_e32 v102, v199, v98
	v_cvt_pk_bf16_f32 v94, v191, v190
	v_cvt_pk_bf16_f32 v95, v189, v188
	v_cvt_pk_bf16_f32 v96, v187, v186
	v_cvt_pk_bf16_f32 v97, v185, v184
	v_cvt_pk_bf16_f32 v98, v129, v128
	v_cvt_pk_bf16_f32 v99, v127, v126
	v_cvt_pk_bf16_f32 v100, v121, v104
	v_cvt_pk_bf16_f32 v101, v103, v102
	global_store_dwordx4 v172, v[98:101], s[4:5] offset:16
	v_lshlrev_b32_e32 v105, 16, v90
	v_and_b32_e32 v90, 0xffff0000, v90
	v_cvt_pk_bf16_f32 v98, v129, v128
	v_cvt_pk_bf16_f32 v99, v127, v126
	v_cvt_pk_bf16_f32 v100, v121, v104
	v_cvt_pk_bf16_f32 v101, v103, v102
	global_load_dwordx4 v[200:203], v[136:137], off
	global_load_dwordx4 v[204:207], v[136:137], off offset:16
	v_lshlrev_b32_e32 v199, 16, v86
	v_and_b32_e32 v198, 0xffff0000, v86
	v_mul_f32_e32 v86, v183, v105
	v_lshlrev_b32_e32 v197, 16, v87
	v_and_b32_e32 v196, 0xffff0000, v87
	v_lshlrev_b32_e32 v195, 16, v88
	v_and_b32_e32 v194, 0xffff0000, v88
	v_lshlrev_b32_e32 v193, 16, v89
	v_and_b32_e32 v192, 0xffff0000, v89
	v_lshlrev_b32_e32 v105, 16, v82
	s_waitcnt vmcnt(1)
	v_fmac_f32_e32 v199, v86, v200
	v_mul_f32_e32 v86, v183, v90
	v_fmac_f32_e32 v198, v86, v201
	v_mul_f32_e32 v86, v183, v208
	v_fmac_f32_e32 v197, v86, v202
	v_mul_f32_e32 v86, v183, v91
	v_fmac_f32_e32 v196, v86, v203
	v_mul_f32_e32 v86, v183, v209
	s_waitcnt vmcnt(0)
	v_fmac_f32_e32 v195, v86, v204
	v_mul_f32_e32 v86, v183, v92
	v_fmac_f32_e32 v194, v86, v205
	v_mul_f32_e32 v86, v183, v210
	v_lshlrev_b32_e32 v208, 16, v78
	v_and_b32_e32 v78, 0xffff0000, v78
	v_fmac_f32_e32 v193, v86, v206
	v_mul_f32_e32 v86, v183, v93
	v_lshlrev_b32_e32 v209, 16, v79
	v_and_b32_e32 v93, 0xffff0000, v82
	v_mul_f32_e32 v78, v182, v78
	v_and_b32_e32 v79, 0xffff0000, v79
	v_lshlrev_b32_e32 v92, 16, v83
	v_fmac_f32_e32 v93, v78, v201
	v_mul_f32_e32 v78, v182, v209
	v_lshlrev_b32_e32 v210, 16, v80
	v_and_b32_e32 v91, 0xffff0000, v83
	v_fmac_f32_e32 v92, v78, v202
	v_mul_f32_e32 v78, v182, v79
	v_and_b32_e32 v80, 0xffff0000, v80
	v_lshlrev_b32_e32 v90, 16, v84
	v_fmac_f32_e32 v91, v78, v203
	v_mul_f32_e32 v78, v182, v210
	v_and_b32_e32 v84, 0xffff0000, v84
	v_fmac_f32_e32 v90, v78, v204
	v_mul_f32_e32 v78, v182, v80
	v_lshlrev_b32_e32 v83, 16, v85
	v_fmac_f32_e32 v84, v78, v205
	v_mul_f32_e32 v78, v182, v211
	v_fmac_f32_e32 v192, v86, v207
	v_cvt_pk_bf16_f32 v86, v199, v198
	v_cvt_pk_bf16_f32 v87, v197, v196
	v_cvt_pk_bf16_f32 v88, v195, v194
	v_cvt_pk_bf16_f32 v89, v193, v192
	v_and_b32_e32 v82, 0xffff0000, v85
	v_mul_f32_e32 v85, v182, v208
	v_fmac_f32_e32 v83, v78, v206
	v_mul_f32_e32 v78, v182, v81
	global_store_dwordx4 v[156:157], v[86:89], off offset:2048
	v_fmac_f32_e32 v105, v85, v200
	v_fmac_f32_e32 v82, v78, v207
	v_cvt_pk_bf16_f32 v86, v199, v198
	v_cvt_pk_bf16_f32 v87, v197, v196
	v_cvt_pk_bf16_f32 v88, v195, v194
	v_cvt_pk_bf16_f32 v89, v193, v192
	v_cvt_pk_bf16_f32 v78, v105, v93
	v_cvt_pk_bf16_f32 v79, v92, v91
	v_cvt_pk_bf16_f32 v80, v90, v84
	v_cvt_pk_bf16_f32 v81, v83, v82
	global_store_dwordx4 v172, v[78:81], s[4:5] offset:2048
	v_lshlrev_b32_e32 v85, 16, v74
	v_and_b32_e32 v74, 0xffff0000, v74
	v_cvt_pk_bf16_f32 v78, v105, v93
	v_cvt_pk_bf16_f32 v79, v92, v91
	v_cvt_pk_bf16_f32 v80, v90, v84
	v_cvt_pk_bf16_f32 v81, v83, v82
	global_load_dwordx4 v[208:211], v[138:139], off
	global_load_dwordx4 v[212:215], v[138:139], off offset:16
	v_lshlrev_b32_e32 v207, 16, v70
	v_and_b32_e32 v206, 0xffff0000, v70
	v_mul_f32_e32 v70, v183, v85
	v_lshlrev_b32_e32 v205, 16, v71
	v_and_b32_e32 v204, 0xffff0000, v71
	v_lshlrev_b32_e32 v203, 16, v72
	v_and_b32_e32 v202, 0xffff0000, v72
	v_lshlrev_b32_e32 v201, 16, v73
	v_and_b32_e32 v200, 0xffff0000, v73
	v_lshlrev_b32_e32 v85, 16, v62
	s_waitcnt vmcnt(1)
	v_fmac_f32_e32 v207, v70, v208
	v_mul_f32_e32 v70, v183, v74
	v_fmac_f32_e32 v206, v70, v209
	v_mul_f32_e32 v70, v183, v216
	v_fmac_f32_e32 v205, v70, v210
	v_mul_f32_e32 v70, v183, v75
	v_fmac_f32_e32 v204, v70, v211
	v_mul_f32_e32 v70, v183, v217
	s_waitcnt vmcnt(0)
	v_fmac_f32_e32 v203, v70, v212
	v_mul_f32_e32 v70, v183, v76
	v_fmac_f32_e32 v202, v70, v213
	v_mul_f32_e32 v70, v183, v218
	v_fmac_f32_e32 v201, v70, v214
	v_mul_f32_e32 v70, v183, v77
	v_fmac_f32_e32 v200, v70, v215
	v_cvt_pk_bf16_f32 v70, v207, v206
	v_cvt_pk_bf16_f32 v71, v205, v204
	v_cvt_pk_bf16_f32 v72, v203, v202
	v_cvt_pk_bf16_f32 v73, v201, v200
	global_store_dwordx4 v[156:157], v[70:73], off offset:2064
	v_lshlrev_b32_e32 v156, 16, v58
	v_and_b32_e32 v58, 0xffff0000, v58
	v_lshlrev_b32_e32 v157, 16, v59
	v_and_b32_e32 v77, 0xffff0000, v62
	v_mul_f32_e32 v58, v182, v58
	v_and_b32_e32 v59, 0xffff0000, v59
	v_lshlrev_b32_e32 v76, 16, v63
	v_fmac_f32_e32 v77, v58, v209
	v_mul_f32_e32 v58, v182, v157
	v_lshlrev_b32_e32 v216, 16, v60
	v_and_b32_e32 v75, 0xffff0000, v63
	v_fmac_f32_e32 v76, v58, v210
	v_mul_f32_e32 v58, v182, v59
	v_and_b32_e32 v60, 0xffff0000, v60
	v_lshlrev_b32_e32 v74, 16, v64
	v_fmac_f32_e32 v75, v58, v211
	v_mul_f32_e32 v58, v182, v216
	v_lshlrev_b32_e32 v217, 16, v61
	v_and_b32_e32 v64, 0xffff0000, v64
	v_fmac_f32_e32 v74, v58, v212
	v_mul_f32_e32 v58, v182, v60
	v_and_b32_e32 v61, 0xffff0000, v61
	v_lshlrev_b32_e32 v63, 16, v65
	v_fmac_f32_e32 v64, v58, v213
	v_mul_f32_e32 v58, v182, v217
	v_and_b32_e32 v62, 0xffff0000, v65
	v_mul_f32_e32 v65, v182, v156
	v_fmac_f32_e32 v63, v58, v214
	v_mul_f32_e32 v58, v182, v61
	v_cvt_pk_bf16_f32 v70, v207, v206
	v_cvt_pk_bf16_f32 v71, v205, v204
	v_cvt_pk_bf16_f32 v72, v203, v202
	v_cvt_pk_bf16_f32 v73, v201, v200
	v_fmac_f32_e32 v85, v65, v208
	v_fmac_f32_e32 v62, v58, v215
	v_cvt_pk_bf16_f32 v58, v85, v77
	v_cvt_pk_bf16_f32 v59, v76, v75
	v_cvt_pk_bf16_f32 v60, v74, v64
	v_cvt_pk_bf16_f32 v61, v63, v62
	global_store_dwordx4 v172, v[58:61], s[4:5] offset:2064
	v_lshlrev_b32_e32 v65, 16, v50
	v_and_b32_e32 v50, 0xffff0000, v50
	v_cvt_pk_bf16_f32 v58, v85, v77
	v_cvt_pk_bf16_f32 v59, v76, v75
	v_cvt_pk_bf16_f32 v60, v74, v64
	v_cvt_pk_bf16_f32 v61, v63, v62
	global_load_dwordx4 v[214:217], v[140:141], off
	global_load_dwordx4 v[218:221], v[140:141], off offset:16
	v_lshlrev_b32_e32 v212, 16, v46
	v_and_b32_e32 v211, 0xffff0000, v46
	v_mul_f32_e32 v46, v183, v65
	v_lshlrev_b32_e32 v213, 16, v51
	v_and_b32_e32 v51, 0xffff0000, v51
	v_lshlrev_b32_e32 v210, 16, v47
	v_and_b32_e32 v209, 0xffff0000, v47
	v_lshlrev_b32_e32 v208, 16, v48
	v_and_b32_e32 v172, 0xffff0000, v48
	v_lshlrev_b32_e32 v157, 16, v49
	v_and_b32_e32 v156, 0xffff0000, v49
	v_lshlrev_b32_e32 v65, 16, v42
	s_waitcnt vmcnt(1)
	v_fmac_f32_e32 v212, v46, v214
	v_mul_f32_e32 v46, v183, v50
	v_fmac_f32_e32 v211, v46, v215
	v_mul_f32_e32 v46, v183, v213
	v_fmac_f32_e32 v210, v46, v216
	v_mul_f32_e32 v46, v183, v51
	v_fmac_f32_e32 v209, v46, v217
	v_mul_f32_e32 v46, v183, v222
	s_waitcnt vmcnt(0)
	v_fmac_f32_e32 v208, v46, v218
	v_mul_f32_e32 v46, v183, v52
	v_fmac_f32_e32 v172, v46, v219
	v_mul_f32_e32 v46, v183, v223
	v_lshlrev_b32_e32 v213, 16, v38
	v_and_b32_e32 v38, 0xffff0000, v38
	v_fmac_f32_e32 v157, v46, v220
	v_mul_f32_e32 v46, v183, v53
	v_lshlrev_b32_e32 v222, 16, v39
	v_and_b32_e32 v53, 0xffff0000, v42
	v_mul_f32_e32 v38, v182, v38
	v_and_b32_e32 v39, 0xffff0000, v39
	v_lshlrev_b32_e32 v52, 16, v43
	v_fmac_f32_e32 v53, v38, v215
	v_mul_f32_e32 v38, v182, v222
	v_lshlrev_b32_e32 v223, 16, v40
	v_and_b32_e32 v51, 0xffff0000, v43
	v_fmac_f32_e32 v52, v38, v216
	v_mul_f32_e32 v38, v182, v39
	v_and_b32_e32 v40, 0xffff0000, v40
	v_lshlrev_b32_e32 v50, 16, v44
	v_fmac_f32_e32 v51, v38, v217
	v_mul_f32_e32 v38, v182, v223
	v_and_b32_e32 v44, 0xffff0000, v44
	v_fmac_f32_e32 v50, v38, v218
	v_mul_f32_e32 v38, v182, v40
	v_lshlrev_b32_e32 v43, 16, v45
	v_fmac_f32_e32 v44, v38, v219
	v_mul_f32_e32 v38, v182, v224
	v_fmac_f32_e32 v156, v46, v221
	v_cvt_pk_bf16_f32 v46, v212, v211
	v_cvt_pk_bf16_f32 v47, v210, v209
	v_cvt_pk_bf16_f32 v48, v208, v172
	v_cvt_pk_bf16_f32 v49, v157, v156
	v_and_b32_e32 v42, 0xffff0000, v45
	v_mul_f32_e32 v45, v182, v213
	v_fmac_f32_e32 v43, v38, v220
	v_mul_f32_e32 v38, v182, v41
	global_store_dwordx4 v[154:155], v[46:49], off
	v_fmac_f32_e32 v65, v45, v214
	v_fmac_f32_e32 v42, v38, v221
	v_cvt_pk_bf16_f32 v46, v212, v211
	v_cvt_pk_bf16_f32 v47, v210, v209
	v_cvt_pk_bf16_f32 v48, v208, v172
	v_cvt_pk_bf16_f32 v49, v157, v156
	v_cvt_pk_bf16_f32 v38, v65, v53
	v_cvt_pk_bf16_f32 v39, v52, v51
	v_cvt_pk_bf16_f32 v40, v50, v44
	v_cvt_pk_bf16_f32 v41, v43, v42
	global_store_dwordx4 v164, v[38:41], s[4:5]
	v_lshlrev_b32_e32 v45, 16, v34
	v_and_b32_e32 v34, 0xffff0000, v34
	v_cvt_pk_bf16_f32 v38, v65, v53
	v_cvt_pk_bf16_f32 v39, v52, v51
	v_cvt_pk_bf16_f32 v40, v50, v44
	v_cvt_pk_bf16_f32 v41, v43, v42
	global_load_dwordx4 v[214:217], v[142:143], off
	global_load_dwordx4 v[218:221], v[142:143], off offset:16
	v_lshlrev_b32_e32 v213, 16, v35
	v_mul_f32_e32 v34, v183, v34
	v_and_b32_e32 v35, 0xffff0000, v35
	v_lshlrev_b32_e32 v222, 16, v36
	v_and_b32_e32 v36, 0xffff0000, v36
	v_lshlrev_b32_e32 v224, 16, v110
	v_and_b32_e32 v110, 0xffff0000, v30
	v_lshlrev_b32_e32 v223, 16, v37
	v_mul_f32_e32 v45, v183, v45
	v_and_b32_e32 v37, 0xffff0000, v37
	s_waitcnt vmcnt(1)
	v_fmac_f32_e32 v225, v34, v215
	v_mul_f32_e32 v34, v183, v213
	v_fmac_f32_e32 v226, v34, v216
	v_mul_f32_e32 v34, v183, v35
	v_lshlrev_b32_e32 v213, 16, v26
	v_and_b32_e32 v26, 0xffff0000, v26
	v_fmac_f32_e32 v227, v34, v217
	v_mul_f32_e32 v34, v183, v222
	v_lshlrev_b32_e32 v222, 16, v27
	v_mul_f32_e32 v26, v182, v26
	s_waitcnt vmcnt(0)
	v_fmac_f32_e32 v228, v34, v218
	v_mul_f32_e32 v34, v183, v36
	v_and_b32_e32 v27, 0xffff0000, v27
	v_fmac_f32_e32 v110, v26, v215
	v_mul_f32_e32 v26, v182, v222
	v_fmac_f32_e32 v229, v34, v219
	v_mul_f32_e32 v34, v183, v223
	v_lshlrev_b32_e32 v223, 16, v28
	v_fmac_f32_e32 v111, v26, v216
	v_mul_f32_e32 v26, v182, v27
	v_fmac_f32_e32 v224, v45, v214
	v_and_b32_e32 v28, 0xffff0000, v28
	v_lshlrev_b32_e32 v45, 16, v30
	v_lshlrev_b32_e32 v30, 16, v32
	v_fmac_f32_e32 v112, v26, v217
	v_mul_f32_e32 v26, v182, v223
	v_fmac_f32_e32 v30, v26, v218
	v_mul_f32_e32 v26, v182, v28
	v_fmac_f32_e32 v230, v34, v220
	v_mul_f32_e32 v34, v183, v37
	v_lshlrev_b32_e32 v32, 16, v33
	v_fmac_f32_e32 v31, v26, v219
	v_mul_f32_e32 v26, v182, v231
	v_fmac_f32_e32 v113, v34, v221
	v_cvt_pk_bf16_f32 v34, v224, v225
	v_cvt_pk_bf16_f32 v35, v226, v227
	v_cvt_pk_bf16_f32 v36, v228, v229
	v_cvt_pk_bf16_f32 v37, v230, v113
	v_and_b32_e32 v33, 0xffff0000, v33
	v_mul_f32_e32 v213, v182, v213
	v_fmac_f32_e32 v32, v26, v220
	v_mul_f32_e32 v26, v182, v29
	global_store_dwordx4 v[154:155], v[34:37], off offset:16
	v_fmac_f32_e32 v45, v213, v214
	v_fmac_f32_e32 v33, v26, v221
	v_cvt_pk_bf16_f32 v34, v224, v225
	v_cvt_pk_bf16_f32 v35, v226, v227
	v_cvt_pk_bf16_f32 v36, v228, v229
	v_cvt_pk_bf16_f32 v37, v230, v113
	v_cvt_pk_bf16_f32 v26, v45, v110
	v_cvt_pk_bf16_f32 v27, v111, v112
	v_cvt_pk_bf16_f32 v28, v30, v31
	v_cvt_pk_bf16_f32 v29, v32, v33
	global_store_dwordx4 v166, v[26:29], s[4:5]
	v_lshlrev_b32_e32 v213, 16, v22
	v_and_b32_e32 v22, 0xffff0000, v22
	v_cvt_pk_bf16_f32 v26, v45, v110
	v_cvt_pk_bf16_f32 v27, v111, v112
	v_cvt_pk_bf16_f32 v28, v30, v31
	v_cvt_pk_bf16_f32 v29, v32, v33
	global_load_dwordx4 v[214:217], v[144:145], off
	global_load_dwordx4 v[218:221], v[144:145], off offset:16
	v_mul_f32_e32 v18, v183, v213
	v_lshlrev_b32_e32 v222, 16, v23
	v_and_b32_e32 v23, 0xffff0000, v23
	v_lshlrev_b32_e32 v223, 16, v24
	v_and_b32_e32 v24, 0xffff0000, v24
	v_lshlrev_b32_e32 v231, 16, v25
	v_and_b32_e32 v25, 0xffff0000, v25
	v_lshlrev_b32_e32 v213, 16, v14
	s_waitcnt vmcnt(1)
	v_fmac_f32_e32 v232, v18, v214
	v_mul_f32_e32 v18, v183, v22
	v_fmac_f32_e32 v233, v18, v215
	v_mul_f32_e32 v18, v183, v222
	v_fmac_f32_e32 v235, v18, v216
	v_mul_f32_e32 v18, v183, v23
	v_lshlrev_b32_e32 v22, 16, v10
	v_and_b32_e32 v10, 0xffff0000, v10
	v_fmac_f32_e32 v236, v18, v217
	v_mul_f32_e32 v18, v183, v223
	v_lshlrev_b32_e32 v23, 16, v11
	v_and_b32_e32 v222, 0xffff0000, v14
	v_mul_f32_e32 v10, v182, v10
	s_waitcnt vmcnt(0)
	v_fmac_f32_e32 v237, v18, v218
	v_mul_f32_e32 v18, v183, v24
	v_and_b32_e32 v11, 0xffff0000, v11
	v_lshlrev_b32_e32 v223, 16, v15
	v_fmac_f32_e32 v222, v10, v215
	v_mul_f32_e32 v10, v182, v23
	v_fmac_f32_e32 v238, v18, v219
	v_mul_f32_e32 v18, v183, v231
	v_lshlrev_b32_e32 v24, 16, v12
	v_and_b32_e32 v231, 0xffff0000, v15
	v_fmac_f32_e32 v223, v10, v216
	v_mul_f32_e32 v10, v182, v11
	v_and_b32_e32 v12, 0xffff0000, v12
	v_fmac_f32_e32 v231, v10, v217
	v_mul_f32_e32 v10, v182, v24
	v_fmac_f32_e32 v239, v18, v220
	v_mul_f32_e32 v18, v183, v25
	v_lshlrev_b32_e32 v25, 16, v13
	v_fmac_f32_e32 v241, v10, v218
	v_mul_f32_e32 v10, v182, v12
	v_and_b32_e32 v13, 0xffff0000, v13
	v_fmac_f32_e32 v242, v10, v219
	v_mul_f32_e32 v10, v182, v25
	v_fmac_f32_e32 v240, v18, v221
	v_cvt_pk_bf16_f32 v18, v232, v233
	v_cvt_pk_bf16_f32 v19, v235, v236
	v_cvt_pk_bf16_f32 v20, v237, v238
	v_cvt_pk_bf16_f32 v21, v239, v240
	v_mul_f32_e32 v14, v182, v22
	v_fmac_f32_e32 v243, v10, v220
	v_mul_f32_e32 v10, v182, v13
	global_store_dwordx4 v[154:155], v[18:21], off offset:2048
	v_fmac_f32_e32 v213, v14, v214
	v_fmac_f32_e32 v244, v10, v221
	v_cvt_pk_bf16_f32 v18, v232, v233
	v_cvt_pk_bf16_f32 v19, v235, v236
	v_cvt_pk_bf16_f32 v20, v237, v238
	v_cvt_pk_bf16_f32 v21, v239, v240
	v_cvt_pk_bf16_f32 v10, v213, v222
	v_cvt_pk_bf16_f32 v11, v223, v231
	v_cvt_pk_bf16_f32 v12, v241, v242
	v_cvt_pk_bf16_f32 v13, v243, v244
	global_store_dwordx4 v165, v[10:13], s[4:5]
	v_lshlrev_b32_e32 v214, 16, v6
	v_and_b32_e32 v6, 0xffff0000, v6
	v_cvt_pk_bf16_f32 v10, v213, v222
	v_cvt_pk_bf16_f32 v11, v223, v231
	v_cvt_pk_bf16_f32 v12, v241, v242
	v_cvt_pk_bf16_f32 v13, v243, v244
	global_load_dwordx4 v[14:17], v[146:147], off
	global_load_dwordx4 v[22:25], v[146:147], off offset:16
	v_lshlrev_b32_e32 v215, 16, v7
	v_lshlrev_b32_e32 v218, 16, v66
	v_and_b32_e32 v66, 0xffff0000, v66
	v_mul_f32_e32 v6, v183, v6
	v_and_b32_e32 v7, 0xffff0000, v7
	v_lshlrev_b32_e32 v219, 16, v67
	v_lshlrev_b32_e32 v216, 16, v8
	v_and_b32_e32 v67, 0xffff0000, v67
	v_and_b32_e32 v8, 0xffff0000, v8
	v_lshlrev_b32_e32 v220, 16, v68
	v_lshlrev_b32_e32 v217, 16, v9
	v_and_b32_e32 v68, 0xffff0000, v68
	v_and_b32_e32 v9, 0xffff0000, v9
	v_lshlrev_b32_e32 v221, 16, v69
	v_and_b32_e32 v69, 0xffff0000, v69
	v_mul_f32_e32 v214, v183, v214
	s_waitcnt vmcnt(1)
	v_fmac_f32_e32 v66, v6, v15
	v_mul_f32_e32 v6, v183, v215
	v_fmac_f32_e32 v219, v6, v16
	v_mul_f32_e32 v6, v183, v7
	v_fmac_f32_e32 v67, v6, v17
	v_mul_f32_e32 v6, v183, v216
	s_waitcnt vmcnt(0)
	v_fmac_f32_e32 v220, v6, v22
	v_mul_f32_e32 v6, v183, v8
	v_fmac_f32_e32 v68, v6, v23
	v_mul_f32_e32 v6, v183, v217
	v_fmac_f32_e32 v221, v6, v24
	v_mul_f32_e32 v6, v183, v9
	v_fmac_f32_e32 v218, v214, v14
	v_fmac_f32_e32 v69, v6, v25
	v_cvt_pk_bf16_f32 v6, v218, v66
	v_cvt_pk_bf16_f32 v7, v219, v67
	v_cvt_pk_bf16_f32 v8, v220, v68
	v_cvt_pk_bf16_f32 v9, v221, v69
	global_store_dwordx4 v[154:155], v[6:9], off offset:2064
	v_lshlrev_b32_e32 v154, 16, v2
	v_lshlrev_b32_e32 v215, 16, v54
	v_mul_f32_e32 v154, v182, v154
	v_fmac_f32_e32 v215, v154, v14
	v_mul_f32_e32 v14, v181, v181
	v_fmac_f32_e32 v14, v179, v179
	v_fmac_f32_e32 v14, v180, v180
	v_fmac_f32_e32 v14, v178, v178
	v_fmac_f32_e32 v14, v177, v177
	v_fmac_f32_e32 v14, v176, v176
	v_fmac_f32_e32 v14, v175, v175
	v_fmac_f32_e32 v14, v174, v174
	v_fmac_f32_e32 v14, v191, v191
	v_fmac_f32_e32 v14, v190, v190
	v_fmac_f32_e32 v14, v189, v189
	v_fmac_f32_e32 v14, v188, v188
	v_fmac_f32_e32 v14, v187, v187
	v_fmac_f32_e32 v14, v186, v186
	v_fmac_f32_e32 v14, v185, v185
	v_fmac_f32_e32 v14, v184, v184
	v_fmac_f32_e32 v14, v199, v199
	v_fmac_f32_e32 v14, v198, v198
	v_fmac_f32_e32 v14, v197, v197
	v_fmac_f32_e32 v14, v196, v196
	v_fmac_f32_e32 v14, v195, v195
	v_fmac_f32_e32 v14, v194, v194
	v_fmac_f32_e32 v14, v193, v193
	v_fmac_f32_e32 v14, v192, v192
	v_fmac_f32_e32 v14, v207, v207
	v_fmac_f32_e32 v14, v206, v206
	v_fmac_f32_e32 v14, v205, v205
	v_fmac_f32_e32 v14, v204, v204
	v_fmac_f32_e32 v14, v203, v203
	v_fmac_f32_e32 v14, v202, v202
	v_fmac_f32_e32 v14, v201, v201
	v_and_b32_e32 v2, 0xffff0000, v2
	v_fmac_f32_e32 v14, v200, v200
	v_and_b32_e32 v54, 0xffff0000, v54
	v_mul_f32_e32 v2, v182, v2
	v_fmac_f32_e32 v14, v212, v212
	v_fmac_f32_e32 v54, v2, v15
	v_fmac_f32_e32 v14, v211, v211
	v_mul_f32_e32 v15, v173, v173
	v_fmac_f32_e32 v14, v210, v210
	v_fmac_f32_e32 v15, v124, v124
	v_fmac_f32_e32 v14, v209, v209
	v_fmac_f32_e32 v15, v125, v125
	v_fmac_f32_e32 v14, v208, v208
	v_fmac_f32_e32 v15, v123, v123
	v_fmac_f32_e32 v14, v172, v172
	v_fmac_f32_e32 v15, v122, v122
	v_fmac_f32_e32 v14, v157, v157
	v_fmac_f32_e32 v15, v120, v120
	v_fmac_f32_e32 v14, v156, v156
	v_fmac_f32_e32 v15, v119, v119
	v_fmac_f32_e32 v14, v224, v224
	v_fmac_f32_e32 v15, v118, v118
	v_fmac_f32_e32 v14, v225, v225
	v_fmac_f32_e32 v15, v129, v129
	v_fmac_f32_e32 v14, v226, v226
	v_fmac_f32_e32 v15, v128, v128
	v_fmac_f32_e32 v14, v227, v227
	v_fmac_f32_e32 v15, v127, v127
	v_fmac_f32_e32 v14, v228, v228
	v_fmac_f32_e32 v15, v126, v126
	v_fmac_f32_e32 v14, v229, v229
	v_fmac_f32_e32 v15, v121, v121
	v_fmac_f32_e32 v14, v230, v230
	v_fmac_f32_e32 v15, v104, v104
	v_fmac_f32_e32 v14, v113, v113
	v_fmac_f32_e32 v15, v103, v103
	v_fmac_f32_e32 v14, v232, v232
	v_fmac_f32_e32 v15, v102, v102
	v_fmac_f32_e32 v14, v233, v233
	v_fmac_f32_e32 v15, v105, v105
	v_fmac_f32_e32 v14, v235, v235
	v_fmac_f32_e32 v15, v93, v93
	v_fmac_f32_e32 v14, v236, v236
	v_fmac_f32_e32 v15, v92, v92
	v_fmac_f32_e32 v14, v237, v237
	v_fmac_f32_e32 v15, v91, v91
	v_fmac_f32_e32 v14, v238, v238
	v_fmac_f32_e32 v15, v90, v90
	v_fmac_f32_e32 v14, v239, v239
	v_fmac_f32_e32 v15, v84, v84
	v_fmac_f32_e32 v14, v240, v240
	v_fmac_f32_e32 v15, v83, v83
	v_fmac_f32_e32 v14, v218, v218
	v_fmac_f32_e32 v15, v82, v82
	v_fmac_f32_e32 v14, v66, v66
	v_fmac_f32_e32 v15, v85, v85
	v_fmac_f32_e32 v14, v219, v219
	v_fmac_f32_e32 v15, v77, v77
	v_fmac_f32_e32 v14, v67, v67
	v_fmac_f32_e32 v15, v76, v76
	v_fmac_f32_e32 v14, v220, v220
	v_fmac_f32_e32 v15, v75, v75
	v_fmac_f32_e32 v14, v68, v68
	v_fmac_f32_e32 v15, v74, v74
	v_lshlrev_b32_e32 v155, 16, v3
	v_fmac_f32_e32 v14, v221, v221
	v_fmac_f32_e32 v15, v64, v64
	v_lshlrev_b32_e32 v216, 16, v55
	v_mul_f32_e32 v2, v182, v155
	v_fmac_f32_e32 v14, v69, v69
	v_fmac_f32_e32 v15, v63, v63
	v_fmac_f32_e32 v216, v2, v16
	v_fmac_f32_e32 v15, v62, v62
	v_fmac_f32_e32 v15, v65, v65
	v_fmac_f32_e32 v15, v53, v53
	v_fmac_f32_e32 v15, v52, v52
	v_fmac_f32_e32 v15, v51, v51
	v_fmac_f32_e32 v15, v50, v50
	s_waitcnt lgkmcnt(0)
	s_nop 1
	v_add_f32_dpp v14, v14, v14 quad_perm:[1,0,3,2] row_mask:0xf bank_mask:0xf
	v_fmac_f32_e32 v15, v44, v44
	v_fmac_f32_e32 v15, v43, v43
	v_fmac_f32_e32 v15, v42, v42
	v_fmac_f32_e32 v15, v45, v45
	v_fmac_f32_e32 v15, v110, v110
	v_fmac_f32_e32 v15, v111, v111
	s_waitcnt lgkmcnt(0)
	s_nop 1
	v_add_f32_dpp v14, v14, v14 quad_perm:[2,3,0,1] row_mask:0xf bank_mask:0xf
	v_fmac_f32_e32 v15, v112, v112
	v_fmac_f32_e32 v15, v30, v30
	v_fmac_f32_e32 v15, v31, v31
	v_fmac_f32_e32 v15, v32, v32
	v_fmac_f32_e32 v15, v33, v33
	v_fmac_f32_e32 v15, v213, v213
	s_waitcnt lgkmcnt(0)
	s_nop 1
	v_add_f32_dpp v14, v14, v14 row_half_mirror row_mask:0xf bank_mask:0xf
	v_fmac_f32_e32 v15, v222, v222
	v_fmac_f32_e32 v15, v223, v223
	v_fmac_f32_e32 v15, v231, v231
	v_fmac_f32_e32 v15, v241, v241
	v_fmac_f32_e32 v15, v242, v242
	v_fmac_f32_e32 v15, v243, v243
	s_waitcnt lgkmcnt(0)
	s_nop 1
	v_add_f32_dpp v14, v14, v14 row_mirror row_mask:0xf bank_mask:0xf
	v_fmac_f32_e32 v15, v244, v244
	v_and_b32_e32 v3, 0xffff0000, v3
	v_fmac_f32_e32 v15, v215, v215
	v_lshlrev_b32_e32 v183, 16, v4
	v_and_b32_e32 v55, 0xffff0000, v55
	v_mul_f32_e32 v2, v182, v3
	v_fmac_f32_e32 v15, v54, v54
	v_and_b32_e32 v4, 0xffff0000, v4
	v_lshlrev_b32_e32 v217, 16, v56
	v_fmac_f32_e32 v55, v2, v17
	v_mul_f32_e32 v2, v182, v183
	v_fmac_f32_e32 v15, v216, v216
	v_lshlrev_b32_e32 v214, 16, v5
	v_and_b32_e32 v56, 0xffff0000, v56
	v_fmac_f32_e32 v217, v2, v22
	v_mul_f32_e32 v2, v182, v4
	v_fmac_f32_e32 v15, v55, v55
	v_and_b32_e32 v5, 0xffff0000, v5
	v_fmac_f32_e32 v56, v2, v23
	v_mul_f32_e32 v2, v182, v214
	s_waitcnt lgkmcnt(0)
	v_mov_b32_e32 v16, v14
	s_nop 1
	v_permlane16_swap_b32_e32 v16, v14
	v_add_f32_e32 v14, v14, v16
	v_fmac_f32_e32 v15, v217, v217
	v_fmac_f32_e32 v245, v2, v24
	v_mul_f32_e32 v2, v182, v5
	v_fmac_f32_e32 v15, v56, v56
	v_fmac_f32_e32 v57, v2, v25
	v_fmac_f32_e32 v15, v245, v245
	v_fmac_f32_e32 v15, v57, v57
	s_waitcnt lgkmcnt(0)
	v_mov_b32_e32 v16, v14
	s_nop 1
	v_permlane32_swap_b32_e32 v16, v14
	v_add_f32_e32 v14, v14, v16
	v_fmamk_f32 v14, v14, 0x39800000, v168
	v_cvt_pk_bf16_f32 v6, v218, v66
	v_cvt_pk_bf16_f32 v7, v219, v67
	v_cvt_pk_bf16_f32 v8, v220, v68
	v_cvt_pk_bf16_f32 v9, v221, v69
	v_cvt_pk_bf16_f32 v2, v215, v54
	v_cvt_pk_bf16_f32 v3, v216, v55
	v_cvt_pk_bf16_f32 v4, v217, v56
	v_mul_f32_e32 v16, 0x4f800000, v14
	v_cmp_gt_f32_e32 vcc, s70, v14
	v_cvt_pk_bf16_f32 v5, v245, v57
	global_store_dwordx4 v167, v[2:5], s[4:5]
	v_cvt_pk_bf16_f32 v23, v215, v54
	v_cvt_pk_bf16_f32 v25, v216, v55
	v_cvt_pk_bf16_f32 v179, v217, v56
	s_nop 0
	v_cndmask_b32_e32 v14, v14, v16, vcc
	v_sqrt_f32_e32 v16, v14
	s_waitcnt lgkmcnt(0)
	s_nop 1
	v_add_f32_dpp v4, v15, v15 quad_perm:[1,0,3,2] row_mask:0xf bank_mask:0xf
	v_cvt_pk_bf16_f32 v178, v245, v57
	v_add_u32_e32 v2, -1, v16
	v_fma_f32 v3, -v2, v16, v14
	v_cmp_ge_f32_e64 s[2:3], 0, v3
	s_waitcnt lgkmcnt(0)
	s_nop 1
	v_add_f32_dpp v4, v4, v4 quad_perm:[2,3,0,1] row_mask:0xf bank_mask:0xf
	v_add_u32_e32 v3, 1, v16
	v_fma_f32 v15, -v3, v16, v14
	v_cndmask_b32_e64 v2, v16, v2, s[2:3]
	v_cmp_lt_f32_e64 s[2:3], 0, v15
	s_nop 1
	v_cndmask_b32_e64 v2, v2, v3, s[2:3]
	v_mul_f32_e32 v3, 0x37800000, v2
	v_cndmask_b32_e32 v2, v2, v3, vcc
	s_waitcnt lgkmcnt(0)
	s_nop 1
	v_add_f32_dpp v3, v4, v4 row_half_mirror row_mask:0xf bank_mask:0xf
	v_cmp_class_f32_e32 vcc, v14, v169
	s_waitcnt lgkmcnt(0)
	s_nop 1
	v_add_f32_dpp v3, v3, v3 row_mirror row_mask:0xf bank_mask:0xf
	v_cndmask_b32_e32 v2, v2, v14, vcc
	v_div_scale_f32 v5, s[2:3], v2, v2, 1.0
	v_rcp_f32_e32 v14, v5
	s_waitcnt lgkmcnt(0)
	v_mov_b32_e32 v4, v3
	s_nop 1
	v_permlane16_swap_b32_e32 v4, v3
	v_add_f32_e32 v3, v3, v4
	v_fma_f32 v15, -v5, v14, 1.0
	v_fmac_f32_e32 v14, v15, v14
	v_div_scale_f32 v15, vcc, 1.0, v2, 1.0
	s_waitcnt lgkmcnt(0)
	v_mov_b32_e32 v4, v3
	s_nop 1
	v_permlane32_swap_b32_e32 v4, v3
	v_add_f32_e32 v3, v3, v4
	v_fmamk_f32 v3, v3, 0x39800000, v168
	v_mul_f32_e32 v4, 0x4f800000, v3
	v_cmp_gt_f32_e64 s[2:3], s70, v3
	v_mul_f32_e32 v16, v15, v14
	v_fma_f32 v17, -v5, v16, v15
	v_cndmask_b32_e64 v3, v3, v4, s[2:3]
	v_sqrt_f32_e32 v4, v3
	v_fmac_f32_e32 v16, v17, v14
	v_fma_f32 v5, -v5, v16, v15
	v_div_fmas_f32 v5, v5, v14, v16
	v_add_u32_e32 v15, -1, v4
	v_fma_f32 v17, -v15, v4, v3
	v_cmp_ge_f32_e64 s[4:5], 0, v17
	v_add_u32_e32 v17, 1, v4
	v_div_fixup_f32 v176, v5, v2, 1.0
	v_cndmask_b32_e64 v15, v4, v15, s[4:5]
	v_fma_f32 v4, -v17, v4, v3
	v_cmp_lt_f32_e64 s[4:5], 0, v4
	s_nop 1
	v_cndmask_b32_e64 v4, v15, v17, s[4:5]
	v_mul_f32_e32 v15, 0x37800000, v4
	v_cndmask_b32_e64 v4, v4, v15, s[2:3]
	v_cmp_class_f32_e64 s[2:3], v3, v169
	s_nop 1
	v_cndmask_b32_e64 v3, v4, v3, s[2:3]
	v_div_scale_f32 v4, s[2:3], v3, v3, 1.0
	v_rcp_f32_e32 v15, v4
	s_nop 0
	v_fma_f32 v2, -v4, v15, 1.0
	v_fmac_f32_e32 v15, v2, v15
	v_div_scale_f32 v2, vcc, 1.0, v3, 1.0
	v_mul_f32_e32 v5, v2, v15
	v_fma_f32 v14, -v4, v5, v2
	v_fmac_f32_e32 v5, v14, v15
	v_fma_f32 v2, -v4, v5, v2
	v_div_fmas_f32 v2, v2, v15, v5
	v_div_fixup_f32 v177, v2, v3, 1.0
	s_and_saveexec_b64 s[2:3], s[0:1]
	s_cbranch_execz .LBB0_1611
	s_lshl_b64 s[4:5], s[38:39], 2
	s_add_u32 s4, s61, s4
	s_addc_u32 s5, s62, s5
	global_store_dword v170, v176, s[46:47]
	global_store_dword v131, v177, s[4:5]
.LBB0_1611:
	s_or_b64 exec, exec, s[2:3]
	v_lshlrev_b32_e32 v124, 16, v106
	v_and_b32_e32 v125, 0xffff0000, v106
	v_lshlrev_b32_e32 v126, 16, v107
	v_and_b32_e32 v127, 0xffff0000, v107
	v_max3_f32 v14, |v124|, 0, |v125|
	v_lshlrev_b32_e32 v4, 16, v108
	v_and_b32_e32 v5, 0xffff0000, v108
	v_max3_f32 v14, v14, |v126|, |v127|
	v_lshlrev_b32_e32 v2, 16, v114
	v_and_b32_e32 v173, 0xffff0000, v114
	v_lshlrev_b32_e32 v118, 16, v109
	v_and_b32_e32 v119, 0xffff0000, v109
	v_max3_f32 v14, v14, |v4|, |v5|
	v_lshlrev_b32_e32 v174, 16, v115
	v_and_b32_e32 v175, 0xffff0000, v115
	v_max3_f32 v22, v14, |v118|, |v119|
	v_max3_f32 v14, |v2|, 0, |v173|
	v_lshlrev_b32_e32 v3, 16, v116
	v_and_b32_e32 v156, 0xffff0000, v116
	v_max3_f32 v14, v14, |v174|, |v175|
	v_lshlrev_b32_e32 v157, 16, v117
	v_and_b32_e32 v172, 0xffff0000, v117
	v_max3_f32 v14, v14, |v3|, |v156|
	v_max3_f32 v24, v14, |v157|, |v172|
	v_lshlrev_b32_e32 v128, 16, v94
	v_and_b32_e32 v129, 0xffff0000, v94
	v_lshlrev_b32_e32 v154, 16, v95
	v_and_b32_e32 v155, 0xffff0000, v95
	v_lshlrev_b32_e32 v114, 16, v98
	v_and_b32_e32 v115, 0xffff0000, v98
	v_max3_f32 v24, v24, |v128|, |v129|
	v_lshlrev_b32_e32 v120, 16, v96
	v_and_b32_e32 v121, 0xffff0000, v96
	v_lshlrev_b32_e32 v116, 16, v99
	v_and_b32_e32 v117, 0xffff0000, v99
	v_max3_f32 v22, v22, |v114|, |v115|
	v_max3_f32 v24, v24, |v154|, |v155|
	v_lshlrev_b32_e32 v122, 16, v97
	v_and_b32_e32 v123, 0xffff0000, v97
	v_lshlrev_b32_e32 v14, 16, v100
	v_and_b32_e32 v15, 0xffff0000, v100
	v_max3_f32 v22, v22, |v116|, |v117|
	v_max3_f32 v24, v24, |v120|, |v121|
	v_lshlrev_b32_e32 v16, 16, v101
	v_and_b32_e32 v17, 0xffff0000, v101
	v_max3_f32 v22, v22, |v14|, |v15|
	v_max3_f32 v24, v24, |v122|, |v123|
	v_lshlrev_b32_e32 v110, 16, v86
	v_and_b32_e32 v111, 0xffff0000, v86
	v_max3_f32 v22, v22, |v16|, |v17|
	v_lshlrev_b32_e32 v112, 16, v87
	v_and_b32_e32 v113, 0xffff0000, v87
	v_lshlrev_b32_e32 v98, 16, v78
	v_and_b32_e32 v99, 0xffff0000, v78
	v_max3_f32 v24, v24, |v110|, |v111|
	v_lshlrev_b32_e32 v106, 16, v88
	v_and_b32_e32 v107, 0xffff0000, v88
	v_lshlrev_b32_e32 v100, 16, v79
	v_and_b32_e32 v101, 0xffff0000, v79
	v_max3_f32 v22, v22, |v98|, |v99|
	v_max3_f32 v24, v24, |v112|, |v113|
	v_lshlrev_b32_e32 v108, 16, v89
	v_and_b32_e32 v109, 0xffff0000, v89
	v_lshlrev_b32_e32 v90, 16, v80
	v_and_b32_e32 v91, 0xffff0000, v80
	v_max3_f32 v22, v22, |v100|, |v101|
	v_max3_f32 v24, v24, |v106|, |v107|
	v_lshlrev_b32_e32 v92, 16, v81
	v_and_b32_e32 v93, 0xffff0000, v81
	v_max3_f32 v22, v22, |v90|, |v91|
	v_max3_f32 v24, v24, |v108|, |v109|
	v_lshlrev_b32_e32 v102, 16, v70
	v_and_b32_e32 v103, 0xffff0000, v70
	v_max3_f32 v22, v22, |v92|, |v93|
	v_lshlrev_b32_e32 v104, 16, v71
	v_and_b32_e32 v105, 0xffff0000, v71
	v_lshlrev_b32_e32 v86, 16, v58
	v_and_b32_e32 v87, 0xffff0000, v58
	v_max3_f32 v24, v24, |v102|, |v103|
	v_lshlrev_b32_e32 v94, 16, v72
	v_and_b32_e32 v95, 0xffff0000, v72
	v_lshlrev_b32_e32 v88, 16, v59
	v_and_b32_e32 v89, 0xffff0000, v59
	v_max3_f32 v22, v22, |v86|, |v87|
	v_max3_f32 v24, v24, |v104|, |v105|
	v_lshlrev_b32_e32 v96, 16, v73
	v_and_b32_e32 v97, 0xffff0000, v73
	v_lshlrev_b32_e32 v82, 16, v60
	v_and_b32_e32 v83, 0xffff0000, v60
	v_max3_f32 v22, v22, |v88|, |v89|
	v_max3_f32 v24, v24, |v94|, |v95|
	v_lshlrev_b32_e32 v84, 16, v61
	v_and_b32_e32 v85, 0xffff0000, v61
	v_max3_f32 v22, v22, |v82|, |v83|
	v_max3_f32 v24, v24, |v96|, |v97|
	v_lshlrev_b32_e32 v78, 16, v46
	v_and_b32_e32 v79, 0xffff0000, v46
	v_max3_f32 v22, v22, |v84|, |v85|
	v_lshlrev_b32_e32 v80, 16, v47
	v_and_b32_e32 v81, 0xffff0000, v47
	v_lshlrev_b32_e32 v66, 16, v38
	v_and_b32_e32 v67, 0xffff0000, v38
	v_max3_f32 v24, v24, |v78|, |v79|
	v_lshlrev_b32_e32 v74, 16, v48
	v_and_b32_e32 v75, 0xffff0000, v48
	v_lshlrev_b32_e32 v68, 16, v39
	v_and_b32_e32 v69, 0xffff0000, v39
	v_max3_f32 v22, v22, |v66|, |v67|
	v_max3_f32 v24, v24, |v80|, |v81|
	v_lshlrev_b32_e32 v76, 16, v49
	v_and_b32_e32 v77, 0xffff0000, v49
	v_lshlrev_b32_e32 v58, 16, v40
	v_and_b32_e32 v59, 0xffff0000, v40
	v_max3_f32 v22, v22, |v68|, |v69|
	v_max3_f32 v24, v24, |v74|, |v75|
	v_lshlrev_b32_e32 v60, 16, v41
	v_and_b32_e32 v61, 0xffff0000, v41
	v_max3_f32 v22, v22, |v58|, |v59|
	v_max3_f32 v24, v24, |v76|, |v77|
	v_lshlrev_b32_e32 v70, 16, v34
	v_and_b32_e32 v71, 0xffff0000, v34
	v_max3_f32 v22, v22, |v60|, |v61|
	v_lshlrev_b32_e32 v72, 16, v35
	v_and_b32_e32 v73, 0xffff0000, v35
	v_lshlrev_b32_e32 v54, 16, v26
	v_and_b32_e32 v55, 0xffff0000, v26
	v_max3_f32 v24, v24, |v70|, |v71|
	v_lshlrev_b32_e32 v62, 16, v36
	v_and_b32_e32 v63, 0xffff0000, v36
	v_lshlrev_b32_e32 v56, 16, v27
	v_and_b32_e32 v57, 0xffff0000, v27
	v_max3_f32 v22, v22, |v54|, |v55|
	v_max3_f32 v24, v24, |v72|, |v73|
	v_lshlrev_b32_e32 v64, 16, v37
	v_and_b32_e32 v65, 0xffff0000, v37
	v_lshlrev_b32_e32 v50, 16, v28
	v_and_b32_e32 v51, 0xffff0000, v28
	v_max3_f32 v22, v22, |v56|, |v57|
	v_max3_f32 v24, v24, |v62|, |v63|
	v_lshlrev_b32_e32 v52, 16, v29
	v_and_b32_e32 v53, 0xffff0000, v29
	v_max3_f32 v22, v22, |v50|, |v51|
	v_max3_f32 v24, v24, |v64|, |v65|
	v_lshlrev_b32_e32 v46, 16, v18
	v_and_b32_e32 v47, 0xffff0000, v18
	v_max3_f32 v22, v22, |v52|, |v53|
	v_lshlrev_b32_e32 v48, 16, v19
	v_and_b32_e32 v49, 0xffff0000, v19
	v_lshlrev_b32_e32 v34, 16, v10
	v_and_b32_e32 v35, 0xffff0000, v10
	v_lshlrev_b32_e32 v36, 16, v11
	v_and_b32_e32 v37, 0xffff0000, v11
	v_max3_f32 v11, v24, |v46|, |v47|
	v_lshlrev_b32_e32 v42, 16, v20
	v_and_b32_e32 v43, 0xffff0000, v20
	v_max3_f32 v10, v22, |v34|, |v35|
	v_max3_f32 v11, v11, |v48|, |v49|
	v_lshlrev_b32_e32 v44, 16, v21
	v_and_b32_e32 v45, 0xffff0000, v21
	v_lshlrev_b32_e32 v26, 16, v12
	v_and_b32_e32 v27, 0xffff0000, v12
	v_max3_f32 v10, v10, |v36|, |v37|
	v_max3_f32 v11, v11, |v42|, |v43|
	v_lshlrev_b32_e32 v28, 16, v13
	v_and_b32_e32 v29, 0xffff0000, v13
	v_max3_f32 v10, v10, |v26|, |v27|
	v_max3_f32 v11, v11, |v44|, |v45|
	v_lshlrev_b32_e32 v38, 16, v6
	v_and_b32_e32 v39, 0xffff0000, v6
	v_max3_f32 v10, v10, |v28|, |v29|
	v_lshlrev_b32_e32 v40, 16, v7
	v_and_b32_e32 v41, 0xffff0000, v7
	v_lshlrev_b32_e32 v22, 16, v23
	v_and_b32_e32 v23, 0xffff0000, v23
	v_max3_f32 v7, v11, |v38|, |v39|
	v_lshlrev_b32_e32 v30, 16, v8
	v_and_b32_e32 v31, 0xffff0000, v8
	v_lshlrev_b32_e32 v24, 16, v25
	v_and_b32_e32 v25, 0xffff0000, v25
	v_max3_f32 v6, v10, |v22|, |v23|
	v_max3_f32 v7, v7, |v40|, |v41|
	v_lshlrev_b32_e32 v32, 16, v9
	v_and_b32_e32 v33, 0xffff0000, v9
	v_lshlrev_b32_e32 v18, 16, v179
	v_and_b32_e32 v19, 0xffff0000, v179
	v_max3_f32 v6, v6, |v24|, |v25|
	v_max3_f32 v7, v7, |v30|, |v31|
	v_lshlrev_b32_e32 v20, 16, v178
	v_and_b32_e32 v21, 0xffff0000, v178
	v_max3_f32 v7, v7, |v32|, |v33|
	v_max3_f32 v6, v6, |v18|, |v19|
	v_max3_f32 v6, v6, |v20|, |v21|
	s_cmp_gt_i32 s14, -1
	s_cselect_b64 s[48:49], -1, 0
	s_waitcnt lgkmcnt(0)
	s_nop 1
	v_max_f32_dpp v7, v7, v7 quad_perm:[1,0,3,2] row_mask:0xf bank_mask:0xf
	s_waitcnt lgkmcnt(0)
	s_nop 1
	v_max_f32_dpp v6, v6, v6 quad_perm:[1,0,3,2] row_mask:0xf bank_mask:0xf
	s_lshl_b64 s[2:3], s[14:15], 12
	s_add_u32 s4, s54, s2
	s_waitcnt lgkmcnt(0)
	s_nop 1
	v_max_f32_dpp v7, v7, v7 quad_perm:[2,3,0,1] row_mask:0xf bank_mask:0xf
	s_waitcnt lgkmcnt(0)
	s_nop 1
	v_max_f32_dpp v6, v6, v6 quad_perm:[2,3,0,1] row_mask:0xf bank_mask:0xf
	s_addc_u32 s5, s55, s3
	s_and_b64 s[2:3], s[48:49], exec
	s_waitcnt lgkmcnt(0)
	s_nop 1
	v_max_f32_dpp v7, v7, v7 row_half_mirror row_mask:0xf bank_mask:0xf
	s_waitcnt lgkmcnt(0)
	s_nop 1
	v_max_f32_dpp v6, v6, v6 row_half_mirror row_mask:0xf bank_mask:0xf
	s_cselect_b32 s3, s5, 0
	s_cselect_b32 s2, s4, 0
	s_waitcnt lgkmcnt(0)
	s_nop 1
	v_max_f32_dpp v7, v7, v7 row_mirror row_mask:0xf bank_mask:0xf
	s_waitcnt lgkmcnt(0)
	s_nop 1
	v_max_f32_dpp v6, v6, v6 row_mirror row_mask:0xf bank_mask:0xf
	s_cmp_gt_i32 s44, -1
	s_mov_b32 s45, s15
	s_waitcnt lgkmcnt(0)
	v_mov_b32_e32 v8, v7
	s_nop 1
	v_permlane16_swap_b32_e32 v8, v7
	v_max_f32_e32 v7, v7, v8
	s_waitcnt lgkmcnt(0)
	v_mov_b32_e32 v9, v6
	s_nop 1
	v_permlane16_swap_b32_e32 v9, v6
	v_max_f32_e32 v6, v6, v9
	ds_bpermute_b32 v9, v163, v6
	s_cselect_b64 s[4:5], -1, 0
	s_lshl_b64 s[50:51], s[44:45], 12
	s_add_u32 s43, s54, s50
	s_addc_u32 s45, s55, s51
	s_waitcnt lgkmcnt(0)
	s_and_b64 s[50:51], s[4:5], exec
	v_mov_b32_e32 v8, v7
	s_nop 1
	v_permlane32_swap_b32_e32 v8, v7
	v_max_f32_e32 v7, v7, v8
	s_waitcnt lgkmcnt(0)
	v_max_f32_e32 v8, v9, v9
	s_cselect_b32 s51, s45, 0
	s_cselect_b32 s50, s43, 0
	v_max_f32_e32 v6, v6, v8
	s_and_saveexec_b64 s[52:53], s[0:1]
	s_cbranch_execz .LBB0_1616
	s_lshl_b64 s[76:77], s[38:39], 2
	s_add_u32 s76, s63, s76
	v_mul_f32_e32 v8, v176, v7
	s_addc_u32 s77, s65, s77
	v_mul_f32_e32 v9, 0x3c010204, v8
	v_mul_f32_e32 v8, v177, v6
	v_mul_f32_e32 v8, 0x3c010204, v8
	s_cmp_eq_u64 s[2:3], 0
	global_store_dword v171, v9, s[46:47]
	global_store_dword v131, v8, s[76:77]
	s_cbranch_scc1 .LBB0_1614
	s_ashr_i32 s47, s14, 31
	s_mov_b32 s46, s14
	s_lshl_b64 s[46:47], s[46:47], 2
	s_add_u32 s14, s56, s46
	s_addc_u32 s43, s57, s47
	s_and_b64 s[46:47], s[48:49], exec
	s_cselect_b32 s47, s43, 0
	s_cselect_b32 s46, s14, 0
	global_store_dword v131, v9, s[46:47]

.LBB0_1632:
	s_cmp_lt_i32 s6, 32
	v_readlane_b32 s65, v252, 37
	v_readlane_b32 s66, v252, 36
	s_cbranch_scc0 .LBB0_1636
	s_ashr_i32 s7, s6, 31
	s_lshl_b64 s[2:3], s[6:7], 12
	s_lshl_b64 s[0:1], s[6:7], 14
	s_add_u32 s4, s8, s0
	s_addc_u32 s5, s9, s1
	s_add_u32 s0, s4, 0x69ac0000
	s_addc_u32 s1, s5, 0
	v_lshlrev_b32_e32 v102, 5, v1
	global_load_dwordx4 v[2:5], v102, s[0:1]
	v_lshlrev_b32_e32 v66, 3, v1
	v_or_b32_e32 v69, 0xe00, v66
	v_lshlrev_b32_e32 v79, 2, v69
	global_load_dwordx4 v[34:37], v79, s[0:1] offset:16
	global_load_dwordx4 v[6:9], v102, s[0:1] offset:16
	global_load_dwordx4 v[14:17], v102, s[0:1] offset:2048
	global_load_dwordx4 v[10:13], v102, s[0:1] offset:2064
	v_or_b32_e32 v103, 0x1000, v102
	global_load_dwordx4 v[22:25], v103, s[0:1]
	global_load_dwordx4 v[18:21], v103, s[0:1] offset:16
	v_or_b32_e32 v104, 0x1800, v102
	global_load_dwordx4 v[30:33], v104, s[0:1]
	global_load_dwordx4 v[26:29], v104, s[0:1] offset:16
	v_or_b32_e32 v72, 0x800, v66
	v_lshlrev_b32_e32 v105, 2, v72
	global_load_dwordx4 v[42:45], v105, s[0:1]
	global_load_dwordx4 v[38:41], v105, s[0:1] offset:16
	v_or_b32_e32 v71, 0xa00, v66
	v_lshlrev_b32_e32 v106, 2, v71
	global_load_dwordx4 v[62:65], v106, s[0:1]
	global_load_dwordx4 v[58:61], v106, s[0:1] offset:16
	v_or_b32_e32 v70, 0xc00, v66
	v_lshlrev_b32_e32 v67, 2, v70
	global_load_dwordx4 v[54:57], v67, s[0:1]
	global_load_dwordx4 v[50:53], v67, s[0:1] offset:16
	global_load_dwordx4 v[46:49], v79, s[0:1]
	s_add_u32 s4, s4, 0x69b40000
	s_addc_u32 s5, s5, 0
	s_add_u32 s10, s10, 0x4000
	s_addc_u32 s11, s11, 0
	global_load_dwordx4 v[82:85], v102, s[4:5] offset:16
	global_load_dwordx4 v[86:89], v102, s[4:5]
	global_load_dwordx4 v[90:93], v102, s[10:11] offset:16
	global_load_dwordx4 v[94:97], v102, s[10:11]
	v_mbcnt_hi_u32_b32 v68, -1, v234
	v_and_b32_e32 v73, 64, v68
	v_xor_b32_e32 v74, 1, v68
	v_add_u32_e32 v80, 64, v73
	v_cmp_lt_i32_e32 vcc, v74, v80
	s_mov_b32 s12, 0xf800000
	v_lshlrev_b32_e32 v72, 1, v72
	v_cndmask_b32_e32 v73, v68, v74, vcc
	v_lshlrev_b32_e32 v73, 2, v73
	v_lshlrev_b32_e32 v71, 1, v71
	v_lshlrev_b32_e32 v70, 1, v70
	s_waitcnt vmcnt(19)
	v_mul_f32_e32 v76, v3, v3
	v_fmac_f32_e32 v76, v2, v2
	v_fmac_f32_e32 v76, v4, v4
	v_fmac_f32_e32 v76, v5, v5
	s_waitcnt vmcnt(17)
	v_fmac_f32_e32 v76, v6, v6
	v_fmac_f32_e32 v76, v7, v7
	v_fmac_f32_e32 v76, v8, v8
	v_fmac_f32_e32 v76, v9, v9
	s_waitcnt vmcnt(16)
	v_fmac_f32_e32 v76, v14, v14
	v_fmac_f32_e32 v76, v15, v15
	v_fmac_f32_e32 v76, v16, v16
	v_fmac_f32_e32 v76, v17, v17
	s_waitcnt vmcnt(15)
	v_fmac_f32_e32 v76, v10, v10
	v_fmac_f32_e32 v76, v11, v11
	v_fmac_f32_e32 v76, v12, v12
	v_fmac_f32_e32 v76, v13, v13
	s_waitcnt vmcnt(14)
	v_fmac_f32_e32 v76, v22, v22
	v_fmac_f32_e32 v76, v23, v23
	v_fmac_f32_e32 v76, v24, v24
	v_fmac_f32_e32 v76, v25, v25
	s_waitcnt vmcnt(13)
	v_fmac_f32_e32 v76, v18, v18
	v_fmac_f32_e32 v76, v19, v19
	v_fmac_f32_e32 v76, v20, v20
	v_fmac_f32_e32 v76, v21, v21
	s_waitcnt vmcnt(12)
	v_fmac_f32_e32 v76, v30, v30
	v_fmac_f32_e32 v76, v31, v31
	v_fmac_f32_e32 v76, v32, v32
	v_fmac_f32_e32 v76, v33, v33
	s_waitcnt vmcnt(11)
	v_fmac_f32_e32 v76, v26, v26
	v_fmac_f32_e32 v76, v27, v27
	v_fmac_f32_e32 v76, v28, v28
	v_fmac_f32_e32 v76, v29, v29
	s_waitcnt vmcnt(10)
	v_fmac_f32_e32 v76, v42, v42
	v_fmac_f32_e32 v76, v43, v43
	v_fmac_f32_e32 v76, v44, v44
	v_fmac_f32_e32 v76, v45, v45
	s_waitcnt vmcnt(9)
	v_fmac_f32_e32 v76, v38, v38
	v_fmac_f32_e32 v76, v39, v39
	v_fmac_f32_e32 v76, v40, v40
	v_fmac_f32_e32 v76, v41, v41
	s_waitcnt vmcnt(8)
	v_fmac_f32_e32 v76, v62, v62
	v_fmac_f32_e32 v76, v63, v63
	v_fmac_f32_e32 v76, v64, v64
	v_fmac_f32_e32 v76, v65, v65
	s_waitcnt vmcnt(7)
	v_fmac_f32_e32 v76, v58, v58
	v_fmac_f32_e32 v76, v59, v59
	v_fmac_f32_e32 v76, v60, v60
	v_fmac_f32_e32 v76, v61, v61
	s_waitcnt vmcnt(6)
	v_fmac_f32_e32 v76, v54, v54
	v_fmac_f32_e32 v76, v55, v55
	v_fmac_f32_e32 v76, v56, v56
	v_fmac_f32_e32 v76, v57, v57
	s_waitcnt vmcnt(5)
	v_fmac_f32_e32 v76, v50, v50
	v_fmac_f32_e32 v76, v51, v51
	v_fmac_f32_e32 v76, v52, v52
	v_fmac_f32_e32 v76, v53, v53
	s_waitcnt vmcnt(4)
	v_fmac_f32_e32 v76, v46, v46
	v_fmac_f32_e32 v76, v47, v47
	v_fmac_f32_e32 v76, v48, v48
	v_fmac_f32_e32 v76, v49, v49
	v_fmac_f32_e32 v76, v34, v34
	v_pk_mul_f32 v[74:75], v[36:37], v[36:37]
	v_fmac_f32_e32 v76, v35, v35
	v_add_f32_e32 v74, v74, v76
	v_add_f32_e32 v74, v75, v74
	v_xor_b32_e32 v76, 2, v68
	v_cmp_lt_i32_e32 vcc, v76, v80
	s_waitcnt lgkmcnt(0)
	s_nop 1
	v_add_f32_dpp v74, v74, v74 quad_perm:[1,0,3,2] row_mask:0xf bank_mask:0xf
	v_cndmask_b32_e32 v76, v68, v76, vcc
	v_lshlrev_b32_e32 v78, 2, v76
	v_xor_b32_e32 v76, 4, v68
	v_cmp_lt_i32_e32 vcc, v76, v80
	s_waitcnt lgkmcnt(0)
	s_nop 1
	v_add_f32_dpp v74, v74, v74 quad_perm:[2,3,0,1] row_mask:0xf bank_mask:0xf
	v_cndmask_b32_e32 v76, v68, v76, vcc
	v_lshlrev_b32_e32 v77, 2, v76
	v_xor_b32_e32 v76, 8, v68
	v_cmp_lt_i32_e32 vcc, v76, v80
	s_waitcnt lgkmcnt(0)
	s_nop 1
	v_add_f32_dpp v74, v74, v74 row_half_mirror row_mask:0xf bank_mask:0xf
	v_cndmask_b32_e32 v76, v68, v76, vcc
	v_lshlrev_b32_e32 v76, 2, v76
	v_xor_b32_e32 v75, 16, v68
	v_cmp_lt_i32_e32 vcc, v75, v80
	s_waitcnt lgkmcnt(0)
	s_nop 1
	v_add_f32_dpp v81, v74, v74 row_mirror row_mask:0xf bank_mask:0xf
	v_cndmask_b32_e32 v75, v68, v75, vcc
	v_lshlrev_b32_e32 v75, 2, v75
	v_xor_b32_e32 v74, 32, v68
	v_cmp_lt_i32_e32 vcc, v74, v80
	s_nop 1
	v_cndmask_b32_e32 v68, v68, v74, vcc
	v_lshlrev_b32_e32 v74, 2, v68
	s_waitcnt lgkmcnt(0)
	v_mov_b32_e32 v68, v81
	v_mov_b32_e32 v98, v81
	s_nop 1
	v_permlane16_swap_b32_e32 v98, v68
	v_add_f32_e32 v68, v68, v98
	v_mov_b32_e32 v81, 0x358637bd
	s_waitcnt lgkmcnt(0)
	v_mov_b32_e32 v80, v68
	s_nop 1
	v_permlane32_swap_b32_e32 v80, v68
	v_add_f32_e32 v68, v68, v80
	v_fmamk_f32 v68, v68, 0x39800000, v81
	v_mul_f32_e32 v80, 0x4f800000, v68
	v_cmp_gt_f32_e32 vcc, s12, v68
	s_nop 1
	v_cndmask_b32_e32 v68, v68, v80, vcc
	v_sqrt_f32_e32 v98, v68
	v_mov_b32_e32 v80, 0x260
	v_add_u32_e32 v99, -1, v98
	v_add_u32_e32 v100, 1, v98
	v_fma_f32 v101, -v99, v98, v68
	v_fma_f32 v107, -v100, v98, v68
	v_cmp_ge_f32_e64 s[0:1], 0, v101
	s_nop 1
	v_cndmask_b32_e64 v98, v98, v99, s[0:1]
	v_cmp_lt_f32_e64 s[0:1], 0, v107
	v_or_b32_e32 v107, 0x800, v102
	s_nop 0
	v_cndmask_b32_e64 v98, v98, v100, s[0:1]
	v_mul_f32_e32 v99, 0x37800000, v98
	v_cndmask_b32_e32 v98, v98, v99, vcc
	v_cmp_class_f32_e32 vcc, v68, v80
	s_nop 1
	v_cndmask_b32_e32 v68, v98, v68, vcc
	v_div_scale_f32 v98, s[0:1], v68, v68, 1.0
	v_rcp_f32_e32 v99, v98
	v_div_scale_f32 v100, vcc, 1.0, v68, 1.0
	s_lshl_b64 s[0:1], s[6:7], 13
	v_fma_f32 v101, -v98, v99, 1.0
	v_fmac_f32_e32 v99, v101, v99
	v_mul_f32_e32 v101, v100, v99
	v_fma_f32 v108, -v98, v101, v100
	v_fmac_f32_e32 v101, v108, v99
	v_fma_f32 v98, -v98, v101, v100
	v_div_fmas_f32 v98, v98, v99, v101
	v_div_fixup_f32 v68, v98, v68, 1.0
	v_pk_mul_f32 v[2:3], v[2:3], v[68:69] op_sel_hi:[1,0]
	v_pk_mul_f32 v[4:5], v[4:5], v[68:69] op_sel_hi:[1,0]
	v_pk_mul_f32 v[98:99], v[6:7], v[68:69] op_sel_hi:[1,0]
	v_pk_mul_f32 v[100:101], v[8:9], v[68:69] op_sel_hi:[1,0]
	s_waitcnt vmcnt(0)
	v_pk_fma_f32 v[6:7], v[94:95], v[2:3], v[86:87]
	v_pk_fma_f32 v[8:9], v[96:97], v[4:5], v[88:89]
	v_pk_fma_f32 v[2:3], v[90:91], v[98:99], v[82:83]
	v_pk_fma_f32 v[4:5], v[92:93], v[100:101], v[84:85]
	global_store_dwordx4 v102, v[6:9], s[4:5]
	global_store_dwordx4 v102, v[2:5], s[4:5] offset:16
	global_load_dwordx4 v[82:85], v107, s[10:11]
	global_load_dwordx4 v[86:89], v102, s[4:5] offset:2048
	global_load_dwordx4 v[90:93], v102, s[4:5] offset:2064
	global_load_dwordx4 v[94:97], v107, s[10:11] offset:16
	v_pk_mul_f32 v[14:15], v[14:15], v[68:69] op_sel_hi:[1,0]
	v_pk_mul_f32 v[16:17], v[16:17], v[68:69] op_sel_hi:[1,0]
	v_pk_mul_f32 v[10:11], v[10:11], v[68:69] op_sel_hi:[1,0]
	v_pk_mul_f32 v[12:13], v[12:13], v[68:69] op_sel_hi:[1,0]
	v_pk_mul_f32 v[22:23], v[22:23], v[68:69] op_sel_hi:[1,0]
	v_pk_mul_f32 v[24:25], v[24:25], v[68:69] op_sel_hi:[1,0]
	v_pk_mul_f32 v[18:19], v[18:19], v[68:69] op_sel_hi:[1,0]
	v_pk_mul_f32 v[20:21], v[20:21], v[68:69] op_sel_hi:[1,0]
	v_pk_mul_f32 v[30:31], v[30:31], v[68:69] op_sel_hi:[1,0]
	v_pk_mul_f32 v[32:33], v[32:33], v[68:69] op_sel_hi:[1,0]
	v_pk_mul_f32 v[26:27], v[26:27], v[68:69] op_sel_hi:[1,0]
	v_pk_mul_f32 v[28:29], v[28:29], v[68:69] op_sel_hi:[1,0]
	v_pk_mul_f32 v[42:43], v[42:43], v[68:69] op_sel_hi:[1,0]
	v_pk_mul_f32 v[44:45], v[44:45], v[68:69] op_sel_hi:[1,0]
	v_pk_mul_f32 v[38:39], v[38:39], v[68:69] op_sel_hi:[1,0]
	v_pk_mul_f32 v[40:41], v[40:41], v[68:69] op_sel_hi:[1,0]
	v_pk_mul_f32 v[62:63], v[62:63], v[68:69] op_sel_hi:[1,0]
	v_pk_mul_f32 v[64:65], v[64:65], v[68:69] op_sel_hi:[1,0]
	v_pk_mul_f32 v[58:59], v[58:59], v[68:69] op_sel_hi:[1,0]
	v_pk_mul_f32 v[60:61], v[60:61], v[68:69] op_sel_hi:[1,0]
	v_pk_mul_f32 v[54:55], v[54:55], v[68:69] op_sel_hi:[1,0]
	v_pk_mul_f32 v[56:57], v[56:57], v[68:69] op_sel_hi:[1,0]
	v_pk_mul_f32 v[50:51], v[50:51], v[68:69] op_sel_hi:[1,0]
	v_pk_mul_f32 v[52:53], v[52:53], v[68:69] op_sel_hi:[1,0]
	v_pk_mul_f32 v[108:109], v[48:49], v[68:69] op_sel_hi:[1,0]
	v_pk_mul_f32 v[110:111], v[34:35], v[68:69] op_sel_hi:[1,0]
	v_pk_mul_f32 v[112:113], v[36:37], v[68:69] op_sel_hi:[1,0]
	v_pk_mul_f32 v[114:115], v[6:7], v[6:7]
	v_pk_mul_f32 v[116:117], v[8:9], v[8:9]
	v_pk_mul_f32 v[118:119], v[2:3], v[2:3]
	v_pk_mul_f32 v[120:121], v[4:5], v[4:5]
	s_add_u32 s0, s8, s0
	s_addc_u32 s1, s9, s1
	s_add_u32 s8, s0, 0x69900000
	s_addc_u32 s9, s1, 0
	s_waitcnt vmcnt(2)
	v_pk_fma_f32 v[14:15], v[82:83], v[14:15], v[86:87]
	v_pk_fma_f32 v[16:17], v[84:85], v[16:17], v[88:89]
	s_waitcnt vmcnt(0)
	v_pk_fma_f32 v[10:11], v[94:95], v[10:11], v[90:91]
	v_pk_fma_f32 v[12:13], v[96:97], v[12:13], v[92:93]
	global_store_dwordx4 v102, v[14:17], s[4:5] offset:2048
	global_store_dwordx4 v102, v[10:13], s[4:5] offset:2064
	global_load_dwordx4 v[82:85], v103, s[10:11]
	global_load_dwordx4 v[86:89], v103, s[4:5]
	global_load_dwordx4 v[90:93], v103, s[4:5] offset:16
	global_load_dwordx4 v[94:97], v103, s[10:11] offset:16
	s_waitcnt vmcnt(2)
	v_pk_fma_f32 v[22:23], v[82:83], v[22:23], v[86:87]
	v_pk_fma_f32 v[24:25], v[84:85], v[24:25], v[88:89]
	s_waitcnt vmcnt(0)
	v_pk_fma_f32 v[18:19], v[94:95], v[18:19], v[90:91]
	v_pk_fma_f32 v[20:21], v[96:97], v[20:21], v[92:93]
	global_store_dwordx4 v103, v[22:25], s[4:5]
	global_store_dwordx4 v103, v[18:21], s[4:5] offset:16
	global_load_dwordx4 v[82:85], v104, s[10:11]
	global_load_dwordx4 v[86:89], v104, s[4:5]
	global_load_dwordx4 v[90:93], v104, s[4:5] offset:16
	global_load_dwordx4 v[94:97], v104, s[10:11] offset:16
	s_waitcnt vmcnt(2)
	v_pk_fma_f32 v[30:31], v[82:83], v[30:31], v[86:87]
	v_pk_fma_f32 v[32:33], v[84:85], v[32:33], v[88:89]
	s_waitcnt vmcnt(0)
	v_pk_fma_f32 v[26:27], v[94:95], v[26:27], v[90:91]
	v_pk_fma_f32 v[28:29], v[96:97], v[28:29], v[92:93]
	global_store_dwordx4 v104, v[30:33], s[4:5]
	global_store_dwordx4 v104, v[26:29], s[4:5] offset:16
	global_load_dwordx4 v[82:85], v105, s[10:11]
	global_load_dwordx4 v[86:89], v105, s[4:5]
	global_load_dwordx4 v[90:93], v105, s[4:5] offset:16
	global_load_dwordx4 v[94:97], v105, s[10:11] offset:16
	s_waitcnt vmcnt(2)
	v_pk_fma_f32 v[42:43], v[82:83], v[42:43], v[86:87]
	v_pk_fma_f32 v[44:45], v[84:85], v[44:45], v[88:89]
	s_waitcnt vmcnt(0)
	v_pk_fma_f32 v[38:39], v[94:95], v[38:39], v[90:91]
	v_pk_fma_f32 v[40:41], v[96:97], v[40:41], v[92:93]
	global_store_dwordx4 v105, v[42:45], s[4:5]
	global_store_dwordx4 v105, v[38:41], s[4:5] offset:16
	global_load_dwordx4 v[82:85], v106, s[10:11]
	global_load_dwordx4 v[86:89], v106, s[4:5]
	global_load_dwordx4 v[90:93], v106, s[4:5] offset:16
	global_load_dwordx4 v[94:97], v106, s[10:11] offset:16
	s_waitcnt vmcnt(2)
	v_pk_fma_f32 v[62:63], v[82:83], v[62:63], v[86:87]
	v_pk_fma_f32 v[64:65], v[84:85], v[64:65], v[88:89]
	s_waitcnt vmcnt(0)
	v_pk_fma_f32 v[58:59], v[94:95], v[58:59], v[90:91]
	v_pk_fma_f32 v[60:61], v[96:97], v[60:61], v[92:93]
	global_store_dwordx4 v106, v[62:65], s[4:5]
	global_store_dwordx4 v106, v[58:61], s[4:5] offset:16
	global_load_dwordx4 v[82:85], v67, s[10:11]
	global_load_dwordx4 v[86:89], v67, s[4:5]
	global_load_dwordx4 v[90:93], v67, s[4:5] offset:16
	global_load_dwordx4 v[94:97], v67, s[10:11] offset:16
	global_load_dwordx4 v[98:101], v79, s[4:5] offset:16
	global_load_dwordx4 v[102:105], v79, s[4:5]
	v_pk_mul_f32 v[106:107], v[46:47], v[68:69] op_sel_hi:[1,0]
	s_waitcnt vmcnt(4)
	v_pk_fma_f32 v[46:47], v[82:83], v[54:55], v[86:87]
	v_pk_fma_f32 v[48:49], v[84:85], v[56:57], v[88:89]
	s_waitcnt vmcnt(2)
	v_pk_fma_f32 v[34:35], v[94:95], v[50:51], v[90:91]
	v_pk_fma_f32 v[36:37], v[96:97], v[52:53], v[92:93]
	global_store_dwordx4 v67, v[46:49], s[4:5]
	global_store_dwordx4 v67, v[34:37], s[4:5] offset:16
	global_load_dwordx4 v[50:53], v79, s[10:11] offset:16
	global_load_dwordx4 v[54:57], v79, s[10:11]
	v_add_f32_e32 v67, v114, v115
	v_add_f32_e32 v67, v116, v67
	v_add_f32_e32 v67, v117, v67
	v_add_f32_e32 v67, v118, v67
	v_add_f32_e32 v67, v119, v67
	v_add_f32_e32 v67, v120, v67
	v_add_f32_e32 v67, v121, v67
	v_pk_mul_f32 v[82:83], v[14:15], v[14:15]
	v_pk_mul_f32 v[84:85], v[16:17], v[16:17]
	v_add_f32_e32 v67, v82, v67
	v_add_f32_e32 v67, v83, v67
	v_add_f32_e32 v67, v84, v67
	v_pk_mul_f32 v[86:87], v[10:11], v[10:11]
	v_add_f32_e32 v67, v85, v67
	v_add_f32_e32 v67, v86, v67
	v_pk_mul_f32 v[88:89], v[12:13], v[12:13]
	v_add_f32_e32 v67, v87, v67
	v_add_f32_e32 v67, v88, v67
	v_add_f32_e32 v67, v89, v67
	v_pk_mul_f32 v[82:83], v[22:23], v[22:23]
	v_pk_mul_f32 v[84:85], v[24:25], v[24:25]
	v_add_f32_e32 v67, v82, v67
	v_add_f32_e32 v67, v83, v67
	v_add_f32_e32 v67, v84, v67
	v_pk_mul_f32 v[86:87], v[18:19], v[18:19]
	v_add_f32_e32 v67, v85, v67
	v_add_f32_e32 v67, v86, v67
	v_pk_mul_f32 v[88:89], v[20:21], v[20:21]
	v_add_f32_e32 v67, v87, v67
	v_add_f32_e32 v67, v88, v67
	v_add_f32_e32 v67, v89, v67
	v_pk_mul_f32 v[82:83], v[30:31], v[30:31]
	v_pk_mul_f32 v[84:85], v[32:33], v[32:33]
	v_add_f32_e32 v67, v82, v67
	v_add_f32_e32 v67, v83, v67
	v_add_f32_e32 v67, v84, v67
	v_pk_mul_f32 v[86:87], v[26:27], v[26:27]
	v_add_f32_e32 v67, v85, v67
	v_add_f32_e32 v67, v86, v67
	v_pk_mul_f32 v[88:89], v[28:29], v[28:29]
	v_add_f32_e32 v67, v87, v67
	v_add_f32_e32 v67, v88, v67
	v_add_f32_e32 v67, v89, v67
	v_pk_mul_f32 v[82:83], v[42:43], v[42:43]
	v_pk_mul_f32 v[84:85], v[44:45], v[44:45]
	v_add_f32_e32 v67, v82, v67
	v_add_f32_e32 v67, v83, v67
	v_add_f32_e32 v67, v84, v67
	v_pk_mul_f32 v[86:87], v[38:39], v[38:39]
	v_add_f32_e32 v67, v85, v67
	v_add_f32_e32 v67, v86, v67
	v_pk_mul_f32 v[88:89], v[40:41], v[40:41]
	v_add_f32_e32 v67, v87, v67
	v_add_f32_e32 v67, v88, v67
	v_add_f32_e32 v67, v89, v67
	v_pk_mul_f32 v[82:83], v[62:63], v[62:63]
	v_pk_mul_f32 v[84:85], v[64:65], v[64:65]
	v_add_f32_e32 v67, v82, v67
	v_add_f32_e32 v67, v83, v67
	v_add_f32_e32 v67, v84, v67
	v_pk_mul_f32 v[86:87], v[58:59], v[58:59]
	v_add_f32_e32 v67, v85, v67
	v_add_f32_e32 v67, v86, v67
	v_pk_mul_f32 v[88:89], v[60:61], v[60:61]
	v_add_f32_e32 v67, v87, v67
	v_add_f32_e32 v67, v88, v67
	v_add_f32_e32 v67, v89, v67
	v_pk_mul_f32 v[82:83], v[46:47], v[46:47]
	v_pk_mul_f32 v[84:85], v[48:49], v[48:49]
	v_add_f32_e32 v67, v82, v67
	v_add_f32_e32 v67, v83, v67
	v_add_f32_e32 v67, v84, v67
	v_pk_mul_f32 v[86:87], v[34:35], v[34:35]
	v_add_f32_e32 v67, v85, v67
	v_add_f32_e32 v67, v86, v67
	v_pk_mul_f32 v[88:89], v[36:37], v[36:37]
	v_add_f32_e32 v67, v87, v67
	v_add_f32_e32 v67, v88, v67
	v_add_f32_e32 v67, v89, v67
	s_waitcnt vmcnt(0)
	v_pk_fma_f32 v[54:55], v[54:55], v[106:107], v[102:103]
	v_pk_fma_f32 v[56:57], v[56:57], v[108:109], v[104:105]
	v_pk_mul_f32 v[82:83], v[54:55], v[54:55]
	v_pk_mul_f32 v[84:85], v[56:57], v[56:57]
	v_add_f32_e32 v67, v82, v67
	v_add_f32_e32 v67, v83, v67
	v_pk_fma_f32 v[50:51], v[50:51], v[110:111], v[98:99]
	v_add_f32_e32 v67, v84, v67
	v_pk_mul_f32 v[86:87], v[50:51], v[50:51]
	v_add_f32_e32 v67, v85, v67
	v_pk_fma_f32 v[52:53], v[52:53], v[112:113], v[100:101]
	v_add_f32_e32 v67, v86, v67
	v_pk_mul_f32 v[88:89], v[52:53], v[52:53]
	v_add_f32_e32 v67, v87, v67
	v_add_f32_e32 v67, v88, v67
	v_add_f32_e32 v67, v89, v67
	global_store_dwordx4 v79, v[54:57], s[4:5]
	global_store_dwordx4 v79, v[50:53], s[4:5] offset:16
	s_movk_i32 s10, 0x7fff
	s_waitcnt lgkmcnt(0)
	s_nop 1
	v_add_f32_dpp v67, v67, v67 quad_perm:[1,0,3,2] row_mask:0xf bank_mask:0xf
	s_waitcnt lgkmcnt(0)
	s_nop 1
	v_add_f32_dpp v67, v67, v67 quad_perm:[2,3,0,1] row_mask:0xf bank_mask:0xf
	s_waitcnt lgkmcnt(0)
	s_nop 1
	v_add_f32_dpp v67, v67, v67 row_half_mirror row_mask:0xf bank_mask:0xf
	s_waitcnt lgkmcnt(0)
	s_nop 1
	v_add_f32_dpp v68, v67, v67 row_mirror row_mask:0xf bank_mask:0xf
	v_mov_b32_e32 v67, 0
	s_waitcnt lgkmcnt(0)
	v_mov_b32_e32 v82, v68
	s_nop 1
	v_permlane16_swap_b32_e32 v82, v68
	v_add_f32_e32 v68, v68, v82
	s_waitcnt lgkmcnt(0)
	v_mov_b32_e32 v82, v68
	s_nop 1
	v_permlane32_swap_b32_e32 v82, v68
	v_add_f32_e32 v68, v68, v82
	v_fmac_f32_e32 v81, 0x39800000, v68
	v_mul_f32_e32 v68, 0x4f800000, v81
	v_cmp_gt_f32_e32 vcc, s12, v81
	s_nop 1
	v_cndmask_b32_e32 v68, v81, v68, vcc
	v_sqrt_f32_e32 v81, v68
	s_nop 0
	v_add_u32_e32 v82, -1, v81
	v_add_u32_e32 v83, 1, v81
	v_fma_f32 v84, -v82, v81, v68
	v_fma_f32 v85, -v83, v81, v68
	v_cmp_ge_f32_e64 s[0:1], 0, v84
	s_nop 1
	v_cndmask_b32_e64 v81, v81, v82, s[0:1]
	v_cmp_lt_f32_e64 s[0:1], 0, v85
	s_nop 1
	v_cndmask_b32_e64 v81, v81, v83, s[0:1]
	v_mul_f32_e32 v82, 0x37800000, v81
	v_cndmask_b32_e32 v81, v81, v82, vcc
	v_cmp_class_f32_e32 vcc, v68, v80
	s_nop 1
	v_cndmask_b32_e32 v68, v81, v68, vcc
	v_div_scale_f32 v80, s[0:1], v68, v68, 1.0
	v_rcp_f32_e32 v81, v80
	v_div_scale_f32 v79, vcc, 1.0, v68, 1.0
	v_fma_f32 v82, -v80, v81, 1.0
	v_fmac_f32_e32 v81, v82, v81
	v_mul_f32_e32 v82, v79, v81
	v_fma_f32 v83, -v80, v82, v79
	v_fmac_f32_e32 v82, v83, v81
	v_fma_f32 v79, -v80, v82, v79
	v_div_fmas_f32 v79, v79, v81, v82
	v_div_fixup_f32 v68, v79, v68, 1.0
	v_mul_f32_e32 v6, v6, v68
	v_mul_f32_e32 v7, v7, v68
	v_mul_f32_e32 v8, v8, v68
	v_mul_f32_e32 v9, v9, v68
	v_mul_f32_e32 v17, v17, v68
	v_mul_f32_e32 v21, v21, v68
	v_mul_f32_e32 v88, v26, v68
	v_mul_f32_e32 v89, v27, v68
	v_mul_f32_e32 v96, v38, v68
	v_mul_f32_e32 v97, v39, v68
	v_bfe_u32 v26, v6, 16, 1
	v_bfe_u32 v27, v7, 16, 1
	v_mul_f32_e32 v79, v2, v68
	v_mul_f32_e32 v80, v3, v68
	v_mul_f32_e32 v82, v5, v68
	v_mul_f32_e32 v25, v25, v68
	v_mul_f32_e32 v90, v28, v68
	v_mul_f32_e32 v91, v29, v68
	v_mul_f32_e32 v98, v40, v68
	v_mul_f32_e32 v99, v41, v68
	v_mul_f32_e32 v100, v62, v68
	v_mul_f32_e32 v101, v63, v68
	v_mul_f32_e32 v111, v49, v68
	v_mul_f32_e32 v115, v37, v68
	v_cvt_pk_bf16_f32 v2, v6, v7
	v_cvt_pk_bf16_f32 v3, v8, v9
	v_bfe_u32 v28, v8, 16, 1
	v_bfe_u32 v29, v9, 16, 1
	v_bfe_u32 v37, v17, 16, 1
	v_bfe_u32 v49, v21, 16, 1
	v_bfe_u32 v62, v96, 16, 1
	v_bfe_u32 v63, v97, 16, 1
	v_add3_u32 v6, v6, v26, s10
	v_add3_u32 v7, v7, v27, s10
	v_mul_f32_e32 v81, v4, v68
	v_mul_f32_e32 v14, v14, v68
	v_mul_f32_e32 v15, v15, v68
	v_mul_f32_e32 v16, v16, v68
	v_mul_f32_e32 v84, v30, v68
	v_mul_f32_e32 v85, v31, v68
	v_mul_f32_e32 v87, v33, v68
	v_mul_f32_e32 v92, v42, v68
	v_mul_f32_e32 v93, v43, v68
	v_mul_f32_e32 v95, v45, v68
	v_mul_f32_e32 v102, v64, v68
	v_mul_f32_e32 v103, v65, v68
	v_cvt_pk_bf16_f32 v4, v79, v80
	v_cvt_pk_bf16_f32 v5, v81, v82
	v_bfe_u32 v30, v79, 16, 1
	v_bfe_u32 v31, v80, 16, 1
	v_bfe_u32 v33, v82, 16, 1
	v_bfe_u32 v45, v25, 16, 1
	v_bfe_u32 v64, v98, 16, 1
	v_bfe_u32 v65, v99, 16, 1
	global_store_dwordx4 v130, v[2:5], s[8:9]
	v_add3_u32 v8, v8, v28, s10
	v_add3_u32 v9, v9, v29, s10
	v_cvt_pk_bf16_f32 v2, v14, v15
	v_cvt_pk_bf16_f32 v3, v16, v17
	v_add3_u32 v17, v17, v37, s10
	v_add3_u32 v37, v21, v49, s10
	v_add3_u32 v154, v96, v62, s10
	v_add3_u32 v155, v97, v63, s10
	v_and_b32_e32 v62, 0xffff0000, v6
	v_and_b32_e32 v63, 0xffff0000, v7
	v_mul_f32_e32 v86, v32, v68
	v_mul_f32_e32 v94, v44, v68
	v_mul_f32_e32 v104, v58, v68
	v_mul_f32_e32 v105, v59, v68
	v_bfe_u32 v32, v81, 16, 1
	v_bfe_u32 v58, v92, 16, 1
	v_bfe_u32 v59, v93, 16, 1
	v_add3_u32 v26, v79, v30, s10
	v_add3_u32 v27, v80, v31, s10
	v_add3_u32 v29, v82, v33, s10
	v_add3_u32 v33, v25, v45, s10
	v_add3_u32 v156, v98, v64, s10
	v_add3_u32 v157, v99, v65, s10
	v_and_b32_e32 v64, 0xffff0000, v8
	v_and_b32_e32 v65, 0xffff0000, v9
	v_and_b32_e32 v45, 0xffff0000, v37
	v_max3_f32 v37, |v62|, 0, |v63|
	v_mul_f32_e32 v106, v60, v68
	v_mul_f32_e32 v107, v61, v68
	v_mul_f32_e32 v112, v34, v68
	v_mul_f32_e32 v113, v35, v68
	v_bfe_u32 v34, v14, 16, 1
	v_bfe_u32 v35, v15, 16, 1
	v_bfe_u32 v60, v94, 16, 1
	v_bfe_u32 v61, v95, 16, 1
	v_add3_u32 v28, v81, v32, s10
	v_add3_u32 v150, v92, v58, s10
	v_add3_u32 v151, v93, v59, s10
	v_and_b32_e32 v58, 0xffff0000, v26
	v_and_b32_e32 v59, 0xffff0000, v27
	v_max3_f32 v37, v37, |v64|, |v65|
	v_mul_f32_e32 v10, v10, v68
	v_mul_f32_e32 v11, v11, v68
	v_mul_f32_e32 v114, v36, v68
	v_mul_f32_e32 v116, v54, v68
	v_mul_f32_e32 v117, v55, v68
	v_bfe_u32 v36, v16, 16, 1
	v_bfe_u32 v54, v88, 16, 1
	v_bfe_u32 v55, v89, 16, 1
	v_add3_u32 v14, v14, v34, s10
	v_add3_u32 v15, v15, v35, s10
	v_add3_u32 v152, v94, v60, s10
	v_add3_u32 v153, v95, v61, s10
	v_and_b32_e32 v60, 0xffff0000, v28
	v_and_b32_e32 v61, 0xffff0000, v29
	v_max3_f32 v37, v37, |v58|, |v59|
	v_mul_f32_e32 v12, v12, v68
	v_mul_f32_e32 v13, v13, v68
	v_mul_f32_e32 v118, v56, v68
	v_mul_f32_e32 v119, v57, v68
	v_bfe_u32 v38, v10, 16, 1
	v_bfe_u32 v39, v11, 16, 1
	v_bfe_u32 v56, v90, 16, 1
	v_bfe_u32 v57, v91, 16, 1
	v_add3_u32 v16, v16, v36, s10
	v_add3_u32 v79, v88, v54, s10
	v_add3_u32 v147, v89, v55, s10
	v_and_b32_e32 v54, 0xffff0000, v14
	v_and_b32_e32 v55, 0xffff0000, v15
	v_max3_f32 v37, v37, |v60|, |v61|
	v_mul_f32_e32 v22, v22, v68
	v_mul_f32_e32 v23, v23, v68
	v_mul_f32_e32 v120, v50, v68
	v_mul_f32_e32 v121, v51, v68
	v_bfe_u32 v40, v12, 16, 1
	v_bfe_u32 v41, v13, 16, 1
	v_bfe_u32 v50, v84, 16, 1
	v_bfe_u32 v51, v85, 16, 1
	v_cvt_pk_bf16_f32 v4, v10, v11
	v_add3_u32 v10, v10, v38, s10
	v_add3_u32 v11, v11, v39, s10
	v_add3_u32 v148, v90, v56, s10
	v_add3_u32 v149, v91, v57, s10
	v_and_b32_e32 v56, 0xffff0000, v16
	v_and_b32_e32 v57, 0xffff0000, v17
	v_max3_f32 v37, v37, |v54|, |v55|
	v_mul_f32_e32 v24, v24, v68
	v_mul_f32_e32 v18, v18, v68
	v_mul_f32_e32 v19, v19, v68
	v_mul_f32_e32 v20, v20, v68
	v_mul_f32_e32 v108, v46, v68
	v_mul_f32_e32 v109, v47, v68
	v_mul_f32_e32 v110, v48, v68
	v_mul_f32_e32 v122, v52, v68
	v_mul_f32_e32 v68, v53, v68
	v_bfe_u32 v42, v22, 16, 1
	v_bfe_u32 v43, v23, 16, 1
	v_bfe_u32 v52, v86, 16, 1
	v_bfe_u32 v53, v87, 16, 1
	v_cvt_pk_bf16_f32 v5, v12, v13
	v_add3_u32 v12, v12, v40, s10
	v_add3_u32 v13, v13, v41, s10
	v_add3_u32 v38, v84, v50, s10
	v_add3_u32 v39, v85, v51, s10
	v_and_b32_e32 v50, 0xffff0000, v10
	v_and_b32_e32 v51, 0xffff0000, v11
	v_max3_f32 v37, v37, |v56|, |v57|
	v_bfe_u32 v44, v24, 16, 1
	v_bfe_u32 v46, v18, 16, 1
	v_bfe_u32 v47, v19, 16, 1
	v_add3_u32 v30, v22, v42, s10
	v_add3_u32 v31, v23, v43, s10
	v_add3_u32 v40, v86, v52, s10
	v_add3_u32 v41, v87, v53, s10
	v_and_b32_e32 v52, 0xffff0000, v12
	v_and_b32_e32 v53, 0xffff0000, v13
	v_max3_f32 v37, v37, |v50|, |v51|
	v_bfe_u32 v48, v20, 16, 1
	v_add3_u32 v32, v24, v44, s10
	v_add3_u32 v34, v18, v46, s10
	v_add3_u32 v35, v19, v47, s10
	v_and_b32_e32 v46, 0xffff0000, v30
	v_and_b32_e32 v47, 0xffff0000, v31
	v_max3_f32 v37, v37, |v52|, |v53|
	v_add3_u32 v36, v20, v48, s10
	v_and_b32_e32 v48, 0xffff0000, v32
	v_and_b32_e32 v49, 0xffff0000, v33
	v_max3_f32 v37, v37, |v46|, |v47|
	v_and_b32_e32 v42, 0xffff0000, v34
	v_and_b32_e32 v43, 0xffff0000, v35
	v_max3_f32 v37, v37, |v48|, |v49|
	v_and_b32_e32 v44, 0xffff0000, v36
	v_max3_f32 v37, v37, |v42|, |v43|
	v_and_b32_e32 v38, 0xffff0000, v38
	v_and_b32_e32 v39, 0xffff0000, v39
	v_max3_f32 v37, v37, |v44|, |v45|
	v_and_b32_e32 v40, 0xffff0000, v40
	v_and_b32_e32 v41, 0xffff0000, v41
	v_max3_f32 v37, v37, |v38|, |v39|
	v_and_b32_e32 v33, 0xffff0000, v79
	v_and_b32_e32 v34, 0xffff0000, v147
	v_max3_f32 v37, v37, |v40|, |v41|
	v_and_b32_e32 v35, 0xffff0000, v148
	v_and_b32_e32 v36, 0xffff0000, v149
	v_max3_f32 v37, v37, |v33|, |v34|
	v_and_b32_e32 v29, 0xffff0000, v150
	v_and_b32_e32 v30, 0xffff0000, v151
	v_max3_f32 v37, v37, |v35|, |v36|
	v_and_b32_e32 v31, 0xffff0000, v152
	v_and_b32_e32 v32, 0xffff0000, v153
	v_max3_f32 v37, v37, |v29|, |v30|
	v_bfe_u32 v83, v100, 16, 1
	v_bfe_u32 v123, v101, 16, 1
	global_store_dwordx4 v130, v[2:5], s[8:9] offset:1024
	v_cvt_pk_bf16_f32 v80, v22, v23
	v_cvt_pk_bf16_f32 v81, v24, v25
	v_and_b32_e32 v25, 0xffff0000, v154
	v_and_b32_e32 v26, 0xffff0000, v155
	v_max3_f32 v37, v37, |v31|, |v32|
	v_bfe_u32 v124, v102, 16, 1
	v_bfe_u32 v125, v103, 16, 1
	v_add3_u32 v158, v100, v83, s10
	v_add3_u32 v123, v101, v123, s10
	v_and_b32_e32 v27, 0xffff0000, v156
	v_and_b32_e32 v28, 0xffff0000, v157
	v_max3_f32 v37, v37, |v25|, |v26|
	v_bfe_u32 v126, v104, 16, 1
	v_bfe_u32 v127, v105, 16, 1
	v_add3_u32 v124, v102, v124, s10
	v_add3_u32 v125, v103, v125, s10
	v_cvt_pk_bf16_f32 v82, v18, v19
	v_cvt_pk_bf16_f32 v83, v20, v21
	v_and_b32_e32 v21, 0xffff0000, v158
	v_and_b32_e32 v22, 0xffff0000, v123
	v_max3_f32 v37, v37, |v27|, |v28|
	v_bfe_u32 v128, v106, 16, 1
	v_bfe_u32 v129, v107, 16, 1
	v_add3_u32 v126, v104, v126, s10
	v_add3_u32 v127, v105, v127, s10
	v_and_b32_e32 v23, 0xffff0000, v124
	v_and_b32_e32 v24, 0xffff0000, v125
	v_max3_f32 v37, v37, |v21|, |v22|
	v_bfe_u32 v131, v108, 16, 1
	v_bfe_u32 v132, v109, 16, 1
	v_add3_u32 v128, v106, v128, s10
	v_add3_u32 v129, v107, v129, s10
	v_and_b32_e32 v17, 0xffff0000, v126
	v_and_b32_e32 v18, 0xffff0000, v127
	v_max3_f32 v37, v37, |v23|, |v24|
	v_bfe_u32 v133, v110, 16, 1
	v_bfe_u32 v134, v111, 16, 1
	v_add3_u32 v131, v108, v131, s10
	v_add3_u32 v132, v109, v132, s10
	v_and_b32_e32 v19, 0xffff0000, v128
	v_and_b32_e32 v20, 0xffff0000, v129
	v_max3_f32 v37, v37, |v17|, |v18|
	v_bfe_u32 v135, v112, 16, 1
	v_bfe_u32 v136, v113, 16, 1
	v_add3_u32 v133, v110, v133, s10
	v_add3_u32 v134, v111, v134, s10
	v_and_b32_e32 v13, 0xffff0000, v131
	v_and_b32_e32 v14, 0xffff0000, v132
	v_max3_f32 v37, v37, |v19|, |v20|
	v_bfe_u32 v137, v114, 16, 1
	v_bfe_u32 v138, v115, 16, 1
	v_add3_u32 v135, v112, v135, s10
	v_add3_u32 v136, v113, v136, s10
	v_and_b32_e32 v15, 0xffff0000, v133
	v_and_b32_e32 v16, 0xffff0000, v134
	v_max3_f32 v37, v37, |v13|, |v14|
	v_bfe_u32 v139, v116, 16, 1
	v_bfe_u32 v140, v117, 16, 1
	v_add3_u32 v137, v114, v137, s10
	v_add3_u32 v138, v115, v138, s10
	v_and_b32_e32 v9, 0xffff0000, v135
	v_and_b32_e32 v10, 0xffff0000, v136
	v_max3_f32 v37, v37, |v15|, |v16|
	v_bfe_u32 v141, v118, 16, 1
	v_bfe_u32 v142, v119, 16, 1
	v_add3_u32 v139, v116, v139, s10
	v_add3_u32 v140, v117, v140, s10
	v_and_b32_e32 v11, 0xffff0000, v137
	v_and_b32_e32 v12, 0xffff0000, v138
	v_max3_f32 v37, v37, |v9|, |v10|
	v_bfe_u32 v143, v120, 16, 1
	v_bfe_u32 v144, v121, 16, 1
	v_add3_u32 v141, v118, v141, s10
	v_add3_u32 v142, v119, v142, s10
	v_and_b32_e32 v5, 0xffff0000, v139
	v_and_b32_e32 v6, 0xffff0000, v140
	v_max3_f32 v37, v37, |v11|, |v12|
	v_bfe_u32 v145, v122, 16, 1
	v_bfe_u32 v146, v68, 16, 1
	v_add3_u32 v143, v120, v143, s10
	v_add3_u32 v144, v121, v144, s10
	v_and_b32_e32 v7, 0xffff0000, v141
	v_and_b32_e32 v8, 0xffff0000, v142
	v_max3_f32 v37, v37, |v5|, |v6|
	v_add3_u32 v145, v122, v145, s10
	v_add3_u32 v146, v68, v146, s10
	v_and_b32_e32 v2, 0xffff0000, v143
	v_and_b32_e32 v3, 0xffff0000, v144
	v_max3_f32 v37, v37, |v7|, |v8|
	v_and_b32_e32 v4, 0xffff0000, v145
	v_max3_f32 v79, v37, |v2|, |v3|
	v_and_b32_e32 v37, 0xffff0000, v146
	v_max3_f32 v79, v79, |v4|, |v37|
	ds_bpermute_b32 v73, v73, v79
	global_store_dwordx4 v130, v[80:83], s[8:9] offset:2048
	v_cmp_eq_u32_e32 vcc, 0, v1
	s_waitcnt lgkmcnt(0)
	v_max_f32_e32 v73, v73, v73
	v_max_f32_e32 v73, v79, v73
	v_cvt_pk_bf16_f32 v80, v84, v85
	ds_bpermute_b32 v84, v78, v73
	v_cvt_pk_bf16_f32 v81, v86, v87
	v_cvt_pk_bf16_f32 v82, v88, v89
	v_cvt_pk_bf16_f32 v83, v90, v91
	global_store_dwordx4 v130, v[80:83], s[8:9] offset:3072
	s_nop 1
	v_cvt_pk_bf16_f32 v80, v92, v93
	v_cvt_pk_bf16_f32 v81, v94, v95
	v_cvt_pk_bf16_f32 v82, v96, v97
	v_cvt_pk_bf16_f32 v83, v98, v99
	global_store_dwordx4 v72, v[80:83], s[8:9]
	s_waitcnt lgkmcnt(0)
	v_max_f32_e32 v72, v84, v84
	v_max_f32_e32 v72, v73, v72
	ds_bpermute_b32 v73, v77, v72
	v_cvt_pk_bf16_f32 v78, v100, v101
	v_cvt_pk_bf16_f32 v79, v102, v103
	v_cvt_pk_bf16_f32 v80, v104, v105
	v_cvt_pk_bf16_f32 v81, v106, v107
	global_store_dwordx4 v71, v[78:81], s[8:9]
	s_waitcnt lgkmcnt(0)
	v_max_f32_e32 v71, v73, v73
	v_max_f32_e32 v71, v72, v71
	ds_bpermute_b32 v72, v76, v71
	v_cvt_pk_bf16_f32 v78, v108, v109
	v_cvt_pk_bf16_f32 v79, v110, v111
	v_cvt_pk_bf16_f32 v80, v112, v113
	v_cvt_pk_bf16_f32 v81, v114, v115
	s_waitcnt lgkmcnt(0)
	v_max_f32_e32 v72, v72, v72
	v_max_f32_e32 v73, v71, v72
	ds_bpermute_b32 v75, v75, v73
	global_store_dwordx4 v70, v[78:81], s[8:9]
	v_cvt_pk_bf16_f32 v70, v116, v117
	v_cvt_pk_bf16_f32 v71, v118, v119
	v_cvt_pk_bf16_f32 v72, v120, v121
	s_waitcnt lgkmcnt(0)
	v_max_f32_e32 v75, v75, v75
	v_max_f32_e32 v75, v73, v75
	ds_bpermute_b32 v74, v74, v75
	v_cvt_pk_bf16_f32 v73, v122, v68
	v_lshlrev_b32_e32 v68, 1, v69
	global_store_dwordx4 v68, v[70:73], s[8:9]
	s_waitcnt lgkmcnt(0)
	v_max_f32_e32 v1, v74, v74
	v_max_f32_e32 v1, v75, v1
	s_and_saveexec_b64 s[0:1], vcc
	s_cbranch_execz .LBB0_1635
	s_lshl_b64 s[4:5], s[6:7], 2
	s_add_u32 s4, s56, s4
	v_mul_f32_e32 v68, 0x3c010204, v1
	s_addc_u32 s5, s57, s5
	global_store_dword v67, v68, s[4:5]

.LBB0_1860:
	s_waitcnt vmcnt(19)
	v_lshlrev_b32_e32 v187, 16, v2
	s_waitcnt vmcnt(1)
	v_lshlrev_b32_e32 v186, 16, v42
	v_and_b32_e32 v195, 0xffff0000, v2
	v_and_b32_e32 v194, 0xffff0000, v42
	v_lshlrev_b32_e32 v197, 16, v3
	v_lshlrev_b32_e32 v196, 16, v43
	v_and_b32_e32 v3, 0xffff0000, v3
	v_and_b32_e32 v2, 0xffff0000, v43
	v_lshlrev_b32_e32 v43, 16, v4
	v_lshlrev_b32_e32 v42, 16, v44
	v_and_b32_e32 v199, 0xffff0000, v4
	v_and_b32_e32 v198, 0xffff0000, v44
	v_lshlrev_b32_e32 v201, 16, v5
	v_lshlrev_b32_e32 v200, 16, v45
	v_and_b32_e32 v5, 0xffff0000, v5
	v_and_b32_e32 v4, 0xffff0000, v45
	v_pk_add_f32 v[44:45], v[186:187], v[194:195]
	v_pk_add_f32 v[202:203], v[196:197], v[2:3]
	v_pk_add_f32 v[204:205], v[42:43], v[198:199]
	v_pk_add_f32 v[206:207], v[200:201], v[4:5]
	v_pk_add_f32 v[186:187], v[186:187], v[194:195] neg_lo:[0,1] neg_hi:[0,1]
	v_pk_add_f32 v[2:3], v[196:197], v[2:3] neg_lo:[0,1] neg_hi:[0,1]
	v_pk_add_f32 v[42:43], v[42:43], v[198:199] neg_lo:[0,1] neg_hi:[0,1]
	v_pk_add_f32 v[4:5], v[200:201], v[4:5] neg_lo:[0,1] neg_hi:[0,1]
	v_pk_add_f32 v[208:209], v[44:45], v[202:203] neg_lo:[0,1] neg_hi:[0,1]
	v_pk_add_f32 v[44:45], v[44:45], v[202:203]
	v_pk_add_f32 v[202:203], v[204:205], v[206:207]
	v_pk_add_f32 v[194:195], v[186:187], v[2:3] neg_lo:[0,1] neg_hi:[0,1]
	v_pk_add_f32 v[196:197], v[42:43], v[4:5] neg_lo:[0,1] neg_hi:[0,1]
	v_pk_add_f32 v[2:3], v[186:187], v[2:3]
	v_pk_add_f32 v[4:5], v[42:43], v[4:5]
	v_pk_add_f32 v[210:211], v[204:205], v[206:207] neg_lo:[0,1] neg_hi:[0,1]
	v_pk_add_f32 v[204:205], v[44:45], v[202:203]
	v_pk_add_f32 v[42:43], v[2:3], v[4:5]
	v_pk_add_f32 v[2:3], v[2:3], v[4:5] neg_lo:[0,1] neg_hi:[0,1]
	v_pk_add_f32 v[44:45], v[44:45], v[202:203] neg_lo:[0,1] neg_hi:[0,1]
	v_pk_add_f32 v[202:203], v[208:209], v[210:211]
	v_pk_add_f32 v[206:207], v[208:209], v[210:211] neg_lo:[0,1] neg_hi:[0,1]
	v_pk_add_f32 v[4:5], v[194:195], v[196:197]
	v_pk_add_f32 v[186:187], v[194:195], v[196:197] neg_lo:[0,1] neg_hi:[0,1]
	v_pk_add_f32 v[194:195], v[204:205], v[204:205] op_sel:[0,1] op_sel_hi:[1,0]
	v_pk_add_f32 v[210:211], v[2:3], v[2:3] op_sel:[0,1] op_sel_hi:[1,0]
	v_pk_add_f32 v[2:3], v[2:3], v[2:3] op_sel:[0,1] op_sel_hi:[1,0] neg_lo:[0,1] neg_hi:[0,1]
	v_pk_add_f32 v[196:197], v[204:205], v[204:205] op_sel:[0,1] op_sel_hi:[1,0] neg_lo:[0,1] neg_hi:[0,1]
	v_pk_add_f32 v[198:199], v[42:43], v[42:43] op_sel:[0,1] op_sel_hi:[1,0]
	v_pk_add_f32 v[204:205], v[4:5], v[4:5] op_sel:[0,1] op_sel_hi:[1,0]
	v_pk_add_f32 v[4:5], v[4:5], v[4:5] op_sel:[0,1] op_sel_hi:[1,0] neg_lo:[0,1] neg_hi:[0,1]
	v_pk_add_f32 v[214:215], v[186:187], v[186:187] op_sel:[0,1] op_sel_hi:[1,0]
	v_pk_add_f32 v[186:187], v[186:187], v[186:187] op_sel:[0,1] op_sel_hi:[1,0] neg_lo:[0,1] neg_hi:[0,1]
	v_xor_b32_e32 v3, v181, v194
	v_pk_add_f32 v[42:43], v[42:43], v[42:43] op_sel:[0,1] op_sel_hi:[1,0] neg_lo:[0,1] neg_hi:[0,1]
	v_pk_add_f32 v[200:201], v[202:203], v[202:203] op_sel:[0,1] op_sel_hi:[1,0]
	v_add_f32_dpp v3, v194, v3 quad_perm:[1,0,3,2] row_mask:0xf bank_mask:0xf bound_ctrl:1
	v_xor_b32_e32 v5, v181, v198
	v_xor_b32_e32 v199, v181, v186
	v_pk_add_f32 v[208:209], v[44:45], v[44:45] op_sel:[0,1] op_sel_hi:[1,0]
	v_pk_add_f32 v[44:45], v[44:45], v[44:45] op_sel:[0,1] op_sel_hi:[1,0] neg_lo:[0,1] neg_hi:[0,1]
	v_add_f32_dpp v5, v198, v5 quad_perm:[1,0,3,2] row_mask:0xf bank_mask:0xf bound_ctrl:1
	v_xor_b32_e32 v43, v181, v200
	v_add_f32_dpp v186, v186, v199 quad_perm:[1,0,3,2] row_mask:0xf bank_mask:0xf bound_ctrl:1
	v_xor_b32_e32 v199, v189, v3
	v_add_f32_dpp v43, v200, v43 quad_perm:[1,0,3,2] row_mask:0xf bank_mask:0xf bound_ctrl:1
	v_xor_b32_e32 v45, v181, v204
	v_add_f32_dpp v3, v3, v199 quad_perm:[2,3,0,1] row_mask:0xf bank_mask:0xf bound_ctrl:1
	v_xor_b32_e32 v199, v189, v5
	v_add_f32_dpp v45, v204, v45 quad_perm:[1,0,3,2] row_mask:0xf bank_mask:0xf bound_ctrl:1
	v_xor_b32_e32 v187, v181, v208
	v_add_f32_dpp v5, v5, v199 quad_perm:[2,3,0,1] row_mask:0xf bank_mask:0xf bound_ctrl:1
	v_xor_b32_e32 v199, v189, v43
	v_pk_add_f32 v[212:213], v[206:207], v[206:207] op_sel:[0,1] op_sel_hi:[1,0]
	v_add_f32_dpp v187, v208, v187 quad_perm:[1,0,3,2] row_mask:0xf bank_mask:0xf bound_ctrl:1
	v_xor_b32_e32 v193, v181, v210
	v_add_f32_dpp v43, v43, v199 quad_perm:[2,3,0,1] row_mask:0xf bank_mask:0xf bound_ctrl:1
	v_xor_b32_e32 v199, v189, v45
	v_add_f32_dpp v193, v210, v193 quad_perm:[1,0,3,2] row_mask:0xf bank_mask:0xf bound_ctrl:1
	v_xor_b32_e32 v194, v181, v212
	v_add_f32_dpp v45, v45, v199 quad_perm:[2,3,0,1] row_mask:0xf bank_mask:0xf bound_ctrl:1
	v_xor_b32_e32 v199, v189, v187
	v_add_f32_dpp v194, v212, v194 quad_perm:[1,0,3,2] row_mask:0xf bank_mask:0xf bound_ctrl:1
	v_xor_b32_e32 v195, v181, v214
	v_add_f32_dpp v187, v187, v199 quad_perm:[2,3,0,1] row_mask:0xf bank_mask:0xf bound_ctrl:1
	v_xor_b32_e32 v199, v189, v193
	v_add_f32_dpp v195, v214, v195 quad_perm:[1,0,3,2] row_mask:0xf bank_mask:0xf bound_ctrl:1
	v_xor_b32_e32 v197, v181, v196
	v_add_f32_dpp v193, v193, v199 quad_perm:[2,3,0,1] row_mask:0xf bank_mask:0xf bound_ctrl:1
	v_xor_b32_e32 v199, v189, v194
	v_pk_add_f32 v[202:203], v[202:203], v[202:203] op_sel:[0,1] op_sel_hi:[1,0] neg_lo:[0,1] neg_hi:[0,1]
	v_add_f32_dpp v196, v196, v197 quad_perm:[1,0,3,2] row_mask:0xf bank_mask:0xf bound_ctrl:1
	v_xor_b32_e32 v197, v181, v42
	v_add_f32_dpp v194, v194, v199 quad_perm:[2,3,0,1] row_mask:0xf bank_mask:0xf bound_ctrl:1
	v_xor_b32_e32 v199, v189, v195
	v_add_f32_dpp v42, v42, v197 quad_perm:[1,0,3,2] row_mask:0xf bank_mask:0xf bound_ctrl:1
	v_xor_b32_e32 v197, v181, v202
	v_add_f32_dpp v195, v195, v199 quad_perm:[2,3,0,1] row_mask:0xf bank_mask:0xf bound_ctrl:1
	v_xor_b32_e32 v199, v189, v196
	v_add_f32_dpp v197, v202, v197 quad_perm:[1,0,3,2] row_mask:0xf bank_mask:0xf bound_ctrl:1
	v_xor_b32_e32 v198, v181, v4
	v_add_f32_dpp v196, v196, v199 quad_perm:[2,3,0,1] row_mask:0xf bank_mask:0xf bound_ctrl:1
	v_xor_b32_e32 v199, v189, v42
	v_add_f32_dpp v4, v4, v198 quad_perm:[1,0,3,2] row_mask:0xf bank_mask:0xf bound_ctrl:1
	v_xor_b32_e32 v198, v181, v44
	v_add_f32_dpp v199, v42, v199 quad_perm:[2,3,0,1] row_mask:0xf bank_mask:0xf bound_ctrl:1
	v_xor_b32_e32 v42, v189, v197
	v_pk_add_f32 v[206:207], v[206:207], v[206:207] op_sel:[0,1] op_sel_hi:[1,0] neg_lo:[0,1] neg_hi:[0,1]
	v_add_f32_dpp v44, v44, v198 quad_perm:[1,0,3,2] row_mask:0xf bank_mask:0xf bound_ctrl:1
	v_xor_b32_e32 v198, v181, v2
	v_add_f32_dpp v197, v197, v42 quad_perm:[2,3,0,1] row_mask:0xf bank_mask:0xf bound_ctrl:1
	v_xor_b32_e32 v42, v189, v4
	v_add_f32_dpp v2, v2, v198 quad_perm:[1,0,3,2] row_mask:0xf bank_mask:0xf bound_ctrl:1
	v_xor_b32_e32 v198, v181, v206
	v_add_f32_dpp v4, v4, v42 quad_perm:[2,3,0,1] row_mask:0xf bank_mask:0xf bound_ctrl:1
	v_xor_b32_e32 v42, v189, v44
	v_add_f32_dpp v198, v206, v198 quad_perm:[1,0,3,2] row_mask:0xf bank_mask:0xf bound_ctrl:1
	s_ashr_i32 s31, s30, 31
	v_add_f32_dpp v200, v44, v42 quad_perm:[2,3,0,1] row_mask:0xf bank_mask:0xf bound_ctrl:1
	v_xor_b32_e32 v42, v189, v2
	v_max_f32_e64 v44, |v194|, |v195|
	s_nop 0
	v_add_f32_dpp v201, v2, v42 quad_perm:[2,3,0,1] row_mask:0xf bank_mask:0xf bound_ctrl:1
	v_xor_b32_e32 v2, v189, v198
	v_max_f32_e64 v42, |v43|, |v45|
	s_nop 0
	v_add_f32_dpp v198, v198, v2 quad_perm:[2,3,0,1] row_mask:0xf bank_mask:0xf bound_ctrl:1
	v_xor_b32_e32 v2, v189, v186
	s_nop 1
	v_add_f32_dpp v186, v186, v2 quad_perm:[2,3,0,1] row_mask:0xf bank_mask:0xf bound_ctrl:1
	v_max_f32_e64 v2, |v3|, |v5|
	v_max3_f32 v2, v2, 0, v42
	v_max_f32_e64 v42, |v187|, |v193|
	v_max3_f32 v2, v2, v42, v44
	v_max_f32_e64 v42, |v196|, |v199|
	v_max_f32_e64 v44, |v197|, |v4|
	v_max3_f32 v2, v2, v42, v44
	v_max_f32_e64 v42, |v200|, |v201|
	v_max_f32_e64 v44, |v198|, |v186|
	v_max3_f32 v216, v2, v42, v44
	v_cvt_pk_bf16_f32 v42, v3, v5
	v_cvt_pk_bf16_f32 v43, v43, v45
	v_cvt_pk_bf16_f32 v44, v187, v193
	v_cvt_pk_bf16_f32 v45, v194, v195
	v_cvt_pk_bf16_f32 v2, v196, v199
	v_cvt_pk_bf16_f32 v3, v197, v4
	v_cvt_pk_bf16_f32 v4, v200, v201
	v_cvt_pk_bf16_f32 v5, v198, v186
	v_and_b32_e32 v187, 0xffff0000, v13
	v_and_b32_e32 v186, 0xffff0000, v9
	v_lshlrev_b32_e32 v195, 16, v10
	v_lshlrev_b32_e32 v194, 16, v6
	v_and_b32_e32 v197, 0xffff0000, v10
	v_and_b32_e32 v196, 0xffff0000, v6
	v_lshlrev_b32_e32 v199, 16, v11
	v_lshlrev_b32_e32 v198, 16, v7
	v_and_b32_e32 v11, 0xffff0000, v11
	v_and_b32_e32 v10, 0xffff0000, v7
	v_lshlrev_b32_e32 v7, 16, v12
	v_lshlrev_b32_e32 v6, 16, v8
	v_and_b32_e32 v201, 0xffff0000, v12
	v_and_b32_e32 v200, 0xffff0000, v8
	v_lshlrev_b32_e32 v13, 16, v13
	v_lshlrev_b32_e32 v12, 16, v9
	v_pk_add_f32 v[8:9], v[194:195], v[196:197]
	v_pk_add_f32 v[202:203], v[198:199], v[10:11]
	v_pk_add_f32 v[204:205], v[6:7], v[200:201]
	v_pk_add_f32 v[206:207], v[12:13], v[186:187]
	v_pk_add_f32 v[194:195], v[194:195], v[196:197] neg_lo:[0,1] neg_hi:[0,1]
	v_pk_add_f32 v[10:11], v[198:199], v[10:11] neg_lo:[0,1] neg_hi:[0,1]
	v_pk_add_f32 v[6:7], v[6:7], v[200:201] neg_lo:[0,1] neg_hi:[0,1]
	v_pk_add_f32 v[12:13], v[12:13], v[186:187] neg_lo:[0,1] neg_hi:[0,1]
	v_pk_add_f32 v[208:209], v[8:9], v[202:203] neg_lo:[0,1] neg_hi:[0,1]
	v_pk_add_f32 v[8:9], v[8:9], v[202:203]
	v_pk_add_f32 v[202:203], v[204:205], v[206:207]
	v_pk_add_f32 v[186:187], v[194:195], v[10:11] neg_lo:[0,1] neg_hi:[0,1]
	v_pk_add_f32 v[196:197], v[6:7], v[12:13] neg_lo:[0,1] neg_hi:[0,1]
	v_pk_add_f32 v[10:11], v[194:195], v[10:11]
	v_pk_add_f32 v[6:7], v[6:7], v[12:13]
	v_pk_add_f32 v[210:211], v[204:205], v[206:207] neg_lo:[0,1] neg_hi:[0,1]
	v_pk_add_f32 v[204:205], v[8:9], v[202:203]
	v_pk_add_f32 v[12:13], v[10:11], v[6:7]
	v_pk_add_f32 v[6:7], v[10:11], v[6:7] neg_lo:[0,1] neg_hi:[0,1]
	v_pk_add_f32 v[8:9], v[8:9], v[202:203] neg_lo:[0,1] neg_hi:[0,1]
	v_pk_add_f32 v[202:203], v[208:209], v[210:211]
	v_pk_add_f32 v[206:207], v[208:209], v[210:211] neg_lo:[0,1] neg_hi:[0,1]
	v_pk_add_f32 v[10:11], v[186:187], v[196:197]
	v_pk_add_f32 v[186:187], v[186:187], v[196:197] neg_lo:[0,1] neg_hi:[0,1]
	v_pk_add_f32 v[194:195], v[204:205], v[204:205] op_sel:[0,1] op_sel_hi:[1,0]
	v_pk_add_f32 v[210:211], v[6:7], v[6:7] op_sel:[0,1] op_sel_hi:[1,0]
	v_pk_add_f32 v[6:7], v[6:7], v[6:7] op_sel:[0,1] op_sel_hi:[1,0] neg_lo:[0,1] neg_hi:[0,1]
	v_pk_add_f32 v[198:199], v[12:13], v[12:13] op_sel:[0,1] op_sel_hi:[1,0]
	v_pk_add_f32 v[208:209], v[8:9], v[8:9] op_sel:[0,1] op_sel_hi:[1,0]
	v_pk_add_f32 v[8:9], v[8:9], v[8:9] op_sel:[0,1] op_sel_hi:[1,0] neg_lo:[0,1] neg_hi:[0,1]
	v_pk_add_f32 v[214:215], v[186:187], v[186:187] op_sel:[0,1] op_sel_hi:[1,0]
	v_pk_add_f32 v[186:187], v[186:187], v[186:187] op_sel:[0,1] op_sel_hi:[1,0] neg_lo:[0,1] neg_hi:[0,1]
	v_xor_b32_e32 v7, v181, v194
	v_pk_add_f32 v[196:197], v[204:205], v[204:205] op_sel:[0,1] op_sel_hi:[1,0] neg_lo:[0,1] neg_hi:[0,1]
	v_pk_add_f32 v[200:201], v[202:203], v[202:203] op_sel:[0,1] op_sel_hi:[1,0]
	v_pk_add_f32 v[204:205], v[10:11], v[10:11] op_sel:[0,1] op_sel_hi:[1,0]
	v_pk_add_f32 v[10:11], v[10:11], v[10:11] op_sel:[0,1] op_sel_hi:[1,0] neg_lo:[0,1] neg_hi:[0,1]
	v_add_f32_dpp v7, v194, v7 quad_perm:[1,0,3,2] row_mask:0xf bank_mask:0xf bound_ctrl:1
	v_xor_b32_e32 v9, v181, v198
	v_xor_b32_e32 v199, v181, v186
	v_pk_add_f32 v[12:13], v[12:13], v[12:13] op_sel:[0,1] op_sel_hi:[1,0] neg_lo:[0,1] neg_hi:[0,1]
	v_add_f32_dpp v9, v198, v9 quad_perm:[1,0,3,2] row_mask:0xf bank_mask:0xf bound_ctrl:1
	v_xor_b32_e32 v11, v181, v200
	v_add_f32_dpp v186, v186, v199 quad_perm:[1,0,3,2] row_mask:0xf bank_mask:0xf bound_ctrl:1
	v_xor_b32_e32 v199, v189, v7
	v_add_f32_dpp v11, v200, v11 quad_perm:[1,0,3,2] row_mask:0xf bank_mask:0xf bound_ctrl:1
	v_xor_b32_e32 v13, v181, v204
	v_add_f32_dpp v7, v7, v199 quad_perm:[2,3,0,1] row_mask:0xf bank_mask:0xf bound_ctrl:1
	v_xor_b32_e32 v199, v189, v9
	v_add_f32_dpp v13, v204, v13 quad_perm:[1,0,3,2] row_mask:0xf bank_mask:0xf bound_ctrl:1
	v_xor_b32_e32 v187, v181, v208
	v_add_f32_dpp v9, v9, v199 quad_perm:[2,3,0,1] row_mask:0xf bank_mask:0xf bound_ctrl:1
	v_xor_b32_e32 v199, v189, v11
	v_pk_add_f32 v[212:213], v[206:207], v[206:207] op_sel:[0,1] op_sel_hi:[1,0]
	v_add_f32_dpp v187, v208, v187 quad_perm:[1,0,3,2] row_mask:0xf bank_mask:0xf bound_ctrl:1
	v_xor_b32_e32 v193, v181, v210
	v_add_f32_dpp v11, v11, v199 quad_perm:[2,3,0,1] row_mask:0xf bank_mask:0xf bound_ctrl:1
	v_xor_b32_e32 v199, v189, v13
	v_add_f32_dpp v193, v210, v193 quad_perm:[1,0,3,2] row_mask:0xf bank_mask:0xf bound_ctrl:1
	v_xor_b32_e32 v194, v181, v212
	v_add_f32_dpp v13, v13, v199 quad_perm:[2,3,0,1] row_mask:0xf bank_mask:0xf bound_ctrl:1
	v_xor_b32_e32 v199, v189, v187
	v_add_f32_dpp v194, v212, v194 quad_perm:[1,0,3,2] row_mask:0xf bank_mask:0xf bound_ctrl:1
	v_xor_b32_e32 v195, v181, v214
	v_add_f32_dpp v187, v187, v199 quad_perm:[2,3,0,1] row_mask:0xf bank_mask:0xf bound_ctrl:1
	v_xor_b32_e32 v199, v189, v193
	v_add_f32_dpp v195, v214, v195 quad_perm:[1,0,3,2] row_mask:0xf bank_mask:0xf bound_ctrl:1
	v_xor_b32_e32 v197, v181, v196
	v_add_f32_dpp v193, v193, v199 quad_perm:[2,3,0,1] row_mask:0xf bank_mask:0xf bound_ctrl:1
	v_xor_b32_e32 v199, v189, v194
	v_pk_add_f32 v[202:203], v[202:203], v[202:203] op_sel:[0,1] op_sel_hi:[1,0] neg_lo:[0,1] neg_hi:[0,1]
	v_add_f32_dpp v196, v196, v197 quad_perm:[1,0,3,2] row_mask:0xf bank_mask:0xf bound_ctrl:1
	v_xor_b32_e32 v197, v181, v12
	v_add_f32_dpp v194, v194, v199 quad_perm:[2,3,0,1] row_mask:0xf bank_mask:0xf bound_ctrl:1
	v_xor_b32_e32 v199, v189, v195
	v_add_f32_dpp v12, v12, v197 quad_perm:[1,0,3,2] row_mask:0xf bank_mask:0xf bound_ctrl:1
	v_xor_b32_e32 v197, v181, v202
	v_add_f32_dpp v195, v195, v199 quad_perm:[2,3,0,1] row_mask:0xf bank_mask:0xf bound_ctrl:1
	v_xor_b32_e32 v199, v189, v196
	v_add_f32_dpp v197, v202, v197 quad_perm:[1,0,3,2] row_mask:0xf bank_mask:0xf bound_ctrl:1
	v_xor_b32_e32 v198, v181, v10
	v_add_f32_dpp v196, v196, v199 quad_perm:[2,3,0,1] row_mask:0xf bank_mask:0xf bound_ctrl:1
	v_xor_b32_e32 v199, v189, v12
	v_add_f32_dpp v10, v10, v198 quad_perm:[1,0,3,2] row_mask:0xf bank_mask:0xf bound_ctrl:1
	v_xor_b32_e32 v198, v181, v8
	v_add_f32_dpp v12, v12, v199 quad_perm:[2,3,0,1] row_mask:0xf bank_mask:0xf bound_ctrl:1
	v_xor_b32_e32 v199, v189, v197
	v_pk_add_f32 v[206:207], v[206:207], v[206:207] op_sel:[0,1] op_sel_hi:[1,0] neg_lo:[0,1] neg_hi:[0,1]
	v_add_f32_dpp v8, v8, v198 quad_perm:[1,0,3,2] row_mask:0xf bank_mask:0xf bound_ctrl:1
	v_xor_b32_e32 v198, v181, v6
	v_add_f32_dpp v197, v197, v199 quad_perm:[2,3,0,1] row_mask:0xf bank_mask:0xf bound_ctrl:1
	v_xor_b32_e32 v199, v189, v10
	v_add_f32_dpp v6, v6, v198 quad_perm:[1,0,3,2] row_mask:0xf bank_mask:0xf bound_ctrl:1
	v_xor_b32_e32 v198, v181, v206
	v_add_f32_dpp v199, v10, v199 quad_perm:[2,3,0,1] row_mask:0xf bank_mask:0xf bound_ctrl:1
	v_xor_b32_e32 v10, v189, v8
	v_add_f32_dpp v198, v206, v198 quad_perm:[1,0,3,2] row_mask:0xf bank_mask:0xf bound_ctrl:1
	s_nop 0
	v_add_f32_dpp v200, v8, v10 quad_perm:[2,3,0,1] row_mask:0xf bank_mask:0xf bound_ctrl:1
	v_xor_b32_e32 v8, v189, v6
	v_max_f32_e64 v10, |v194|, |v195|
	s_nop 0
	v_add_f32_dpp v201, v6, v8 quad_perm:[2,3,0,1] row_mask:0xf bank_mask:0xf bound_ctrl:1
	v_xor_b32_e32 v6, v189, v198
	v_max_f32_e64 v8, |v11|, |v13|
	s_nop 0
	v_add_f32_dpp v198, v198, v6 quad_perm:[2,3,0,1] row_mask:0xf bank_mask:0xf bound_ctrl:1
	v_xor_b32_e32 v6, v189, v186
	s_nop 1
	v_add_f32_dpp v186, v186, v6 quad_perm:[2,3,0,1] row_mask:0xf bank_mask:0xf bound_ctrl:1
	v_max_f32_e64 v6, |v7|, |v9|
	v_max3_f32 v6, v216, v6, v8
	v_max_f32_e64 v8, |v187|, |v193|
	v_max3_f32 v6, v6, v8, v10
	v_max_f32_e64 v8, |v196|, |v12|
	v_max_f32_e64 v10, |v197|, |v199|
	v_max3_f32 v6, v6, v8, v10
	v_max_f32_e64 v8, |v200|, |v201|
	v_max_f32_e64 v10, |v198|, |v186|
	v_max3_f32 v216, v6, v8, v10
	v_cvt_pk_bf16_f32 v6, v7, v9
	v_cvt_pk_bf16_f32 v7, v11, v13
	v_cvt_pk_bf16_f32 v8, v187, v193
	v_cvt_pk_bf16_f32 v9, v194, v195
	v_cvt_pk_bf16_f32 v10, v196, v12
	v_cvt_pk_bf16_f32 v11, v197, v199
	v_cvt_pk_bf16_f32 v12, v200, v201
	v_cvt_pk_bf16_f32 v13, v198, v186
	v_and_b32_e32 v187, 0xffff0000, v25
	v_and_b32_e32 v186, 0xffff0000, v17
	v_lshlrev_b32_e32 v195, 16, v22
	v_lshlrev_b32_e32 v194, 16, v14
	v_and_b32_e32 v197, 0xffff0000, v22
	v_and_b32_e32 v196, 0xffff0000, v14
	v_lshlrev_b32_e32 v199, 16, v23
	v_lshlrev_b32_e32 v198, 16, v15
	v_and_b32_e32 v23, 0xffff0000, v23
	v_and_b32_e32 v22, 0xffff0000, v15
	v_lshlrev_b32_e32 v15, 16, v24
	v_lshlrev_b32_e32 v14, 16, v16
	v_and_b32_e32 v201, 0xffff0000, v24
	v_and_b32_e32 v200, 0xffff0000, v16
	v_lshlrev_b32_e32 v25, 16, v25
	v_lshlrev_b32_e32 v24, 16, v17
	v_pk_add_f32 v[16:17], v[194:195], v[196:197]
	v_pk_add_f32 v[202:203], v[198:199], v[22:23]
	v_pk_add_f32 v[204:205], v[14:15], v[200:201]
	v_pk_add_f32 v[206:207], v[24:25], v[186:187]
	v_pk_add_f32 v[194:195], v[194:195], v[196:197] neg_lo:[0,1] neg_hi:[0,1]
	v_pk_add_f32 v[22:23], v[198:199], v[22:23] neg_lo:[0,1] neg_hi:[0,1]
	v_pk_add_f32 v[14:15], v[14:15], v[200:201] neg_lo:[0,1] neg_hi:[0,1]
	v_pk_add_f32 v[24:25], v[24:25], v[186:187] neg_lo:[0,1] neg_hi:[0,1]
	v_pk_add_f32 v[208:209], v[16:17], v[202:203] neg_lo:[0,1] neg_hi:[0,1]
	v_pk_add_f32 v[16:17], v[16:17], v[202:203]
	v_pk_add_f32 v[202:203], v[204:205], v[206:207]
	v_pk_add_f32 v[186:187], v[194:195], v[22:23] neg_lo:[0,1] neg_hi:[0,1]
	v_pk_add_f32 v[196:197], v[14:15], v[24:25] neg_lo:[0,1] neg_hi:[0,1]
	v_pk_add_f32 v[22:23], v[194:195], v[22:23]
	v_pk_add_f32 v[14:15], v[14:15], v[24:25]
	v_pk_add_f32 v[210:211], v[204:205], v[206:207] neg_lo:[0,1] neg_hi:[0,1]
	v_pk_add_f32 v[204:205], v[16:17], v[202:203]
	v_pk_add_f32 v[24:25], v[22:23], v[14:15]
	v_pk_add_f32 v[14:15], v[22:23], v[14:15] neg_lo:[0,1] neg_hi:[0,1]
	v_pk_add_f32 v[16:17], v[16:17], v[202:203] neg_lo:[0,1] neg_hi:[0,1]
	v_pk_add_f32 v[202:203], v[208:209], v[210:211]
	v_pk_add_f32 v[206:207], v[208:209], v[210:211] neg_lo:[0,1] neg_hi:[0,1]
	v_pk_add_f32 v[22:23], v[186:187], v[196:197]
	v_pk_add_f32 v[186:187], v[186:187], v[196:197] neg_lo:[0,1] neg_hi:[0,1]
	v_pk_add_f32 v[194:195], v[204:205], v[204:205] op_sel:[0,1] op_sel_hi:[1,0]
	v_pk_add_f32 v[210:211], v[14:15], v[14:15] op_sel:[0,1] op_sel_hi:[1,0]
	v_pk_add_f32 v[14:15], v[14:15], v[14:15] op_sel:[0,1] op_sel_hi:[1,0] neg_lo:[0,1] neg_hi:[0,1]
	v_pk_add_f32 v[198:199], v[24:25], v[24:25] op_sel:[0,1] op_sel_hi:[1,0]
	v_pk_add_f32 v[208:209], v[16:17], v[16:17] op_sel:[0,1] op_sel_hi:[1,0]
	v_pk_add_f32 v[16:17], v[16:17], v[16:17] op_sel:[0,1] op_sel_hi:[1,0] neg_lo:[0,1] neg_hi:[0,1]
	v_pk_add_f32 v[214:215], v[186:187], v[186:187] op_sel:[0,1] op_sel_hi:[1,0]
	v_pk_add_f32 v[186:187], v[186:187], v[186:187] op_sel:[0,1] op_sel_hi:[1,0] neg_lo:[0,1] neg_hi:[0,1]
	v_xor_b32_e32 v15, v181, v194
	v_pk_add_f32 v[196:197], v[204:205], v[204:205] op_sel:[0,1] op_sel_hi:[1,0] neg_lo:[0,1] neg_hi:[0,1]
	v_pk_add_f32 v[200:201], v[202:203], v[202:203] op_sel:[0,1] op_sel_hi:[1,0]
	v_pk_add_f32 v[204:205], v[22:23], v[22:23] op_sel:[0,1] op_sel_hi:[1,0]
	v_pk_add_f32 v[22:23], v[22:23], v[22:23] op_sel:[0,1] op_sel_hi:[1,0] neg_lo:[0,1] neg_hi:[0,1]
	v_add_f32_dpp v15, v194, v15 quad_perm:[1,0,3,2] row_mask:0xf bank_mask:0xf bound_ctrl:1
	v_xor_b32_e32 v17, v181, v198
	v_xor_b32_e32 v199, v181, v186
	v_pk_add_f32 v[24:25], v[24:25], v[24:25] op_sel:[0,1] op_sel_hi:[1,0] neg_lo:[0,1] neg_hi:[0,1]
	v_add_f32_dpp v17, v198, v17 quad_perm:[1,0,3,2] row_mask:0xf bank_mask:0xf bound_ctrl:1
	v_xor_b32_e32 v23, v181, v200
	v_add_f32_dpp v186, v186, v199 quad_perm:[1,0,3,2] row_mask:0xf bank_mask:0xf bound_ctrl:1
	v_xor_b32_e32 v199, v189, v15
	v_add_f32_dpp v23, v200, v23 quad_perm:[1,0,3,2] row_mask:0xf bank_mask:0xf bound_ctrl:1
	v_xor_b32_e32 v25, v181, v204
	v_add_f32_dpp v15, v15, v199 quad_perm:[2,3,0,1] row_mask:0xf bank_mask:0xf bound_ctrl:1
	v_xor_b32_e32 v199, v189, v17
	v_add_f32_dpp v25, v204, v25 quad_perm:[1,0,3,2] row_mask:0xf bank_mask:0xf bound_ctrl:1
	v_xor_b32_e32 v187, v181, v208
	v_add_f32_dpp v17, v17, v199 quad_perm:[2,3,0,1] row_mask:0xf bank_mask:0xf bound_ctrl:1
	v_xor_b32_e32 v199, v189, v23
	v_pk_add_f32 v[212:213], v[206:207], v[206:207] op_sel:[0,1] op_sel_hi:[1,0]
	v_add_f32_dpp v187, v208, v187 quad_perm:[1,0,3,2] row_mask:0xf bank_mask:0xf bound_ctrl:1
	v_xor_b32_e32 v193, v181, v210
	v_add_f32_dpp v23, v23, v199 quad_perm:[2,3,0,1] row_mask:0xf bank_mask:0xf bound_ctrl:1
	v_xor_b32_e32 v199, v189, v25
	v_add_f32_dpp v193, v210, v193 quad_perm:[1,0,3,2] row_mask:0xf bank_mask:0xf bound_ctrl:1
	v_xor_b32_e32 v194, v181, v212
	v_add_f32_dpp v25, v25, v199 quad_perm:[2,3,0,1] row_mask:0xf bank_mask:0xf bound_ctrl:1
	v_xor_b32_e32 v199, v189, v187
	v_add_f32_dpp v194, v212, v194 quad_perm:[1,0,3,2] row_mask:0xf bank_mask:0xf bound_ctrl:1
	v_xor_b32_e32 v195, v181, v214
	v_add_f32_dpp v187, v187, v199 quad_perm:[2,3,0,1] row_mask:0xf bank_mask:0xf bound_ctrl:1
	v_xor_b32_e32 v199, v189, v193
	v_add_f32_dpp v195, v214, v195 quad_perm:[1,0,3,2] row_mask:0xf bank_mask:0xf bound_ctrl:1
	v_xor_b32_e32 v197, v181, v196
	v_add_f32_dpp v193, v193, v199 quad_perm:[2,3,0,1] row_mask:0xf bank_mask:0xf bound_ctrl:1
	v_xor_b32_e32 v199, v189, v194
	v_pk_add_f32 v[202:203], v[202:203], v[202:203] op_sel:[0,1] op_sel_hi:[1,0] neg_lo:[0,1] neg_hi:[0,1]
	v_add_f32_dpp v196, v196, v197 quad_perm:[1,0,3,2] row_mask:0xf bank_mask:0xf bound_ctrl:1
	v_xor_b32_e32 v197, v181, v24
	v_add_f32_dpp v194, v194, v199 quad_perm:[2,3,0,1] row_mask:0xf bank_mask:0xf bound_ctrl:1
	v_xor_b32_e32 v199, v189, v195
	v_add_f32_dpp v24, v24, v197 quad_perm:[1,0,3,2] row_mask:0xf bank_mask:0xf bound_ctrl:1
	v_xor_b32_e32 v197, v181, v202
	v_add_f32_dpp v195, v195, v199 quad_perm:[2,3,0,1] row_mask:0xf bank_mask:0xf bound_ctrl:1
	v_xor_b32_e32 v199, v189, v196
	v_add_f32_dpp v197, v202, v197 quad_perm:[1,0,3,2] row_mask:0xf bank_mask:0xf bound_ctrl:1
	v_xor_b32_e32 v198, v181, v22
	v_add_f32_dpp v196, v196, v199 quad_perm:[2,3,0,1] row_mask:0xf bank_mask:0xf bound_ctrl:1
	v_xor_b32_e32 v199, v189, v24
	v_add_f32_dpp v22, v22, v198 quad_perm:[1,0,3,2] row_mask:0xf bank_mask:0xf bound_ctrl:1
	v_xor_b32_e32 v198, v181, v16
	v_add_f32_dpp v24, v24, v199 quad_perm:[2,3,0,1] row_mask:0xf bank_mask:0xf bound_ctrl:1
	v_xor_b32_e32 v199, v189, v197
	v_pk_add_f32 v[206:207], v[206:207], v[206:207] op_sel:[0,1] op_sel_hi:[1,0] neg_lo:[0,1] neg_hi:[0,1]
	v_add_f32_dpp v16, v16, v198 quad_perm:[1,0,3,2] row_mask:0xf bank_mask:0xf bound_ctrl:1
	v_xor_b32_e32 v198, v181, v14
	v_add_f32_dpp v197, v197, v199 quad_perm:[2,3,0,1] row_mask:0xf bank_mask:0xf bound_ctrl:1
	v_xor_b32_e32 v199, v189, v22
	v_add_f32_dpp v14, v14, v198 quad_perm:[1,0,3,2] row_mask:0xf bank_mask:0xf bound_ctrl:1
	v_xor_b32_e32 v198, v181, v206
	v_add_f32_dpp v199, v22, v199 quad_perm:[2,3,0,1] row_mask:0xf bank_mask:0xf bound_ctrl:1
	v_xor_b32_e32 v22, v189, v16
	v_add_f32_dpp v198, v206, v198 quad_perm:[1,0,3,2] row_mask:0xf bank_mask:0xf bound_ctrl:1
	s_nop 0
	v_add_f32_dpp v200, v16, v22 quad_perm:[2,3,0,1] row_mask:0xf bank_mask:0xf bound_ctrl:1
	v_xor_b32_e32 v16, v189, v14
	v_max_f32_e64 v22, |v194|, |v195|
	s_nop 0
	v_add_f32_dpp v201, v14, v16 quad_perm:[2,3,0,1] row_mask:0xf bank_mask:0xf bound_ctrl:1
	v_xor_b32_e32 v14, v189, v198
	v_max_f32_e64 v16, |v23|, |v25|
	s_nop 0
	v_add_f32_dpp v198, v198, v14 quad_perm:[2,3,0,1] row_mask:0xf bank_mask:0xf bound_ctrl:1
	v_xor_b32_e32 v14, v189, v186
	s_nop 1
	v_add_f32_dpp v186, v186, v14 quad_perm:[2,3,0,1] row_mask:0xf bank_mask:0xf bound_ctrl:1
	v_max_f32_e64 v14, |v15|, |v17|
	v_max3_f32 v14, v216, v14, v16
	v_max_f32_e64 v16, |v187|, |v193|
	v_max3_f32 v14, v14, v16, v22
	v_max_f32_e64 v16, |v196|, |v24|
	v_max_f32_e64 v22, |v197|, |v199|
	v_max3_f32 v14, v14, v16, v22
	v_max_f32_e64 v16, |v200|, |v201|
	v_max_f32_e64 v22, |v198|, |v186|
	v_max3_f32 v216, v14, v16, v22
	v_cvt_pk_bf16_f32 v14, v15, v17
	v_cvt_pk_bf16_f32 v15, v23, v25
	v_cvt_pk_bf16_f32 v16, v187, v193
	v_cvt_pk_bf16_f32 v17, v194, v195
	v_cvt_pk_bf16_f32 v22, v196, v24
	v_cvt_pk_bf16_f32 v23, v197, v199
	v_cvt_pk_bf16_f32 v24, v200, v201
	v_cvt_pk_bf16_f32 v25, v198, v186
	v_and_b32_e32 v187, 0xffff0000, v29
	v_and_b32_e32 v186, 0xffff0000, v21
	v_lshlrev_b32_e32 v195, 16, v26
	v_lshlrev_b32_e32 v194, 16, v18
	v_and_b32_e32 v197, 0xffff0000, v26
	v_and_b32_e32 v196, 0xffff0000, v18
	v_lshlrev_b32_e32 v199, 16, v27
	v_lshlrev_b32_e32 v198, 16, v19
	v_and_b32_e32 v27, 0xffff0000, v27
	v_and_b32_e32 v26, 0xffff0000, v19
	v_lshlrev_b32_e32 v19, 16, v28
	v_lshlrev_b32_e32 v18, 16, v20
	v_and_b32_e32 v201, 0xffff0000, v28
	v_and_b32_e32 v200, 0xffff0000, v20
	v_lshlrev_b32_e32 v29, 16, v29
	v_lshlrev_b32_e32 v28, 16, v21
	v_pk_add_f32 v[20:21], v[194:195], v[196:197]
	v_pk_add_f32 v[202:203], v[198:199], v[26:27]
	v_pk_add_f32 v[204:205], v[18:19], v[200:201]
	v_pk_add_f32 v[206:207], v[28:29], v[186:187]
	v_pk_add_f32 v[194:195], v[194:195], v[196:197] neg_lo:[0,1] neg_hi:[0,1]
	v_pk_add_f32 v[26:27], v[198:199], v[26:27] neg_lo:[0,1] neg_hi:[0,1]
	v_pk_add_f32 v[18:19], v[18:19], v[200:201] neg_lo:[0,1] neg_hi:[0,1]
	v_pk_add_f32 v[28:29], v[28:29], v[186:187] neg_lo:[0,1] neg_hi:[0,1]
	v_pk_add_f32 v[208:209], v[20:21], v[202:203] neg_lo:[0,1] neg_hi:[0,1]
	v_pk_add_f32 v[20:21], v[20:21], v[202:203]
	v_pk_add_f32 v[202:203], v[204:205], v[206:207]
	v_pk_add_f32 v[186:187], v[194:195], v[26:27] neg_lo:[0,1] neg_hi:[0,1]
	v_pk_add_f32 v[196:197], v[18:19], v[28:29] neg_lo:[0,1] neg_hi:[0,1]
	v_pk_add_f32 v[26:27], v[194:195], v[26:27]
	v_pk_add_f32 v[18:19], v[18:19], v[28:29]
	v_pk_add_f32 v[210:211], v[204:205], v[206:207] neg_lo:[0,1] neg_hi:[0,1]
	v_pk_add_f32 v[204:205], v[20:21], v[202:203]
	v_pk_add_f32 v[28:29], v[26:27], v[18:19]
	v_pk_add_f32 v[18:19], v[26:27], v[18:19] neg_lo:[0,1] neg_hi:[0,1]
	v_pk_add_f32 v[20:21], v[20:21], v[202:203] neg_lo:[0,1] neg_hi:[0,1]
	v_pk_add_f32 v[202:203], v[208:209], v[210:211]
	v_pk_add_f32 v[206:207], v[208:209], v[210:211] neg_lo:[0,1] neg_hi:[0,1]
	v_pk_add_f32 v[26:27], v[186:187], v[196:197]
	v_pk_add_f32 v[186:187], v[186:187], v[196:197] neg_lo:[0,1] neg_hi:[0,1]
	v_pk_add_f32 v[194:195], v[204:205], v[204:205] op_sel:[0,1] op_sel_hi:[1,0]
	v_pk_add_f32 v[210:211], v[18:19], v[18:19] op_sel:[0,1] op_sel_hi:[1,0]
	v_pk_add_f32 v[18:19], v[18:19], v[18:19] op_sel:[0,1] op_sel_hi:[1,0] neg_lo:[0,1] neg_hi:[0,1]
	v_pk_add_f32 v[198:199], v[28:29], v[28:29] op_sel:[0,1] op_sel_hi:[1,0]
	v_pk_add_f32 v[208:209], v[20:21], v[20:21] op_sel:[0,1] op_sel_hi:[1,0]
	v_pk_add_f32 v[20:21], v[20:21], v[20:21] op_sel:[0,1] op_sel_hi:[1,0] neg_lo:[0,1] neg_hi:[0,1]
	v_pk_add_f32 v[214:215], v[186:187], v[186:187] op_sel:[0,1] op_sel_hi:[1,0]
	v_pk_add_f32 v[186:187], v[186:187], v[186:187] op_sel:[0,1] op_sel_hi:[1,0] neg_lo:[0,1] neg_hi:[0,1]
	v_xor_b32_e32 v19, v181, v194
	v_pk_add_f32 v[196:197], v[204:205], v[204:205] op_sel:[0,1] op_sel_hi:[1,0] neg_lo:[0,1] neg_hi:[0,1]
	v_pk_add_f32 v[200:201], v[202:203], v[202:203] op_sel:[0,1] op_sel_hi:[1,0]
	v_pk_add_f32 v[204:205], v[26:27], v[26:27] op_sel:[0,1] op_sel_hi:[1,0]
	v_pk_add_f32 v[26:27], v[26:27], v[26:27] op_sel:[0,1] op_sel_hi:[1,0] neg_lo:[0,1] neg_hi:[0,1]
	v_add_f32_dpp v19, v194, v19 quad_perm:[1,0,3,2] row_mask:0xf bank_mask:0xf bound_ctrl:1
	v_xor_b32_e32 v21, v181, v198
	v_xor_b32_e32 v199, v181, v186
	v_pk_add_f32 v[28:29], v[28:29], v[28:29] op_sel:[0,1] op_sel_hi:[1,0] neg_lo:[0,1] neg_hi:[0,1]
	v_add_f32_dpp v21, v198, v21 quad_perm:[1,0,3,2] row_mask:0xf bank_mask:0xf bound_ctrl:1
	v_xor_b32_e32 v27, v181, v200
	v_add_f32_dpp v186, v186, v199 quad_perm:[1,0,3,2] row_mask:0xf bank_mask:0xf bound_ctrl:1
	v_xor_b32_e32 v199, v189, v19
	v_add_f32_dpp v27, v200, v27 quad_perm:[1,0,3,2] row_mask:0xf bank_mask:0xf bound_ctrl:1
	v_xor_b32_e32 v29, v181, v204
	v_add_f32_dpp v19, v19, v199 quad_perm:[2,3,0,1] row_mask:0xf bank_mask:0xf bound_ctrl:1
	v_xor_b32_e32 v199, v189, v21
	v_add_f32_dpp v29, v204, v29 quad_perm:[1,0,3,2] row_mask:0xf bank_mask:0xf bound_ctrl:1
	v_xor_b32_e32 v187, v181, v208
	v_add_f32_dpp v21, v21, v199 quad_perm:[2,3,0,1] row_mask:0xf bank_mask:0xf bound_ctrl:1
	v_xor_b32_e32 v199, v189, v27
	v_pk_add_f32 v[212:213], v[206:207], v[206:207] op_sel:[0,1] op_sel_hi:[1,0]
	v_add_f32_dpp v187, v208, v187 quad_perm:[1,0,3,2] row_mask:0xf bank_mask:0xf bound_ctrl:1
	v_xor_b32_e32 v193, v181, v210
	v_add_f32_dpp v27, v27, v199 quad_perm:[2,3,0,1] row_mask:0xf bank_mask:0xf bound_ctrl:1
	v_xor_b32_e32 v199, v189, v29
	v_add_f32_dpp v193, v210, v193 quad_perm:[1,0,3,2] row_mask:0xf bank_mask:0xf bound_ctrl:1
	v_xor_b32_e32 v194, v181, v212
	v_add_f32_dpp v29, v29, v199 quad_perm:[2,3,0,1] row_mask:0xf bank_mask:0xf bound_ctrl:1
	v_xor_b32_e32 v199, v189, v187
	v_add_f32_dpp v194, v212, v194 quad_perm:[1,0,3,2] row_mask:0xf bank_mask:0xf bound_ctrl:1
	v_xor_b32_e32 v195, v181, v214
	v_add_f32_dpp v187, v187, v199 quad_perm:[2,3,0,1] row_mask:0xf bank_mask:0xf bound_ctrl:1
	v_xor_b32_e32 v199, v189, v193
	v_add_f32_dpp v195, v214, v195 quad_perm:[1,0,3,2] row_mask:0xf bank_mask:0xf bound_ctrl:1
	v_xor_b32_e32 v197, v181, v196
	v_add_f32_dpp v193, v193, v199 quad_perm:[2,3,0,1] row_mask:0xf bank_mask:0xf bound_ctrl:1
	v_xor_b32_e32 v199, v189, v194
	v_pk_add_f32 v[202:203], v[202:203], v[202:203] op_sel:[0,1] op_sel_hi:[1,0] neg_lo:[0,1] neg_hi:[0,1]
	v_add_f32_dpp v196, v196, v197 quad_perm:[1,0,3,2] row_mask:0xf bank_mask:0xf bound_ctrl:1
	v_xor_b32_e32 v197, v181, v28
	v_add_f32_dpp v194, v194, v199 quad_perm:[2,3,0,1] row_mask:0xf bank_mask:0xf bound_ctrl:1
	v_xor_b32_e32 v199, v189, v195
	v_add_f32_dpp v28, v28, v197 quad_perm:[1,0,3,2] row_mask:0xf bank_mask:0xf bound_ctrl:1
	v_xor_b32_e32 v197, v181, v202
	v_add_f32_dpp v195, v195, v199 quad_perm:[2,3,0,1] row_mask:0xf bank_mask:0xf bound_ctrl:1
	v_xor_b32_e32 v199, v189, v196
	v_add_f32_dpp v197, v202, v197 quad_perm:[1,0,3,2] row_mask:0xf bank_mask:0xf bound_ctrl:1
	v_xor_b32_e32 v198, v181, v26
	v_add_f32_dpp v196, v196, v199 quad_perm:[2,3,0,1] row_mask:0xf bank_mask:0xf bound_ctrl:1
	v_xor_b32_e32 v199, v189, v28
	v_add_f32_dpp v26, v26, v198 quad_perm:[1,0,3,2] row_mask:0xf bank_mask:0xf bound_ctrl:1
	v_xor_b32_e32 v198, v181, v20
	v_add_f32_dpp v28, v28, v199 quad_perm:[2,3,0,1] row_mask:0xf bank_mask:0xf bound_ctrl:1
	v_xor_b32_e32 v199, v189, v197
	v_pk_add_f32 v[206:207], v[206:207], v[206:207] op_sel:[0,1] op_sel_hi:[1,0] neg_lo:[0,1] neg_hi:[0,1]
	v_add_f32_dpp v20, v20, v198 quad_perm:[1,0,3,2] row_mask:0xf bank_mask:0xf bound_ctrl:1
	v_xor_b32_e32 v198, v181, v18
	v_add_f32_dpp v197, v197, v199 quad_perm:[2,3,0,1] row_mask:0xf bank_mask:0xf bound_ctrl:1
	v_xor_b32_e32 v199, v189, v26
	v_add_f32_dpp v18, v18, v198 quad_perm:[1,0,3,2] row_mask:0xf bank_mask:0xf bound_ctrl:1
	v_xor_b32_e32 v198, v181, v206
	v_add_f32_dpp v199, v26, v199 quad_perm:[2,3,0,1] row_mask:0xf bank_mask:0xf bound_ctrl:1
	v_xor_b32_e32 v26, v189, v20
	v_add_f32_dpp v198, v206, v198 quad_perm:[1,0,3,2] row_mask:0xf bank_mask:0xf bound_ctrl:1
	s_nop 0
	v_add_f32_dpp v200, v20, v26 quad_perm:[2,3,0,1] row_mask:0xf bank_mask:0xf bound_ctrl:1
	v_xor_b32_e32 v20, v189, v18
	v_max_f32_e64 v26, |v194|, |v195|
	s_nop 0
	v_add_f32_dpp v201, v18, v20 quad_perm:[2,3,0,1] row_mask:0xf bank_mask:0xf bound_ctrl:1
	v_xor_b32_e32 v18, v189, v198
	v_max_f32_e64 v20, |v27|, |v29|
	s_nop 0
	v_add_f32_dpp v198, v198, v18 quad_perm:[2,3,0,1] row_mask:0xf bank_mask:0xf bound_ctrl:1
	v_xor_b32_e32 v18, v189, v186
	s_nop 1
	v_add_f32_dpp v186, v186, v18 quad_perm:[2,3,0,1] row_mask:0xf bank_mask:0xf bound_ctrl:1
	v_max_f32_e64 v18, |v19|, |v21|
	v_max3_f32 v18, v216, v18, v20
	v_max_f32_e64 v20, |v187|, |v193|
	v_max3_f32 v18, v18, v20, v26
	v_max_f32_e64 v20, |v196|, |v28|
	v_max_f32_e64 v26, |v197|, |v199|
	v_max3_f32 v18, v18, v20, v26
	v_max_f32_e64 v20, |v200|, |v201|
	v_max_f32_e64 v26, |v198|, |v186|
	v_max3_f32 v216, v18, v20, v26
	v_cvt_pk_bf16_f32 v18, v19, v21
	v_cvt_pk_bf16_f32 v19, v27, v29
	v_cvt_pk_bf16_f32 v20, v187, v193
	v_cvt_pk_bf16_f32 v21, v194, v195
	v_cvt_pk_bf16_f32 v26, v196, v28
	v_cvt_pk_bf16_f32 v27, v197, v199
	v_cvt_pk_bf16_f32 v28, v200, v201
	v_cvt_pk_bf16_f32 v29, v198, v186
	v_and_b32_e32 v187, 0xffff0000, v37
	v_and_b32_e32 v186, 0xffff0000, v33
	v_lshlrev_b32_e32 v195, 16, v34
	v_lshlrev_b32_e32 v194, 16, v30
	v_and_b32_e32 v197, 0xffff0000, v34
	v_and_b32_e32 v196, 0xffff0000, v30
	v_lshlrev_b32_e32 v199, 16, v35
	v_lshlrev_b32_e32 v198, 16, v31
	v_and_b32_e32 v35, 0xffff0000, v35
	v_and_b32_e32 v34, 0xffff0000, v31
	v_lshlrev_b32_e32 v31, 16, v36
	v_lshlrev_b32_e32 v30, 16, v32
	v_and_b32_e32 v201, 0xffff0000, v36
	v_and_b32_e32 v200, 0xffff0000, v32
	v_lshlrev_b32_e32 v37, 16, v37
	v_lshlrev_b32_e32 v36, 16, v33
	v_pk_add_f32 v[32:33], v[194:195], v[196:197]
	v_pk_add_f32 v[202:203], v[198:199], v[34:35]
	v_pk_add_f32 v[204:205], v[30:31], v[200:201]
	v_pk_add_f32 v[206:207], v[36:37], v[186:187]
	v_pk_add_f32 v[194:195], v[194:195], v[196:197] neg_lo:[0,1] neg_hi:[0,1]
	v_pk_add_f32 v[34:35], v[198:199], v[34:35] neg_lo:[0,1] neg_hi:[0,1]
	v_pk_add_f32 v[30:31], v[30:31], v[200:201] neg_lo:[0,1] neg_hi:[0,1]
	v_pk_add_f32 v[36:37], v[36:37], v[186:187] neg_lo:[0,1] neg_hi:[0,1]
	v_pk_add_f32 v[208:209], v[32:33], v[202:203] neg_lo:[0,1] neg_hi:[0,1]
	v_pk_add_f32 v[32:33], v[32:33], v[202:203]
	v_pk_add_f32 v[202:203], v[204:205], v[206:207]
	v_pk_add_f32 v[186:187], v[194:195], v[34:35] neg_lo:[0,1] neg_hi:[0,1]
	v_pk_add_f32 v[196:197], v[30:31], v[36:37] neg_lo:[0,1] neg_hi:[0,1]
	v_pk_add_f32 v[34:35], v[194:195], v[34:35]
	v_pk_add_f32 v[30:31], v[30:31], v[36:37]
	v_pk_add_f32 v[210:211], v[204:205], v[206:207] neg_lo:[0,1] neg_hi:[0,1]
	v_pk_add_f32 v[204:205], v[32:33], v[202:203]
	v_pk_add_f32 v[36:37], v[34:35], v[30:31]
	v_pk_add_f32 v[30:31], v[34:35], v[30:31] neg_lo:[0,1] neg_hi:[0,1]
	v_pk_add_f32 v[32:33], v[32:33], v[202:203] neg_lo:[0,1] neg_hi:[0,1]
	v_pk_add_f32 v[202:203], v[208:209], v[210:211]
	v_pk_add_f32 v[206:207], v[208:209], v[210:211] neg_lo:[0,1] neg_hi:[0,1]
	v_pk_add_f32 v[34:35], v[186:187], v[196:197]
	v_pk_add_f32 v[186:187], v[186:187], v[196:197] neg_lo:[0,1] neg_hi:[0,1]
	v_pk_add_f32 v[194:195], v[204:205], v[204:205] op_sel:[0,1] op_sel_hi:[1,0]
	v_pk_add_f32 v[210:211], v[30:31], v[30:31] op_sel:[0,1] op_sel_hi:[1,0]
	v_pk_add_f32 v[30:31], v[30:31], v[30:31] op_sel:[0,1] op_sel_hi:[1,0] neg_lo:[0,1] neg_hi:[0,1]
	v_pk_add_f32 v[198:199], v[36:37], v[36:37] op_sel:[0,1] op_sel_hi:[1,0]
	v_pk_add_f32 v[208:209], v[32:33], v[32:33] op_sel:[0,1] op_sel_hi:[1,0]
	v_pk_add_f32 v[32:33], v[32:33], v[32:33] op_sel:[0,1] op_sel_hi:[1,0] neg_lo:[0,1] neg_hi:[0,1]
	v_pk_add_f32 v[214:215], v[186:187], v[186:187] op_sel:[0,1] op_sel_hi:[1,0]
	v_pk_add_f32 v[186:187], v[186:187], v[186:187] op_sel:[0,1] op_sel_hi:[1,0] neg_lo:[0,1] neg_hi:[0,1]
	v_xor_b32_e32 v31, v181, v194
	v_pk_add_f32 v[196:197], v[204:205], v[204:205] op_sel:[0,1] op_sel_hi:[1,0] neg_lo:[0,1] neg_hi:[0,1]
	v_pk_add_f32 v[200:201], v[202:203], v[202:203] op_sel:[0,1] op_sel_hi:[1,0]
	v_pk_add_f32 v[204:205], v[34:35], v[34:35] op_sel:[0,1] op_sel_hi:[1,0]
	v_pk_add_f32 v[34:35], v[34:35], v[34:35] op_sel:[0,1] op_sel_hi:[1,0] neg_lo:[0,1] neg_hi:[0,1]
	v_add_f32_dpp v31, v194, v31 quad_perm:[1,0,3,2] row_mask:0xf bank_mask:0xf bound_ctrl:1
	v_xor_b32_e32 v33, v181, v198
	v_xor_b32_e32 v199, v181, v186
	v_pk_add_f32 v[36:37], v[36:37], v[36:37] op_sel:[0,1] op_sel_hi:[1,0] neg_lo:[0,1] neg_hi:[0,1]
	v_add_f32_dpp v33, v198, v33 quad_perm:[1,0,3,2] row_mask:0xf bank_mask:0xf bound_ctrl:1
	v_xor_b32_e32 v35, v181, v200
	v_add_f32_dpp v186, v186, v199 quad_perm:[1,0,3,2] row_mask:0xf bank_mask:0xf bound_ctrl:1
	v_xor_b32_e32 v199, v189, v31
	v_add_f32_dpp v35, v200, v35 quad_perm:[1,0,3,2] row_mask:0xf bank_mask:0xf bound_ctrl:1
	v_xor_b32_e32 v37, v181, v204
	v_add_f32_dpp v31, v31, v199 quad_perm:[2,3,0,1] row_mask:0xf bank_mask:0xf bound_ctrl:1
	v_xor_b32_e32 v199, v189, v33
	v_add_f32_dpp v37, v204, v37 quad_perm:[1,0,3,2] row_mask:0xf bank_mask:0xf bound_ctrl:1
	v_xor_b32_e32 v187, v181, v208
	v_add_f32_dpp v33, v33, v199 quad_perm:[2,3,0,1] row_mask:0xf bank_mask:0xf bound_ctrl:1
	v_xor_b32_e32 v199, v189, v35
	v_pk_add_f32 v[212:213], v[206:207], v[206:207] op_sel:[0,1] op_sel_hi:[1,0]
	v_add_f32_dpp v187, v208, v187 quad_perm:[1,0,3,2] row_mask:0xf bank_mask:0xf bound_ctrl:1
	v_xor_b32_e32 v193, v181, v210
	v_add_f32_dpp v35, v35, v199 quad_perm:[2,3,0,1] row_mask:0xf bank_mask:0xf bound_ctrl:1
	v_xor_b32_e32 v199, v189, v37
	v_add_f32_dpp v193, v210, v193 quad_perm:[1,0,3,2] row_mask:0xf bank_mask:0xf bound_ctrl:1
	v_xor_b32_e32 v194, v181, v212
	v_add_f32_dpp v37, v37, v199 quad_perm:[2,3,0,1] row_mask:0xf bank_mask:0xf bound_ctrl:1
	v_xor_b32_e32 v199, v189, v187
	v_add_f32_dpp v194, v212, v194 quad_perm:[1,0,3,2] row_mask:0xf bank_mask:0xf bound_ctrl:1
	v_xor_b32_e32 v195, v181, v214
	v_add_f32_dpp v187, v187, v199 quad_perm:[2,3,0,1] row_mask:0xf bank_mask:0xf bound_ctrl:1
	v_xor_b32_e32 v199, v189, v193
	v_add_f32_dpp v195, v214, v195 quad_perm:[1,0,3,2] row_mask:0xf bank_mask:0xf bound_ctrl:1
	v_xor_b32_e32 v197, v181, v196
	v_add_f32_dpp v193, v193, v199 quad_perm:[2,3,0,1] row_mask:0xf bank_mask:0xf bound_ctrl:1
	v_xor_b32_e32 v199, v189, v194
	v_pk_add_f32 v[202:203], v[202:203], v[202:203] op_sel:[0,1] op_sel_hi:[1,0] neg_lo:[0,1] neg_hi:[0,1]
	v_add_f32_dpp v196, v196, v197 quad_perm:[1,0,3,2] row_mask:0xf bank_mask:0xf bound_ctrl:1
	v_xor_b32_e32 v197, v181, v36
	v_add_f32_dpp v194, v194, v199 quad_perm:[2,3,0,1] row_mask:0xf bank_mask:0xf bound_ctrl:1
	v_xor_b32_e32 v199, v189, v195
	v_add_f32_dpp v36, v36, v197 quad_perm:[1,0,3,2] row_mask:0xf bank_mask:0xf bound_ctrl:1
	v_xor_b32_e32 v197, v181, v202
	v_add_f32_dpp v195, v195, v199 quad_perm:[2,3,0,1] row_mask:0xf bank_mask:0xf bound_ctrl:1
	v_xor_b32_e32 v199, v189, v196
	v_add_f32_dpp v197, v202, v197 quad_perm:[1,0,3,2] row_mask:0xf bank_mask:0xf bound_ctrl:1
	v_xor_b32_e32 v198, v181, v34
	v_add_f32_dpp v196, v196, v199 quad_perm:[2,3,0,1] row_mask:0xf bank_mask:0xf bound_ctrl:1
	v_xor_b32_e32 v199, v189, v36
	v_add_f32_dpp v34, v34, v198 quad_perm:[1,0,3,2] row_mask:0xf bank_mask:0xf bound_ctrl:1
	v_xor_b32_e32 v198, v181, v32
	v_add_f32_dpp v36, v36, v199 quad_perm:[2,3,0,1] row_mask:0xf bank_mask:0xf bound_ctrl:1
	v_xor_b32_e32 v199, v189, v197
	v_pk_add_f32 v[206:207], v[206:207], v[206:207] op_sel:[0,1] op_sel_hi:[1,0] neg_lo:[0,1] neg_hi:[0,1]
	v_add_f32_dpp v32, v32, v198 quad_perm:[1,0,3,2] row_mask:0xf bank_mask:0xf bound_ctrl:1
	v_xor_b32_e32 v198, v181, v30
	v_add_f32_dpp v197, v197, v199 quad_perm:[2,3,0,1] row_mask:0xf bank_mask:0xf bound_ctrl:1
	v_xor_b32_e32 v199, v189, v34
	v_add_f32_dpp v30, v30, v198 quad_perm:[1,0,3,2] row_mask:0xf bank_mask:0xf bound_ctrl:1
	v_xor_b32_e32 v198, v181, v206
	v_add_f32_dpp v199, v34, v199 quad_perm:[2,3,0,1] row_mask:0xf bank_mask:0xf bound_ctrl:1
	v_xor_b32_e32 v34, v189, v32
	v_add_f32_dpp v198, v206, v198 quad_perm:[1,0,3,2] row_mask:0xf bank_mask:0xf bound_ctrl:1
	s_nop 0
	v_add_f32_dpp v200, v32, v34 quad_perm:[2,3,0,1] row_mask:0xf bank_mask:0xf bound_ctrl:1
	v_xor_b32_e32 v32, v189, v30
	v_max_f32_e64 v34, |v194|, |v195|
	s_nop 0
	v_add_f32_dpp v201, v30, v32 quad_perm:[2,3,0,1] row_mask:0xf bank_mask:0xf bound_ctrl:1
	v_xor_b32_e32 v30, v189, v198
	v_max_f32_e64 v32, |v35|, |v37|
	s_nop 0
	v_add_f32_dpp v198, v198, v30 quad_perm:[2,3,0,1] row_mask:0xf bank_mask:0xf bound_ctrl:1
	v_xor_b32_e32 v30, v189, v186
	s_nop 1
	v_add_f32_dpp v186, v186, v30 quad_perm:[2,3,0,1] row_mask:0xf bank_mask:0xf bound_ctrl:1
	v_max_f32_e64 v30, |v31|, |v33|
	v_max3_f32 v30, v216, v30, v32
	v_max_f32_e64 v32, |v187|, |v193|
	v_max3_f32 v30, v30, v32, v34
	v_max_f32_e64 v32, |v196|, |v36|
	v_max_f32_e64 v34, |v197|, |v199|
	v_max3_f32 v30, v30, v32, v34
	v_max_f32_e64 v32, |v200|, |v201|
	v_max_f32_e64 v34, |v198|, |v186|
	v_max3_f32 v216, v30, v32, v34
	v_cvt_pk_bf16_f32 v30, v31, v33
	v_cvt_pk_bf16_f32 v31, v35, v37
	v_cvt_pk_bf16_f32 v32, v187, v193
	v_cvt_pk_bf16_f32 v33, v194, v195
	v_cvt_pk_bf16_f32 v34, v196, v36
	v_cvt_pk_bf16_f32 v35, v197, v199
	v_cvt_pk_bf16_f32 v36, v200, v201
	v_cvt_pk_bf16_f32 v37, v198, v186
	v_and_b32_e32 v187, 0xffff0000, v49
	v_and_b32_e32 v186, 0xffff0000, v41
	v_lshlrev_b32_e32 v195, 16, v46
	v_lshlrev_b32_e32 v194, 16, v38
	v_and_b32_e32 v197, 0xffff0000, v46
	v_and_b32_e32 v196, 0xffff0000, v38
	v_lshlrev_b32_e32 v199, 16, v47
	v_lshlrev_b32_e32 v198, 16, v39
	v_and_b32_e32 v47, 0xffff0000, v47
	v_and_b32_e32 v46, 0xffff0000, v39
	v_lshlrev_b32_e32 v39, 16, v48
	v_lshlrev_b32_e32 v38, 16, v40
	v_and_b32_e32 v201, 0xffff0000, v48
	v_and_b32_e32 v200, 0xffff0000, v40
	v_lshlrev_b32_e32 v49, 16, v49
	v_lshlrev_b32_e32 v48, 16, v41
	v_pk_add_f32 v[40:41], v[194:195], v[196:197]
	v_pk_add_f32 v[202:203], v[198:199], v[46:47]
	v_pk_add_f32 v[204:205], v[38:39], v[200:201]
	v_pk_add_f32 v[206:207], v[48:49], v[186:187]
	v_pk_add_f32 v[194:195], v[194:195], v[196:197] neg_lo:[0,1] neg_hi:[0,1]
	v_pk_add_f32 v[46:47], v[198:199], v[46:47] neg_lo:[0,1] neg_hi:[0,1]
	v_pk_add_f32 v[38:39], v[38:39], v[200:201] neg_lo:[0,1] neg_hi:[0,1]
	v_pk_add_f32 v[48:49], v[48:49], v[186:187] neg_lo:[0,1] neg_hi:[0,1]
	v_pk_add_f32 v[208:209], v[40:41], v[202:203] neg_lo:[0,1] neg_hi:[0,1]
	v_pk_add_f32 v[40:41], v[40:41], v[202:203]
	v_pk_add_f32 v[202:203], v[204:205], v[206:207]
	v_pk_add_f32 v[186:187], v[194:195], v[46:47] neg_lo:[0,1] neg_hi:[0,1]
	v_pk_add_f32 v[196:197], v[38:39], v[48:49] neg_lo:[0,1] neg_hi:[0,1]
	v_pk_add_f32 v[46:47], v[194:195], v[46:47]
	v_pk_add_f32 v[38:39], v[38:39], v[48:49]
	v_pk_add_f32 v[210:211], v[204:205], v[206:207] neg_lo:[0,1] neg_hi:[0,1]
	v_pk_add_f32 v[204:205], v[40:41], v[202:203]
	v_pk_add_f32 v[48:49], v[46:47], v[38:39]
	v_pk_add_f32 v[38:39], v[46:47], v[38:39] neg_lo:[0,1] neg_hi:[0,1]
	v_pk_add_f32 v[40:41], v[40:41], v[202:203] neg_lo:[0,1] neg_hi:[0,1]
	v_pk_add_f32 v[202:203], v[208:209], v[210:211]
	v_pk_add_f32 v[206:207], v[208:209], v[210:211] neg_lo:[0,1] neg_hi:[0,1]
	v_pk_add_f32 v[46:47], v[186:187], v[196:197]
	v_pk_add_f32 v[186:187], v[186:187], v[196:197] neg_lo:[0,1] neg_hi:[0,1]
	v_pk_add_f32 v[194:195], v[204:205], v[204:205] op_sel:[0,1] op_sel_hi:[1,0]
	v_pk_add_f32 v[210:211], v[38:39], v[38:39] op_sel:[0,1] op_sel_hi:[1,0]
	v_pk_add_f32 v[38:39], v[38:39], v[38:39] op_sel:[0,1] op_sel_hi:[1,0] neg_lo:[0,1] neg_hi:[0,1]
	v_pk_add_f32 v[198:199], v[48:49], v[48:49] op_sel:[0,1] op_sel_hi:[1,0]
	v_pk_add_f32 v[208:209], v[40:41], v[40:41] op_sel:[0,1] op_sel_hi:[1,0]
	v_pk_add_f32 v[40:41], v[40:41], v[40:41] op_sel:[0,1] op_sel_hi:[1,0] neg_lo:[0,1] neg_hi:[0,1]
	v_pk_add_f32 v[214:215], v[186:187], v[186:187] op_sel:[0,1] op_sel_hi:[1,0]
	v_pk_add_f32 v[186:187], v[186:187], v[186:187] op_sel:[0,1] op_sel_hi:[1,0] neg_lo:[0,1] neg_hi:[0,1]
	v_xor_b32_e32 v39, v181, v194
	v_pk_add_f32 v[196:197], v[204:205], v[204:205] op_sel:[0,1] op_sel_hi:[1,0] neg_lo:[0,1] neg_hi:[0,1]
	v_pk_add_f32 v[200:201], v[202:203], v[202:203] op_sel:[0,1] op_sel_hi:[1,0]
	v_pk_add_f32 v[204:205], v[46:47], v[46:47] op_sel:[0,1] op_sel_hi:[1,0]
	v_pk_add_f32 v[46:47], v[46:47], v[46:47] op_sel:[0,1] op_sel_hi:[1,0] neg_lo:[0,1] neg_hi:[0,1]
	v_add_f32_dpp v39, v194, v39 quad_perm:[1,0,3,2] row_mask:0xf bank_mask:0xf bound_ctrl:1
	v_xor_b32_e32 v41, v181, v198
	v_xor_b32_e32 v199, v181, v186
	v_pk_add_f32 v[48:49], v[48:49], v[48:49] op_sel:[0,1] op_sel_hi:[1,0] neg_lo:[0,1] neg_hi:[0,1]
	v_add_f32_dpp v41, v198, v41 quad_perm:[1,0,3,2] row_mask:0xf bank_mask:0xf bound_ctrl:1
	v_xor_b32_e32 v47, v181, v200
	v_add_f32_dpp v186, v186, v199 quad_perm:[1,0,3,2] row_mask:0xf bank_mask:0xf bound_ctrl:1
	v_xor_b32_e32 v199, v189, v39
	v_add_f32_dpp v47, v200, v47 quad_perm:[1,0,3,2] row_mask:0xf bank_mask:0xf bound_ctrl:1
	v_xor_b32_e32 v49, v181, v204
	v_add_f32_dpp v39, v39, v199 quad_perm:[2,3,0,1] row_mask:0xf bank_mask:0xf bound_ctrl:1
	v_xor_b32_e32 v199, v189, v41
	v_add_f32_dpp v49, v204, v49 quad_perm:[1,0,3,2] row_mask:0xf bank_mask:0xf bound_ctrl:1
	v_xor_b32_e32 v187, v181, v208
	v_add_f32_dpp v41, v41, v199 quad_perm:[2,3,0,1] row_mask:0xf bank_mask:0xf bound_ctrl:1
	v_xor_b32_e32 v199, v189, v47
	v_pk_add_f32 v[212:213], v[206:207], v[206:207] op_sel:[0,1] op_sel_hi:[1,0]
	v_add_f32_dpp v187, v208, v187 quad_perm:[1,0,3,2] row_mask:0xf bank_mask:0xf bound_ctrl:1
	v_xor_b32_e32 v193, v181, v210
	v_add_f32_dpp v47, v47, v199 quad_perm:[2,3,0,1] row_mask:0xf bank_mask:0xf bound_ctrl:1
	v_xor_b32_e32 v199, v189, v49
	v_add_f32_dpp v193, v210, v193 quad_perm:[1,0,3,2] row_mask:0xf bank_mask:0xf bound_ctrl:1
	v_xor_b32_e32 v194, v181, v212
	v_add_f32_dpp v49, v49, v199 quad_perm:[2,3,0,1] row_mask:0xf bank_mask:0xf bound_ctrl:1
	v_xor_b32_e32 v199, v189, v187
	v_add_f32_dpp v194, v212, v194 quad_perm:[1,0,3,2] row_mask:0xf bank_mask:0xf bound_ctrl:1
	v_xor_b32_e32 v195, v181, v214
	v_add_f32_dpp v187, v187, v199 quad_perm:[2,3,0,1] row_mask:0xf bank_mask:0xf bound_ctrl:1
	v_xor_b32_e32 v199, v189, v193
	v_add_f32_dpp v195, v214, v195 quad_perm:[1,0,3,2] row_mask:0xf bank_mask:0xf bound_ctrl:1
	v_xor_b32_e32 v197, v181, v196
	v_add_f32_dpp v193, v193, v199 quad_perm:[2,3,0,1] row_mask:0xf bank_mask:0xf bound_ctrl:1
	v_xor_b32_e32 v199, v189, v194
	v_pk_add_f32 v[202:203], v[202:203], v[202:203] op_sel:[0,1] op_sel_hi:[1,0] neg_lo:[0,1] neg_hi:[0,1]
	v_add_f32_dpp v196, v196, v197 quad_perm:[1,0,3,2] row_mask:0xf bank_mask:0xf bound_ctrl:1
	v_xor_b32_e32 v197, v181, v48
	v_add_f32_dpp v194, v194, v199 quad_perm:[2,3,0,1] row_mask:0xf bank_mask:0xf bound_ctrl:1
	v_xor_b32_e32 v199, v189, v195
	v_add_f32_dpp v48, v48, v197 quad_perm:[1,0,3,2] row_mask:0xf bank_mask:0xf bound_ctrl:1
	v_xor_b32_e32 v197, v181, v202
	v_add_f32_dpp v195, v195, v199 quad_perm:[2,3,0,1] row_mask:0xf bank_mask:0xf bound_ctrl:1
	v_xor_b32_e32 v199, v189, v196
	v_add_f32_dpp v197, v202, v197 quad_perm:[1,0,3,2] row_mask:0xf bank_mask:0xf bound_ctrl:1
	v_xor_b32_e32 v198, v181, v46
	v_add_f32_dpp v196, v196, v199 quad_perm:[2,3,0,1] row_mask:0xf bank_mask:0xf bound_ctrl:1
	v_xor_b32_e32 v199, v189, v48
	v_add_f32_dpp v46, v46, v198 quad_perm:[1,0,3,2] row_mask:0xf bank_mask:0xf bound_ctrl:1
	v_xor_b32_e32 v198, v181, v40
	v_add_f32_dpp v48, v48, v199 quad_perm:[2,3,0,1] row_mask:0xf bank_mask:0xf bound_ctrl:1
	v_xor_b32_e32 v199, v189, v197
	v_pk_add_f32 v[206:207], v[206:207], v[206:207] op_sel:[0,1] op_sel_hi:[1,0] neg_lo:[0,1] neg_hi:[0,1]
	v_add_f32_dpp v40, v40, v198 quad_perm:[1,0,3,2] row_mask:0xf bank_mask:0xf bound_ctrl:1
	v_xor_b32_e32 v198, v181, v38
	v_add_f32_dpp v197, v197, v199 quad_perm:[2,3,0,1] row_mask:0xf bank_mask:0xf bound_ctrl:1
	v_xor_b32_e32 v199, v189, v46
	v_add_f32_dpp v38, v38, v198 quad_perm:[1,0,3,2] row_mask:0xf bank_mask:0xf bound_ctrl:1
	v_xor_b32_e32 v198, v181, v206
	v_add_f32_dpp v199, v46, v199 quad_perm:[2,3,0,1] row_mask:0xf bank_mask:0xf bound_ctrl:1
	v_xor_b32_e32 v46, v189, v40
	v_add_f32_dpp v198, v206, v198 quad_perm:[1,0,3,2] row_mask:0xf bank_mask:0xf bound_ctrl:1
	s_nop 0
	v_add_f32_dpp v200, v40, v46 quad_perm:[2,3,0,1] row_mask:0xf bank_mask:0xf bound_ctrl:1
	v_xor_b32_e32 v40, v189, v38
	v_max_f32_e64 v46, |v194|, |v195|
	s_nop 0
	v_add_f32_dpp v201, v38, v40 quad_perm:[2,3,0,1] row_mask:0xf bank_mask:0xf bound_ctrl:1
	v_xor_b32_e32 v38, v189, v198
	v_max_f32_e64 v40, |v47|, |v49|
	s_nop 0
	v_add_f32_dpp v198, v198, v38 quad_perm:[2,3,0,1] row_mask:0xf bank_mask:0xf bound_ctrl:1
	v_xor_b32_e32 v38, v189, v186
	s_nop 1
	v_add_f32_dpp v186, v186, v38 quad_perm:[2,3,0,1] row_mask:0xf bank_mask:0xf bound_ctrl:1
	v_max_f32_e64 v38, |v39|, |v41|
	v_max3_f32 v38, v216, v38, v40
	v_max_f32_e64 v40, |v187|, |v193|
	v_max3_f32 v38, v38, v40, v46
	v_max_f32_e64 v40, |v196|, |v48|
	v_max_f32_e64 v46, |v197|, |v199|
	v_max3_f32 v38, v38, v40, v46
	v_max_f32_e64 v40, |v200|, |v201|
	v_max_f32_e64 v46, |v198|, |v186|
	v_max3_f32 v216, v38, v40, v46
	v_cvt_pk_bf16_f32 v38, v39, v41
	v_cvt_pk_bf16_f32 v39, v47, v49
	v_cvt_pk_bf16_f32 v40, v187, v193
	v_cvt_pk_bf16_f32 v41, v194, v195
	v_cvt_pk_bf16_f32 v46, v196, v48
	v_cvt_pk_bf16_f32 v47, v197, v199
	v_cvt_pk_bf16_f32 v48, v200, v201
	v_cvt_pk_bf16_f32 v49, v198, v186
	v_and_b32_e32 v187, 0xffff0000, v57
	v_and_b32_e32 v186, 0xffff0000, v53
	v_lshlrev_b32_e32 v195, 16, v54
	v_lshlrev_b32_e32 v194, 16, v50
	v_and_b32_e32 v197, 0xffff0000, v54
	v_and_b32_e32 v196, 0xffff0000, v50
	v_lshlrev_b32_e32 v199, 16, v55
	v_lshlrev_b32_e32 v198, 16, v51
	v_and_b32_e32 v55, 0xffff0000, v55
	v_and_b32_e32 v54, 0xffff0000, v51
	v_lshlrev_b32_e32 v51, 16, v56
	v_lshlrev_b32_e32 v50, 16, v52
	v_and_b32_e32 v201, 0xffff0000, v56
	v_and_b32_e32 v200, 0xffff0000, v52
	v_lshlrev_b32_e32 v57, 16, v57
	v_lshlrev_b32_e32 v56, 16, v53
	v_pk_add_f32 v[52:53], v[194:195], v[196:197]
	v_pk_add_f32 v[202:203], v[198:199], v[54:55]
	v_pk_add_f32 v[204:205], v[50:51], v[200:201]
	v_pk_add_f32 v[206:207], v[56:57], v[186:187]
	v_pk_add_f32 v[194:195], v[194:195], v[196:197] neg_lo:[0,1] neg_hi:[0,1]
	v_pk_add_f32 v[54:55], v[198:199], v[54:55] neg_lo:[0,1] neg_hi:[0,1]
	v_pk_add_f32 v[50:51], v[50:51], v[200:201] neg_lo:[0,1] neg_hi:[0,1]
	v_pk_add_f32 v[56:57], v[56:57], v[186:187] neg_lo:[0,1] neg_hi:[0,1]
	v_pk_add_f32 v[208:209], v[52:53], v[202:203] neg_lo:[0,1] neg_hi:[0,1]
	v_pk_add_f32 v[52:53], v[52:53], v[202:203]
	v_pk_add_f32 v[202:203], v[204:205], v[206:207]
	v_pk_add_f32 v[186:187], v[194:195], v[54:55] neg_lo:[0,1] neg_hi:[0,1]
	v_pk_add_f32 v[196:197], v[50:51], v[56:57] neg_lo:[0,1] neg_hi:[0,1]
	v_pk_add_f32 v[54:55], v[194:195], v[54:55]
	v_pk_add_f32 v[50:51], v[50:51], v[56:57]
	v_pk_add_f32 v[210:211], v[204:205], v[206:207] neg_lo:[0,1] neg_hi:[0,1]
	v_pk_add_f32 v[204:205], v[52:53], v[202:203]
	v_pk_add_f32 v[56:57], v[54:55], v[50:51]
	v_pk_add_f32 v[50:51], v[54:55], v[50:51] neg_lo:[0,1] neg_hi:[0,1]
	v_pk_add_f32 v[52:53], v[52:53], v[202:203] neg_lo:[0,1] neg_hi:[0,1]
	v_pk_add_f32 v[202:203], v[208:209], v[210:211]
	v_pk_add_f32 v[206:207], v[208:209], v[210:211] neg_lo:[0,1] neg_hi:[0,1]
	v_pk_add_f32 v[54:55], v[186:187], v[196:197]
	v_pk_add_f32 v[186:187], v[186:187], v[196:197] neg_lo:[0,1] neg_hi:[0,1]
	v_pk_add_f32 v[194:195], v[204:205], v[204:205] op_sel:[0,1] op_sel_hi:[1,0]
	v_pk_add_f32 v[210:211], v[50:51], v[50:51] op_sel:[0,1] op_sel_hi:[1,0]
	v_pk_add_f32 v[50:51], v[50:51], v[50:51] op_sel:[0,1] op_sel_hi:[1,0] neg_lo:[0,1] neg_hi:[0,1]
	v_pk_add_f32 v[198:199], v[56:57], v[56:57] op_sel:[0,1] op_sel_hi:[1,0]
	v_pk_add_f32 v[208:209], v[52:53], v[52:53] op_sel:[0,1] op_sel_hi:[1,0]
	v_pk_add_f32 v[52:53], v[52:53], v[52:53] op_sel:[0,1] op_sel_hi:[1,0] neg_lo:[0,1] neg_hi:[0,1]
	v_pk_add_f32 v[214:215], v[186:187], v[186:187] op_sel:[0,1] op_sel_hi:[1,0]
	v_pk_add_f32 v[186:187], v[186:187], v[186:187] op_sel:[0,1] op_sel_hi:[1,0] neg_lo:[0,1] neg_hi:[0,1]
	v_xor_b32_e32 v51, v181, v194
	v_pk_add_f32 v[196:197], v[204:205], v[204:205] op_sel:[0,1] op_sel_hi:[1,0] neg_lo:[0,1] neg_hi:[0,1]
	v_pk_add_f32 v[200:201], v[202:203], v[202:203] op_sel:[0,1] op_sel_hi:[1,0]
	v_pk_add_f32 v[204:205], v[54:55], v[54:55] op_sel:[0,1] op_sel_hi:[1,0]
	v_pk_add_f32 v[54:55], v[54:55], v[54:55] op_sel:[0,1] op_sel_hi:[1,0] neg_lo:[0,1] neg_hi:[0,1]
	v_add_f32_dpp v51, v194, v51 quad_perm:[1,0,3,2] row_mask:0xf bank_mask:0xf bound_ctrl:1
	v_xor_b32_e32 v53, v181, v198
	v_xor_b32_e32 v199, v181, v186
	v_pk_add_f32 v[56:57], v[56:57], v[56:57] op_sel:[0,1] op_sel_hi:[1,0] neg_lo:[0,1] neg_hi:[0,1]
	v_add_f32_dpp v53, v198, v53 quad_perm:[1,0,3,2] row_mask:0xf bank_mask:0xf bound_ctrl:1
	v_xor_b32_e32 v55, v181, v200
	v_add_f32_dpp v186, v186, v199 quad_perm:[1,0,3,2] row_mask:0xf bank_mask:0xf bound_ctrl:1
	v_xor_b32_e32 v199, v189, v51
	v_add_f32_dpp v55, v200, v55 quad_perm:[1,0,3,2] row_mask:0xf bank_mask:0xf bound_ctrl:1
	v_xor_b32_e32 v57, v181, v204
	v_add_f32_dpp v51, v51, v199 quad_perm:[2,3,0,1] row_mask:0xf bank_mask:0xf bound_ctrl:1
	v_xor_b32_e32 v199, v189, v53
	v_add_f32_dpp v57, v204, v57 quad_perm:[1,0,3,2] row_mask:0xf bank_mask:0xf bound_ctrl:1
	v_xor_b32_e32 v187, v181, v208
	v_add_f32_dpp v53, v53, v199 quad_perm:[2,3,0,1] row_mask:0xf bank_mask:0xf bound_ctrl:1
	v_xor_b32_e32 v199, v189, v55
	v_pk_add_f32 v[212:213], v[206:207], v[206:207] op_sel:[0,1] op_sel_hi:[1,0]
	v_add_f32_dpp v187, v208, v187 quad_perm:[1,0,3,2] row_mask:0xf bank_mask:0xf bound_ctrl:1
	v_xor_b32_e32 v193, v181, v210
	v_add_f32_dpp v55, v55, v199 quad_perm:[2,3,0,1] row_mask:0xf bank_mask:0xf bound_ctrl:1
	v_xor_b32_e32 v199, v189, v57
	v_add_f32_dpp v193, v210, v193 quad_perm:[1,0,3,2] row_mask:0xf bank_mask:0xf bound_ctrl:1
	v_xor_b32_e32 v194, v181, v212
	v_add_f32_dpp v57, v57, v199 quad_perm:[2,3,0,1] row_mask:0xf bank_mask:0xf bound_ctrl:1
	v_xor_b32_e32 v199, v189, v187
	v_add_f32_dpp v194, v212, v194 quad_perm:[1,0,3,2] row_mask:0xf bank_mask:0xf bound_ctrl:1
	v_xor_b32_e32 v195, v181, v214
	v_add_f32_dpp v187, v187, v199 quad_perm:[2,3,0,1] row_mask:0xf bank_mask:0xf bound_ctrl:1
	v_xor_b32_e32 v199, v189, v193
	v_add_f32_dpp v195, v214, v195 quad_perm:[1,0,3,2] row_mask:0xf bank_mask:0xf bound_ctrl:1
	v_xor_b32_e32 v197, v181, v196
	v_add_f32_dpp v193, v193, v199 quad_perm:[2,3,0,1] row_mask:0xf bank_mask:0xf bound_ctrl:1
	v_xor_b32_e32 v199, v189, v194
	v_pk_add_f32 v[202:203], v[202:203], v[202:203] op_sel:[0,1] op_sel_hi:[1,0] neg_lo:[0,1] neg_hi:[0,1]
	v_add_f32_dpp v196, v196, v197 quad_perm:[1,0,3,2] row_mask:0xf bank_mask:0xf bound_ctrl:1
	v_xor_b32_e32 v197, v181, v56
	v_add_f32_dpp v194, v194, v199 quad_perm:[2,3,0,1] row_mask:0xf bank_mask:0xf bound_ctrl:1
	v_xor_b32_e32 v199, v189, v195
	v_add_f32_dpp v56, v56, v197 quad_perm:[1,0,3,2] row_mask:0xf bank_mask:0xf bound_ctrl:1
	v_xor_b32_e32 v197, v181, v202
	v_add_f32_dpp v195, v195, v199 quad_perm:[2,3,0,1] row_mask:0xf bank_mask:0xf bound_ctrl:1
	v_xor_b32_e32 v199, v189, v196
	v_add_f32_dpp v197, v202, v197 quad_perm:[1,0,3,2] row_mask:0xf bank_mask:0xf bound_ctrl:1
	v_xor_b32_e32 v198, v181, v54
	v_add_f32_dpp v196, v196, v199 quad_perm:[2,3,0,1] row_mask:0xf bank_mask:0xf bound_ctrl:1
	v_xor_b32_e32 v199, v189, v56
	v_add_f32_dpp v54, v54, v198 quad_perm:[1,0,3,2] row_mask:0xf bank_mask:0xf bound_ctrl:1
	v_xor_b32_e32 v198, v181, v52
	v_add_f32_dpp v56, v56, v199 quad_perm:[2,3,0,1] row_mask:0xf bank_mask:0xf bound_ctrl:1
	v_xor_b32_e32 v199, v189, v197
	v_pk_add_f32 v[206:207], v[206:207], v[206:207] op_sel:[0,1] op_sel_hi:[1,0] neg_lo:[0,1] neg_hi:[0,1]
	v_add_f32_dpp v52, v52, v198 quad_perm:[1,0,3,2] row_mask:0xf bank_mask:0xf bound_ctrl:1
	v_xor_b32_e32 v198, v181, v50
	v_add_f32_dpp v197, v197, v199 quad_perm:[2,3,0,1] row_mask:0xf bank_mask:0xf bound_ctrl:1
	v_xor_b32_e32 v199, v189, v54
	v_add_f32_dpp v50, v50, v198 quad_perm:[1,0,3,2] row_mask:0xf bank_mask:0xf bound_ctrl:1
	v_xor_b32_e32 v198, v181, v206
	v_add_f32_dpp v199, v54, v199 quad_perm:[2,3,0,1] row_mask:0xf bank_mask:0xf bound_ctrl:1
	v_xor_b32_e32 v54, v189, v52
	v_add_f32_dpp v198, v206, v198 quad_perm:[1,0,3,2] row_mask:0xf bank_mask:0xf bound_ctrl:1
	s_nop 0
	v_add_f32_dpp v200, v52, v54 quad_perm:[2,3,0,1] row_mask:0xf bank_mask:0xf bound_ctrl:1
	v_xor_b32_e32 v52, v189, v50
	v_max_f32_e64 v54, |v194|, |v195|
	s_nop 0
	v_add_f32_dpp v201, v50, v52 quad_perm:[2,3,0,1] row_mask:0xf bank_mask:0xf bound_ctrl:1
	v_xor_b32_e32 v50, v189, v198
	v_max_f32_e64 v52, |v55|, |v57|
	s_nop 0
	v_add_f32_dpp v198, v198, v50 quad_perm:[2,3,0,1] row_mask:0xf bank_mask:0xf bound_ctrl:1
	v_xor_b32_e32 v50, v189, v186
	s_nop 1
	v_add_f32_dpp v186, v186, v50 quad_perm:[2,3,0,1] row_mask:0xf bank_mask:0xf bound_ctrl:1
	v_max_f32_e64 v50, |v51|, |v53|
	v_max3_f32 v50, v216, v50, v52
	v_max_f32_e64 v52, |v187|, |v193|
	v_max3_f32 v50, v50, v52, v54
	v_max_f32_e64 v52, |v196|, |v56|
	v_max_f32_e64 v54, |v197|, |v199|
	v_max3_f32 v50, v50, v52, v54
	v_max_f32_e64 v52, |v200|, |v201|
	v_max_f32_e64 v54, |v198|, |v186|
	v_max3_f32 v216, v50, v52, v54
	v_cvt_pk_bf16_f32 v50, v51, v53
	v_cvt_pk_bf16_f32 v51, v55, v57
	v_cvt_pk_bf16_f32 v52, v187, v193
	v_cvt_pk_bf16_f32 v53, v194, v195
	v_cvt_pk_bf16_f32 v54, v196, v56
	v_cvt_pk_bf16_f32 v55, v197, v199
	v_cvt_pk_bf16_f32 v56, v200, v201
	v_cvt_pk_bf16_f32 v57, v198, v186
	v_and_b32_e32 v187, 0xffff0000, v65
	v_and_b32_e32 v186, 0xffff0000, v61
	v_lshlrev_b32_e32 v195, 16, v62
	v_lshlrev_b32_e32 v194, 16, v58
	v_and_b32_e32 v197, 0xffff0000, v62
	v_and_b32_e32 v196, 0xffff0000, v58
	v_lshlrev_b32_e32 v199, 16, v63
	v_lshlrev_b32_e32 v198, 16, v59
	v_and_b32_e32 v63, 0xffff0000, v63
	v_and_b32_e32 v62, 0xffff0000, v59
	v_lshlrev_b32_e32 v59, 16, v64
	v_lshlrev_b32_e32 v58, 16, v60
	v_and_b32_e32 v201, 0xffff0000, v64
	v_and_b32_e32 v200, 0xffff0000, v60
	v_lshlrev_b32_e32 v65, 16, v65
	v_lshlrev_b32_e32 v64, 16, v61
	v_pk_add_f32 v[60:61], v[194:195], v[196:197]
	v_pk_add_f32 v[202:203], v[198:199], v[62:63]
	v_pk_add_f32 v[204:205], v[58:59], v[200:201]
	v_pk_add_f32 v[206:207], v[64:65], v[186:187]
	v_pk_add_f32 v[194:195], v[194:195], v[196:197] neg_lo:[0,1] neg_hi:[0,1]
	v_pk_add_f32 v[62:63], v[198:199], v[62:63] neg_lo:[0,1] neg_hi:[0,1]
	v_pk_add_f32 v[58:59], v[58:59], v[200:201] neg_lo:[0,1] neg_hi:[0,1]
	v_pk_add_f32 v[64:65], v[64:65], v[186:187] neg_lo:[0,1] neg_hi:[0,1]
	v_pk_add_f32 v[208:209], v[60:61], v[202:203] neg_lo:[0,1] neg_hi:[0,1]
	v_pk_add_f32 v[60:61], v[60:61], v[202:203]
	v_pk_add_f32 v[202:203], v[204:205], v[206:207]
	v_pk_add_f32 v[186:187], v[194:195], v[62:63] neg_lo:[0,1] neg_hi:[0,1]
	v_pk_add_f32 v[196:197], v[58:59], v[64:65] neg_lo:[0,1] neg_hi:[0,1]
	v_pk_add_f32 v[62:63], v[194:195], v[62:63]
	v_pk_add_f32 v[58:59], v[58:59], v[64:65]
	v_pk_add_f32 v[210:211], v[204:205], v[206:207] neg_lo:[0,1] neg_hi:[0,1]
	v_pk_add_f32 v[204:205], v[60:61], v[202:203]
	v_pk_add_f32 v[64:65], v[62:63], v[58:59]
	v_pk_add_f32 v[58:59], v[62:63], v[58:59] neg_lo:[0,1] neg_hi:[0,1]
	v_pk_add_f32 v[60:61], v[60:61], v[202:203] neg_lo:[0,1] neg_hi:[0,1]
	v_pk_add_f32 v[202:203], v[208:209], v[210:211]
	v_pk_add_f32 v[206:207], v[208:209], v[210:211] neg_lo:[0,1] neg_hi:[0,1]
	v_pk_add_f32 v[62:63], v[186:187], v[196:197]
	v_pk_add_f32 v[186:187], v[186:187], v[196:197] neg_lo:[0,1] neg_hi:[0,1]
	v_pk_add_f32 v[194:195], v[204:205], v[204:205] op_sel:[0,1] op_sel_hi:[1,0]
	v_pk_add_f32 v[210:211], v[58:59], v[58:59] op_sel:[0,1] op_sel_hi:[1,0]
	v_pk_add_f32 v[58:59], v[58:59], v[58:59] op_sel:[0,1] op_sel_hi:[1,0] neg_lo:[0,1] neg_hi:[0,1]
	v_pk_add_f32 v[198:199], v[64:65], v[64:65] op_sel:[0,1] op_sel_hi:[1,0]
	v_pk_add_f32 v[208:209], v[60:61], v[60:61] op_sel:[0,1] op_sel_hi:[1,0]
	v_pk_add_f32 v[60:61], v[60:61], v[60:61] op_sel:[0,1] op_sel_hi:[1,0] neg_lo:[0,1] neg_hi:[0,1]
	v_pk_add_f32 v[214:215], v[186:187], v[186:187] op_sel:[0,1] op_sel_hi:[1,0]
	v_pk_add_f32 v[186:187], v[186:187], v[186:187] op_sel:[0,1] op_sel_hi:[1,0] neg_lo:[0,1] neg_hi:[0,1]
	v_xor_b32_e32 v59, v181, v194
	v_pk_add_f32 v[196:197], v[204:205], v[204:205] op_sel:[0,1] op_sel_hi:[1,0] neg_lo:[0,1] neg_hi:[0,1]
	v_pk_add_f32 v[200:201], v[202:203], v[202:203] op_sel:[0,1] op_sel_hi:[1,0]
	v_pk_add_f32 v[204:205], v[62:63], v[62:63] op_sel:[0,1] op_sel_hi:[1,0]
	v_pk_add_f32 v[62:63], v[62:63], v[62:63] op_sel:[0,1] op_sel_hi:[1,0] neg_lo:[0,1] neg_hi:[0,1]
	v_add_f32_dpp v59, v194, v59 quad_perm:[1,0,3,2] row_mask:0xf bank_mask:0xf bound_ctrl:1
	v_xor_b32_e32 v61, v181, v198
	v_xor_b32_e32 v199, v181, v186
	v_pk_add_f32 v[64:65], v[64:65], v[64:65] op_sel:[0,1] op_sel_hi:[1,0] neg_lo:[0,1] neg_hi:[0,1]
	v_add_f32_dpp v61, v198, v61 quad_perm:[1,0,3,2] row_mask:0xf bank_mask:0xf bound_ctrl:1
	v_xor_b32_e32 v63, v181, v200
	v_add_f32_dpp v186, v186, v199 quad_perm:[1,0,3,2] row_mask:0xf bank_mask:0xf bound_ctrl:1
	v_xor_b32_e32 v199, v189, v59
	v_add_f32_dpp v63, v200, v63 quad_perm:[1,0,3,2] row_mask:0xf bank_mask:0xf bound_ctrl:1
	v_xor_b32_e32 v65, v181, v204
	v_add_f32_dpp v59, v59, v199 quad_perm:[2,3,0,1] row_mask:0xf bank_mask:0xf bound_ctrl:1
	v_xor_b32_e32 v199, v189, v61
	v_add_f32_dpp v65, v204, v65 quad_perm:[1,0,3,2] row_mask:0xf bank_mask:0xf bound_ctrl:1
	v_xor_b32_e32 v187, v181, v208
	v_add_f32_dpp v61, v61, v199 quad_perm:[2,3,0,1] row_mask:0xf bank_mask:0xf bound_ctrl:1
	v_xor_b32_e32 v199, v189, v63
	v_pk_add_f32 v[212:213], v[206:207], v[206:207] op_sel:[0,1] op_sel_hi:[1,0]
	v_add_f32_dpp v187, v208, v187 quad_perm:[1,0,3,2] row_mask:0xf bank_mask:0xf bound_ctrl:1
	v_xor_b32_e32 v193, v181, v210
	v_add_f32_dpp v63, v63, v199 quad_perm:[2,3,0,1] row_mask:0xf bank_mask:0xf bound_ctrl:1
	v_xor_b32_e32 v199, v189, v65
	v_add_f32_dpp v193, v210, v193 quad_perm:[1,0,3,2] row_mask:0xf bank_mask:0xf bound_ctrl:1
	v_xor_b32_e32 v194, v181, v212
	v_add_f32_dpp v65, v65, v199 quad_perm:[2,3,0,1] row_mask:0xf bank_mask:0xf bound_ctrl:1
	v_xor_b32_e32 v199, v189, v187
	v_add_f32_dpp v194, v212, v194 quad_perm:[1,0,3,2] row_mask:0xf bank_mask:0xf bound_ctrl:1
	v_xor_b32_e32 v195, v181, v214
	v_add_f32_dpp v187, v187, v199 quad_perm:[2,3,0,1] row_mask:0xf bank_mask:0xf bound_ctrl:1
	v_xor_b32_e32 v199, v189, v193
	v_add_f32_dpp v195, v214, v195 quad_perm:[1,0,3,2] row_mask:0xf bank_mask:0xf bound_ctrl:1
	v_xor_b32_e32 v197, v181, v196
	v_add_f32_dpp v193, v193, v199 quad_perm:[2,3,0,1] row_mask:0xf bank_mask:0xf bound_ctrl:1
	v_xor_b32_e32 v199, v189, v194
	v_pk_add_f32 v[202:203], v[202:203], v[202:203] op_sel:[0,1] op_sel_hi:[1,0] neg_lo:[0,1] neg_hi:[0,1]
	v_add_f32_dpp v196, v196, v197 quad_perm:[1,0,3,2] row_mask:0xf bank_mask:0xf bound_ctrl:1
	v_xor_b32_e32 v197, v181, v64
	v_add_f32_dpp v194, v194, v199 quad_perm:[2,3,0,1] row_mask:0xf bank_mask:0xf bound_ctrl:1
	v_xor_b32_e32 v199, v189, v195
	v_add_f32_dpp v64, v64, v197 quad_perm:[1,0,3,2] row_mask:0xf bank_mask:0xf bound_ctrl:1
	v_xor_b32_e32 v197, v181, v202
	v_add_f32_dpp v195, v195, v199 quad_perm:[2,3,0,1] row_mask:0xf bank_mask:0xf bound_ctrl:1
	v_xor_b32_e32 v199, v189, v196
	v_add_f32_dpp v197, v202, v197 quad_perm:[1,0,3,2] row_mask:0xf bank_mask:0xf bound_ctrl:1
	v_xor_b32_e32 v198, v181, v62
	v_add_f32_dpp v196, v196, v199 quad_perm:[2,3,0,1] row_mask:0xf bank_mask:0xf bound_ctrl:1
	v_xor_b32_e32 v199, v189, v64
	v_add_f32_dpp v62, v62, v198 quad_perm:[1,0,3,2] row_mask:0xf bank_mask:0xf bound_ctrl:1
	v_xor_b32_e32 v198, v181, v60
	v_add_f32_dpp v64, v64, v199 quad_perm:[2,3,0,1] row_mask:0xf bank_mask:0xf bound_ctrl:1
	v_xor_b32_e32 v199, v189, v197
	v_pk_add_f32 v[206:207], v[206:207], v[206:207] op_sel:[0,1] op_sel_hi:[1,0] neg_lo:[0,1] neg_hi:[0,1]
	v_add_f32_dpp v60, v60, v198 quad_perm:[1,0,3,2] row_mask:0xf bank_mask:0xf bound_ctrl:1
	v_xor_b32_e32 v198, v181, v58
	v_add_f32_dpp v197, v197, v199 quad_perm:[2,3,0,1] row_mask:0xf bank_mask:0xf bound_ctrl:1
	v_xor_b32_e32 v199, v189, v62
	v_add_f32_dpp v58, v58, v198 quad_perm:[1,0,3,2] row_mask:0xf bank_mask:0xf bound_ctrl:1
	v_xor_b32_e32 v198, v181, v206
	v_add_f32_dpp v199, v62, v199 quad_perm:[2,3,0,1] row_mask:0xf bank_mask:0xf bound_ctrl:1
	v_xor_b32_e32 v62, v189, v60
	v_add_f32_dpp v198, v206, v198 quad_perm:[1,0,3,2] row_mask:0xf bank_mask:0xf bound_ctrl:1
	s_nop 0
	v_add_f32_dpp v200, v60, v62 quad_perm:[2,3,0,1] row_mask:0xf bank_mask:0xf bound_ctrl:1
	v_xor_b32_e32 v60, v189, v58
	v_max_f32_e64 v62, |v194|, |v195|
	s_nop 0
	v_add_f32_dpp v201, v58, v60 quad_perm:[2,3,0,1] row_mask:0xf bank_mask:0xf bound_ctrl:1
	v_xor_b32_e32 v58, v189, v198
	v_max_f32_e64 v60, |v63|, |v65|
	s_nop 0
	v_add_f32_dpp v198, v198, v58 quad_perm:[2,3,0,1] row_mask:0xf bank_mask:0xf bound_ctrl:1
	v_xor_b32_e32 v58, v189, v186
	s_nop 1
	v_add_f32_dpp v186, v186, v58 quad_perm:[2,3,0,1] row_mask:0xf bank_mask:0xf bound_ctrl:1
	v_max_f32_e64 v58, |v59|, |v61|
	v_max3_f32 v58, v216, v58, v60
	v_max_f32_e64 v60, |v187|, |v193|
	v_max3_f32 v58, v58, v60, v62
	v_max_f32_e64 v60, |v196|, |v64|
	v_max_f32_e64 v62, |v197|, |v199|
	v_max3_f32 v58, v58, v60, v62
	v_max_f32_e64 v60, |v200|, |v201|
	v_max_f32_e64 v62, |v198|, |v186|
	v_max3_f32 v216, v58, v60, v62
	v_cvt_pk_bf16_f32 v58, v59, v61
	v_cvt_pk_bf16_f32 v59, v63, v65
	v_cvt_pk_bf16_f32 v60, v187, v193
	v_cvt_pk_bf16_f32 v61, v194, v195
	v_cvt_pk_bf16_f32 v62, v196, v64
	v_cvt_pk_bf16_f32 v63, v197, v199
	v_cvt_pk_bf16_f32 v64, v200, v201
	v_cvt_pk_bf16_f32 v65, v198, v186
	v_and_b32_e32 v187, 0xffff0000, v157
	v_and_b32_e32 v186, 0xffff0000, v149
	v_lshlrev_b32_e32 v195, 16, v154
	v_lshlrev_b32_e32 v194, 16, v146
	v_and_b32_e32 v197, 0xffff0000, v154
	v_and_b32_e32 v196, 0xffff0000, v146
	v_lshlrev_b32_e32 v199, 16, v155
	v_lshlrev_b32_e32 v198, 16, v147
	v_and_b32_e32 v155, 0xffff0000, v155
	v_and_b32_e32 v154, 0xffff0000, v147
	v_lshlrev_b32_e32 v147, 16, v156
	v_lshlrev_b32_e32 v146, 16, v148
	v_and_b32_e32 v201, 0xffff0000, v156
	v_and_b32_e32 v200, 0xffff0000, v148
	v_lshlrev_b32_e32 v157, 16, v157
	v_lshlrev_b32_e32 v156, 16, v149
	v_pk_add_f32 v[148:149], v[194:195], v[196:197]
	v_pk_add_f32 v[202:203], v[198:199], v[154:155]
	v_pk_add_f32 v[204:205], v[146:147], v[200:201]
	v_pk_add_f32 v[206:207], v[156:157], v[186:187]
	v_pk_add_f32 v[194:195], v[194:195], v[196:197] neg_lo:[0,1] neg_hi:[0,1]
	v_pk_add_f32 v[154:155], v[198:199], v[154:155] neg_lo:[0,1] neg_hi:[0,1]
	v_pk_add_f32 v[146:147], v[146:147], v[200:201] neg_lo:[0,1] neg_hi:[0,1]
	v_pk_add_f32 v[156:157], v[156:157], v[186:187] neg_lo:[0,1] neg_hi:[0,1]
	v_pk_add_f32 v[208:209], v[148:149], v[202:203] neg_lo:[0,1] neg_hi:[0,1]
	v_pk_add_f32 v[148:149], v[148:149], v[202:203]
	v_pk_add_f32 v[202:203], v[204:205], v[206:207]
	v_pk_add_f32 v[186:187], v[194:195], v[154:155] neg_lo:[0,1] neg_hi:[0,1]
	v_pk_add_f32 v[196:197], v[146:147], v[156:157] neg_lo:[0,1] neg_hi:[0,1]
	v_pk_add_f32 v[154:155], v[194:195], v[154:155]
	v_pk_add_f32 v[146:147], v[146:147], v[156:157]
	v_pk_add_f32 v[210:211], v[204:205], v[206:207] neg_lo:[0,1] neg_hi:[0,1]
	v_pk_add_f32 v[204:205], v[148:149], v[202:203]
	v_pk_add_f32 v[156:157], v[154:155], v[146:147]
	v_pk_add_f32 v[146:147], v[154:155], v[146:147] neg_lo:[0,1] neg_hi:[0,1]
	v_pk_add_f32 v[148:149], v[148:149], v[202:203] neg_lo:[0,1] neg_hi:[0,1]
	v_pk_add_f32 v[202:203], v[208:209], v[210:211]
	v_pk_add_f32 v[206:207], v[208:209], v[210:211] neg_lo:[0,1] neg_hi:[0,1]
	v_pk_add_f32 v[154:155], v[186:187], v[196:197]
	v_pk_add_f32 v[186:187], v[186:187], v[196:197] neg_lo:[0,1] neg_hi:[0,1]
	v_pk_add_f32 v[194:195], v[204:205], v[204:205] op_sel:[0,1] op_sel_hi:[1,0]
	v_pk_add_f32 v[210:211], v[146:147], v[146:147] op_sel:[0,1] op_sel_hi:[1,0]
	v_pk_add_f32 v[146:147], v[146:147], v[146:147] op_sel:[0,1] op_sel_hi:[1,0] neg_lo:[0,1] neg_hi:[0,1]
	v_pk_add_f32 v[198:199], v[156:157], v[156:157] op_sel:[0,1] op_sel_hi:[1,0]
	v_pk_add_f32 v[208:209], v[148:149], v[148:149] op_sel:[0,1] op_sel_hi:[1,0]
	v_pk_add_f32 v[148:149], v[148:149], v[148:149] op_sel:[0,1] op_sel_hi:[1,0] neg_lo:[0,1] neg_hi:[0,1]
	v_pk_add_f32 v[214:215], v[186:187], v[186:187] op_sel:[0,1] op_sel_hi:[1,0]
	v_pk_add_f32 v[186:187], v[186:187], v[186:187] op_sel:[0,1] op_sel_hi:[1,0] neg_lo:[0,1] neg_hi:[0,1]
	v_xor_b32_e32 v147, v181, v194
	v_pk_add_f32 v[196:197], v[204:205], v[204:205] op_sel:[0,1] op_sel_hi:[1,0] neg_lo:[0,1] neg_hi:[0,1]
	v_pk_add_f32 v[200:201], v[202:203], v[202:203] op_sel:[0,1] op_sel_hi:[1,0]
	v_pk_add_f32 v[204:205], v[154:155], v[154:155] op_sel:[0,1] op_sel_hi:[1,0]
	v_pk_add_f32 v[154:155], v[154:155], v[154:155] op_sel:[0,1] op_sel_hi:[1,0] neg_lo:[0,1] neg_hi:[0,1]
	v_add_f32_dpp v147, v194, v147 quad_perm:[1,0,3,2] row_mask:0xf bank_mask:0xf bound_ctrl:1
	v_xor_b32_e32 v149, v181, v198
	v_xor_b32_e32 v199, v181, v186
	v_pk_add_f32 v[156:157], v[156:157], v[156:157] op_sel:[0,1] op_sel_hi:[1,0] neg_lo:[0,1] neg_hi:[0,1]
	v_add_f32_dpp v149, v198, v149 quad_perm:[1,0,3,2] row_mask:0xf bank_mask:0xf bound_ctrl:1
	v_xor_b32_e32 v155, v181, v200
	v_xor_b32_e32 v187, v181, v208
	v_add_f32_dpp v186, v186, v199 quad_perm:[1,0,3,2] row_mask:0xf bank_mask:0xf bound_ctrl:1
	v_xor_b32_e32 v199, v189, v147
	v_add_f32_dpp v155, v200, v155 quad_perm:[1,0,3,2] row_mask:0xf bank_mask:0xf bound_ctrl:1
	v_xor_b32_e32 v157, v181, v204
	v_add_f32_dpp v187, v208, v187 quad_perm:[1,0,3,2] row_mask:0xf bank_mask:0xf bound_ctrl:1
	v_add_f32_dpp v208, v147, v199 quad_perm:[2,3,0,1] row_mask:0xf bank_mask:0xf bound_ctrl:1
	v_xor_b32_e32 v147, v189, v149
	v_add_f32_dpp v157, v204, v157 quad_perm:[1,0,3,2] row_mask:0xf bank_mask:0xf bound_ctrl:1
	v_xor_b32_e32 v193, v181, v210
	v_add_f32_dpp v209, v149, v147 quad_perm:[2,3,0,1] row_mask:0xf bank_mask:0xf bound_ctrl:1
	v_xor_b32_e32 v147, v189, v155
	v_pk_add_f32 v[212:213], v[206:207], v[206:207] op_sel:[0,1] op_sel_hi:[1,0]
	v_add_f32_dpp v193, v210, v193 quad_perm:[1,0,3,2] row_mask:0xf bank_mask:0xf bound_ctrl:1
	v_add_f32_dpp v210, v155, v147 quad_perm:[2,3,0,1] row_mask:0xf bank_mask:0xf bound_ctrl:1
	v_xor_b32_e32 v147, v189, v157
	v_xor_b32_e32 v194, v181, v212
	v_xor_b32_e32 v195, v181, v214
	v_add_f32_dpp v211, v157, v147 quad_perm:[2,3,0,1] row_mask:0xf bank_mask:0xf bound_ctrl:1
	v_xor_b32_e32 v147, v189, v187
	v_add_f32_dpp v194, v212, v194 quad_perm:[1,0,3,2] row_mask:0xf bank_mask:0xf bound_ctrl:1
	v_add_f32_dpp v195, v214, v195 quad_perm:[1,0,3,2] row_mask:0xf bank_mask:0xf bound_ctrl:1
	v_add_f32_dpp v212, v187, v147 quad_perm:[2,3,0,1] row_mask:0xf bank_mask:0xf bound_ctrl:1
	v_xor_b32_e32 v147, v189, v193
	v_xor_b32_e32 v197, v181, v196
	v_pk_add_f32 v[202:203], v[202:203], v[202:203] op_sel:[0,1] op_sel_hi:[1,0] neg_lo:[0,1] neg_hi:[0,1]
	v_add_f32_dpp v213, v193, v147 quad_perm:[2,3,0,1] row_mask:0xf bank_mask:0xf bound_ctrl:1
	v_xor_b32_e32 v147, v189, v194
	v_add_f32_dpp v196, v196, v197 quad_perm:[1,0,3,2] row_mask:0xf bank_mask:0xf bound_ctrl:1
	v_xor_b32_e32 v197, v181, v156
	v_add_f32_dpp v214, v194, v147 quad_perm:[2,3,0,1] row_mask:0xf bank_mask:0xf bound_ctrl:1
	v_xor_b32_e32 v147, v189, v195
	v_add_f32_dpp v156, v156, v197 quad_perm:[1,0,3,2] row_mask:0xf bank_mask:0xf bound_ctrl:1
	v_xor_b32_e32 v197, v181, v202
	v_add_f32_dpp v215, v195, v147 quad_perm:[2,3,0,1] row_mask:0xf bank_mask:0xf bound_ctrl:1
	v_xor_b32_e32 v147, v189, v196
	v_add_f32_dpp v197, v202, v197 quad_perm:[1,0,3,2] row_mask:0xf bank_mask:0xf bound_ctrl:1
	v_xor_b32_e32 v198, v181, v154
	v_add_f32_dpp v217, v196, v147 quad_perm:[2,3,0,1] row_mask:0xf bank_mask:0xf bound_ctrl:1
	v_xor_b32_e32 v147, v189, v156
	v_add_f32_dpp v154, v154, v198 quad_perm:[1,0,3,2] row_mask:0xf bank_mask:0xf bound_ctrl:1
	v_xor_b32_e32 v198, v181, v148
	v_add_f32_dpp v218, v156, v147 quad_perm:[2,3,0,1] row_mask:0xf bank_mask:0xf bound_ctrl:1
	v_xor_b32_e32 v147, v189, v197
	v_pk_add_f32 v[206:207], v[206:207], v[206:207] op_sel:[0,1] op_sel_hi:[1,0] neg_lo:[0,1] neg_hi:[0,1]
	v_add_f32_dpp v148, v148, v198 quad_perm:[1,0,3,2] row_mask:0xf bank_mask:0xf bound_ctrl:1
	v_xor_b32_e32 v198, v181, v146
	v_add_f32_dpp v219, v197, v147 quad_perm:[2,3,0,1] row_mask:0xf bank_mask:0xf bound_ctrl:1
	v_xor_b32_e32 v147, v189, v154
	v_add_f32_dpp v146, v146, v198 quad_perm:[1,0,3,2] row_mask:0xf bank_mask:0xf bound_ctrl:1
	v_xor_b32_e32 v198, v181, v206
	v_add_f32_dpp v220, v154, v147 quad_perm:[2,3,0,1] row_mask:0xf bank_mask:0xf bound_ctrl:1
	v_xor_b32_e32 v147, v189, v148
	v_add_f32_dpp v198, v206, v198 quad_perm:[1,0,3,2] row_mask:0xf bank_mask:0xf bound_ctrl:1
	s_waitcnt vmcnt(0)
	v_lshlrev_b32_e32 v149, 16, v110
	v_add_f32_dpp v221, v148, v147 quad_perm:[2,3,0,1] row_mask:0xf bank_mask:0xf bound_ctrl:1
	v_xor_b32_e32 v147, v189, v146
	v_max_f32_e64 v148, |v214|, |v215|
	v_and_b32_e32 v155, 0xffff0000, v110
	v_add_f32_dpp v222, v146, v147 quad_perm:[2,3,0,1] row_mask:0xf bank_mask:0xf bound_ctrl:1
	v_xor_b32_e32 v146, v189, v198
	v_max_f32_e64 v147, |v210|, |v211|
	v_and_b32_e32 v154, 0xffff0000, v98
	v_add_f32_dpp v223, v198, v146 quad_perm:[2,3,0,1] row_mask:0xf bank_mask:0xf bound_ctrl:1
	v_xor_b32_e32 v146, v189, v186
	v_lshlrev_b32_e32 v157, 16, v111
	v_lshlrev_b32_e32 v156, 16, v99
	v_add_f32_dpp v224, v186, v146 quad_perm:[2,3,0,1] row_mask:0xf bank_mask:0xf bound_ctrl:1
	v_max_f32_e64 v146, |v208|, |v209|
	v_max3_f32 v146, v216, v146, v147
	v_max_f32_e64 v147, |v212|, |v213|
	v_max3_f32 v146, v146, v147, v148
	v_max_f32_e64 v147, |v217|, |v218|
	v_max_f32_e64 v148, |v219|, |v220|
	v_max3_f32 v146, v146, v147, v148
	v_max_f32_e64 v147, |v221|, |v222|
	v_max_f32_e64 v148, |v223|, |v224|
	v_max3_f32 v193, v146, v147, v148
	v_and_b32_e32 v147, 0xffff0000, v113
	v_and_b32_e32 v146, 0xffff0000, v101
	v_lshlrev_b32_e32 v148, 16, v98
	v_and_b32_e32 v111, 0xffff0000, v111
	v_and_b32_e32 v110, 0xffff0000, v99
	v_lshlrev_b32_e32 v99, 16, v112
	v_lshlrev_b32_e32 v98, 16, v100
	v_and_b32_e32 v187, 0xffff0000, v112
	v_and_b32_e32 v186, 0xffff0000, v100
	v_lshlrev_b32_e32 v113, 16, v113
	v_lshlrev_b32_e32 v112, 16, v101
	v_pk_add_f32 v[100:101], v[148:149], v[154:155]
	v_pk_add_f32 v[194:195], v[156:157], v[110:111]
	v_pk_add_f32 v[196:197], v[98:99], v[186:187]
	v_pk_add_f32 v[198:199], v[112:113], v[146:147]
	v_pk_add_f32 v[148:149], v[148:149], v[154:155] neg_lo:[0,1] neg_hi:[0,1]
	v_pk_add_f32 v[110:111], v[156:157], v[110:111] neg_lo:[0,1] neg_hi:[0,1]
	v_pk_add_f32 v[98:99], v[98:99], v[186:187] neg_lo:[0,1] neg_hi:[0,1]
	v_pk_add_f32 v[112:113], v[112:113], v[146:147] neg_lo:[0,1] neg_hi:[0,1]
	v_pk_add_f32 v[200:201], v[100:101], v[194:195] neg_lo:[0,1] neg_hi:[0,1]
	v_pk_add_f32 v[202:203], v[196:197], v[198:199] neg_lo:[0,1] neg_hi:[0,1]
	v_pk_add_f32 v[100:101], v[100:101], v[194:195]
	v_pk_add_f32 v[194:195], v[196:197], v[198:199]
	v_pk_add_f32 v[146:147], v[148:149], v[110:111] neg_lo:[0,1] neg_hi:[0,1]
	v_pk_add_f32 v[154:155], v[98:99], v[112:113] neg_lo:[0,1] neg_hi:[0,1]
	v_pk_add_f32 v[110:111], v[148:149], v[110:111]
	v_pk_add_f32 v[98:99], v[98:99], v[112:113]
	v_pk_add_f32 v[196:197], v[100:101], v[194:195]
	v_pk_add_f32 v[100:101], v[100:101], v[194:195] neg_lo:[0,1] neg_hi:[0,1]
	v_pk_add_f32 v[194:195], v[200:201], v[202:203]
	v_pk_add_f32 v[112:113], v[110:111], v[98:99]
	v_pk_add_f32 v[98:99], v[110:111], v[98:99] neg_lo:[0,1] neg_hi:[0,1]
	v_pk_add_f32 v[110:111], v[146:147], v[154:155]
	v_pk_add_f32 v[198:199], v[200:201], v[202:203] neg_lo:[0,1] neg_hi:[0,1]
	v_pk_add_f32 v[146:147], v[146:147], v[154:155] neg_lo:[0,1] neg_hi:[0,1]
	v_pk_add_f32 v[148:149], v[196:197], v[196:197] op_sel:[0,1] op_sel_hi:[1,0]
	v_pk_add_f32 v[154:155], v[196:197], v[196:197] op_sel:[0,1] op_sel_hi:[1,0] neg_lo:[0,1] neg_hi:[0,1]
	v_pk_add_f32 v[186:187], v[194:195], v[194:195] op_sel:[0,1] op_sel_hi:[1,0]
	v_pk_add_f32 v[196:197], v[110:111], v[110:111] op_sel:[0,1] op_sel_hi:[1,0]
	v_pk_add_f32 v[110:111], v[110:111], v[110:111] op_sel:[0,1] op_sel_hi:[1,0] neg_lo:[0,1] neg_hi:[0,1]
	v_pk_add_f32 v[202:203], v[98:99], v[98:99] op_sel:[0,1] op_sel_hi:[1,0]
	v_pk_add_f32 v[98:99], v[98:99], v[98:99] op_sel:[0,1] op_sel_hi:[1,0] neg_lo:[0,1] neg_hi:[0,1]
	v_pk_add_f32 v[156:157], v[112:113], v[112:113] op_sel:[0,1] op_sel_hi:[1,0]
	v_pk_add_f32 v[200:201], v[100:101], v[100:101] op_sel:[0,1] op_sel_hi:[1,0]
	v_pk_add_f32 v[100:101], v[100:101], v[100:101] op_sel:[0,1] op_sel_hi:[1,0] neg_lo:[0,1] neg_hi:[0,1]
	v_pk_add_f32 v[206:207], v[146:147], v[146:147] op_sel:[0,1] op_sel_hi:[1,0]
	v_pk_add_f32 v[146:147], v[146:147], v[146:147] op_sel:[0,1] op_sel_hi:[1,0] neg_lo:[0,1] neg_hi:[0,1]
	v_xor_b32_e32 v99, v181, v148
	v_xor_b32_e32 v111, v181, v186
	v_xor_b32_e32 v101, v181, v156
	v_add_f32_dpp v99, v148, v99 quad_perm:[1,0,3,2] row_mask:0xf bank_mask:0xf bound_ctrl:1
	v_add_f32_dpp v111, v186, v111 quad_perm:[1,0,3,2] row_mask:0xf bank_mask:0xf bound_ctrl:1
	v_xor_b32_e32 v186, v181, v146
	v_pk_add_f32 v[112:113], v[112:113], v[112:113] op_sel:[0,1] op_sel_hi:[1,0] neg_lo:[0,1] neg_hi:[0,1]
	v_add_f32_dpp v101, v156, v101 quad_perm:[1,0,3,2] row_mask:0xf bank_mask:0xf bound_ctrl:1
	v_xor_b32_e32 v147, v181, v200
	v_add_f32_dpp v146, v146, v186 quad_perm:[1,0,3,2] row_mask:0xf bank_mask:0xf bound_ctrl:1
	v_xor_b32_e32 v186, v189, v99
	v_xor_b32_e32 v113, v181, v196
	v_add_f32_dpp v147, v200, v147 quad_perm:[1,0,3,2] row_mask:0xf bank_mask:0xf bound_ctrl:1
	v_add_f32_dpp v200, v99, v186 quad_perm:[2,3,0,1] row_mask:0xf bank_mask:0xf bound_ctrl:1
	v_xor_b32_e32 v99, v189, v101
	v_add_f32_dpp v113, v196, v113 quad_perm:[1,0,3,2] row_mask:0xf bank_mask:0xf bound_ctrl:1
	v_xor_b32_e32 v148, v181, v202
	v_add_f32_dpp v201, v101, v99 quad_perm:[2,3,0,1] row_mask:0xf bank_mask:0xf bound_ctrl:1
	v_xor_b32_e32 v99, v189, v111
	v_pk_add_f32 v[204:205], v[198:199], v[198:199] op_sel:[0,1] op_sel_hi:[1,0]
	v_add_f32_dpp v148, v202, v148 quad_perm:[1,0,3,2] row_mask:0xf bank_mask:0xf bound_ctrl:1
	v_add_f32_dpp v202, v111, v99 quad_perm:[2,3,0,1] row_mask:0xf bank_mask:0xf bound_ctrl:1
	v_xor_b32_e32 v99, v189, v113
	v_xor_b32_e32 v149, v181, v204
	v_xor_b32_e32 v155, v181, v206
	v_add_f32_dpp v203, v113, v99 quad_perm:[2,3,0,1] row_mask:0xf bank_mask:0xf bound_ctrl:1
	v_xor_b32_e32 v99, v189, v147
	v_add_f32_dpp v149, v204, v149 quad_perm:[1,0,3,2] row_mask:0xf bank_mask:0xf bound_ctrl:1
	v_add_f32_dpp v155, v206, v155 quad_perm:[1,0,3,2] row_mask:0xf bank_mask:0xf bound_ctrl:1
	v_add_f32_dpp v204, v147, v99 quad_perm:[2,3,0,1] row_mask:0xf bank_mask:0xf bound_ctrl:1
	v_xor_b32_e32 v99, v189, v148
	v_xor_b32_e32 v156, v181, v154
	v_pk_add_f32 v[194:195], v[194:195], v[194:195] op_sel:[0,1] op_sel_hi:[1,0] neg_lo:[0,1] neg_hi:[0,1]
	v_add_f32_dpp v205, v148, v99 quad_perm:[2,3,0,1] row_mask:0xf bank_mask:0xf bound_ctrl:1
	v_xor_b32_e32 v99, v189, v149
	v_add_f32_dpp v154, v154, v156 quad_perm:[1,0,3,2] row_mask:0xf bank_mask:0xf bound_ctrl:1
	v_xor_b32_e32 v156, v181, v112
	v_add_f32_dpp v206, v149, v99 quad_perm:[2,3,0,1] row_mask:0xf bank_mask:0xf bound_ctrl:1
	v_xor_b32_e32 v99, v189, v155
	v_add_f32_dpp v112, v112, v156 quad_perm:[1,0,3,2] row_mask:0xf bank_mask:0xf bound_ctrl:1
	v_xor_b32_e32 v156, v181, v194
	v_add_f32_dpp v207, v155, v99 quad_perm:[2,3,0,1] row_mask:0xf bank_mask:0xf bound_ctrl:1
	v_xor_b32_e32 v99, v189, v154
	v_add_f32_dpp v156, v194, v156 quad_perm:[1,0,3,2] row_mask:0xf bank_mask:0xf bound_ctrl:1
	v_xor_b32_e32 v157, v181, v110
	v_add_f32_dpp v216, v154, v99 quad_perm:[2,3,0,1] row_mask:0xf bank_mask:0xf bound_ctrl:1
	v_xor_b32_e32 v99, v189, v112
	v_add_f32_dpp v110, v110, v157 quad_perm:[1,0,3,2] row_mask:0xf bank_mask:0xf bound_ctrl:1
	v_xor_b32_e32 v157, v181, v100
	v_add_f32_dpp v225, v112, v99 quad_perm:[2,3,0,1] row_mask:0xf bank_mask:0xf bound_ctrl:1
	v_xor_b32_e32 v99, v189, v156
	v_pk_add_f32 v[198:199], v[198:199], v[198:199] op_sel:[0,1] op_sel_hi:[1,0] neg_lo:[0,1] neg_hi:[0,1]
	v_add_f32_dpp v100, v100, v157 quad_perm:[1,0,3,2] row_mask:0xf bank_mask:0xf bound_ctrl:1
	v_xor_b32_e32 v157, v181, v98
	v_add_f32_dpp v226, v156, v99 quad_perm:[2,3,0,1] row_mask:0xf bank_mask:0xf bound_ctrl:1
	v_xor_b32_e32 v99, v189, v110
	v_add_f32_dpp v98, v98, v157 quad_perm:[1,0,3,2] row_mask:0xf bank_mask:0xf bound_ctrl:1
	v_xor_b32_e32 v157, v181, v198
	v_add_f32_dpp v227, v110, v99 quad_perm:[2,3,0,1] row_mask:0xf bank_mask:0xf bound_ctrl:1
	v_xor_b32_e32 v99, v189, v100
	v_add_f32_dpp v157, v198, v157 quad_perm:[1,0,3,2] row_mask:0xf bank_mask:0xf bound_ctrl:1
	v_lshlrev_b32_e32 v101, 16, v70
	v_add_f32_dpp v228, v100, v99 quad_perm:[2,3,0,1] row_mask:0xf bank_mask:0xf bound_ctrl:1
	v_xor_b32_e32 v99, v189, v98
	v_max_f32_e64 v100, |v206|, |v207|
	v_and_b32_e32 v111, 0xffff0000, v70
	v_add_f32_dpp v229, v98, v99 quad_perm:[2,3,0,1] row_mask:0xf bank_mask:0xf bound_ctrl:1
	v_xor_b32_e32 v98, v189, v157
	v_max_f32_e64 v99, |v202|, |v203|
	v_and_b32_e32 v110, 0xffff0000, v66
	v_add_f32_dpp v230, v157, v98 quad_perm:[2,3,0,1] row_mask:0xf bank_mask:0xf bound_ctrl:1
	v_xor_b32_e32 v98, v189, v146
	v_lshlrev_b32_e32 v112, 16, v67
	v_lshlrev_b32_e32 v113, 16, v71
	v_add_f32_dpp v231, v146, v98 quad_perm:[2,3,0,1] row_mask:0xf bank_mask:0xf bound_ctrl:1
	v_max_f32_e64 v98, |v200|, |v201|
	v_max3_f32 v98, v193, v98, v99
	v_max_f32_e64 v99, |v204|, |v205|
	v_max3_f32 v98, v98, v99, v100
	v_max_f32_e64 v99, |v216|, |v225|
	v_max_f32_e64 v100, |v226|, |v227|
	v_max3_f32 v98, v98, v99, v100
	v_max_f32_e64 v99, |v228|, |v229|
	v_max_f32_e64 v100, |v230|, |v231|
	v_max3_f32 v193, v98, v99, v100
	v_and_b32_e32 v99, 0xffff0000, v73
	v_and_b32_e32 v98, 0xffff0000, v69
	v_lshlrev_b32_e32 v100, 16, v66
	v_and_b32_e32 v71, 0xffff0000, v71
	v_and_b32_e32 v70, 0xffff0000, v67
	v_lshlrev_b32_e32 v67, 16, v72
	v_lshlrev_b32_e32 v66, 16, v68
	v_and_b32_e32 v147, 0xffff0000, v72
	v_and_b32_e32 v146, 0xffff0000, v68
	v_lshlrev_b32_e32 v68, 16, v69
	v_lshlrev_b32_e32 v69, 16, v73
	v_pk_add_f32 v[72:73], v[100:101], v[110:111]
	v_pk_add_f32 v[148:149], v[112:113], v[70:71]
	v_pk_add_f32 v[154:155], v[66:67], v[146:147]
	v_pk_add_f32 v[156:157], v[68:69], v[98:99]
	v_pk_add_f32 v[100:101], v[100:101], v[110:111] neg_lo:[0,1] neg_hi:[0,1]
	v_pk_add_f32 v[70:71], v[112:113], v[70:71] neg_lo:[0,1] neg_hi:[0,1]
	v_pk_add_f32 v[66:67], v[66:67], v[146:147] neg_lo:[0,1] neg_hi:[0,1]
	v_pk_add_f32 v[68:69], v[68:69], v[98:99] neg_lo:[0,1] neg_hi:[0,1]
	v_pk_add_f32 v[186:187], v[72:73], v[148:149] neg_lo:[0,1] neg_hi:[0,1]
	v_pk_add_f32 v[194:195], v[154:155], v[156:157] neg_lo:[0,1] neg_hi:[0,1]
	v_pk_add_f32 v[72:73], v[72:73], v[148:149]
	v_pk_add_f32 v[148:149], v[154:155], v[156:157]
	v_pk_add_f32 v[98:99], v[100:101], v[70:71] neg_lo:[0,1] neg_hi:[0,1]
	v_pk_add_f32 v[110:111], v[66:67], v[68:69] neg_lo:[0,1] neg_hi:[0,1]
	v_pk_add_f32 v[70:71], v[100:101], v[70:71]
	v_pk_add_f32 v[66:67], v[66:67], v[68:69]
	v_pk_add_f32 v[154:155], v[72:73], v[148:149]
	v_pk_add_f32 v[72:73], v[72:73], v[148:149] neg_lo:[0,1] neg_hi:[0,1]
	v_pk_add_f32 v[148:149], v[186:187], v[194:195]
	v_pk_add_f32 v[68:69], v[70:71], v[66:67]
	v_pk_add_f32 v[66:67], v[70:71], v[66:67] neg_lo:[0,1] neg_hi:[0,1]
	v_pk_add_f32 v[70:71], v[98:99], v[110:111]
	v_pk_add_f32 v[156:157], v[186:187], v[194:195] neg_lo:[0,1] neg_hi:[0,1]
	v_pk_add_f32 v[98:99], v[98:99], v[110:111] neg_lo:[0,1] neg_hi:[0,1]
	v_pk_add_f32 v[100:101], v[154:155], v[154:155] op_sel:[0,1] op_sel_hi:[1,0]
	v_pk_add_f32 v[110:111], v[154:155], v[154:155] op_sel:[0,1] op_sel_hi:[1,0] neg_lo:[0,1] neg_hi:[0,1]
	v_pk_add_f32 v[146:147], v[148:149], v[148:149] op_sel:[0,1] op_sel_hi:[1,0]
	v_pk_add_f32 v[154:155], v[70:71], v[70:71] op_sel:[0,1] op_sel_hi:[1,0]
	v_pk_add_f32 v[70:71], v[70:71], v[70:71] op_sel:[0,1] op_sel_hi:[1,0] neg_lo:[0,1] neg_hi:[0,1]
	v_pk_add_f32 v[194:195], v[66:67], v[66:67] op_sel:[0,1] op_sel_hi:[1,0]
	v_pk_add_f32 v[66:67], v[66:67], v[66:67] op_sel:[0,1] op_sel_hi:[1,0] neg_lo:[0,1] neg_hi:[0,1]
	v_pk_add_f32 v[112:113], v[68:69], v[68:69] op_sel:[0,1] op_sel_hi:[1,0]
	v_pk_add_f32 v[68:69], v[68:69], v[68:69] op_sel:[0,1] op_sel_hi:[1,0] neg_lo:[0,1] neg_hi:[0,1]
	v_pk_add_f32 v[198:199], v[98:99], v[98:99] op_sel:[0,1] op_sel_hi:[1,0]
	v_pk_add_f32 v[98:99], v[98:99], v[98:99] op_sel:[0,1] op_sel_hi:[1,0] neg_lo:[0,1] neg_hi:[0,1]
	v_xor_b32_e32 v67, v181, v100
	v_xor_b32_e32 v71, v181, v146
	v_xor_b32_e32 v69, v181, v112
	v_add_f32_dpp v67, v100, v67 quad_perm:[1,0,3,2] row_mask:0xf bank_mask:0xf bound_ctrl:1
	v_add_f32_dpp v71, v146, v71 quad_perm:[1,0,3,2] row_mask:0xf bank_mask:0xf bound_ctrl:1
	v_xor_b32_e32 v146, v181, v98
	v_pk_add_f32 v[186:187], v[72:73], v[72:73] op_sel:[0,1] op_sel_hi:[1,0]
	v_pk_add_f32 v[72:73], v[72:73], v[72:73] op_sel:[0,1] op_sel_hi:[1,0] neg_lo:[0,1] neg_hi:[0,1]
	v_add_f32_dpp v69, v112, v69 quad_perm:[1,0,3,2] row_mask:0xf bank_mask:0xf bound_ctrl:1
	v_add_f32_dpp v98, v98, v146 quad_perm:[1,0,3,2] row_mask:0xf bank_mask:0xf bound_ctrl:1
	v_xor_b32_e32 v146, v189, v67
	v_xor_b32_e32 v73, v181, v154
	v_xor_b32_e32 v99, v181, v186
	v_add_f32_dpp v67, v67, v146 quad_perm:[2,3,0,1] row_mask:0xf bank_mask:0xf bound_ctrl:1
	v_xor_b32_e32 v146, v189, v69
	v_add_f32_dpp v73, v154, v73 quad_perm:[1,0,3,2] row_mask:0xf bank_mask:0xf bound_ctrl:1
	v_pk_add_f32 v[196:197], v[156:157], v[156:157] op_sel:[0,1] op_sel_hi:[1,0]
	v_add_f32_dpp v69, v69, v146 quad_perm:[2,3,0,1] row_mask:0xf bank_mask:0xf bound_ctrl:1
	v_xor_b32_e32 v146, v189, v71
	v_add_f32_dpp v99, v186, v99 quad_perm:[1,0,3,2] row_mask:0xf bank_mask:0xf bound_ctrl:1
	v_xor_b32_e32 v100, v181, v194
	v_add_f32_dpp v71, v71, v146 quad_perm:[2,3,0,1] row_mask:0xf bank_mask:0xf bound_ctrl:1
	v_xor_b32_e32 v146, v189, v73
	v_add_f32_dpp v100, v194, v100 quad_perm:[1,0,3,2] row_mask:0xf bank_mask:0xf bound_ctrl:1
	v_xor_b32_e32 v101, v181, v196
	v_add_f32_dpp v73, v73, v146 quad_perm:[2,3,0,1] row_mask:0xf bank_mask:0xf bound_ctrl:1
	v_xor_b32_e32 v146, v189, v99
	v_add_f32_dpp v101, v196, v101 quad_perm:[1,0,3,2] row_mask:0xf bank_mask:0xf bound_ctrl:1
	v_xor_b32_e32 v111, v181, v198
	v_add_f32_dpp v186, v99, v146 quad_perm:[2,3,0,1] row_mask:0xf bank_mask:0xf bound_ctrl:1
	v_xor_b32_e32 v99, v189, v100
	v_add_f32_dpp v111, v198, v111 quad_perm:[1,0,3,2] row_mask:0xf bank_mask:0xf bound_ctrl:1
	v_xor_b32_e32 v112, v181, v110
	v_add_f32_dpp v187, v100, v99 quad_perm:[2,3,0,1] row_mask:0xf bank_mask:0xf bound_ctrl:1
	v_xor_b32_e32 v99, v189, v101
	v_pk_add_f32 v[148:149], v[148:149], v[148:149] op_sel:[0,1] op_sel_hi:[1,0] neg_lo:[0,1] neg_hi:[0,1]
	v_add_f32_dpp v110, v110, v112 quad_perm:[1,0,3,2] row_mask:0xf bank_mask:0xf bound_ctrl:1
	v_xor_b32_e32 v112, v181, v68
	v_add_f32_dpp v198, v101, v99 quad_perm:[2,3,0,1] row_mask:0xf bank_mask:0xf bound_ctrl:1
	v_xor_b32_e32 v99, v189, v111
	v_add_f32_dpp v68, v68, v112 quad_perm:[1,0,3,2] row_mask:0xf bank_mask:0xf bound_ctrl:1
	v_xor_b32_e32 v112, v181, v148
	v_add_f32_dpp v199, v111, v99 quad_perm:[2,3,0,1] row_mask:0xf bank_mask:0xf bound_ctrl:1
	v_xor_b32_e32 v99, v189, v110
	v_add_f32_dpp v112, v148, v112 quad_perm:[1,0,3,2] row_mask:0xf bank_mask:0xf bound_ctrl:1
	v_xor_b32_e32 v113, v181, v70
	v_add_f32_dpp v232, v110, v99 quad_perm:[2,3,0,1] row_mask:0xf bank_mask:0xf bound_ctrl:1
	v_xor_b32_e32 v99, v189, v68
	v_add_f32_dpp v70, v70, v113 quad_perm:[1,0,3,2] row_mask:0xf bank_mask:0xf bound_ctrl:1
	v_xor_b32_e32 v113, v181, v72
	v_add_f32_dpp v233, v68, v99 quad_perm:[2,3,0,1] row_mask:0xf bank_mask:0xf bound_ctrl:1
	v_xor_b32_e32 v68, v189, v112
	v_pk_add_f32 v[156:157], v[156:157], v[156:157] op_sel:[0,1] op_sel_hi:[1,0] neg_lo:[0,1] neg_hi:[0,1]
	v_add_f32_dpp v72, v72, v113 quad_perm:[1,0,3,2] row_mask:0xf bank_mask:0xf bound_ctrl:1
	v_xor_b32_e32 v113, v181, v66
	v_add_f32_dpp v235, v112, v68 quad_perm:[2,3,0,1] row_mask:0xf bank_mask:0xf bound_ctrl:1
	v_xor_b32_e32 v68, v189, v70
	v_add_f32_dpp v66, v66, v113 quad_perm:[1,0,3,2] row_mask:0xf bank_mask:0xf bound_ctrl:1
	v_xor_b32_e32 v113, v181, v156
	v_add_f32_dpp v236, v70, v68 quad_perm:[2,3,0,1] row_mask:0xf bank_mask:0xf bound_ctrl:1
	v_xor_b32_e32 v68, v189, v72
	v_add_f32_dpp v113, v156, v113 quad_perm:[1,0,3,2] row_mask:0xf bank_mask:0xf bound_ctrl:1
	v_max_f32_e64 v70, |v198|, |v199|
	v_add_f32_dpp v72, v72, v68 quad_perm:[2,3,0,1] row_mask:0xf bank_mask:0xf bound_ctrl:1
	v_xor_b32_e32 v68, v189, v66
	v_cvt_pk_bf16_f32 v146, v208, v209
	v_cvt_pk_bf16_f32 v147, v210, v211
	v_cvt_pk_bf16_f32 v148, v212, v213
	v_cvt_pk_bf16_f32 v149, v214, v215
	v_cvt_pk_bf16_f32 v154, v217, v218
	s_nop 1
	v_add_f32_dpp v237, v66, v68 quad_perm:[2,3,0,1] row_mask:0xf bank_mask:0xf bound_ctrl:1
	v_xor_b32_e32 v66, v189, v113
	v_max_f32_e64 v68, |v71|, |v73|
	v_cvt_pk_bf16_f32 v155, v219, v220
	v_cvt_pk_bf16_f32 v156, v221, v222
	v_cvt_pk_bf16_f32 v157, v223, v224
	s_nop 0
	v_add_f32_dpp v238, v113, v66 quad_perm:[2,3,0,1] row_mask:0xf bank_mask:0xf bound_ctrl:1
	v_xor_b32_e32 v66, v189, v98
	s_nop 1
	v_add_f32_dpp v239, v98, v66 quad_perm:[2,3,0,1] row_mask:0xf bank_mask:0xf bound_ctrl:1
	v_max_f32_e64 v66, |v67|, |v69|
	v_max3_f32 v66, v193, v66, v68
	v_max_f32_e64 v68, |v186|, |v187|
	v_max3_f32 v66, v66, v68, v70
	v_max_f32_e64 v68, |v232|, |v233|
	v_max_f32_e64 v70, |v235|, |v236|
	v_max3_f32 v66, v66, v68, v70
	v_max_f32_e64 v68, |v72|, |v237|
	v_max_f32_e64 v70, |v238|, |v239|
	v_max3_f32 v66, v66, v68, v70
	v_and_b32_e32 v68, 64, v190
	v_add_u32_e32 v70, 64, v68
	v_xor_b32_e32 v68, 1, v190
	v_cmp_lt_i32_e32 vcc, v68, v70
	v_cvt_pk_bf16_f32 v98, v200, v201
	v_cvt_pk_bf16_f32 v99, v202, v203
	v_cvt_pk_bf16_f32 v100, v204, v205
	v_cvt_pk_bf16_f32 v101, v206, v207
	v_cvt_pk_bf16_f32 v110, v216, v225
	s_nop 1
	v_cndmask_b32_e32 v68, v190, v68, vcc
	v_lshlrev_b32_e32 v193, 2, v68
	v_cvt_pk_bf16_f32 v111, v226, v227
	v_cvt_pk_bf16_f32 v112, v228, v229
	v_cvt_pk_bf16_f32 v113, v230, v231
	s_waitcnt lgkmcnt(0)
	s_nop 1
	v_max_f32_dpp v66, v66, v66 quad_perm:[1,0,3,2] row_mask:0xf bank_mask:0xf
	v_xor_b32_e32 v68, 2, v190
	v_cmp_lt_i32_e32 vcc, v68, v70
	s_nop 1
	v_cndmask_b32_e32 v68, v190, v68, vcc
	v_lshlrev_b32_e32 v194, 2, v68
	s_waitcnt lgkmcnt(0)
	s_nop 1
	v_max_f32_dpp v66, v66, v66 quad_perm:[2,3,0,1] row_mask:0xf bank_mask:0xf
	v_xor_b32_e32 v68, 4, v190
	v_cmp_lt_i32_e32 vcc, v68, v70
	s_nop 1
	v_cndmask_b32_e32 v68, v190, v68, vcc
	v_lshlrev_b32_e32 v195, 2, v68
	s_waitcnt lgkmcnt(0)
	s_nop 1
	v_max_f32_dpp v66, v66, v66 row_half_mirror row_mask:0xf bank_mask:0xf
	v_xor_b32_e32 v68, 8, v190
	v_cmp_lt_i32_e32 vcc, v68, v70
	s_nop 1
	v_cndmask_b32_e32 v68, v190, v68, vcc
	v_lshlrev_b32_e32 v196, 2, v68
	s_waitcnt lgkmcnt(0)
	s_nop 1
	v_max_f32_dpp v200, v66, v66 row_mirror row_mask:0xf bank_mask:0xf
	v_xor_b32_e32 v66, 16, v190
	v_cmp_lt_i32_e32 vcc, v66, v70
	s_nop 1
	v_cndmask_b32_e32 v66, v190, v66, vcc
	v_lshlrev_b32_e32 v197, 2, v66
	ds_bpermute_b32 v201, v197, v200
	v_cvt_pk_bf16_f32 v66, v67, v69
	v_cvt_pk_bf16_f32 v67, v71, v73
	v_cvt_pk_bf16_f32 v68, v186, v187
	v_cvt_pk_bf16_f32 v69, v198, v199
	s_waitcnt lgkmcnt(0)
	v_max_f32_e32 v71, v201, v201
	v_max_f32_e32 v186, v200, v71
	v_xor_b32_e32 v71, 32, v190
	v_cmp_lt_i32_e32 vcc, v71, v70
	s_nop 1
	v_cndmask_b32_e32 v70, v190, v71, vcc
	v_lshlrev_b32_e32 v198, 2, v70
	v_cvt_pk_bf16_f32 v70, v232, v233
	v_cvt_pk_bf16_f32 v71, v235, v236
	v_cvt_pk_bf16_f32 v72, v72, v237
	v_cvt_pk_bf16_f32 v73, v238, v239
	s_waitcnt lgkmcnt(0)
	v_mov_b32_e32 v187, v186
	s_nop 1
	v_permlane32_swap_b32_e32 v187, v186
	v_max_f32_e32 v186, v186, v187
	s_and_saveexec_b64 s[34:35], s[2:3]
	s_cbranch_execz .LBB0_1862
	s_lshl_b64 s[46:47], s[30:31], 2
	s_sub_u32 s46, s37, s46
	s_subb_u32 s47, s38, s47
	v_mul_f32_e32 v187, 0x3a810204, v186
	global_store_dword v179, v187, s[46:47]

.LBB0_1869:
	v_lshlrev_b32_e32 v187, 16, v78
	v_lshlrev_b32_e32 v186, 16, v74
	v_and_b32_e32 v201, 0xffff0000, v78
	v_and_b32_e32 v200, 0xffff0000, v74
	v_lshlrev_b32_e32 v202, 16, v75
	v_lshlrev_b32_e32 v203, 16, v79
	v_and_b32_e32 v79, 0xffff0000, v79
	v_and_b32_e32 v78, 0xffff0000, v75
	v_lshlrev_b32_e32 v75, 16, v80
	v_lshlrev_b32_e32 v74, 16, v76
	v_and_b32_e32 v205, 0xffff0000, v80
	v_and_b32_e32 v204, 0xffff0000, v76
	v_lshlrev_b32_e32 v206, 16, v77
	v_lshlrev_b32_e32 v207, 16, v81
	v_and_b32_e32 v81, 0xffff0000, v81
	v_and_b32_e32 v80, 0xffff0000, v77
	v_pk_add_f32 v[76:77], v[186:187], v[200:201]
	v_pk_add_f32 v[208:209], v[202:203], v[78:79]
	v_pk_add_f32 v[210:211], v[74:75], v[204:205]
	v_pk_add_f32 v[212:213], v[206:207], v[80:81]
	v_pk_add_f32 v[186:187], v[186:187], v[200:201] neg_lo:[0,1] neg_hi:[0,1]
	v_pk_add_f32 v[78:79], v[202:203], v[78:79] neg_lo:[0,1] neg_hi:[0,1]
	v_pk_add_f32 v[74:75], v[74:75], v[204:205] neg_lo:[0,1] neg_hi:[0,1]
	v_pk_add_f32 v[80:81], v[206:207], v[80:81] neg_lo:[0,1] neg_hi:[0,1]
	v_pk_add_f32 v[214:215], v[76:77], v[208:209] neg_lo:[0,1] neg_hi:[0,1]
	v_pk_add_f32 v[76:77], v[76:77], v[208:209]
	v_pk_add_f32 v[208:209], v[210:211], v[212:213]
	v_pk_add_f32 v[200:201], v[186:187], v[78:79] neg_lo:[0,1] neg_hi:[0,1]
	v_pk_add_f32 v[202:203], v[74:75], v[80:81] neg_lo:[0,1] neg_hi:[0,1]
	v_pk_add_f32 v[78:79], v[186:187], v[78:79]
	v_pk_add_f32 v[74:75], v[74:75], v[80:81]
	v_pk_add_f32 v[216:217], v[210:211], v[212:213] neg_lo:[0,1] neg_hi:[0,1]
	v_pk_add_f32 v[210:211], v[76:77], v[208:209]
	v_pk_add_f32 v[80:81], v[78:79], v[74:75]
	v_pk_add_f32 v[74:75], v[78:79], v[74:75] neg_lo:[0,1] neg_hi:[0,1]
	v_pk_add_f32 v[76:77], v[76:77], v[208:209] neg_lo:[0,1] neg_hi:[0,1]
	v_pk_add_f32 v[208:209], v[214:215], v[216:217]
	v_pk_add_f32 v[212:213], v[214:215], v[216:217] neg_lo:[0,1] neg_hi:[0,1]
	v_pk_add_f32 v[78:79], v[200:201], v[202:203]
	v_pk_add_f32 v[186:187], v[200:201], v[202:203] neg_lo:[0,1] neg_hi:[0,1]
	v_pk_add_f32 v[200:201], v[210:211], v[210:211] op_sel:[1,0] op_sel_hi:[0,1]
	v_pk_add_f32 v[216:217], v[74:75], v[74:75] op_sel:[1,0] op_sel_hi:[0,1]
	v_pk_add_f32 v[74:75], v[74:75], v[74:75] op_sel:[0,1] op_sel_hi:[1,0] neg_lo:[0,1] neg_hi:[0,1]
	v_pk_add_f32 v[204:205], v[80:81], v[80:81] op_sel:[1,0] op_sel_hi:[0,1]
	v_pk_add_f32 v[214:215], v[76:77], v[76:77] op_sel:[1,0] op_sel_hi:[0,1]
	v_pk_add_f32 v[76:77], v[76:77], v[76:77] op_sel:[0,1] op_sel_hi:[1,0] neg_lo:[0,1] neg_hi:[0,1]
	v_pk_add_f32 v[220:221], v[186:187], v[186:187] op_sel:[1,0] op_sel_hi:[0,1]
	v_pk_add_f32 v[186:187], v[186:187], v[186:187] op_sel:[0,1] op_sel_hi:[1,0] neg_lo:[0,1] neg_hi:[0,1]
	v_xor_b32_e32 v75, v181, v200
	v_pk_add_f32 v[202:203], v[210:211], v[210:211] op_sel:[0,1] op_sel_hi:[1,0] neg_lo:[0,1] neg_hi:[0,1]
	v_pk_add_f32 v[206:207], v[208:209], v[208:209] op_sel:[1,0] op_sel_hi:[0,1]
	v_pk_add_f32 v[210:211], v[78:79], v[78:79] op_sel:[1,0] op_sel_hi:[0,1]
	v_pk_add_f32 v[78:79], v[78:79], v[78:79] op_sel:[0,1] op_sel_hi:[1,0] neg_lo:[0,1] neg_hi:[0,1]
	v_add_f32_dpp v75, v200, v75 quad_perm:[1,0,3,2] row_mask:0xf bank_mask:0xf bound_ctrl:1
	v_xor_b32_e32 v77, v181, v204
	v_xor_b32_e32 v205, v181, v186
	v_pk_add_f32 v[80:81], v[80:81], v[80:81] op_sel:[0,1] op_sel_hi:[1,0] neg_lo:[0,1] neg_hi:[0,1]
	v_add_f32_dpp v77, v204, v77 quad_perm:[1,0,3,2] row_mask:0xf bank_mask:0xf bound_ctrl:1
	v_xor_b32_e32 v79, v181, v206
	v_add_f32_dpp v186, v186, v205 quad_perm:[1,0,3,2] row_mask:0xf bank_mask:0xf bound_ctrl:1
	v_xor_b32_e32 v205, v189, v75
	v_add_f32_dpp v79, v206, v79 quad_perm:[1,0,3,2] row_mask:0xf bank_mask:0xf bound_ctrl:1
	v_xor_b32_e32 v81, v181, v210
	v_add_f32_dpp v75, v75, v205 quad_perm:[2,3,0,1] row_mask:0xf bank_mask:0xf bound_ctrl:1
	v_xor_b32_e32 v205, v189, v77
	v_add_f32_dpp v81, v210, v81 quad_perm:[1,0,3,2] row_mask:0xf bank_mask:0xf bound_ctrl:1
	v_xor_b32_e32 v187, v181, v214
	v_add_f32_dpp v77, v77, v205 quad_perm:[2,3,0,1] row_mask:0xf bank_mask:0xf bound_ctrl:1
	v_xor_b32_e32 v205, v189, v79
	v_pk_add_f32 v[218:219], v[212:213], v[212:213] op_sel:[1,0] op_sel_hi:[0,1]
	v_add_f32_dpp v187, v214, v187 quad_perm:[1,0,3,2] row_mask:0xf bank_mask:0xf bound_ctrl:1
	v_xor_b32_e32 v199, v181, v216
	v_add_f32_dpp v79, v79, v205 quad_perm:[2,3,0,1] row_mask:0xf bank_mask:0xf bound_ctrl:1
	v_xor_b32_e32 v205, v189, v81
	v_add_f32_dpp v199, v216, v199 quad_perm:[1,0,3,2] row_mask:0xf bank_mask:0xf bound_ctrl:1
	v_xor_b32_e32 v200, v181, v218
	v_add_f32_dpp v81, v81, v205 quad_perm:[2,3,0,1] row_mask:0xf bank_mask:0xf bound_ctrl:1
	v_xor_b32_e32 v205, v189, v187
	v_add_f32_dpp v200, v218, v200 quad_perm:[1,0,3,2] row_mask:0xf bank_mask:0xf bound_ctrl:1
	v_xor_b32_e32 v201, v181, v220
	v_add_f32_dpp v187, v187, v205 quad_perm:[2,3,0,1] row_mask:0xf bank_mask:0xf bound_ctrl:1
	v_xor_b32_e32 v205, v189, v199
	v_add_f32_dpp v201, v220, v201 quad_perm:[1,0,3,2] row_mask:0xf bank_mask:0xf bound_ctrl:1
	v_xor_b32_e32 v203, v181, v202
	v_add_f32_dpp v199, v199, v205 quad_perm:[2,3,0,1] row_mask:0xf bank_mask:0xf bound_ctrl:1
	v_xor_b32_e32 v205, v189, v200
	v_pk_add_f32 v[208:209], v[208:209], v[208:209] op_sel:[0,1] op_sel_hi:[1,0] neg_lo:[0,1] neg_hi:[0,1]
	v_add_f32_dpp v202, v202, v203 quad_perm:[1,0,3,2] row_mask:0xf bank_mask:0xf bound_ctrl:1
	v_xor_b32_e32 v203, v181, v80
	v_add_f32_dpp v200, v200, v205 quad_perm:[2,3,0,1] row_mask:0xf bank_mask:0xf bound_ctrl:1
	v_xor_b32_e32 v205, v189, v201
	v_add_f32_dpp v80, v80, v203 quad_perm:[1,0,3,2] row_mask:0xf bank_mask:0xf bound_ctrl:1
	v_xor_b32_e32 v203, v181, v208
	v_add_f32_dpp v201, v201, v205 quad_perm:[2,3,0,1] row_mask:0xf bank_mask:0xf bound_ctrl:1
	v_xor_b32_e32 v205, v189, v202
	v_add_f32_dpp v203, v208, v203 quad_perm:[1,0,3,2] row_mask:0xf bank_mask:0xf bound_ctrl:1
	v_xor_b32_e32 v204, v181, v78
	v_add_f32_dpp v202, v202, v205 quad_perm:[2,3,0,1] row_mask:0xf bank_mask:0xf bound_ctrl:1
	v_xor_b32_e32 v205, v189, v80
	v_add_f32_dpp v78, v78, v204 quad_perm:[1,0,3,2] row_mask:0xf bank_mask:0xf bound_ctrl:1
	v_xor_b32_e32 v204, v181, v76
	v_add_f32_dpp v80, v80, v205 quad_perm:[2,3,0,1] row_mask:0xf bank_mask:0xf bound_ctrl:1
	v_xor_b32_e32 v205, v189, v203
	v_pk_add_f32 v[212:213], v[212:213], v[212:213] op_sel:[0,1] op_sel_hi:[1,0] neg_lo:[0,1] neg_hi:[0,1]
	v_add_f32_dpp v76, v76, v204 quad_perm:[1,0,3,2] row_mask:0xf bank_mask:0xf bound_ctrl:1
	v_xor_b32_e32 v204, v181, v74
	v_add_f32_dpp v203, v203, v205 quad_perm:[2,3,0,1] row_mask:0xf bank_mask:0xf bound_ctrl:1
	v_xor_b32_e32 v205, v189, v78
	v_add_f32_dpp v74, v74, v204 quad_perm:[1,0,3,2] row_mask:0xf bank_mask:0xf bound_ctrl:1
	v_xor_b32_e32 v204, v181, v212
	v_add_f32_dpp v205, v78, v205 quad_perm:[2,3,0,1] row_mask:0xf bank_mask:0xf bound_ctrl:1
	v_xor_b32_e32 v78, v189, v76
	v_add_f32_dpp v204, v212, v204 quad_perm:[1,0,3,2] row_mask:0xf bank_mask:0xf bound_ctrl:1
	s_ashr_i32 s27, s26, 31
	v_add_f32_dpp v206, v76, v78 quad_perm:[2,3,0,1] row_mask:0xf bank_mask:0xf bound_ctrl:1
	v_xor_b32_e32 v76, v189, v74
	v_max_f32_e64 v78, |v200|, |v201|
	s_nop 0
	v_add_f32_dpp v207, v74, v76 quad_perm:[2,3,0,1] row_mask:0xf bank_mask:0xf bound_ctrl:1
	v_xor_b32_e32 v74, v189, v204
	v_max_f32_e64 v76, |v79|, |v81|
	s_nop 0
	v_add_f32_dpp v204, v204, v74 quad_perm:[2,3,0,1] row_mask:0xf bank_mask:0xf bound_ctrl:1
	v_xor_b32_e32 v74, v189, v186
	s_nop 1
	v_add_f32_dpp v186, v186, v74 quad_perm:[2,3,0,1] row_mask:0xf bank_mask:0xf bound_ctrl:1
	v_max_f32_e64 v74, |v75|, |v77|
	v_max3_f32 v74, v74, 0, v76
	v_max_f32_e64 v76, |v187|, |v199|
	v_max3_f32 v74, v74, v76, v78
	v_max_f32_e64 v76, |v202|, |v80|
	v_max_f32_e64 v78, |v203|, |v205|
	v_max3_f32 v74, v74, v76, v78
	v_max_f32_e64 v76, |v206|, |v207|
	v_max_f32_e64 v78, |v204|, |v186|
	v_max3_f32 v222, v74, v76, v78
	v_cvt_pk_bf16_f32 v74, v75, v77
	v_cvt_pk_bf16_f32 v75, v79, v81
	v_cvt_pk_bf16_f32 v76, v187, v199
	v_cvt_pk_bf16_f32 v77, v200, v201
	v_cvt_pk_bf16_f32 v78, v202, v80
	v_cvt_pk_bf16_f32 v79, v203, v205
	v_cvt_pk_bf16_f32 v80, v206, v207
	v_cvt_pk_bf16_f32 v81, v204, v186
	v_and_b32_e32 v187, 0xffff0000, v89
	v_and_b32_e32 v186, 0xffff0000, v85
	v_lshlrev_b32_e32 v201, 16, v86
	v_lshlrev_b32_e32 v200, 16, v82
	v_and_b32_e32 v203, 0xffff0000, v86
	v_and_b32_e32 v202, 0xffff0000, v82
	v_lshlrev_b32_e32 v204, 16, v83
	v_lshlrev_b32_e32 v205, 16, v87
	v_and_b32_e32 v87, 0xffff0000, v87
	v_and_b32_e32 v86, 0xffff0000, v83
	v_lshlrev_b32_e32 v83, 16, v88
	v_lshlrev_b32_e32 v82, 16, v84
	v_and_b32_e32 v207, 0xffff0000, v88
	v_and_b32_e32 v206, 0xffff0000, v84
	v_lshlrev_b32_e32 v84, 16, v85
	v_lshlrev_b32_e32 v85, 16, v89
	v_pk_add_f32 v[88:89], v[200:201], v[202:203]
	v_pk_add_f32 v[208:209], v[204:205], v[86:87]
	v_pk_add_f32 v[210:211], v[82:83], v[206:207]
	v_pk_add_f32 v[212:213], v[84:85], v[186:187]
	v_pk_add_f32 v[200:201], v[200:201], v[202:203] neg_lo:[0,1] neg_hi:[0,1]
	v_pk_add_f32 v[86:87], v[204:205], v[86:87] neg_lo:[0,1] neg_hi:[0,1]
	v_pk_add_f32 v[82:83], v[82:83], v[206:207] neg_lo:[0,1] neg_hi:[0,1]
	v_pk_add_f32 v[84:85], v[84:85], v[186:187] neg_lo:[0,1] neg_hi:[0,1]
	v_pk_add_f32 v[214:215], v[88:89], v[208:209] neg_lo:[0,1] neg_hi:[0,1]
	v_pk_add_f32 v[88:89], v[88:89], v[208:209]
	v_pk_add_f32 v[208:209], v[210:211], v[212:213]
	v_pk_add_f32 v[186:187], v[200:201], v[86:87] neg_lo:[0,1] neg_hi:[0,1]
	v_pk_add_f32 v[202:203], v[82:83], v[84:85] neg_lo:[0,1] neg_hi:[0,1]
	v_pk_add_f32 v[86:87], v[200:201], v[86:87]
	v_pk_add_f32 v[82:83], v[82:83], v[84:85]
	v_pk_add_f32 v[216:217], v[210:211], v[212:213] neg_lo:[0,1] neg_hi:[0,1]
	v_pk_add_f32 v[210:211], v[88:89], v[208:209]
	v_pk_add_f32 v[84:85], v[86:87], v[82:83]
	v_pk_add_f32 v[82:83], v[86:87], v[82:83] neg_lo:[0,1] neg_hi:[0,1]
	v_pk_add_f32 v[88:89], v[88:89], v[208:209] neg_lo:[0,1] neg_hi:[0,1]
	v_pk_add_f32 v[208:209], v[214:215], v[216:217]
	v_pk_add_f32 v[212:213], v[214:215], v[216:217] neg_lo:[0,1] neg_hi:[0,1]
	v_pk_add_f32 v[86:87], v[186:187], v[202:203]
	v_pk_add_f32 v[186:187], v[186:187], v[202:203] neg_lo:[0,1] neg_hi:[0,1]
	v_pk_add_f32 v[200:201], v[210:211], v[210:211] op_sel:[1,0] op_sel_hi:[0,1]
	v_pk_add_f32 v[216:217], v[82:83], v[82:83] op_sel:[1,0] op_sel_hi:[0,1]
	v_pk_add_f32 v[82:83], v[82:83], v[82:83] op_sel:[0,1] op_sel_hi:[1,0] neg_lo:[0,1] neg_hi:[0,1]
	v_pk_add_f32 v[204:205], v[84:85], v[84:85] op_sel:[1,0] op_sel_hi:[0,1]
	v_pk_add_f32 v[84:85], v[84:85], v[84:85] op_sel:[0,1] op_sel_hi:[1,0] neg_lo:[0,1] neg_hi:[0,1]
	v_pk_add_f32 v[220:221], v[186:187], v[186:187] op_sel:[1,0] op_sel_hi:[0,1]
	v_pk_add_f32 v[186:187], v[186:187], v[186:187] op_sel:[0,1] op_sel_hi:[1,0] neg_lo:[0,1] neg_hi:[0,1]
	v_xor_b32_e32 v83, v181, v200
	v_pk_add_f32 v[202:203], v[210:211], v[210:211] op_sel:[0,1] op_sel_hi:[1,0] neg_lo:[0,1] neg_hi:[0,1]
	v_pk_add_f32 v[206:207], v[208:209], v[208:209] op_sel:[1,0] op_sel_hi:[0,1]
	v_pk_add_f32 v[210:211], v[86:87], v[86:87] op_sel:[1,0] op_sel_hi:[0,1]
	v_pk_add_f32 v[86:87], v[86:87], v[86:87] op_sel:[0,1] op_sel_hi:[1,0] neg_lo:[0,1] neg_hi:[0,1]
	v_add_f32_dpp v83, v200, v83 quad_perm:[1,0,3,2] row_mask:0xf bank_mask:0xf bound_ctrl:1
	v_xor_b32_e32 v85, v181, v204
	v_xor_b32_e32 v205, v181, v186
	v_pk_add_f32 v[214:215], v[88:89], v[88:89] op_sel:[1,0] op_sel_hi:[0,1]
	v_pk_add_f32 v[88:89], v[88:89], v[88:89] op_sel:[0,1] op_sel_hi:[1,0] neg_lo:[0,1] neg_hi:[0,1]
	v_add_f32_dpp v85, v204, v85 quad_perm:[1,0,3,2] row_mask:0xf bank_mask:0xf bound_ctrl:1
	v_xor_b32_e32 v87, v181, v206
	v_add_f32_dpp v186, v186, v205 quad_perm:[1,0,3,2] row_mask:0xf bank_mask:0xf bound_ctrl:1
	v_xor_b32_e32 v205, v189, v83
	v_add_f32_dpp v87, v206, v87 quad_perm:[1,0,3,2] row_mask:0xf bank_mask:0xf bound_ctrl:1
	v_xor_b32_e32 v89, v181, v210
	v_add_f32_dpp v83, v83, v205 quad_perm:[2,3,0,1] row_mask:0xf bank_mask:0xf bound_ctrl:1
	v_xor_b32_e32 v205, v189, v85
	v_add_f32_dpp v89, v210, v89 quad_perm:[1,0,3,2] row_mask:0xf bank_mask:0xf bound_ctrl:1
	v_xor_b32_e32 v187, v181, v214
	v_add_f32_dpp v85, v85, v205 quad_perm:[2,3,0,1] row_mask:0xf bank_mask:0xf bound_ctrl:1
	v_xor_b32_e32 v205, v189, v87
	v_pk_add_f32 v[218:219], v[212:213], v[212:213] op_sel:[1,0] op_sel_hi:[0,1]
	v_add_f32_dpp v187, v214, v187 quad_perm:[1,0,3,2] row_mask:0xf bank_mask:0xf bound_ctrl:1
	v_xor_b32_e32 v199, v181, v216
	v_add_f32_dpp v87, v87, v205 quad_perm:[2,3,0,1] row_mask:0xf bank_mask:0xf bound_ctrl:1
	v_xor_b32_e32 v205, v189, v89
	v_add_f32_dpp v199, v216, v199 quad_perm:[1,0,3,2] row_mask:0xf bank_mask:0xf bound_ctrl:1
	v_xor_b32_e32 v200, v181, v218
	v_add_f32_dpp v89, v89, v205 quad_perm:[2,3,0,1] row_mask:0xf bank_mask:0xf bound_ctrl:1
	v_xor_b32_e32 v205, v189, v187
	v_add_f32_dpp v200, v218, v200 quad_perm:[1,0,3,2] row_mask:0xf bank_mask:0xf bound_ctrl:1
	v_xor_b32_e32 v201, v181, v220
	v_add_f32_dpp v187, v187, v205 quad_perm:[2,3,0,1] row_mask:0xf bank_mask:0xf bound_ctrl:1
	v_xor_b32_e32 v205, v189, v199
	v_add_f32_dpp v201, v220, v201 quad_perm:[1,0,3,2] row_mask:0xf bank_mask:0xf bound_ctrl:1
	v_xor_b32_e32 v203, v181, v202
	v_add_f32_dpp v199, v199, v205 quad_perm:[2,3,0,1] row_mask:0xf bank_mask:0xf bound_ctrl:1
	v_xor_b32_e32 v205, v189, v200
	v_pk_add_f32 v[208:209], v[208:209], v[208:209] op_sel:[0,1] op_sel_hi:[1,0] neg_lo:[0,1] neg_hi:[0,1]
	v_add_f32_dpp v202, v202, v203 quad_perm:[1,0,3,2] row_mask:0xf bank_mask:0xf bound_ctrl:1
	v_xor_b32_e32 v203, v181, v84
	v_add_f32_dpp v200, v200, v205 quad_perm:[2,3,0,1] row_mask:0xf bank_mask:0xf bound_ctrl:1
	v_xor_b32_e32 v205, v189, v201
	v_add_f32_dpp v84, v84, v203 quad_perm:[1,0,3,2] row_mask:0xf bank_mask:0xf bound_ctrl:1
	v_xor_b32_e32 v203, v181, v208
	v_add_f32_dpp v201, v201, v205 quad_perm:[2,3,0,1] row_mask:0xf bank_mask:0xf bound_ctrl:1
	v_xor_b32_e32 v205, v189, v202
	v_add_f32_dpp v203, v208, v203 quad_perm:[1,0,3,2] row_mask:0xf bank_mask:0xf bound_ctrl:1
	v_xor_b32_e32 v204, v181, v86
	v_add_f32_dpp v202, v202, v205 quad_perm:[2,3,0,1] row_mask:0xf bank_mask:0xf bound_ctrl:1
	v_xor_b32_e32 v205, v189, v84
	v_add_f32_dpp v86, v86, v204 quad_perm:[1,0,3,2] row_mask:0xf bank_mask:0xf bound_ctrl:1
	v_xor_b32_e32 v204, v181, v88
	v_add_f32_dpp v205, v84, v205 quad_perm:[2,3,0,1] row_mask:0xf bank_mask:0xf bound_ctrl:1
	v_xor_b32_e32 v84, v189, v203
	v_pk_add_f32 v[212:213], v[212:213], v[212:213] op_sel:[0,1] op_sel_hi:[1,0] neg_lo:[0,1] neg_hi:[0,1]
	v_add_f32_dpp v88, v88, v204 quad_perm:[1,0,3,2] row_mask:0xf bank_mask:0xf bound_ctrl:1
	v_xor_b32_e32 v204, v181, v82
	v_add_f32_dpp v203, v203, v84 quad_perm:[2,3,0,1] row_mask:0xf bank_mask:0xf bound_ctrl:1
	v_xor_b32_e32 v84, v189, v86
	v_add_f32_dpp v82, v82, v204 quad_perm:[1,0,3,2] row_mask:0xf bank_mask:0xf bound_ctrl:1
	v_xor_b32_e32 v204, v181, v212
	v_add_f32_dpp v206, v86, v84 quad_perm:[2,3,0,1] row_mask:0xf bank_mask:0xf bound_ctrl:1
	v_xor_b32_e32 v84, v189, v88
	v_add_f32_dpp v204, v212, v204 quad_perm:[1,0,3,2] row_mask:0xf bank_mask:0xf bound_ctrl:1
	v_max_f32_e64 v86, |v200|, |v201|
	v_add_f32_dpp v88, v88, v84 quad_perm:[2,3,0,1] row_mask:0xf bank_mask:0xf bound_ctrl:1
	v_xor_b32_e32 v84, v189, v82
	s_nop 1
	v_add_f32_dpp v207, v82, v84 quad_perm:[2,3,0,1] row_mask:0xf bank_mask:0xf bound_ctrl:1
	v_xor_b32_e32 v82, v189, v204
	v_max_f32_e64 v84, |v87|, |v89|
	s_nop 0
	v_add_f32_dpp v204, v204, v82 quad_perm:[2,3,0,1] row_mask:0xf bank_mask:0xf bound_ctrl:1
	v_xor_b32_e32 v82, v189, v186
	s_nop 1
	v_add_f32_dpp v186, v186, v82 quad_perm:[2,3,0,1] row_mask:0xf bank_mask:0xf bound_ctrl:1
	v_max_f32_e64 v82, |v83|, |v85|
	v_max3_f32 v82, v222, v82, v84
	v_max_f32_e64 v84, |v187|, |v199|
	v_max3_f32 v82, v82, v84, v86
	v_max_f32_e64 v84, |v202|, |v205|
	v_max_f32_e64 v86, |v203|, |v206|
	v_max3_f32 v82, v82, v84, v86
	v_max_f32_e64 v84, |v88|, |v207|
	v_max_f32_e64 v86, |v204|, |v186|
	v_max3_f32 v222, v82, v84, v86
	v_cvt_pk_bf16_f32 v82, v83, v85
	v_cvt_pk_bf16_f32 v83, v87, v89
	v_cvt_pk_bf16_f32 v84, v187, v199
	v_cvt_pk_bf16_f32 v85, v200, v201
	v_cvt_pk_bf16_f32 v86, v202, v205
	v_cvt_pk_bf16_f32 v87, v203, v206
	v_cvt_pk_bf16_f32 v88, v88, v207
	v_cvt_pk_bf16_f32 v89, v204, v186
	v_and_b32_e32 v187, 0xffff0000, v97
	v_and_b32_e32 v186, 0xffff0000, v93
	v_lshlrev_b32_e32 v201, 16, v94
	v_lshlrev_b32_e32 v200, 16, v90
	v_and_b32_e32 v203, 0xffff0000, v94
	v_and_b32_e32 v202, 0xffff0000, v90
	v_lshlrev_b32_e32 v204, 16, v91
	v_lshlrev_b32_e32 v205, 16, v95
	v_and_b32_e32 v95, 0xffff0000, v95
	v_and_b32_e32 v94, 0xffff0000, v91
	v_lshlrev_b32_e32 v91, 16, v96
	v_lshlrev_b32_e32 v90, 16, v92
	v_and_b32_e32 v207, 0xffff0000, v96
	v_and_b32_e32 v206, 0xffff0000, v92
	v_lshlrev_b32_e32 v92, 16, v93
	v_lshlrev_b32_e32 v93, 16, v97
	v_pk_add_f32 v[96:97], v[200:201], v[202:203]
	v_pk_add_f32 v[208:209], v[204:205], v[94:95]
	v_pk_add_f32 v[210:211], v[90:91], v[206:207]
	v_pk_add_f32 v[212:213], v[92:93], v[186:187]
	v_pk_add_f32 v[200:201], v[200:201], v[202:203] neg_lo:[0,1] neg_hi:[0,1]
	v_pk_add_f32 v[94:95], v[204:205], v[94:95] neg_lo:[0,1] neg_hi:[0,1]
	v_pk_add_f32 v[90:91], v[90:91], v[206:207] neg_lo:[0,1] neg_hi:[0,1]
	v_pk_add_f32 v[92:93], v[92:93], v[186:187] neg_lo:[0,1] neg_hi:[0,1]
	v_pk_add_f32 v[214:215], v[96:97], v[208:209] neg_lo:[0,1] neg_hi:[0,1]
	v_pk_add_f32 v[96:97], v[96:97], v[208:209]
	v_pk_add_f32 v[208:209], v[210:211], v[212:213]
	v_pk_add_f32 v[186:187], v[200:201], v[94:95] neg_lo:[0,1] neg_hi:[0,1]
	v_pk_add_f32 v[202:203], v[90:91], v[92:93] neg_lo:[0,1] neg_hi:[0,1]
	v_pk_add_f32 v[94:95], v[200:201], v[94:95]
	v_pk_add_f32 v[90:91], v[90:91], v[92:93]
	v_pk_add_f32 v[216:217], v[210:211], v[212:213] neg_lo:[0,1] neg_hi:[0,1]
	v_pk_add_f32 v[210:211], v[96:97], v[208:209]
	v_pk_add_f32 v[92:93], v[94:95], v[90:91]
	v_pk_add_f32 v[90:91], v[94:95], v[90:91] neg_lo:[0,1] neg_hi:[0,1]
	v_pk_add_f32 v[96:97], v[96:97], v[208:209] neg_lo:[0,1] neg_hi:[0,1]
	v_pk_add_f32 v[208:209], v[214:215], v[216:217]
	v_pk_add_f32 v[212:213], v[214:215], v[216:217] neg_lo:[0,1] neg_hi:[0,1]
	v_pk_add_f32 v[94:95], v[186:187], v[202:203]
	v_pk_add_f32 v[186:187], v[186:187], v[202:203] neg_lo:[0,1] neg_hi:[0,1]
	v_pk_add_f32 v[200:201], v[210:211], v[210:211] op_sel:[1,0] op_sel_hi:[0,1]
	v_pk_add_f32 v[216:217], v[90:91], v[90:91] op_sel:[1,0] op_sel_hi:[0,1]
	v_pk_add_f32 v[90:91], v[90:91], v[90:91] op_sel:[0,1] op_sel_hi:[1,0] neg_lo:[0,1] neg_hi:[0,1]
	v_pk_add_f32 v[204:205], v[92:93], v[92:93] op_sel:[1,0] op_sel_hi:[0,1]
	v_pk_add_f32 v[92:93], v[92:93], v[92:93] op_sel:[0,1] op_sel_hi:[1,0] neg_lo:[0,1] neg_hi:[0,1]
	v_pk_add_f32 v[220:221], v[186:187], v[186:187] op_sel:[1,0] op_sel_hi:[0,1]
	v_pk_add_f32 v[186:187], v[186:187], v[186:187] op_sel:[0,1] op_sel_hi:[1,0] neg_lo:[0,1] neg_hi:[0,1]
	v_xor_b32_e32 v91, v181, v200
	v_pk_add_f32 v[202:203], v[210:211], v[210:211] op_sel:[0,1] op_sel_hi:[1,0] neg_lo:[0,1] neg_hi:[0,1]
	v_pk_add_f32 v[206:207], v[208:209], v[208:209] op_sel:[1,0] op_sel_hi:[0,1]
	v_pk_add_f32 v[210:211], v[94:95], v[94:95] op_sel:[1,0] op_sel_hi:[0,1]
	v_pk_add_f32 v[94:95], v[94:95], v[94:95] op_sel:[0,1] op_sel_hi:[1,0] neg_lo:[0,1] neg_hi:[0,1]
	v_add_f32_dpp v91, v200, v91 quad_perm:[1,0,3,2] row_mask:0xf bank_mask:0xf bound_ctrl:1
	v_xor_b32_e32 v93, v181, v204
	v_xor_b32_e32 v205, v181, v186
	v_pk_add_f32 v[214:215], v[96:97], v[96:97] op_sel:[1,0] op_sel_hi:[0,1]
	v_pk_add_f32 v[96:97], v[96:97], v[96:97] op_sel:[0,1] op_sel_hi:[1,0] neg_lo:[0,1] neg_hi:[0,1]
	v_add_f32_dpp v93, v204, v93 quad_perm:[1,0,3,2] row_mask:0xf bank_mask:0xf bound_ctrl:1
	v_xor_b32_e32 v95, v181, v206
	v_add_f32_dpp v186, v186, v205 quad_perm:[1,0,3,2] row_mask:0xf bank_mask:0xf bound_ctrl:1
	v_xor_b32_e32 v205, v189, v91
	v_add_f32_dpp v95, v206, v95 quad_perm:[1,0,3,2] row_mask:0xf bank_mask:0xf bound_ctrl:1
	v_xor_b32_e32 v97, v181, v210
	v_add_f32_dpp v91, v91, v205 quad_perm:[2,3,0,1] row_mask:0xf bank_mask:0xf bound_ctrl:1
	v_xor_b32_e32 v205, v189, v93
	v_add_f32_dpp v97, v210, v97 quad_perm:[1,0,3,2] row_mask:0xf bank_mask:0xf bound_ctrl:1
	v_xor_b32_e32 v187, v181, v214
	v_add_f32_dpp v93, v93, v205 quad_perm:[2,3,0,1] row_mask:0xf bank_mask:0xf bound_ctrl:1
	v_xor_b32_e32 v205, v189, v95
	v_pk_add_f32 v[218:219], v[212:213], v[212:213] op_sel:[1,0] op_sel_hi:[0,1]
	v_add_f32_dpp v187, v214, v187 quad_perm:[1,0,3,2] row_mask:0xf bank_mask:0xf bound_ctrl:1
	v_xor_b32_e32 v199, v181, v216
	v_add_f32_dpp v95, v95, v205 quad_perm:[2,3,0,1] row_mask:0xf bank_mask:0xf bound_ctrl:1
	v_xor_b32_e32 v205, v189, v97
	v_add_f32_dpp v199, v216, v199 quad_perm:[1,0,3,2] row_mask:0xf bank_mask:0xf bound_ctrl:1
	v_xor_b32_e32 v200, v181, v218
	v_add_f32_dpp v97, v97, v205 quad_perm:[2,3,0,1] row_mask:0xf bank_mask:0xf bound_ctrl:1
	v_xor_b32_e32 v205, v189, v187
	v_add_f32_dpp v200, v218, v200 quad_perm:[1,0,3,2] row_mask:0xf bank_mask:0xf bound_ctrl:1
	v_xor_b32_e32 v201, v181, v220
	v_add_f32_dpp v187, v187, v205 quad_perm:[2,3,0,1] row_mask:0xf bank_mask:0xf bound_ctrl:1
	v_xor_b32_e32 v205, v189, v199
	v_add_f32_dpp v201, v220, v201 quad_perm:[1,0,3,2] row_mask:0xf bank_mask:0xf bound_ctrl:1
	v_xor_b32_e32 v203, v181, v202
	v_add_f32_dpp v199, v199, v205 quad_perm:[2,3,0,1] row_mask:0xf bank_mask:0xf bound_ctrl:1
	v_xor_b32_e32 v205, v189, v200
	v_pk_add_f32 v[208:209], v[208:209], v[208:209] op_sel:[0,1] op_sel_hi:[1,0] neg_lo:[0,1] neg_hi:[0,1]
	v_add_f32_dpp v202, v202, v203 quad_perm:[1,0,3,2] row_mask:0xf bank_mask:0xf bound_ctrl:1
	v_xor_b32_e32 v203, v181, v92
	v_add_f32_dpp v200, v200, v205 quad_perm:[2,3,0,1] row_mask:0xf bank_mask:0xf bound_ctrl:1
	v_xor_b32_e32 v205, v189, v201
	v_add_f32_dpp v92, v92, v203 quad_perm:[1,0,3,2] row_mask:0xf bank_mask:0xf bound_ctrl:1
	v_xor_b32_e32 v203, v181, v208
	v_add_f32_dpp v201, v201, v205 quad_perm:[2,3,0,1] row_mask:0xf bank_mask:0xf bound_ctrl:1
	v_xor_b32_e32 v205, v189, v202
	v_add_f32_dpp v203, v208, v203 quad_perm:[1,0,3,2] row_mask:0xf bank_mask:0xf bound_ctrl:1
	v_xor_b32_e32 v204, v181, v94
	v_add_f32_dpp v202, v202, v205 quad_perm:[2,3,0,1] row_mask:0xf bank_mask:0xf bound_ctrl:1
	v_xor_b32_e32 v205, v189, v92
	v_add_f32_dpp v94, v94, v204 quad_perm:[1,0,3,2] row_mask:0xf bank_mask:0xf bound_ctrl:1
	v_xor_b32_e32 v204, v181, v96
	v_add_f32_dpp v205, v92, v205 quad_perm:[2,3,0,1] row_mask:0xf bank_mask:0xf bound_ctrl:1
	v_xor_b32_e32 v92, v189, v203
	v_pk_add_f32 v[212:213], v[212:213], v[212:213] op_sel:[0,1] op_sel_hi:[1,0] neg_lo:[0,1] neg_hi:[0,1]
	v_add_f32_dpp v96, v96, v204 quad_perm:[1,0,3,2] row_mask:0xf bank_mask:0xf bound_ctrl:1
	v_xor_b32_e32 v204, v181, v90
	v_add_f32_dpp v203, v203, v92 quad_perm:[2,3,0,1] row_mask:0xf bank_mask:0xf bound_ctrl:1
	v_xor_b32_e32 v92, v189, v94
	v_add_f32_dpp v90, v90, v204 quad_perm:[1,0,3,2] row_mask:0xf bank_mask:0xf bound_ctrl:1
	v_xor_b32_e32 v204, v181, v212
	v_add_f32_dpp v206, v94, v92 quad_perm:[2,3,0,1] row_mask:0xf bank_mask:0xf bound_ctrl:1
	v_xor_b32_e32 v92, v189, v96
	v_add_f32_dpp v204, v212, v204 quad_perm:[1,0,3,2] row_mask:0xf bank_mask:0xf bound_ctrl:1
	v_max_f32_e64 v94, |v200|, |v201|
	v_add_f32_dpp v96, v96, v92 quad_perm:[2,3,0,1] row_mask:0xf bank_mask:0xf bound_ctrl:1
	v_xor_b32_e32 v92, v189, v90
	s_nop 1
	v_add_f32_dpp v207, v90, v92 quad_perm:[2,3,0,1] row_mask:0xf bank_mask:0xf bound_ctrl:1
	v_xor_b32_e32 v90, v189, v204
	v_max_f32_e64 v92, |v95|, |v97|
	s_nop 0
	v_add_f32_dpp v204, v204, v90 quad_perm:[2,3,0,1] row_mask:0xf bank_mask:0xf bound_ctrl:1
	v_xor_b32_e32 v90, v189, v186
	s_nop 1
	v_add_f32_dpp v186, v186, v90 quad_perm:[2,3,0,1] row_mask:0xf bank_mask:0xf bound_ctrl:1
	v_max_f32_e64 v90, |v91|, |v93|
	v_max3_f32 v90, v222, v90, v92
	v_max_f32_e64 v92, |v187|, |v199|
	v_max3_f32 v90, v90, v92, v94
	v_max_f32_e64 v92, |v202|, |v205|
	v_max_f32_e64 v94, |v203|, |v206|
	v_max3_f32 v90, v90, v92, v94
	v_max_f32_e64 v92, |v96|, |v207|
	v_max_f32_e64 v94, |v204|, |v186|
	v_max3_f32 v222, v90, v92, v94
	v_cvt_pk_bf16_f32 v90, v91, v93
	v_cvt_pk_bf16_f32 v91, v95, v97
	v_cvt_pk_bf16_f32 v92, v187, v199
	v_cvt_pk_bf16_f32 v93, v200, v201
	v_cvt_pk_bf16_f32 v94, v202, v205
	v_cvt_pk_bf16_f32 v95, v203, v206
	v_cvt_pk_bf16_f32 v96, v96, v207
	v_cvt_pk_bf16_f32 v97, v204, v186
	v_and_b32_e32 v187, 0xffff0000, v109
	v_and_b32_e32 v186, 0xffff0000, v105
	v_lshlrev_b32_e32 v201, 16, v106
	v_lshlrev_b32_e32 v200, 16, v102
	v_and_b32_e32 v203, 0xffff0000, v106
	v_and_b32_e32 v202, 0xffff0000, v102
	v_lshlrev_b32_e32 v204, 16, v103
	v_lshlrev_b32_e32 v205, 16, v107
	v_and_b32_e32 v107, 0xffff0000, v107
	v_and_b32_e32 v106, 0xffff0000, v103
	v_lshlrev_b32_e32 v103, 16, v108
	v_lshlrev_b32_e32 v102, 16, v104
	v_and_b32_e32 v207, 0xffff0000, v108
	v_and_b32_e32 v206, 0xffff0000, v104
	v_lshlrev_b32_e32 v104, 16, v105
	v_lshlrev_b32_e32 v105, 16, v109
	v_pk_add_f32 v[108:109], v[200:201], v[202:203]
	v_pk_add_f32 v[208:209], v[204:205], v[106:107]
	v_pk_add_f32 v[210:211], v[102:103], v[206:207]
	v_pk_add_f32 v[212:213], v[104:105], v[186:187]
	v_pk_add_f32 v[200:201], v[200:201], v[202:203] neg_lo:[0,1] neg_hi:[0,1]
	v_pk_add_f32 v[106:107], v[204:205], v[106:107] neg_lo:[0,1] neg_hi:[0,1]
	v_pk_add_f32 v[102:103], v[102:103], v[206:207] neg_lo:[0,1] neg_hi:[0,1]
	v_pk_add_f32 v[104:105], v[104:105], v[186:187] neg_lo:[0,1] neg_hi:[0,1]
	v_pk_add_f32 v[214:215], v[108:109], v[208:209] neg_lo:[0,1] neg_hi:[0,1]
	v_pk_add_f32 v[108:109], v[108:109], v[208:209]
	v_pk_add_f32 v[208:209], v[210:211], v[212:213]
	v_pk_add_f32 v[186:187], v[200:201], v[106:107] neg_lo:[0,1] neg_hi:[0,1]
	v_pk_add_f32 v[202:203], v[102:103], v[104:105] neg_lo:[0,1] neg_hi:[0,1]
	v_pk_add_f32 v[106:107], v[200:201], v[106:107]
	v_pk_add_f32 v[102:103], v[102:103], v[104:105]
	v_pk_add_f32 v[216:217], v[210:211], v[212:213] neg_lo:[0,1] neg_hi:[0,1]
	v_pk_add_f32 v[210:211], v[108:109], v[208:209]
	v_pk_add_f32 v[104:105], v[106:107], v[102:103]
	v_pk_add_f32 v[102:103], v[106:107], v[102:103] neg_lo:[0,1] neg_hi:[0,1]
	v_pk_add_f32 v[108:109], v[108:109], v[208:209] neg_lo:[0,1] neg_hi:[0,1]
	v_pk_add_f32 v[208:209], v[214:215], v[216:217]
	v_pk_add_f32 v[212:213], v[214:215], v[216:217] neg_lo:[0,1] neg_hi:[0,1]
	v_pk_add_f32 v[106:107], v[186:187], v[202:203]
	v_pk_add_f32 v[186:187], v[186:187], v[202:203] neg_lo:[0,1] neg_hi:[0,1]
	v_pk_add_f32 v[200:201], v[210:211], v[210:211] op_sel:[1,0] op_sel_hi:[0,1]
	v_pk_add_f32 v[216:217], v[102:103], v[102:103] op_sel:[1,0] op_sel_hi:[0,1]
	v_pk_add_f32 v[102:103], v[102:103], v[102:103] op_sel:[0,1] op_sel_hi:[1,0] neg_lo:[0,1] neg_hi:[0,1]
	v_pk_add_f32 v[204:205], v[104:105], v[104:105] op_sel:[1,0] op_sel_hi:[0,1]
	v_pk_add_f32 v[104:105], v[104:105], v[104:105] op_sel:[0,1] op_sel_hi:[1,0] neg_lo:[0,1] neg_hi:[0,1]
	v_pk_add_f32 v[220:221], v[186:187], v[186:187] op_sel:[1,0] op_sel_hi:[0,1]
	v_pk_add_f32 v[186:187], v[186:187], v[186:187] op_sel:[0,1] op_sel_hi:[1,0] neg_lo:[0,1] neg_hi:[0,1]
	v_xor_b32_e32 v103, v181, v200
	v_pk_add_f32 v[202:203], v[210:211], v[210:211] op_sel:[0,1] op_sel_hi:[1,0] neg_lo:[0,1] neg_hi:[0,1]
	v_pk_add_f32 v[206:207], v[208:209], v[208:209] op_sel:[1,0] op_sel_hi:[0,1]
	v_pk_add_f32 v[210:211], v[106:107], v[106:107] op_sel:[1,0] op_sel_hi:[0,1]
	v_pk_add_f32 v[106:107], v[106:107], v[106:107] op_sel:[0,1] op_sel_hi:[1,0] neg_lo:[0,1] neg_hi:[0,1]
	v_add_f32_dpp v103, v200, v103 quad_perm:[1,0,3,2] row_mask:0xf bank_mask:0xf bound_ctrl:1
	v_xor_b32_e32 v105, v181, v204
	v_xor_b32_e32 v205, v181, v186
	v_pk_add_f32 v[214:215], v[108:109], v[108:109] op_sel:[1,0] op_sel_hi:[0,1]
	v_pk_add_f32 v[108:109], v[108:109], v[108:109] op_sel:[0,1] op_sel_hi:[1,0] neg_lo:[0,1] neg_hi:[0,1]
	v_add_f32_dpp v105, v204, v105 quad_perm:[1,0,3,2] row_mask:0xf bank_mask:0xf bound_ctrl:1
	v_xor_b32_e32 v107, v181, v206
	v_add_f32_dpp v186, v186, v205 quad_perm:[1,0,3,2] row_mask:0xf bank_mask:0xf bound_ctrl:1
	v_xor_b32_e32 v205, v189, v103
	v_add_f32_dpp v107, v206, v107 quad_perm:[1,0,3,2] row_mask:0xf bank_mask:0xf bound_ctrl:1
	v_xor_b32_e32 v109, v181, v210
	v_add_f32_dpp v103, v103, v205 quad_perm:[2,3,0,1] row_mask:0xf bank_mask:0xf bound_ctrl:1
	v_xor_b32_e32 v205, v189, v105
	v_add_f32_dpp v109, v210, v109 quad_perm:[1,0,3,2] row_mask:0xf bank_mask:0xf bound_ctrl:1
	v_xor_b32_e32 v187, v181, v214
	v_add_f32_dpp v105, v105, v205 quad_perm:[2,3,0,1] row_mask:0xf bank_mask:0xf bound_ctrl:1
	v_xor_b32_e32 v205, v189, v107
	v_pk_add_f32 v[218:219], v[212:213], v[212:213] op_sel:[1,0] op_sel_hi:[0,1]
	v_add_f32_dpp v187, v214, v187 quad_perm:[1,0,3,2] row_mask:0xf bank_mask:0xf bound_ctrl:1
	v_xor_b32_e32 v199, v181, v216
	v_add_f32_dpp v107, v107, v205 quad_perm:[2,3,0,1] row_mask:0xf bank_mask:0xf bound_ctrl:1
	v_xor_b32_e32 v205, v189, v109
	v_add_f32_dpp v199, v216, v199 quad_perm:[1,0,3,2] row_mask:0xf bank_mask:0xf bound_ctrl:1
	v_xor_b32_e32 v200, v181, v218
	v_add_f32_dpp v109, v109, v205 quad_perm:[2,3,0,1] row_mask:0xf bank_mask:0xf bound_ctrl:1
	v_xor_b32_e32 v205, v189, v187
	v_add_f32_dpp v200, v218, v200 quad_perm:[1,0,3,2] row_mask:0xf bank_mask:0xf bound_ctrl:1
	v_xor_b32_e32 v201, v181, v220
	v_add_f32_dpp v187, v187, v205 quad_perm:[2,3,0,1] row_mask:0xf bank_mask:0xf bound_ctrl:1
	v_xor_b32_e32 v205, v189, v199
	v_add_f32_dpp v201, v220, v201 quad_perm:[1,0,3,2] row_mask:0xf bank_mask:0xf bound_ctrl:1
	v_xor_b32_e32 v203, v181, v202
	v_add_f32_dpp v199, v199, v205 quad_perm:[2,3,0,1] row_mask:0xf bank_mask:0xf bound_ctrl:1
	v_xor_b32_e32 v205, v189, v200
	v_pk_add_f32 v[208:209], v[208:209], v[208:209] op_sel:[0,1] op_sel_hi:[1,0] neg_lo:[0,1] neg_hi:[0,1]
	v_add_f32_dpp v202, v202, v203 quad_perm:[1,0,3,2] row_mask:0xf bank_mask:0xf bound_ctrl:1
	v_xor_b32_e32 v203, v181, v104
	v_add_f32_dpp v200, v200, v205 quad_perm:[2,3,0,1] row_mask:0xf bank_mask:0xf bound_ctrl:1
	v_xor_b32_e32 v205, v189, v201
	v_add_f32_dpp v104, v104, v203 quad_perm:[1,0,3,2] row_mask:0xf bank_mask:0xf bound_ctrl:1
	v_xor_b32_e32 v203, v181, v208
	v_add_f32_dpp v201, v201, v205 quad_perm:[2,3,0,1] row_mask:0xf bank_mask:0xf bound_ctrl:1
	v_xor_b32_e32 v205, v189, v202
	v_add_f32_dpp v203, v208, v203 quad_perm:[1,0,3,2] row_mask:0xf bank_mask:0xf bound_ctrl:1
	v_xor_b32_e32 v204, v181, v106
	v_add_f32_dpp v202, v202, v205 quad_perm:[2,3,0,1] row_mask:0xf bank_mask:0xf bound_ctrl:1
	v_xor_b32_e32 v205, v189, v104
	v_add_f32_dpp v106, v106, v204 quad_perm:[1,0,3,2] row_mask:0xf bank_mask:0xf bound_ctrl:1
	v_xor_b32_e32 v204, v181, v108
	v_add_f32_dpp v205, v104, v205 quad_perm:[2,3,0,1] row_mask:0xf bank_mask:0xf bound_ctrl:1
	v_xor_b32_e32 v104, v189, v203
	v_pk_add_f32 v[212:213], v[212:213], v[212:213] op_sel:[0,1] op_sel_hi:[1,0] neg_lo:[0,1] neg_hi:[0,1]
	v_add_f32_dpp v108, v108, v204 quad_perm:[1,0,3,2] row_mask:0xf bank_mask:0xf bound_ctrl:1
	v_xor_b32_e32 v204, v181, v102
	v_add_f32_dpp v203, v203, v104 quad_perm:[2,3,0,1] row_mask:0xf bank_mask:0xf bound_ctrl:1
	v_xor_b32_e32 v104, v189, v106
	v_add_f32_dpp v102, v102, v204 quad_perm:[1,0,3,2] row_mask:0xf bank_mask:0xf bound_ctrl:1
	v_xor_b32_e32 v204, v181, v212
	v_add_f32_dpp v206, v106, v104 quad_perm:[2,3,0,1] row_mask:0xf bank_mask:0xf bound_ctrl:1
	v_xor_b32_e32 v104, v189, v108
	v_add_f32_dpp v204, v212, v204 quad_perm:[1,0,3,2] row_mask:0xf bank_mask:0xf bound_ctrl:1
	v_max_f32_e64 v106, |v200|, |v201|
	v_add_f32_dpp v108, v108, v104 quad_perm:[2,3,0,1] row_mask:0xf bank_mask:0xf bound_ctrl:1
	v_xor_b32_e32 v104, v189, v102
	s_nop 1
	v_add_f32_dpp v207, v102, v104 quad_perm:[2,3,0,1] row_mask:0xf bank_mask:0xf bound_ctrl:1
	v_xor_b32_e32 v102, v189, v204
	v_max_f32_e64 v104, |v107|, |v109|
	s_nop 0
	v_add_f32_dpp v204, v204, v102 quad_perm:[2,3,0,1] row_mask:0xf bank_mask:0xf bound_ctrl:1
	v_xor_b32_e32 v102, v189, v186
	s_nop 1
	v_add_f32_dpp v186, v186, v102 quad_perm:[2,3,0,1] row_mask:0xf bank_mask:0xf bound_ctrl:1
	v_max_f32_e64 v102, |v103|, |v105|
	v_max3_f32 v102, v222, v102, v104
	v_max_f32_e64 v104, |v187|, |v199|
	v_max3_f32 v102, v102, v104, v106
	v_max_f32_e64 v104, |v202|, |v205|
	v_max_f32_e64 v106, |v203|, |v206|
	v_max3_f32 v102, v102, v104, v106
	v_max_f32_e64 v104, |v108|, |v207|
	v_max_f32_e64 v106, |v204|, |v186|
	v_max3_f32 v222, v102, v104, v106
	v_cvt_pk_bf16_f32 v102, v103, v105
	v_cvt_pk_bf16_f32 v103, v107, v109
	v_cvt_pk_bf16_f32 v104, v187, v199
	v_cvt_pk_bf16_f32 v105, v200, v201
	v_cvt_pk_bf16_f32 v106, v202, v205
	v_cvt_pk_bf16_f32 v107, v203, v206
	v_cvt_pk_bf16_f32 v108, v108, v207
	v_cvt_pk_bf16_f32 v109, v204, v186
	v_and_b32_e32 v187, 0xffff0000, v121
	v_and_b32_e32 v186, 0xffff0000, v117
	v_lshlrev_b32_e32 v201, 16, v118
	v_lshlrev_b32_e32 v200, 16, v114
	v_and_b32_e32 v203, 0xffff0000, v118
	v_and_b32_e32 v202, 0xffff0000, v114
	v_lshlrev_b32_e32 v204, 16, v115
	v_lshlrev_b32_e32 v205, 16, v119
	v_and_b32_e32 v119, 0xffff0000, v119
	v_and_b32_e32 v118, 0xffff0000, v115
	v_lshlrev_b32_e32 v115, 16, v120
	v_lshlrev_b32_e32 v114, 16, v116
	v_and_b32_e32 v207, 0xffff0000, v120
	v_and_b32_e32 v206, 0xffff0000, v116
	v_lshlrev_b32_e32 v116, 16, v117
	v_lshlrev_b32_e32 v117, 16, v121
	v_pk_add_f32 v[120:121], v[200:201], v[202:203]
	v_pk_add_f32 v[208:209], v[204:205], v[118:119]
	v_pk_add_f32 v[210:211], v[114:115], v[206:207]
	v_pk_add_f32 v[212:213], v[116:117], v[186:187]
	v_pk_add_f32 v[200:201], v[200:201], v[202:203] neg_lo:[0,1] neg_hi:[0,1]
	v_pk_add_f32 v[118:119], v[204:205], v[118:119] neg_lo:[0,1] neg_hi:[0,1]
	v_pk_add_f32 v[114:115], v[114:115], v[206:207] neg_lo:[0,1] neg_hi:[0,1]
	v_pk_add_f32 v[116:117], v[116:117], v[186:187] neg_lo:[0,1] neg_hi:[0,1]
	v_pk_add_f32 v[214:215], v[120:121], v[208:209] neg_lo:[0,1] neg_hi:[0,1]
	v_pk_add_f32 v[120:121], v[120:121], v[208:209]
	v_pk_add_f32 v[208:209], v[210:211], v[212:213]
	v_pk_add_f32 v[186:187], v[200:201], v[118:119] neg_lo:[0,1] neg_hi:[0,1]
	v_pk_add_f32 v[202:203], v[114:115], v[116:117] neg_lo:[0,1] neg_hi:[0,1]
	v_pk_add_f32 v[118:119], v[200:201], v[118:119]
	v_pk_add_f32 v[114:115], v[114:115], v[116:117]
	v_pk_add_f32 v[216:217], v[210:211], v[212:213] neg_lo:[0,1] neg_hi:[0,1]
	v_pk_add_f32 v[210:211], v[120:121], v[208:209]
	v_pk_add_f32 v[116:117], v[118:119], v[114:115]
	v_pk_add_f32 v[114:115], v[118:119], v[114:115] neg_lo:[0,1] neg_hi:[0,1]
	v_pk_add_f32 v[120:121], v[120:121], v[208:209] neg_lo:[0,1] neg_hi:[0,1]
	v_pk_add_f32 v[208:209], v[214:215], v[216:217]
	v_pk_add_f32 v[212:213], v[214:215], v[216:217] neg_lo:[0,1] neg_hi:[0,1]
	v_pk_add_f32 v[118:119], v[186:187], v[202:203]
	v_pk_add_f32 v[186:187], v[186:187], v[202:203] neg_lo:[0,1] neg_hi:[0,1]
	v_pk_add_f32 v[200:201], v[210:211], v[210:211] op_sel:[1,0] op_sel_hi:[0,1]
	v_pk_add_f32 v[216:217], v[114:115], v[114:115] op_sel:[1,0] op_sel_hi:[0,1]
	v_pk_add_f32 v[114:115], v[114:115], v[114:115] op_sel:[0,1] op_sel_hi:[1,0] neg_lo:[0,1] neg_hi:[0,1]
	v_pk_add_f32 v[204:205], v[116:117], v[116:117] op_sel:[1,0] op_sel_hi:[0,1]
	v_pk_add_f32 v[116:117], v[116:117], v[116:117] op_sel:[0,1] op_sel_hi:[1,0] neg_lo:[0,1] neg_hi:[0,1]
	v_pk_add_f32 v[220:221], v[186:187], v[186:187] op_sel:[1,0] op_sel_hi:[0,1]
	v_pk_add_f32 v[186:187], v[186:187], v[186:187] op_sel:[0,1] op_sel_hi:[1,0] neg_lo:[0,1] neg_hi:[0,1]
	v_xor_b32_e32 v115, v181, v200
	v_pk_add_f32 v[202:203], v[210:211], v[210:211] op_sel:[0,1] op_sel_hi:[1,0] neg_lo:[0,1] neg_hi:[0,1]
	v_pk_add_f32 v[206:207], v[208:209], v[208:209] op_sel:[1,0] op_sel_hi:[0,1]
	v_pk_add_f32 v[210:211], v[118:119], v[118:119] op_sel:[1,0] op_sel_hi:[0,1]
	v_pk_add_f32 v[118:119], v[118:119], v[118:119] op_sel:[0,1] op_sel_hi:[1,0] neg_lo:[0,1] neg_hi:[0,1]
	v_add_f32_dpp v115, v200, v115 quad_perm:[1,0,3,2] row_mask:0xf bank_mask:0xf bound_ctrl:1
	v_xor_b32_e32 v117, v181, v204
	v_xor_b32_e32 v205, v181, v186
	v_pk_add_f32 v[214:215], v[120:121], v[120:121] op_sel:[1,0] op_sel_hi:[0,1]
	v_pk_add_f32 v[120:121], v[120:121], v[120:121] op_sel:[0,1] op_sel_hi:[1,0] neg_lo:[0,1] neg_hi:[0,1]
	v_add_f32_dpp v117, v204, v117 quad_perm:[1,0,3,2] row_mask:0xf bank_mask:0xf bound_ctrl:1
	v_xor_b32_e32 v119, v181, v206
	v_add_f32_dpp v186, v186, v205 quad_perm:[1,0,3,2] row_mask:0xf bank_mask:0xf bound_ctrl:1
	v_xor_b32_e32 v205, v189, v115
	v_add_f32_dpp v119, v206, v119 quad_perm:[1,0,3,2] row_mask:0xf bank_mask:0xf bound_ctrl:1
	v_xor_b32_e32 v121, v181, v210
	v_add_f32_dpp v115, v115, v205 quad_perm:[2,3,0,1] row_mask:0xf bank_mask:0xf bound_ctrl:1
	v_xor_b32_e32 v205, v189, v117
	v_add_f32_dpp v121, v210, v121 quad_perm:[1,0,3,2] row_mask:0xf bank_mask:0xf bound_ctrl:1
	v_xor_b32_e32 v187, v181, v214
	v_add_f32_dpp v117, v117, v205 quad_perm:[2,3,0,1] row_mask:0xf bank_mask:0xf bound_ctrl:1
	v_xor_b32_e32 v205, v189, v119
	v_pk_add_f32 v[218:219], v[212:213], v[212:213] op_sel:[1,0] op_sel_hi:[0,1]
	v_add_f32_dpp v187, v214, v187 quad_perm:[1,0,3,2] row_mask:0xf bank_mask:0xf bound_ctrl:1
	v_xor_b32_e32 v199, v181, v216
	v_add_f32_dpp v119, v119, v205 quad_perm:[2,3,0,1] row_mask:0xf bank_mask:0xf bound_ctrl:1
	v_xor_b32_e32 v205, v189, v121
	v_add_f32_dpp v199, v216, v199 quad_perm:[1,0,3,2] row_mask:0xf bank_mask:0xf bound_ctrl:1
	v_xor_b32_e32 v200, v181, v218
	v_add_f32_dpp v121, v121, v205 quad_perm:[2,3,0,1] row_mask:0xf bank_mask:0xf bound_ctrl:1
	v_xor_b32_e32 v205, v189, v187
	v_add_f32_dpp v200, v218, v200 quad_perm:[1,0,3,2] row_mask:0xf bank_mask:0xf bound_ctrl:1
	v_xor_b32_e32 v201, v181, v220
	v_add_f32_dpp v187, v187, v205 quad_perm:[2,3,0,1] row_mask:0xf bank_mask:0xf bound_ctrl:1
	v_xor_b32_e32 v205, v189, v199
	v_add_f32_dpp v201, v220, v201 quad_perm:[1,0,3,2] row_mask:0xf bank_mask:0xf bound_ctrl:1
	v_xor_b32_e32 v203, v181, v202
	v_add_f32_dpp v199, v199, v205 quad_perm:[2,3,0,1] row_mask:0xf bank_mask:0xf bound_ctrl:1
	v_xor_b32_e32 v205, v189, v200
	v_pk_add_f32 v[208:209], v[208:209], v[208:209] op_sel:[0,1] op_sel_hi:[1,0] neg_lo:[0,1] neg_hi:[0,1]
	v_add_f32_dpp v202, v202, v203 quad_perm:[1,0,3,2] row_mask:0xf bank_mask:0xf bound_ctrl:1
	v_xor_b32_e32 v203, v181, v116
	v_add_f32_dpp v200, v200, v205 quad_perm:[2,3,0,1] row_mask:0xf bank_mask:0xf bound_ctrl:1
	v_xor_b32_e32 v205, v189, v201
	v_add_f32_dpp v116, v116, v203 quad_perm:[1,0,3,2] row_mask:0xf bank_mask:0xf bound_ctrl:1
	v_xor_b32_e32 v203, v181, v208
	v_add_f32_dpp v201, v201, v205 quad_perm:[2,3,0,1] row_mask:0xf bank_mask:0xf bound_ctrl:1
	v_xor_b32_e32 v205, v189, v202
	v_add_f32_dpp v203, v208, v203 quad_perm:[1,0,3,2] row_mask:0xf bank_mask:0xf bound_ctrl:1
	v_xor_b32_e32 v204, v181, v118
	v_add_f32_dpp v202, v202, v205 quad_perm:[2,3,0,1] row_mask:0xf bank_mask:0xf bound_ctrl:1
	v_xor_b32_e32 v205, v189, v116
	v_add_f32_dpp v118, v118, v204 quad_perm:[1,0,3,2] row_mask:0xf bank_mask:0xf bound_ctrl:1
	v_xor_b32_e32 v204, v181, v120
	v_add_f32_dpp v205, v116, v205 quad_perm:[2,3,0,1] row_mask:0xf bank_mask:0xf bound_ctrl:1
	v_xor_b32_e32 v116, v189, v203
	v_pk_add_f32 v[212:213], v[212:213], v[212:213] op_sel:[0,1] op_sel_hi:[1,0] neg_lo:[0,1] neg_hi:[0,1]
	v_add_f32_dpp v120, v120, v204 quad_perm:[1,0,3,2] row_mask:0xf bank_mask:0xf bound_ctrl:1
	v_xor_b32_e32 v204, v181, v114
	v_add_f32_dpp v203, v203, v116 quad_perm:[2,3,0,1] row_mask:0xf bank_mask:0xf bound_ctrl:1
	v_xor_b32_e32 v116, v189, v118
	v_add_f32_dpp v114, v114, v204 quad_perm:[1,0,3,2] row_mask:0xf bank_mask:0xf bound_ctrl:1
	v_xor_b32_e32 v204, v181, v212
	v_add_f32_dpp v206, v118, v116 quad_perm:[2,3,0,1] row_mask:0xf bank_mask:0xf bound_ctrl:1
	v_xor_b32_e32 v116, v189, v120
	v_add_f32_dpp v204, v212, v204 quad_perm:[1,0,3,2] row_mask:0xf bank_mask:0xf bound_ctrl:1
	v_max_f32_e64 v118, |v200|, |v201|
	v_add_f32_dpp v120, v120, v116 quad_perm:[2,3,0,1] row_mask:0xf bank_mask:0xf bound_ctrl:1
	v_xor_b32_e32 v116, v189, v114
	s_nop 1
	v_add_f32_dpp v207, v114, v116 quad_perm:[2,3,0,1] row_mask:0xf bank_mask:0xf bound_ctrl:1
	v_xor_b32_e32 v114, v189, v204
	v_max_f32_e64 v116, |v119|, |v121|
	s_nop 0
	v_add_f32_dpp v204, v204, v114 quad_perm:[2,3,0,1] row_mask:0xf bank_mask:0xf bound_ctrl:1
	v_xor_b32_e32 v114, v189, v186
	s_nop 1
	v_add_f32_dpp v186, v186, v114 quad_perm:[2,3,0,1] row_mask:0xf bank_mask:0xf bound_ctrl:1
	v_max_f32_e64 v114, |v115|, |v117|
	v_max3_f32 v114, v222, v114, v116
	v_max_f32_e64 v116, |v187|, |v199|
	v_max3_f32 v114, v114, v116, v118
	v_max_f32_e64 v116, |v202|, |v205|
	v_max_f32_e64 v118, |v203|, |v206|
	v_max3_f32 v114, v114, v116, v118
	v_max_f32_e64 v116, |v120|, |v207|
	v_max_f32_e64 v118, |v204|, |v186|
	v_max3_f32 v222, v114, v116, v118
	v_cvt_pk_bf16_f32 v114, v115, v117
	v_cvt_pk_bf16_f32 v115, v119, v121
	v_cvt_pk_bf16_f32 v116, v187, v199
	v_cvt_pk_bf16_f32 v117, v200, v201
	v_cvt_pk_bf16_f32 v118, v202, v205
	v_cvt_pk_bf16_f32 v119, v203, v206
	v_cvt_pk_bf16_f32 v120, v120, v207
	v_cvt_pk_bf16_f32 v121, v204, v186
	v_and_b32_e32 v187, 0xffff0000, v129
	v_and_b32_e32 v186, 0xffff0000, v125
	v_lshlrev_b32_e32 v201, 16, v126
	v_lshlrev_b32_e32 v200, 16, v122
	v_and_b32_e32 v203, 0xffff0000, v126
	v_and_b32_e32 v202, 0xffff0000, v122
	v_lshlrev_b32_e32 v204, 16, v123
	v_lshlrev_b32_e32 v205, 16, v127
	v_and_b32_e32 v127, 0xffff0000, v127
	v_and_b32_e32 v126, 0xffff0000, v123
	v_lshlrev_b32_e32 v123, 16, v128
	v_lshlrev_b32_e32 v122, 16, v124
	v_and_b32_e32 v207, 0xffff0000, v128
	v_and_b32_e32 v206, 0xffff0000, v124
	v_lshlrev_b32_e32 v124, 16, v125
	v_lshlrev_b32_e32 v125, 16, v129
	v_pk_add_f32 v[128:129], v[200:201], v[202:203]
	v_pk_add_f32 v[208:209], v[204:205], v[126:127]
	v_pk_add_f32 v[210:211], v[122:123], v[206:207]
	v_pk_add_f32 v[212:213], v[124:125], v[186:187]
	v_pk_add_f32 v[200:201], v[200:201], v[202:203] neg_lo:[0,1] neg_hi:[0,1]
	v_pk_add_f32 v[126:127], v[204:205], v[126:127] neg_lo:[0,1] neg_hi:[0,1]
	v_pk_add_f32 v[122:123], v[122:123], v[206:207] neg_lo:[0,1] neg_hi:[0,1]
	v_pk_add_f32 v[124:125], v[124:125], v[186:187] neg_lo:[0,1] neg_hi:[0,1]
	v_pk_add_f32 v[214:215], v[128:129], v[208:209] neg_lo:[0,1] neg_hi:[0,1]
	v_pk_add_f32 v[128:129], v[128:129], v[208:209]
	v_pk_add_f32 v[208:209], v[210:211], v[212:213]
	v_pk_add_f32 v[186:187], v[200:201], v[126:127] neg_lo:[0,1] neg_hi:[0,1]
	v_pk_add_f32 v[202:203], v[122:123], v[124:125] neg_lo:[0,1] neg_hi:[0,1]
	v_pk_add_f32 v[126:127], v[200:201], v[126:127]
	v_pk_add_f32 v[122:123], v[122:123], v[124:125]
	v_pk_add_f32 v[216:217], v[210:211], v[212:213] neg_lo:[0,1] neg_hi:[0,1]
	v_pk_add_f32 v[210:211], v[128:129], v[208:209]
	v_pk_add_f32 v[124:125], v[126:127], v[122:123]
	v_pk_add_f32 v[122:123], v[126:127], v[122:123] neg_lo:[0,1] neg_hi:[0,1]
	v_pk_add_f32 v[128:129], v[128:129], v[208:209] neg_lo:[0,1] neg_hi:[0,1]
	v_pk_add_f32 v[208:209], v[214:215], v[216:217]
	v_pk_add_f32 v[212:213], v[214:215], v[216:217] neg_lo:[0,1] neg_hi:[0,1]
	v_pk_add_f32 v[126:127], v[186:187], v[202:203]
	v_pk_add_f32 v[186:187], v[186:187], v[202:203] neg_lo:[0,1] neg_hi:[0,1]
	v_pk_add_f32 v[200:201], v[210:211], v[210:211] op_sel:[1,0] op_sel_hi:[0,1]
	v_pk_add_f32 v[216:217], v[122:123], v[122:123] op_sel:[1,0] op_sel_hi:[0,1]
	v_pk_add_f32 v[122:123], v[122:123], v[122:123] op_sel:[0,1] op_sel_hi:[1,0] neg_lo:[0,1] neg_hi:[0,1]
	v_pk_add_f32 v[204:205], v[124:125], v[124:125] op_sel:[1,0] op_sel_hi:[0,1]
	v_pk_add_f32 v[124:125], v[124:125], v[124:125] op_sel:[0,1] op_sel_hi:[1,0] neg_lo:[0,1] neg_hi:[0,1]
	v_pk_add_f32 v[220:221], v[186:187], v[186:187] op_sel:[1,0] op_sel_hi:[0,1]
	v_pk_add_f32 v[186:187], v[186:187], v[186:187] op_sel:[0,1] op_sel_hi:[1,0] neg_lo:[0,1] neg_hi:[0,1]
	v_xor_b32_e32 v123, v181, v200
	v_pk_add_f32 v[202:203], v[210:211], v[210:211] op_sel:[0,1] op_sel_hi:[1,0] neg_lo:[0,1] neg_hi:[0,1]
	v_pk_add_f32 v[206:207], v[208:209], v[208:209] op_sel:[1,0] op_sel_hi:[0,1]
	v_pk_add_f32 v[210:211], v[126:127], v[126:127] op_sel:[1,0] op_sel_hi:[0,1]
	v_pk_add_f32 v[126:127], v[126:127], v[126:127] op_sel:[0,1] op_sel_hi:[1,0] neg_lo:[0,1] neg_hi:[0,1]
	v_add_f32_dpp v123, v200, v123 quad_perm:[1,0,3,2] row_mask:0xf bank_mask:0xf bound_ctrl:1
	v_xor_b32_e32 v125, v181, v204
	v_xor_b32_e32 v205, v181, v186
	v_pk_add_f32 v[214:215], v[128:129], v[128:129] op_sel:[1,0] op_sel_hi:[0,1]
	v_pk_add_f32 v[128:129], v[128:129], v[128:129] op_sel:[0,1] op_sel_hi:[1,0] neg_lo:[0,1] neg_hi:[0,1]
	v_add_f32_dpp v125, v204, v125 quad_perm:[1,0,3,2] row_mask:0xf bank_mask:0xf bound_ctrl:1
	v_xor_b32_e32 v127, v181, v206
	v_add_f32_dpp v186, v186, v205 quad_perm:[1,0,3,2] row_mask:0xf bank_mask:0xf bound_ctrl:1
	v_xor_b32_e32 v205, v189, v123
	v_add_f32_dpp v127, v206, v127 quad_perm:[1,0,3,2] row_mask:0xf bank_mask:0xf bound_ctrl:1
	v_xor_b32_e32 v129, v181, v210
	v_add_f32_dpp v123, v123, v205 quad_perm:[2,3,0,1] row_mask:0xf bank_mask:0xf bound_ctrl:1
	v_xor_b32_e32 v205, v189, v125
	v_add_f32_dpp v129, v210, v129 quad_perm:[1,0,3,2] row_mask:0xf bank_mask:0xf bound_ctrl:1
	v_xor_b32_e32 v187, v181, v214
	v_add_f32_dpp v125, v125, v205 quad_perm:[2,3,0,1] row_mask:0xf bank_mask:0xf bound_ctrl:1
	v_xor_b32_e32 v205, v189, v127
	v_pk_add_f32 v[218:219], v[212:213], v[212:213] op_sel:[1,0] op_sel_hi:[0,1]
	v_add_f32_dpp v187, v214, v187 quad_perm:[1,0,3,2] row_mask:0xf bank_mask:0xf bound_ctrl:1
	v_xor_b32_e32 v199, v181, v216
	v_add_f32_dpp v127, v127, v205 quad_perm:[2,3,0,1] row_mask:0xf bank_mask:0xf bound_ctrl:1
	v_xor_b32_e32 v205, v189, v129
	v_add_f32_dpp v199, v216, v199 quad_perm:[1,0,3,2] row_mask:0xf bank_mask:0xf bound_ctrl:1
	v_xor_b32_e32 v200, v181, v218
	v_add_f32_dpp v129, v129, v205 quad_perm:[2,3,0,1] row_mask:0xf bank_mask:0xf bound_ctrl:1
	v_xor_b32_e32 v205, v189, v187
	v_add_f32_dpp v200, v218, v200 quad_perm:[1,0,3,2] row_mask:0xf bank_mask:0xf bound_ctrl:1
	v_xor_b32_e32 v201, v181, v220
	v_add_f32_dpp v187, v187, v205 quad_perm:[2,3,0,1] row_mask:0xf bank_mask:0xf bound_ctrl:1
	v_xor_b32_e32 v205, v189, v199
	v_add_f32_dpp v201, v220, v201 quad_perm:[1,0,3,2] row_mask:0xf bank_mask:0xf bound_ctrl:1
	v_xor_b32_e32 v203, v181, v202
	v_add_f32_dpp v199, v199, v205 quad_perm:[2,3,0,1] row_mask:0xf bank_mask:0xf bound_ctrl:1
	v_xor_b32_e32 v205, v189, v200
	v_pk_add_f32 v[208:209], v[208:209], v[208:209] op_sel:[0,1] op_sel_hi:[1,0] neg_lo:[0,1] neg_hi:[0,1]
	v_add_f32_dpp v202, v202, v203 quad_perm:[1,0,3,2] row_mask:0xf bank_mask:0xf bound_ctrl:1
	v_xor_b32_e32 v203, v181, v124
	v_add_f32_dpp v200, v200, v205 quad_perm:[2,3,0,1] row_mask:0xf bank_mask:0xf bound_ctrl:1
	v_xor_b32_e32 v205, v189, v201
	v_add_f32_dpp v124, v124, v203 quad_perm:[1,0,3,2] row_mask:0xf bank_mask:0xf bound_ctrl:1
	v_xor_b32_e32 v203, v181, v208
	v_add_f32_dpp v201, v201, v205 quad_perm:[2,3,0,1] row_mask:0xf bank_mask:0xf bound_ctrl:1
	v_xor_b32_e32 v205, v189, v202
	v_add_f32_dpp v203, v208, v203 quad_perm:[1,0,3,2] row_mask:0xf bank_mask:0xf bound_ctrl:1
	v_xor_b32_e32 v204, v181, v126
	v_add_f32_dpp v202, v202, v205 quad_perm:[2,3,0,1] row_mask:0xf bank_mask:0xf bound_ctrl:1
	v_xor_b32_e32 v205, v189, v124
	v_add_f32_dpp v126, v126, v204 quad_perm:[1,0,3,2] row_mask:0xf bank_mask:0xf bound_ctrl:1
	v_xor_b32_e32 v204, v181, v128
	v_add_f32_dpp v205, v124, v205 quad_perm:[2,3,0,1] row_mask:0xf bank_mask:0xf bound_ctrl:1
	v_xor_b32_e32 v124, v189, v203
	v_pk_add_f32 v[212:213], v[212:213], v[212:213] op_sel:[0,1] op_sel_hi:[1,0] neg_lo:[0,1] neg_hi:[0,1]
	v_add_f32_dpp v128, v128, v204 quad_perm:[1,0,3,2] row_mask:0xf bank_mask:0xf bound_ctrl:1
	v_xor_b32_e32 v204, v181, v122
	v_add_f32_dpp v203, v203, v124 quad_perm:[2,3,0,1] row_mask:0xf bank_mask:0xf bound_ctrl:1
	v_xor_b32_e32 v124, v189, v126
	v_add_f32_dpp v122, v122, v204 quad_perm:[1,0,3,2] row_mask:0xf bank_mask:0xf bound_ctrl:1
	v_xor_b32_e32 v204, v181, v212
	v_add_f32_dpp v206, v126, v124 quad_perm:[2,3,0,1] row_mask:0xf bank_mask:0xf bound_ctrl:1
	v_xor_b32_e32 v124, v189, v128
	v_add_f32_dpp v204, v212, v204 quad_perm:[1,0,3,2] row_mask:0xf bank_mask:0xf bound_ctrl:1
	v_max_f32_e64 v126, |v200|, |v201|
	v_add_f32_dpp v128, v128, v124 quad_perm:[2,3,0,1] row_mask:0xf bank_mask:0xf bound_ctrl:1
	v_xor_b32_e32 v124, v189, v122
	s_nop 1
	v_add_f32_dpp v207, v122, v124 quad_perm:[2,3,0,1] row_mask:0xf bank_mask:0xf bound_ctrl:1
	v_xor_b32_e32 v122, v189, v204
	v_max_f32_e64 v124, |v127|, |v129|
	s_nop 0
	v_add_f32_dpp v204, v204, v122 quad_perm:[2,3,0,1] row_mask:0xf bank_mask:0xf bound_ctrl:1
	v_xor_b32_e32 v122, v189, v186
	s_nop 1
	v_add_f32_dpp v186, v186, v122 quad_perm:[2,3,0,1] row_mask:0xf bank_mask:0xf bound_ctrl:1
	v_max_f32_e64 v122, |v123|, |v125|
	v_max3_f32 v122, v222, v122, v124
	v_max_f32_e64 v124, |v187|, |v199|
	v_max3_f32 v122, v122, v124, v126
	v_max_f32_e64 v124, |v202|, |v205|
	v_max_f32_e64 v126, |v203|, |v206|
	v_max3_f32 v122, v122, v124, v126
	v_max_f32_e64 v124, |v128|, |v207|
	v_max_f32_e64 v126, |v204|, |v186|
	v_max3_f32 v222, v122, v124, v126
	v_cvt_pk_bf16_f32 v122, v123, v125
	v_cvt_pk_bf16_f32 v123, v127, v129
	v_cvt_pk_bf16_f32 v124, v187, v199
	v_cvt_pk_bf16_f32 v125, v200, v201
	v_cvt_pk_bf16_f32 v126, v202, v205
	v_cvt_pk_bf16_f32 v127, v203, v206
	v_cvt_pk_bf16_f32 v128, v128, v207
	v_cvt_pk_bf16_f32 v129, v204, v186
	v_and_b32_e32 v187, 0xffff0000, v137
	v_and_b32_e32 v186, 0xffff0000, v133
	v_lshlrev_b32_e32 v201, 16, v134
	v_lshlrev_b32_e32 v200, 16, v130
	v_and_b32_e32 v203, 0xffff0000, v134
	v_and_b32_e32 v202, 0xffff0000, v130
	v_lshlrev_b32_e32 v204, 16, v131
	v_lshlrev_b32_e32 v205, 16, v135
	v_and_b32_e32 v135, 0xffff0000, v135
	v_and_b32_e32 v134, 0xffff0000, v131
	v_lshlrev_b32_e32 v131, 16, v136
	v_lshlrev_b32_e32 v130, 16, v132
	v_and_b32_e32 v207, 0xffff0000, v136
	v_and_b32_e32 v206, 0xffff0000, v132
	v_lshlrev_b32_e32 v132, 16, v133
	v_lshlrev_b32_e32 v133, 16, v137
	v_pk_add_f32 v[136:137], v[200:201], v[202:203]
	v_pk_add_f32 v[208:209], v[204:205], v[134:135]
	v_pk_add_f32 v[210:211], v[130:131], v[206:207]
	v_pk_add_f32 v[212:213], v[132:133], v[186:187]
	v_pk_add_f32 v[200:201], v[200:201], v[202:203] neg_lo:[0,1] neg_hi:[0,1]
	v_pk_add_f32 v[134:135], v[204:205], v[134:135] neg_lo:[0,1] neg_hi:[0,1]
	v_pk_add_f32 v[130:131], v[130:131], v[206:207] neg_lo:[0,1] neg_hi:[0,1]
	v_pk_add_f32 v[132:133], v[132:133], v[186:187] neg_lo:[0,1] neg_hi:[0,1]
	v_pk_add_f32 v[214:215], v[136:137], v[208:209] neg_lo:[0,1] neg_hi:[0,1]
	v_pk_add_f32 v[136:137], v[136:137], v[208:209]
	v_pk_add_f32 v[208:209], v[210:211], v[212:213]
	v_pk_add_f32 v[186:187], v[200:201], v[134:135] neg_lo:[0,1] neg_hi:[0,1]
	v_pk_add_f32 v[202:203], v[130:131], v[132:133] neg_lo:[0,1] neg_hi:[0,1]
	v_pk_add_f32 v[134:135], v[200:201], v[134:135]
	v_pk_add_f32 v[130:131], v[130:131], v[132:133]
	v_pk_add_f32 v[216:217], v[210:211], v[212:213] neg_lo:[0,1] neg_hi:[0,1]
	v_pk_add_f32 v[210:211], v[136:137], v[208:209]
	v_pk_add_f32 v[132:133], v[134:135], v[130:131]
	v_pk_add_f32 v[130:131], v[134:135], v[130:131] neg_lo:[0,1] neg_hi:[0,1]
	v_pk_add_f32 v[136:137], v[136:137], v[208:209] neg_lo:[0,1] neg_hi:[0,1]
	v_pk_add_f32 v[208:209], v[214:215], v[216:217]
	v_pk_add_f32 v[212:213], v[214:215], v[216:217] neg_lo:[0,1] neg_hi:[0,1]
	v_pk_add_f32 v[134:135], v[186:187], v[202:203]
	v_pk_add_f32 v[186:187], v[186:187], v[202:203] neg_lo:[0,1] neg_hi:[0,1]
	v_pk_add_f32 v[200:201], v[210:211], v[210:211] op_sel:[1,0] op_sel_hi:[0,1]
	v_pk_add_f32 v[216:217], v[130:131], v[130:131] op_sel:[1,0] op_sel_hi:[0,1]
	v_pk_add_f32 v[130:131], v[130:131], v[130:131] op_sel:[0,1] op_sel_hi:[1,0] neg_lo:[0,1] neg_hi:[0,1]
	v_pk_add_f32 v[204:205], v[132:133], v[132:133] op_sel:[1,0] op_sel_hi:[0,1]
	v_pk_add_f32 v[132:133], v[132:133], v[132:133] op_sel:[0,1] op_sel_hi:[1,0] neg_lo:[0,1] neg_hi:[0,1]
	v_pk_add_f32 v[220:221], v[186:187], v[186:187] op_sel:[1,0] op_sel_hi:[0,1]
	v_pk_add_f32 v[186:187], v[186:187], v[186:187] op_sel:[0,1] op_sel_hi:[1,0] neg_lo:[0,1] neg_hi:[0,1]
	v_xor_b32_e32 v131, v181, v200
	v_pk_add_f32 v[202:203], v[210:211], v[210:211] op_sel:[0,1] op_sel_hi:[1,0] neg_lo:[0,1] neg_hi:[0,1]
	v_pk_add_f32 v[206:207], v[208:209], v[208:209] op_sel:[1,0] op_sel_hi:[0,1]
	v_pk_add_f32 v[210:211], v[134:135], v[134:135] op_sel:[1,0] op_sel_hi:[0,1]
	v_pk_add_f32 v[134:135], v[134:135], v[134:135] op_sel:[0,1] op_sel_hi:[1,0] neg_lo:[0,1] neg_hi:[0,1]
	v_add_f32_dpp v131, v200, v131 quad_perm:[1,0,3,2] row_mask:0xf bank_mask:0xf bound_ctrl:1
	v_xor_b32_e32 v133, v181, v204
	v_xor_b32_e32 v205, v181, v186
	v_pk_add_f32 v[214:215], v[136:137], v[136:137] op_sel:[1,0] op_sel_hi:[0,1]
	v_pk_add_f32 v[136:137], v[136:137], v[136:137] op_sel:[0,1] op_sel_hi:[1,0] neg_lo:[0,1] neg_hi:[0,1]
	v_add_f32_dpp v133, v204, v133 quad_perm:[1,0,3,2] row_mask:0xf bank_mask:0xf bound_ctrl:1
	v_xor_b32_e32 v135, v181, v206
	v_add_f32_dpp v186, v186, v205 quad_perm:[1,0,3,2] row_mask:0xf bank_mask:0xf bound_ctrl:1
	v_xor_b32_e32 v205, v189, v131
	v_add_f32_dpp v135, v206, v135 quad_perm:[1,0,3,2] row_mask:0xf bank_mask:0xf bound_ctrl:1
	v_xor_b32_e32 v137, v181, v210
	v_add_f32_dpp v131, v131, v205 quad_perm:[2,3,0,1] row_mask:0xf bank_mask:0xf bound_ctrl:1
	v_xor_b32_e32 v205, v189, v133
	v_add_f32_dpp v137, v210, v137 quad_perm:[1,0,3,2] row_mask:0xf bank_mask:0xf bound_ctrl:1
	v_xor_b32_e32 v187, v181, v214
	v_add_f32_dpp v133, v133, v205 quad_perm:[2,3,0,1] row_mask:0xf bank_mask:0xf bound_ctrl:1
	v_xor_b32_e32 v205, v189, v135
	v_pk_add_f32 v[218:219], v[212:213], v[212:213] op_sel:[1,0] op_sel_hi:[0,1]
	v_add_f32_dpp v187, v214, v187 quad_perm:[1,0,3,2] row_mask:0xf bank_mask:0xf bound_ctrl:1
	v_xor_b32_e32 v199, v181, v216
	v_add_f32_dpp v135, v135, v205 quad_perm:[2,3,0,1] row_mask:0xf bank_mask:0xf bound_ctrl:1
	v_xor_b32_e32 v205, v189, v137
	v_add_f32_dpp v199, v216, v199 quad_perm:[1,0,3,2] row_mask:0xf bank_mask:0xf bound_ctrl:1
	v_xor_b32_e32 v200, v181, v218
	v_add_f32_dpp v137, v137, v205 quad_perm:[2,3,0,1] row_mask:0xf bank_mask:0xf bound_ctrl:1
	v_xor_b32_e32 v205, v189, v187
	v_add_f32_dpp v200, v218, v200 quad_perm:[1,0,3,2] row_mask:0xf bank_mask:0xf bound_ctrl:1
	v_xor_b32_e32 v201, v181, v220
	v_add_f32_dpp v187, v187, v205 quad_perm:[2,3,0,1] row_mask:0xf bank_mask:0xf bound_ctrl:1
	v_xor_b32_e32 v205, v189, v199
	v_add_f32_dpp v201, v220, v201 quad_perm:[1,0,3,2] row_mask:0xf bank_mask:0xf bound_ctrl:1
	v_xor_b32_e32 v203, v181, v202
	v_add_f32_dpp v199, v199, v205 quad_perm:[2,3,0,1] row_mask:0xf bank_mask:0xf bound_ctrl:1
	v_xor_b32_e32 v205, v189, v200
	v_pk_add_f32 v[208:209], v[208:209], v[208:209] op_sel:[0,1] op_sel_hi:[1,0] neg_lo:[0,1] neg_hi:[0,1]
	v_add_f32_dpp v202, v202, v203 quad_perm:[1,0,3,2] row_mask:0xf bank_mask:0xf bound_ctrl:1
	v_xor_b32_e32 v203, v181, v132
	v_add_f32_dpp v200, v200, v205 quad_perm:[2,3,0,1] row_mask:0xf bank_mask:0xf bound_ctrl:1
	v_xor_b32_e32 v205, v189, v201
	v_add_f32_dpp v132, v132, v203 quad_perm:[1,0,3,2] row_mask:0xf bank_mask:0xf bound_ctrl:1
	v_xor_b32_e32 v203, v181, v208
	v_add_f32_dpp v201, v201, v205 quad_perm:[2,3,0,1] row_mask:0xf bank_mask:0xf bound_ctrl:1
	v_xor_b32_e32 v205, v189, v202
	v_add_f32_dpp v203, v208, v203 quad_perm:[1,0,3,2] row_mask:0xf bank_mask:0xf bound_ctrl:1
	v_xor_b32_e32 v204, v181, v134
	v_add_f32_dpp v202, v202, v205 quad_perm:[2,3,0,1] row_mask:0xf bank_mask:0xf bound_ctrl:1
	v_xor_b32_e32 v205, v189, v132
	v_add_f32_dpp v134, v134, v204 quad_perm:[1,0,3,2] row_mask:0xf bank_mask:0xf bound_ctrl:1
	v_xor_b32_e32 v204, v181, v136
	v_add_f32_dpp v205, v132, v205 quad_perm:[2,3,0,1] row_mask:0xf bank_mask:0xf bound_ctrl:1
	v_xor_b32_e32 v132, v189, v203
	v_pk_add_f32 v[212:213], v[212:213], v[212:213] op_sel:[0,1] op_sel_hi:[1,0] neg_lo:[0,1] neg_hi:[0,1]
	v_add_f32_dpp v136, v136, v204 quad_perm:[1,0,3,2] row_mask:0xf bank_mask:0xf bound_ctrl:1
	v_xor_b32_e32 v204, v181, v130
	v_add_f32_dpp v203, v203, v132 quad_perm:[2,3,0,1] row_mask:0xf bank_mask:0xf bound_ctrl:1
	v_xor_b32_e32 v132, v189, v134
	v_add_f32_dpp v130, v130, v204 quad_perm:[1,0,3,2] row_mask:0xf bank_mask:0xf bound_ctrl:1
	v_xor_b32_e32 v204, v181, v212
	v_add_f32_dpp v206, v134, v132 quad_perm:[2,3,0,1] row_mask:0xf bank_mask:0xf bound_ctrl:1
	v_xor_b32_e32 v132, v189, v136
	v_add_f32_dpp v204, v212, v204 quad_perm:[1,0,3,2] row_mask:0xf bank_mask:0xf bound_ctrl:1
	v_max_f32_e64 v134, |v200|, |v201|
	v_add_f32_dpp v136, v136, v132 quad_perm:[2,3,0,1] row_mask:0xf bank_mask:0xf bound_ctrl:1
	v_xor_b32_e32 v132, v189, v130
	s_nop 1
	v_add_f32_dpp v207, v130, v132 quad_perm:[2,3,0,1] row_mask:0xf bank_mask:0xf bound_ctrl:1
	v_xor_b32_e32 v130, v189, v204
	v_max_f32_e64 v132, |v135|, |v137|
	s_nop 0
	v_add_f32_dpp v204, v204, v130 quad_perm:[2,3,0,1] row_mask:0xf bank_mask:0xf bound_ctrl:1
	v_xor_b32_e32 v130, v189, v186
	s_nop 1
	v_add_f32_dpp v186, v186, v130 quad_perm:[2,3,0,1] row_mask:0xf bank_mask:0xf bound_ctrl:1
	v_max_f32_e64 v130, |v131|, |v133|
	v_max3_f32 v130, v222, v130, v132
	v_max_f32_e64 v132, |v187|, |v199|
	v_max3_f32 v130, v130, v132, v134
	v_max_f32_e64 v132, |v202|, |v205|
	v_max_f32_e64 v134, |v203|, |v206|
	v_max3_f32 v130, v130, v132, v134
	v_max_f32_e64 v132, |v136|, |v207|
	v_max_f32_e64 v134, |v204|, |v186|
	v_max3_f32 v222, v130, v132, v134
	v_cvt_pk_bf16_f32 v130, v131, v133
	v_cvt_pk_bf16_f32 v131, v135, v137
	v_cvt_pk_bf16_f32 v132, v187, v199
	v_cvt_pk_bf16_f32 v133, v200, v201
	v_cvt_pk_bf16_f32 v134, v202, v205
	v_cvt_pk_bf16_f32 v135, v203, v206
	v_cvt_pk_bf16_f32 v136, v136, v207
	v_cvt_pk_bf16_f32 v137, v204, v186
	v_and_b32_e32 v187, 0xffff0000, v145
	v_and_b32_e32 v186, 0xffff0000, v141
	v_lshlrev_b32_e32 v201, 16, v142
	v_lshlrev_b32_e32 v200, 16, v138
	v_and_b32_e32 v203, 0xffff0000, v142
	v_and_b32_e32 v202, 0xffff0000, v138
	v_lshlrev_b32_e32 v204, 16, v139
	v_lshlrev_b32_e32 v205, 16, v143
	v_and_b32_e32 v143, 0xffff0000, v143
	v_and_b32_e32 v142, 0xffff0000, v139
	v_lshlrev_b32_e32 v139, 16, v144
	v_lshlrev_b32_e32 v138, 16, v140
	v_and_b32_e32 v207, 0xffff0000, v144
	v_and_b32_e32 v206, 0xffff0000, v140
	v_lshlrev_b32_e32 v140, 16, v141
	v_lshlrev_b32_e32 v141, 16, v145
	v_pk_add_f32 v[144:145], v[200:201], v[202:203]
	v_pk_add_f32 v[208:209], v[204:205], v[142:143]
	v_pk_add_f32 v[210:211], v[138:139], v[206:207]
	v_pk_add_f32 v[212:213], v[140:141], v[186:187]
	v_pk_add_f32 v[200:201], v[200:201], v[202:203] neg_lo:[0,1] neg_hi:[0,1]
	v_pk_add_f32 v[142:143], v[204:205], v[142:143] neg_lo:[0,1] neg_hi:[0,1]
	v_pk_add_f32 v[138:139], v[138:139], v[206:207] neg_lo:[0,1] neg_hi:[0,1]
	v_pk_add_f32 v[140:141], v[140:141], v[186:187] neg_lo:[0,1] neg_hi:[0,1]
	v_pk_add_f32 v[214:215], v[144:145], v[208:209] neg_lo:[0,1] neg_hi:[0,1]
	v_pk_add_f32 v[144:145], v[144:145], v[208:209]
	v_pk_add_f32 v[208:209], v[210:211], v[212:213]
	v_pk_add_f32 v[186:187], v[200:201], v[142:143] neg_lo:[0,1] neg_hi:[0,1]
	v_pk_add_f32 v[202:203], v[138:139], v[140:141] neg_lo:[0,1] neg_hi:[0,1]
	v_pk_add_f32 v[142:143], v[200:201], v[142:143]
	v_pk_add_f32 v[138:139], v[138:139], v[140:141]
	v_pk_add_f32 v[216:217], v[210:211], v[212:213] neg_lo:[0,1] neg_hi:[0,1]
	v_pk_add_f32 v[210:211], v[144:145], v[208:209]
	v_pk_add_f32 v[140:141], v[142:143], v[138:139]
	v_pk_add_f32 v[138:139], v[142:143], v[138:139] neg_lo:[0,1] neg_hi:[0,1]
	v_pk_add_f32 v[144:145], v[144:145], v[208:209] neg_lo:[0,1] neg_hi:[0,1]
	v_pk_add_f32 v[208:209], v[214:215], v[216:217]
	v_pk_add_f32 v[212:213], v[214:215], v[216:217] neg_lo:[0,1] neg_hi:[0,1]
	v_pk_add_f32 v[142:143], v[186:187], v[202:203]
	v_pk_add_f32 v[186:187], v[186:187], v[202:203] neg_lo:[0,1] neg_hi:[0,1]
	v_pk_add_f32 v[200:201], v[210:211], v[210:211] op_sel:[1,0] op_sel_hi:[0,1]
	v_pk_add_f32 v[216:217], v[138:139], v[138:139] op_sel:[1,0] op_sel_hi:[0,1]
	v_pk_add_f32 v[138:139], v[138:139], v[138:139] op_sel:[0,1] op_sel_hi:[1,0] neg_lo:[0,1] neg_hi:[0,1]
	v_pk_add_f32 v[204:205], v[140:141], v[140:141] op_sel:[1,0] op_sel_hi:[0,1]
	v_pk_add_f32 v[140:141], v[140:141], v[140:141] op_sel:[0,1] op_sel_hi:[1,0] neg_lo:[0,1] neg_hi:[0,1]
	v_pk_add_f32 v[220:221], v[186:187], v[186:187] op_sel:[1,0] op_sel_hi:[0,1]
	v_pk_add_f32 v[186:187], v[186:187], v[186:187] op_sel:[0,1] op_sel_hi:[1,0] neg_lo:[0,1] neg_hi:[0,1]
	v_xor_b32_e32 v139, v181, v200
	v_pk_add_f32 v[202:203], v[210:211], v[210:211] op_sel:[0,1] op_sel_hi:[1,0] neg_lo:[0,1] neg_hi:[0,1]
	v_pk_add_f32 v[206:207], v[208:209], v[208:209] op_sel:[1,0] op_sel_hi:[0,1]
	v_pk_add_f32 v[210:211], v[142:143], v[142:143] op_sel:[1,0] op_sel_hi:[0,1]
	v_pk_add_f32 v[142:143], v[142:143], v[142:143] op_sel:[0,1] op_sel_hi:[1,0] neg_lo:[0,1] neg_hi:[0,1]
	v_add_f32_dpp v139, v200, v139 quad_perm:[1,0,3,2] row_mask:0xf bank_mask:0xf bound_ctrl:1
	v_xor_b32_e32 v141, v181, v204
	v_xor_b32_e32 v205, v181, v186
	v_pk_add_f32 v[214:215], v[144:145], v[144:145] op_sel:[1,0] op_sel_hi:[0,1]
	v_pk_add_f32 v[144:145], v[144:145], v[144:145] op_sel:[0,1] op_sel_hi:[1,0] neg_lo:[0,1] neg_hi:[0,1]
	v_add_f32_dpp v141, v204, v141 quad_perm:[1,0,3,2] row_mask:0xf bank_mask:0xf bound_ctrl:1
	v_xor_b32_e32 v143, v181, v206
	v_add_f32_dpp v186, v186, v205 quad_perm:[1,0,3,2] row_mask:0xf bank_mask:0xf bound_ctrl:1
	v_xor_b32_e32 v205, v189, v139
	v_add_f32_dpp v143, v206, v143 quad_perm:[1,0,3,2] row_mask:0xf bank_mask:0xf bound_ctrl:1
	v_xor_b32_e32 v145, v181, v210
	v_add_f32_dpp v139, v139, v205 quad_perm:[2,3,0,1] row_mask:0xf bank_mask:0xf bound_ctrl:1
	v_xor_b32_e32 v205, v189, v141
	v_add_f32_dpp v145, v210, v145 quad_perm:[1,0,3,2] row_mask:0xf bank_mask:0xf bound_ctrl:1
	v_xor_b32_e32 v187, v181, v214
	v_add_f32_dpp v141, v141, v205 quad_perm:[2,3,0,1] row_mask:0xf bank_mask:0xf bound_ctrl:1
	v_xor_b32_e32 v205, v189, v143
	v_pk_add_f32 v[218:219], v[212:213], v[212:213] op_sel:[1,0] op_sel_hi:[0,1]
	v_add_f32_dpp v187, v214, v187 quad_perm:[1,0,3,2] row_mask:0xf bank_mask:0xf bound_ctrl:1
	v_xor_b32_e32 v199, v181, v216
	v_add_f32_dpp v143, v143, v205 quad_perm:[2,3,0,1] row_mask:0xf bank_mask:0xf bound_ctrl:1
	v_xor_b32_e32 v205, v189, v145
	v_add_f32_dpp v199, v216, v199 quad_perm:[1,0,3,2] row_mask:0xf bank_mask:0xf bound_ctrl:1
	v_xor_b32_e32 v200, v181, v218
	v_add_f32_dpp v145, v145, v205 quad_perm:[2,3,0,1] row_mask:0xf bank_mask:0xf bound_ctrl:1
	v_xor_b32_e32 v205, v189, v187
	v_add_f32_dpp v200, v218, v200 quad_perm:[1,0,3,2] row_mask:0xf bank_mask:0xf bound_ctrl:1
	v_xor_b32_e32 v201, v181, v220
	v_add_f32_dpp v187, v187, v205 quad_perm:[2,3,0,1] row_mask:0xf bank_mask:0xf bound_ctrl:1
	v_xor_b32_e32 v205, v189, v199
	v_add_f32_dpp v201, v220, v201 quad_perm:[1,0,3,2] row_mask:0xf bank_mask:0xf bound_ctrl:1
	v_xor_b32_e32 v203, v181, v202
	v_add_f32_dpp v199, v199, v205 quad_perm:[2,3,0,1] row_mask:0xf bank_mask:0xf bound_ctrl:1
	v_xor_b32_e32 v205, v189, v200
	v_pk_add_f32 v[208:209], v[208:209], v[208:209] op_sel:[0,1] op_sel_hi:[1,0] neg_lo:[0,1] neg_hi:[0,1]
	v_add_f32_dpp v202, v202, v203 quad_perm:[1,0,3,2] row_mask:0xf bank_mask:0xf bound_ctrl:1
	v_xor_b32_e32 v203, v181, v140
	v_add_f32_dpp v200, v200, v205 quad_perm:[2,3,0,1] row_mask:0xf bank_mask:0xf bound_ctrl:1
	v_xor_b32_e32 v205, v189, v201
	v_add_f32_dpp v140, v140, v203 quad_perm:[1,0,3,2] row_mask:0xf bank_mask:0xf bound_ctrl:1
	v_xor_b32_e32 v203, v181, v208
	v_add_f32_dpp v201, v201, v205 quad_perm:[2,3,0,1] row_mask:0xf bank_mask:0xf bound_ctrl:1
	v_xor_b32_e32 v205, v189, v202
	v_add_f32_dpp v203, v208, v203 quad_perm:[1,0,3,2] row_mask:0xf bank_mask:0xf bound_ctrl:1
	v_xor_b32_e32 v204, v181, v142
	v_add_f32_dpp v202, v202, v205 quad_perm:[2,3,0,1] row_mask:0xf bank_mask:0xf bound_ctrl:1
	v_xor_b32_e32 v205, v189, v140
	v_add_f32_dpp v142, v142, v204 quad_perm:[1,0,3,2] row_mask:0xf bank_mask:0xf bound_ctrl:1
	v_xor_b32_e32 v204, v181, v144
	v_add_f32_dpp v205, v140, v205 quad_perm:[2,3,0,1] row_mask:0xf bank_mask:0xf bound_ctrl:1
	v_xor_b32_e32 v140, v189, v203
	v_pk_add_f32 v[212:213], v[212:213], v[212:213] op_sel:[0,1] op_sel_hi:[1,0] neg_lo:[0,1] neg_hi:[0,1]
	v_add_f32_dpp v144, v144, v204 quad_perm:[1,0,3,2] row_mask:0xf bank_mask:0xf bound_ctrl:1
	v_xor_b32_e32 v204, v181, v138
	v_add_f32_dpp v203, v203, v140 quad_perm:[2,3,0,1] row_mask:0xf bank_mask:0xf bound_ctrl:1
	v_xor_b32_e32 v140, v189, v142
	v_add_f32_dpp v138, v138, v204 quad_perm:[1,0,3,2] row_mask:0xf bank_mask:0xf bound_ctrl:1
	v_xor_b32_e32 v204, v181, v212
	v_add_f32_dpp v206, v142, v140 quad_perm:[2,3,0,1] row_mask:0xf bank_mask:0xf bound_ctrl:1
	v_xor_b32_e32 v140, v189, v144
	v_add_f32_dpp v204, v212, v204 quad_perm:[1,0,3,2] row_mask:0xf bank_mask:0xf bound_ctrl:1
	v_max_f32_e64 v142, |v200|, |v201|
	v_add_f32_dpp v144, v144, v140 quad_perm:[2,3,0,1] row_mask:0xf bank_mask:0xf bound_ctrl:1
	v_xor_b32_e32 v140, v189, v138
	s_nop 1
	v_add_f32_dpp v207, v138, v140 quad_perm:[2,3,0,1] row_mask:0xf bank_mask:0xf bound_ctrl:1
	v_xor_b32_e32 v138, v189, v204
	v_max_f32_e64 v140, |v143|, |v145|
	s_nop 0
	v_add_f32_dpp v204, v204, v138 quad_perm:[2,3,0,1] row_mask:0xf bank_mask:0xf bound_ctrl:1
	v_xor_b32_e32 v138, v189, v186
	s_nop 1
	v_add_f32_dpp v186, v186, v138 quad_perm:[2,3,0,1] row_mask:0xf bank_mask:0xf bound_ctrl:1
	v_max_f32_e64 v138, |v139|, |v141|
	v_max3_f32 v138, v222, v138, v140
	v_max_f32_e64 v140, |v187|, |v199|
	v_max3_f32 v138, v138, v140, v142
	v_max_f32_e64 v140, |v202|, |v205|
	v_max_f32_e64 v142, |v203|, |v206|
	v_max3_f32 v138, v138, v140, v142
	v_max_f32_e64 v140, |v144|, |v207|
	v_max_f32_e64 v142, |v204|, |v186|
	v_max3_f32 v222, v138, v140, v142
	v_cvt_pk_bf16_f32 v138, v139, v141
	v_cvt_pk_bf16_f32 v139, v143, v145
	v_cvt_pk_bf16_f32 v140, v187, v199
	v_cvt_pk_bf16_f32 v141, v200, v201
	v_cvt_pk_bf16_f32 v142, v202, v205
	v_cvt_pk_bf16_f32 v143, v203, v206
	v_cvt_pk_bf16_f32 v144, v144, v207
	v_cvt_pk_bf16_f32 v145, v204, v186
	v_and_b32_e32 v187, 0xffff0000, v177
	v_and_b32_e32 v186, 0xffff0000, v173
	v_lshlrev_b32_e32 v201, 16, v174
	v_lshlrev_b32_e32 v200, 16, v170
	v_and_b32_e32 v203, 0xffff0000, v174
	v_and_b32_e32 v202, 0xffff0000, v170
	v_lshlrev_b32_e32 v204, 16, v171
	v_lshlrev_b32_e32 v205, 16, v175
	v_and_b32_e32 v175, 0xffff0000, v175
	v_and_b32_e32 v174, 0xffff0000, v171
	v_lshlrev_b32_e32 v171, 16, v176
	v_lshlrev_b32_e32 v170, 16, v172
	v_and_b32_e32 v207, 0xffff0000, v176
	v_and_b32_e32 v206, 0xffff0000, v172
	v_lshlrev_b32_e32 v172, 16, v173
	v_lshlrev_b32_e32 v173, 16, v177
	v_pk_add_f32 v[176:177], v[200:201], v[202:203]
	v_pk_add_f32 v[208:209], v[204:205], v[174:175]
	v_pk_add_f32 v[210:211], v[170:171], v[206:207]
	v_pk_add_f32 v[212:213], v[172:173], v[186:187]
	v_pk_add_f32 v[200:201], v[200:201], v[202:203] neg_lo:[0,1] neg_hi:[0,1]
	v_pk_add_f32 v[174:175], v[204:205], v[174:175] neg_lo:[0,1] neg_hi:[0,1]
	v_pk_add_f32 v[170:171], v[170:171], v[206:207] neg_lo:[0,1] neg_hi:[0,1]
	v_pk_add_f32 v[172:173], v[172:173], v[186:187] neg_lo:[0,1] neg_hi:[0,1]
	v_pk_add_f32 v[214:215], v[176:177], v[208:209] neg_lo:[0,1] neg_hi:[0,1]
	v_pk_add_f32 v[176:177], v[176:177], v[208:209]
	v_pk_add_f32 v[208:209], v[210:211], v[212:213]
	v_pk_add_f32 v[186:187], v[200:201], v[174:175] neg_lo:[0,1] neg_hi:[0,1]
	v_pk_add_f32 v[202:203], v[170:171], v[172:173] neg_lo:[0,1] neg_hi:[0,1]
	v_pk_add_f32 v[174:175], v[200:201], v[174:175]
	v_pk_add_f32 v[170:171], v[170:171], v[172:173]
	v_pk_add_f32 v[216:217], v[210:211], v[212:213] neg_lo:[0,1] neg_hi:[0,1]
	v_pk_add_f32 v[210:211], v[176:177], v[208:209]
	v_pk_add_f32 v[172:173], v[174:175], v[170:171]
	v_pk_add_f32 v[170:171], v[174:175], v[170:171] neg_lo:[0,1] neg_hi:[0,1]
	v_pk_add_f32 v[176:177], v[176:177], v[208:209] neg_lo:[0,1] neg_hi:[0,1]
	v_pk_add_f32 v[208:209], v[214:215], v[216:217]
	v_pk_add_f32 v[212:213], v[214:215], v[216:217] neg_lo:[0,1] neg_hi:[0,1]
	v_pk_add_f32 v[174:175], v[186:187], v[202:203]
	v_pk_add_f32 v[186:187], v[186:187], v[202:203] neg_lo:[0,1] neg_hi:[0,1]
	v_pk_add_f32 v[200:201], v[210:211], v[210:211] op_sel:[1,0] op_sel_hi:[0,1]
	v_pk_add_f32 v[216:217], v[170:171], v[170:171] op_sel:[1,0] op_sel_hi:[0,1]
	v_pk_add_f32 v[170:171], v[170:171], v[170:171] op_sel:[0,1] op_sel_hi:[1,0] neg_lo:[0,1] neg_hi:[0,1]
	v_pk_add_f32 v[204:205], v[172:173], v[172:173] op_sel:[1,0] op_sel_hi:[0,1]
	v_pk_add_f32 v[172:173], v[172:173], v[172:173] op_sel:[0,1] op_sel_hi:[1,0] neg_lo:[0,1] neg_hi:[0,1]
	v_pk_add_f32 v[220:221], v[186:187], v[186:187] op_sel:[1,0] op_sel_hi:[0,1]
	v_pk_add_f32 v[186:187], v[186:187], v[186:187] op_sel:[0,1] op_sel_hi:[1,0] neg_lo:[0,1] neg_hi:[0,1]
	v_xor_b32_e32 v171, v181, v200
	v_pk_add_f32 v[202:203], v[210:211], v[210:211] op_sel:[0,1] op_sel_hi:[1,0] neg_lo:[0,1] neg_hi:[0,1]
	v_pk_add_f32 v[206:207], v[208:209], v[208:209] op_sel:[1,0] op_sel_hi:[0,1]
	v_pk_add_f32 v[210:211], v[174:175], v[174:175] op_sel:[1,0] op_sel_hi:[0,1]
	v_pk_add_f32 v[174:175], v[174:175], v[174:175] op_sel:[0,1] op_sel_hi:[1,0] neg_lo:[0,1] neg_hi:[0,1]
	v_pk_add_f32 v[214:215], v[176:177], v[176:177] op_sel:[1,0] op_sel_hi:[0,1]
	v_add_f32_dpp v171, v200, v171 quad_perm:[1,0,3,2] row_mask:0xf bank_mask:0xf bound_ctrl:1
	v_xor_b32_e32 v173, v181, v204
	v_xor_b32_e32 v205, v181, v186
	v_pk_add_f32 v[176:177], v[176:177], v[176:177] op_sel:[0,1] op_sel_hi:[1,0] neg_lo:[0,1] neg_hi:[0,1]
	v_add_f32_dpp v173, v204, v173 quad_perm:[1,0,3,2] row_mask:0xf bank_mask:0xf bound_ctrl:1
	v_xor_b32_e32 v175, v181, v206
	v_xor_b32_e32 v187, v181, v214
	v_add_f32_dpp v186, v186, v205 quad_perm:[1,0,3,2] row_mask:0xf bank_mask:0xf bound_ctrl:1
	v_xor_b32_e32 v205, v189, v171
	v_add_f32_dpp v175, v206, v175 quad_perm:[1,0,3,2] row_mask:0xf bank_mask:0xf bound_ctrl:1
	v_xor_b32_e32 v177, v181, v210
	v_add_f32_dpp v187, v214, v187 quad_perm:[1,0,3,2] row_mask:0xf bank_mask:0xf bound_ctrl:1
	v_add_f32_dpp v214, v171, v205 quad_perm:[2,3,0,1] row_mask:0xf bank_mask:0xf bound_ctrl:1
	v_xor_b32_e32 v171, v189, v173
	v_add_f32_dpp v177, v210, v177 quad_perm:[1,0,3,2] row_mask:0xf bank_mask:0xf bound_ctrl:1
	v_xor_b32_e32 v199, v181, v216
	v_add_f32_dpp v215, v173, v171 quad_perm:[2,3,0,1] row_mask:0xf bank_mask:0xf bound_ctrl:1
	v_xor_b32_e32 v171, v189, v175
	v_pk_add_f32 v[218:219], v[212:213], v[212:213] op_sel:[1,0] op_sel_hi:[0,1]
	v_add_f32_dpp v199, v216, v199 quad_perm:[1,0,3,2] row_mask:0xf bank_mask:0xf bound_ctrl:1
	v_add_f32_dpp v216, v175, v171 quad_perm:[2,3,0,1] row_mask:0xf bank_mask:0xf bound_ctrl:1
	v_xor_b32_e32 v171, v189, v177
	v_xor_b32_e32 v200, v181, v218
	v_xor_b32_e32 v201, v181, v220
	v_add_f32_dpp v217, v177, v171 quad_perm:[2,3,0,1] row_mask:0xf bank_mask:0xf bound_ctrl:1
	v_xor_b32_e32 v171, v189, v187
	v_add_f32_dpp v200, v218, v200 quad_perm:[1,0,3,2] row_mask:0xf bank_mask:0xf bound_ctrl:1
	v_add_f32_dpp v201, v220, v201 quad_perm:[1,0,3,2] row_mask:0xf bank_mask:0xf bound_ctrl:1
	v_add_f32_dpp v218, v187, v171 quad_perm:[2,3,0,1] row_mask:0xf bank_mask:0xf bound_ctrl:1
	v_xor_b32_e32 v171, v189, v199
	v_xor_b32_e32 v203, v181, v202
	v_pk_add_f32 v[208:209], v[208:209], v[208:209] op_sel:[0,1] op_sel_hi:[1,0] neg_lo:[0,1] neg_hi:[0,1]
	v_add_f32_dpp v199, v199, v171 quad_perm:[2,3,0,1] row_mask:0xf bank_mask:0xf bound_ctrl:1
	v_xor_b32_e32 v171, v189, v200
	v_add_f32_dpp v202, v202, v203 quad_perm:[1,0,3,2] row_mask:0xf bank_mask:0xf bound_ctrl:1
	v_xor_b32_e32 v203, v181, v172
	v_add_f32_dpp v219, v200, v171 quad_perm:[2,3,0,1] row_mask:0xf bank_mask:0xf bound_ctrl:1
	v_xor_b32_e32 v171, v189, v201
	v_add_f32_dpp v172, v172, v203 quad_perm:[1,0,3,2] row_mask:0xf bank_mask:0xf bound_ctrl:1
	v_xor_b32_e32 v203, v181, v208
	v_add_f32_dpp v220, v201, v171 quad_perm:[2,3,0,1] row_mask:0xf bank_mask:0xf bound_ctrl:1
	v_xor_b32_e32 v171, v189, v202
	v_add_f32_dpp v203, v208, v203 quad_perm:[1,0,3,2] row_mask:0xf bank_mask:0xf bound_ctrl:1
	v_xor_b32_e32 v204, v181, v174
	v_add_f32_dpp v221, v202, v171 quad_perm:[2,3,0,1] row_mask:0xf bank_mask:0xf bound_ctrl:1
	v_xor_b32_e32 v171, v189, v172
	v_add_f32_dpp v174, v174, v204 quad_perm:[1,0,3,2] row_mask:0xf bank_mask:0xf bound_ctrl:1
	v_xor_b32_e32 v204, v181, v176
	v_add_f32_dpp v223, v172, v171 quad_perm:[2,3,0,1] row_mask:0xf bank_mask:0xf bound_ctrl:1
	v_xor_b32_e32 v171, v189, v203
	v_pk_add_f32 v[212:213], v[212:213], v[212:213] op_sel:[0,1] op_sel_hi:[1,0] neg_lo:[0,1] neg_hi:[0,1]
	v_add_f32_dpp v176, v176, v204 quad_perm:[1,0,3,2] row_mask:0xf bank_mask:0xf bound_ctrl:1
	v_xor_b32_e32 v204, v181, v170
	v_add_f32_dpp v224, v203, v171 quad_perm:[2,3,0,1] row_mask:0xf bank_mask:0xf bound_ctrl:1
	v_xor_b32_e32 v171, v189, v174
	v_add_f32_dpp v170, v170, v204 quad_perm:[1,0,3,2] row_mask:0xf bank_mask:0xf bound_ctrl:1
	v_xor_b32_e32 v204, v181, v212
	v_add_f32_dpp v225, v174, v171 quad_perm:[2,3,0,1] row_mask:0xf bank_mask:0xf bound_ctrl:1
	v_xor_b32_e32 v171, v189, v176
	v_add_f32_dpp v204, v212, v204 quad_perm:[1,0,3,2] row_mask:0xf bank_mask:0xf bound_ctrl:1
	v_max_f32_e64 v172, |v219|, |v220|
	v_add_f32_dpp v226, v176, v171 quad_perm:[2,3,0,1] row_mask:0xf bank_mask:0xf bound_ctrl:1
	v_xor_b32_e32 v171, v189, v170
	v_lshlrev_b32_e32 v173, 16, v166
	v_and_b32_e32 v175, 0xffff0000, v166
	v_add_f32_dpp v227, v170, v171 quad_perm:[2,3,0,1] row_mask:0xf bank_mask:0xf bound_ctrl:1
	v_xor_b32_e32 v170, v189, v204
	v_max_f32_e64 v171, |v216|, |v217|
	v_and_b32_e32 v174, 0xffff0000, v162
	v_add_f32_dpp v228, v204, v170 quad_perm:[2,3,0,1] row_mask:0xf bank_mask:0xf bound_ctrl:1
	v_xor_b32_e32 v170, v189, v186
	v_lshlrev_b32_e32 v176, 16, v163
	v_lshlrev_b32_e32 v177, 16, v167
	v_add_f32_dpp v229, v186, v170 quad_perm:[2,3,0,1] row_mask:0xf bank_mask:0xf bound_ctrl:1
	v_max_f32_e64 v170, |v214|, |v215|
	v_max3_f32 v170, v222, v170, v171
	v_max_f32_e64 v171, |v218|, |v199|
	v_max3_f32 v170, v170, v171, v172
	v_max_f32_e64 v171, |v221|, |v223|
	v_max_f32_e64 v172, |v224|, |v225|
	v_max3_f32 v170, v170, v171, v172
	v_max_f32_e64 v171, |v226|, |v227|
	v_max_f32_e64 v172, |v228|, |v229|
	v_max3_f32 v222, v170, v171, v172
	v_and_b32_e32 v171, 0xffff0000, v169
	v_and_b32_e32 v170, 0xffff0000, v165
	v_lshlrev_b32_e32 v172, 16, v162
	v_and_b32_e32 v167, 0xffff0000, v167
	v_and_b32_e32 v166, 0xffff0000, v163
	v_lshlrev_b32_e32 v163, 16, v168
	v_lshlrev_b32_e32 v162, 16, v164
	v_and_b32_e32 v187, 0xffff0000, v168
	v_and_b32_e32 v186, 0xffff0000, v164
	v_lshlrev_b32_e32 v164, 16, v165
	v_lshlrev_b32_e32 v165, 16, v169
	v_pk_add_f32 v[168:169], v[172:173], v[174:175]
	v_pk_add_f32 v[200:201], v[176:177], v[166:167]
	v_pk_add_f32 v[202:203], v[162:163], v[186:187]
	v_pk_add_f32 v[204:205], v[164:165], v[170:171]
	v_pk_add_f32 v[172:173], v[172:173], v[174:175] neg_lo:[0,1] neg_hi:[0,1]
	v_pk_add_f32 v[166:167], v[176:177], v[166:167] neg_lo:[0,1] neg_hi:[0,1]
	v_pk_add_f32 v[162:163], v[162:163], v[186:187] neg_lo:[0,1] neg_hi:[0,1]
	v_pk_add_f32 v[164:165], v[164:165], v[170:171] neg_lo:[0,1] neg_hi:[0,1]
	v_pk_add_f32 v[206:207], v[168:169], v[200:201] neg_lo:[0,1] neg_hi:[0,1]
	v_pk_add_f32 v[208:209], v[202:203], v[204:205] neg_lo:[0,1] neg_hi:[0,1]
	v_pk_add_f32 v[168:169], v[168:169], v[200:201]
	v_pk_add_f32 v[200:201], v[202:203], v[204:205]
	v_pk_add_f32 v[170:171], v[172:173], v[166:167] neg_lo:[0,1] neg_hi:[0,1]
	v_pk_add_f32 v[174:175], v[162:163], v[164:165] neg_lo:[0,1] neg_hi:[0,1]
	v_pk_add_f32 v[166:167], v[172:173], v[166:167]
	v_pk_add_f32 v[162:163], v[162:163], v[164:165]
	v_pk_add_f32 v[202:203], v[168:169], v[200:201]
	v_pk_add_f32 v[168:169], v[168:169], v[200:201] neg_lo:[0,1] neg_hi:[0,1]
	v_pk_add_f32 v[200:201], v[206:207], v[208:209]
	v_pk_add_f32 v[164:165], v[166:167], v[162:163]
	v_pk_add_f32 v[162:163], v[166:167], v[162:163] neg_lo:[0,1] neg_hi:[0,1]
	v_pk_add_f32 v[166:167], v[170:171], v[174:175]
	v_pk_add_f32 v[204:205], v[206:207], v[208:209] neg_lo:[0,1] neg_hi:[0,1]
	v_pk_add_f32 v[170:171], v[170:171], v[174:175] neg_lo:[0,1] neg_hi:[0,1]
	v_pk_add_f32 v[172:173], v[202:203], v[202:203] op_sel:[1,0] op_sel_hi:[0,1]
	v_pk_add_f32 v[174:175], v[202:203], v[202:203] op_sel:[0,1] op_sel_hi:[1,0] neg_lo:[0,1] neg_hi:[0,1]
	v_pk_add_f32 v[186:187], v[200:201], v[200:201] op_sel:[1,0] op_sel_hi:[0,1]
	v_pk_add_f32 v[202:203], v[166:167], v[166:167] op_sel:[1,0] op_sel_hi:[0,1]
	v_pk_add_f32 v[166:167], v[166:167], v[166:167] op_sel:[0,1] op_sel_hi:[1,0] neg_lo:[0,1] neg_hi:[0,1]
	v_pk_add_f32 v[208:209], v[162:163], v[162:163] op_sel:[1,0] op_sel_hi:[0,1]
	v_pk_add_f32 v[162:163], v[162:163], v[162:163] op_sel:[0,1] op_sel_hi:[1,0] neg_lo:[0,1] neg_hi:[0,1]
	v_pk_add_f32 v[176:177], v[164:165], v[164:165] op_sel:[1,0] op_sel_hi:[0,1]
	v_pk_add_f32 v[164:165], v[164:165], v[164:165] op_sel:[0,1] op_sel_hi:[1,0] neg_lo:[0,1] neg_hi:[0,1]
	v_pk_add_f32 v[212:213], v[170:171], v[170:171] op_sel:[1,0] op_sel_hi:[0,1]
	v_pk_add_f32 v[170:171], v[170:171], v[170:171] op_sel:[0,1] op_sel_hi:[1,0] neg_lo:[0,1] neg_hi:[0,1]
	v_xor_b32_e32 v163, v181, v172
	v_xor_b32_e32 v167, v181, v186
	v_pk_add_f32 v[206:207], v[168:169], v[168:169] op_sel:[1,0] op_sel_hi:[0,1]
	v_add_f32_dpp v163, v172, v163 quad_perm:[1,0,3,2] row_mask:0xf bank_mask:0xf bound_ctrl:1
	v_xor_b32_e32 v165, v181, v176
	v_add_f32_dpp v167, v186, v167 quad_perm:[1,0,3,2] row_mask:0xf bank_mask:0xf bound_ctrl:1
	v_xor_b32_e32 v186, v181, v170
	v_pk_add_f32 v[168:169], v[168:169], v[168:169] op_sel:[0,1] op_sel_hi:[1,0] neg_lo:[0,1] neg_hi:[0,1]
	v_add_f32_dpp v165, v176, v165 quad_perm:[1,0,3,2] row_mask:0xf bank_mask:0xf bound_ctrl:1
	v_xor_b32_e32 v171, v181, v206
	v_add_f32_dpp v170, v170, v186 quad_perm:[1,0,3,2] row_mask:0xf bank_mask:0xf bound_ctrl:1
	v_xor_b32_e32 v186, v189, v163
	v_xor_b32_e32 v169, v181, v202
	v_add_f32_dpp v171, v206, v171 quad_perm:[1,0,3,2] row_mask:0xf bank_mask:0xf bound_ctrl:1
	v_add_f32_dpp v206, v163, v186 quad_perm:[2,3,0,1] row_mask:0xf bank_mask:0xf bound_ctrl:1
	v_xor_b32_e32 v163, v189, v165
	v_add_f32_dpp v169, v202, v169 quad_perm:[1,0,3,2] row_mask:0xf bank_mask:0xf bound_ctrl:1
	v_xor_b32_e32 v172, v181, v208
	v_add_f32_dpp v207, v165, v163 quad_perm:[2,3,0,1] row_mask:0xf bank_mask:0xf bound_ctrl:1
	v_xor_b32_e32 v163, v189, v167
	v_pk_add_f32 v[210:211], v[204:205], v[204:205] op_sel:[1,0] op_sel_hi:[0,1]
	v_add_f32_dpp v172, v208, v172 quad_perm:[1,0,3,2] row_mask:0xf bank_mask:0xf bound_ctrl:1
	v_add_f32_dpp v208, v167, v163 quad_perm:[2,3,0,1] row_mask:0xf bank_mask:0xf bound_ctrl:1
	v_xor_b32_e32 v163, v189, v169
	v_xor_b32_e32 v173, v181, v210
	v_xor_b32_e32 v175, v181, v212
	v_add_f32_dpp v209, v169, v163 quad_perm:[2,3,0,1] row_mask:0xf bank_mask:0xf bound_ctrl:1
	v_xor_b32_e32 v163, v189, v171
	v_add_f32_dpp v173, v210, v173 quad_perm:[1,0,3,2] row_mask:0xf bank_mask:0xf bound_ctrl:1
	v_add_f32_dpp v175, v212, v175 quad_perm:[1,0,3,2] row_mask:0xf bank_mask:0xf bound_ctrl:1
	v_add_f32_dpp v210, v171, v163 quad_perm:[2,3,0,1] row_mask:0xf bank_mask:0xf bound_ctrl:1
	v_xor_b32_e32 v163, v189, v172
	v_xor_b32_e32 v176, v181, v174
	v_pk_add_f32 v[200:201], v[200:201], v[200:201] op_sel:[0,1] op_sel_hi:[1,0] neg_lo:[0,1] neg_hi:[0,1]
	v_add_f32_dpp v211, v172, v163 quad_perm:[2,3,0,1] row_mask:0xf bank_mask:0xf bound_ctrl:1
	v_xor_b32_e32 v163, v189, v173
	v_add_f32_dpp v174, v174, v176 quad_perm:[1,0,3,2] row_mask:0xf bank_mask:0xf bound_ctrl:1
	v_xor_b32_e32 v176, v181, v164
	v_add_f32_dpp v212, v173, v163 quad_perm:[2,3,0,1] row_mask:0xf bank_mask:0xf bound_ctrl:1
	v_xor_b32_e32 v163, v189, v175
	v_add_f32_dpp v164, v164, v176 quad_perm:[1,0,3,2] row_mask:0xf bank_mask:0xf bound_ctrl:1
	v_xor_b32_e32 v176, v181, v200
	v_add_f32_dpp v213, v175, v163 quad_perm:[2,3,0,1] row_mask:0xf bank_mask:0xf bound_ctrl:1
	v_xor_b32_e32 v163, v189, v174
	v_add_f32_dpp v176, v200, v176 quad_perm:[1,0,3,2] row_mask:0xf bank_mask:0xf bound_ctrl:1
	v_xor_b32_e32 v177, v181, v166
	v_add_f32_dpp v230, v174, v163 quad_perm:[2,3,0,1] row_mask:0xf bank_mask:0xf bound_ctrl:1
	v_xor_b32_e32 v163, v189, v164
	v_add_f32_dpp v166, v166, v177 quad_perm:[1,0,3,2] row_mask:0xf bank_mask:0xf bound_ctrl:1
	v_xor_b32_e32 v177, v181, v168
	v_add_f32_dpp v231, v164, v163 quad_perm:[2,3,0,1] row_mask:0xf bank_mask:0xf bound_ctrl:1
	v_xor_b32_e32 v163, v189, v176
	v_pk_add_f32 v[204:205], v[204:205], v[204:205] op_sel:[0,1] op_sel_hi:[1,0] neg_lo:[0,1] neg_hi:[0,1]
	v_add_f32_dpp v168, v168, v177 quad_perm:[1,0,3,2] row_mask:0xf bank_mask:0xf bound_ctrl:1
	v_xor_b32_e32 v177, v181, v162
	v_add_f32_dpp v232, v176, v163 quad_perm:[2,3,0,1] row_mask:0xf bank_mask:0xf bound_ctrl:1
	v_xor_b32_e32 v163, v189, v166
	v_add_f32_dpp v162, v162, v177 quad_perm:[1,0,3,2] row_mask:0xf bank_mask:0xf bound_ctrl:1
	v_xor_b32_e32 v177, v181, v204
	v_add_f32_dpp v233, v166, v163 quad_perm:[2,3,0,1] row_mask:0xf bank_mask:0xf bound_ctrl:1
	v_xor_b32_e32 v163, v189, v168
	v_add_f32_dpp v177, v204, v177 quad_perm:[1,0,3,2] row_mask:0xf bank_mask:0xf bound_ctrl:1
	v_max_f32_e64 v164, |v212|, |v213|
	v_add_f32_dpp v235, v168, v163 quad_perm:[2,3,0,1] row_mask:0xf bank_mask:0xf bound_ctrl:1
	v_xor_b32_e32 v163, v189, v162
	v_lshlrev_b32_e32 v165, 16, v158
	v_and_b32_e32 v167, 0xffff0000, v158
	v_add_f32_dpp v236, v162, v163 quad_perm:[2,3,0,1] row_mask:0xf bank_mask:0xf bound_ctrl:1
	v_xor_b32_e32 v162, v189, v177
	v_max_f32_e64 v163, |v208|, |v209|
	v_and_b32_e32 v166, 0xffff0000, v150
	v_add_f32_dpp v237, v177, v162 quad_perm:[2,3,0,1] row_mask:0xf bank_mask:0xf bound_ctrl:1
	v_xor_b32_e32 v162, v189, v170
	v_lshlrev_b32_e32 v168, 16, v151
	v_lshlrev_b32_e32 v169, 16, v159
	v_add_f32_dpp v238, v170, v162 quad_perm:[2,3,0,1] row_mask:0xf bank_mask:0xf bound_ctrl:1
	v_max_f32_e64 v162, |v206|, |v207|
	v_max3_f32 v162, v222, v162, v163
	v_max_f32_e64 v163, |v210|, |v211|
	v_max3_f32 v162, v162, v163, v164
	v_max_f32_e64 v163, |v230|, |v231|
	v_max_f32_e64 v164, |v232|, |v233|
	v_max3_f32 v162, v162, v163, v164
	v_max_f32_e64 v163, |v235|, |v236|
	v_max_f32_e64 v164, |v237|, |v238|
	v_max3_f32 v222, v162, v163, v164
	v_and_b32_e32 v163, 0xffff0000, v161
	v_and_b32_e32 v162, 0xffff0000, v153
	v_lshlrev_b32_e32 v164, 16, v150
	v_and_b32_e32 v159, 0xffff0000, v159
	v_and_b32_e32 v158, 0xffff0000, v151
	v_lshlrev_b32_e32 v151, 16, v160
	v_lshlrev_b32_e32 v150, 16, v152
	v_and_b32_e32 v171, 0xffff0000, v160
	v_and_b32_e32 v170, 0xffff0000, v152
	v_lshlrev_b32_e32 v152, 16, v153
	v_lshlrev_b32_e32 v153, 16, v161
	v_pk_add_f32 v[160:161], v[164:165], v[166:167]
	v_pk_add_f32 v[172:173], v[168:169], v[158:159]
	v_pk_add_f32 v[174:175], v[150:151], v[170:171]
	v_pk_add_f32 v[176:177], v[152:153], v[162:163]
	v_pk_add_f32 v[164:165], v[164:165], v[166:167] neg_lo:[0,1] neg_hi:[0,1]
	v_pk_add_f32 v[158:159], v[168:169], v[158:159] neg_lo:[0,1] neg_hi:[0,1]
	v_pk_add_f32 v[150:151], v[150:151], v[170:171] neg_lo:[0,1] neg_hi:[0,1]
	v_pk_add_f32 v[152:153], v[152:153], v[162:163] neg_lo:[0,1] neg_hi:[0,1]
	v_pk_add_f32 v[186:187], v[160:161], v[172:173] neg_lo:[0,1] neg_hi:[0,1]
	v_pk_add_f32 v[200:201], v[174:175], v[176:177] neg_lo:[0,1] neg_hi:[0,1]
	v_pk_add_f32 v[160:161], v[160:161], v[172:173]
	v_pk_add_f32 v[172:173], v[174:175], v[176:177]
	v_pk_add_f32 v[162:163], v[164:165], v[158:159] neg_lo:[0,1] neg_hi:[0,1]
	v_pk_add_f32 v[166:167], v[150:151], v[152:153] neg_lo:[0,1] neg_hi:[0,1]
	v_pk_add_f32 v[158:159], v[164:165], v[158:159]
	v_pk_add_f32 v[150:151], v[150:151], v[152:153]
	v_pk_add_f32 v[174:175], v[160:161], v[172:173]
	v_pk_add_f32 v[160:161], v[160:161], v[172:173] neg_lo:[0,1] neg_hi:[0,1]
	v_pk_add_f32 v[172:173], v[186:187], v[200:201]
	v_pk_add_f32 v[152:153], v[158:159], v[150:151]
	v_pk_add_f32 v[150:151], v[158:159], v[150:151] neg_lo:[0,1] neg_hi:[0,1]
	v_pk_add_f32 v[158:159], v[162:163], v[166:167]
	v_pk_add_f32 v[176:177], v[186:187], v[200:201] neg_lo:[0,1] neg_hi:[0,1]
	v_pk_add_f32 v[162:163], v[162:163], v[166:167] neg_lo:[0,1] neg_hi:[0,1]
	v_pk_add_f32 v[164:165], v[174:175], v[174:175] op_sel:[1,0] op_sel_hi:[0,1]
	v_pk_add_f32 v[166:167], v[174:175], v[174:175] op_sel:[0,1] op_sel_hi:[1,0] neg_lo:[0,1] neg_hi:[0,1]
	v_pk_add_f32 v[170:171], v[172:173], v[172:173] op_sel:[1,0] op_sel_hi:[0,1]
	v_pk_add_f32 v[174:175], v[158:159], v[158:159] op_sel:[1,0] op_sel_hi:[0,1]
	v_pk_add_f32 v[158:159], v[158:159], v[158:159] op_sel:[0,1] op_sel_hi:[1,0] neg_lo:[0,1] neg_hi:[0,1]
	v_pk_add_f32 v[200:201], v[150:151], v[150:151] op_sel:[1,0] op_sel_hi:[0,1]
	v_pk_add_f32 v[150:151], v[150:151], v[150:151] op_sel:[0,1] op_sel_hi:[1,0] neg_lo:[0,1] neg_hi:[0,1]
	v_pk_add_f32 v[168:169], v[152:153], v[152:153] op_sel:[1,0] op_sel_hi:[0,1]
	v_pk_add_f32 v[152:153], v[152:153], v[152:153] op_sel:[0,1] op_sel_hi:[1,0] neg_lo:[0,1] neg_hi:[0,1]
	v_pk_add_f32 v[204:205], v[162:163], v[162:163] op_sel:[1,0] op_sel_hi:[0,1]
	v_pk_add_f32 v[162:163], v[162:163], v[162:163] op_sel:[0,1] op_sel_hi:[1,0] neg_lo:[0,1] neg_hi:[0,1]
	v_xor_b32_e32 v151, v181, v164
	v_xor_b32_e32 v159, v181, v170
	v_xor_b32_e32 v153, v181, v168
	v_add_f32_dpp v151, v164, v151 quad_perm:[1,0,3,2] row_mask:0xf bank_mask:0xf bound_ctrl:1
	v_add_f32_dpp v159, v170, v159 quad_perm:[1,0,3,2] row_mask:0xf bank_mask:0xf bound_ctrl:1
	v_xor_b32_e32 v170, v181, v162
	v_pk_add_f32 v[186:187], v[160:161], v[160:161] op_sel:[1,0] op_sel_hi:[0,1]
	v_pk_add_f32 v[160:161], v[160:161], v[160:161] op_sel:[0,1] op_sel_hi:[1,0] neg_lo:[0,1] neg_hi:[0,1]
	v_add_f32_dpp v153, v168, v153 quad_perm:[1,0,3,2] row_mask:0xf bank_mask:0xf bound_ctrl:1
	v_add_f32_dpp v162, v162, v170 quad_perm:[1,0,3,2] row_mask:0xf bank_mask:0xf bound_ctrl:1
	v_xor_b32_e32 v170, v189, v151
	v_xor_b32_e32 v161, v181, v174
	v_xor_b32_e32 v163, v181, v186
	v_add_f32_dpp v151, v151, v170 quad_perm:[2,3,0,1] row_mask:0xf bank_mask:0xf bound_ctrl:1
	v_xor_b32_e32 v170, v189, v153
	v_add_f32_dpp v161, v174, v161 quad_perm:[1,0,3,2] row_mask:0xf bank_mask:0xf bound_ctrl:1
	v_pk_add_f32 v[202:203], v[176:177], v[176:177] op_sel:[1,0] op_sel_hi:[0,1]
	v_add_f32_dpp v153, v153, v170 quad_perm:[2,3,0,1] row_mask:0xf bank_mask:0xf bound_ctrl:1
	v_xor_b32_e32 v170, v189, v159
	v_add_f32_dpp v163, v186, v163 quad_perm:[1,0,3,2] row_mask:0xf bank_mask:0xf bound_ctrl:1
	v_xor_b32_e32 v164, v181, v200
	v_add_f32_dpp v159, v159, v170 quad_perm:[2,3,0,1] row_mask:0xf bank_mask:0xf bound_ctrl:1
	v_xor_b32_e32 v170, v189, v161
	v_add_f32_dpp v164, v200, v164 quad_perm:[1,0,3,2] row_mask:0xf bank_mask:0xf bound_ctrl:1
	v_xor_b32_e32 v165, v181, v202
	v_add_f32_dpp v161, v161, v170 quad_perm:[2,3,0,1] row_mask:0xf bank_mask:0xf bound_ctrl:1
	v_xor_b32_e32 v170, v189, v163
	v_add_f32_dpp v165, v202, v165 quad_perm:[1,0,3,2] row_mask:0xf bank_mask:0xf bound_ctrl:1
	v_xor_b32_e32 v167, v181, v204
	v_add_f32_dpp v186, v163, v170 quad_perm:[2,3,0,1] row_mask:0xf bank_mask:0xf bound_ctrl:1
	v_xor_b32_e32 v163, v189, v164
	v_add_f32_dpp v167, v204, v167 quad_perm:[1,0,3,2] row_mask:0xf bank_mask:0xf bound_ctrl:1
	v_xor_b32_e32 v168, v181, v166
	v_add_f32_dpp v187, v164, v163 quad_perm:[2,3,0,1] row_mask:0xf bank_mask:0xf bound_ctrl:1
	v_xor_b32_e32 v163, v189, v165
	v_pk_add_f32 v[172:173], v[172:173], v[172:173] op_sel:[0,1] op_sel_hi:[1,0] neg_lo:[0,1] neg_hi:[0,1]
	v_add_f32_dpp v166, v166, v168 quad_perm:[1,0,3,2] row_mask:0xf bank_mask:0xf bound_ctrl:1
	v_xor_b32_e32 v168, v181, v152
	v_add_f32_dpp v200, v165, v163 quad_perm:[2,3,0,1] row_mask:0xf bank_mask:0xf bound_ctrl:1
	v_xor_b32_e32 v163, v189, v167
	v_add_f32_dpp v152, v152, v168 quad_perm:[1,0,3,2] row_mask:0xf bank_mask:0xf bound_ctrl:1
	v_xor_b32_e32 v168, v181, v172
	v_add_f32_dpp v201, v167, v163 quad_perm:[2,3,0,1] row_mask:0xf bank_mask:0xf bound_ctrl:1
	v_xor_b32_e32 v163, v189, v166
	v_add_f32_dpp v168, v172, v168 quad_perm:[1,0,3,2] row_mask:0xf bank_mask:0xf bound_ctrl:1
	v_xor_b32_e32 v169, v181, v158
	v_add_f32_dpp v202, v166, v163 quad_perm:[2,3,0,1] row_mask:0xf bank_mask:0xf bound_ctrl:1
	v_xor_b32_e32 v163, v189, v152
	v_add_f32_dpp v158, v158, v169 quad_perm:[1,0,3,2] row_mask:0xf bank_mask:0xf bound_ctrl:1
	v_xor_b32_e32 v169, v181, v160
	v_add_f32_dpp v203, v152, v163 quad_perm:[2,3,0,1] row_mask:0xf bank_mask:0xf bound_ctrl:1
	v_xor_b32_e32 v152, v189, v168
	v_pk_add_f32 v[176:177], v[176:177], v[176:177] op_sel:[0,1] op_sel_hi:[1,0] neg_lo:[0,1] neg_hi:[0,1]
	v_add_f32_dpp v160, v160, v169 quad_perm:[1,0,3,2] row_mask:0xf bank_mask:0xf bound_ctrl:1
	v_xor_b32_e32 v169, v181, v150
	v_add_f32_dpp v204, v168, v152 quad_perm:[2,3,0,1] row_mask:0xf bank_mask:0xf bound_ctrl:1
	v_xor_b32_e32 v152, v189, v158
	v_add_f32_dpp v150, v150, v169 quad_perm:[1,0,3,2] row_mask:0xf bank_mask:0xf bound_ctrl:1
	v_xor_b32_e32 v169, v181, v176
	v_add_f32_dpp v205, v158, v152 quad_perm:[2,3,0,1] row_mask:0xf bank_mask:0xf bound_ctrl:1
	v_xor_b32_e32 v152, v189, v160
	v_add_f32_dpp v169, v176, v169 quad_perm:[1,0,3,2] row_mask:0xf bank_mask:0xf bound_ctrl:1
	v_max_f32_e64 v158, |v200|, |v201|
	v_add_f32_dpp v160, v160, v152 quad_perm:[2,3,0,1] row_mask:0xf bank_mask:0xf bound_ctrl:1
	v_xor_b32_e32 v152, v189, v150
	v_cvt_pk_bf16_f32 v170, v214, v215
	v_cvt_pk_bf16_f32 v171, v216, v217
	v_cvt_pk_bf16_f32 v172, v218, v199
	v_cvt_pk_bf16_f32 v173, v219, v220
	v_cvt_pk_bf16_f32 v174, v221, v223
	s_nop 1
	v_add_f32_dpp v239, v150, v152 quad_perm:[2,3,0,1] row_mask:0xf bank_mask:0xf bound_ctrl:1
	v_xor_b32_e32 v150, v189, v169
	v_max_f32_e64 v152, |v159|, |v161|
	v_cvt_pk_bf16_f32 v175, v224, v225
	v_cvt_pk_bf16_f32 v176, v226, v227
	v_cvt_pk_bf16_f32 v177, v228, v229
	s_nop 0
	v_add_f32_dpp v240, v169, v150 quad_perm:[2,3,0,1] row_mask:0xf bank_mask:0xf bound_ctrl:1
	v_xor_b32_e32 v150, v189, v162
	s_nop 1
	v_add_f32_dpp v241, v162, v150 quad_perm:[2,3,0,1] row_mask:0xf bank_mask:0xf bound_ctrl:1
	v_max_f32_e64 v150, |v151|, |v153|
	v_max3_f32 v150, v222, v150, v152
	v_max_f32_e64 v152, |v186|, |v187|
	v_max3_f32 v150, v150, v152, v158
	v_max_f32_e64 v152, |v202|, |v203|
	v_max_f32_e64 v158, |v204|, |v205|
	v_max3_f32 v150, v150, v152, v158
	v_max_f32_e64 v152, |v160|, |v239|
	v_max_f32_e64 v158, |v240|, |v241|
	v_max3_f32 v150, v150, v152, v158
	v_cvt_pk_bf16_f32 v162, v206, v207
	v_cvt_pk_bf16_f32 v163, v208, v209
	v_cvt_pk_bf16_f32 v164, v210, v211
	v_cvt_pk_bf16_f32 v165, v212, v213
	s_waitcnt lgkmcnt(0)
	s_nop 1
	v_max_f32_dpp v150, v150, v150 quad_perm:[1,0,3,2] row_mask:0xf bank_mask:0xf
	v_cvt_pk_bf16_f32 v166, v230, v231
	v_cvt_pk_bf16_f32 v167, v232, v233
	v_cvt_pk_bf16_f32 v168, v235, v236
	v_cvt_pk_bf16_f32 v169, v237, v238
	s_waitcnt lgkmcnt(0)
	s_nop 1
	v_max_f32_dpp v150, v150, v150 quad_perm:[2,3,0,1] row_mask:0xf bank_mask:0xf
	s_waitcnt lgkmcnt(0)
	s_nop 1
	v_max_f32_dpp v150, v150, v150 row_half_mirror row_mask:0xf bank_mask:0xf
	s_waitcnt lgkmcnt(0)
	s_nop 1
	v_max_f32_dpp v158, v150, v150 row_mirror row_mask:0xf bank_mask:0xf
	ds_bpermute_b32 v193, v197, v158
	v_cvt_pk_bf16_f32 v150, v151, v153
	v_cvt_pk_bf16_f32 v151, v159, v161
	v_cvt_pk_bf16_f32 v152, v186, v187
	v_cvt_pk_bf16_f32 v153, v200, v201
	s_waitcnt lgkmcnt(0)
	v_max_f32_e32 v159, v193, v193
	v_max_f32_e32 v186, v158, v159
	v_cvt_pk_bf16_f32 v158, v202, v203
	v_cvt_pk_bf16_f32 v159, v204, v205
	v_cvt_pk_bf16_f32 v160, v160, v239
	v_cvt_pk_bf16_f32 v161, v240, v241
	s_waitcnt lgkmcnt(0)
	v_mov_b32_e32 v187, v186
	s_nop 1
	v_permlane32_swap_b32_e32 v187, v186
	v_max_f32_e32 v186, v186, v187
	s_and_saveexec_b64 s[28:29], s[2:3]
	s_cbranch_execz .LBB0_1871
	s_lshl_b64 s[30:31], s[26:27], 2
	s_sub_u32 s30, s37, s30
	s_subb_u32 s31, s38, s31
	v_mul_f32_e32 v187, 0x3a810204, v186
	global_store_dword v179, v187, s[30:31]

.LBB0_2025:
	s_add_i32 s0, s42, s24
	s_cmpk_gt_i32 s0, 0x1fff
	s_mov_b64 s[0:1], -1
	s_cbranch_scc0 .LBB0_2027
	v_lshl_add_u64 v[124:125], s[16:17], 0, v[68:69]
	v_add_co_u32_e32 v0, vcc, 0x3b100000, v124
	v_and_b32_e32 v8, 64, v165
	s_nop 0
	v_addc_co_u32_e32 v1, vcc, 0, v125, vcc
	global_load_dwordx4 v[76:79], v[0:1], off
	global_load_dwordx4 v[80:83], v[0:1], off offset:1024
	global_load_dwordx4 v[84:87], v[0:1], off offset:2048
	global_load_dwordx4 v[88:91], v[0:1], off offset:3072
	v_add_co_u32_e32 v0, vcc, s20, v124
	v_xor_b32_e32 v9, 1, v165
	s_nop 0
	v_addc_co_u32_e32 v1, vcc, 0, v125, vcc
	global_load_dwordx4 v[142:145], v[0:1], off offset:3072
	global_load_dwordx4 v[92:95], v[0:1], off
	global_load_dwordx4 v[146:149], v[0:1], off offset:1024
	global_load_dwordx4 v[150:153], v[0:1], off offset:2048
	v_add_co_u32_e32 v74, vcc, s23, v124
	v_add_u32_e32 v162, 64, v8
	s_nop 0
	v_addc_co_u32_e32 v75, vcc, 0, v125, vcc
	v_cmp_lt_i32_e32 vcc, v9, v162
	global_load_dwordx4 v[0:3], v[12:13], off offset:16
	global_load_dwordx4 v[4:7], v[12:13], off
	v_cndmask_b32_e32 v96, v165, v9, vcc
	global_load_dwordx4 v[8:11], v[74:75], off offset:-4096
	v_lshlrev_b32_e32 v164, 2, v96
	s_waitcnt vmcnt(10)
	v_lshlrev_b32_e32 v138, 16, v76
	v_and_b32_e32 v139, 0xffff0000, v76
	v_lshlrev_b32_e32 v140, 16, v77
	v_and_b32_e32 v141, 0xffff0000, v77
	v_pk_mul_f32 v[158:159], v[138:139], v[138:139]
	v_pk_mul_f32 v[160:161], v[140:141], v[140:141]
	v_add_f32_e32 v158, v158, v159
	v_lshlrev_b32_e32 v126, 16, v78
	v_and_b32_e32 v127, 0xffff0000, v78
	v_add_f32_e32 v158, v160, v158
	v_pk_mul_f32 v[154:155], v[126:127], v[126:127]
	v_add_f32_e32 v158, v161, v158
	v_lshlrev_b32_e32 v132, 16, v79
	v_and_b32_e32 v133, 0xffff0000, v79
	v_add_f32_e32 v154, v154, v158
	v_pk_mul_f32 v[156:157], v[132:133], v[132:133]
	v_add_f32_e32 v154, v155, v154
	s_waitcnt vmcnt(9)
	v_lshlrev_b32_e32 v134, 16, v80
	v_and_b32_e32 v135, 0xffff0000, v80
	v_add_f32_e32 v154, v156, v154
	v_pk_mul_f32 v[170:171], v[134:135], v[134:135]
	v_add_f32_e32 v154, v157, v154
	v_lshlrev_b32_e32 v136, 16, v81
	v_and_b32_e32 v137, 0xffff0000, v81
	v_add_f32_e32 v154, v170, v154
	v_pk_mul_f32 v[172:173], v[136:137], v[136:137]
	v_add_f32_e32 v154, v171, v154
	v_lshlrev_b32_e32 v128, 16, v82
	v_and_b32_e32 v129, 0xffff0000, v82
	v_add_f32_e32 v154, v172, v154
	v_pk_mul_f32 v[166:167], v[128:129], v[128:129]
	v_add_f32_e32 v154, v173, v154
	v_lshlrev_b32_e32 v130, 16, v83
	v_and_b32_e32 v131, 0xffff0000, v83
	v_add_f32_e32 v154, v166, v154
	v_pk_mul_f32 v[168:169], v[130:131], v[130:131]
	v_add_f32_e32 v154, v167, v154
	s_waitcnt vmcnt(8)
	v_lshlrev_b32_e32 v120, 16, v84
	v_and_b32_e32 v121, 0xffff0000, v84
	v_add_f32_e32 v154, v168, v154
	v_pk_mul_f32 v[178:179], v[120:121], v[120:121]
	v_add_f32_e32 v154, v169, v154
	v_lshlrev_b32_e32 v122, 16, v85
	v_and_b32_e32 v123, 0xffff0000, v85
	v_add_f32_e32 v154, v178, v154
	v_pk_mul_f32 v[180:181], v[122:123], v[122:123]
	v_add_f32_e32 v154, v179, v154
	v_lshlrev_b32_e32 v116, 16, v86
	v_and_b32_e32 v117, 0xffff0000, v86
	v_add_f32_e32 v154, v180, v154
	v_pk_mul_f32 v[174:175], v[116:117], v[116:117]
	v_add_f32_e32 v154, v181, v154
	v_lshlrev_b32_e32 v118, 16, v87
	v_and_b32_e32 v119, 0xffff0000, v87
	v_add_f32_e32 v154, v174, v154
	v_pk_mul_f32 v[176:177], v[118:119], v[118:119]
	v_add_f32_e32 v154, v175, v154
	s_waitcnt vmcnt(7)
	v_lshlrev_b32_e32 v112, 16, v88
	v_and_b32_e32 v113, 0xffff0000, v88
	v_add_f32_e32 v154, v176, v154
	v_pk_mul_f32 v[186:187], v[112:113], v[112:113]
	v_add_f32_e32 v154, v177, v154
	v_lshlrev_b32_e32 v114, 16, v89
	v_and_b32_e32 v115, 0xffff0000, v89
	v_add_f32_e32 v154, v186, v154
	v_pk_mul_f32 v[188:189], v[114:115], v[114:115]
	v_add_f32_e32 v154, v187, v154
	v_lshlrev_b32_e32 v104, 16, v90
	v_and_b32_e32 v105, 0xffff0000, v90
	v_add_f32_e32 v154, v188, v154
	v_pk_mul_f32 v[182:183], v[104:105], v[104:105]
	v_add_f32_e32 v154, v189, v154
	v_lshlrev_b32_e32 v108, 16, v91
	v_and_b32_e32 v109, 0xffff0000, v91
	v_add_f32_e32 v154, v182, v154
	v_pk_mul_f32 v[184:185], v[108:109], v[108:109]
	v_add_f32_e32 v154, v183, v154
	s_waitcnt vmcnt(5)
	v_lshlrev_b32_e32 v106, 16, v92
	v_and_b32_e32 v107, 0xffff0000, v92
	v_add_f32_e32 v154, v184, v154
	v_pk_mul_f32 v[196:197], v[106:107], v[106:107]
	v_add_f32_e32 v154, v185, v154
	v_lshlrev_b32_e32 v110, 16, v93
	v_and_b32_e32 v111, 0xffff0000, v93
	v_add_f32_e32 v154, v196, v154
	v_pk_mul_f32 v[198:199], v[110:111], v[110:111]
	v_add_f32_e32 v154, v197, v154
	v_lshlrev_b32_e32 v100, 16, v94
	v_and_b32_e32 v101, 0xffff0000, v94
	v_add_f32_e32 v154, v198, v154
	v_pk_mul_f32 v[192:193], v[100:101], v[100:101]
	v_add_f32_e32 v154, v199, v154
	v_lshlrev_b32_e32 v102, 16, v95
	v_and_b32_e32 v103, 0xffff0000, v95
	v_add_f32_e32 v154, v192, v154
	v_pk_mul_f32 v[194:195], v[102:103], v[102:103]
	v_add_f32_e32 v154, v193, v154
	s_waitcnt vmcnt(4)
	v_lshlrev_b32_e32 v96, 16, v146
	v_and_b32_e32 v97, 0xffff0000, v146
	v_add_f32_e32 v154, v194, v154
	v_pk_mul_f32 v[202:203], v[96:97], v[96:97]
	v_add_f32_e32 v154, v195, v154
	v_lshlrev_b32_e32 v98, 16, v147
	v_and_b32_e32 v99, 0xffff0000, v147
	v_add_f32_e32 v154, v202, v154
	v_pk_mul_f32 v[146:147], v[98:99], v[98:99]
	v_add_f32_e32 v154, v203, v154
	v_lshlrev_b32_e32 v92, 16, v148
	v_and_b32_e32 v93, 0xffff0000, v148
	v_add_f32_e32 v146, v146, v154
	v_pk_mul_f32 v[200:201], v[92:93], v[92:93]
	v_add_f32_e32 v146, v147, v146
	v_lshlrev_b32_e32 v94, 16, v149
	v_and_b32_e32 v95, 0xffff0000, v149
	v_add_f32_e32 v146, v200, v146
	v_pk_mul_f32 v[148:149], v[94:95], v[94:95]
	v_add_f32_e32 v146, v201, v146
	s_waitcnt vmcnt(3)
	v_lshlrev_b32_e32 v88, 16, v150
	v_and_b32_e32 v89, 0xffff0000, v150
	v_add_f32_e32 v146, v148, v146
	v_pk_mul_f32 v[206:207], v[88:89], v[88:89]
	v_add_f32_e32 v146, v149, v146
	v_lshlrev_b32_e32 v90, 16, v151
	v_and_b32_e32 v91, 0xffff0000, v151
	v_add_f32_e32 v146, v206, v146
	v_pk_mul_f32 v[150:151], v[90:91], v[90:91]
	v_add_f32_e32 v146, v207, v146
	v_lshlrev_b32_e32 v84, 16, v152
	v_and_b32_e32 v85, 0xffff0000, v152
	v_add_f32_e32 v146, v150, v146
	v_pk_mul_f32 v[204:205], v[84:85], v[84:85]
	v_add_f32_e32 v146, v151, v146
	v_lshlrev_b32_e32 v86, 16, v153
	v_and_b32_e32 v87, 0xffff0000, v153
	v_add_f32_e32 v146, v204, v146
	v_pk_mul_f32 v[152:153], v[86:87], v[86:87]
	v_add_f32_e32 v146, v205, v146
	v_lshlrev_b32_e32 v80, 16, v142
	v_and_b32_e32 v81, 0xffff0000, v142
	v_add_f32_e32 v146, v152, v146
	v_pk_mul_f32 v[208:209], v[80:81], v[80:81]
	v_add_f32_e32 v146, v153, v146
	v_lshlrev_b32_e32 v82, 16, v143
	v_and_b32_e32 v83, 0xffff0000, v143
	v_add_f32_e32 v146, v208, v146
	v_pk_mul_f32 v[142:143], v[82:83], v[82:83]
	v_add_f32_e32 v146, v209, v146
	v_lshlrev_b32_e32 v78, 16, v144
	v_and_b32_e32 v79, 0xffff0000, v144
	v_add_f32_e32 v142, v142, v146
	v_and_b32_e32 v76, 0xffff0000, v145
	v_lshlrev_b32_e32 v77, 16, v145
	v_pk_mul_f32 v[144:145], v[78:79], v[78:79]
	v_add_f32_e32 v142, v143, v142
	v_add_f32_e32 v142, v144, v142
	v_pk_mul_f32 v[190:191], v[76:77], v[76:77]
	v_add_f32_e32 v142, v145, v142
	v_add_f32_e32 v142, v191, v142
	v_add_f32_e32 v142, v190, v142
	v_xor_b32_e32 v144, 2, v165
	v_cmp_lt_i32_e32 vcc, v144, v162
	s_waitcnt vmcnt(0)
	v_and_b32_e32 v147, 0xffff0000, v8
	v_and_b32_e32 v149, 0xffff0000, v9
	v_cndmask_b32_e32 v144, v165, v144, vcc
	v_lshlrev_b32_e32 v144, 2, v144
	s_waitcnt lgkmcnt(0)
	s_nop 1
	v_add_f32_dpp v142, v142, v142 quad_perm:[1,0,3,2] row_mask:0xf bank_mask:0xf
	v_xor_b32_e32 v144, 4, v165
	v_cmp_lt_i32_e32 vcc, v144, v162
	s_waitcnt lgkmcnt(0)
	s_nop 1
	v_add_f32_dpp v142, v142, v142 quad_perm:[2,3,0,1] row_mask:0xf bank_mask:0xf
	v_cndmask_b32_e32 v144, v165, v144, vcc
	v_lshlrev_b32_e32 v144, 2, v144
	v_xor_b32_e32 v144, 8, v165
	v_cmp_lt_i32_e32 vcc, v144, v162
	s_waitcnt lgkmcnt(0)
	s_nop 1
	v_add_f32_dpp v142, v142, v142 row_half_mirror row_mask:0xf bank_mask:0xf
	v_cndmask_b32_e32 v144, v165, v144, vcc
	v_lshlrev_b32_e32 v144, 2, v144
	v_xor_b32_e32 v144, 16, v165
	v_cmp_lt_i32_e32 vcc, v144, v162
	s_waitcnt lgkmcnt(0)
	s_nop 1
	v_add_f32_dpp v142, v142, v142 row_mirror row_mask:0xf bank_mask:0xf
	v_cndmask_b32_e32 v144, v165, v144, vcc
	v_lshlrev_b32_e32 v144, 2, v144
	v_xor_b32_e32 v144, 32, v165
	v_cmp_lt_i32_e32 vcc, v144, v162
	s_waitcnt lgkmcnt(0)
	v_mov_b32_e32 v145, v142
	v_mov_b32_e32 v143, v142
	s_nop 1
	v_permlane16_swap_b32_e32 v143, v145
	v_add_f32_e32 v145, v145, v143
	v_cndmask_b32_e32 v144, v165, v144, vcc
	v_lshlrev_b32_e32 v144, 2, v144
	v_add_co_u32_e32 v142, vcc, s21, v124
	v_lshlrev_b32_e32 v124, 16, v10
	s_nop 0
	v_addc_co_u32_e32 v143, vcc, 0, v125, vcc
	v_and_b32_e32 v125, 0xffff0000, v10
	s_waitcnt lgkmcnt(0)
	v_mov_b32_e32 v10, v145
	v_mov_b32_e32 v146, v145
	s_nop 1
	v_permlane32_swap_b32_e32 v146, v10
	v_add_f32_e32 v10, v10, v146
	v_fmamk_f32 v10, v10, 0x39800000, v65
	v_mul_f32_e32 v145, 0x4f800000, v10
	v_cmp_gt_f32_e32 vcc, s22, v10
	v_lshlrev_b32_e32 v146, 16, v8
	v_lshlrev_b32_e32 v144, 16, v11
	v_cndmask_b32_e32 v10, v10, v145, vcc
	v_sqrt_f32_e32 v148, v10
	v_and_b32_e32 v145, 0xffff0000, v11
	v_add_u32_e32 v8, -1, v148
	v_fma_f32 v11, -v8, v148, v10
	v_cmp_ge_f32_e64 s[0:1], 0, v11
	v_add_u32_e32 v11, 1, v148
	s_nop 0
	v_cndmask_b32_e64 v8, v148, v8, s[0:1]
	v_fma_f32 v148, -v11, v148, v10
	v_cmp_lt_f32_e64 s[0:1], 0, v148
	v_lshlrev_b32_e32 v148, 16, v9
	s_nop 0
	v_cndmask_b32_e64 v8, v8, v11, s[0:1]
	v_mul_f32_e32 v11, 0x37800000, v8
	v_cndmask_b32_e32 v8, v8, v11, vcc
	v_cmp_class_f32_e32 vcc, v10, v163
	s_nop 1
	v_cndmask_b32_e32 v8, v8, v10, vcc
	v_div_scale_f32 v150, s[0:1], v8, v8, 1.0
	v_rcp_f32_e32 v151, v150
	v_lshl_add_u64 v[10:11], s[14:15], 0, v[72:73]
	s_mov_b64 s[0:1], 0
	v_fma_f32 v9, -v150, v151, 1.0
	v_fmac_f32_e32 v151, v9, v151
	v_div_scale_f32 v9, vcc, 1.0, v8, 1.0
	v_mul_f32_e32 v152, v9, v151
	v_fma_f32 v153, -v150, v152, v9
	v_fmac_f32_e32 v152, v153, v151
	v_fma_f32 v9, -v150, v152, v9
	v_div_fmas_f32 v9, v9, v151, v152
	v_div_fixup_f32 v8, v9, v8, 1.0
	v_pk_mul_f32 v[138:139], v[8:9], v[138:139] op_sel_hi:[0,1]
	v_pk_fma_f32 v[4:5], v[4:5], v[138:139], v[146:147]
	v_pk_mul_f32 v[138:139], v[8:9], v[140:141] op_sel_hi:[0,1]
	v_pk_mul_f32 v[126:127], v[8:9], v[126:127] op_sel_hi:[0,1]
	v_pk_fma_f32 v[6:7], v[6:7], v[138:139], v[148:149]
	v_pk_fma_f32 v[0:1], v[0:1], v[126:127], v[124:125]
	v_pk_mul_f32 v[124:125], v[8:9], v[132:133] op_sel_hi:[0,1]
	v_pk_fma_f32 v[2:3], v[2:3], v[124:125], v[144:145]
	global_store_dwordx4 v[10:11], v[4:7], off
	global_store_dwordx4 v[10:11], v[0:3], off offset:16
	global_load_dwordx4 v[0:3], v[142:143], off offset:1024
	s_nop 0
	global_load_dwordx4 v[4:7], v[14:15], off
	global_load_dwordx4 v[124:127], v[14:15], off offset:16
	v_pk_mul_f32 v[132:133], v[8:9], v[134:135] op_sel_hi:[0,1]
	v_pk_mul_f32 v[134:135], v[8:9], v[136:137] op_sel_hi:[0,1]
	v_pk_mul_f32 v[128:129], v[8:9], v[128:129] op_sel_hi:[0,1]
	v_pk_mul_f32 v[130:131], v[8:9], v[130:131] op_sel_hi:[0,1]
	v_pk_mul_f32 v[120:121], v[8:9], v[120:121] op_sel_hi:[0,1]
	v_pk_mul_f32 v[122:123], v[8:9], v[122:123] op_sel_hi:[0,1]
	v_pk_mul_f32 v[116:117], v[8:9], v[116:117] op_sel_hi:[0,1]
	v_pk_mul_f32 v[118:119], v[8:9], v[118:119] op_sel_hi:[0,1]
	v_pk_mul_f32 v[112:113], v[8:9], v[112:113] op_sel_hi:[0,1]
	v_pk_mul_f32 v[114:115], v[8:9], v[114:115] op_sel_hi:[0,1]
	v_pk_mul_f32 v[104:105], v[8:9], v[104:105] op_sel_hi:[0,1]
	v_pk_mul_f32 v[108:109], v[8:9], v[108:109] op_sel_hi:[0,1]
	v_pk_mul_f32 v[100:101], v[8:9], v[100:101] op_sel_hi:[0,1]
	v_pk_mul_f32 v[102:103], v[8:9], v[102:103] op_sel_hi:[0,1]
	v_pk_mul_f32 v[96:97], v[8:9], v[96:97] op_sel_hi:[0,1]
	v_pk_mul_f32 v[98:99], v[8:9], v[98:99] op_sel_hi:[0,1]
	v_pk_mul_f32 v[92:93], v[8:9], v[92:93] op_sel_hi:[0,1]
	v_pk_mul_f32 v[94:95], v[8:9], v[94:95] op_sel_hi:[0,1]
	v_pk_mul_f32 v[88:89], v[8:9], v[88:89] op_sel_hi:[0,1]
	v_pk_mul_f32 v[90:91], v[8:9], v[90:91] op_sel_hi:[0,1]
	v_pk_mul_f32 v[84:85], v[8:9], v[84:85] op_sel_hi:[0,1]
	v_pk_mul_f32 v[86:87], v[8:9], v[86:87] op_sel_hi:[0,1]
	v_pk_mul_f32 v[78:79], v[8:9], v[78:79] op_sel_hi:[0,1]
	s_waitcnt vmcnt(2)
	v_lshlrev_b32_e32 v136, 16, v0
	v_and_b32_e32 v137, 0xffff0000, v0
	v_lshlrev_b32_e32 v138, 16, v1
	v_and_b32_e32 v139, 0xffff0000, v1
	v_lshlrev_b32_e32 v140, 16, v2
	v_and_b32_e32 v141, 0xffff0000, v2
	v_lshlrev_b32_e32 v144, 16, v3
	v_and_b32_e32 v145, 0xffff0000, v3
	s_waitcnt vmcnt(1)
	v_pk_fma_f32 v[0:1], v[4:5], v[132:133], v[136:137]
	v_pk_fma_f32 v[2:3], v[6:7], v[134:135], v[138:139]
	s_waitcnt vmcnt(0)
	v_pk_fma_f32 v[4:5], v[124:125], v[128:129], v[140:141]
	v_pk_fma_f32 v[6:7], v[126:127], v[130:131], v[144:145]
	global_store_dwordx4 v[10:11], v[0:3], off offset:2048
	global_store_dwordx4 v[10:11], v[4:7], off offset:2064
	global_load_dwordx4 v[0:3], v[142:143], off offset:2048
	s_nop 0
	global_load_dwordx4 v[4:7], v[16:17], off
	global_load_dwordx4 v[124:127], v[16:17], off offset:16
	v_add_co_u32_e32 v128, vcc, s18, v10
	s_waitcnt vmcnt(2)
	v_lshlrev_b32_e32 v132, 16, v0
	v_addc_co_u32_e32 v129, vcc, 0, v11, vcc
	v_add_co_u32_e32 v130, vcc, s9, v10
	v_and_b32_e32 v133, 0xffff0000, v0
	v_lshlrev_b32_e32 v134, 16, v1
	v_and_b32_e32 v135, 0xffff0000, v1
	v_addc_co_u32_e32 v131, vcc, 0, v11, vcc
	v_lshlrev_b32_e32 v136, 16, v2
	v_and_b32_e32 v137, 0xffff0000, v2
	v_lshlrev_b32_e32 v138, 16, v3
	v_and_b32_e32 v139, 0xffff0000, v3
	s_waitcnt vmcnt(1)
	v_pk_fma_f32 v[0:1], v[4:5], v[120:121], v[132:133]
	v_pk_fma_f32 v[2:3], v[6:7], v[122:123], v[134:135]
	s_waitcnt vmcnt(0)
	v_pk_fma_f32 v[4:5], v[124:125], v[116:117], v[136:137]
	v_pk_fma_f32 v[6:7], v[126:127], v[118:119], v[138:139]
	global_store_dwordx4 v[130:131], v[0:3], off offset:-4096
	global_store_dwordx4 v[128:129], v[4:7], off offset:16
	global_load_dwordx4 v[0:3], v[142:143], off offset:3072
	s_nop 0
	global_load_dwordx4 v[4:7], v[18:19], off
	global_load_dwordx4 v[116:119], v[18:19], off offset:16
	v_add_co_u32_e32 v10, vcc, s19, v10
	s_waitcnt vmcnt(2)
	v_lshlrev_b32_e32 v120, 16, v0
	v_and_b32_e32 v121, 0xffff0000, v0
	v_lshlrev_b32_e32 v122, 16, v1
	v_and_b32_e32 v123, 0xffff0000, v1
	v_lshlrev_b32_e32 v124, 16, v2
	v_and_b32_e32 v125, 0xffff0000, v2
	v_lshlrev_b32_e32 v126, 16, v3
	v_and_b32_e32 v127, 0xffff0000, v3
	s_waitcnt vmcnt(1)
	v_pk_fma_f32 v[0:1], v[4:5], v[112:113], v[120:121]
	v_pk_fma_f32 v[2:3], v[6:7], v[114:115], v[122:123]
	s_waitcnt vmcnt(0)
	v_pk_fma_f32 v[4:5], v[116:117], v[104:105], v[124:125]
	v_pk_fma_f32 v[6:7], v[118:119], v[108:109], v[126:127]
	global_store_dwordx4 v[128:129], v[0:3], off offset:2048
	global_store_dwordx4 v[128:129], v[4:7], off offset:2064
	global_load_dwordx4 v[0:3], v[74:75], off
	s_nop 0
	global_load_dwordx4 v[4:7], v[20:21], off
	global_load_dwordx4 v[112:115], v[20:21], off offset:16
	v_pk_mul_f32 v[104:105], v[8:9], v[106:107] op_sel_hi:[0,1]
	v_pk_mul_f32 v[106:107], v[8:9], v[110:111] op_sel_hi:[0,1]
	v_addc_co_u32_e32 v11, vcc, 0, v11, vcc
	s_waitcnt vmcnt(2)
	v_lshlrev_b32_e32 v108, 16, v0
	v_and_b32_e32 v109, 0xffff0000, v0
	v_lshlrev_b32_e32 v110, 16, v1
	v_and_b32_e32 v111, 0xffff0000, v1
	v_lshlrev_b32_e32 v116, 16, v2
	v_and_b32_e32 v117, 0xffff0000, v2
	v_lshlrev_b32_e32 v118, 16, v3
	v_and_b32_e32 v119, 0xffff0000, v3
	s_waitcnt vmcnt(1)
	v_pk_fma_f32 v[0:1], v[4:5], v[104:105], v[108:109]
	v_pk_fma_f32 v[2:3], v[6:7], v[106:107], v[110:111]
	s_waitcnt vmcnt(0)
	v_pk_fma_f32 v[4:5], v[112:113], v[100:101], v[116:117]
	v_pk_fma_f32 v[6:7], v[114:115], v[102:103], v[118:119]
	global_store_dwordx4 v[130:131], v[0:3], off
	global_store_dwordx4 v[130:131], v[4:7], off offset:16
	global_load_dwordx4 v[0:3], v[74:75], off offset:1024
	s_nop 0
	global_load_dwordx4 v[4:7], v[22:23], off
	global_load_dwordx4 v[100:103], v[22:23], off offset:16
	s_waitcnt vmcnt(2)
	v_lshlrev_b32_e32 v104, 16, v0
	v_and_b32_e32 v105, 0xffff0000, v0
	v_lshlrev_b32_e32 v106, 16, v1
	v_and_b32_e32 v107, 0xffff0000, v1
	v_lshlrev_b32_e32 v108, 16, v2
	v_and_b32_e32 v109, 0xffff0000, v2
	v_lshlrev_b32_e32 v110, 16, v3
	v_and_b32_e32 v111, 0xffff0000, v3
	s_waitcnt vmcnt(1)
	v_pk_fma_f32 v[0:1], v[4:5], v[96:97], v[104:105]
	v_pk_fma_f32 v[2:3], v[6:7], v[98:99], v[106:107]
	s_waitcnt vmcnt(0)
	v_pk_fma_f32 v[4:5], v[100:101], v[92:93], v[108:109]
	v_pk_fma_f32 v[6:7], v[102:103], v[94:95], v[110:111]
	global_store_dwordx4 v[130:131], v[0:3], off offset:2048
	global_store_dwordx4 v[130:131], v[4:7], off offset:2064
	global_load_dwordx4 v[0:3], v[74:75], off offset:2048
	s_nop 0
	global_load_dwordx4 v[4:7], v[24:25], off
	global_load_dwordx4 v[92:95], v[24:25], off offset:16
	s_waitcnt vmcnt(2)
	v_lshlrev_b32_e32 v96, 16, v0
	v_and_b32_e32 v97, 0xffff0000, v0
	v_lshlrev_b32_e32 v98, 16, v1
	v_and_b32_e32 v99, 0xffff0000, v1
	v_lshlrev_b32_e32 v100, 16, v2
	v_and_b32_e32 v101, 0xffff0000, v2
	v_lshlrev_b32_e32 v102, 16, v3
	v_and_b32_e32 v103, 0xffff0000, v3
	s_waitcnt vmcnt(1)
	v_pk_fma_f32 v[0:1], v[4:5], v[88:89], v[96:97]
	v_pk_fma_f32 v[2:3], v[6:7], v[90:91], v[98:99]
	s_waitcnt vmcnt(0)
	v_pk_fma_f32 v[4:5], v[92:93], v[84:85], v[100:101]
	v_pk_fma_f32 v[6:7], v[94:95], v[86:87], v[102:103]
	global_store_dwordx4 v[10:11], v[0:3], off
	global_store_dwordx4 v[10:11], v[4:7], off offset:16
	global_load_dwordx4 v[0:3], v[74:75], off offset:3072
	s_nop 0
	global_load_dwordx4 v[4:7], v[26:27], off
	global_load_dwordx4 v[84:87], v[26:27], off offset:16
	v_pk_mul_f32 v[74:75], v[8:9], v[80:81] op_sel_hi:[0,1]
	v_pk_mul_f32 v[80:81], v[8:9], v[82:83] op_sel_hi:[0,1]
	v_pk_mul_f32 v[8:9], v[8:9], v[76:77] op_sel_hi:[0,1]
	s_waitcnt vmcnt(2)
	v_lshlrev_b32_e32 v76, 16, v0
	v_and_b32_e32 v77, 0xffff0000, v0
	v_lshlrev_b32_e32 v82, 16, v1
	v_and_b32_e32 v83, 0xffff0000, v1
	v_lshlrev_b32_e32 v88, 16, v2
	v_and_b32_e32 v89, 0xffff0000, v2
	v_lshlrev_b32_e32 v90, 16, v3
	v_and_b32_e32 v91, 0xffff0000, v3
	s_waitcnt vmcnt(1)
	v_pk_fma_f32 v[0:1], v[4:5], v[74:75], v[76:77]
	v_pk_fma_f32 v[2:3], v[6:7], v[80:81], v[82:83]
	s_waitcnt vmcnt(0)
	v_pk_fma_f32 v[4:5], v[84:85], v[78:79], v[88:89]
	v_pk_fma_f32 v[6:7], v[86:87], v[8:9], v[90:91] op_sel:[0,1,0] op_sel_hi:[1,0,1]
	global_store_dwordx4 v[10:11], v[0:3], off offset:2048
	global_store_dwordx4 v[10:11], v[4:7], off offset:2064
.LBB0_2027:
	s_andn2_b64 vcc, exec, s[0:1]
	s_cbranch_vccnz .LBB0_2024
	v_lshl_add_u64 v[8:9], s[16:17], 0, v[60:61]
	v_add_co_u32_e32 v0, vcc, 0x3b100000, v8
	v_lshl_add_u64 v[76:77], s[16:17], 0, v[70:71]
	s_nop 0
	v_addc_co_u32_e32 v1, vcc, 0, v9, vcc
	v_add_co_u32_e32 v2, vcc, 0x3b100000, v76
	s_nop 1
	v_addc_co_u32_e32 v3, vcc, 0, v77, vcc
	global_load_dwordx2 v[184:185], v[0:1], off
	global_load_dwordx2 v[176:177], v[0:1], off offset:512
	global_load_dwordx2 v[166:167], v[0:1], off offset:1024
	global_load_dwordx2 v[154:155], v[0:1], off offset:1536
	global_load_dwordx2 v[182:183], v[2:3], off
	global_load_dwordx2 v[174:175], v[2:3], off offset:512
	global_load_dwordx2 v[160:161], v[2:3], off offset:1024
	global_load_dwordx2 v[150:151], v[2:3], off offset:1536
	global_load_dwordx2 v[144:145], v[0:1], off offset:2048
	global_load_dwordx2 v[132:133], v[0:1], off offset:2560
	global_load_dwordx2 v[124:125], v[0:1], off offset:3072
	global_load_dwordx2 v[116:117], v[0:1], off offset:3584
	global_load_dwordx2 v[140:141], v[2:3], off offset:2048
	global_load_dwordx2 v[130:131], v[2:3], off offset:2560
	global_load_dwordx2 v[122:123], v[2:3], off offset:3072
	global_load_dwordx2 v[114:115], v[2:3], off offset:3584
	v_add_co_u32_e32 v0, vcc, s20, v8
	s_waitcnt vmcnt(15)
	v_and_b32_e32 v157, 0xffff0000, v185
	v_addc_co_u32_e32 v1, vcc, 0, v9, vcc
	v_add_co_u32_e32 v82, vcc, s20, v76
	v_lshlrev_b32_e32 v156, 16, v185
	s_nop 0
	v_addc_co_u32_e32 v83, vcc, 0, v77, vcc
	global_load_dwordx2 v[106:107], v[0:1], off
	global_load_dwordx2 v[98:99], v[0:1], off offset:512
	global_load_dwordx2 v[92:93], v[0:1], off offset:1024
	global_load_dwordx2 v[88:89], v[0:1], off offset:1536
	global_load_dwordx2 v[108:109], v[82:83], off
	global_load_dwordx2 v[100:101], v[82:83], off offset:512
	global_load_dwordx2 v[90:91], v[82:83], off offset:1024
	global_load_dwordx2 v[86:87], v[82:83], off offset:1536
	global_load_dwordx2 v[78:79], v[0:1], off offset:2048
	global_load_dwordx2 v[10:11], v[0:1], off offset:2560
	global_load_dwordx2 v[6:7], v[0:1], off offset:3072
	global_load_dwordx2 v[2:3], v[0:1], off offset:3584
	global_load_dwordx2 v[80:81], v[82:83], off offset:2048
	global_load_dwordx2 v[74:75], v[82:83], off offset:2560
	global_load_dwordx2 v[4:5], v[82:83], off offset:3072
	s_nop 0
	global_load_dwordx2 v[0:1], v[82:83], off offset:3584
	v_mul_f32_e32 v162, v157, v157
	s_waitcnt vmcnt(27)
	v_and_b32_e32 v195, 0xffff0000, v183
	v_pk_fma_f32 v[156:157], v[156:157], v[156:157], v[162:163] op_sel_hi:[1,1,0]
	v_lshlrev_b32_e32 v194, 16, v183
	v_mul_f32_e32 v162, v195, v195
	v_and_b32_e32 v147, 0xffff0000, v184
	v_pk_fma_f32 v[194:195], v[194:195], v[194:195], v[162:163] op_sel_hi:[1,1,0]
	v_and_b32_e32 v162, 0xffff0000, v154
	v_lshlrev_b32_e32 v146, 16, v184
	v_mul_f32_e32 v212, v162, v162
	v_mul_f32_e32 v162, v147, v147
	v_and_b32_e32 v199, 0xffff0000, v177
	v_and_b32_e32 v198, 0xffff0000, v176
	v_lshlrev_b32_e32 v209, 16, v154
	v_and_b32_e32 v208, 0xffff0000, v155
	v_pk_fma_f32 v[146:147], v[146:147], v[146:147], v[162:163] op_sel_hi:[1,1,0]
	v_lshlrev_b32_e32 v197, 16, v177
	v_lshlrev_b32_e32 v196, 16, v176
	v_pk_mul_f32 v[198:199], v[198:199], v[198:199]
	v_mul_f32_e32 v213, v208, v208
	v_mov_b32_e32 v208, v146
	v_mov_b32_e32 v210, v156
	v_mov_b32_e32 v211, v209
	v_pk_fma_f32 v[196:197], v[196:197], v[196:197], v[198:199]
	s_waitcnt vmcnt(26)
	v_and_b32_e32 v201, 0xffff0000, v175
	v_and_b32_e32 v200, 0xffff0000, v174
	v_pk_add_f32 v[146:147], v[146:147], v[156:157]
	v_pk_mul_f32 v[156:157], v[208:209], v[210:211]
	v_lshlrev_b32_e32 v199, 16, v175
	v_lshlrev_b32_e32 v198, 16, v174
	v_pk_mul_f32 v[200:201], v[200:201], v[200:201]
	v_mov_b32_e32 v147, v157
	v_pk_add_f32 v[156:157], v[196:197], v[196:197] op_sel:[0,1] op_sel_hi:[1,0]
	v_pk_fma_f32 v[198:199], v[198:199], v[198:199], v[200:201]
	v_and_b32_e32 v201, 0xffff0000, v166
	v_and_b32_e32 v203, 0xffff0000, v167
	v_mov_b32_e32 v157, v212
	v_lshlrev_b32_e32 v200, 16, v166
	v_lshlrev_b32_e32 v202, 16, v167
	v_lshlrev_b32_e32 v164, 16, v155
	v_pk_add_f32 v[146:147], v[146:147], v[156:157]
	v_mul_f32_e32 v156, v201, v201
	v_mul_f32_e32 v162, v203, v203
	v_mul_f32_e32 v164, v164, v164
	v_pk_fma_f32 v[156:157], v[200:201], v[200:201], v[156:157] op_sel_hi:[1,1,0]
	v_pk_fma_f32 v[196:197], v[202:203], v[202:203], v[162:163] op_sel_hi:[1,1,0]
	v_mov_b32_e32 v157, v164
	v_mov_b32_e32 v197, v213
	v_pk_add_f32 v[156:157], v[156:157], v[196:197]
	v_and_b32_e32 v173, 0xffff0000, v182
	v_pk_add_f32 v[146:147], v[146:147], v[156:157]
	s_waitcnt vmcnt(24)
	v_and_b32_e32 v156, 0xffff0000, v150
	v_lshlrev_b32_e32 v172, 16, v182
	v_lshlrev_b32_e32 v157, 16, v150
	v_mul_f32_e32 v200, v156, v156
	v_mul_f32_e32 v156, v173, v173
	v_pk_fma_f32 v[172:173], v[172:173], v[172:173], v[156:157] op_sel_hi:[1,1,0]
	v_mov_b32_e32 v196, v194
	v_mov_b32_e32 v156, v172
	v_mov_b32_e32 v197, v157
	v_pk_add_f32 v[172:173], v[172:173], v[194:195]
	v_pk_mul_f32 v[156:157], v[156:157], v[196:197]
	v_and_b32_e32 v205, 0xffff0000, v160
	v_lshlrev_b32_e32 v162, 16, v151
	v_mov_b32_e32 v173, v157
	v_pk_add_f32 v[156:157], v[198:199], v[198:199] op_sel:[0,1] op_sel_hi:[1,0]
	v_lshlrev_b32_e32 v204, 16, v160
	v_and_b32_e32 v207, 0xffff0000, v161
	v_mul_f32_e32 v201, v162, v162
	v_mov_b32_e32 v157, v200
	v_mul_f32_e32 v162, v205, v205
	v_lshlrev_b32_e32 v206, 16, v161
	v_and_b32_e32 v164, 0xffff0000, v151
	v_pk_add_f32 v[156:157], v[172:173], v[156:157]
	v_pk_fma_f32 v[172:173], v[204:205], v[204:205], v[162:163] op_sel_hi:[1,1,0]
	v_mul_f32_e32 v162, v207, v207
	v_mul_f32_e32 v164, v164, v164
	v_pk_fma_f32 v[194:195], v[206:207], v[206:207], v[162:163] op_sel_hi:[1,1,0]
	v_mov_b32_e32 v173, v201
	v_mov_b32_e32 v195, v164
	v_pk_add_f32 v[172:173], v[172:173], v[194:195]
	s_waitcnt vmcnt(23)
	v_and_b32_e32 v195, 0xffff0000, v145
	v_and_b32_e32 v194, 0xffff0000, v144
	v_pk_add_f32 v[156:157], v[156:157], v[172:173]
	v_lshlrev_b32_e32 v173, 16, v145
	v_lshlrev_b32_e32 v172, 16, v144
	v_pk_mul_f32 v[194:195], v[194:195], v[194:195]
	s_waitcnt vmcnt(19)
	v_and_b32_e32 v197, 0xffff0000, v141
	v_pk_fma_f32 v[172:173], v[172:173], v[172:173], v[194:195]
	v_and_b32_e32 v196, 0xffff0000, v140
	v_pk_add_f32 v[172:173], v[172:173], v[172:173] op_sel:[0,1] op_sel_hi:[1,0]
	v_lshlrev_b32_e32 v195, 16, v141
	v_lshlrev_b32_e32 v194, 16, v140
	v_pk_mul_f32 v[196:197], v[196:197], v[196:197]
	v_and_b32_e32 v199, 0xffff0000, v133
	v_and_b32_e32 v198, 0xffff0000, v132
	v_lshlrev_b32_e32 v209, 16, v116
	v_and_b32_e32 v208, 0xffff0000, v117
	v_pk_add_f32 v[146:147], v[146:147], v[146:147] op_sel:[0,1] op_sel_hi:[1,0]
	v_pk_fma_f32 v[194:195], v[194:195], v[194:195], v[196:197]
	v_lshlrev_b32_e32 v197, 16, v133
	v_lshlrev_b32_e32 v196, 16, v132
	v_pk_mul_f32 v[198:199], v[198:199], v[198:199]
	s_waitcnt vmcnt(18)
	v_and_b32_e32 v201, 0xffff0000, v131
	v_and_b32_e32 v200, 0xffff0000, v130
	v_mul_f32_e32 v212, v208, v208
	v_mov_b32_e32 v208, v146
	v_mov_b32_e32 v210, v172
	v_mov_b32_e32 v211, v209
	v_pk_fma_f32 v[196:197], v[196:197], v[196:197], v[198:199]
	v_lshlrev_b32_e32 v199, 16, v131
	v_lshlrev_b32_e32 v198, 16, v130
	v_pk_mul_f32 v[200:201], v[200:201], v[200:201]
	v_and_b32_e32 v162, 0xffff0000, v116
	v_pk_add_f32 v[146:147], v[146:147], v[172:173]
	v_pk_mul_f32 v[172:173], v[208:209], v[210:211]
	v_pk_fma_f32 v[198:199], v[198:199], v[198:199], v[200:201]
	v_and_b32_e32 v201, 0xffff0000, v124
	v_mul_f32_e32 v162, v162, v162
	v_mov_b32_e32 v147, v173
	v_pk_add_f32 v[172:173], v[196:197], v[196:197] op_sel:[0,1] op_sel_hi:[1,0]
	v_lshlrev_b32_e32 v200, 16, v124
	v_and_b32_e32 v203, 0xffff0000, v125
	v_mov_b32_e32 v173, v162
	v_mul_f32_e32 v162, v201, v201
	v_lshlrev_b32_e32 v202, 16, v125
	v_lshlrev_b32_e32 v164, 16, v117
	v_pk_add_f32 v[146:147], v[146:147], v[172:173]
	v_pk_fma_f32 v[172:173], v[200:201], v[200:201], v[162:163] op_sel_hi:[1,1,0]
	v_mul_f32_e32 v162, v203, v203
	v_mul_f32_e32 v164, v164, v164
	v_pk_fma_f32 v[196:197], v[202:203], v[202:203], v[162:163] op_sel_hi:[1,1,0]
	v_mov_b32_e32 v173, v164
	v_mov_b32_e32 v197, v212
	v_pk_add_f32 v[172:173], v[172:173], v[196:197]
	v_pk_add_f32 v[194:195], v[194:195], v[194:195] op_sel:[0,1] op_sel_hi:[1,0]
	v_pk_add_f32 v[146:147], v[146:147], v[172:173]
	s_waitcnt vmcnt(16)
	v_lshlrev_b32_e32 v173, 16, v114
	v_and_b32_e32 v172, 0xffff0000, v115
	v_pk_add_f32 v[156:157], v[156:157], v[156:157] op_sel:[0,1] op_sel_hi:[1,0]
	v_mul_f32_e32 v200, v172, v172
	v_mov_b32_e32 v172, v156
	v_mov_b32_e32 v196, v194
	v_mov_b32_e32 v197, v173
	v_and_b32_e32 v162, 0xffff0000, v114
	v_pk_add_f32 v[156:157], v[156:157], v[194:195]
	v_pk_mul_f32 v[172:173], v[172:173], v[196:197]
	v_and_b32_e32 v205, 0xffff0000, v122
	v_mul_f32_e32 v162, v162, v162
	v_mov_b32_e32 v157, v173
	v_pk_add_f32 v[172:173], v[198:199], v[198:199] op_sel:[0,1] op_sel_hi:[1,0]
	v_lshlrev_b32_e32 v204, 16, v122
	v_and_b32_e32 v207, 0xffff0000, v123
	v_mov_b32_e32 v173, v162
	v_mul_f32_e32 v162, v205, v205
	v_lshlrev_b32_e32 v206, 16, v123
	v_lshlrev_b32_e32 v164, 16, v115
	v_pk_add_f32 v[156:157], v[156:157], v[172:173]
	v_pk_fma_f32 v[172:173], v[204:205], v[204:205], v[162:163] op_sel_hi:[1,1,0]
	v_mul_f32_e32 v162, v207, v207
	v_mul_f32_e32 v164, v164, v164
	v_pk_fma_f32 v[194:195], v[206:207], v[206:207], v[162:163] op_sel_hi:[1,1,0]
	v_mov_b32_e32 v173, v164
	v_mov_b32_e32 v195, v200
	v_pk_add_f32 v[172:173], v[172:173], v[194:195]
	s_waitcnt vmcnt(15)
	v_and_b32_e32 v195, 0xffff0000, v107
	v_and_b32_e32 v194, 0xffff0000, v106
	v_pk_add_f32 v[156:157], v[156:157], v[172:173]
	v_lshlrev_b32_e32 v173, 16, v107
	v_lshlrev_b32_e32 v172, 16, v106
	v_pk_mul_f32 v[194:195], v[194:195], v[194:195]
	s_waitcnt vmcnt(11)
	v_and_b32_e32 v197, 0xffff0000, v109
	v_pk_fma_f32 v[172:173], v[172:173], v[172:173], v[194:195]
	v_and_b32_e32 v196, 0xffff0000, v108
	v_pk_add_f32 v[172:173], v[172:173], v[172:173] op_sel:[0,1] op_sel_hi:[1,0]
	v_lshlrev_b32_e32 v195, 16, v109
	v_lshlrev_b32_e32 v194, 16, v108
	v_pk_mul_f32 v[196:197], v[196:197], v[196:197]
	v_and_b32_e32 v199, 0xffff0000, v99
	v_and_b32_e32 v198, 0xffff0000, v98
	v_lshlrev_b32_e32 v209, 16, v88
	v_and_b32_e32 v208, 0xffff0000, v89
	v_pk_add_f32 v[146:147], v[146:147], v[146:147] op_sel:[0,1] op_sel_hi:[1,0]
	v_pk_fma_f32 v[194:195], v[194:195], v[194:195], v[196:197]
	v_lshlrev_b32_e32 v197, 16, v99
	v_lshlrev_b32_e32 v196, 16, v98
	v_pk_mul_f32 v[198:199], v[198:199], v[198:199]
	s_waitcnt vmcnt(10)
	v_and_b32_e32 v201, 0xffff0000, v101
	v_and_b32_e32 v200, 0xffff0000, v100
	v_mul_f32_e32 v212, v208, v208
	v_mov_b32_e32 v208, v146
	v_mov_b32_e32 v210, v172
	v_mov_b32_e32 v211, v209
	v_pk_fma_f32 v[196:197], v[196:197], v[196:197], v[198:199]
	v_lshlrev_b32_e32 v199, 16, v101
	v_lshlrev_b32_e32 v198, 16, v100
	v_pk_mul_f32 v[200:201], v[200:201], v[200:201]
	v_and_b32_e32 v162, 0xffff0000, v88
	v_pk_add_f32 v[146:147], v[146:147], v[172:173]
	v_pk_mul_f32 v[172:173], v[208:209], v[210:211]
	v_pk_fma_f32 v[198:199], v[198:199], v[198:199], v[200:201]
	v_and_b32_e32 v201, 0xffff0000, v92
	v_mul_f32_e32 v162, v162, v162
	v_mov_b32_e32 v147, v173
	v_pk_add_f32 v[172:173], v[196:197], v[196:197] op_sel:[0,1] op_sel_hi:[1,0]
	v_lshlrev_b32_e32 v200, 16, v92
	v_and_b32_e32 v203, 0xffff0000, v93
	v_mov_b32_e32 v173, v162
	v_mul_f32_e32 v162, v201, v201
	v_lshlrev_b32_e32 v202, 16, v93
	v_lshlrev_b32_e32 v164, 16, v89
	v_pk_add_f32 v[146:147], v[146:147], v[172:173]
	v_pk_fma_f32 v[172:173], v[200:201], v[200:201], v[162:163] op_sel_hi:[1,1,0]
	v_mul_f32_e32 v162, v203, v203
	v_mul_f32_e32 v164, v164, v164
	v_pk_fma_f32 v[196:197], v[202:203], v[202:203], v[162:163] op_sel_hi:[1,1,0]
	v_mov_b32_e32 v173, v164
	v_mov_b32_e32 v197, v212
	v_pk_add_f32 v[172:173], v[172:173], v[196:197]
	v_pk_add_f32 v[194:195], v[194:195], v[194:195] op_sel:[0,1] op_sel_hi:[1,0]
	v_pk_add_f32 v[146:147], v[146:147], v[172:173]
	s_waitcnt vmcnt(8)
	v_lshlrev_b32_e32 v173, 16, v86
	v_and_b32_e32 v172, 0xffff0000, v87
	v_pk_add_f32 v[156:157], v[156:157], v[156:157] op_sel:[0,1] op_sel_hi:[1,0]
	v_mul_f32_e32 v200, v172, v172
	v_mov_b32_e32 v172, v156
	v_mov_b32_e32 v196, v194
	v_mov_b32_e32 v197, v173
	v_and_b32_e32 v162, 0xffff0000, v86
	v_pk_add_f32 v[156:157], v[156:157], v[194:195]
	v_pk_mul_f32 v[172:173], v[172:173], v[196:197]
	v_and_b32_e32 v205, 0xffff0000, v90
	v_mul_f32_e32 v162, v162, v162
	v_mov_b32_e32 v157, v173
	v_pk_add_f32 v[172:173], v[198:199], v[198:199] op_sel:[0,1] op_sel_hi:[1,0]
	v_lshlrev_b32_e32 v204, 16, v90
	v_and_b32_e32 v207, 0xffff0000, v91
	v_mov_b32_e32 v173, v162
	v_mul_f32_e32 v162, v205, v205
	v_lshlrev_b32_e32 v206, 16, v91
	v_lshlrev_b32_e32 v164, 16, v87
	v_pk_add_f32 v[156:157], v[156:157], v[172:173]
	v_pk_fma_f32 v[172:173], v[204:205], v[204:205], v[162:163] op_sel_hi:[1,1,0]
	v_mul_f32_e32 v162, v207, v207
	v_mul_f32_e32 v164, v164, v164
	v_pk_fma_f32 v[194:195], v[206:207], v[206:207], v[162:163] op_sel_hi:[1,1,0]
	v_mov_b32_e32 v173, v164
	v_mov_b32_e32 v195, v200
	v_pk_add_f32 v[172:173], v[172:173], v[194:195]
	s_waitcnt vmcnt(7)
	v_and_b32_e32 v195, 0xffff0000, v79
	v_and_b32_e32 v194, 0xffff0000, v78
	v_pk_add_f32 v[156:157], v[156:157], v[172:173]
	v_lshlrev_b32_e32 v173, 16, v79
	v_lshlrev_b32_e32 v172, 16, v78
	v_pk_mul_f32 v[194:195], v[194:195], v[194:195]
	s_waitcnt vmcnt(3)
	v_and_b32_e32 v197, 0xffff0000, v81
	v_pk_fma_f32 v[172:173], v[172:173], v[172:173], v[194:195]
	v_and_b32_e32 v196, 0xffff0000, v80
	v_pk_add_f32 v[172:173], v[172:173], v[172:173] op_sel:[0,1] op_sel_hi:[1,0]
	v_lshlrev_b32_e32 v195, 16, v81
	v_lshlrev_b32_e32 v194, 16, v80
	v_pk_mul_f32 v[196:197], v[196:197], v[196:197]
	v_and_b32_e32 v199, 0xffff0000, v11
	v_and_b32_e32 v198, 0xffff0000, v10
	v_lshlrev_b32_e32 v209, 16, v2
	v_and_b32_e32 v208, 0xffff0000, v3
	v_pk_add_f32 v[146:147], v[146:147], v[146:147] op_sel:[0,1] op_sel_hi:[1,0]
	v_pk_fma_f32 v[194:195], v[194:195], v[194:195], v[196:197]
	v_lshlrev_b32_e32 v197, 16, v11
	v_lshlrev_b32_e32 v196, 16, v10
	v_pk_mul_f32 v[198:199], v[198:199], v[198:199]
	s_waitcnt vmcnt(2)
	v_and_b32_e32 v201, 0xffff0000, v75
	v_and_b32_e32 v200, 0xffff0000, v74
	v_mul_f32_e32 v212, v208, v208
	v_mov_b32_e32 v208, v146
	v_mov_b32_e32 v210, v172
	v_mov_b32_e32 v211, v209
	v_pk_fma_f32 v[196:197], v[196:197], v[196:197], v[198:199]
	v_lshlrev_b32_e32 v199, 16, v75
	v_lshlrev_b32_e32 v198, 16, v74
	v_pk_mul_f32 v[200:201], v[200:201], v[200:201]
	v_and_b32_e32 v162, 0xffff0000, v2
	v_pk_add_f32 v[146:147], v[146:147], v[172:173]
	v_pk_mul_f32 v[172:173], v[208:209], v[210:211]
	v_pk_fma_f32 v[198:199], v[198:199], v[198:199], v[200:201]
	v_and_b32_e32 v201, 0xffff0000, v6
	v_mul_f32_e32 v162, v162, v162
	v_mov_b32_e32 v147, v173
	v_pk_add_f32 v[172:173], v[196:197], v[196:197] op_sel:[0,1] op_sel_hi:[1,0]
	v_lshlrev_b32_e32 v200, 16, v6
	v_and_b32_e32 v203, 0xffff0000, v7
	v_mov_b32_e32 v173, v162
	v_mul_f32_e32 v162, v201, v201
	v_add_co_u32_e32 v82, vcc, s21, v8
	v_lshlrev_b32_e32 v202, 16, v7
	v_lshlrev_b32_e32 v164, 16, v3
	v_pk_add_f32 v[146:147], v[146:147], v[172:173]
	v_pk_fma_f32 v[172:173], v[200:201], v[200:201], v[162:163] op_sel_hi:[1,1,0]
	v_mul_f32_e32 v162, v203, v203
	v_addc_co_u32_e32 v83, vcc, 0, v9, vcc
	v_mul_f32_e32 v164, v164, v164
	v_pk_fma_f32 v[196:197], v[202:203], v[202:203], v[162:163] op_sel_hi:[1,1,0]
	v_add_co_u32_e32 v8, vcc, s23, v8
	v_mov_b32_e32 v173, v164
	v_mov_b32_e32 v197, v212
	v_addc_co_u32_e32 v9, vcc, 0, v9, vcc
	v_pk_add_f32 v[172:173], v[172:173], v[196:197]
	v_add_co_u32_e32 v84, vcc, s21, v76
	v_pk_add_f32 v[146:147], v[146:147], v[172:173]
	s_nop 0
	v_addc_co_u32_e32 v85, vcc, 0, v77, vcc
	v_add_f32_e32 v162, v146, v147
	s_waitcnt vmcnt(0)
	v_and_b32_e32 v146, 0xffff0000, v0
	v_add_co_u32_e32 v136, vcc, s23, v76
	v_mul_f32_e32 v196, v146, v146
	v_and_b32_e32 v146, 64, v165
	v_addc_co_u32_e32 v137, vcc, 0, v77, vcc
	v_add_u32_e32 v197, 64, v146
	v_xor_b32_e32 v146, 1, v165
	v_cmp_lt_i32_e32 vcc, v146, v197
	v_pk_add_f32 v[194:195], v[194:195], v[194:195] op_sel:[0,1] op_sel_hi:[1,0]
	v_lshlrev_b32_e32 v147, 16, v0
	v_cndmask_b32_e32 v146, v165, v146, vcc
	v_lshlrev_b32_e32 v200, 2, v146
	v_and_b32_e32 v172, 0xffff0000, v1
	v_pk_add_f32 v[156:157], v[156:157], v[156:157] op_sel:[0,1] op_sel_hi:[1,0]
	v_mul_f32_e32 v201, v172, v172
	v_mov_b32_e32 v146, v156
	s_waitcnt lgkmcnt(0)
	s_nop 1
	v_add_f32_dpp v162, v162, v162 quad_perm:[1,0,3,2] row_mask:0xf bank_mask:0xf
	v_xor_b32_e32 v173, 2, v165
	v_cmp_lt_i32_e32 vcc, v173, v197
	v_mov_b32_e32 v172, v194
	v_pk_add_f32 v[156:157], v[156:157], v[194:195]
	v_cndmask_b32_e32 v173, v165, v173, vcc
	v_lshlrev_b32_e32 v202, 2, v173
	v_mov_b32_e32 v173, v147
	v_pk_mul_f32 v[146:147], v[146:147], v[172:173]
	v_and_b32_e32 v205, 0xffff0000, v4
	v_xor_b32_e32 v146, 4, v165
	v_cmp_lt_i32_e32 vcc, v146, v197
	s_waitcnt lgkmcnt(0)
	s_nop 1
	v_add_f32_dpp v162, v162, v162 quad_perm:[2,3,0,1] row_mask:0xf bank_mask:0xf
	v_mov_b32_e32 v157, v147
	v_cndmask_b32_e32 v146, v165, v146, vcc
	v_lshlrev_b32_e32 v203, 2, v146
	v_pk_add_f32 v[146:147], v[198:199], v[198:199] op_sel:[0,1] op_sel_hi:[1,0]
	v_lshlrev_b32_e32 v204, 16, v4
	v_mov_b32_e32 v147, v196
	v_pk_add_f32 v[146:147], v[156:157], v[146:147]
	v_xor_b32_e32 v157, 8, v165
	v_cmp_lt_i32_e32 vcc, v157, v197
	s_waitcnt lgkmcnt(0)
	s_nop 1
	v_add_f32_dpp v194, v162, v162 row_half_mirror row_mask:0xf bank_mask:0xf
	v_lshlrev_b32_e32 v164, 16, v1
	v_cndmask_b32_e32 v157, v165, v157, vcc
	v_lshlrev_b32_e32 v198, 2, v157
	v_mul_f32_e32 v156, v205, v205
	v_mul_f32_e32 v164, v164, v164
	v_pk_fma_f32 v[156:157], v[204:205], v[204:205], v[156:157] op_sel_hi:[1,1,0]
	v_and_b32_e32 v207, 0xffff0000, v5
	v_mov_b32_e32 v157, v164
	v_xor_b32_e32 v164, 16, v165
	v_lshlrev_b32_e32 v206, 16, v5
	v_mul_f32_e32 v162, v207, v207
	v_cmp_lt_i32_e32 vcc, v164, v197
	v_pk_fma_f32 v[172:173], v[206:207], v[206:207], v[162:163] op_sel_hi:[1,1,0]
	s_waitcnt lgkmcnt(0)
	s_nop 1
	v_add_f32_dpp v162, v194, v194 row_mirror row_mask:0xf bank_mask:0xf
	v_cndmask_b32_e32 v164, v165, v164, vcc
	v_lshlrev_b32_e32 v164, 2, v164
	v_mov_b32_e32 v173, v201
	v_pk_add_f32 v[156:157], v[156:157], v[172:173]
	global_load_dwordx2 v[188:189], v[82:83], off offset:512
	global_load_dwordx2 v[180:181], v[82:83], off offset:1024
	global_load_dwordx2 v[170:171], v[82:83], off offset:1536
	global_load_dwordx2 v[158:159], v[82:83], off offset:2048
	global_load_dwordx2 v[178:179], v[84:85], off offset:1024
	global_load_dwordx2 v[168:169], v[84:85], off offset:1536
	global_load_dwordx2 v[152:153], v[84:85], off offset:2048
	global_load_dwordx2 v[142:143], v[84:85], off offset:2560
	global_load_dwordx2 v[186:187], v[84:85], off offset:512
	global_load_dwordx2 v[148:149], v[82:83], off offset:2560
	global_load_dwordx2 v[138:139], v[82:83], off offset:3072
	global_load_dwordx2 v[128:129], v[82:83], off offset:3584
	global_load_dwordx2 v[192:193], v[8:9], off offset:-4096
	global_load_dwordx2 v[134:135], v[84:85], off offset:3072
	global_load_dwordx2 v[120:121], v[8:9], off
	global_load_dwordx2 v[126:127], v[84:85], off offset:3584
	global_load_dwordx2 v[118:119], v[136:137], off
	global_load_dwordx2 v[110:111], v[136:137], off offset:512
	global_load_dwordx2 v[102:103], v[136:137], off offset:1024
	global_load_dwordx2 v[94:95], v[136:137], off offset:1536
	global_load_dwordx2 v[112:113], v[8:9], off offset:512
	global_load_dwordx2 v[104:105], v[8:9], off offset:1024
	global_load_dwordx2 v[96:97], v[8:9], off offset:1536
	global_load_dwordx2 v[84:85], v[8:9], off offset:2048
	global_load_dwordx2 v[190:191], v[136:137], off offset:-4096
	global_load_dwordx2 v[82:83], v[8:9], off offset:2560
	global_load_dwordx2 v[76:77], v[8:9], off offset:3072
	s_nop 0
	global_load_dwordx2 v[8:9], v[8:9], off offset:3584
	v_pk_add_f32 v[146:147], v[146:147], v[156:157]
	s_waitcnt lgkmcnt(0)
	v_mov_b32_e32 v194, v162
	s_nop 1
	v_permlane16_swap_b32_e32 v194, v162
	v_add_f32_e32 v162, v162, v194
	v_add_f32_e32 v195, v146, v147
	v_xor_b32_e32 v146, 32, v165
	v_cmp_lt_i32_e32 vcc, v146, v197
	s_waitcnt lgkmcnt(0)
	s_nop 1
	v_add_f32_dpp v200, v195, v195 quad_perm:[1,0,3,2] row_mask:0xf bank_mask:0xf
	v_cndmask_b32_e32 v146, v165, v146, vcc
	v_lshlrev_b32_e32 v199, 2, v146
	global_load_dwordx2 v[172:173], v[136:137], off offset:2048
	global_load_dwordx2 v[156:157], v[136:137], off offset:2560
	global_load_dwordx2 v[146:147], v[136:137], off offset:3072
	s_nop 0
	global_load_dwordx2 v[136:137], v[136:137], off offset:3584
	s_waitcnt lgkmcnt(0)
	v_mov_b32_e32 v194, v162
	s_nop 1
	v_permlane32_swap_b32_e32 v194, v162
	v_add_f32_e32 v162, v162, v194
	global_load_dwordx4 v[194:197], v[28:29], off
	v_fmamk_f32 v162, v162, 0x39800000, v65
	v_mul_f32_e32 v202, 0x4f800000, v162
	v_cmp_gt_f32_e32 vcc, s22, v162
	s_waitcnt lgkmcnt(0)
	s_nop 1
	v_add_f32_dpp v200, v200, v200 quad_perm:[2,3,0,1] row_mask:0xf bank_mask:0xf
	v_cndmask_b32_e32 v162, v162, v202, vcc
	v_sqrt_f32_e32 v202, v162
	s_waitcnt lgkmcnt(0)
	s_nop 1
	v_add_f32_dpp v200, v200, v200 row_half_mirror row_mask:0xf bank_mask:0xf
	ds_bpermute_b32 v198, v198, v200
	v_add_u32_e32 v201, -1, v202
	s_waitcnt lgkmcnt(0)
	v_add_f32_e32 v198, v200, v198
	ds_bpermute_b32 v164, v164, v198
	v_fma_f32 v200, -v201, v202, v162
	v_cmp_ge_f32_e64 s[0:1], 0, v200
	s_waitcnt lgkmcnt(0)
	v_add_f32_e32 v164, v198, v164
	v_cndmask_b32_e64 v200, v202, v201, s[0:1]
	v_add_u32_e32 v201, 1, v202
	v_fma_f32 v199, -v201, v202, v162
	v_cmp_lt_f32_e64 s[0:1], 0, v199
	s_waitcnt lgkmcnt(0)
	v_mov_b32_e32 v198, v164
	s_nop 1
	v_permlane32_swap_b32_e32 v198, v164
	v_add_f32_e32 v164, v164, v198
	v_fmamk_f32 v164, v164, 0x39800000, v65
	v_cndmask_b32_e64 v199, v200, v201, s[0:1]
	v_mul_f32_e32 v198, 0x4f800000, v164
	v_cmp_gt_f32_e64 s[0:1], s22, v164
	v_mul_f32_e32 v200, 0x37800000, v199
	v_cndmask_b32_e32 v199, v199, v200, vcc
	v_cndmask_b32_e64 v164, v164, v198, s[0:1]
	v_sqrt_f32_e32 v198, v164
	v_cmp_class_f32_e32 vcc, v162, v163
	s_nop 1
	v_cndmask_b32_e32 v162, v199, v162, vcc
	v_add_u32_e32 v199, -1, v198
	v_fma_f32 v200, -v199, v198, v164
	v_cmp_ge_f32_e32 vcc, 0, v200
	v_add_u32_e32 v200, 1, v198
	s_nop 0
	v_cndmask_b32_e32 v199, v198, v199, vcc
	v_fma_f32 v198, -v200, v198, v164
	v_cmp_lt_f32_e32 vcc, 0, v198
	s_nop 1
	v_cndmask_b32_e32 v198, v199, v200, vcc
	v_div_scale_f32 v200, s[26:27], v162, v162, 1.0
	v_rcp_f32_e32 v201, v200
	v_mul_f32_e32 v199, 0x37800000, v198
	v_cndmask_b32_e64 v198, v198, v199, s[0:1]
	v_cmp_class_f32_e32 vcc, v164, v163
	s_nop 1
	v_cndmask_b32_e32 v164, v198, v164, vcc
	v_fma_f32 v198, -v200, v201, 1.0
	v_fmac_f32_e32 v201, v198, v201
	v_div_scale_f32 v198, vcc, 1.0, v162, 1.0
	v_mul_f32_e32 v199, v198, v201
	v_fma_f32 v202, -v200, v199, v198
	v_fmac_f32_e32 v199, v202, v201
	v_fma_f32 v198, -v200, v199, v198
	v_div_scale_f32 v200, s[0:1], v164, v164, 1.0
	v_rcp_f32_e32 v202, v200
	v_div_fmas_f32 v198, v198, v201, v199
	v_div_fixup_f32 v162, v198, v162, 1.0
	v_fma_f32 v198, -v200, v202, 1.0
	v_fmac_f32_e32 v202, v198, v202
	v_div_scale_f32 v198, vcc, 1.0, v164, 1.0
	v_mul_f32_e32 v199, v198, v202
	v_fma_f32 v201, -v200, v199, v198
	v_fmac_f32_e32 v199, v201, v202
	v_fma_f32 v198, -v200, v199, v198
	v_div_fmas_f32 v198, v198, v202, v199
	v_lshlrev_b32_e32 v200, 16, v184
	v_and_b32_e32 v201, 0xffff0000, v184
	v_lshlrev_b32_e32 v184, 16, v185
	v_and_b32_e32 v185, 0xffff0000, v185
	v_div_fixup_f32 v164, v198, v164, 1.0
	s_waitcnt vmcnt(20)
	v_lshlrev_b32_e32 v198, 16, v192
	v_and_b32_e32 v199, 0xffff0000, v192
	v_pk_mul_f32 v[200:201], v[162:163], v[200:201] op_sel_hi:[0,1]
	v_lshlrev_b32_e32 v192, 16, v193
	v_and_b32_e32 v193, 0xffff0000, v193
	v_pk_mul_f32 v[184:185], v[162:163], v[184:185] op_sel_hi:[0,1]
	s_waitcnt vmcnt(0)
	v_pk_fma_f32 v[198:199], v[200:201], v[194:195], v[198:199]
	v_pk_fma_f32 v[200:201], v[184:185], v[196:197], v[192:193]
	v_lshl_add_u64 v[184:185], s[14:15], 0, v[66:67]
	global_store_dwordx4 v[184:185], v[198:201], off
	v_lshlrev_b32_e32 v192, 16, v190
	v_and_b32_e32 v193, 0xffff0000, v190
	v_lshlrev_b32_e32 v198, 16, v182
	v_and_b32_e32 v199, 0xffff0000, v182
	v_lshlrev_b32_e32 v182, 16, v183
	v_and_b32_e32 v183, 0xffff0000, v183
	v_pk_mul_f32 v[198:199], v[164:165], v[198:199] op_sel_hi:[0,1]
	v_lshlrev_b32_e32 v190, 16, v191
	v_and_b32_e32 v191, 0xffff0000, v191
	v_pk_mul_f32 v[182:183], v[164:165], v[182:183] op_sel_hi:[0,1]
	v_pk_fma_f32 v[192:193], v[198:199], v[194:195], v[192:193]
	v_pk_fma_f32 v[194:195], v[182:183], v[196:197], v[190:191]
	v_lshl_add_u64 v[182:183], s[14:15], 0, v[62:63]
	global_store_dwordx4 v[182:183], v[192:195], off
	global_load_dwordx4 v[190:193], v[30:31], off
	v_lshlrev_b32_e32 v196, 16, v176
	v_and_b32_e32 v197, 0xffff0000, v176
	v_lshlrev_b32_e32 v176, 16, v177
	v_and_b32_e32 v177, 0xffff0000, v177
	v_lshlrev_b32_e32 v194, 16, v188
	v_and_b32_e32 v195, 0xffff0000, v188
	v_pk_mul_f32 v[196:197], v[162:163], v[196:197] op_sel_hi:[0,1]
	v_lshlrev_b32_e32 v188, 16, v189
	v_and_b32_e32 v189, 0xffff0000, v189
	v_pk_mul_f32 v[176:177], v[162:163], v[176:177] op_sel_hi:[0,1]
	s_waitcnt vmcnt(0)
	v_pk_fma_f32 v[194:195], v[196:197], v[190:191], v[194:195]
	v_pk_fma_f32 v[196:197], v[176:177], v[192:193], v[188:189]
	v_lshlrev_b32_e32 v188, 16, v174
	v_and_b32_e32 v189, 0xffff0000, v174
	v_lshlrev_b32_e32 v176, 16, v186
	v_and_b32_e32 v177, 0xffff0000, v186
	v_pk_mul_f32 v[188:189], v[164:165], v[188:189] op_sel_hi:[0,1]
	v_lshlrev_b32_e32 v174, 16, v175
	v_and_b32_e32 v175, 0xffff0000, v175
	v_pk_fma_f32 v[188:189], v[188:189], v[190:191], v[176:177]
	v_lshlrev_b32_e32 v176, 16, v187
	v_and_b32_e32 v177, 0xffff0000, v187
	v_pk_mul_f32 v[174:175], v[164:165], v[174:175] op_sel_hi:[0,1]
	v_pk_fma_f32 v[190:191], v[174:175], v[192:193], v[176:177]
	global_store_dwordx4 v[184:185], v[194:197], off offset:1024
	global_store_dwordx4 v[182:183], v[188:191], off offset:1024
	global_load_dwordx4 v[174:177], v[32:33], off
	v_lshlrev_b32_e32 v186, 16, v180
	v_lshlrev_b32_e32 v188, 16, v166
	v_and_b32_e32 v189, 0xffff0000, v166
	v_lshlrev_b32_e32 v166, 16, v167
	v_and_b32_e32 v167, 0xffff0000, v167
	v_and_b32_e32 v187, 0xffff0000, v180
	v_pk_mul_f32 v[188:189], v[162:163], v[188:189] op_sel_hi:[0,1]
	v_lshlrev_b32_e32 v180, 16, v181
	v_and_b32_e32 v181, 0xffff0000, v181
	v_pk_mul_f32 v[166:167], v[162:163], v[166:167] op_sel_hi:[0,1]
	s_waitcnt vmcnt(0)
	v_pk_fma_f32 v[186:187], v[188:189], v[174:175], v[186:187]
	v_pk_fma_f32 v[188:189], v[166:167], v[176:177], v[180:181]
	v_lshlrev_b32_e32 v180, 16, v160
	v_and_b32_e32 v181, 0xffff0000, v160
	v_lshlrev_b32_e32 v166, 16, v178
	v_and_b32_e32 v167, 0xffff0000, v178
	v_pk_mul_f32 v[180:181], v[164:165], v[180:181] op_sel_hi:[0,1]
	v_lshlrev_b32_e32 v160, 16, v161
	v_and_b32_e32 v161, 0xffff0000, v161
	v_pk_fma_f32 v[174:175], v[180:181], v[174:175], v[166:167]
	v_lshlrev_b32_e32 v166, 16, v179
	v_and_b32_e32 v167, 0xffff0000, v179
	v_pk_mul_f32 v[160:161], v[164:165], v[160:161] op_sel_hi:[0,1]
	v_pk_fma_f32 v[176:177], v[160:161], v[176:177], v[166:167]
	global_store_dwordx4 v[184:185], v[186:189], off offset:2048
	global_store_dwordx4 v[182:183], v[174:177], off offset:2048
	global_load_dwordx4 v[174:177], v[34:35], off
	v_lshlrev_b32_e32 v166, 16, v154
	v_and_b32_e32 v167, 0xffff0000, v154
	v_lshlrev_b32_e32 v160, 16, v170
	v_and_b32_e32 v161, 0xffff0000, v170
	v_pk_mul_f32 v[166:167], v[162:163], v[166:167] op_sel_hi:[0,1]
	v_lshlrev_b32_e32 v154, 16, v155
	v_and_b32_e32 v155, 0xffff0000, v155
	v_pk_mul_f32 v[154:155], v[162:163], v[154:155] op_sel_hi:[0,1]
	s_waitcnt vmcnt(0)
	v_pk_fma_f32 v[178:179], v[166:167], v[174:175], v[160:161]
	v_lshlrev_b32_e32 v160, 16, v171
	v_and_b32_e32 v161, 0xffff0000, v171
	v_pk_fma_f32 v[180:181], v[154:155], v[176:177], v[160:161]
	v_lshlrev_b32_e32 v160, 16, v150
	v_and_b32_e32 v161, 0xffff0000, v150
	v_lshlrev_b32_e32 v154, 16, v168
	v_and_b32_e32 v155, 0xffff0000, v168
	v_pk_mul_f32 v[160:161], v[164:165], v[160:161] op_sel_hi:[0,1]
	v_lshlrev_b32_e32 v150, 16, v151
	v_and_b32_e32 v151, 0xffff0000, v151
	v_pk_fma_f32 v[166:167], v[160:161], v[174:175], v[154:155]
	v_lshlrev_b32_e32 v154, 16, v169
	v_and_b32_e32 v155, 0xffff0000, v169
	v_pk_mul_f32 v[150:151], v[164:165], v[150:151] op_sel_hi:[0,1]
	v_pk_fma_f32 v[168:169], v[150:151], v[176:177], v[154:155]
	global_store_dwordx4 v[184:185], v[178:181], off offset:3072
	global_store_dwordx4 v[182:183], v[166:169], off offset:3072
	global_load_dwordx4 v[166:169], v[36:37], off
	v_lshlrev_b32_e32 v154, 16, v144
	v_and_b32_e32 v155, 0xffff0000, v144
	v_lshlrev_b32_e32 v150, 16, v158
	v_and_b32_e32 v151, 0xffff0000, v158
	v_pk_mul_f32 v[154:155], v[162:163], v[154:155] op_sel_hi:[0,1]
	v_lshlrev_b32_e32 v144, 16, v145
	v_and_b32_e32 v145, 0xffff0000, v145
	v_pk_mul_f32 v[144:145], v[162:163], v[144:145] op_sel_hi:[0,1]
	v_lshlrev_b32_e32 v160, 16, v132
	v_and_b32_e32 v161, 0xffff0000, v132
	v_lshlrev_b32_e32 v132, 16, v133
	v_and_b32_e32 v133, 0xffff0000, v133
	v_lshlrev_b32_e32 v158, 16, v148
	v_pk_mul_f32 v[160:161], v[162:163], v[160:161] op_sel_hi:[0,1]
	v_pk_mul_f32 v[132:133], v[162:163], v[132:133] op_sel_hi:[0,1]
	s_waitcnt vmcnt(0)
	v_pk_fma_f32 v[174:175], v[154:155], v[166:167], v[150:151]
	v_lshlrev_b32_e32 v150, 16, v159
	v_and_b32_e32 v151, 0xffff0000, v159
	v_pk_fma_f32 v[176:177], v[144:145], v[168:169], v[150:151]
	v_add_co_u32_e32 v144, vcc, s9, v184
	v_lshlrev_b32_e32 v154, 16, v140
	v_and_b32_e32 v155, 0xffff0000, v140
	v_lshlrev_b32_e32 v140, 16, v141
	v_and_b32_e32 v141, 0xffff0000, v141
	v_addc_co_u32_e32 v145, vcc, 0, v185, vcc
	v_lshlrev_b32_e32 v150, 16, v152
	v_and_b32_e32 v151, 0xffff0000, v152
	v_lshlrev_b32_e32 v152, 16, v153
	v_and_b32_e32 v153, 0xffff0000, v153
	v_pk_mul_f32 v[140:141], v[164:165], v[140:141] op_sel_hi:[0,1]
	v_pk_mul_f32 v[154:155], v[164:165], v[154:155] op_sel_hi:[0,1]
	v_pk_fma_f32 v[152:153], v[140:141], v[168:169], v[152:153]
	v_add_co_u32_e32 v140, vcc, s9, v182
	v_pk_fma_f32 v[150:151], v[154:155], v[166:167], v[150:151]
	s_nop 0
	v_addc_co_u32_e32 v141, vcc, 0, v183, vcc
	global_store_dwordx4 v[144:145], v[174:177], off offset:-4096
	global_store_dwordx4 v[140:141], v[150:153], off offset:-4096
	global_load_dwordx4 v[150:153], v[38:39], off
	v_and_b32_e32 v159, 0xffff0000, v148
	v_lshlrev_b32_e32 v148, 16, v149
	v_and_b32_e32 v149, 0xffff0000, v149
	v_add_co_u32_e32 v154, vcc, s18, v184
	s_waitcnt vmcnt(0)
	v_pk_fma_f32 v[158:159], v[160:161], v[150:151], v[158:159]
	v_pk_fma_f32 v[160:161], v[132:133], v[152:153], v[148:149]
	v_lshlrev_b32_e32 v148, 16, v130
	v_and_b32_e32 v149, 0xffff0000, v130
	v_addc_co_u32_e32 v155, vcc, 0, v185, vcc
	v_lshlrev_b32_e32 v132, 16, v142
	v_and_b32_e32 v133, 0xffff0000, v142
	v_pk_mul_f32 v[148:149], v[164:165], v[148:149] op_sel_hi:[0,1]
	v_lshlrev_b32_e32 v130, 16, v131
	v_and_b32_e32 v131, 0xffff0000, v131
	v_add_co_u32_e32 v166, vcc, s18, v182
	v_pk_fma_f32 v[148:149], v[148:149], v[150:151], v[132:133]
	v_lshlrev_b32_e32 v132, 16, v143
	v_and_b32_e32 v133, 0xffff0000, v143
	v_pk_mul_f32 v[130:131], v[164:165], v[130:131] op_sel_hi:[0,1]
	v_addc_co_u32_e32 v167, vcc, 0, v183, vcc
	v_pk_fma_f32 v[150:151], v[130:131], v[152:153], v[132:133]
	global_store_dwordx4 v[154:155], v[158:161], off offset:1024
	global_store_dwordx4 v[166:167], v[148:151], off offset:1024
	global_load_dwordx4 v[130:133], v[40:41], off
	v_lshlrev_b32_e32 v142, 16, v138
	v_lshlrev_b32_e32 v148, 16, v124
	v_and_b32_e32 v149, 0xffff0000, v124
	v_lshlrev_b32_e32 v124, 16, v125
	v_and_b32_e32 v125, 0xffff0000, v125
	v_and_b32_e32 v143, 0xffff0000, v138
	v_lshlrev_b32_e32 v138, 16, v139
	v_and_b32_e32 v139, 0xffff0000, v139
	v_pk_mul_f32 v[124:125], v[162:163], v[124:125] op_sel_hi:[0,1]
	v_pk_mul_f32 v[148:149], v[162:163], v[148:149] op_sel_hi:[0,1]
	s_waitcnt vmcnt(0)
	v_pk_fma_f32 v[150:151], v[124:125], v[132:133], v[138:139]
	v_lshlrev_b32_e32 v138, 16, v122
	v_and_b32_e32 v139, 0xffff0000, v122
	v_lshlrev_b32_e32 v124, 16, v134
	v_and_b32_e32 v125, 0xffff0000, v134
	v_pk_mul_f32 v[138:139], v[164:165], v[138:139] op_sel_hi:[0,1]
	v_lshlrev_b32_e32 v122, 16, v123
	v_and_b32_e32 v123, 0xffff0000, v123
	v_pk_fma_f32 v[148:149], v[148:149], v[130:131], v[142:143]
	v_pk_fma_f32 v[130:131], v[138:139], v[130:131], v[124:125]
	v_lshlrev_b32_e32 v124, 16, v135
	v_and_b32_e32 v125, 0xffff0000, v135
	v_pk_mul_f32 v[122:123], v[164:165], v[122:123] op_sel_hi:[0,1]
	v_pk_fma_f32 v[132:133], v[122:123], v[132:133], v[124:125]
	global_store_dwordx4 v[154:155], v[148:151], off offset:2048
	global_store_dwordx4 v[166:167], v[130:133], off offset:2048
	global_load_dwordx4 v[122:125], v[42:43], off
	s_nop 0
	v_lshlrev_b32_e32 v132, 16, v116
	v_and_b32_e32 v133, 0xffff0000, v116
	v_lshlrev_b32_e32 v116, 16, v117
	v_and_b32_e32 v117, 0xffff0000, v117
	v_lshlrev_b32_e32 v130, 16, v128
	v_and_b32_e32 v131, 0xffff0000, v128
	v_pk_mul_f32 v[132:133], v[162:163], v[132:133] op_sel_hi:[0,1]
	v_lshlrev_b32_e32 v128, 16, v129
	v_and_b32_e32 v129, 0xffff0000, v129
	v_pk_mul_f32 v[116:117], v[162:163], v[116:117] op_sel_hi:[0,1]
	s_waitcnt vmcnt(0)
	v_pk_fma_f32 v[130:131], v[132:133], v[122:123], v[130:131]
	v_pk_fma_f32 v[132:133], v[116:117], v[124:125], v[128:129]
	v_lshlrev_b32_e32 v128, 16, v114
	v_and_b32_e32 v129, 0xffff0000, v114
	v_lshlrev_b32_e32 v116, 16, v126
	v_and_b32_e32 v117, 0xffff0000, v126
	v_pk_mul_f32 v[128:129], v[164:165], v[128:129] op_sel_hi:[0,1]
	v_lshlrev_b32_e32 v114, 16, v115
	v_and_b32_e32 v115, 0xffff0000, v115
	v_pk_fma_f32 v[122:123], v[128:129], v[122:123], v[116:117]
	v_lshlrev_b32_e32 v116, 16, v127
	v_and_b32_e32 v117, 0xffff0000, v127
	v_pk_mul_f32 v[114:115], v[164:165], v[114:115] op_sel_hi:[0,1]
	v_pk_fma_f32 v[124:125], v[114:115], v[124:125], v[116:117]
	global_store_dwordx4 v[154:155], v[130:133], off offset:3072
	global_store_dwordx4 v[166:167], v[122:125], off offset:3072
	global_load_dwordx4 v[114:117], v[44:45], off
	v_lshlrev_b32_e32 v126, 16, v106
	v_and_b32_e32 v127, 0xffff0000, v106
	v_lshlrev_b32_e32 v106, 16, v107
	v_and_b32_e32 v107, 0xffff0000, v107
	v_lshlrev_b32_e32 v122, 16, v120
	v_and_b32_e32 v123, 0xffff0000, v120
	v_lshlrev_b32_e32 v120, 16, v121
	v_and_b32_e32 v121, 0xffff0000, v121
	v_lshlrev_b32_e32 v128, 16, v108
	v_and_b32_e32 v129, 0xffff0000, v108
	v_lshlrev_b32_e32 v108, 16, v109
	v_and_b32_e32 v109, 0xffff0000, v109
	v_pk_mul_f32 v[126:127], v[162:163], v[126:127] op_sel_hi:[0,1]
	v_pk_mul_f32 v[130:131], v[162:163], v[106:107] op_sel_hi:[0,1]
	v_lshlrev_b32_e32 v124, 16, v118
	v_and_b32_e32 v125, 0xffff0000, v118
	v_lshlrev_b32_e32 v118, 16, v119
	v_and_b32_e32 v119, 0xffff0000, v119
	v_pk_mul_f32 v[128:129], v[164:165], v[128:129] op_sel_hi:[0,1]
	v_pk_mul_f32 v[132:133], v[164:165], v[108:109] op_sel_hi:[0,1]
	s_waitcnt vmcnt(0)
	v_pk_fma_f32 v[106:107], v[126:127], v[114:115], v[122:123]
	v_pk_fma_f32 v[108:109], v[130:131], v[116:117], v[120:121]
	v_pk_fma_f32 v[114:115], v[128:129], v[114:115], v[124:125]
	v_pk_fma_f32 v[116:117], v[132:133], v[116:117], v[118:119]
	global_store_dwordx4 v[144:145], v[106:109], off
	global_store_dwordx4 v[140:141], v[114:117], off
	global_load_dwordx4 v[106:109], v[46:47], off
	v_lshlrev_b32_e32 v118, 16, v98
	v_and_b32_e32 v119, 0xffff0000, v98
	v_lshlrev_b32_e32 v98, 16, v99
	v_and_b32_e32 v99, 0xffff0000, v99
	v_lshlrev_b32_e32 v114, 16, v112
	v_and_b32_e32 v115, 0xffff0000, v112
	v_lshlrev_b32_e32 v112, 16, v113
	v_and_b32_e32 v113, 0xffff0000, v113
	v_lshlrev_b32_e32 v120, 16, v100
	v_and_b32_e32 v121, 0xffff0000, v100
	v_lshlrev_b32_e32 v100, 16, v101
	v_and_b32_e32 v101, 0xffff0000, v101
	v_pk_mul_f32 v[118:119], v[162:163], v[118:119] op_sel_hi:[0,1]
	v_pk_mul_f32 v[122:123], v[162:163], v[98:99] op_sel_hi:[0,1]
	v_lshlrev_b32_e32 v116, 16, v110
	v_and_b32_e32 v117, 0xffff0000, v110
	v_lshlrev_b32_e32 v110, 16, v111
	v_and_b32_e32 v111, 0xffff0000, v111
	v_pk_mul_f32 v[120:121], v[164:165], v[120:121] op_sel_hi:[0,1]
	v_pk_mul_f32 v[124:125], v[164:165], v[100:101] op_sel_hi:[0,1]
	s_waitcnt vmcnt(0)
	v_pk_fma_f32 v[98:99], v[118:119], v[106:107], v[114:115]
	v_pk_fma_f32 v[100:101], v[122:123], v[108:109], v[112:113]
	v_pk_fma_f32 v[106:107], v[120:121], v[106:107], v[116:117]
	v_pk_fma_f32 v[108:109], v[124:125], v[108:109], v[110:111]
	global_store_dwordx4 v[144:145], v[98:101], off offset:1024
	global_store_dwordx4 v[140:141], v[106:109], off offset:1024
	global_load_dwordx4 v[98:101], v[48:49], off
	v_lshlrev_b32_e32 v110, 16, v92
	v_and_b32_e32 v111, 0xffff0000, v92
	v_lshlrev_b32_e32 v92, 16, v93
	v_and_b32_e32 v93, 0xffff0000, v93
	v_lshlrev_b32_e32 v106, 16, v104
	v_and_b32_e32 v107, 0xffff0000, v104
	v_lshlrev_b32_e32 v104, 16, v105
	v_and_b32_e32 v105, 0xffff0000, v105
	v_lshlrev_b32_e32 v112, 16, v90
	v_and_b32_e32 v113, 0xffff0000, v90
	v_lshlrev_b32_e32 v90, 16, v91
	v_and_b32_e32 v91, 0xffff0000, v91
	v_pk_mul_f32 v[110:111], v[162:163], v[110:111] op_sel_hi:[0,1]
	v_pk_mul_f32 v[92:93], v[162:163], v[92:93] op_sel_hi:[0,1]
	v_lshlrev_b32_e32 v108, 16, v102
	v_and_b32_e32 v109, 0xffff0000, v102
	v_lshlrev_b32_e32 v102, 16, v103
	v_and_b32_e32 v103, 0xffff0000, v103
	v_pk_mul_f32 v[112:113], v[164:165], v[112:113] op_sel_hi:[0,1]
	v_pk_mul_f32 v[114:115], v[164:165], v[90:91] op_sel_hi:[0,1]
	s_waitcnt vmcnt(0)
	v_pk_fma_f32 v[90:91], v[110:111], v[98:99], v[106:107]
	v_pk_fma_f32 v[92:93], v[92:93], v[100:101], v[104:105]
	v_pk_fma_f32 v[98:99], v[112:113], v[98:99], v[108:109]
	v_pk_fma_f32 v[100:101], v[114:115], v[100:101], v[102:103]
	global_store_dwordx4 v[144:145], v[90:93], off offset:2048
	global_store_dwordx4 v[140:141], v[98:101], off offset:2048
	global_load_dwordx4 v[90:93], v[50:51], off
	v_lshlrev_b32_e32 v102, 16, v88
	v_and_b32_e32 v103, 0xffff0000, v88
	v_lshlrev_b32_e32 v88, 16, v89
	v_and_b32_e32 v89, 0xffff0000, v89
	v_lshlrev_b32_e32 v98, 16, v96
	v_and_b32_e32 v99, 0xffff0000, v96
	v_lshlrev_b32_e32 v96, 16, v97
	v_and_b32_e32 v97, 0xffff0000, v97
	v_lshlrev_b32_e32 v104, 16, v86
	v_and_b32_e32 v105, 0xffff0000, v86
	v_lshlrev_b32_e32 v86, 16, v87
	v_and_b32_e32 v87, 0xffff0000, v87
	v_pk_mul_f32 v[102:103], v[162:163], v[102:103] op_sel_hi:[0,1]
	v_pk_mul_f32 v[88:89], v[162:163], v[88:89] op_sel_hi:[0,1]
	v_lshlrev_b32_e32 v100, 16, v94
	v_and_b32_e32 v101, 0xffff0000, v94
	v_lshlrev_b32_e32 v94, 16, v95
	v_and_b32_e32 v95, 0xffff0000, v95
	v_pk_mul_f32 v[104:105], v[164:165], v[104:105] op_sel_hi:[0,1]
	v_pk_mul_f32 v[106:107], v[164:165], v[86:87] op_sel_hi:[0,1]
	s_waitcnt vmcnt(0)
	v_pk_fma_f32 v[86:87], v[102:103], v[90:91], v[98:99]
	v_pk_fma_f32 v[88:89], v[88:89], v[92:93], v[96:97]
	v_pk_fma_f32 v[90:91], v[104:105], v[90:91], v[100:101]
	v_pk_fma_f32 v[92:93], v[106:107], v[92:93], v[94:95]
	global_store_dwordx4 v[144:145], v[86:89], off offset:3072
	global_store_dwordx4 v[140:141], v[90:93], off offset:3072
	global_load_dwordx4 v[86:89], v[52:53], off
	v_lshlrev_b32_e32 v100, 16, v78
	v_add_co_u32_e32 v90, vcc, s19, v184
	v_and_b32_e32 v101, 0xffff0000, v78
	v_lshlrev_b32_e32 v78, 16, v79
	v_and_b32_e32 v79, 0xffff0000, v79
	v_addc_co_u32_e32 v91, vcc, 0, v185, vcc
	v_lshlrev_b32_e32 v94, 16, v84
	v_and_b32_e32 v95, 0xffff0000, v84
	v_lshlrev_b32_e32 v84, 16, v85
	v_and_b32_e32 v85, 0xffff0000, v85
	v_lshlrev_b32_e32 v102, 16, v80
	v_and_b32_e32 v103, 0xffff0000, v80
	v_lshlrev_b32_e32 v80, 16, v81
	v_and_b32_e32 v81, 0xffff0000, v81
	v_pk_mul_f32 v[100:101], v[162:163], v[100:101] op_sel_hi:[0,1]
	v_pk_mul_f32 v[104:105], v[162:163], v[78:79] op_sel_hi:[0,1]
	v_add_co_u32_e32 v92, vcc, s19, v182
	v_lshlrev_b32_e32 v96, 16, v172
	v_and_b32_e32 v97, 0xffff0000, v172
	v_lshlrev_b32_e32 v98, 16, v173
	v_and_b32_e32 v99, 0xffff0000, v173
	v_pk_mul_f32 v[102:103], v[164:165], v[102:103] op_sel_hi:[0,1]
	v_pk_mul_f32 v[106:107], v[164:165], v[80:81] op_sel_hi:[0,1]
	v_addc_co_u32_e32 v93, vcc, 0, v183, vcc
	s_waitcnt vmcnt(0)
	v_pk_fma_f32 v[78:79], v[100:101], v[86:87], v[94:95]
	v_pk_fma_f32 v[80:81], v[104:105], v[88:89], v[84:85]
	v_pk_fma_f32 v[84:85], v[102:103], v[86:87], v[96:97]
	v_pk_fma_f32 v[86:87], v[106:107], v[88:89], v[98:99]
	global_store_dwordx4 v[90:91], v[78:81], off
	global_store_dwordx4 v[92:93], v[84:87], off
	global_load_dwordx4 v[78:81], v[54:55], off
	v_lshlrev_b32_e32 v96, 16, v74
	v_lshlrev_b32_e32 v84, 16, v82
	v_and_b32_e32 v85, 0xffff0000, v82
	v_lshlrev_b32_e32 v86, 16, v83
	v_and_b32_e32 v87, 0xffff0000, v83
	v_lshlrev_b32_e32 v82, 16, v10
	v_and_b32_e32 v83, 0xffff0000, v10
	v_lshlrev_b32_e32 v10, 16, v11
	v_and_b32_e32 v11, 0xffff0000, v11
	v_and_b32_e32 v97, 0xffff0000, v74
	v_lshlrev_b32_e32 v74, 16, v75
	v_and_b32_e32 v75, 0xffff0000, v75
	v_pk_mul_f32 v[82:83], v[162:163], v[82:83] op_sel_hi:[0,1]
	v_pk_mul_f32 v[10:11], v[162:163], v[10:11] op_sel_hi:[0,1]
	v_lshlrev_b32_e32 v88, 16, v156
	v_and_b32_e32 v89, 0xffff0000, v156
	v_lshlrev_b32_e32 v94, 16, v157
	v_and_b32_e32 v95, 0xffff0000, v157
	v_pk_mul_f32 v[96:97], v[164:165], v[96:97] op_sel_hi:[0,1]
	v_pk_mul_f32 v[74:75], v[164:165], v[74:75] op_sel_hi:[0,1]
	s_waitcnt vmcnt(0)
	v_pk_fma_f32 v[82:83], v[82:83], v[78:79], v[84:85]
	v_pk_fma_f32 v[84:85], v[10:11], v[80:81], v[86:87]
	v_pk_fma_f32 v[78:79], v[96:97], v[78:79], v[88:89]
	v_pk_fma_f32 v[80:81], v[74:75], v[80:81], v[94:95]
	global_store_dwordx4 v[90:91], v[82:85], off offset:1024
	global_store_dwordx4 v[92:93], v[78:81], off offset:1024
	global_load_dwordx4 v[78:81], v[56:57], off
	v_lshlrev_b32_e32 v84, 16, v6
	v_and_b32_e32 v85, 0xffff0000, v6
	v_lshlrev_b32_e32 v6, 16, v7
	v_and_b32_e32 v7, 0xffff0000, v7
	v_lshlrev_b32_e32 v10, 16, v76
	v_and_b32_e32 v11, 0xffff0000, v76
	v_lshlrev_b32_e32 v74, 16, v77
	v_and_b32_e32 v75, 0xffff0000, v77
	v_lshlrev_b32_e32 v86, 16, v4
	v_and_b32_e32 v87, 0xffff0000, v4
	v_lshlrev_b32_e32 v4, 16, v5
	v_and_b32_e32 v5, 0xffff0000, v5
	v_pk_mul_f32 v[84:85], v[162:163], v[84:85] op_sel_hi:[0,1]
	v_pk_mul_f32 v[6:7], v[162:163], v[6:7] op_sel_hi:[0,1]
	v_lshlrev_b32_e32 v76, 16, v146
	v_and_b32_e32 v77, 0xffff0000, v146
	v_lshlrev_b32_e32 v82, 16, v147
	v_and_b32_e32 v83, 0xffff0000, v147
	v_pk_mul_f32 v[86:87], v[164:165], v[86:87] op_sel_hi:[0,1]
	v_pk_mul_f32 v[88:89], v[164:165], v[4:5] op_sel_hi:[0,1]
	s_waitcnt vmcnt(0)
	v_pk_fma_f32 v[4:5], v[84:85], v[78:79], v[10:11]
	v_pk_fma_f32 v[6:7], v[6:7], v[80:81], v[74:75]
	v_pk_fma_f32 v[74:75], v[86:87], v[78:79], v[76:77]
	v_pk_fma_f32 v[76:77], v[88:89], v[80:81], v[82:83]
	global_store_dwordx4 v[90:91], v[4:7], off offset:2048
	global_store_dwordx4 v[92:93], v[74:77], off offset:2048
	global_load_dwordx4 v[4:7], v[58:59], off
	v_lshlrev_b32_e32 v78, 16, v2
	v_and_b32_e32 v79, 0xffff0000, v2
	v_lshlrev_b32_e32 v2, 16, v3
	v_and_b32_e32 v3, 0xffff0000, v3
	v_lshlrev_b32_e32 v10, 16, v8
	v_and_b32_e32 v11, 0xffff0000, v8
	v_lshlrev_b32_e32 v8, 16, v9
	v_and_b32_e32 v9, 0xffff0000, v9
	v_lshlrev_b32_e32 v80, 16, v0
	v_and_b32_e32 v81, 0xffff0000, v0
	v_lshlrev_b32_e32 v0, 16, v1
	v_and_b32_e32 v1, 0xffff0000, v1
	v_pk_mul_f32 v[78:79], v[162:163], v[78:79] op_sel_hi:[0,1]
	v_pk_mul_f32 v[2:3], v[162:163], v[2:3] op_sel_hi:[0,1]
	v_lshlrev_b32_e32 v74, 16, v136
	v_and_b32_e32 v75, 0xffff0000, v136
	v_lshlrev_b32_e32 v76, 16, v137
	v_and_b32_e32 v77, 0xffff0000, v137
	v_pk_mul_f32 v[80:81], v[164:165], v[80:81] op_sel_hi:[0,1]
	v_pk_mul_f32 v[82:83], v[164:165], v[0:1] op_sel_hi:[0,1]
	s_waitcnt vmcnt(0)
	v_pk_fma_f32 v[0:1], v[78:79], v[4:5], v[10:11]
	v_pk_fma_f32 v[2:3], v[2:3], v[6:7], v[8:9]
	v_pk_fma_f32 v[4:5], v[80:81], v[4:5], v[74:75]
	v_pk_fma_f32 v[6:7], v[82:83], v[6:7], v[76:77]
	global_store_dwordx4 v[90:91], v[0:3], off offset:3072
	global_store_dwordx4 v[92:93], v[4:7], off offset:3072
	s_branch .LBB0_2024
.LBB0_2029:
	s_cmp_lt_i32 s8, 32
	s_cbranch_scc0 .LBB0_2031
	s_ashr_i32 s9, s8, 31
	s_lshl_b64 s[0:1], s[8:9], 14
	s_waitcnt lgkmcnt(0)
	s_add_u32 s8, s6, s0
	s_addc_u32 s9, s7, s1
	s_add_u32 s6, s8, 0x69ac0000
	s_addc_u32 s7, s9, 0
	global_load_dwordx4 v[28:31], v64, s[6:7]
	v_or_b32_e32 v65, 0x3800, v64
	global_load_dwordx4 v[0:3], v65, s[6:7] offset:16
	global_load_dwordx4 v[60:63], v64, s[6:7] offset:16
	global_load_dwordx4 v[56:59], v64, s[6:7] offset:2048
	global_load_dwordx4 v[52:55], v64, s[6:7] offset:2064
	v_or_b32_e32 v86, 0x1000, v64
	global_load_dwordx4 v[48:51], v86, s[6:7]
	global_load_dwordx4 v[44:47], v86, s[6:7] offset:16
	v_or_b32_e32 v87, 0x1800, v64
	global_load_dwordx4 v[40:43], v87, s[6:7]
	global_load_dwordx4 v[36:39], v87, s[6:7] offset:16
	v_or_b32_e32 v88, 0x2000, v64
	global_load_dwordx4 v[32:35], v88, s[6:7]
	global_load_dwordx4 v[24:27], v88, s[6:7] offset:16
	v_or_b32_e32 v89, 0x2800, v64
	global_load_dwordx4 v[20:23], v89, s[6:7]
	global_load_dwordx4 v[16:19], v89, s[6:7] offset:16
	s_waitcnt vmcnt(14)
	v_or_b32_e32 v67, 0x3000, v64
	global_load_dwordx4 v[12:15], v67, s[6:7]
	global_load_dwordx4 v[8:11], v67, s[6:7] offset:16
	global_load_dwordx4 v[4:7], v65, s[6:7]
	v_mbcnt_hi_u32_b32 v66, -1, v234
	v_and_b32_e32 v68, 64, v66
	s_add_u32 s6, s8, 0x69b40000
	v_xor_b32_e32 v69, 1, v66
	v_add_u32_e32 v90, 64, v68
	s_addc_u32 s7, s9, 0
	v_cmp_lt_i32_e32 vcc, v69, v90
	s_add_u32 s2, s2, 0x4000
	s_addc_u32 s3, s3, 0
	v_cndmask_b32_e32 v68, v66, v69, vcc
	v_lshlrev_b32_e32 v91, 2, v68
	global_load_dwordx4 v[68:71], v64, s[6:7] offset:16
	global_load_dwordx4 v[72:75], v64, s[6:7]
	global_load_dwordx4 v[76:79], v64, s[2:3] offset:16
	global_load_dwordx4 v[80:83], v64, s[2:3]
	s_mov_b32 s8, 0xf800000
	s_add_u32 s0, s4, s0
	s_addc_u32 s5, s5, s1
	s_add_u32 s4, s0, 0x8000000
	s_addc_u32 s5, s5, 0
	s_waitcnt vmcnt(18)
	v_pk_mul_f32 v[84:85], v[2:3], v[2:3]
	v_mul_f32_e32 v92, v29, v29
	v_fmac_f32_e32 v92, v28, v28
	v_fmac_f32_e32 v92, v30, v30
	v_fmac_f32_e32 v92, v31, v31
	s_waitcnt vmcnt(17)
	v_fmac_f32_e32 v92, v60, v60
	v_fmac_f32_e32 v92, v61, v61
	v_fmac_f32_e32 v92, v62, v62
	v_fmac_f32_e32 v92, v63, v63
	s_waitcnt vmcnt(16)
	v_fmac_f32_e32 v92, v56, v56
	v_fmac_f32_e32 v92, v57, v57
	v_fmac_f32_e32 v92, v58, v58
	v_fmac_f32_e32 v92, v59, v59
	s_waitcnt vmcnt(15)
	v_fmac_f32_e32 v92, v52, v52
	v_fmac_f32_e32 v92, v53, v53
	v_fmac_f32_e32 v92, v54, v54
	v_fmac_f32_e32 v92, v55, v55
	s_waitcnt vmcnt(14)
	v_fmac_f32_e32 v92, v48, v48
	v_fmac_f32_e32 v92, v49, v49
	v_fmac_f32_e32 v92, v50, v50
	v_fmac_f32_e32 v92, v51, v51
	s_waitcnt vmcnt(13)
	v_fmac_f32_e32 v92, v44, v44
	v_fmac_f32_e32 v92, v45, v45
	v_fmac_f32_e32 v92, v46, v46
	v_fmac_f32_e32 v92, v47, v47
	s_waitcnt vmcnt(12)
	v_fmac_f32_e32 v92, v40, v40
	v_fmac_f32_e32 v92, v41, v41
	v_fmac_f32_e32 v92, v42, v42
	v_fmac_f32_e32 v92, v43, v43
	s_waitcnt vmcnt(11)
	v_fmac_f32_e32 v92, v36, v36
	v_fmac_f32_e32 v92, v37, v37
	v_fmac_f32_e32 v92, v38, v38
	v_fmac_f32_e32 v92, v39, v39
	s_waitcnt vmcnt(10)
	v_fmac_f32_e32 v92, v32, v32
	v_fmac_f32_e32 v92, v33, v33
	v_fmac_f32_e32 v92, v34, v34
	v_fmac_f32_e32 v92, v35, v35
	s_waitcnt vmcnt(9)
	v_fmac_f32_e32 v92, v24, v24
	v_fmac_f32_e32 v92, v25, v25
	v_fmac_f32_e32 v92, v26, v26
	v_fmac_f32_e32 v92, v27, v27
	s_waitcnt vmcnt(8)
	v_fmac_f32_e32 v92, v20, v20
	v_fmac_f32_e32 v92, v21, v21
	v_fmac_f32_e32 v92, v22, v22
	v_fmac_f32_e32 v92, v23, v23
	s_waitcnt vmcnt(7)
	v_fmac_f32_e32 v92, v16, v16
	v_fmac_f32_e32 v92, v17, v17
	v_fmac_f32_e32 v92, v18, v18
	v_fmac_f32_e32 v92, v19, v19
	s_waitcnt vmcnt(6)
	v_fmac_f32_e32 v92, v12, v12
	v_fmac_f32_e32 v92, v13, v13
	v_fmac_f32_e32 v92, v14, v14
	v_fmac_f32_e32 v92, v15, v15
	s_waitcnt vmcnt(5)
	v_fmac_f32_e32 v92, v8, v8
	v_fmac_f32_e32 v92, v9, v9
	v_fmac_f32_e32 v92, v10, v10
	v_fmac_f32_e32 v92, v11, v11
	s_waitcnt vmcnt(4)
	v_fmac_f32_e32 v92, v4, v4
	v_fmac_f32_e32 v92, v5, v5
	v_fmac_f32_e32 v92, v6, v6
	v_fmac_f32_e32 v92, v7, v7
	v_fmac_f32_e32 v92, v0, v0
	v_fmac_f32_e32 v92, v1, v1
	v_add_f32_e32 v84, v84, v92
	v_add_f32_e32 v84, v85, v84
	v_xor_b32_e32 v91, 2, v66
	v_cmp_lt_i32_e32 vcc, v91, v90
	s_waitcnt lgkmcnt(0)
	s_nop 1
	v_add_f32_dpp v84, v84, v84 quad_perm:[1,0,3,2] row_mask:0xf bank_mask:0xf
	v_cndmask_b32_e32 v91, v66, v91, vcc
	v_lshlrev_b32_e32 v91, 2, v91
	v_xor_b32_e32 v91, 4, v66
	v_cmp_lt_i32_e32 vcc, v91, v90
	s_waitcnt lgkmcnt(0)
	s_nop 1
	v_add_f32_dpp v84, v84, v84 quad_perm:[2,3,0,1] row_mask:0xf bank_mask:0xf
	v_cndmask_b32_e32 v91, v66, v91, vcc
	v_lshlrev_b32_e32 v91, 2, v91
	v_xor_b32_e32 v91, 8, v66
	v_cmp_lt_i32_e32 vcc, v91, v90
	s_waitcnt lgkmcnt(0)
	s_nop 1
	v_add_f32_dpp v84, v84, v84 row_half_mirror row_mask:0xf bank_mask:0xf
	v_cndmask_b32_e32 v91, v66, v91, vcc
	v_lshlrev_b32_e32 v91, 2, v91
	v_xor_b32_e32 v91, 16, v66
	v_cmp_lt_i32_e32 vcc, v91, v90
	s_waitcnt lgkmcnt(0)
	s_nop 1
	v_add_f32_dpp v84, v84, v84 row_mirror row_mask:0xf bank_mask:0xf
	v_cndmask_b32_e32 v91, v66, v91, vcc
	v_lshlrev_b32_e32 v91, 2, v91
	v_xor_b32_e32 v91, 32, v66
	v_cmp_lt_i32_e32 vcc, v91, v90
	v_mov_b32_e32 v90, 0x260
	s_waitcnt lgkmcnt(0)
	v_mov_b32_e32 v85, v84
	s_nop 1
	v_permlane16_swap_b32_e32 v85, v84
	v_add_f32_e32 v84, v84, v85
	v_cndmask_b32_e32 v66, v66, v91, vcc
	v_lshlrev_b32_e32 v66, 2, v66
	ds_bpermute_b32 v66, v66, v84
	v_mov_b32_e32 v85, 0x358637bd
	v_or_b32_e32 v91, 0x800, v64
	s_waitcnt lgkmcnt(0)
	v_add_f32_e32 v66, v84, v66
	v_fmac_f32_e32 v85, 0x39800000, v66
	v_mul_f32_e32 v66, 0x4f800000, v85
	v_cmp_gt_f32_e32 vcc, s8, v85
	s_nop 1
	v_cndmask_b32_e32 v66, v85, v66, vcc
	v_sqrt_f32_e32 v84, v66
	s_nop 0
	v_add_u32_e32 v85, -1, v84
	v_add_u32_e32 v92, 1, v84
	v_fma_f32 v93, -v85, v84, v66
	v_fma_f32 v94, -v92, v84, v66
	v_cmp_ge_f32_e64 s[0:1], 0, v93
	s_nop 1
	v_cndmask_b32_e64 v84, v84, v85, s[0:1]
	v_cmp_lt_f32_e64 s[0:1], 0, v94
	s_nop 1
	v_cndmask_b32_e64 v84, v84, v92, s[0:1]
	v_mul_f32_e32 v85, 0x37800000, v84
	v_cndmask_b32_e32 v84, v84, v85, vcc
	v_cmp_class_f32_e32 vcc, v66, v90
	s_nop 1
	v_cndmask_b32_e32 v66, v84, v66, vcc
	v_div_scale_f32 v84, s[0:1], v66, v66, 1.0
	v_rcp_f32_e32 v85, v84
	v_div_scale_f32 v90, vcc, 1.0, v66, 1.0
	v_fma_f32 v92, -v84, v85, 1.0
	v_fmac_f32_e32 v85, v92, v85
	v_mul_f32_e32 v92, v90, v85
	v_fma_f32 v93, -v84, v92, v90
	v_fmac_f32_e32 v92, v93, v85
	v_fma_f32 v84, -v84, v92, v90
	v_div_fmas_f32 v84, v84, v85, v92
	v_div_fixup_f32 v66, v84, v66, 1.0
	v_pk_mul_f32 v[28:29], v[28:29], v[66:67] op_sel_hi:[1,0]
	v_pk_mul_f32 v[30:31], v[30:31], v[66:67] op_sel_hi:[1,0]
	v_pk_mul_f32 v[60:61], v[60:61], v[66:67] op_sel_hi:[1,0]
	v_pk_mul_f32 v[62:63], v[62:63], v[66:67] op_sel_hi:[1,0]
	s_waitcnt vmcnt(0)
	v_pk_fma_f32 v[30:31], v[82:83], v[30:31], v[74:75]
	v_pk_fma_f32 v[28:29], v[80:81], v[28:29], v[72:73]
	v_pk_fma_f32 v[62:63], v[78:79], v[62:63], v[70:71]
	v_pk_fma_f32 v[60:61], v[76:77], v[60:61], v[68:69]
	global_store_dwordx4 v64, v[28:31], s[4:5]
	global_store_dwordx4 v64, v[60:63], s[4:5] offset:16
	global_load_dwordx4 v[28:31], v91, s[2:3]
	s_nop 0
	global_load_dwordx4 v[60:63], v64, s[6:7] offset:2048
	global_load_dwordx4 v[68:71], v64, s[6:7] offset:2064
	global_load_dwordx4 v[72:75], v91, s[2:3] offset:16
	v_pk_mul_f32 v[58:59], v[58:59], v[66:67] op_sel_hi:[1,0]
	v_pk_mul_f32 v[56:57], v[56:57], v[66:67] op_sel_hi:[1,0]
	v_pk_mul_f32 v[54:55], v[54:55], v[66:67] op_sel_hi:[1,0]
	v_pk_mul_f32 v[52:53], v[52:53], v[66:67] op_sel_hi:[1,0]
	v_pk_mul_f32 v[50:51], v[50:51], v[66:67] op_sel_hi:[1,0]
	v_pk_mul_f32 v[48:49], v[48:49], v[66:67] op_sel_hi:[1,0]
	v_pk_mul_f32 v[46:47], v[46:47], v[66:67] op_sel_hi:[1,0]
	v_pk_mul_f32 v[44:45], v[44:45], v[66:67] op_sel_hi:[1,0]
	v_pk_mul_f32 v[42:43], v[42:43], v[66:67] op_sel_hi:[1,0]
	v_pk_mul_f32 v[40:41], v[40:41], v[66:67] op_sel_hi:[1,0]
	v_pk_mul_f32 v[38:39], v[38:39], v[66:67] op_sel_hi:[1,0]
	v_pk_mul_f32 v[36:37], v[36:37], v[66:67] op_sel_hi:[1,0]
	v_pk_mul_f32 v[34:35], v[34:35], v[66:67] op_sel_hi:[1,0]
	v_pk_mul_f32 v[32:33], v[32:33], v[66:67] op_sel_hi:[1,0]
	v_pk_mul_f32 v[22:23], v[22:23], v[66:67] op_sel_hi:[1,0]
	v_pk_mul_f32 v[20:21], v[20:21], v[66:67] op_sel_hi:[1,0]
	v_pk_mul_f32 v[14:15], v[14:15], v[66:67] op_sel_hi:[1,0]
	v_pk_mul_f32 v[12:13], v[12:13], v[66:67] op_sel_hi:[1,0]
	v_pk_mul_f32 v[6:7], v[6:7], v[66:67] op_sel_hi:[1,0]
	v_pk_mul_f32 v[4:5], v[4:5], v[66:67] op_sel_hi:[1,0]
	s_waitcnt vmcnt(2)
	v_pk_fma_f32 v[28:29], v[28:29], v[56:57], v[60:61]
	v_pk_fma_f32 v[30:31], v[30:31], v[58:59], v[62:63]
	s_waitcnt vmcnt(0)
	v_pk_fma_f32 v[52:53], v[72:73], v[52:53], v[68:69]
	v_pk_fma_f32 v[54:55], v[74:75], v[54:55], v[70:71]
	global_store_dwordx4 v64, v[28:31], s[4:5] offset:2048
	global_store_dwordx4 v64, v[52:55], s[4:5] offset:2064
	global_load_dwordx4 v[28:31], v86, s[2:3]
	s_nop 0
	global_load_dwordx4 v[52:55], v86, s[6:7]
	global_load_dwordx4 v[56:59], v86, s[6:7] offset:16
	global_load_dwordx4 v[60:63], v86, s[2:3] offset:16
	s_waitcnt vmcnt(2)
	v_pk_fma_f32 v[28:29], v[28:29], v[48:49], v[52:53]
	v_pk_fma_f32 v[30:31], v[30:31], v[50:51], v[54:55]
	s_waitcnt vmcnt(0)
	v_pk_fma_f32 v[44:45], v[60:61], v[44:45], v[56:57]
	v_pk_fma_f32 v[46:47], v[62:63], v[46:47], v[58:59]
	global_store_dwordx4 v86, v[28:31], s[4:5]
	global_store_dwordx4 v86, v[44:47], s[4:5] offset:16
	global_load_dwordx4 v[28:31], v87, s[2:3]
	s_nop 0
	global_load_dwordx4 v[44:47], v87, s[6:7]
	global_load_dwordx4 v[48:51], v87, s[6:7] offset:16
	global_load_dwordx4 v[52:55], v87, s[2:3] offset:16
	s_waitcnt vmcnt(2)
	v_pk_fma_f32 v[28:29], v[28:29], v[40:41], v[44:45]
	v_pk_fma_f32 v[30:31], v[30:31], v[42:43], v[46:47]
	s_waitcnt vmcnt(0)
	v_pk_fma_f32 v[36:37], v[52:53], v[36:37], v[48:49]
	v_pk_fma_f32 v[38:39], v[54:55], v[38:39], v[50:51]
	global_store_dwordx4 v87, v[28:31], s[4:5]
	global_store_dwordx4 v87, v[36:39], s[4:5] offset:16
	global_load_dwordx4 v[28:31], v88, s[2:3]
	s_nop 0
	global_load_dwordx4 v[36:39], v88, s[6:7]
	global_load_dwordx4 v[40:43], v88, s[6:7] offset:16
	global_load_dwordx4 v[44:47], v88, s[2:3] offset:16
	v_pk_mul_f32 v[48:49], v[26:27], v[66:67] op_sel_hi:[1,0]
	v_pk_mul_f32 v[50:51], v[24:25], v[66:67] op_sel_hi:[1,0]
	s_waitcnt vmcnt(2)
	v_pk_fma_f32 v[24:25], v[28:29], v[32:33], v[36:37]
	v_pk_fma_f32 v[26:27], v[30:31], v[34:35], v[38:39]
	s_waitcnt vmcnt(0)
	v_pk_fma_f32 v[28:29], v[44:45], v[50:51], v[40:41]
	v_pk_fma_f32 v[30:31], v[46:47], v[48:49], v[42:43]
	global_store_dwordx4 v88, v[24:27], s[4:5]
	global_store_dwordx4 v88, v[28:31], s[4:5] offset:16
	global_load_dwordx4 v[24:27], v89, s[2:3]
	s_nop 0
	global_load_dwordx4 v[28:31], v89, s[6:7]
	global_load_dwordx4 v[32:35], v89, s[6:7] offset:16
	global_load_dwordx4 v[36:39], v89, s[2:3] offset:16
	v_pk_mul_f32 v[40:41], v[18:19], v[66:67] op_sel_hi:[1,0]
	v_pk_mul_f32 v[42:43], v[16:17], v[66:67] op_sel_hi:[1,0]
	s_waitcnt vmcnt(2)
	v_pk_fma_f32 v[16:17], v[24:25], v[20:21], v[28:29]
	v_pk_fma_f32 v[18:19], v[26:27], v[22:23], v[30:31]
	s_waitcnt vmcnt(0)
	v_pk_fma_f32 v[20:21], v[36:37], v[42:43], v[32:33]
	v_pk_fma_f32 v[22:23], v[38:39], v[40:41], v[34:35]
	global_store_dwordx4 v89, v[16:19], s[4:5]
	global_store_dwordx4 v89, v[20:23], s[4:5] offset:16
	global_load_dwordx4 v[16:19], v67, s[2:3]
	s_nop 0
	global_load_dwordx4 v[20:23], v67, s[6:7]
	global_load_dwordx4 v[24:27], v67, s[6:7] offset:16
	global_load_dwordx4 v[28:31], v67, s[2:3] offset:16
	v_pk_mul_f32 v[32:33], v[10:11], v[66:67] op_sel_hi:[1,0]
	v_pk_mul_f32 v[34:35], v[8:9], v[66:67] op_sel_hi:[1,0]
	s_waitcnt vmcnt(2)
	v_pk_fma_f32 v[8:9], v[16:17], v[12:13], v[20:21]
	v_pk_fma_f32 v[10:11], v[18:19], v[14:15], v[22:23]
	s_waitcnt vmcnt(0)
	v_pk_fma_f32 v[12:13], v[28:29], v[34:35], v[24:25]
	v_pk_fma_f32 v[14:15], v[30:31], v[32:33], v[26:27]
	global_store_dwordx4 v67, v[8:11], s[4:5]
	global_store_dwordx4 v67, v[12:15], s[4:5] offset:16
	global_load_dwordx4 v[8:11], v65, s[2:3]
	s_nop 0
	global_load_dwordx4 v[12:15], v65, s[6:7]
	global_load_dwordx4 v[16:19], v65, s[6:7] offset:16
	global_load_dwordx4 v[20:23], v65, s[2:3] offset:16
	v_pk_mul_f32 v[24:25], v[2:3], v[66:67] op_sel_hi:[1,0]
	v_pk_mul_f32 v[26:27], v[0:1], v[66:67] op_sel_hi:[1,0]
	s_waitcnt vmcnt(2)
	v_pk_fma_f32 v[0:1], v[8:9], v[4:5], v[12:13]
	v_pk_fma_f32 v[2:3], v[10:11], v[6:7], v[14:15]
	s_waitcnt vmcnt(0)
	v_pk_fma_f32 v[4:5], v[20:21], v[26:27], v[16:17]
	v_pk_fma_f32 v[6:7], v[22:23], v[24:25], v[18:19]
	global_store_dwordx4 v65, v[0:3], s[4:5]
	global_store_dwordx4 v65, v[4:7], s[4:5] offset:16
